# GEMM K-loops: the 4 B0 fragment LDS reads of phases 1 and 5 issued inside the preceding MFMA segment (phases 8 and 4) with an added vmcnt(10) cover; L-segment read counts rebalanced 12/4/8/0 -> 8/4/8/
# speedup vs baseline: 1.0111x; 1.0053x over previous
; template <class Map, class Epi>
; DI void gemm_phase(LAS unsigned char* lds, const Map& MP, const Epi& E, const int nM, const int nN, const int K, const int lda, const int ldb) {
;     ...
;         const bool has_next = sched_next(ui + 1, nM, nN, G, cblk, nxt);
;         const char* nA = has_next ? MP.a(nxt) : cA; const char* nB = has_next ? MP.b(nxt) : cB;
;         for (int t = 0; t < nt; t += 2) {
;             const bool last = (t == nt - 2);
;             const char* a1 = cA + (size_t)(t + 1) * kstep;
;             const char* a2 = last ? nA : cA + (size_t)(t + 2) * kstep; const char* b2 = last ? nB : cB + (size_t)(t + 2) * kstep;
;             const char* a3 = a2 + kstep; const char* b3 = b2 + kstep;
;             PG8_LDB(B0, 0, 0); PG8_SCHED; PG8_LDA(At, 0, 0); PG8_STAGE(PG8_SA(1, 1), a1 + hstepA, voffA);
;             PG8_WAIT_L(8); PG8_BAR; PG8_WAIT_L(0); PG8_MMA(0, 0, At, B0); PG8_BAR; PG8_SCHED;
;             PG8_LDB(B1, 0, 1); PG8_STAGE(PG8_SB(0, 0), b2, voffB);
;             PG8_BAR; PG8_WAIT_L(0); PG8_MMA(0, 1, At, B1); PG8_BAR;
;             PG8_LDA(At, 0, 1); PG8_STAGE(PG8_SA(0, 0), a2, voffA);
;             PG8_BAR; PG8_WAIT_L(0); PG8_MMA(1, 0, At, B0); PG8_BAR; PG8_SCHED;
;             PG8_STAGE(PG8_SB(0, 1), b2 + hstepB, voffB);
;             PG8_WAIT_V(6); PG8_BAR; PG8_MMA(1, 1, At, B1); PG8_BAR;
;             PG8_LDB(B0, 1, 0); PG8_SCHED; PG8_LDA(At, 1, 0); PG8_STAGE(PG8_SA(0, 1), a2 + hstepA, voffA);
;             PG8_WAIT_L(8); PG8_BAR; PG8_WAIT_L(0); PG8_MMA(0, 0, At, B0); PG8_BAR; PG8_SCHED;
;             PG8_LDB(B1, 1, 1); PG8_STAGE(PG8_SB(1, 0), b3, voffB);
;             PG8_BAR; PG8_WAIT_L(0); PG8_MMA(0, 1, At, B1); PG8_BAR;
;             PG8_LDA(At, 1, 1); PG8_STAGE(PG8_SA(1, 0), a3, voffA);
;             PG8_BAR; PG8_WAIT_L(0); PG8_MMA(1, 0, At, B0); PG8_BAR; PG8_SCHED;
;             PG8_STAGE(PG8_SB(1, 1), b3 + hstepB, voffB);
;             PG8_WAIT_V(6); PG8_BAR; PG8_MMA(1, 1, At, B1); PG8_BAR;
;         }
;         { int frr = fr, fqq = fq; asm volatile("" : "+v"(frr), "+v"(fqq)); E(acc, cur, wr, wc, frr, fqq); }
;         if (!has_next) break;
; #pragma unroll
;         for (int a = 0; a < 2; ++a)
; #pragma unroll
;             for (int b = 0; b < 2; ++b)
; #pragma unroll
;                 for (int m = 0; m < 4; ++m)
; #pragma unroll
;                     for (int n = 0; n < 2; ++n) acc[a][b][m][n] = (f32x4){0.f, 0.f, 0.f, 0.f};
.LBB1_228:
	s_ashr_i32 s17, s16, 31
	v_cmp_lt_i64_e32 vcc, s[18:19], v[156:157]
	s_lshl_b64 s[18:19], s[16:17], 20
	s_add_u32 s17, s31, s18
	s_addc_u32 s20, s33, s19
	s_lshl_b32 s18, s52, 8
	s_and_b32 s18, s18, 0xfffffe00
	s_ashr_i32 s19, s18, 31
	s_lshl_b64 s[18:19], s[18:19], 1
	s_add_u32 s18, s17, s18
	s_addc_u32 s19, s20, s19
	s_and_b64 s[20:21], vcc, exec
	s_cselect_b32 s17, s19, s27
	s_cselect_b32 s43, s18, s26
	s_ashr_i32 s20, s52, 1
	s_ashr_i32 s21, s20, 31
	s_lshl_b64 s[20:21], s[20:21], 19
	s_add_u32 s20, s6, s20
	s_addc_u32 s21, s7, s21
	s_lshl_b32 s28, s52, 18
	s_and_b32 s28, s28, 0x40000
	s_add_u32 s20, s20, s28
	s_addc_u32 s21, s21, 0
	s_and_b64 s[28:29], vcc, exec
	s_cselect_b32 s53, s21, s25
	s_cselect_b32 s54, s20, s24
	s_add_u32 s55, s24, 0x100
	s_addc_u32 s56, s25, 0
	s_add_u32 s24, s26, 0x80080
	v_mov_b32_e32 v0, 0
	s_addc_u32 s25, s27, 0
	s_mov_b32 s57, -2
	v_mov_b32_e32 v1, v0
	v_mov_b32_e32 v2, v0
	v_mov_b32_e32 v3, v0
	v_mov_b32_e32 v4, v0
	v_mov_b32_e32 v5, v0
	v_mov_b32_e32 v6, v0
	v_mov_b32_e32 v7, v0
	v_mov_b32_e32 v16, v0
	v_mov_b32_e32 v17, v0
	v_mov_b32_e32 v18, v0
	v_mov_b32_e32 v19, v0
	v_mov_b32_e32 v20, v0
	v_mov_b32_e32 v21, v0
	v_mov_b32_e32 v22, v0
	v_mov_b32_e32 v23, v0
	v_mov_b32_e32 v32, v0
	v_mov_b32_e32 v33, v0
	v_mov_b32_e32 v34, v0
	v_mov_b32_e32 v35, v0
	v_mov_b32_e32 v36, v0
	v_mov_b32_e32 v37, v0
	v_mov_b32_e32 v38, v0
	v_mov_b32_e32 v39, v0
	v_mov_b32_e32 v48, v0
	v_mov_b32_e32 v49, v0
	v_mov_b32_e32 v50, v0
	v_mov_b32_e32 v51, v0
	v_mov_b32_e32 v52, v0
	v_mov_b32_e32 v53, v0
	v_mov_b32_e32 v54, v0
	v_mov_b32_e32 v55, v0
	v_mov_b32_e32 v8, v0
	v_mov_b32_e32 v9, v0
	v_mov_b32_e32 v10, v0
	v_mov_b32_e32 v11, v0
	v_mov_b32_e32 v12, v0
	v_mov_b32_e32 v13, v0
	v_mov_b32_e32 v14, v0
	v_mov_b32_e32 v15, v0
	v_mov_b32_e32 v24, v0
	v_mov_b32_e32 v25, v0
	v_mov_b32_e32 v26, v0
	v_mov_b32_e32 v27, v0
	v_mov_b32_e32 v28, v0
	v_mov_b32_e32 v29, v0
	v_mov_b32_e32 v30, v0
	v_mov_b32_e32 v31, v0
	v_mov_b32_e32 v40, v0
	v_mov_b32_e32 v41, v0
	v_mov_b32_e32 v42, v0
	v_mov_b32_e32 v43, v0
	v_mov_b32_e32 v44, v0
	v_mov_b32_e32 v45, v0
	v_mov_b32_e32 v46, v0
	v_mov_b32_e32 v47, v0
	v_mov_b32_e32 v56, v0
	v_mov_b32_e32 v57, v0
	v_mov_b32_e32 v58, v0
	v_mov_b32_e32 v59, v0
	v_mov_b32_e32 v60, v0
	v_mov_b32_e32 v61, v0
	v_mov_b32_e32 v62, v0
	v_mov_b32_e32 v63, v0
	v_mov_b32_e32 v64, v0
	v_mov_b32_e32 v65, v0
	v_mov_b32_e32 v66, v0
	v_mov_b32_e32 v67, v0
	v_mov_b32_e32 v68, v0
	v_mov_b32_e32 v69, v0
	v_mov_b32_e32 v70, v0
	v_mov_b32_e32 v71, v0
	v_mov_b32_e32 v96, v0
	v_mov_b32_e32 v97, v0
	v_mov_b32_e32 v98, v0
	v_mov_b32_e32 v99, v0
	v_mov_b32_e32 v100, v0
	v_mov_b32_e32 v101, v0
	v_mov_b32_e32 v102, v0
	v_mov_b32_e32 v103, v0
	v_mov_b32_e32 v112, v0
	v_mov_b32_e32 v113, v0
	v_mov_b32_e32 v114, v0
	v_mov_b32_e32 v115, v0
	v_mov_b32_e32 v116, v0
	v_mov_b32_e32 v117, v0
	v_mov_b32_e32 v118, v0
	v_mov_b32_e32 v119, v0
	v_mov_b32_e32 v128, v0
	v_mov_b32_e32 v129, v0
	v_mov_b32_e32 v130, v0
	v_mov_b32_e32 v131, v0
	v_mov_b32_e32 v132, v0
	v_mov_b32_e32 v133, v0
	v_mov_b32_e32 v134, v0
	v_mov_b32_e32 v135, v0
	v_mov_b32_e32 v88, v0
	v_mov_b32_e32 v89, v0
	v_mov_b32_e32 v90, v0
	v_mov_b32_e32 v91, v0
	v_mov_b32_e32 v92, v0
	v_mov_b32_e32 v93, v0
	v_mov_b32_e32 v94, v0
	v_mov_b32_e32 v95, v0
	v_mov_b32_e32 v104, v0
	v_mov_b32_e32 v105, v0
	v_mov_b32_e32 v106, v0
	v_mov_b32_e32 v107, v0
	v_mov_b32_e32 v108, v0
	v_mov_b32_e32 v109, v0
	v_mov_b32_e32 v110, v0
	v_mov_b32_e32 v111, v0
	v_mov_b32_e32 v120, v0
	v_mov_b32_e32 v121, v0
	v_mov_b32_e32 v122, v0
	v_mov_b32_e32 v123, v0
	v_mov_b32_e32 v124, v0
	v_mov_b32_e32 v125, v0
	v_mov_b32_e32 v126, v0
	v_mov_b32_e32 v127, v0
	v_mov_b32_e32 v136, v0
	v_mov_b32_e32 v137, v0
	v_mov_b32_e32 v138, v0
	v_mov_b32_e32 v139, v0
	v_mov_b32_e32 v140, v0
	v_mov_b32_e32 v141, v0
	v_mov_b32_e32 v142, v0
	v_mov_b32_e32 v143, v0
	ds_read_b128 v[72:75], v167
	ds_read_b128 v[76:79], v167 offset:1024
	ds_read_b128 v[80:83], v167 offset:2048
	ds_read_b128 v[84:87], v167 offset:3072
.LBB1_229:
	s_add_u32 s26, s24, 0xfff80080
	s_addc_u32 s27, s25, -1
	s_cmp_eq_u32 s57, 4
	s_cselect_b32 s29, s17, s27
	s_cselect_b32 s28, s43, s26
	s_cselect_b32 s27, s53, s56
	s_cselect_b32 s26, s54, s55
	s_add_i32 m0, s2, 0xc000
	ds_read_b128 v[160:163], v168
	ds_read_b128 v[170:173], v168 offset:1024
	ds_read_b128 v[174:177], v168 offset:2048
	ds_read_b128 v[178:181], v168 offset:3072
	ds_read_b128 v[182:185], v168 offset:4096
	ds_read_b128 v[186:189], v168 offset:5120
	ds_read_b128 v[190:193], v168 offset:6144
	ds_read_b128 v[198:201], v168 offset:7168
	global_load_lds_dwordx4 v154, s[24:25]
	s_add_i32 m0, s2, 0xe000
	s_nop 0
	global_load_lds_dwordx4 v152, s[24:25]
	s_waitcnt lgkmcnt(8)
	s_barrier
	s_setprio 1
	s_waitcnt lgkmcnt(7)
	v_mfma_f32_16x16x32_bf16 v[140:143], v[72:75], v[160:163], v[140:143]
	v_mfma_f32_16x16x32_bf16 v[136:139], v[80:83], v[160:163], v[136:139]
	s_waitcnt lgkmcnt(5)
	v_mfma_f32_16x16x32_bf16 v[124:127], v[72:75], v[174:177], v[124:127]
	v_mfma_f32_16x16x32_bf16 v[120:123], v[80:83], v[174:177], v[120:123]
	s_waitcnt lgkmcnt(3)
	v_mfma_f32_16x16x32_bf16 v[108:111], v[72:75], v[182:185], v[108:111]
	v_mfma_f32_16x16x32_bf16 v[104:107], v[80:83], v[182:185], v[104:107]
	s_waitcnt lgkmcnt(1)
	v_mfma_f32_16x16x32_bf16 v[92:95], v[72:75], v[190:193], v[92:95]
	v_mfma_f32_16x16x32_bf16 v[88:91], v[80:83], v[190:193], v[88:91]
	v_mfma_f32_16x16x32_bf16 v[140:143], v[76:79], v[170:173], v[140:143]
	v_mfma_f32_16x16x32_bf16 v[136:139], v[84:87], v[170:173], v[136:139]
	v_mfma_f32_16x16x32_bf16 v[124:127], v[76:79], v[178:181], v[124:127]
	v_mfma_f32_16x16x32_bf16 v[120:123], v[84:87], v[178:181], v[120:123]
	v_mfma_f32_16x16x32_bf16 v[108:111], v[76:79], v[186:189], v[108:111]
	v_mfma_f32_16x16x32_bf16 v[104:107], v[84:87], v[186:189], v[104:107]
	s_waitcnt lgkmcnt(0)
	v_mfma_f32_16x16x32_bf16 v[92:95], v[76:79], v[198:201], v[92:95]
	v_mfma_f32_16x16x32_bf16 v[88:91], v[84:87], v[198:201], v[88:91]
	s_setprio 0
	s_barrier
; #define PG8_STAGE(bufoff, gbase, voff) do { _Pragma("unroll") for (int _i = 0; _i < 2; ++_i) \
;         __builtin_amdgcn_global_load_lds((const unsigned*)((const char*)(gbase) + (voff)[_i]), (LAS unsigned*)(lds + (bufoff) + ldsw + _i * 8192), 16, 0, 0); } while (0)
; #define PG8_LDA(dst, b, h) do { _Pragma("unroll") for (int m = 0; m < 4; ++m) _Pragma("unroll") for (int k = 0; k < 2; ++k) dst[m][k] = *(const LAS bf16x8*)(lds + PG8_SA(b, h) + aoff + m * 2048 + k * 1024); } while (0)
; #define PG8_LDB(dst, b, h) do { _Pragma("unroll") for (int n = 0; n < 2; ++n) _Pragma("unroll") for (int k = 0; k < 2; ++k) dst[n][k] = *(const LAS bf16x8*)(lds + PG8_SB(b, h) + boff + n * 2048 + k * 1024); } while (0)
; #define PG8_MMA(ai, bj, At, Bt) do { __builtin_amdgcn_s_setprio(1); _Pragma("unroll") for (int m = 0; m < 4; ++m) _Pragma("unroll") for (int n = 0; n < 2; ++n) _Pragma("unroll") for (int k = 0; k < 2; ++k) \
;         acc[ai][bj][m][n] = __builtin_amdgcn_mfma_f32_16x16x32_bf16(Bt[n][k], At[m][k], acc[ai][bj][m][n], 0, 0, 0); __builtin_amdgcn_s_setprio(0); } while (0)
; #define PG8_WAIT_V(n) asm volatile("s_waitcnt vmcnt(" #n ")" ::: "memory")
; #define PG8_WAIT_L(n) asm volatile("s_waitcnt lgkmcnt(" #n ")" ::: "memory")
; #define PG8_BAR __builtin_amdgcn_s_barrier()
; #define PG8_SCHED __builtin_amdgcn_sched_barrier(0)
; template <class Map, class Epi>
; DI void gemm_phase(LAS unsigned char* lds, const Map& MP, const Epi& E, const int nM, const int nN, const int K, const int lda, const int ldb) {
;     ...
;             PG8_LDB(B1, 0, 1); PG8_STAGE(PG8_SB(0, 0), b2, voffB);
;             PG8_BAR; PG8_WAIT_L(0); PG8_MMA(0, 1, At, B1); PG8_BAR;
;             PG8_LDA(At, 0, 1); PG8_STAGE(PG8_SA(0, 0), a2, voffA);
;             PG8_BAR; PG8_WAIT_L(0); PG8_MMA(1, 0, At, B0); PG8_BAR; PG8_SCHED;
;             PG8_STAGE(PG8_SB(0, 1), b2 + hstepB, voffB);
;             PG8_WAIT_V(6); PG8_BAR; PG8_MMA(1, 1, At, B1); PG8_BAR;
;             PG8_LDB(B0, 1, 0); PG8_SCHED; PG8_LDA(At, 1, 0); PG8_STAGE(PG8_SA(0, 1), a2 + hstepA, voffA);
;             PG8_WAIT_L(8); PG8_BAR; PG8_WAIT_L(0); PG8_MMA(0, 0, At, B0); PG8_BAR; PG8_SCHED;
	s_add_i32 s58, s48, s34
	v_lshl_add_u64 v[194:195], s[26:27], 0, v[148:149]
	s_mov_b32 m0, s58
	ds_read_b128 v[202:205], v169
	ds_read_b128 v[206:209], v169 offset:1024
	ds_read_b128 v[210:213], v169 offset:2048
	ds_read_b128 v[214:217], v169 offset:3072
	global_load_lds_dwordx4 v[194:195], off
	v_lshl_add_u64 v[218:219], s[26:27], 0, v[144:145]
	s_add_i32 m0, s58, 0x2000
	s_nop 0
	global_load_lds_dwordx4 v[218:219], off
	s_barrier
	s_setprio 1
	s_waitcnt lgkmcnt(3)
	v_mfma_f32_16x16x32_bf16 v[132:135], v[202:205], v[160:163], v[132:135]
	s_waitcnt lgkmcnt(1)
	v_mfma_f32_16x16x32_bf16 v[128:131], v[210:213], v[160:163], v[128:131]
	v_mfma_f32_16x16x32_bf16 v[116:119], v[202:205], v[174:177], v[116:119]
	v_mfma_f32_16x16x32_bf16 v[112:115], v[210:213], v[174:177], v[112:115]
	v_mfma_f32_16x16x32_bf16 v[100:103], v[202:205], v[182:185], v[100:103]
	v_mfma_f32_16x16x32_bf16 v[96:99], v[210:213], v[182:185], v[96:99]
	v_mfma_f32_16x16x32_bf16 v[68:71], v[202:205], v[190:193], v[68:71]
	v_mfma_f32_16x16x32_bf16 v[64:67], v[210:213], v[190:193], v[64:67]
	v_mfma_f32_16x16x32_bf16 v[132:135], v[206:209], v[170:173], v[132:135]
	s_waitcnt lgkmcnt(0)
	v_mfma_f32_16x16x32_bf16 v[128:131], v[214:217], v[170:173], v[128:131]
	v_mfma_f32_16x16x32_bf16 v[116:119], v[206:209], v[178:181], v[116:119]
	v_mfma_f32_16x16x32_bf16 v[112:115], v[214:217], v[178:181], v[112:115]
	v_mfma_f32_16x16x32_bf16 v[100:103], v[206:209], v[186:189], v[100:103]
	v_mfma_f32_16x16x32_bf16 v[96:99], v[214:217], v[186:189], v[96:99]
	v_mfma_f32_16x16x32_bf16 v[68:71], v[206:209], v[198:201], v[68:71]
	v_mfma_f32_16x16x32_bf16 v[64:67], v[214:217], v[198:201], v[64:67]
	s_setprio 0
	s_mov_b32 m0, s2
	v_lshl_add_u64 v[220:221], s[28:29], 0, v[150:151]
	s_barrier
	ds_read_b128 v[160:163], v168 offset:16384
	ds_read_b128 v[170:173], v168 offset:17408
	ds_read_b128 v[174:177], v168 offset:18432
	ds_read_b128 v[178:181], v168 offset:19456
	ds_read_b128 v[182:185], v168 offset:20480
	ds_read_b128 v[186:189], v168 offset:21504
	ds_read_b128 v[190:193], v168 offset:22528
	ds_read_b128 v[198:201], v168 offset:23552
	global_load_lds_dwordx4 v[220:221], off
	v_lshl_add_u64 v[222:223], s[28:29], 0, v[146:147]
	s_mov_b32 m0, s4
	s_nop 0
	global_load_lds_dwordx4 v[222:223], off
	s_waitcnt vmcnt(10)
	s_barrier
	s_setprio 1
	s_waitcnt lgkmcnt(7)
	v_mfma_f32_16x16x32_bf16 v[60:63], v[72:75], v[160:163], v[60:63]
	v_mfma_f32_16x16x32_bf16 v[56:59], v[80:83], v[160:163], v[56:59]
	s_waitcnt lgkmcnt(5)
	v_mfma_f32_16x16x32_bf16 v[44:47], v[72:75], v[174:177], v[44:47]
	v_mfma_f32_16x16x32_bf16 v[40:43], v[80:83], v[174:177], v[40:43]
	s_waitcnt lgkmcnt(3)
	v_mfma_f32_16x16x32_bf16 v[28:31], v[72:75], v[182:185], v[28:31]
	v_mfma_f32_16x16x32_bf16 v[24:27], v[80:83], v[182:185], v[24:27]
	s_waitcnt lgkmcnt(1)
	v_mfma_f32_16x16x32_bf16 v[12:15], v[72:75], v[190:193], v[12:15]
	v_mfma_f32_16x16x32_bf16 v[8:11], v[80:83], v[190:193], v[8:11]
	v_mfma_f32_16x16x32_bf16 v[60:63], v[76:79], v[170:173], v[60:63]
	v_mfma_f32_16x16x32_bf16 v[56:59], v[84:87], v[170:173], v[56:59]
	v_mfma_f32_16x16x32_bf16 v[44:47], v[76:79], v[178:181], v[44:47]
	v_mfma_f32_16x16x32_bf16 v[40:43], v[84:87], v[178:181], v[40:43]
	v_mfma_f32_16x16x32_bf16 v[28:31], v[76:79], v[186:189], v[28:31]
	v_mfma_f32_16x16x32_bf16 v[24:27], v[84:87], v[186:189], v[24:27]
	s_waitcnt lgkmcnt(0)
	v_mfma_f32_16x16x32_bf16 v[12:15], v[76:79], v[198:201], v[12:15]
	v_mfma_f32_16x16x32_bf16 v[8:11], v[84:87], v[198:201], v[8:11]
	s_setprio 0
	s_barrier
	s_add_u32 s58, s26, 0x20000
	s_addc_u32 s59, s27, 0
	s_add_i32 s60, s49, s34
	s_mov_b32 m0, s60
	s_nop 0
	global_load_lds_dwordx4 v148, s[58:59]
	s_add_i32 m0, s60, 0x2000
	s_nop 0
	global_load_lds_dwordx4 v144, s[58:59]
	s_waitcnt vmcnt(6)
	s_barrier
	s_setprio 1
	v_mfma_f32_16x16x32_bf16 v[52:55], v[202:205], v[160:163], v[52:55]
	v_mfma_f32_16x16x32_bf16 v[48:51], v[210:213], v[160:163], v[48:51]
	s_add_i32 s58, 0, 0x18000
	v_add_u32_e32 v84, s58, v166
	ds_read_b128 v[72:75], v84
	v_mfma_f32_16x16x32_bf16 v[36:39], v[202:205], v[174:177], v[36:39]
	v_mfma_f32_16x16x32_bf16 v[32:35], v[210:213], v[174:177], v[32:35]
	ds_read_b128 v[76:79], v84 offset:1024
	v_mfma_f32_16x16x32_bf16 v[20:23], v[202:205], v[182:185], v[20:23]
	v_mfma_f32_16x16x32_bf16 v[16:19], v[210:213], v[182:185], v[16:19]
	ds_read_b128 v[80:83], v84 offset:2048
	v_mfma_f32_16x16x32_bf16 v[4:7], v[202:205], v[190:193], v[4:7]
	v_mfma_f32_16x16x32_bf16 v[0:3], v[210:213], v[190:193], v[0:3]
	ds_read_b128 v[84:87], v84 offset:3072
	v_mfma_f32_16x16x32_bf16 v[52:55], v[206:209], v[170:173], v[52:55]
	v_mfma_f32_16x16x32_bf16 v[48:51], v[214:217], v[170:173], v[48:51]
	v_mfma_f32_16x16x32_bf16 v[36:39], v[206:209], v[178:181], v[36:39]
	v_mfma_f32_16x16x32_bf16 v[32:35], v[214:217], v[178:181], v[32:35]
	v_mfma_f32_16x16x32_bf16 v[20:23], v[206:209], v[186:189], v[20:23]
	v_mfma_f32_16x16x32_bf16 v[16:19], v[214:217], v[186:189], v[16:19]
	v_mfma_f32_16x16x32_bf16 v[4:7], v[206:209], v[198:201], v[4:7]
	v_mfma_f32_16x16x32_bf16 v[0:3], v[214:217], v[198:201], v[0:3]
	s_setprio 0
	s_barrier
	s_add_u32 s28, s28, 0x80000
	s_addc_u32 s29, s29, 0
	s_mov_b32 m0, s5
	ds_read_b128 v[160:163], v168 offset:32768
	ds_read_b128 v[170:173], v168 offset:33792
	ds_read_b128 v[174:177], v168 offset:34816
	ds_read_b128 v[178:181], v168 offset:35840
	ds_read_b128 v[182:185], v168 offset:36864
	ds_read_b128 v[186:189], v168 offset:37888
	ds_read_b128 v[190:193], v168 offset:38912
	ds_read_b128 v[198:201], v168 offset:39936
	global_load_lds_dwordx4 v150, s[28:29]
	s_mov_b32 m0, s23
	s_nop 0
	global_load_lds_dwordx4 v146, s[28:29]
	s_waitcnt lgkmcnt(8)
	s_barrier
; #define PG8_STAGE(bufoff, gbase, voff) do { _Pragma("unroll") for (int _i = 0; _i < 2; ++_i) \
;         __builtin_amdgcn_global_load_lds((const unsigned*)((const char*)(gbase) + (voff)[_i]), (LAS unsigned*)(lds + (bufoff) + ldsw + _i * 8192), 16, 0, 0); } while (0)
; #define PG8_LDA(dst, b, h) do { _Pragma("unroll") for (int m = 0; m < 4; ++m) _Pragma("unroll") for (int k = 0; k < 2; ++k) dst[m][k] = *(const LAS bf16x8*)(lds + PG8_SA(b, h) + aoff + m * 2048 + k * 1024); } while (0)
; #define PG8_LDB(dst, b, h) do { _Pragma("unroll") for (int n = 0; n < 2; ++n) _Pragma("unroll") for (int k = 0; k < 2; ++k) dst[n][k] = *(const LAS bf16x8*)(lds + PG8_SB(b, h) + boff + n * 2048 + k * 1024); } while (0)
; #define PG8_MMA(ai, bj, At, Bt) do { __builtin_amdgcn_s_setprio(1); _Pragma("unroll") for (int m = 0; m < 4; ++m) _Pragma("unroll") for (int n = 0; n < 2; ++n) _Pragma("unroll") for (int k = 0; k < 2; ++k) \
;         acc[ai][bj][m][n] = __builtin_amdgcn_mfma_f32_16x16x32_bf16(Bt[n][k], At[m][k], acc[ai][bj][m][n], 0, 0, 0); __builtin_amdgcn_s_setprio(0); } while (0)
; #define PG8_WAIT_V(n) asm volatile("s_waitcnt vmcnt(" #n ")" ::: "memory")
; #define PG8_WAIT_L(n) asm volatile("s_waitcnt lgkmcnt(" #n ")" ::: "memory")
; #define PG8_BAR __builtin_amdgcn_s_barrier()
; #define PG8_SCHED __builtin_amdgcn_sched_barrier(0)
; template <class Map, class Epi>
; DI void gemm_phase(LAS unsigned char* lds, const Map& MP, const Epi& E, const int nM, const int nN, const int K, const int lda, const int ldb) {
;     ...
;             PG8_LDB(B0, 1, 0); PG8_SCHED; PG8_LDA(At, 1, 0); PG8_STAGE(PG8_SA(0, 1), a2 + hstepA, voffA);
;             PG8_WAIT_L(8); PG8_BAR; PG8_WAIT_L(0); PG8_MMA(0, 0, At, B0); PG8_BAR; PG8_SCHED;
;             PG8_LDB(B1, 1, 1); PG8_STAGE(PG8_SB(1, 0), b3, voffB);
;             PG8_BAR; PG8_WAIT_L(0); PG8_MMA(0, 1, At, B1); PG8_BAR;
;             PG8_LDA(At, 1, 1); PG8_STAGE(PG8_SA(1, 0), a3, voffA);
;             PG8_BAR; PG8_WAIT_L(0); PG8_MMA(1, 0, At, B0); PG8_BAR; PG8_SCHED;
;             PG8_STAGE(PG8_SB(1, 1), b3 + hstepB, voffB);
;             PG8_WAIT_V(6); PG8_BAR; PG8_MMA(1, 1, At, B1); PG8_BAR;
	s_setprio 1
	s_waitcnt lgkmcnt(7)
	v_mfma_f32_16x16x32_bf16 v[140:143], v[72:75], v[160:163], v[140:143]
	v_mfma_f32_16x16x32_bf16 v[136:139], v[80:83], v[160:163], v[136:139]
	s_waitcnt lgkmcnt(5)
	v_mfma_f32_16x16x32_bf16 v[124:127], v[72:75], v[174:177], v[124:127]
	v_mfma_f32_16x16x32_bf16 v[120:123], v[80:83], v[174:177], v[120:123]
	s_waitcnt lgkmcnt(3)
	v_mfma_f32_16x16x32_bf16 v[108:111], v[72:75], v[182:185], v[108:111]
	v_mfma_f32_16x16x32_bf16 v[104:107], v[80:83], v[182:185], v[104:107]
	s_waitcnt lgkmcnt(1)
	v_mfma_f32_16x16x32_bf16 v[92:95], v[72:75], v[190:193], v[92:95]
	v_mfma_f32_16x16x32_bf16 v[88:91], v[80:83], v[190:193], v[88:91]
	v_mfma_f32_16x16x32_bf16 v[140:143], v[76:79], v[170:173], v[140:143]
	v_mfma_f32_16x16x32_bf16 v[136:139], v[84:87], v[170:173], v[136:139]
	v_mfma_f32_16x16x32_bf16 v[124:127], v[76:79], v[178:181], v[124:127]
	v_mfma_f32_16x16x32_bf16 v[120:123], v[84:87], v[178:181], v[120:123]
	v_mfma_f32_16x16x32_bf16 v[108:111], v[76:79], v[186:189], v[108:111]
	v_mfma_f32_16x16x32_bf16 v[104:107], v[84:87], v[186:189], v[104:107]
	s_waitcnt lgkmcnt(0)
	v_mfma_f32_16x16x32_bf16 v[92:95], v[76:79], v[198:201], v[92:95]
	v_mfma_f32_16x16x32_bf16 v[88:91], v[84:87], v[198:201], v[88:91]
	s_setprio 0
	s_barrier
	s_add_i32 s28, 0, 0x1c000
	s_add_i32 s29, s58, s34
	v_add_u32_e32 v196, s28, v166
	v_lshl_add_u64 v[194:195], v[194:195], 0, s[12:13]
	s_mov_b32 m0, s29
	ds_read_b128 v[202:205], v196
	ds_read_b128 v[206:209], v196 offset:1024
	ds_read_b128 v[210:213], v196 offset:2048
	ds_read_b128 v[214:217], v196 offset:3072
	global_load_lds_dwordx4 v[194:195], off
	v_lshl_add_u64 v[194:195], v[218:219], 0, s[12:13]
	s_add_i32 m0, s29, 0x2000
	s_nop 0
	global_load_lds_dwordx4 v[194:195], off
	s_barrier
	s_setprio 1
	s_waitcnt lgkmcnt(3)
	v_mfma_f32_16x16x32_bf16 v[132:135], v[202:205], v[160:163], v[132:135]
	s_waitcnt lgkmcnt(1)
	v_mfma_f32_16x16x32_bf16 v[128:131], v[210:213], v[160:163], v[128:131]
	v_mfma_f32_16x16x32_bf16 v[116:119], v[202:205], v[174:177], v[116:119]
	v_mfma_f32_16x16x32_bf16 v[112:115], v[210:213], v[174:177], v[112:115]
	v_mfma_f32_16x16x32_bf16 v[100:103], v[202:205], v[182:185], v[100:103]
	v_mfma_f32_16x16x32_bf16 v[96:99], v[210:213], v[182:185], v[96:99]
	v_mfma_f32_16x16x32_bf16 v[68:71], v[202:205], v[190:193], v[68:71]
	v_mfma_f32_16x16x32_bf16 v[64:67], v[210:213], v[190:193], v[64:67]
	v_mfma_f32_16x16x32_bf16 v[132:135], v[206:209], v[170:173], v[132:135]
	s_waitcnt lgkmcnt(0)
	v_mfma_f32_16x16x32_bf16 v[128:131], v[214:217], v[170:173], v[128:131]
	v_mfma_f32_16x16x32_bf16 v[116:119], v[206:209], v[178:181], v[116:119]
	v_mfma_f32_16x16x32_bf16 v[112:115], v[214:217], v[178:181], v[112:115]
	v_mfma_f32_16x16x32_bf16 v[100:103], v[206:209], v[186:189], v[100:103]
	v_mfma_f32_16x16x32_bf16 v[96:99], v[214:217], v[186:189], v[96:99]
	v_mfma_f32_16x16x32_bf16 v[68:71], v[206:209], v[198:201], v[68:71]
	v_mfma_f32_16x16x32_bf16 v[64:67], v[214:217], v[198:201], v[64:67]
	s_setprio 0
	s_mov_b32 m0, s39
	v_lshl_add_u64 v[194:195], v[220:221], 0, s[12:13]
	s_barrier
	ds_read_b128 v[160:163], v168 offset:49152
	ds_read_b128 v[170:173], v168 offset:50176
	ds_read_b128 v[174:177], v168 offset:51200
	ds_read_b128 v[178:181], v168 offset:52224
	ds_read_b128 v[182:185], v168 offset:53248
	ds_read_b128 v[186:189], v168 offset:54272
	ds_read_b128 v[190:193], v168 offset:55296
	ds_read_b128 v[198:201], v168 offset:56320
	global_load_lds_dwordx4 v[194:195], off
	v_lshl_add_u64 v[194:195], v[222:223], 0, s[12:13]
	s_mov_b32 m0, s46
	s_nop 0
	global_load_lds_dwordx4 v[194:195], off
	s_waitcnt vmcnt(10)
	s_barrier
; #define PG8_STAGE(bufoff, gbase, voff) do { _Pragma("unroll") for (int _i = 0; _i < 2; ++_i) \
;         __builtin_amdgcn_global_load_lds((const unsigned*)((const char*)(gbase) + (voff)[_i]), (LAS unsigned*)(lds + (bufoff) + ldsw + _i * 8192), 16, 0, 0); } while (0)
; #define PG8_MMA(ai, bj, At, Bt) do { __builtin_amdgcn_s_setprio(1); _Pragma("unroll") for (int m = 0; m < 4; ++m) _Pragma("unroll") for (int n = 0; n < 2; ++n) _Pragma("unroll") for (int k = 0; k < 2; ++k) \
;         acc[ai][bj][m][n] = __builtin_amdgcn_mfma_f32_16x16x32_bf16(Bt[n][k], At[m][k], acc[ai][bj][m][n], 0, 0, 0); __builtin_amdgcn_s_setprio(0); } while (0)
; #define PG8_WAIT_V(n) asm volatile("s_waitcnt vmcnt(" #n ")" ::: "memory")
; #define PG8_BAR __builtin_amdgcn_s_barrier()
;     DI void operator()(const f32x4 (&acc)[2][2][4][2], const Unit& u, int wr, int wc, int fr, int fq) const {
;         const int row0 = u.pm * BM + wr * 64 + fr, col0 = u.pn * BM + wc * 32 + 8 * fq;
;         f32x4 sc[2][2];
; #pragma unroll
;         for (int bj = 0; bj < 2; ++bj)
; #pragma unroll
;             for (int n = 0; n < 2; ++n) sc[bj][n] = scale ? *(const f32x4*)(scale + col0 + bj * HALF + 4 * n) : (f32x4){1.f, 1.f, 1.f, 1.f};
; template <class Map, class Epi>
; DI void gemm_phase(LAS unsigned char* lds, const Map& MP, const Epi& E, const int nM, const int nN, const int K, const int lda, const int ldb) {
;     ...
;             PG8_STAGE(PG8_SB(1, 1), b3 + hstepB, voffB);
;             PG8_WAIT_V(6); PG8_BAR; PG8_MMA(1, 1, At, B1); PG8_BAR;
;         }
;         { int frr = fr, fqq = fq; asm volatile("" : "+v"(frr), "+v"(fqq)); E(acc, cur, wr, wc, frr, fqq); }
	s_setprio 1
	s_waitcnt lgkmcnt(7)
	v_mfma_f32_16x16x32_bf16 v[60:63], v[72:75], v[160:163], v[60:63]
	v_mfma_f32_16x16x32_bf16 v[56:59], v[80:83], v[160:163], v[56:59]
	s_waitcnt lgkmcnt(5)
	v_mfma_f32_16x16x32_bf16 v[44:47], v[72:75], v[174:177], v[44:47]
	v_mfma_f32_16x16x32_bf16 v[40:43], v[80:83], v[174:177], v[40:43]
	s_waitcnt lgkmcnt(3)
	v_mfma_f32_16x16x32_bf16 v[28:31], v[72:75], v[182:185], v[28:31]
	v_mfma_f32_16x16x32_bf16 v[24:27], v[80:83], v[182:185], v[24:27]
	s_waitcnt lgkmcnt(1)
	v_mfma_f32_16x16x32_bf16 v[12:15], v[72:75], v[190:193], v[12:15]
	v_mfma_f32_16x16x32_bf16 v[8:11], v[80:83], v[190:193], v[8:11]
	v_mfma_f32_16x16x32_bf16 v[60:63], v[76:79], v[170:173], v[60:63]
	v_mfma_f32_16x16x32_bf16 v[56:59], v[84:87], v[170:173], v[56:59]
	v_mfma_f32_16x16x32_bf16 v[44:47], v[76:79], v[178:181], v[44:47]
	v_mfma_f32_16x16x32_bf16 v[40:43], v[84:87], v[178:181], v[40:43]
	v_mfma_f32_16x16x32_bf16 v[28:31], v[76:79], v[186:189], v[28:31]
	v_mfma_f32_16x16x32_bf16 v[24:27], v[84:87], v[186:189], v[24:27]
	s_waitcnt lgkmcnt(0)
	v_mfma_f32_16x16x32_bf16 v[12:15], v[76:79], v[198:201], v[12:15]
	v_mfma_f32_16x16x32_bf16 v[8:11], v[84:87], v[198:201], v[8:11]
	s_setprio 0
	s_barrier
	s_add_u32 s26, s26, 0x20080
	s_addc_u32 s27, s27, 0
	s_add_i32 s28, s28, s34
	s_mov_b32 m0, s28
	s_nop 0
	global_load_lds_dwordx4 v148, s[26:27]
	s_add_i32 m0, s28, 0x2000
	s_nop 0
	global_load_lds_dwordx4 v144, s[26:27]
	s_waitcnt vmcnt(6)
	s_barrier
	s_setprio 1
	v_mfma_f32_16x16x32_bf16 v[52:55], v[202:205], v[160:163], v[52:55]
	v_mfma_f32_16x16x32_bf16 v[48:51], v[210:213], v[160:163], v[48:51]
	ds_read_b128 v[72:75], v167
	v_mfma_f32_16x16x32_bf16 v[36:39], v[202:205], v[174:177], v[36:39]
	v_mfma_f32_16x16x32_bf16 v[32:35], v[210:213], v[174:177], v[32:35]
	ds_read_b128 v[76:79], v167 offset:1024
	v_mfma_f32_16x16x32_bf16 v[20:23], v[202:205], v[182:185], v[20:23]
	v_mfma_f32_16x16x32_bf16 v[16:19], v[210:213], v[182:185], v[16:19]
	ds_read_b128 v[80:83], v167 offset:2048
	v_mfma_f32_16x16x32_bf16 v[4:7], v[202:205], v[190:193], v[4:7]
	v_mfma_f32_16x16x32_bf16 v[0:3], v[210:213], v[190:193], v[0:3]
	ds_read_b128 v[84:87], v167 offset:3072
	v_mfma_f32_16x16x32_bf16 v[52:55], v[206:209], v[170:173], v[52:55]
	v_mfma_f32_16x16x32_bf16 v[48:51], v[214:217], v[170:173], v[48:51]
	v_mfma_f32_16x16x32_bf16 v[36:39], v[206:209], v[178:181], v[36:39]
	v_mfma_f32_16x16x32_bf16 v[32:35], v[214:217], v[178:181], v[32:35]
	v_mfma_f32_16x16x32_bf16 v[20:23], v[206:209], v[186:189], v[20:23]
	v_mfma_f32_16x16x32_bf16 v[16:19], v[214:217], v[186:189], v[16:19]
	v_mfma_f32_16x16x32_bf16 v[4:7], v[206:209], v[198:201], v[4:7]
	v_mfma_f32_16x16x32_bf16 v[0:3], v[214:217], v[198:201], v[0:3]
	s_setprio 0
	s_add_i32 s57, s57, 2
	s_add_u32 s55, s55, 0x100
	s_addc_u32 s56, s56, 0
	s_add_u32 s24, s24, 0x100
	s_addc_u32 s25, s25, 0
	s_cmp_gt_u32 s57, 5
	s_barrier
	s_cbranch_scc0 .LBB1_229
	s_waitcnt lgkmcnt(0)
	s_lshl_b32 s17, s42, 8
	v_mov_b32_e32 v170, v164
	v_mov_b32_e32 v72, v165
	s_or_b32 s17, s17, s38
	v_mov_b32_e32 v80, 1.0
	v_lshl_add_u32 v160, v72, 3, s17
	v_ashrrev_i32_e32 v161, 31, v160
	v_cndmask_b32_e64 v72, 0, 1, s[14:15]
	v_lshl_add_u64 v[162:163], v[160:161], 2, s[8:9]
	v_cmp_ne_u32_e64 s[42:43], 1, v72
	s_andn2_b64 vcc, exec, s[14:15]
	v_mov_b32_e32 v84, 1.0
	v_mov_b32_e32 v85, 1.0
	v_mov_b32_e32 v86, 1.0
	v_mov_b32_e32 v87, 1.0
	s_cbranch_vccnz .LBB1_232
	global_load_dwordx4 v[84:87], v[162:163], off

; template <class Map, class Epi>
; DI void gemm_phase(LAS unsigned char* lds, const Map& MP, const Epi& E, const int nM, const int nN, const int K, const int lda, const int ldb) {
;     ...
;         const bool has_next = sched_next(ui + 1, nM, nN, G, cblk, nxt);
;         const char* nA = has_next ? MP.a(nxt) : cA; const char* nB = has_next ? MP.b(nxt) : cB;
;         for (int t = 0; t < nt; t += 2) {
;             const bool last = (t == nt - 2);
;             const char* a1 = cA + (size_t)(t + 1) * kstep;
;             const char* a2 = last ? nA : cA + (size_t)(t + 2) * kstep; const char* b2 = last ? nB : cB + (size_t)(t + 2) * kstep;
;             const char* a3 = a2 + kstep; const char* b3 = b2 + kstep;
;             PG8_LDB(B0, 0, 0); PG8_SCHED; PG8_LDA(At, 0, 0); PG8_STAGE(PG8_SA(1, 1), a1 + hstepA, voffA);
;             PG8_WAIT_L(8); PG8_BAR; PG8_WAIT_L(0); PG8_MMA(0, 0, At, B0); PG8_BAR; PG8_SCHED;
;             PG8_LDB(B1, 0, 1); PG8_STAGE(PG8_SB(0, 0), b2, voffB);
;             PG8_BAR; PG8_WAIT_L(0); PG8_MMA(0, 1, At, B1); PG8_BAR;
;             PG8_LDA(At, 0, 1); PG8_STAGE(PG8_SA(0, 0), a2, voffA);
;             PG8_BAR; PG8_WAIT_L(0); PG8_MMA(1, 0, At, B0); PG8_BAR; PG8_SCHED;
;             PG8_STAGE(PG8_SB(0, 1), b2 + hstepB, voffB);
;             PG8_WAIT_V(6); PG8_BAR; PG8_MMA(1, 1, At, B1); PG8_BAR;
;             PG8_LDB(B0, 1, 0); PG8_SCHED; PG8_LDA(At, 1, 0); PG8_STAGE(PG8_SA(0, 1), a2 + hstepA, voffA);
;             PG8_WAIT_L(8); PG8_BAR; PG8_WAIT_L(0); PG8_MMA(0, 0, At, B0); PG8_BAR; PG8_SCHED;
;             PG8_LDB(B1, 1, 1); PG8_STAGE(PG8_SB(1, 0), b3, voffB);
;             PG8_BAR; PG8_WAIT_L(0); PG8_MMA(0, 1, At, B1); PG8_BAR;
;             PG8_LDA(At, 1, 1); PG8_STAGE(PG8_SA(1, 0), a3, voffA);
;             PG8_BAR; PG8_WAIT_L(0); PG8_MMA(1, 0, At, B0); PG8_BAR; PG8_SCHED;
;             PG8_STAGE(PG8_SB(1, 1), b3 + hstepB, voffB);
;             PG8_WAIT_V(6); PG8_BAR; PG8_MMA(1, 1, At, B1); PG8_BAR;
;         }
;         { int frr = fr, fqq = fq; asm volatile("" : "+v"(frr), "+v"(fqq)); E(acc, cur, wr, wc, frr, fqq); }
;         if (!has_next) break;
; #pragma unroll
;         for (int a = 0; a < 2; ++a)
; #pragma unroll
;             for (int b = 0; b < 2; ++b)
; #pragma unroll
;                 for (int m = 0; m < 4; ++m)
; #pragma unroll
;                     for (int n = 0; n < 2; ++n) acc[a][b][m][n] = (f32x4){0.f, 0.f, 0.f, 0.f};
.LBB1_379:
	s_ashr_i32 s23, s22, 31
	v_cmp_lt_i64_e32 vcc, s[24:25], v[180:181]
	s_lshl_b64 s[24:25], s[22:23], 20
	s_add_u32 s24, s31, s24
	s_addc_u32 s25, s34, s25
	s_and_b64 s[26:27], vcc, exec
	s_cselect_b32 s23, s25, s29
	s_cselect_b32 s61, s24, s28
	s_ashr_i32 s21, s20, 31
	s_lshl_b64 s[26:27], s[20:21], 20
	s_add_u32 s26, s35, s26
	s_addc_u32 s27, s36, s27
	s_and_b64 s[46:47], vcc, exec
	s_cselect_b32 s21, s27, s45
	s_cselect_b32 s58, s26, s44
	s_add_u32 s59, s44, 0x100
	s_addc_u32 vcc_lo, s45, 0
	s_add_u32 s44, s28, 0x80080
	v_mov_b32_e32 v0, 0
	s_addc_u32 s45, s29, 0
	s_mov_b32 vcc_hi, -2
	v_mov_b32_e32 v1, v0
	v_mov_b32_e32 v2, v0
	v_mov_b32_e32 v3, v0
	v_mov_b32_e32 v4, v0
	v_mov_b32_e32 v5, v0
	v_mov_b32_e32 v6, v0
	v_mov_b32_e32 v7, v0
	v_mov_b32_e32 v20, v0
	v_mov_b32_e32 v21, v0
	v_mov_b32_e32 v22, v0
	v_mov_b32_e32 v23, v0
	v_mov_b32_e32 v28, v0
	v_mov_b32_e32 v29, v0
	v_mov_b32_e32 v30, v0
	v_mov_b32_e32 v31, v0
	v_mov_b32_e32 v36, v0
	v_mov_b32_e32 v37, v0
	v_mov_b32_e32 v38, v0
	v_mov_b32_e32 v39, v0
	v_mov_b32_e32 v44, v0
	v_mov_b32_e32 v45, v0
	v_mov_b32_e32 v46, v0
	v_mov_b32_e32 v47, v0
	v_mov_b32_e32 v52, v0
	v_mov_b32_e32 v53, v0
	v_mov_b32_e32 v54, v0
	v_mov_b32_e32 v55, v0
	v_mov_b32_e32 v56, v0
	v_mov_b32_e32 v57, v0
	v_mov_b32_e32 v58, v0
	v_mov_b32_e32 v59, v0
	v_mov_b32_e32 v8, v0
	v_mov_b32_e32 v9, v0
	v_mov_b32_e32 v10, v0
	v_mov_b32_e32 v11, v0
	v_mov_b32_e32 v12, v0
	v_mov_b32_e32 v13, v0
	v_mov_b32_e32 v14, v0
	v_mov_b32_e32 v15, v0
	v_mov_b32_e32 v16, v0
	v_mov_b32_e32 v17, v0
	v_mov_b32_e32 v18, v0
	v_mov_b32_e32 v19, v0
	v_mov_b32_e32 v24, v0
	v_mov_b32_e32 v25, v0
	v_mov_b32_e32 v26, v0
	v_mov_b32_e32 v27, v0
	v_mov_b32_e32 v32, v0
	v_mov_b32_e32 v33, v0
	v_mov_b32_e32 v34, v0
	v_mov_b32_e32 v35, v0
	v_mov_b32_e32 v40, v0
	v_mov_b32_e32 v41, v0
	v_mov_b32_e32 v42, v0
	v_mov_b32_e32 v43, v0
	v_mov_b32_e32 v48, v0
	v_mov_b32_e32 v49, v0
	v_mov_b32_e32 v50, v0
	v_mov_b32_e32 v51, v0
	v_mov_b32_e32 v60, v0
	v_mov_b32_e32 v61, v0
	v_mov_b32_e32 v62, v0
	v_mov_b32_e32 v63, v0
	v_mov_b32_e32 v64, v0
	v_mov_b32_e32 v65, v0
	v_mov_b32_e32 v66, v0
	v_mov_b32_e32 v67, v0
	v_mov_b32_e32 v68, v0
	v_mov_b32_e32 v69, v0
	v_mov_b32_e32 v70, v0
	v_mov_b32_e32 v71, v0
	v_mov_b32_e32 v116, v0
	v_mov_b32_e32 v117, v0
	v_mov_b32_e32 v118, v0
	v_mov_b32_e32 v119, v0
	v_mov_b32_e32 v124, v0
	v_mov_b32_e32 v125, v0
	v_mov_b32_e32 v126, v0
	v_mov_b32_e32 v127, v0
	v_mov_b32_e32 v132, v0
	v_mov_b32_e32 v133, v0
	v_mov_b32_e32 v134, v0
	v_mov_b32_e32 v135, v0
	v_mov_b32_e32 v140, v0
	v_mov_b32_e32 v141, v0
	v_mov_b32_e32 v142, v0
	v_mov_b32_e32 v143, v0
	v_mov_b32_e32 v152, v0
	v_mov_b32_e32 v153, v0
	v_mov_b32_e32 v154, v0
	v_mov_b32_e32 v155, v0
	v_mov_b32_e32 v156, v0
	v_mov_b32_e32 v157, v0
	v_mov_b32_e32 v158, v0
	v_mov_b32_e32 v159, v0
	v_mov_b32_e32 v72, v0
	v_mov_b32_e32 v73, v0
	v_mov_b32_e32 v74, v0
	v_mov_b32_e32 v75, v0
	v_mov_b32_e32 v76, v0
	v_mov_b32_e32 v77, v0
	v_mov_b32_e32 v78, v0
	v_mov_b32_e32 v79, v0
	v_mov_b32_e32 v104, v0
	v_mov_b32_e32 v105, v0
	v_mov_b32_e32 v106, v0
	v_mov_b32_e32 v107, v0
	v_mov_b32_e32 v120, v0
	v_mov_b32_e32 v121, v0
	v_mov_b32_e32 v122, v0
	v_mov_b32_e32 v123, v0
	v_mov_b32_e32 v128, v0
	v_mov_b32_e32 v129, v0
	v_mov_b32_e32 v130, v0
	v_mov_b32_e32 v131, v0
	v_mov_b32_e32 v136, v0
	v_mov_b32_e32 v137, v0
	v_mov_b32_e32 v138, v0
	v_mov_b32_e32 v139, v0
	v_mov_b32_e32 v144, v0
	v_mov_b32_e32 v145, v0
	v_mov_b32_e32 v146, v0
	v_mov_b32_e32 v147, v0
	v_mov_b32_e32 v148, v0
	v_mov_b32_e32 v149, v0
	v_mov_b32_e32 v150, v0
	v_mov_b32_e32 v151, v0
	ds_read_b128 v[80:83], v189
	ds_read_b128 v[84:87], v189 offset:1024
	ds_read_b128 v[88:91], v189 offset:2048
	ds_read_b128 v[92:95], v189 offset:3072
.LBB1_380:
	s_add_u32 s28, s44, 0xfff80080
	s_addc_u32 s29, s45, -1
	s_cmp_eq_u32 vcc_hi, 28
	s_cselect_b32 s47, s23, s29
	s_cselect_b32 s46, s61, s28
	s_cselect_b32 s29, s21, vcc_lo
	s_cselect_b32 s28, s58, s59
	s_add_i32 m0, s38, 0xc000
	ds_read_b128 v[96:99], v190
	ds_read_b128 v[100:103], v190 offset:1024
	ds_read_b128 v[108:111], v190 offset:2048
	ds_read_b128 v[112:115], v190 offset:3072
	ds_read_b128 v[160:163], v190 offset:4096
	ds_read_b128 v[164:167], v190 offset:5120
	ds_read_b128 v[198:201], v190 offset:6144
	ds_read_b128 v[202:205], v190 offset:7168
	global_load_lds_dwordx4 v178, s[44:45]
	s_add_i32 m0, s38, 0xe000
	s_nop 0
	global_load_lds_dwordx4 v176, s[44:45]
	s_waitcnt lgkmcnt(8)
	s_barrier
	s_setprio 1
	s_waitcnt lgkmcnt(7)
	v_mfma_f32_16x16x32_bf16 v[148:151], v[80:83], v[96:99], v[148:151]
	v_mfma_f32_16x16x32_bf16 v[144:147], v[88:91], v[96:99], v[144:147]
	s_waitcnt lgkmcnt(5)
	v_mfma_f32_16x16x32_bf16 v[136:139], v[80:83], v[108:111], v[136:139]
	v_mfma_f32_16x16x32_bf16 v[128:131], v[88:91], v[108:111], v[128:131]
	s_waitcnt lgkmcnt(3)
	v_mfma_f32_16x16x32_bf16 v[120:123], v[80:83], v[160:163], v[120:123]
	v_mfma_f32_16x16x32_bf16 v[104:107], v[88:91], v[160:163], v[104:107]
	s_waitcnt lgkmcnt(1)
	v_mfma_f32_16x16x32_bf16 v[76:79], v[80:83], v[198:201], v[76:79]
	v_mfma_f32_16x16x32_bf16 v[72:75], v[88:91], v[198:201], v[72:75]
	v_mfma_f32_16x16x32_bf16 v[148:151], v[84:87], v[100:103], v[148:151]
	v_mfma_f32_16x16x32_bf16 v[144:147], v[92:95], v[100:103], v[144:147]
	v_mfma_f32_16x16x32_bf16 v[136:139], v[84:87], v[112:115], v[136:139]
	v_mfma_f32_16x16x32_bf16 v[128:131], v[92:95], v[112:115], v[128:131]
	v_mfma_f32_16x16x32_bf16 v[120:123], v[84:87], v[164:167], v[120:123]
	v_mfma_f32_16x16x32_bf16 v[104:107], v[92:95], v[164:167], v[104:107]
	s_waitcnt lgkmcnt(0)
	v_mfma_f32_16x16x32_bf16 v[76:79], v[84:87], v[202:205], v[76:79]
	v_mfma_f32_16x16x32_bf16 v[72:75], v[92:95], v[202:205], v[72:75]
	s_setprio 0
	s_barrier
; #define PG8_STAGE(bufoff, gbase, voff) do { _Pragma("unroll") for (int _i = 0; _i < 2; ++_i) \
;         __builtin_amdgcn_global_load_lds((const unsigned*)((const char*)(gbase) + (voff)[_i]), (LAS unsigned*)(lds + (bufoff) + ldsw + _i * 8192), 16, 0, 0); } while (0)
; #define PG8_LDA(dst, b, h) do { _Pragma("unroll") for (int m = 0; m < 4; ++m) _Pragma("unroll") for (int k = 0; k < 2; ++k) dst[m][k] = *(const LAS bf16x8*)(lds + PG8_SA(b, h) + aoff + m * 2048 + k * 1024); } while (0)
; #define PG8_LDB(dst, b, h) do { _Pragma("unroll") for (int n = 0; n < 2; ++n) _Pragma("unroll") for (int k = 0; k < 2; ++k) dst[n][k] = *(const LAS bf16x8*)(lds + PG8_SB(b, h) + boff + n * 2048 + k * 1024); } while (0)
; #define PG8_MMA(ai, bj, At, Bt) do { __builtin_amdgcn_s_setprio(1); _Pragma("unroll") for (int m = 0; m < 4; ++m) _Pragma("unroll") for (int n = 0; n < 2; ++n) _Pragma("unroll") for (int k = 0; k < 2; ++k) \
;         acc[ai][bj][m][n] = __builtin_amdgcn_mfma_f32_16x16x32_bf16(Bt[n][k], At[m][k], acc[ai][bj][m][n], 0, 0, 0); __builtin_amdgcn_s_setprio(0); } while (0)
; #define PG8_WAIT_V(n) asm volatile("s_waitcnt vmcnt(" #n ")" ::: "memory")
; #define PG8_WAIT_L(n) asm volatile("s_waitcnt lgkmcnt(" #n ")" ::: "memory")
; #define PG8_BAR __builtin_amdgcn_s_barrier()
; #define PG8_SCHED __builtin_amdgcn_sched_barrier(0)
; template <class Map, class Epi>
; DI void gemm_phase(LAS unsigned char* lds, const Map& MP, const Epi& E, const int nM, const int nN, const int K, const int lda, const int ldb) {
;     ...
;             PG8_LDB(B1, 0, 1); PG8_STAGE(PG8_SB(0, 0), b2, voffB);
;             PG8_BAR; PG8_WAIT_L(0); PG8_MMA(0, 1, At, B1); PG8_BAR;
;             PG8_LDA(At, 0, 1); PG8_STAGE(PG8_SA(0, 0), a2, voffA);
;             PG8_BAR; PG8_WAIT_L(0); PG8_MMA(1, 0, At, B0); PG8_BAR; PG8_SCHED;
;             PG8_STAGE(PG8_SB(0, 1), b2 + hstepB, voffB);
;             PG8_WAIT_V(6); PG8_BAR; PG8_MMA(1, 1, At, B1); PG8_BAR;
;             PG8_LDB(B0, 1, 0); PG8_SCHED; PG8_LDA(At, 1, 0); PG8_STAGE(PG8_SA(0, 1), a2 + hstepA, voffA);
;             PG8_WAIT_L(8); PG8_BAR; PG8_WAIT_L(0); PG8_MMA(0, 0, At, B0); PG8_BAR; PG8_SCHED;
	s_add_i32 s68, s5, s37
	v_lshl_add_u64 v[184:185], s[28:29], 0, v[172:173]
	s_mov_b32 m0, s68
	ds_read_b128 v[206:209], v191
	ds_read_b128 v[210:213], v191 offset:1024
	ds_read_b128 v[214:217], v191 offset:2048
	ds_read_b128 v[218:221], v191 offset:3072
	global_load_lds_dwordx4 v[184:185], off
	v_lshl_add_u64 v[194:195], s[28:29], 0, v[168:169]
	s_add_i32 m0, s68, 0x2000
	s_nop 0
	global_load_lds_dwordx4 v[194:195], off
	s_barrier
	s_setprio 1
	s_waitcnt lgkmcnt(3)
	v_mfma_f32_16x16x32_bf16 v[156:159], v[206:209], v[96:99], v[156:159]
	s_waitcnt lgkmcnt(1)
	v_mfma_f32_16x16x32_bf16 v[96:99], v[214:217], v[96:99], v[152:155]
	v_mfma_f32_16x16x32_bf16 v[156:159], v[210:213], v[100:103], v[156:159]
	s_waitcnt lgkmcnt(0)
	v_mfma_f32_16x16x32_bf16 v[96:99], v[218:221], v[100:103], v[96:99]
	v_mfma_f32_16x16x32_bf16 v[100:103], v[206:209], v[108:111], v[140:143]
	v_mfma_f32_16x16x32_bf16 v[108:111], v[214:217], v[108:111], v[132:135]
	v_mfma_f32_16x16x32_bf16 v[116:119], v[214:217], v[160:163], v[116:119]
	v_mfma_f32_16x16x32_bf16 v[68:71], v[206:209], v[198:201], v[68:71]
	v_mfma_f32_16x16x32_bf16 v[64:67], v[214:217], v[198:201], v[64:67]
	v_mfma_f32_16x16x32_bf16 v[100:103], v[210:213], v[112:115], v[100:103]
	v_mfma_f32_16x16x32_bf16 v[108:111], v[218:221], v[112:115], v[108:111]
	v_mfma_f32_16x16x32_bf16 v[112:115], v[206:209], v[160:163], v[124:127]
	v_mfma_f32_16x16x32_bf16 v[116:119], v[218:221], v[164:167], v[116:119]
	v_mfma_f32_16x16x32_bf16 v[68:71], v[210:213], v[202:205], v[68:71]
	v_mfma_f32_16x16x32_bf16 v[64:67], v[218:221], v[202:205], v[64:67]
	v_mfma_f32_16x16x32_bf16 v[112:115], v[210:213], v[164:167], v[112:115]
	s_setprio 0
	s_mov_b32 m0, s38
	v_lshl_add_u64 v[226:227], s[46:47], 0, v[174:175]
	s_barrier
	ds_read_b128 v[124:127], v190 offset:16384
	ds_read_b128 v[132:135], v190 offset:17408
	ds_read_b128 v[140:143], v190 offset:18432
	ds_read_b128 v[152:155], v190 offset:19456
	ds_read_b128 v[160:163], v190 offset:20480
	ds_read_b128 v[164:167], v190 offset:21504
	ds_read_b128 v[198:201], v190 offset:22528
	ds_read_b128 v[202:205], v190 offset:23552
	global_load_lds_dwordx4 v[226:227], off
	v_lshl_add_u64 v[234:235], s[46:47], 0, v[170:171]
	s_mov_b32 m0, s39
	s_nop 0
	global_load_lds_dwordx4 v[234:235], off
	s_waitcnt vmcnt(10)
	s_barrier
	s_setprio 1
	s_waitcnt lgkmcnt(7)
	v_mfma_f32_16x16x32_bf16 v[60:63], v[80:83], v[124:127], v[60:63]
	v_mfma_f32_16x16x32_bf16 v[48:51], v[88:91], v[124:127], v[48:51]
	s_waitcnt lgkmcnt(5)
	v_mfma_f32_16x16x32_bf16 v[40:43], v[80:83], v[140:143], v[40:43]
	v_mfma_f32_16x16x32_bf16 v[32:35], v[88:91], v[140:143], v[32:35]
	s_waitcnt lgkmcnt(3)
	v_mfma_f32_16x16x32_bf16 v[24:27], v[80:83], v[160:163], v[24:27]
	v_mfma_f32_16x16x32_bf16 v[16:19], v[88:91], v[160:163], v[16:19]
	s_waitcnt lgkmcnt(1)
	v_mfma_f32_16x16x32_bf16 v[12:15], v[80:83], v[198:201], v[12:15]
	v_mfma_f32_16x16x32_bf16 v[8:11], v[88:91], v[198:201], v[8:11]
	v_mfma_f32_16x16x32_bf16 v[60:63], v[84:87], v[132:135], v[60:63]
	v_mfma_f32_16x16x32_bf16 v[48:51], v[92:95], v[132:135], v[48:51]
	v_mfma_f32_16x16x32_bf16 v[40:43], v[84:87], v[152:155], v[40:43]
	v_mfma_f32_16x16x32_bf16 v[32:35], v[92:95], v[152:155], v[32:35]
	v_mfma_f32_16x16x32_bf16 v[24:27], v[84:87], v[164:167], v[24:27]
	v_mfma_f32_16x16x32_bf16 v[16:19], v[92:95], v[164:167], v[16:19]
	s_waitcnt lgkmcnt(0)
	v_mfma_f32_16x16x32_bf16 v[12:15], v[84:87], v[202:205], v[12:15]
	v_mfma_f32_16x16x32_bf16 v[8:11], v[92:95], v[202:205], v[8:11]
	s_setprio 0
	s_barrier
	s_add_u32 s68, s28, 0x80000
	s_addc_u32 s69, s29, 0
	s_add_i32 s70, s2, s37
	s_mov_b32 m0, s70
	s_nop 0
	global_load_lds_dwordx4 v172, s[68:69]
	s_add_i32 m0, s70, 0x2000
	s_nop 0
	global_load_lds_dwordx4 v168, s[68:69]
	s_waitcnt vmcnt(6)
	s_barrier
	s_setprio 1
	v_mfma_f32_16x16x32_bf16 v[56:59], v[206:209], v[124:127], v[56:59]
	v_mfma_f32_16x16x32_bf16 v[52:55], v[214:217], v[124:127], v[52:55]
	s_add_i32 s68, 0, 0x18000
	v_add_u32_e32 v92, s68, v188
	ds_read_b128 v[80:83], v92
	v_mfma_f32_16x16x32_bf16 v[44:47], v[206:209], v[140:143], v[44:47]
	v_mfma_f32_16x16x32_bf16 v[36:39], v[214:217], v[140:143], v[36:39]
	ds_read_b128 v[84:87], v92 offset:1024
	v_mfma_f32_16x16x32_bf16 v[28:31], v[206:209], v[160:163], v[28:31]
	v_mfma_f32_16x16x32_bf16 v[20:23], v[214:217], v[160:163], v[20:23]
	ds_read_b128 v[88:91], v92 offset:2048
	v_mfma_f32_16x16x32_bf16 v[4:7], v[206:209], v[198:201], v[4:7]
	v_mfma_f32_16x16x32_bf16 v[0:3], v[214:217], v[198:201], v[0:3]
	ds_read_b128 v[92:95], v92 offset:3072
	v_mfma_f32_16x16x32_bf16 v[56:59], v[210:213], v[132:135], v[56:59]
	v_mfma_f32_16x16x32_bf16 v[52:55], v[218:221], v[132:135], v[52:55]
	v_mfma_f32_16x16x32_bf16 v[44:47], v[210:213], v[152:155], v[44:47]
	v_mfma_f32_16x16x32_bf16 v[36:39], v[218:221], v[152:155], v[36:39]
	v_mfma_f32_16x16x32_bf16 v[28:31], v[210:213], v[164:167], v[28:31]
	v_mfma_f32_16x16x32_bf16 v[20:23], v[218:221], v[164:167], v[20:23]
	v_mfma_f32_16x16x32_bf16 v[4:7], v[210:213], v[202:205], v[4:7]
	v_mfma_f32_16x16x32_bf16 v[0:3], v[218:221], v[202:205], v[0:3]
	s_setprio 0
	s_barrier
	s_add_u32 s46, s46, 0x80000
	s_addc_u32 s47, s47, 0
	s_mov_b32 m0, s56
	ds_read_b128 v[124:127], v190 offset:32768
	ds_read_b128 v[132:135], v190 offset:33792
	ds_read_b128 v[160:163], v190 offset:34816
	ds_read_b128 v[164:167], v190 offset:35840
	ds_read_b128 v[198:201], v190 offset:36864
	ds_read_b128 v[202:205], v190 offset:37888
	ds_read_b128 v[206:209], v190 offset:38912
	ds_read_b128 v[210:213], v190 offset:39936
	global_load_lds_dwordx4 v174, s[46:47]
	s_mov_b32 m0, s57
	s_nop 0
	global_load_lds_dwordx4 v170, s[46:47]
	s_waitcnt lgkmcnt(8)
	s_barrier
; #define PG8_STAGE(bufoff, gbase, voff) do { _Pragma("unroll") for (int _i = 0; _i < 2; ++_i) \
;         __builtin_amdgcn_global_load_lds((const unsigned*)((const char*)(gbase) + (voff)[_i]), (LAS unsigned*)(lds + (bufoff) + ldsw + _i * 8192), 16, 0, 0); } while (0)
; #define PG8_LDA(dst, b, h) do { _Pragma("unroll") for (int m = 0; m < 4; ++m) _Pragma("unroll") for (int k = 0; k < 2; ++k) dst[m][k] = *(const LAS bf16x8*)(lds + PG8_SA(b, h) + aoff + m * 2048 + k * 1024); } while (0)
; #define PG8_LDB(dst, b, h) do { _Pragma("unroll") for (int n = 0; n < 2; ++n) _Pragma("unroll") for (int k = 0; k < 2; ++k) dst[n][k] = *(const LAS bf16x8*)(lds + PG8_SB(b, h) + boff + n * 2048 + k * 1024); } while (0)
; #define PG8_MMA(ai, bj, At, Bt) do { __builtin_amdgcn_s_setprio(1); _Pragma("unroll") for (int m = 0; m < 4; ++m) _Pragma("unroll") for (int n = 0; n < 2; ++n) _Pragma("unroll") for (int k = 0; k < 2; ++k) \
;         acc[ai][bj][m][n] = __builtin_amdgcn_mfma_f32_16x16x32_bf16(Bt[n][k], At[m][k], acc[ai][bj][m][n], 0, 0, 0); __builtin_amdgcn_s_setprio(0); } while (0)
; #define PG8_WAIT_V(n) asm volatile("s_waitcnt vmcnt(" #n ")" ::: "memory")
; #define PG8_WAIT_L(n) asm volatile("s_waitcnt lgkmcnt(" #n ")" ::: "memory")
; #define PG8_BAR __builtin_amdgcn_s_barrier()
; #define PG8_SCHED __builtin_amdgcn_sched_barrier(0)
; template <class Map, class Epi>
; DI void gemm_phase(LAS unsigned char* lds, const Map& MP, const Epi& E, const int nM, const int nN, const int K, const int lda, const int ldb) {
;     ...
;             PG8_WAIT_L(8); PG8_BAR; PG8_WAIT_L(0); PG8_MMA(0, 0, At, B0); PG8_BAR; PG8_SCHED;
;             PG8_LDB(B1, 1, 1); PG8_STAGE(PG8_SB(1, 0), b3, voffB);
;             PG8_BAR; PG8_WAIT_L(0); PG8_MMA(0, 1, At, B1); PG8_BAR;
;             PG8_LDA(At, 1, 1); PG8_STAGE(PG8_SA(1, 0), a3, voffA);
;             PG8_BAR; PG8_WAIT_L(0); PG8_MMA(1, 0, At, B0); PG8_BAR; PG8_SCHED;
;             PG8_STAGE(PG8_SB(1, 1), b3 + hstepB, voffB);
;             PG8_WAIT_V(6); PG8_BAR; PG8_MMA(1, 1, At, B1); PG8_BAR;
	s_setprio 1
	s_waitcnt lgkmcnt(7)
	v_mfma_f32_16x16x32_bf16 v[140:143], v[80:83], v[124:127], v[148:151]
	s_waitcnt lgkmcnt(6)
	v_mfma_f32_16x16x32_bf16 v[148:151], v[84:87], v[132:135], v[140:143]
	v_mfma_f32_16x16x32_bf16 v[140:143], v[88:91], v[124:127], v[144:147]
	s_waitcnt lgkmcnt(5)
	v_mfma_f32_16x16x32_bf16 v[136:139], v[80:83], v[160:163], v[136:139]
	v_mfma_f32_16x16x32_bf16 v[128:131], v[88:91], v[160:163], v[128:131]
	s_waitcnt lgkmcnt(3)
	v_mfma_f32_16x16x32_bf16 v[120:123], v[80:83], v[198:201], v[120:123]
	v_mfma_f32_16x16x32_bf16 v[104:107], v[88:91], v[198:201], v[104:107]
	s_waitcnt lgkmcnt(1)
	v_mfma_f32_16x16x32_bf16 v[76:79], v[80:83], v[206:209], v[76:79]
	v_mfma_f32_16x16x32_bf16 v[72:75], v[88:91], v[206:209], v[72:75]
	v_mfma_f32_16x16x32_bf16 v[144:147], v[92:95], v[132:135], v[140:143]
	v_mfma_f32_16x16x32_bf16 v[136:139], v[84:87], v[164:167], v[136:139]
	v_mfma_f32_16x16x32_bf16 v[128:131], v[92:95], v[164:167], v[128:131]
	v_mfma_f32_16x16x32_bf16 v[120:123], v[84:87], v[202:205], v[120:123]
	v_mfma_f32_16x16x32_bf16 v[104:107], v[92:95], v[202:205], v[104:107]
	s_waitcnt lgkmcnt(0)
	v_mfma_f32_16x16x32_bf16 v[76:79], v[84:87], v[210:213], v[76:79]
	v_mfma_f32_16x16x32_bf16 v[72:75], v[92:95], v[210:213], v[72:75]
	s_setprio 0
	s_barrier
	s_add_i32 s46, 0, 0x1c000
	v_add_u32_e32 v140, s46, v188
	s_add_i32 s47, s68, s37
	ds_read_b128 v[214:217], v140
	ds_read_b128 v[218:221], v140 offset:1024
	ds_read_b128 v[222:225], v140 offset:2048
	ds_read_b128 v[230:233], v140 offset:3072
	v_lshl_add_u64 v[140:141], v[184:185], 0, s[14:15]
	s_mov_b32 m0, s47
	s_nop 0
	global_load_lds_dwordx4 v[140:141], off
	v_lshl_add_u64 v[140:141], v[194:195], 0, s[14:15]
	s_add_i32 m0, s47, 0x2000
	s_nop 0
	global_load_lds_dwordx4 v[140:141], off
	s_barrier
	s_setprio 1
	s_waitcnt lgkmcnt(1)
	v_mfma_f32_16x16x32_bf16 v[96:99], v[222:225], v[124:127], v[96:99]
	v_mfma_f32_16x16x32_bf16 v[140:143], v[214:217], v[124:127], v[156:159]
	s_waitcnt lgkmcnt(0)
	v_mfma_f32_16x16x32_bf16 v[152:155], v[230:233], v[132:135], v[96:99]
	v_mfma_f32_16x16x32_bf16 v[96:99], v[214:217], v[160:163], v[100:103]
	v_mfma_f32_16x16x32_bf16 v[156:159], v[218:221], v[132:135], v[140:143]
	v_mfma_f32_16x16x32_bf16 v[140:143], v[218:221], v[164:167], v[96:99]
	v_mfma_f32_16x16x32_bf16 v[96:99], v[222:225], v[160:163], v[108:111]
	v_mfma_f32_16x16x32_bf16 v[132:135], v[230:233], v[164:167], v[96:99]
	v_mfma_f32_16x16x32_bf16 v[96:99], v[214:217], v[198:201], v[112:115]
	v_mfma_f32_16x16x32_bf16 v[124:127], v[218:221], v[202:205], v[96:99]
	v_mfma_f32_16x16x32_bf16 v[96:99], v[222:225], v[198:201], v[116:119]
	v_mfma_f32_16x16x32_bf16 v[68:71], v[214:217], v[206:209], v[68:71]
	v_mfma_f32_16x16x32_bf16 v[64:67], v[222:225], v[206:209], v[64:67]
	v_mfma_f32_16x16x32_bf16 v[116:119], v[230:233], v[202:205], v[96:99]
	v_mfma_f32_16x16x32_bf16 v[68:71], v[218:221], v[210:213], v[68:71]
	v_mfma_f32_16x16x32_bf16 v[64:67], v[230:233], v[210:213], v[64:67]
	s_setprio 0
	s_mov_b32 m0, s62
	v_lshl_add_u64 v[184:185], v[226:227], 0, s[14:15]
	s_barrier
	ds_read_b128 v[96:99], v190 offset:49152
	ds_read_b128 v[100:103], v190 offset:50176
	ds_read_b128 v[108:111], v190 offset:51200
	ds_read_b128 v[112:115], v190 offset:52224
	ds_read_b128 v[160:163], v190 offset:53248
	ds_read_b128 v[164:167], v190 offset:54272
	ds_read_b128 v[198:201], v190 offset:55296
	ds_read_b128 v[202:205], v190 offset:56320
	global_load_lds_dwordx4 v[184:185], off
	v_lshl_add_u64 v[184:185], v[234:235], 0, s[14:15]
	s_mov_b32 m0, s63
	s_nop 0
	global_load_lds_dwordx4 v[184:185], off
	s_waitcnt vmcnt(10)
	s_barrier
	s_setprio 1
	s_waitcnt lgkmcnt(7)
	v_mfma_f32_16x16x32_bf16 v[60:63], v[80:83], v[96:99], v[60:63]
	v_mfma_f32_16x16x32_bf16 v[48:51], v[88:91], v[96:99], v[48:51]
	s_waitcnt lgkmcnt(5)
	v_mfma_f32_16x16x32_bf16 v[40:43], v[80:83], v[108:111], v[40:43]
	v_mfma_f32_16x16x32_bf16 v[32:35], v[88:91], v[108:111], v[32:35]
	s_waitcnt lgkmcnt(3)
	v_mfma_f32_16x16x32_bf16 v[24:27], v[80:83], v[160:163], v[24:27]
	v_mfma_f32_16x16x32_bf16 v[16:19], v[88:91], v[160:163], v[16:19]
	s_waitcnt lgkmcnt(1)
	v_mfma_f32_16x16x32_bf16 v[12:15], v[80:83], v[198:201], v[12:15]
	v_mfma_f32_16x16x32_bf16 v[8:11], v[88:91], v[198:201], v[8:11]
	v_mfma_f32_16x16x32_bf16 v[60:63], v[84:87], v[100:103], v[60:63]
	v_mfma_f32_16x16x32_bf16 v[48:51], v[92:95], v[100:103], v[48:51]
	v_mfma_f32_16x16x32_bf16 v[40:43], v[84:87], v[112:115], v[40:43]
	v_mfma_f32_16x16x32_bf16 v[32:35], v[92:95], v[112:115], v[32:35]
	v_mfma_f32_16x16x32_bf16 v[24:27], v[84:87], v[164:167], v[24:27]
	v_mfma_f32_16x16x32_bf16 v[16:19], v[92:95], v[164:167], v[16:19]
	s_waitcnt lgkmcnt(0)
	v_mfma_f32_16x16x32_bf16 v[12:15], v[84:87], v[202:205], v[12:15]
	v_mfma_f32_16x16x32_bf16 v[8:11], v[92:95], v[202:205], v[8:11]
	s_setprio 0
	s_barrier
	s_add_u32 s28, s28, 0x80080
	s_addc_u32 s29, s29, 0
	s_add_i32 s46, s46, s37
	s_mov_b32 m0, s46
	s_nop 0
	global_load_lds_dwordx4 v172, s[28:29]
	s_add_i32 m0, s46, 0x2000
	s_nop 0
	global_load_lds_dwordx4 v168, s[28:29]
	s_waitcnt vmcnt(6)
	s_barrier
; #define PG8_BAR __builtin_amdgcn_s_barrier()
;     DI void operator()(const f32x4 (&acc)[2][2][4][2], const Unit& u, int wr, int wc, int fr, int fq) const {
;         const int row0 = u.pm * BM + wr * 64 + fr, ch0 = u.pn * 128 + wc * 32 + 8 * fq;
;         f32x4 w0[2], w1[2], w2[2], bb[2];
; #pragma unroll
;         for (int n = 0; n < 2; ++n) { w0[n] = *(const f32x4*)(cw + ch0 + 4 * n); w1[n] = *(const f32x4*)(cw + DFF + ch0 + 4 * n); w2[n] = *(const f32x4*)(cw + 2 * DFF + ch0 + 4 * n); bb[n] = *(const f32x4*)(cb + ch0 + 4 * n); }
; #pragma unroll
;         for (int ai = 0; ai < 2; ++ai)
; #pragma unroll
;             for (int m = 0; m < 4; ++m) {
;                 const bool efirst = (m == 0) && (fr == 0), elast = (m == 3) && (fr == 15);
;                 const int row = row0 + ai * HALF + m * 16;
;                 f32x4 gc[2];
; #pragma unroll
;                 for (int n = 0; n < 2; ++n) {
;                     const f32x4 g = acc[ai][0][m][n];
;                     const f32x4 gprev = acc[ai][0][m > 0 ? m - 1 : 0][n], gnext = acc[ai][0][m < 3 ? m + 1 : 3][n];
;                     f32x4 up, dn;
; #pragma unroll
;                     for (int e = 0; e < 4; ++e) {
;                         const float pu = (m > 0 && fr == 15) ? gprev[e] : g[e];
;                         const float pd = (m < 3 && fr == 0) ? gnext[e] : g[e];
;                         up[e] = dpp_ror1(pu); dn[e] = dpp_ror15(pd);
;                     }
;                     if (efirst) up = (f32x4){0.f, 0.f, 0.f, 0.f};
;                     if (elast) dn = (f32x4){0.f, 0.f, 0.f, 0.f};
;                     gc[n] = w0[n] * up + w1[n] * g + w2[n] * dn + bb[n];
;                 }
;                 if (efirst || elast) {
;                     const size_t eo = (size_t)((row >> 6) * 2 + (elast ? 1 : 0)) * DFF + ch0;
; #pragma unroll
;                     for (int n = 0; n < 2; ++n) { *(f32x4*)(EP + eo + 4 * n) = gc[n]; *(f32x4*)(ER + eo + 4 * n) = acc[ai][0][m][n]; *(f32x4*)(EV + eo + 4 * n) = acc[ai][1][m][n]; }
; template <class Map, class Epi>
; DI void gemm_phase(LAS unsigned char* lds, const Map& MP, const Epi& E, const int nM, const int nN, const int K, const int lda, const int ldb) {
;     ...
;             PG8_WAIT_V(6); PG8_BAR; PG8_MMA(1, 1, At, B1); PG8_BAR;
;         }
;         { int frr = fr, fqq = fq; asm volatile("" : "+v"(frr), "+v"(fqq)); E(acc, cur, wr, wc, frr, fqq); }
	s_setprio 1
	v_mfma_f32_16x16x32_bf16 v[56:59], v[214:217], v[96:99], v[56:59]
	v_mfma_f32_16x16x32_bf16 v[52:55], v[222:225], v[96:99], v[52:55]
	ds_read_b128 v[80:83], v189
	v_mfma_f32_16x16x32_bf16 v[44:47], v[214:217], v[108:111], v[44:47]
	v_mfma_f32_16x16x32_bf16 v[36:39], v[222:225], v[108:111], v[36:39]
	ds_read_b128 v[84:87], v189 offset:1024
	v_mfma_f32_16x16x32_bf16 v[28:31], v[214:217], v[160:163], v[28:31]
	v_mfma_f32_16x16x32_bf16 v[20:23], v[222:225], v[160:163], v[20:23]
	ds_read_b128 v[88:91], v189 offset:2048
	v_mfma_f32_16x16x32_bf16 v[4:7], v[214:217], v[198:201], v[4:7]
	v_mfma_f32_16x16x32_bf16 v[0:3], v[222:225], v[198:201], v[0:3]
	ds_read_b128 v[92:95], v189 offset:3072
	v_mfma_f32_16x16x32_bf16 v[56:59], v[218:221], v[100:103], v[56:59]
	v_mfma_f32_16x16x32_bf16 v[52:55], v[230:233], v[100:103], v[52:55]
	v_mfma_f32_16x16x32_bf16 v[44:47], v[218:221], v[112:115], v[44:47]
	v_mfma_f32_16x16x32_bf16 v[36:39], v[230:233], v[112:115], v[36:39]
	v_mfma_f32_16x16x32_bf16 v[28:31], v[218:221], v[164:167], v[28:31]
	v_mfma_f32_16x16x32_bf16 v[20:23], v[230:233], v[164:167], v[20:23]
	v_mfma_f32_16x16x32_bf16 v[4:7], v[218:221], v[202:205], v[4:7]
	v_mfma_f32_16x16x32_bf16 v[0:3], v[230:233], v[202:205], v[0:3]
	s_setprio 0
	s_add_i32 vcc_hi, vcc_hi, 2
	s_add_u32 s59, s59, 0x100
	s_addc_u32 vcc_lo, vcc_lo, 0
	s_add_u32 s44, s44, 0x100
	s_addc_u32 s45, s45, 0
	s_cmp_gt_u32 vcc_hi, 29
	s_barrier
	s_cbranch_scc0 .LBB1_380
	s_waitcnt lgkmcnt(0)
	s_lshl_b32 s23, s43, 7
	v_mov_b32_e32 v194, v186
	v_mov_b32_e32 v80, v187
	s_or_b32 s23, s23, s67
	v_mov_b32_e32 v160, 0
	v_lshl_add_u32 v184, v80, 3, s23
	v_ashrrev_i32_e32 v185, 31, v184
	v_lshlrev_b64 v[80:81], 2, v[184:185]
	v_lshl_add_u64 v[84:85], s[52:53], 0, v[80:81]
	v_lshl_add_u64 v[88:89], s[16:17], 0, v[80:81]
	v_lshl_add_u64 v[92:93], s[18:19], 0, v[80:81]
	v_lshl_add_u64 v[112:113], s[54:55], 0, v[80:81]
	global_load_dwordx4 v[80:83], v[84:85], off offset:16
	global_load_dwordx4 v[96:99], v[84:85], off
	s_nop 0
	global_load_dwordx4 v[84:87], v[88:89], off offset:16
	global_load_dwordx4 v[100:103], v[88:89], off
	s_nop 0
	global_load_dwordx4 v[88:91], v[92:93], off offset:16
	global_load_dwordx4 v[108:111], v[92:93], off
	s_nop 0
	global_load_dwordx4 v[92:95], v[112:113], off offset:16
	s_nop 0
	global_load_dwordx4 v[112:115], v[112:113], off
	v_cmp_eq_u32_e32 vcc, 0, v194
	v_mov_b32_e32 v164, 0
	v_mov_b32_e32 v195, 0
	v_cndmask_b32_e32 v161, v148, v136, vcc
	v_cndmask_b32_e32 v162, v149, v137, vcc
	v_cndmask_b32_e32 v163, v150, v138, vcc
	v_mov_b32_dpp v160, v161 row_ror:15 row_mask:0xf bank_mask:0xf
	v_mov_b32_e32 v161, 0
	v_mov_b32_e32 v166, 0
	v_mov_b32_e32 v167, 0
	v_mov_b32_dpp v161, v162 row_ror:15 row_mask:0xf bank_mask:0xf
	v_mov_b32_e32 v162, 0
	v_mov_b32_dpp v164, v150 row_ror:1 row_mask:0xf bank_mask:0xf
	v_cndmask_b32_e32 v165, v151, v139, vcc
	v_mov_b32_dpp v162, v163 row_ror:15 row_mask:0xf bank_mask:0xf
	v_mov_b32_dpp v195, v151 row_ror:1 row_mask:0xf bank_mask:0xf
	v_mov_b32_e32 v163, 0
	v_mov_b32_dpp v166, v148 row_ror:1 row_mask:0xf bank_mask:0xf
	v_mov_b32_dpp v167, v149 row_ror:1 row_mask:0xf bank_mask:0xf
	v_mov_b32_dpp v163, v165 row_ror:15 row_mask:0xf bank_mask:0xf
	v_cndmask_b32_e64 v165, v195, 0, vcc
	v_cndmask_b32_e64 v164, v164, 0, vcc
	v_cndmask_b32_e64 v167, v167, 0, vcc
	v_cndmask_b32_e64 v166, v166, 0, vcc
	v_mov_b32_e32 v195, 0
	v_mov_b32_e32 v196, 0
	v_mov_b32_e32 v198, 0
	v_mov_b32_e32 v200, 0
	v_mov_b32_dpp v195, v144 row_ror:1 row_mask:0xf bank_mask:0xf
	v_mov_b32_dpp v196, v145 row_ror:1 row_mask:0xf bank_mask:0xf
	v_mov_b32_dpp v198, v146 row_ror:1 row_mask:0xf bank_mask:0xf
	v_cndmask_b32_e32 v199, v147, v131, vcc
	v_mov_b32_dpp v200, v147 row_ror:1 row_mask:0xf bank_mask:0xf
	v_cndmask_b32_e64 v198, v198, 0, vcc
	v_cndmask_b32_e64 v201, v196, 0, vcc
	s_lshl_b32 s21, s42, 8
	s_add_i32 s21, s21, s49
	v_add_u32_e32 v193, s21, v194
	v_cmp_ne_u32_e64 s[46:47], 0, v194
	s_waitcnt vmcnt(0)
	v_pk_mul_f32 v[164:165], v[98:99], v[164:165]
	v_pk_mul_f32 v[166:167], v[96:97], v[166:167]
	v_pk_fma_f32 v[164:165], v[150:151], v[102:103], v[164:165]
	v_pk_fma_f32 v[166:167], v[148:149], v[100:101], v[166:167]
	v_pk_fma_f32 v[162:163], v[110:111], v[162:163], v[164:165]
	v_cndmask_b32_e32 v165, v144, v128, vcc
	v_mov_b32_e32 v164, 0
	v_pk_fma_f32 v[160:161], v[108:109], v[160:161], v[166:167]
	v_cndmask_b32_e32 v166, v145, v129, vcc
	v_mov_b32_dpp v164, v165 row_ror:15 row_mask:0xf bank_mask:0xf
	v_mov_b32_e32 v165, 0
	v_cndmask_b32_e32 v167, v146, v130, vcc
	v_pk_add_f32 v[162:163], v[114:115], v[162:163]
	v_mov_b32_dpp v165, v166 row_ror:15 row_mask:0xf bank_mask:0xf
	v_mov_b32_e32 v166, 0
	v_pk_add_f32 v[160:161], v[112:113], v[160:161]
	s_nop 0
	v_mov_b32_dpp v166, v167 row_ror:15 row_mask:0xf bank_mask:0xf
	v_mov_b32_e32 v167, 0
	s_nop 1
	v_mov_b32_dpp v167, v199 row_ror:15 row_mask:0xf bank_mask:0xf
	v_cndmask_b32_e64 v199, v200, 0, vcc
	v_cndmask_b32_e64 v200, v195, 0, vcc
	v_pk_mul_f32 v[200:201], v[80:81], v[200:201]
	v_pk_mul_f32 v[198:199], v[82:83], v[198:199]
	v_pk_fma_f32 v[200:201], v[144:145], v[84:85], v[200:201]
	v_pk_fma_f32 v[198:199], v[146:147], v[86:87], v[198:199]
	v_pk_fma_f32 v[164:165], v[88:89], v[164:165], v[200:201]
	v_pk_fma_f32 v[166:167], v[90:91], v[166:167], v[198:199]
	v_pk_add_f32 v[164:165], v[92:93], v[164:165]
	v_pk_add_f32 v[166:167], v[94:95], v[166:167]
	s_and_saveexec_b64 s[28:29], s[46:47]
	s_xor_b64 s[28:29], exec, s[28:29]
	s_cbranch_execz .LBB1_383
; DI unsigned pack2(float a, float b) { f32x2 v = {a, b}; hwbf16x2 r = __builtin_convertvector(v, hwbf16x2); return __builtin_bit_cast(unsigned, r); }
; DI float silu_mul(float g, float v) { return g * v * __builtin_amdgcn_rcpf(1.0f + __builtin_amdgcn_exp2f(-LOG2E * g)); }
;     DI void operator()(const f32x4 (&acc)[2][2][4][2], const Unit& u, int wr, int wc, int fr, int fq) const {
;     ...
;                     const f32x4 v0 = acc[ai][1][m][0], v1 = acc[ai][1][m][1];
;                     u32x4 o;
;                     o[0] = pack2(silu_mul(gc[0][0], v0[0]), silu_mul(gc[0][1], v0[1])); o[1] = pack2(silu_mul(gc[0][2], v0[2]), silu_mul(gc[0][3], v0[3]));
;                     o[2] = pack2(silu_mul(gc[1][0], v1[0]), silu_mul(gc[1][1], v1[1])); o[3] = pack2(silu_mul(gc[1][2], v1[2]), silu_mul(gc[1][3], v1[3]));
;                     *(u32x4*)(ACT + (size_t)row * DFF + ch0) = o;
	v_mul_f32_e32 v195, 0xbfb8aa3b, v160
	v_exp_f32_e32 v195, v195
	v_mul_f32_e32 v196, 0xbfb8aa3b, v161
	v_exp_f32_e32 v196, v196
	v_pk_mul_f32 v[160:161], v[156:157], v[160:161]
	v_add_f32_e32 v195, 1.0, v195
	v_rcp_f32_e32 v198, v195
	v_add_f32_e32 v196, 1.0, v196
	v_mul_f32_e32 v195, 0xbfb8aa3b, v162
	v_rcp_f32_e32 v199, v196
	v_exp_f32_e32 v195, v195
	v_mul_f32_e32 v196, 0xbfb8aa3b, v163
	v_exp_f32_e32 v196, v196
	v_pk_mul_f32 v[160:161], v[160:161], v[198:199]
	v_add_f32_e32 v195, 1.0, v195
	v_rcp_f32_e32 v200, v195
	v_add_f32_e32 v195, 1.0, v196
	v_rcp_f32_e32 v201, v195
	v_cvt_pk_bf16_f32 v160, v160, v161
	v_mul_f32_e32 v161, 0xbfb8aa3b, v164
	v_exp_f32_e32 v195, v161
	v_mul_f32_e32 v161, 0xbfb8aa3b, v165
	v_exp_f32_e32 v196, v161
	v_pk_mul_f32 v[162:163], v[158:159], v[162:163]
	v_pk_mul_f32 v[164:165], v[152:153], v[164:165]
	v_pk_mul_f32 v[162:163], v[162:163], v[200:201]
	s_nop 0
	v_cvt_pk_bf16_f32 v161, v162, v163
	v_add_f32_e32 v162, 1.0, v195
	v_mul_f32_e32 v195, 0xbfb8aa3b, v166
	v_add_f32_e32 v163, 1.0, v196
	v_exp_f32_e32 v195, v195
	v_mul_f32_e32 v196, 0xbfb8aa3b, v167
	v_exp_f32_e32 v196, v196
	v_rcp_f32_e32 v162, v162
	v_add_f32_e32 v195, 1.0, v195
	v_rcp_f32_e32 v198, v195
	v_add_f32_e32 v195, 1.0, v196
	v_rcp_f32_e32 v163, v163
	v_rcp_f32_e32 v199, v195
	v_pk_mul_f32 v[166:167], v[154:155], v[166:167]
	v_pk_mul_f32 v[162:163], v[164:165], v[162:163]
	v_pk_mul_f32 v[164:165], v[166:167], v[198:199]
	v_cvt_pk_bf16_f32 v162, v162, v163
	v_cvt_pk_bf16_f32 v163, v164, v165
	v_mov_b64_e32 v[164:165], s[6:7]
	v_mad_i64_i32 v[164:165], s[42:43], v193, s30, v[164:165]
	v_lshl_add_u64 v[164:165], v[184:185], 1, v[164:165]
	global_store_dwordx4 v[164:165], v[160:163], off

;     DI const char* a(const Unit& u) const { return (const char*)(A + (size_t)u.pm * BM * lda); }
; #define PG8_BAR __builtin_amdgcn_s_barrier()
; template <class Map, class Epi>
; DI void gemm_phase(LAS unsigned char* lds, const Map& MP, const Epi& E, const int nM, const int nN, const int K, const int lda, const int ldb) {
;     ...
;         for (int t = 0; t < nt; t += 2) {
;             const bool last = (t == nt - 2);
;             const char* a1 = cA + (size_t)(t + 1) * kstep;
;             const char* a2 = last ? nA : cA + (size_t)(t + 2) * kstep; const char* b2 = last ? nB : cB + (size_t)(t + 2) * kstep;
;             const char* a3 = a2 + kstep; const char* b3 = b2 + kstep;
;             PG8_LDB(B0, 0, 0); PG8_SCHED; PG8_LDA(At, 0, 0); PG8_STAGE(PG8_SA(1, 1), a1 + hstepA, voffA);
;             PG8_WAIT_L(8); PG8_BAR; PG8_WAIT_L(0); PG8_MMA(0, 0, At, B0); PG8_BAR; PG8_SCHED;
;             PG8_LDB(B1, 0, 1); PG8_STAGE(PG8_SB(0, 0), b2, voffB);
;             PG8_BAR; PG8_WAIT_L(0); PG8_MMA(0, 1, At, B1); PG8_BAR;
;             PG8_LDA(At, 0, 1); PG8_STAGE(PG8_SA(0, 0), a2, voffA);
;             PG8_BAR; PG8_WAIT_L(0); PG8_MMA(1, 0, At, B0); PG8_BAR; PG8_SCHED;
;             PG8_STAGE(PG8_SB(0, 1), b2 + hstepB, voffB);
;             PG8_WAIT_V(6); PG8_BAR; PG8_MMA(1, 1, At, B1); PG8_BAR;
;             PG8_LDB(B0, 1, 0); PG8_SCHED; PG8_LDA(At, 1, 0); PG8_STAGE(PG8_SA(0, 1), a2 + hstepA, voffA);
;             PG8_WAIT_L(8); PG8_BAR; PG8_WAIT_L(0); PG8_MMA(0, 0, At, B0); PG8_BAR; PG8_SCHED;
;             PG8_LDB(B1, 1, 1); PG8_STAGE(PG8_SB(1, 0), b3, voffB);
;             PG8_BAR; PG8_WAIT_L(0); PG8_MMA(0, 1, At, B1); PG8_BAR;
;             PG8_LDA(At, 1, 1); PG8_STAGE(PG8_SA(1, 0), a3, voffA);
;             PG8_BAR; PG8_WAIT_L(0); PG8_MMA(1, 0, At, B0); PG8_BAR; PG8_SCHED;
;             PG8_STAGE(PG8_SB(1, 1), b3 + hstepB, voffB);
;             PG8_WAIT_V(6); PG8_BAR; PG8_MMA(1, 1, At, B1); PG8_BAR;
;         }
;         { int frr = fr, fqq = fq; asm volatile("" : "+v"(frr), "+v"(fqq)); E(acc, cur, wr, wc, frr, fqq); }
;         if (!has_next) break;
; #pragma unroll
;         for (int a = 0; a < 2; ++a)
; #pragma unroll
;             for (int b = 0; b < 2; ++b)
; #pragma unroll
;                 for (int m = 0; m < 4; ++m)
; #pragma unroll
;                     for (int n = 0; n < 2; ++n) acc[a][b][m][n] = (f32x4){0.f, 0.f, 0.f, 0.f};
.LBB1_549:
	s_add_u32 s5, s10, 0x100
	v_mov_b32_e32 v0, 0
	s_addc_u32 s38, s11, 0
	s_mov_b32 s3, -2
	v_mov_b32_e32 v1, v0
	v_mov_b32_e32 v2, v0
	v_mov_b32_e32 v3, v0
	v_mov_b32_e32 v4, v0
	v_mov_b32_e32 v5, v0
	v_mov_b32_e32 v6, v0
	v_mov_b32_e32 v7, v0
	v_mov_b32_e32 v16, v0
	v_mov_b32_e32 v17, v0
	v_mov_b32_e32 v18, v0
	v_mov_b32_e32 v19, v0
	v_mov_b32_e32 v20, v0
	v_mov_b32_e32 v21, v0
	v_mov_b32_e32 v22, v0
	v_mov_b32_e32 v23, v0
	v_mov_b32_e32 v32, v0
	v_mov_b32_e32 v33, v0
	v_mov_b32_e32 v34, v0
	v_mov_b32_e32 v35, v0
	v_mov_b32_e32 v36, v0
	v_mov_b32_e32 v37, v0
	v_mov_b32_e32 v38, v0
	v_mov_b32_e32 v39, v0
	v_mov_b32_e32 v48, v0
	v_mov_b32_e32 v49, v0
	v_mov_b32_e32 v50, v0
	v_mov_b32_e32 v51, v0
	v_mov_b32_e32 v52, v0
	v_mov_b32_e32 v53, v0
	v_mov_b32_e32 v54, v0
	v_mov_b32_e32 v55, v0
	v_mov_b32_e32 v8, v0
	v_mov_b32_e32 v9, v0
	v_mov_b32_e32 v10, v0
	v_mov_b32_e32 v11, v0
	v_mov_b32_e32 v12, v0
	v_mov_b32_e32 v13, v0
	v_mov_b32_e32 v14, v0
	v_mov_b32_e32 v15, v0
	v_mov_b32_e32 v24, v0
	v_mov_b32_e32 v25, v0
	v_mov_b32_e32 v26, v0
	v_mov_b32_e32 v27, v0
	v_mov_b32_e32 v28, v0
	v_mov_b32_e32 v29, v0
	v_mov_b32_e32 v30, v0
	v_mov_b32_e32 v31, v0
	v_mov_b32_e32 v40, v0
	v_mov_b32_e32 v41, v0
	v_mov_b32_e32 v42, v0
	v_mov_b32_e32 v43, v0
	v_mov_b32_e32 v44, v0
	v_mov_b32_e32 v45, v0
	v_mov_b32_e32 v46, v0
	v_mov_b32_e32 v47, v0
	v_mov_b32_e32 v56, v0
	v_mov_b32_e32 v57, v0
	v_mov_b32_e32 v58, v0
	v_mov_b32_e32 v59, v0
	v_mov_b32_e32 v60, v0
	v_mov_b32_e32 v61, v0
	v_mov_b32_e32 v62, v0
	v_mov_b32_e32 v63, v0
	v_mov_b32_e32 v64, v0
	v_mov_b32_e32 v65, v0
	v_mov_b32_e32 v66, v0
	v_mov_b32_e32 v67, v0
	v_mov_b32_e32 v68, v0
	v_mov_b32_e32 v69, v0
	v_mov_b32_e32 v70, v0
	v_mov_b32_e32 v71, v0
	v_mov_b32_e32 v80, v0
	v_mov_b32_e32 v81, v0
	v_mov_b32_e32 v82, v0
	v_mov_b32_e32 v83, v0
	v_mov_b32_e32 v84, v0
	v_mov_b32_e32 v85, v0
	v_mov_b32_e32 v86, v0
	v_mov_b32_e32 v87, v0
	v_mov_b32_e32 v96, v0
	v_mov_b32_e32 v97, v0
	v_mov_b32_e32 v98, v0
	v_mov_b32_e32 v99, v0
	v_mov_b32_e32 v100, v0
	v_mov_b32_e32 v101, v0
	v_mov_b32_e32 v102, v0
	v_mov_b32_e32 v103, v0
	v_mov_b32_e32 v112, v0
	v_mov_b32_e32 v113, v0
	v_mov_b32_e32 v114, v0
	v_mov_b32_e32 v115, v0
	v_mov_b32_e32 v116, v0
	v_mov_b32_e32 v117, v0
	v_mov_b32_e32 v118, v0
	v_mov_b32_e32 v119, v0
	v_mov_b32_e32 v72, v0
	v_mov_b32_e32 v73, v0
	v_mov_b32_e32 v74, v0
	v_mov_b32_e32 v75, v0
	v_mov_b32_e32 v76, v0
	v_mov_b32_e32 v77, v0
	v_mov_b32_e32 v78, v0
	v_mov_b32_e32 v79, v0
	v_mov_b32_e32 v88, v0
	v_mov_b32_e32 v89, v0
	v_mov_b32_e32 v90, v0
	v_mov_b32_e32 v91, v0
	v_mov_b32_e32 v92, v0
	v_mov_b32_e32 v93, v0
	v_mov_b32_e32 v94, v0
	v_mov_b32_e32 v95, v0
	v_mov_b32_e32 v104, v0
	v_mov_b32_e32 v105, v0
	v_mov_b32_e32 v106, v0
	v_mov_b32_e32 v107, v0
	v_mov_b32_e32 v108, v0
	v_mov_b32_e32 v109, v0
	v_mov_b32_e32 v110, v0
	v_mov_b32_e32 v111, v0
	v_mov_b32_e32 v120, v0
	v_mov_b32_e32 v121, v0
	v_mov_b32_e32 v122, v0
	v_mov_b32_e32 v123, v0
	v_mov_b32_e32 v124, v0
	v_mov_b32_e32 v125, v0
	v_mov_b32_e32 v126, v0
	v_mov_b32_e32 v127, v0
	ds_read_b128 v[152:155], v149
	ds_read_b128 v[156:159], v149 offset:1024
	ds_read_b128 v[160:163], v149 offset:2048
	ds_read_b128 v[164:167], v149 offset:3072
.LBB1_550:
	s_add_u32 s10, s8, 0x100
	s_addc_u32 s11, s9, 0
	s_cmpk_eq_i32 s3, 0x54
	s_cselect_b32 s15, s43, s11
	s_cselect_b32 s14, s42, s10
	s_cselect_b32 s13, s7, s38
	s_cselect_b32 s12, s6, s5
	s_add_i32 m0, s24, 0xc000
	ds_read_b128 v[168:171], v150
	ds_read_b128 v[172:175], v150 offset:1024
	ds_read_b128 v[176:179], v150 offset:2048
	ds_read_b128 v[180:183], v150 offset:3072
	ds_read_b128 v[184:187], v150 offset:4096
	ds_read_b128 v[188:191], v150 offset:5120
	ds_read_b128 v[192:195], v150 offset:6144
	ds_read_b128 v[198:201], v150 offset:7168
	global_load_lds_dwordx4 v138, s[8:9]
	s_add_i32 m0, s24, 0xe000
	s_nop 0
	global_load_lds_dwordx4 v136, s[8:9]
	s_waitcnt lgkmcnt(8)
	s_barrier
	s_setprio 1
	s_waitcnt lgkmcnt(7)
	v_mfma_f32_16x16x32_bf16 v[124:127], v[152:155], v[168:171], v[124:127]
	v_mfma_f32_16x16x32_bf16 v[120:123], v[160:163], v[168:171], v[120:123]
	s_waitcnt lgkmcnt(5)
	v_mfma_f32_16x16x32_bf16 v[108:111], v[152:155], v[176:179], v[108:111]
	v_mfma_f32_16x16x32_bf16 v[104:107], v[160:163], v[176:179], v[104:107]
	s_waitcnt lgkmcnt(3)
	v_mfma_f32_16x16x32_bf16 v[92:95], v[152:155], v[184:187], v[92:95]
	v_mfma_f32_16x16x32_bf16 v[88:91], v[160:163], v[184:187], v[88:91]
	s_waitcnt lgkmcnt(1)
	v_mfma_f32_16x16x32_bf16 v[76:79], v[152:155], v[192:195], v[76:79]
	v_mfma_f32_16x16x32_bf16 v[72:75], v[160:163], v[192:195], v[72:75]
	v_mfma_f32_16x16x32_bf16 v[124:127], v[156:159], v[172:175], v[124:127]
	v_mfma_f32_16x16x32_bf16 v[120:123], v[164:167], v[172:175], v[120:123]
	v_mfma_f32_16x16x32_bf16 v[108:111], v[156:159], v[180:183], v[108:111]
	v_mfma_f32_16x16x32_bf16 v[104:107], v[164:167], v[180:183], v[104:107]
	v_mfma_f32_16x16x32_bf16 v[92:95], v[156:159], v[188:191], v[92:95]
	v_mfma_f32_16x16x32_bf16 v[88:91], v[164:167], v[188:191], v[88:91]
	s_waitcnt lgkmcnt(0)
	v_mfma_f32_16x16x32_bf16 v[76:79], v[156:159], v[198:201], v[76:79]
	v_mfma_f32_16x16x32_bf16 v[72:75], v[164:167], v[198:201], v[72:75]
	s_setprio 0
	s_barrier
	s_add_i32 s8, s35, s22
	v_lshl_add_u64 v[144:145], s[12:13], 0, v[132:133]
	s_mov_b32 m0, s8
	ds_read_b128 v[202:205], v151
	ds_read_b128 v[206:209], v151 offset:1024
	ds_read_b128 v[210:213], v151 offset:2048
	ds_read_b128 v[214:217], v151 offset:3072
	global_load_lds_dwordx4 v[144:145], off
	v_lshl_add_u64 v[218:219], s[12:13], 0, v[128:129]
	s_add_i32 m0, s8, 0x2000
	s_nop 0
	global_load_lds_dwordx4 v[218:219], off
	s_barrier
; #define PG8_STAGE(bufoff, gbase, voff) do { _Pragma("unroll") for (int _i = 0; _i < 2; ++_i) \
;         __builtin_amdgcn_global_load_lds((const unsigned*)((const char*)(gbase) + (voff)[_i]), (LAS unsigned*)(lds + (bufoff) + ldsw + _i * 8192), 16, 0, 0); } while (0)
; #define PG8_LDA(dst, b, h) do { _Pragma("unroll") for (int m = 0; m < 4; ++m) _Pragma("unroll") for (int k = 0; k < 2; ++k) dst[m][k] = *(const LAS bf16x8*)(lds + PG8_SA(b, h) + aoff + m * 2048 + k * 1024); } while (0)
; #define PG8_LDB(dst, b, h) do { _Pragma("unroll") for (int n = 0; n < 2; ++n) _Pragma("unroll") for (int k = 0; k < 2; ++k) dst[n][k] = *(const LAS bf16x8*)(lds + PG8_SB(b, h) + boff + n * 2048 + k * 1024); } while (0)
; #define PG8_MMA(ai, bj, At, Bt) do { __builtin_amdgcn_s_setprio(1); _Pragma("unroll") for (int m = 0; m < 4; ++m) _Pragma("unroll") for (int n = 0; n < 2; ++n) _Pragma("unroll") for (int k = 0; k < 2; ++k) \
;         acc[ai][bj][m][n] = __builtin_amdgcn_mfma_f32_16x16x32_bf16(Bt[n][k], At[m][k], acc[ai][bj][m][n], 0, 0, 0); __builtin_amdgcn_s_setprio(0); } while (0)
; #define PG8_WAIT_V(n) asm volatile("s_waitcnt vmcnt(" #n ")" ::: "memory")
; #define PG8_WAIT_L(n) asm volatile("s_waitcnt lgkmcnt(" #n ")" ::: "memory")
; #define PG8_BAR __builtin_amdgcn_s_barrier()
; #define PG8_SCHED __builtin_amdgcn_sched_barrier(0)
; template <class Map, class Epi>
; DI void gemm_phase(LAS unsigned char* lds, const Map& MP, const Epi& E, const int nM, const int nN, const int K, const int lda, const int ldb) {
;     ...
;             PG8_BAR; PG8_WAIT_L(0); PG8_MMA(0, 1, At, B1); PG8_BAR;
;             PG8_LDA(At, 0, 1); PG8_STAGE(PG8_SA(0, 0), a2, voffA);
;             PG8_BAR; PG8_WAIT_L(0); PG8_MMA(1, 0, At, B0); PG8_BAR; PG8_SCHED;
;             PG8_STAGE(PG8_SB(0, 1), b2 + hstepB, voffB);
;             PG8_WAIT_V(6); PG8_BAR; PG8_MMA(1, 1, At, B1); PG8_BAR;
;             PG8_LDB(B0, 1, 0); PG8_SCHED; PG8_LDA(At, 1, 0); PG8_STAGE(PG8_SA(0, 1), a2 + hstepA, voffA);
;             PG8_WAIT_L(8); PG8_BAR; PG8_WAIT_L(0); PG8_MMA(0, 0, At, B0); PG8_BAR; PG8_SCHED;
	s_setprio 1
	s_waitcnt lgkmcnt(3)
	v_mfma_f32_16x16x32_bf16 v[116:119], v[202:205], v[168:171], v[116:119]
	s_waitcnt lgkmcnt(1)
	v_mfma_f32_16x16x32_bf16 v[112:115], v[210:213], v[168:171], v[112:115]
	v_mfma_f32_16x16x32_bf16 v[100:103], v[202:205], v[176:179], v[100:103]
	v_mfma_f32_16x16x32_bf16 v[96:99], v[210:213], v[176:179], v[96:99]
	v_mfma_f32_16x16x32_bf16 v[84:87], v[202:205], v[184:187], v[84:87]
	v_mfma_f32_16x16x32_bf16 v[80:83], v[210:213], v[184:187], v[80:83]
	v_mfma_f32_16x16x32_bf16 v[68:71], v[202:205], v[192:195], v[68:71]
	v_mfma_f32_16x16x32_bf16 v[64:67], v[210:213], v[192:195], v[64:67]
	v_mfma_f32_16x16x32_bf16 v[116:119], v[206:209], v[172:175], v[116:119]
	s_waitcnt lgkmcnt(0)
	v_mfma_f32_16x16x32_bf16 v[112:115], v[214:217], v[172:175], v[112:115]
	v_mfma_f32_16x16x32_bf16 v[100:103], v[206:209], v[180:183], v[100:103]
	v_mfma_f32_16x16x32_bf16 v[96:99], v[214:217], v[180:183], v[96:99]
	v_mfma_f32_16x16x32_bf16 v[84:87], v[206:209], v[188:191], v[84:87]
	v_mfma_f32_16x16x32_bf16 v[80:83], v[214:217], v[188:191], v[80:83]
	v_mfma_f32_16x16x32_bf16 v[68:71], v[206:209], v[198:201], v[68:71]
	v_mfma_f32_16x16x32_bf16 v[64:67], v[214:217], v[198:201], v[64:67]
	s_setprio 0
	s_mov_b32 m0, s24
	v_lshl_add_u64 v[220:221], s[14:15], 0, v[134:135]
	s_barrier
	ds_read_b128 v[168:171], v150 offset:16384
	ds_read_b128 v[172:175], v150 offset:17408
	ds_read_b128 v[176:179], v150 offset:18432
	ds_read_b128 v[180:183], v150 offset:19456
	ds_read_b128 v[184:187], v150 offset:20480
	ds_read_b128 v[188:191], v150 offset:21504
	ds_read_b128 v[192:195], v150 offset:22528
	ds_read_b128 v[198:201], v150 offset:23552
	global_load_lds_dwordx4 v[220:221], off
	v_lshl_add_u64 v[222:223], s[14:15], 0, v[130:131]
	s_mov_b32 m0, s25
	s_nop 0
	global_load_lds_dwordx4 v[222:223], off
	s_waitcnt vmcnt(10)
	s_barrier
	s_setprio 1
	s_waitcnt lgkmcnt(7)
	v_mfma_f32_16x16x32_bf16 v[60:63], v[152:155], v[168:171], v[60:63]
	v_mfma_f32_16x16x32_bf16 v[56:59], v[160:163], v[168:171], v[56:59]
	s_waitcnt lgkmcnt(5)
	v_mfma_f32_16x16x32_bf16 v[44:47], v[152:155], v[176:179], v[44:47]
	v_mfma_f32_16x16x32_bf16 v[40:43], v[160:163], v[176:179], v[40:43]
	s_waitcnt lgkmcnt(3)
	v_mfma_f32_16x16x32_bf16 v[28:31], v[152:155], v[184:187], v[28:31]
	v_mfma_f32_16x16x32_bf16 v[24:27], v[160:163], v[184:187], v[24:27]
	s_waitcnt lgkmcnt(1)
	v_mfma_f32_16x16x32_bf16 v[12:15], v[152:155], v[192:195], v[12:15]
	v_mfma_f32_16x16x32_bf16 v[8:11], v[160:163], v[192:195], v[8:11]
	v_mfma_f32_16x16x32_bf16 v[60:63], v[156:159], v[172:175], v[60:63]
	v_mfma_f32_16x16x32_bf16 v[56:59], v[164:167], v[172:175], v[56:59]
	v_mfma_f32_16x16x32_bf16 v[44:47], v[156:159], v[180:183], v[44:47]
	v_mfma_f32_16x16x32_bf16 v[40:43], v[164:167], v[180:183], v[40:43]
	v_mfma_f32_16x16x32_bf16 v[28:31], v[156:159], v[188:191], v[28:31]
	v_mfma_f32_16x16x32_bf16 v[24:27], v[164:167], v[188:191], v[24:27]
	s_waitcnt lgkmcnt(0)
	v_mfma_f32_16x16x32_bf16 v[12:15], v[156:159], v[198:201], v[12:15]
	v_mfma_f32_16x16x32_bf16 v[8:11], v[164:167], v[198:201], v[8:11]
	s_setprio 0
	s_barrier
	s_add_u32 s8, s12, 0x160000
	s_addc_u32 s9, s13, 0
	s_add_i32 s39, s36, s22
	s_mov_b32 m0, s39
	s_nop 0
	global_load_lds_dwordx4 v132, s[8:9]
	s_add_i32 m0, s39, 0x2000
	s_nop 0
	global_load_lds_dwordx4 v128, s[8:9]
	s_waitcnt vmcnt(6)
	s_barrier
	s_setprio 1
	v_mfma_f32_16x16x32_bf16 v[52:55], v[202:205], v[168:171], v[52:55]
	v_mfma_f32_16x16x32_bf16 v[48:51], v[210:213], v[168:171], v[48:51]
	s_add_i32 s39, 0, 0x18000
	v_add_u32_e32 v164, s39, v148
	ds_read_b128 v[152:155], v164
	v_mfma_f32_16x16x32_bf16 v[36:39], v[202:205], v[176:179], v[36:39]
	v_mfma_f32_16x16x32_bf16 v[32:35], v[210:213], v[176:179], v[32:35]
	ds_read_b128 v[156:159], v164 offset:1024
	v_mfma_f32_16x16x32_bf16 v[20:23], v[202:205], v[184:187], v[20:23]
	v_mfma_f32_16x16x32_bf16 v[16:19], v[210:213], v[184:187], v[16:19]
	ds_read_b128 v[160:163], v164 offset:2048
	v_mfma_f32_16x16x32_bf16 v[4:7], v[202:205], v[192:195], v[4:7]
	v_mfma_f32_16x16x32_bf16 v[0:3], v[210:213], v[192:195], v[0:3]
	ds_read_b128 v[164:167], v164 offset:3072
	v_mfma_f32_16x16x32_bf16 v[52:55], v[206:209], v[172:175], v[52:55]
	v_mfma_f32_16x16x32_bf16 v[48:51], v[214:217], v[172:175], v[48:51]
	v_mfma_f32_16x16x32_bf16 v[36:39], v[206:209], v[180:183], v[36:39]
	v_mfma_f32_16x16x32_bf16 v[32:35], v[214:217], v[180:183], v[32:35]
	v_mfma_f32_16x16x32_bf16 v[20:23], v[206:209], v[188:191], v[20:23]
	v_mfma_f32_16x16x32_bf16 v[16:19], v[214:217], v[188:191], v[16:19]
	v_mfma_f32_16x16x32_bf16 v[4:7], v[206:209], v[198:201], v[4:7]
	v_mfma_f32_16x16x32_bf16 v[0:3], v[214:217], v[198:201], v[0:3]
	s_setprio 0
	s_barrier
	s_add_u32 s8, s14, 0x160000
	s_addc_u32 s9, s15, 0
	s_mov_b32 m0, s26
	ds_read_b128 v[168:171], v150 offset:32768
	ds_read_b128 v[172:175], v150 offset:33792
	ds_read_b128 v[176:179], v150 offset:34816
	ds_read_b128 v[180:183], v150 offset:35840
	ds_read_b128 v[184:187], v150 offset:36864
	ds_read_b128 v[188:191], v150 offset:37888
	ds_read_b128 v[192:195], v150 offset:38912
	ds_read_b128 v[198:201], v150 offset:39936
	global_load_lds_dwordx4 v134, s[8:9]
	s_mov_b32 m0, s27
	s_nop 0
	global_load_lds_dwordx4 v130, s[8:9]
	s_waitcnt lgkmcnt(8)
	s_barrier
; #define PG8_STAGE(bufoff, gbase, voff) do { _Pragma("unroll") for (int _i = 0; _i < 2; ++_i) \
;         __builtin_amdgcn_global_load_lds((const unsigned*)((const char*)(gbase) + (voff)[_i]), (LAS unsigned*)(lds + (bufoff) + ldsw + _i * 8192), 16, 0, 0); } while (0)
; #define PG8_LDA(dst, b, h) do { _Pragma("unroll") for (int m = 0; m < 4; ++m) _Pragma("unroll") for (int k = 0; k < 2; ++k) dst[m][k] = *(const LAS bf16x8*)(lds + PG8_SA(b, h) + aoff + m * 2048 + k * 1024); } while (0)
; #define PG8_LDB(dst, b, h) do { _Pragma("unroll") for (int n = 0; n < 2; ++n) _Pragma("unroll") for (int k = 0; k < 2; ++k) dst[n][k] = *(const LAS bf16x8*)(lds + PG8_SB(b, h) + boff + n * 2048 + k * 1024); } while (0)
; #define PG8_MMA(ai, bj, At, Bt) do { __builtin_amdgcn_s_setprio(1); _Pragma("unroll") for (int m = 0; m < 4; ++m) _Pragma("unroll") for (int n = 0; n < 2; ++n) _Pragma("unroll") for (int k = 0; k < 2; ++k) \
;         acc[ai][bj][m][n] = __builtin_amdgcn_mfma_f32_16x16x32_bf16(Bt[n][k], At[m][k], acc[ai][bj][m][n], 0, 0, 0); __builtin_amdgcn_s_setprio(0); } while (0)
; #define PG8_WAIT_V(n) asm volatile("s_waitcnt vmcnt(" #n ")" ::: "memory")
; #define PG8_WAIT_L(n) asm volatile("s_waitcnt lgkmcnt(" #n ")" ::: "memory")
; #define PG8_BAR __builtin_amdgcn_s_barrier()
; #define PG8_SCHED __builtin_amdgcn_sched_barrier(0)
; template <class Map, class Epi>
; DI void gemm_phase(LAS unsigned char* lds, const Map& MP, const Epi& E, const int nM, const int nN, const int K, const int lda, const int ldb) {
;     ...
;             PG8_WAIT_L(8); PG8_BAR; PG8_WAIT_L(0); PG8_MMA(0, 0, At, B0); PG8_BAR; PG8_SCHED;
;             PG8_LDB(B1, 1, 1); PG8_STAGE(PG8_SB(1, 0), b3, voffB);
;             PG8_BAR; PG8_WAIT_L(0); PG8_MMA(0, 1, At, B1); PG8_BAR;
;             PG8_LDA(At, 1, 1); PG8_STAGE(PG8_SA(1, 0), a3, voffA);
;             PG8_BAR; PG8_WAIT_L(0); PG8_MMA(1, 0, At, B0); PG8_BAR; PG8_SCHED;
;             PG8_STAGE(PG8_SB(1, 1), b3 + hstepB, voffB);
;             PG8_WAIT_V(6); PG8_BAR; PG8_MMA(1, 1, At, B1); PG8_BAR;
	s_setprio 1
	s_waitcnt lgkmcnt(7)
	v_mfma_f32_16x16x32_bf16 v[124:127], v[152:155], v[168:171], v[124:127]
	v_mfma_f32_16x16x32_bf16 v[120:123], v[160:163], v[168:171], v[120:123]
	s_waitcnt lgkmcnt(5)
	v_mfma_f32_16x16x32_bf16 v[108:111], v[152:155], v[176:179], v[108:111]
	v_mfma_f32_16x16x32_bf16 v[104:107], v[160:163], v[176:179], v[104:107]
	s_waitcnt lgkmcnt(3)
	v_mfma_f32_16x16x32_bf16 v[92:95], v[152:155], v[184:187], v[92:95]
	v_mfma_f32_16x16x32_bf16 v[88:91], v[160:163], v[184:187], v[88:91]
	s_waitcnt lgkmcnt(1)
	v_mfma_f32_16x16x32_bf16 v[76:79], v[152:155], v[192:195], v[76:79]
	v_mfma_f32_16x16x32_bf16 v[72:75], v[160:163], v[192:195], v[72:75]
	v_mfma_f32_16x16x32_bf16 v[124:127], v[156:159], v[172:175], v[124:127]
	v_mfma_f32_16x16x32_bf16 v[120:123], v[164:167], v[172:175], v[120:123]
	v_mfma_f32_16x16x32_bf16 v[108:111], v[156:159], v[180:183], v[108:111]
	v_mfma_f32_16x16x32_bf16 v[104:107], v[164:167], v[180:183], v[104:107]
	v_mfma_f32_16x16x32_bf16 v[92:95], v[156:159], v[188:191], v[92:95]
	v_mfma_f32_16x16x32_bf16 v[88:91], v[164:167], v[188:191], v[88:91]
	s_waitcnt lgkmcnt(0)
	v_mfma_f32_16x16x32_bf16 v[76:79], v[156:159], v[198:201], v[76:79]
	v_mfma_f32_16x16x32_bf16 v[72:75], v[164:167], v[198:201], v[72:75]
	s_setprio 0
	s_barrier
	s_add_i32 s14, 0, 0x1c000
	s_add_i32 s8, s39, s22
	v_add_u32_e32 v196, s14, v148
	v_lshl_add_u64 v[144:145], v[144:145], 0, s[52:53]
	s_mov_b32 m0, s8
	ds_read_b128 v[202:205], v196
	ds_read_b128 v[206:209], v196 offset:1024
	ds_read_b128 v[210:213], v196 offset:2048
	ds_read_b128 v[214:217], v196 offset:3072
	global_load_lds_dwordx4 v[144:145], off
	v_lshl_add_u64 v[144:145], v[218:219], 0, s[52:53]
	s_add_i32 m0, s8, 0x2000
	s_nop 0
	global_load_lds_dwordx4 v[144:145], off
	s_barrier
	s_setprio 1
	s_waitcnt lgkmcnt(3)
	v_mfma_f32_16x16x32_bf16 v[116:119], v[202:205], v[168:171], v[116:119]
	s_waitcnt lgkmcnt(1)
	v_mfma_f32_16x16x32_bf16 v[112:115], v[210:213], v[168:171], v[112:115]
	v_mfma_f32_16x16x32_bf16 v[100:103], v[202:205], v[176:179], v[100:103]
	v_mfma_f32_16x16x32_bf16 v[96:99], v[210:213], v[176:179], v[96:99]
	v_mfma_f32_16x16x32_bf16 v[84:87], v[202:205], v[184:187], v[84:87]
	v_mfma_f32_16x16x32_bf16 v[80:83], v[210:213], v[184:187], v[80:83]
	v_mfma_f32_16x16x32_bf16 v[68:71], v[202:205], v[192:195], v[68:71]
	v_mfma_f32_16x16x32_bf16 v[64:67], v[210:213], v[192:195], v[64:67]
	v_mfma_f32_16x16x32_bf16 v[116:119], v[206:209], v[172:175], v[116:119]
	s_waitcnt lgkmcnt(0)
	v_mfma_f32_16x16x32_bf16 v[112:115], v[214:217], v[172:175], v[112:115]
	v_mfma_f32_16x16x32_bf16 v[100:103], v[206:209], v[180:183], v[100:103]
	v_mfma_f32_16x16x32_bf16 v[96:99], v[214:217], v[180:183], v[96:99]
	v_mfma_f32_16x16x32_bf16 v[84:87], v[206:209], v[188:191], v[84:87]
	v_mfma_f32_16x16x32_bf16 v[80:83], v[214:217], v[188:191], v[80:83]
	v_mfma_f32_16x16x32_bf16 v[68:71], v[206:209], v[198:201], v[68:71]
	v_mfma_f32_16x16x32_bf16 v[64:67], v[214:217], v[198:201], v[64:67]
	s_setprio 0
	s_mov_b32 m0, s30
	v_lshl_add_u64 v[144:145], v[220:221], 0, s[52:53]
	s_barrier
	ds_read_b128 v[168:171], v150 offset:49152
	ds_read_b128 v[172:175], v150 offset:50176
	ds_read_b128 v[176:179], v150 offset:51200
	ds_read_b128 v[180:183], v150 offset:52224
	ds_read_b128 v[184:187], v150 offset:53248
	ds_read_b128 v[188:191], v150 offset:54272
	ds_read_b128 v[192:195], v150 offset:55296
	ds_read_b128 v[198:201], v150 offset:56320
	global_load_lds_dwordx4 v[144:145], off
	v_lshl_add_u64 v[144:145], v[222:223], 0, s[52:53]
	s_mov_b32 m0, s31
	s_nop 0
	global_load_lds_dwordx4 v[144:145], off
	s_waitcnt vmcnt(10)
	s_barrier
	s_setprio 1
	s_waitcnt lgkmcnt(7)
	v_mfma_f32_16x16x32_bf16 v[60:63], v[152:155], v[168:171], v[60:63]
	v_mfma_f32_16x16x32_bf16 v[56:59], v[160:163], v[168:171], v[56:59]
	s_waitcnt lgkmcnt(5)
	v_mfma_f32_16x16x32_bf16 v[44:47], v[152:155], v[176:179], v[44:47]
	v_mfma_f32_16x16x32_bf16 v[40:43], v[160:163], v[176:179], v[40:43]
	s_waitcnt lgkmcnt(3)
	v_mfma_f32_16x16x32_bf16 v[28:31], v[152:155], v[184:187], v[28:31]
	v_mfma_f32_16x16x32_bf16 v[24:27], v[160:163], v[184:187], v[24:27]
	s_waitcnt lgkmcnt(1)
	v_mfma_f32_16x16x32_bf16 v[12:15], v[152:155], v[192:195], v[12:15]
	v_mfma_f32_16x16x32_bf16 v[8:11], v[160:163], v[192:195], v[8:11]
	v_mfma_f32_16x16x32_bf16 v[60:63], v[156:159], v[172:175], v[60:63]
	v_mfma_f32_16x16x32_bf16 v[56:59], v[164:167], v[172:175], v[56:59]
	v_mfma_f32_16x16x32_bf16 v[44:47], v[156:159], v[180:183], v[44:47]
	v_mfma_f32_16x16x32_bf16 v[40:43], v[164:167], v[180:183], v[40:43]
	v_mfma_f32_16x16x32_bf16 v[28:31], v[156:159], v[188:191], v[28:31]
	v_mfma_f32_16x16x32_bf16 v[24:27], v[164:167], v[188:191], v[24:27]
	s_waitcnt lgkmcnt(0)
	v_mfma_f32_16x16x32_bf16 v[12:15], v[156:159], v[198:201], v[12:15]
	v_mfma_f32_16x16x32_bf16 v[8:11], v[164:167], v[198:201], v[8:11]
	s_setprio 0
	s_barrier
	s_add_u32 s8, s12, 0x160080
	s_addc_u32 s9, s13, 0
	s_add_i32 s12, s14, s22
	s_mov_b32 m0, s12
	s_nop 0
	global_load_lds_dwordx4 v132, s[8:9]
	s_add_i32 m0, s12, 0x2000
	s_nop 0
	global_load_lds_dwordx4 v128, s[8:9]
	s_waitcnt vmcnt(6)
	s_barrier
; DI unsigned pack2(float a, float b) { f32x2 v = {a, b}; hwbf16x2 r = __builtin_convertvector(v, hwbf16x2); return __builtin_bit_cast(unsigned, r); }
; DI float bflo(unsigned w) { return __uint_as_float(w << 16); }
; DI float bfhi(unsigned w) { return __uint_as_float(w & 0xffff0000u); }
; #define PG8_MMA(ai, bj, At, Bt) do { __builtin_amdgcn_s_setprio(1); _Pragma("unroll") for (int m = 0; m < 4; ++m) _Pragma("unroll") for (int n = 0; n < 2; ++n) _Pragma("unroll") for (int k = 0; k < 2; ++k) \
;         acc[ai][bj][m][n] = __builtin_amdgcn_mfma_f32_16x16x32_bf16(Bt[n][k], At[m][k], acc[ai][bj][m][n], 0, 0, 0); __builtin_amdgcn_s_setprio(0); } while (0)
; #define PG8_WAIT_V(n) asm volatile("s_waitcnt vmcnt(" #n ")" ::: "memory")
;     DI void operator()(const f32x4 (&acc)[2][2][4][2], const Unit& u, int wr, int wc, int fr, int fq) const {
;     ...
;         for (int ai = 0; ai < 2; ++ai)
; #pragma unroll
;             for (int m = 0; m < 4; ++m) { const size_t ro = (size_t)(row0 + ai * HALF + m * 16) * D + col0;
; #pragma unroll
;                 for (int bj = 0; bj < 2; ++bj) {
;                     f32x4 x0, x1;
;                     if constexpr (IB) { const u32x4 w = *(const u32x4*)((const bf16_t*)Xin + ro + bj * HALF);
;                         x0 = (f32x4){bflo(w[0]), bfhi(w[0]), bflo(w[1]), bfhi(w[1])}; x1 = (f32x4){bflo(w[2]), bfhi(w[2]), bflo(w[3]), bfhi(w[3])}; }
;                     else { x0 = *(const f32x4*)((const float*)Xin + ro + bj * HALF); x1 = *(const f32x4*)((const float*)Xin + ro + bj * HALF + 4); }
;                     x0 += acc[ai][bj][m][0] * sc[bj][0]; x1 += acc[ai][bj][m][1] * sc[bj][1];
;                     if constexpr (OB) { u32x4 o; o[0] = pack2(x0[0], x0[1]); o[1] = pack2(x0[2], x0[3]); o[2] = pack2(x1[0], x1[1]); o[3] = pack2(x1[2], x1[3]);
;                         *(u32x4*)((bf16_t*)Xout + ro + bj * HALF) = o; }
;                     else { *(f32x4*)((float*)Xout + ro + bj * HALF) = x0; *(f32x4*)((float*)Xout + ro + bj * HALF + 4) = x1; } } }
; template <class Map, class Epi>
; DI void gemm_phase(LAS unsigned char* lds, const Map& MP, const Epi& E, const int nM, const int nN, const int K, const int lda, const int ldb) {
;     ...
;             PG8_WAIT_V(6); PG8_BAR; PG8_MMA(1, 1, At, B1); PG8_BAR;
;         }
;         { int frr = fr, fqq = fq; asm volatile("" : "+v"(frr), "+v"(fqq)); E(acc, cur, wr, wc, frr, fqq); }
	s_setprio 1
	v_mfma_f32_16x16x32_bf16 v[52:55], v[202:205], v[168:171], v[52:55]
	v_mfma_f32_16x16x32_bf16 v[48:51], v[210:213], v[168:171], v[48:51]
	ds_read_b128 v[152:155], v149
	v_mfma_f32_16x16x32_bf16 v[36:39], v[202:205], v[176:179], v[36:39]
	v_mfma_f32_16x16x32_bf16 v[32:35], v[210:213], v[176:179], v[32:35]
	ds_read_b128 v[156:159], v149 offset:1024
	v_mfma_f32_16x16x32_bf16 v[20:23], v[202:205], v[184:187], v[20:23]
	v_mfma_f32_16x16x32_bf16 v[16:19], v[210:213], v[184:187], v[16:19]
	ds_read_b128 v[160:163], v149 offset:2048
	v_mfma_f32_16x16x32_bf16 v[4:7], v[202:205], v[192:195], v[4:7]
	v_mfma_f32_16x16x32_bf16 v[0:3], v[210:213], v[192:195], v[0:3]
	ds_read_b128 v[164:167], v149 offset:3072
	v_mfma_f32_16x16x32_bf16 v[52:55], v[206:209], v[172:175], v[52:55]
	v_mfma_f32_16x16x32_bf16 v[48:51], v[214:217], v[172:175], v[48:51]
	v_mfma_f32_16x16x32_bf16 v[36:39], v[206:209], v[180:183], v[36:39]
	v_mfma_f32_16x16x32_bf16 v[32:35], v[214:217], v[180:183], v[32:35]
	v_mfma_f32_16x16x32_bf16 v[20:23], v[206:209], v[188:191], v[20:23]
	v_mfma_f32_16x16x32_bf16 v[16:19], v[214:217], v[188:191], v[16:19]
	v_mfma_f32_16x16x32_bf16 v[4:7], v[206:209], v[198:201], v[4:7]
	v_mfma_f32_16x16x32_bf16 v[0:3], v[214:217], v[198:201], v[0:3]
	s_setprio 0
	s_add_i32 s3, s3, 2
	s_add_u32 s5, s5, 0x100
	s_addc_u32 s38, s38, 0
	s_cmpk_gt_u32 s3, 0x55
	s_mov_b64 s[8:9], s[10:11]
	s_barrier
	s_cbranch_scc0 .LBB1_550
	s_waitcnt lgkmcnt(0)
	v_mov_b32_e32 v144, v146
	v_mov_b32_e32 v152, v147
	s_lshl_b32 s2, s2, 8
	s_add_i32 s2, s2, s29
	s_lshl_b32 s3, s4, 8
	v_add_u32_e32 v152, s2, v152
	s_or_b32 s3, s3, s54
	v_ashrrev_i32_e32 v153, 31, v152
	v_lshl_add_u32 v144, v144, 3, s3
	v_lshlrev_b64 v[152:153], 12, v[152:153]
	v_ashrrev_i32_e32 v145, 31, v144
	v_lshl_add_u64 v[152:153], s[46:47], 0, v[152:153]
	v_lshl_add_u64 v[144:145], v[144:145], 1, v[152:153]
	global_load_dwordx4 v[160:163], v[144:145], off
	global_load_dwordx4 v[164:167], v[144:145], off offset:256
	s_mov_b64 s[98:99], 0x10000
	v_lshl_add_u64 v[154:155], v[144:145], 0, s[98:99]
	global_load_dwordx4 v[168:171], v[154:155], off
	global_load_dwordx4 v[172:175], v[154:155], off offset:256
	s_mov_b64 s[98:99], 0x20000
	v_lshl_add_u64 v[154:155], v[144:145], 0, s[98:99]
	global_load_dwordx4 v[176:179], v[154:155], off
	global_load_dwordx4 v[180:183], v[154:155], off offset:256
	s_mov_b64 s[98:99], 0x30000
	v_lshl_add_u64 v[154:155], v[144:145], 0, s[98:99]
	global_load_dwordx4 v[184:187], v[154:155], off
	global_load_dwordx4 v[188:191], v[154:155], off offset:256
	s_mov_b64 s[98:99], 0x80000
	v_lshl_add_u64 v[154:155], v[144:145], 0, s[98:99]
	global_load_dwordx4 v[192:195], v[154:155], off
	global_load_dwordx4 v[198:201], v[154:155], off offset:256
	s_mov_b64 s[98:99], 0x90000
	v_lshl_add_u64 v[154:155], v[144:145], 0, s[98:99]
	global_load_dwordx4 v[202:205], v[154:155], off
	global_load_dwordx4 v[206:209], v[154:155], off offset:256
	s_mov_b64 s[98:99], 0xa0000
	v_lshl_add_u64 v[154:155], v[144:145], 0, s[98:99]
	global_load_dwordx4 v[210:213], v[154:155], off
	global_load_dwordx4 v[214:217], v[154:155], off offset:256
	s_mov_b64 s[98:99], 0xb0000
	v_lshl_add_u64 v[154:155], v[144:145], 0, s[98:99]
	global_load_dwordx4 v[248:251], v[154:155], off
	global_load_dwordx4 v[252:255], v[154:155], off offset:256
	s_waitcnt vmcnt(15)
	s_nop 1
	v_mov_b32_e32 v152, v160
	v_mov_b32_e32 v153, v161
	v_mov_b32_e32 v154, v162
	v_mov_b32_e32 v155, v163
	s_mov_b64 s[2:3], 0x10000
	s_mov_b32 s4, s37
	s_mov_b64 s[10:11], s[6:7]
	s_mov_b64 s[8:9], s[42:43]
	s_waitcnt lgkmcnt(0)
	v_lshlrev_b32_e32 v156, 16, v152
	v_and_b32_e32 v157, 0xffff0000, v152
	v_lshlrev_b32_e32 v152, 16, v153
	v_and_b32_e32 v153, 0xffff0000, v153
	v_lshlrev_b32_e32 v158, 16, v154
	v_and_b32_e32 v159, 0xffff0000, v154
	v_lshlrev_b32_e32 v154, 16, v155
	v_and_b32_e32 v155, 0xffff0000, v155
	v_pk_add_f32 v[126:127], v[126:127], v[152:153]
	v_pk_add_f32 v[124:125], v[124:125], v[156:157]
	v_pk_add_f32 v[152:153], v[122:123], v[154:155]
	v_pk_add_f32 v[122:123], v[120:121], v[158:159]
	v_cvt_pk_bf16_f32 v120, v124, v125
	v_cvt_pk_bf16_f32 v121, v126, v127
	v_cvt_pk_bf16_f32 v122, v122, v123
	v_cvt_pk_bf16_f32 v123, v152, v153
	global_store_dwordx4 v[144:145], v[120:123], off
	s_waitcnt vmcnt(15)
	s_nop 1
	v_mov_b32_e32 v120, v164
	v_mov_b32_e32 v121, v165
	v_mov_b32_e32 v122, v166
	v_mov_b32_e32 v123, v167
	s_waitcnt lgkmcnt(0)
	v_lshlrev_b32_e32 v124, 16, v120
	v_and_b32_e32 v125, 0xffff0000, v120
	v_lshlrev_b32_e32 v120, 16, v121
	v_and_b32_e32 v121, 0xffff0000, v121
	v_lshlrev_b32_e32 v126, 16, v122
	v_and_b32_e32 v127, 0xffff0000, v122
	v_lshlrev_b32_e32 v122, 16, v123
	v_and_b32_e32 v123, 0xffff0000, v123
	v_pk_add_f32 v[116:117], v[116:117], v[124:125]
	v_pk_add_f32 v[118:119], v[118:119], v[120:121]
	v_pk_add_f32 v[120:121], v[114:115], v[122:123]
	v_pk_add_f32 v[114:115], v[112:113], v[126:127]
	v_cvt_pk_bf16_f32 v112, v116, v117
	v_lshl_add_u64 v[116:117], v[144:145], 0, s[2:3]
	s_mov_b32 s2, 0x10000
	v_cvt_pk_bf16_f32 v113, v118, v119
	v_add_co_u32_e32 v118, vcc, s2, v144
	v_cvt_pk_bf16_f32 v114, v114, v115
	v_cvt_pk_bf16_f32 v115, v120, v121
	v_addc_co_u32_e32 v119, vcc, 0, v145, vcc
	global_store_dwordx4 v[144:145], v[112:115], off offset:256
	s_waitcnt vmcnt(15)
	s_nop 1
	v_mov_b32_e32 v112, v168
	v_mov_b32_e32 v113, v169
	v_mov_b32_e32 v114, v170
	v_mov_b32_e32 v115, v171
	s_mov_b64 s[2:3], 0x20000
	s_waitcnt lgkmcnt(0)
; DI unsigned pack2(float a, float b) { f32x2 v = {a, b}; hwbf16x2 r = __builtin_convertvector(v, hwbf16x2); return __builtin_bit_cast(unsigned, r); }
; DI float bflo(unsigned w) { return __uint_as_float(w << 16); }
; DI float bfhi(unsigned w) { return __uint_as_float(w & 0xffff0000u); }
;     DI void operator()(const f32x4 (&acc)[2][2][4][2], const Unit& u, int wr, int wc, int fr, int fq) const {
;     ...
;         for (int ai = 0; ai < 2; ++ai)
; #pragma unroll
;             for (int m = 0; m < 4; ++m) { const size_t ro = (size_t)(row0 + ai * HALF + m * 16) * D + col0;
; #pragma unroll
;                 for (int bj = 0; bj < 2; ++bj) {
;                     f32x4 x0, x1;
;                     if constexpr (IB) { const u32x4 w = *(const u32x4*)((const bf16_t*)Xin + ro + bj * HALF);
;                         x0 = (f32x4){bflo(w[0]), bfhi(w[0]), bflo(w[1]), bfhi(w[1])}; x1 = (f32x4){bflo(w[2]), bfhi(w[2]), bflo(w[3]), bfhi(w[3])}; }
;                     else { x0 = *(const f32x4*)((const float*)Xin + ro + bj * HALF); x1 = *(const f32x4*)((const float*)Xin + ro + bj * HALF + 4); }
;                     x0 += acc[ai][bj][m][0] * sc[bj][0]; x1 += acc[ai][bj][m][1] * sc[bj][1];
;                     if constexpr (OB) { u32x4 o; o[0] = pack2(x0[0], x0[1]); o[1] = pack2(x0[2], x0[3]); o[2] = pack2(x1[0], x1[1]); o[3] = pack2(x1[2], x1[3]);
;                         *(u32x4*)((bf16_t*)Xout + ro + bj * HALF) = o; }
;                     else { *(f32x4*)((float*)Xout + ro + bj * HALF) = x0; *(f32x4*)((float*)Xout + ro + bj * HALF + 4) = x1; } } }
	v_lshlrev_b32_e32 v120, 16, v112
	v_and_b32_e32 v121, 0xffff0000, v112
	v_lshlrev_b32_e32 v112, 16, v113
	v_and_b32_e32 v113, 0xffff0000, v113
	v_lshlrev_b32_e32 v122, 16, v114
	v_and_b32_e32 v123, 0xffff0000, v114
	v_lshlrev_b32_e32 v114, 16, v115
	v_and_b32_e32 v115, 0xffff0000, v115
	v_pk_add_f32 v[110:111], v[110:111], v[112:113]
	v_pk_add_f32 v[108:109], v[108:109], v[120:121]
	v_pk_add_f32 v[112:113], v[106:107], v[114:115]
	v_pk_add_f32 v[106:107], v[104:105], v[122:123]
	v_cvt_pk_bf16_f32 v104, v108, v109
	v_cvt_pk_bf16_f32 v105, v110, v111
	v_cvt_pk_bf16_f32 v106, v106, v107
	v_cvt_pk_bf16_f32 v107, v112, v113
	global_store_dwordx4 v[118:119], v[104:107], off
	s_waitcnt vmcnt(15)
	s_nop 1
	v_mov_b32_e32 v104, v172
	v_mov_b32_e32 v105, v173
	v_mov_b32_e32 v106, v174
	v_mov_b32_e32 v107, v175
	s_waitcnt lgkmcnt(0)
	v_lshlrev_b32_e32 v108, 16, v104
	v_and_b32_e32 v109, 0xffff0000, v104
	v_lshlrev_b32_e32 v104, 16, v105
	v_and_b32_e32 v105, 0xffff0000, v105
	v_lshlrev_b32_e32 v110, 16, v106
	v_and_b32_e32 v111, 0xffff0000, v106
	v_lshlrev_b32_e32 v106, 16, v107
	v_and_b32_e32 v107, 0xffff0000, v107
	v_pk_add_f32 v[100:101], v[100:101], v[108:109]
	v_pk_add_f32 v[102:103], v[102:103], v[104:105]
	v_pk_add_f32 v[104:105], v[98:99], v[106:107]
	v_pk_add_f32 v[98:99], v[96:97], v[110:111]
	v_cvt_pk_bf16_f32 v96, v100, v101
	v_lshl_add_u64 v[100:101], v[144:145], 0, s[2:3]
	s_mov_b32 s2, 0x20000
	v_cvt_pk_bf16_f32 v97, v102, v103
	v_add_co_u32_e32 v102, vcc, s2, v144
	v_cvt_pk_bf16_f32 v98, v98, v99
	v_cvt_pk_bf16_f32 v99, v104, v105
	v_addc_co_u32_e32 v103, vcc, 0, v145, vcc
	global_store_dwordx4 v[116:117], v[96:99], off offset:256
	s_waitcnt vmcnt(15)
	s_nop 1
	v_mov_b32_e32 v96, v176
	v_mov_b32_e32 v97, v177
	v_mov_b32_e32 v98, v178
	v_mov_b32_e32 v99, v179
	s_mov_b64 s[2:3], 0x30000
	s_waitcnt lgkmcnt(0)
	v_lshlrev_b32_e32 v104, 16, v96
	v_and_b32_e32 v105, 0xffff0000, v96
	v_lshlrev_b32_e32 v96, 16, v97
	v_and_b32_e32 v97, 0xffff0000, v97
	v_lshlrev_b32_e32 v106, 16, v98
	v_and_b32_e32 v107, 0xffff0000, v98
	v_lshlrev_b32_e32 v98, 16, v99
	v_and_b32_e32 v99, 0xffff0000, v99
	v_pk_add_f32 v[94:95], v[94:95], v[96:97]
	v_pk_add_f32 v[92:93], v[92:93], v[104:105]
	v_pk_add_f32 v[96:97], v[90:91], v[98:99]
	v_pk_add_f32 v[90:91], v[88:89], v[106:107]
	v_cvt_pk_bf16_f32 v88, v92, v93
	v_cvt_pk_bf16_f32 v89, v94, v95
	v_cvt_pk_bf16_f32 v90, v90, v91
	v_cvt_pk_bf16_f32 v91, v96, v97
	global_store_dwordx4 v[102:103], v[88:91], off
	s_waitcnt vmcnt(15)
	s_nop 1
	v_mov_b32_e32 v88, v180
	v_mov_b32_e32 v89, v181
	v_mov_b32_e32 v90, v182
	v_mov_b32_e32 v91, v183
	s_waitcnt lgkmcnt(0)
	v_lshlrev_b32_e32 v92, 16, v88
	v_and_b32_e32 v93, 0xffff0000, v88
	v_lshlrev_b32_e32 v88, 16, v89
	v_and_b32_e32 v89, 0xffff0000, v89
	v_lshlrev_b32_e32 v94, 16, v90
	v_and_b32_e32 v95, 0xffff0000, v90
	v_lshlrev_b32_e32 v90, 16, v91
	v_and_b32_e32 v91, 0xffff0000, v91
	v_pk_add_f32 v[86:87], v[86:87], v[88:89]
	v_pk_add_f32 v[84:85], v[84:85], v[92:93]
	v_pk_add_f32 v[88:89], v[82:83], v[90:91]
	v_pk_add_f32 v[82:83], v[80:81], v[94:95]
	v_cvt_pk_bf16_f32 v80, v84, v85
	v_cvt_pk_bf16_f32 v81, v86, v87
	v_cvt_pk_bf16_f32 v82, v82, v83
	v_cvt_pk_bf16_f32 v83, v88, v89
	global_store_dwordx4 v[100:101], v[80:83], off offset:256
	s_nop 1
	v_lshl_add_u64 v[80:81], v[144:145], 0, s[2:3]
	s_mov_b32 s2, 0x30000
	v_add_co_u32_e32 v86, vcc, s2, v144
	s_mov_b64 s[2:3], 0x80000
	s_nop 0
	v_addc_co_u32_e32 v87, vcc, 0, v145, vcc
	s_waitcnt vmcnt(15)
	s_nop 1
	v_mov_b32_e32 v82, v184
	v_mov_b32_e32 v83, v185
	v_mov_b32_e32 v84, v186
	v_mov_b32_e32 v85, v187
	s_waitcnt lgkmcnt(0)
	v_lshlrev_b32_e32 v88, 16, v82
	v_and_b32_e32 v89, 0xffff0000, v82
	v_lshlrev_b32_e32 v82, 16, v83
	v_and_b32_e32 v83, 0xffff0000, v83
	v_lshlrev_b32_e32 v90, 16, v84
	v_and_b32_e32 v91, 0xffff0000, v84
	v_lshlrev_b32_e32 v84, 16, v85
	v_and_b32_e32 v85, 0xffff0000, v85
	v_pk_add_f32 v[78:79], v[78:79], v[82:83]
	v_pk_add_f32 v[76:77], v[76:77], v[88:89]
	v_pk_add_f32 v[82:83], v[74:75], v[84:85]
	v_pk_add_f32 v[74:75], v[72:73], v[90:91]
	v_cvt_pk_bf16_f32 v72, v76, v77
	v_cvt_pk_bf16_f32 v73, v78, v79
	v_cvt_pk_bf16_f32 v74, v74, v75
	v_cvt_pk_bf16_f32 v75, v82, v83
	global_store_dwordx4 v[86:87], v[72:75], off
	s_waitcnt vmcnt(15)
	s_nop 1
	v_mov_b32_e32 v72, v188
	v_mov_b32_e32 v73, v189
	v_mov_b32_e32 v74, v190
	v_mov_b32_e32 v75, v191
	s_waitcnt lgkmcnt(0)
	v_lshlrev_b32_e32 v76, 16, v72
	v_and_b32_e32 v77, 0xffff0000, v72
	v_lshlrev_b32_e32 v72, 16, v73
	v_and_b32_e32 v73, 0xffff0000, v73
	v_lshlrev_b32_e32 v78, 16, v74
	v_and_b32_e32 v79, 0xffff0000, v74
	v_lshlrev_b32_e32 v74, 16, v75
	v_and_b32_e32 v75, 0xffff0000, v75
	v_pk_add_f32 v[70:71], v[70:71], v[72:73]
	v_pk_add_f32 v[68:69], v[68:69], v[76:77]
	v_pk_add_f32 v[72:73], v[66:67], v[74:75]
	v_pk_add_f32 v[66:67], v[64:65], v[78:79]
	v_cvt_pk_bf16_f32 v64, v68, v69
	v_cvt_pk_bf16_f32 v65, v70, v71
	v_cvt_pk_bf16_f32 v66, v66, v67
	v_cvt_pk_bf16_f32 v67, v72, v73
	global_store_dwordx4 v[80:81], v[64:67], off offset:256
	s_nop 1
	v_lshl_add_u64 v[64:65], v[144:145], 0, s[2:3]
	s_mov_b32 s2, 0x80000
	v_add_co_u32_e32 v70, vcc, s2, v144
	s_mov_b64 s[2:3], 0x90000
	s_nop 0
	v_addc_co_u32_e32 v71, vcc, 0, v145, vcc
	s_waitcnt vmcnt(15)
	s_nop 1
	v_mov_b32_e32 v66, v192
	v_mov_b32_e32 v67, v193
	v_mov_b32_e32 v68, v194
	v_mov_b32_e32 v69, v195
	s_waitcnt lgkmcnt(0)
; DI unsigned pack2(float a, float b) { f32x2 v = {a, b}; hwbf16x2 r = __builtin_convertvector(v, hwbf16x2); return __builtin_bit_cast(unsigned, r); }
; DI float bflo(unsigned w) { return __uint_as_float(w << 16); }
; DI float bfhi(unsigned w) { return __uint_as_float(w & 0xffff0000u); }
; #define PG8_WAIT_V(n) asm volatile("s_waitcnt vmcnt(" #n ")" ::: "memory")
; #define PG8_BAR __builtin_amdgcn_s_barrier()
;     DI void operator()(const f32x4 (&acc)[2][2][4][2], const Unit& u, int wr, int wc, int fr, int fq) const {
;     ...
;         for (int ai = 0; ai < 2; ++ai)
; #pragma unroll
;             for (int m = 0; m < 4; ++m) { const size_t ro = (size_t)(row0 + ai * HALF + m * 16) * D + col0;
; #pragma unroll
;                 for (int bj = 0; bj < 2; ++bj) {
;                     f32x4 x0, x1;
;                     if constexpr (IB) { const u32x4 w = *(const u32x4*)((const bf16_t*)Xin + ro + bj * HALF);
;                         x0 = (f32x4){bflo(w[0]), bfhi(w[0]), bflo(w[1]), bfhi(w[1])}; x1 = (f32x4){bflo(w[2]), bfhi(w[2]), bflo(w[3]), bfhi(w[3])}; }
;                     else { x0 = *(const f32x4*)((const float*)Xin + ro + bj * HALF); x1 = *(const f32x4*)((const float*)Xin + ro + bj * HALF + 4); }
;                     x0 += acc[ai][bj][m][0] * sc[bj][0]; x1 += acc[ai][bj][m][1] * sc[bj][1];
;                     if constexpr (OB) { u32x4 o; o[0] = pack2(x0[0], x0[1]); o[1] = pack2(x0[2], x0[3]); o[2] = pack2(x1[0], x1[1]); o[3] = pack2(x1[2], x1[3]);
;                         *(u32x4*)((bf16_t*)Xout + ro + bj * HALF) = o; }
;                     else { *(f32x4*)((float*)Xout + ro + bj * HALF) = x0; *(f32x4*)((float*)Xout + ro + bj * HALF + 4) = x1; } } }
; template <class Map, class Epi>
; DI void gemm_phase(LAS unsigned char* lds, const Map& MP, const Epi& E, const int nM, const int nN, const int K, const int lda, const int ldb) {
;     ...
;         if (!has_next) break;
;     ...
;     PG8_WAIT_V(0);
;     if (wr == 0) PG8_BAR;
;     PG8_BAR;
	v_lshlrev_b32_e32 v72, 16, v66
	v_and_b32_e32 v73, 0xffff0000, v66
	v_lshlrev_b32_e32 v66, 16, v67
	v_and_b32_e32 v67, 0xffff0000, v67
	v_lshlrev_b32_e32 v74, 16, v68
	v_and_b32_e32 v75, 0xffff0000, v68
	v_lshlrev_b32_e32 v68, 16, v69
	v_and_b32_e32 v69, 0xffff0000, v69
	v_pk_add_f32 v[62:63], v[62:63], v[66:67]
	v_pk_add_f32 v[60:61], v[60:61], v[72:73]
	v_pk_add_f32 v[66:67], v[58:59], v[68:69]
	v_pk_add_f32 v[58:59], v[56:57], v[74:75]
	v_cvt_pk_bf16_f32 v56, v60, v61
	v_cvt_pk_bf16_f32 v57, v62, v63
	v_cvt_pk_bf16_f32 v58, v58, v59
	v_cvt_pk_bf16_f32 v59, v66, v67
	global_store_dwordx4 v[70:71], v[56:59], off
	s_waitcnt vmcnt(15)
	s_nop 1
	v_mov_b32_e32 v56, v198
	v_mov_b32_e32 v57, v199
	v_mov_b32_e32 v58, v200
	v_mov_b32_e32 v59, v201
	s_waitcnt lgkmcnt(0)
	v_lshlrev_b32_e32 v60, 16, v56
	v_and_b32_e32 v61, 0xffff0000, v56
	v_lshlrev_b32_e32 v56, 16, v57
	v_and_b32_e32 v57, 0xffff0000, v57
	v_lshlrev_b32_e32 v62, 16, v58
	v_and_b32_e32 v63, 0xffff0000, v58
	v_lshlrev_b32_e32 v58, 16, v59
	v_and_b32_e32 v59, 0xffff0000, v59
	v_pk_add_f32 v[54:55], v[54:55], v[56:57]
	v_pk_add_f32 v[52:53], v[52:53], v[60:61]
	v_pk_add_f32 v[56:57], v[50:51], v[58:59]
	v_pk_add_f32 v[50:51], v[48:49], v[62:63]
	v_cvt_pk_bf16_f32 v48, v52, v53
	v_cvt_pk_bf16_f32 v49, v54, v55
	v_cvt_pk_bf16_f32 v50, v50, v51
	v_cvt_pk_bf16_f32 v51, v56, v57
	global_store_dwordx4 v[64:65], v[48:51], off offset:256
	s_nop 1
	v_lshl_add_u64 v[48:49], v[144:145], 0, s[2:3]
	s_mov_b32 s2, 0x90000
	v_add_co_u32_e32 v54, vcc, s2, v144
	s_mov_b64 s[2:3], 0xa0000
	s_nop 0
	v_addc_co_u32_e32 v55, vcc, 0, v145, vcc
	s_waitcnt vmcnt(15)
	s_nop 1
	v_mov_b32_e32 v50, v202
	v_mov_b32_e32 v51, v203
	v_mov_b32_e32 v52, v204
	v_mov_b32_e32 v53, v205
	s_waitcnt lgkmcnt(0)
	v_lshlrev_b32_e32 v56, 16, v50
	v_and_b32_e32 v57, 0xffff0000, v50
	v_lshlrev_b32_e32 v50, 16, v51
	v_and_b32_e32 v51, 0xffff0000, v51
	v_lshlrev_b32_e32 v58, 16, v52
	v_and_b32_e32 v59, 0xffff0000, v52
	v_lshlrev_b32_e32 v52, 16, v53
	v_and_b32_e32 v53, 0xffff0000, v53
	v_pk_add_f32 v[46:47], v[46:47], v[50:51]
	v_pk_add_f32 v[44:45], v[44:45], v[56:57]
	v_pk_add_f32 v[50:51], v[42:43], v[52:53]
	v_pk_add_f32 v[42:43], v[40:41], v[58:59]
	v_cvt_pk_bf16_f32 v40, v44, v45
	v_cvt_pk_bf16_f32 v41, v46, v47
	v_cvt_pk_bf16_f32 v42, v42, v43
	v_cvt_pk_bf16_f32 v43, v50, v51
	global_store_dwordx4 v[54:55], v[40:43], off
	s_waitcnt vmcnt(15)
	s_nop 1
	v_mov_b32_e32 v40, v206
	v_mov_b32_e32 v41, v207
	v_mov_b32_e32 v42, v208
	v_mov_b32_e32 v43, v209
	s_waitcnt lgkmcnt(0)
	v_lshlrev_b32_e32 v44, 16, v40
	v_and_b32_e32 v45, 0xffff0000, v40
	v_lshlrev_b32_e32 v40, 16, v41
	v_and_b32_e32 v41, 0xffff0000, v41
	v_lshlrev_b32_e32 v46, 16, v42
	v_and_b32_e32 v47, 0xffff0000, v42
	v_lshlrev_b32_e32 v42, 16, v43
	v_and_b32_e32 v43, 0xffff0000, v43
	v_pk_add_f32 v[38:39], v[38:39], v[40:41]
	v_pk_add_f32 v[36:37], v[36:37], v[44:45]
	v_pk_add_f32 v[40:41], v[34:35], v[42:43]
	v_pk_add_f32 v[34:35], v[32:33], v[46:47]
	v_cvt_pk_bf16_f32 v32, v36, v37
	v_cvt_pk_bf16_f32 v33, v38, v39
	v_cvt_pk_bf16_f32 v34, v34, v35
	v_cvt_pk_bf16_f32 v35, v40, v41
	global_store_dwordx4 v[48:49], v[32:35], off offset:256
	s_nop 1
	v_lshl_add_u64 v[32:33], v[144:145], 0, s[2:3]
	s_mov_b32 s2, 0xa0000
	v_add_co_u32_e32 v38, vcc, s2, v144
	s_mov_b64 s[2:3], 0xb0000
	s_nop 0
	v_addc_co_u32_e32 v39, vcc, 0, v145, vcc
	s_waitcnt vmcnt(15)
	s_nop 1
	v_mov_b32_e32 v34, v210
	v_mov_b32_e32 v35, v211
	v_mov_b32_e32 v36, v212
	v_mov_b32_e32 v37, v213
	s_waitcnt lgkmcnt(0)
	v_lshlrev_b32_e32 v40, 16, v34
	v_and_b32_e32 v41, 0xffff0000, v34
	v_lshlrev_b32_e32 v34, 16, v35
	v_and_b32_e32 v35, 0xffff0000, v35
	v_lshlrev_b32_e32 v42, 16, v36
	v_and_b32_e32 v43, 0xffff0000, v36
	v_lshlrev_b32_e32 v36, 16, v37
	v_and_b32_e32 v37, 0xffff0000, v37
	v_pk_add_f32 v[30:31], v[30:31], v[34:35]
	v_pk_add_f32 v[28:29], v[28:29], v[40:41]
	v_pk_add_f32 v[34:35], v[26:27], v[36:37]
	v_pk_add_f32 v[26:27], v[24:25], v[42:43]
	v_cvt_pk_bf16_f32 v24, v28, v29
	v_cvt_pk_bf16_f32 v25, v30, v31
	v_cvt_pk_bf16_f32 v26, v26, v27
	v_cvt_pk_bf16_f32 v27, v34, v35
	global_store_dwordx4 v[38:39], v[24:27], off
	s_waitcnt vmcnt(15)
	s_nop 1
	v_mov_b32_e32 v24, v214
	v_mov_b32_e32 v25, v215
	v_mov_b32_e32 v26, v216
	v_mov_b32_e32 v27, v217
	s_waitcnt lgkmcnt(0)
	v_lshlrev_b32_e32 v28, 16, v24
	v_and_b32_e32 v29, 0xffff0000, v24
	v_lshlrev_b32_e32 v24, 16, v25
	v_and_b32_e32 v25, 0xffff0000, v25
	v_lshlrev_b32_e32 v30, 16, v26
	v_and_b32_e32 v31, 0xffff0000, v26
	v_lshlrev_b32_e32 v26, 16, v27
	v_and_b32_e32 v27, 0xffff0000, v27
	v_pk_add_f32 v[22:23], v[22:23], v[24:25]
	v_pk_add_f32 v[20:21], v[20:21], v[28:29]
	v_pk_add_f32 v[24:25], v[18:19], v[26:27]
	v_pk_add_f32 v[18:19], v[16:17], v[30:31]
	v_cvt_pk_bf16_f32 v16, v20, v21
	v_cvt_pk_bf16_f32 v17, v22, v23
	v_cvt_pk_bf16_f32 v18, v18, v19
	v_cvt_pk_bf16_f32 v19, v24, v25
	global_store_dwordx4 v[32:33], v[16:19], off offset:256
	s_nop 1
	v_lshl_add_u64 v[16:17], v[144:145], 0, s[2:3]
	s_mov_b32 s2, 0xb0000
	v_add_co_u32_e32 v22, vcc, s2, v144
	s_mov_b32 s2, s55
	s_nop 0
	v_addc_co_u32_e32 v23, vcc, 0, v145, vcc
	s_waitcnt vmcnt(15)
	s_nop 1
	v_mov_b32_e32 v18, v248
	v_mov_b32_e32 v19, v249
	v_mov_b32_e32 v20, v250
	v_mov_b32_e32 v21, v251
	s_and_b64 vcc, exec, s[40:41]
	s_waitcnt lgkmcnt(0)
	v_lshlrev_b32_e32 v24, 16, v18
	v_and_b32_e32 v25, 0xffff0000, v18
	v_lshlrev_b32_e32 v18, 16, v19
	v_and_b32_e32 v19, 0xffff0000, v19
	v_lshlrev_b32_e32 v26, 16, v20
	v_and_b32_e32 v27, 0xffff0000, v20
	v_lshlrev_b32_e32 v20, 16, v21
	v_and_b32_e32 v21, 0xffff0000, v21
	v_pk_add_f32 v[14:15], v[14:15], v[18:19]
	v_pk_add_f32 v[12:13], v[12:13], v[24:25]
	v_pk_add_f32 v[18:19], v[10:11], v[20:21]
	v_pk_add_f32 v[10:11], v[8:9], v[26:27]
	v_cvt_pk_bf16_f32 v8, v12, v13
	v_cvt_pk_bf16_f32 v9, v14, v15
	v_cvt_pk_bf16_f32 v10, v10, v11
	v_cvt_pk_bf16_f32 v11, v18, v19
	global_store_dwordx4 v[22:23], v[8:11], off
	s_waitcnt vmcnt(15)
	s_nop 1
	v_mov_b32_e32 v8, v252
	v_mov_b32_e32 v9, v253
	v_mov_b32_e32 v10, v254
	v_mov_b32_e32 v11, v255
	s_waitcnt lgkmcnt(0)
	v_lshlrev_b32_e32 v12, 16, v8
	v_and_b32_e32 v13, 0xffff0000, v8
	v_lshlrev_b32_e32 v8, 16, v9
	v_and_b32_e32 v9, 0xffff0000, v9
	v_lshlrev_b32_e32 v14, 16, v10
	v_and_b32_e32 v15, 0xffff0000, v10
	v_lshlrev_b32_e32 v10, 16, v11
	v_and_b32_e32 v11, 0xffff0000, v11
	v_pk_add_f32 v[6:7], v[6:7], v[8:9]
	v_pk_add_f32 v[4:5], v[4:5], v[12:13]
	v_pk_add_f32 v[8:9], v[2:3], v[10:11]
	v_pk_add_f32 v[2:3], v[0:1], v[14:15]
	v_cvt_pk_bf16_f32 v0, v4, v5
	v_cvt_pk_bf16_f32 v1, v6, v7
	v_cvt_pk_bf16_f32 v2, v2, v3
	v_cvt_pk_bf16_f32 v3, v8, v9
	global_store_dwordx4 v[16:17], v[0:3], off offset:256
	s_cbranch_vccz .LBB1_543
	s_waitcnt vmcnt(0)
	s_cmpk_gt_u32 s17, 0xff
	s_cbranch_scc1 .LBB1_554
	s_barrier

; template <class Map, class Epi>
; DI void gemm_phase(LAS unsigned char* lds, const Map& MP, const Epi& E, const int nM, const int nN, const int K, const int lda, const int ldb) {
;     ...
;         const bool has_next = sched_next(ui + 1, nM, nN, G, cblk, nxt);
;         const char* nA = has_next ? MP.a(nxt) : cA; const char* nB = has_next ? MP.b(nxt) : cB;
;         for (int t = 0; t < nt; t += 2) {
;             const bool last = (t == nt - 2);
;             const char* a1 = cA + (size_t)(t + 1) * kstep;
;             const char* a2 = last ? nA : cA + (size_t)(t + 2) * kstep; const char* b2 = last ? nB : cB + (size_t)(t + 2) * kstep;
;             const char* a3 = a2 + kstep; const char* b3 = b2 + kstep;
;             PG8_LDB(B0, 0, 0); PG8_SCHED; PG8_LDA(At, 0, 0); PG8_STAGE(PG8_SA(1, 1), a1 + hstepA, voffA);
;             PG8_WAIT_L(8); PG8_BAR; PG8_WAIT_L(0); PG8_MMA(0, 0, At, B0); PG8_BAR; PG8_SCHED;
;             PG8_LDB(B1, 0, 1); PG8_STAGE(PG8_SB(0, 0), b2, voffB);
;             PG8_BAR; PG8_WAIT_L(0); PG8_MMA(0, 1, At, B1); PG8_BAR;
;             PG8_LDA(At, 0, 1); PG8_STAGE(PG8_SA(0, 0), a2, voffA);
;             PG8_BAR; PG8_WAIT_L(0); PG8_MMA(1, 0, At, B0); PG8_BAR; PG8_SCHED;
;             PG8_STAGE(PG8_SB(0, 1), b2 + hstepB, voffB);
;             PG8_WAIT_V(6); PG8_BAR; PG8_MMA(1, 1, At, B1); PG8_BAR;
;             PG8_LDB(B0, 1, 0); PG8_SCHED; PG8_LDA(At, 1, 0); PG8_STAGE(PG8_SA(0, 1), a2 + hstepA, voffA);
;             PG8_WAIT_L(8); PG8_BAR; PG8_WAIT_L(0); PG8_MMA(0, 0, At, B0); PG8_BAR; PG8_SCHED;
;             PG8_LDB(B1, 1, 1); PG8_STAGE(PG8_SB(1, 0), b3, voffB);
;             PG8_BAR; PG8_WAIT_L(0); PG8_MMA(0, 1, At, B1); PG8_BAR;
;             PG8_LDA(At, 1, 1); PG8_STAGE(PG8_SA(1, 0), a3, voffA);
;             PG8_BAR; PG8_WAIT_L(0); PG8_MMA(1, 0, At, B0); PG8_BAR; PG8_SCHED;
;             PG8_STAGE(PG8_SB(1, 1), b3 + hstepB, voffB);
;             PG8_WAIT_V(6); PG8_BAR; PG8_MMA(1, 1, At, B1); PG8_BAR;
;         }
;         { int frr = fr, fqq = fq; asm volatile("" : "+v"(frr), "+v"(fqq)); E(acc, cur, wr, wc, frr, fqq); }
;         if (!has_next) break;
; #pragma unroll
;         for (int a = 0; a < 2; ++a)
; #pragma unroll
;             for (int b = 0; b < 2; ++b)
; #pragma unroll
;                 for (int m = 0; m < 4; ++m)
; #pragma unroll
;                     for (int n = 0; n < 2; ++n) acc[a][b][m][n] = (f32x4){0.f, 0.f, 0.f, 0.f};
.LBB1_692:
	s_ashr_i32 s15, s14, 31
	v_cmp_lt_i64_e32 vcc, s[16:17], v[140:141]
	s_lshl_b64 s[16:17], s[14:15], 20
	s_add_u32 s16, s5, s16
	s_addc_u32 s17, s26, s17
	s_and_b64 s[18:19], vcc, exec
	s_cselect_b32 s15, s17, s23
	s_cselect_b32 s48, s16, s22
	s_ashr_i32 s13, s12, 31
	s_lshl_b64 s[18:19], s[12:13], 20
	s_add_u32 s18, s27, s18
	s_addc_u32 s19, s28, s19
	s_and_b64 s[24:25], vcc, exec
	s_cselect_b32 s13, s19, s21
	s_cselect_b32 s49, s18, s20
	s_add_u32 s52, s20, 0x100
	s_addc_u32 s53, s21, 0
	s_add_u32 s20, s22, 0x80080
	v_mov_b32_e32 v0, 0
	s_addc_u32 s21, s23, 0
	s_mov_b32 s54, -2
	v_mov_b32_e32 v1, v0
	v_mov_b32_e32 v2, v0
	v_mov_b32_e32 v3, v0
	v_mov_b32_e32 v4, v0
	v_mov_b32_e32 v5, v0
	v_mov_b32_e32 v6, v0
	v_mov_b32_e32 v7, v0
	v_mov_b32_e32 v8, v0
	v_mov_b32_e32 v9, v0
	v_mov_b32_e32 v10, v0
	v_mov_b32_e32 v11, v0
	v_mov_b32_e32 v12, v0
	v_mov_b32_e32 v13, v0
	v_mov_b32_e32 v14, v0
	v_mov_b32_e32 v15, v0
	v_mov_b32_e32 v24, v0
	v_mov_b32_e32 v25, v0
	v_mov_b32_e32 v26, v0
	v_mov_b32_e32 v27, v0
	v_mov_b32_e32 v28, v0
	v_mov_b32_e32 v29, v0
	v_mov_b32_e32 v30, v0
	v_mov_b32_e32 v31, v0
	v_mov_b32_e32 v40, v0
	v_mov_b32_e32 v41, v0
	v_mov_b32_e32 v42, v0
	v_mov_b32_e32 v43, v0
	v_mov_b32_e32 v44, v0
	v_mov_b32_e32 v45, v0
	v_mov_b32_e32 v46, v0
	v_mov_b32_e32 v47, v0
	v_mov_b32_e32 v16, v0
	v_mov_b32_e32 v17, v0
	v_mov_b32_e32 v18, v0
	v_mov_b32_e32 v19, v0
	v_mov_b32_e32 v20, v0
	v_mov_b32_e32 v21, v0
	v_mov_b32_e32 v22, v0
	v_mov_b32_e32 v23, v0
	v_mov_b32_e32 v32, v0
	v_mov_b32_e32 v33, v0
	v_mov_b32_e32 v34, v0
	v_mov_b32_e32 v35, v0
	v_mov_b32_e32 v36, v0
	v_mov_b32_e32 v37, v0
	v_mov_b32_e32 v38, v0
	v_mov_b32_e32 v39, v0
	v_mov_b32_e32 v48, v0
	v_mov_b32_e32 v49, v0
	v_mov_b32_e32 v50, v0
	v_mov_b32_e32 v51, v0
	v_mov_b32_e32 v52, v0
	v_mov_b32_e32 v53, v0
	v_mov_b32_e32 v54, v0
	v_mov_b32_e32 v55, v0
	v_mov_b32_e32 v56, v0
	v_mov_b32_e32 v57, v0
	v_mov_b32_e32 v58, v0
	v_mov_b32_e32 v59, v0
	v_mov_b32_e32 v60, v0
	v_mov_b32_e32 v61, v0
	v_mov_b32_e32 v62, v0
	v_mov_b32_e32 v63, v0
	v_mov_b32_e32 v64, v0
	v_mov_b32_e32 v65, v0
	v_mov_b32_e32 v66, v0
	v_mov_b32_e32 v67, v0
	v_mov_b32_e32 v68, v0
	v_mov_b32_e32 v69, v0
	v_mov_b32_e32 v70, v0
	v_mov_b32_e32 v71, v0
	v_mov_b32_e32 v72, v0
	v_mov_b32_e32 v73, v0
	v_mov_b32_e32 v74, v0
	v_mov_b32_e32 v75, v0
	v_mov_b32_e32 v76, v0
	v_mov_b32_e32 v77, v0
	v_mov_b32_e32 v78, v0
	v_mov_b32_e32 v79, v0
	v_mov_b32_e32 v88, v0
	v_mov_b32_e32 v89, v0
	v_mov_b32_e32 v90, v0
	v_mov_b32_e32 v91, v0
	v_mov_b32_e32 v92, v0
	v_mov_b32_e32 v93, v0
	v_mov_b32_e32 v94, v0
	v_mov_b32_e32 v95, v0
	v_mov_b32_e32 v104, v0
	v_mov_b32_e32 v105, v0
	v_mov_b32_e32 v106, v0
	v_mov_b32_e32 v107, v0
	v_mov_b32_e32 v108, v0
	v_mov_b32_e32 v109, v0
	v_mov_b32_e32 v110, v0
	v_mov_b32_e32 v111, v0
	v_mov_b32_e32 v80, v0
	v_mov_b32_e32 v81, v0
	v_mov_b32_e32 v82, v0
	v_mov_b32_e32 v83, v0
	v_mov_b32_e32 v84, v0
	v_mov_b32_e32 v85, v0
	v_mov_b32_e32 v86, v0
	v_mov_b32_e32 v87, v0
	v_mov_b32_e32 v96, v0
	v_mov_b32_e32 v97, v0
	v_mov_b32_e32 v98, v0
	v_mov_b32_e32 v99, v0
	v_mov_b32_e32 v100, v0
	v_mov_b32_e32 v101, v0
	v_mov_b32_e32 v102, v0
	v_mov_b32_e32 v103, v0
	v_mov_b32_e32 v112, v0
	v_mov_b32_e32 v113, v0
	v_mov_b32_e32 v114, v0
	v_mov_b32_e32 v115, v0
	v_mov_b32_e32 v116, v0
	v_mov_b32_e32 v117, v0
	v_mov_b32_e32 v118, v0
	v_mov_b32_e32 v119, v0
	v_mov_b32_e32 v120, v0
	v_mov_b32_e32 v121, v0
	v_mov_b32_e32 v122, v0
	v_mov_b32_e32 v123, v0
	v_mov_b32_e32 v124, v0
	v_mov_b32_e32 v125, v0
	v_mov_b32_e32 v126, v0
	v_mov_b32_e32 v127, v0
	ds_read_b128 v[150:153], v147
	ds_read_b128 v[154:157], v147 offset:1024
	ds_read_b128 v[158:161], v147 offset:2048
	ds_read_b128 v[162:165], v147 offset:3072
.LBB1_693:
	s_add_u32 s3, s20, 0xfff80080
	s_addc_u32 s22, s21, -1
	s_cmp_eq_u32 s54, 28
	s_cselect_b32 s25, s15, s22
	s_cselect_b32 s24, s48, s3
	s_cselect_b32 s23, s13, s53
	s_cselect_b32 s22, s49, s52
	s_add_i32 m0, s31, 0xc000
	ds_read_b128 v[166:169], v148
	ds_read_b128 v[170:173], v148 offset:1024
	ds_read_b128 v[174:177], v148 offset:2048
	ds_read_b128 v[178:181], v148 offset:3072
	ds_read_b128 v[182:185], v148 offset:4096
	ds_read_b128 v[186:189], v148 offset:5120
	ds_read_b128 v[190:193], v148 offset:6144
	ds_read_b128 v[198:201], v148 offset:7168
	global_load_lds_dwordx4 v138, s[20:21]
	s_add_i32 m0, s31, 0xe000
	s_nop 0
	global_load_lds_dwordx4 v136, s[20:21]
	s_waitcnt lgkmcnt(8)
	s_barrier
	s_setprio 1
	s_waitcnt lgkmcnt(7)
	v_mfma_f32_16x16x32_bf16 v[124:127], v[150:153], v[166:169], v[124:127]
	v_mfma_f32_16x16x32_bf16 v[120:123], v[158:161], v[166:169], v[120:123]
	s_waitcnt lgkmcnt(5)
	v_mfma_f32_16x16x32_bf16 v[116:119], v[150:153], v[174:177], v[116:119]
	v_mfma_f32_16x16x32_bf16 v[112:115], v[158:161], v[174:177], v[112:115]
	s_waitcnt lgkmcnt(3)
	v_mfma_f32_16x16x32_bf16 v[100:103], v[150:153], v[182:185], v[100:103]
	v_mfma_f32_16x16x32_bf16 v[96:99], v[158:161], v[182:185], v[96:99]
	s_waitcnt lgkmcnt(1)
	v_mfma_f32_16x16x32_bf16 v[84:87], v[150:153], v[190:193], v[84:87]
	v_mfma_f32_16x16x32_bf16 v[80:83], v[158:161], v[190:193], v[80:83]
	v_mfma_f32_16x16x32_bf16 v[124:127], v[154:157], v[170:173], v[124:127]
	v_mfma_f32_16x16x32_bf16 v[120:123], v[162:165], v[170:173], v[120:123]
	v_mfma_f32_16x16x32_bf16 v[116:119], v[154:157], v[178:181], v[116:119]
	v_mfma_f32_16x16x32_bf16 v[112:115], v[162:165], v[178:181], v[112:115]
	v_mfma_f32_16x16x32_bf16 v[100:103], v[154:157], v[186:189], v[100:103]
	v_mfma_f32_16x16x32_bf16 v[96:99], v[162:165], v[186:189], v[96:99]
	s_waitcnt lgkmcnt(0)
	v_mfma_f32_16x16x32_bf16 v[84:87], v[154:157], v[198:201], v[84:87]
	v_mfma_f32_16x16x32_bf16 v[80:83], v[162:165], v[198:201], v[80:83]
	s_setprio 0
	s_barrier
; #define PG8_STAGE(bufoff, gbase, voff) do { _Pragma("unroll") for (int _i = 0; _i < 2; ++_i) \
;         __builtin_amdgcn_global_load_lds((const unsigned*)((const char*)(gbase) + (voff)[_i]), (LAS unsigned*)(lds + (bufoff) + ldsw + _i * 8192), 16, 0, 0); } while (0)
; #define PG8_LDA(dst, b, h) do { _Pragma("unroll") for (int m = 0; m < 4; ++m) _Pragma("unroll") for (int k = 0; k < 2; ++k) dst[m][k] = *(const LAS bf16x8*)(lds + PG8_SA(b, h) + aoff + m * 2048 + k * 1024); } while (0)
; #define PG8_LDB(dst, b, h) do { _Pragma("unroll") for (int n = 0; n < 2; ++n) _Pragma("unroll") for (int k = 0; k < 2; ++k) dst[n][k] = *(const LAS bf16x8*)(lds + PG8_SB(b, h) + boff + n * 2048 + k * 1024); } while (0)
; #define PG8_MMA(ai, bj, At, Bt) do { __builtin_amdgcn_s_setprio(1); _Pragma("unroll") for (int m = 0; m < 4; ++m) _Pragma("unroll") for (int n = 0; n < 2; ++n) _Pragma("unroll") for (int k = 0; k < 2; ++k) \
;         acc[ai][bj][m][n] = __builtin_amdgcn_mfma_f32_16x16x32_bf16(Bt[n][k], At[m][k], acc[ai][bj][m][n], 0, 0, 0); __builtin_amdgcn_s_setprio(0); } while (0)
; #define PG8_WAIT_V(n) asm volatile("s_waitcnt vmcnt(" #n ")" ::: "memory")
; #define PG8_WAIT_L(n) asm volatile("s_waitcnt lgkmcnt(" #n ")" ::: "memory")
; #define PG8_BAR __builtin_amdgcn_s_barrier()
; #define PG8_SCHED __builtin_amdgcn_sched_barrier(0)
; template <class Map, class Epi>
; DI void gemm_phase(LAS unsigned char* lds, const Map& MP, const Epi& E, const int nM, const int nN, const int K, const int lda, const int ldb) {
;     ...
;             PG8_LDB(B1, 0, 1); PG8_STAGE(PG8_SB(0, 0), b2, voffB);
;             PG8_BAR; PG8_WAIT_L(0); PG8_MMA(0, 1, At, B1); PG8_BAR;
;             PG8_LDA(At, 0, 1); PG8_STAGE(PG8_SA(0, 0), a2, voffA);
;             PG8_BAR; PG8_WAIT_L(0); PG8_MMA(1, 0, At, B0); PG8_BAR; PG8_SCHED;
;             PG8_STAGE(PG8_SB(0, 1), b2 + hstepB, voffB);
;             PG8_WAIT_V(6); PG8_BAR; PG8_MMA(1, 1, At, B1); PG8_BAR;
;             PG8_LDB(B0, 1, 0); PG8_SCHED; PG8_LDA(At, 1, 0); PG8_STAGE(PG8_SA(0, 1), a2 + hstepA, voffA);
;             PG8_WAIT_L(8); PG8_BAR; PG8_WAIT_L(0); PG8_MMA(0, 0, At, B0); PG8_BAR; PG8_SCHED;
	s_add_i32 s3, s44, s29
	v_lshl_add_u64 v[194:195], s[22:23], 0, v[132:133]
	s_mov_b32 m0, s3
	ds_read_b128 v[202:205], v149
	ds_read_b128 v[206:209], v149 offset:1024
	ds_read_b128 v[210:213], v149 offset:2048
	ds_read_b128 v[214:217], v149 offset:3072
	global_load_lds_dwordx4 v[194:195], off
	v_lshl_add_u64 v[218:219], s[22:23], 0, v[128:129]
	s_add_i32 m0, s3, 0x2000
	s_nop 0
	global_load_lds_dwordx4 v[218:219], off
	s_barrier
	s_setprio 1
	s_waitcnt lgkmcnt(3)
	v_mfma_f32_16x16x32_bf16 v[108:111], v[202:205], v[166:169], v[108:111]
	s_waitcnt lgkmcnt(1)
	v_mfma_f32_16x16x32_bf16 v[104:107], v[210:213], v[166:169], v[104:107]
	v_mfma_f32_16x16x32_bf16 v[92:95], v[202:205], v[174:177], v[92:95]
	v_mfma_f32_16x16x32_bf16 v[88:91], v[210:213], v[174:177], v[88:91]
	v_mfma_f32_16x16x32_bf16 v[76:79], v[202:205], v[182:185], v[76:79]
	v_mfma_f32_16x16x32_bf16 v[72:75], v[210:213], v[182:185], v[72:75]
	v_mfma_f32_16x16x32_bf16 v[68:71], v[202:205], v[190:193], v[68:71]
	v_mfma_f32_16x16x32_bf16 v[64:67], v[210:213], v[190:193], v[64:67]
	v_mfma_f32_16x16x32_bf16 v[108:111], v[206:209], v[170:173], v[108:111]
	s_waitcnt lgkmcnt(0)
	v_mfma_f32_16x16x32_bf16 v[104:107], v[214:217], v[170:173], v[104:107]
	v_mfma_f32_16x16x32_bf16 v[92:95], v[206:209], v[178:181], v[92:95]
	v_mfma_f32_16x16x32_bf16 v[88:91], v[214:217], v[178:181], v[88:91]
	v_mfma_f32_16x16x32_bf16 v[76:79], v[206:209], v[186:189], v[76:79]
	v_mfma_f32_16x16x32_bf16 v[72:75], v[214:217], v[186:189], v[72:75]
	v_mfma_f32_16x16x32_bf16 v[68:71], v[206:209], v[198:201], v[68:71]
	v_mfma_f32_16x16x32_bf16 v[64:67], v[214:217], v[198:201], v[64:67]
	s_setprio 0
	s_mov_b32 m0, s31
	v_lshl_add_u64 v[220:221], s[24:25], 0, v[134:135]
	s_barrier
	ds_read_b128 v[166:169], v148 offset:16384
	ds_read_b128 v[170:173], v148 offset:17408
	ds_read_b128 v[174:177], v148 offset:18432
	ds_read_b128 v[178:181], v148 offset:19456
	ds_read_b128 v[182:185], v148 offset:20480
	ds_read_b128 v[186:189], v148 offset:21504
	ds_read_b128 v[190:193], v148 offset:22528
	ds_read_b128 v[198:201], v148 offset:23552
	global_load_lds_dwordx4 v[220:221], off
	v_lshl_add_u64 v[222:223], s[24:25], 0, v[130:131]
	s_mov_b32 m0, s11
	s_nop 0
	global_load_lds_dwordx4 v[222:223], off
	s_waitcnt vmcnt(10)
	s_barrier
	s_setprio 1
	s_waitcnt lgkmcnt(7)
	v_mfma_f32_16x16x32_bf16 v[60:63], v[150:153], v[166:169], v[60:63]
	v_mfma_f32_16x16x32_bf16 v[56:59], v[158:161], v[166:169], v[56:59]
	s_waitcnt lgkmcnt(5)
	v_mfma_f32_16x16x32_bf16 v[52:55], v[150:153], v[174:177], v[52:55]
	v_mfma_f32_16x16x32_bf16 v[48:51], v[158:161], v[174:177], v[48:51]
	s_waitcnt lgkmcnt(3)
	v_mfma_f32_16x16x32_bf16 v[36:39], v[150:153], v[182:185], v[36:39]
	v_mfma_f32_16x16x32_bf16 v[32:35], v[158:161], v[182:185], v[32:35]
	s_waitcnt lgkmcnt(1)
	v_mfma_f32_16x16x32_bf16 v[20:23], v[150:153], v[190:193], v[20:23]
	v_mfma_f32_16x16x32_bf16 v[16:19], v[158:161], v[190:193], v[16:19]
	v_mfma_f32_16x16x32_bf16 v[60:63], v[154:157], v[170:173], v[60:63]
	v_mfma_f32_16x16x32_bf16 v[56:59], v[162:165], v[170:173], v[56:59]
	v_mfma_f32_16x16x32_bf16 v[52:55], v[154:157], v[178:181], v[52:55]
	v_mfma_f32_16x16x32_bf16 v[48:51], v[162:165], v[178:181], v[48:51]
	v_mfma_f32_16x16x32_bf16 v[36:39], v[154:157], v[186:189], v[36:39]
	v_mfma_f32_16x16x32_bf16 v[32:35], v[162:165], v[186:189], v[32:35]
	s_waitcnt lgkmcnt(0)
	v_mfma_f32_16x16x32_bf16 v[20:23], v[154:157], v[198:201], v[20:23]
	v_mfma_f32_16x16x32_bf16 v[16:19], v[162:165], v[198:201], v[16:19]
	s_setprio 0
	s_barrier
	s_add_u32 s56, s22, 0x80000
	s_addc_u32 s57, s23, 0
	s_add_i32 s3, s45, s29
	s_mov_b32 m0, s3
	s_nop 0
	global_load_lds_dwordx4 v132, s[56:57]
	s_add_i32 m0, s3, 0x2000
	s_nop 0
	global_load_lds_dwordx4 v128, s[56:57]
	s_waitcnt vmcnt(6)
	s_barrier
	s_setprio 1
	v_mfma_f32_16x16x32_bf16 v[44:47], v[202:205], v[166:169], v[44:47]
	v_mfma_f32_16x16x32_bf16 v[40:43], v[210:213], v[166:169], v[40:43]
	s_add_i32 s3, 0, 0x18000
	v_add_u32_e32 v162, s3, v146
	ds_read_b128 v[150:153], v162
	v_mfma_f32_16x16x32_bf16 v[28:31], v[202:205], v[174:177], v[28:31]
	v_mfma_f32_16x16x32_bf16 v[24:27], v[210:213], v[174:177], v[24:27]
	ds_read_b128 v[154:157], v162 offset:1024
	v_mfma_f32_16x16x32_bf16 v[12:15], v[202:205], v[182:185], v[12:15]
	v_mfma_f32_16x16x32_bf16 v[8:11], v[210:213], v[182:185], v[8:11]
	ds_read_b128 v[158:161], v162 offset:2048
	v_mfma_f32_16x16x32_bf16 v[4:7], v[202:205], v[190:193], v[4:7]
	v_mfma_f32_16x16x32_bf16 v[0:3], v[210:213], v[190:193], v[0:3]
	ds_read_b128 v[162:165], v162 offset:3072
	v_mfma_f32_16x16x32_bf16 v[44:47], v[206:209], v[170:173], v[44:47]
	v_mfma_f32_16x16x32_bf16 v[40:43], v[214:217], v[170:173], v[40:43]
	v_mfma_f32_16x16x32_bf16 v[28:31], v[206:209], v[178:181], v[28:31]
	v_mfma_f32_16x16x32_bf16 v[24:27], v[214:217], v[178:181], v[24:27]
	v_mfma_f32_16x16x32_bf16 v[12:15], v[206:209], v[186:189], v[12:15]
	v_mfma_f32_16x16x32_bf16 v[8:11], v[214:217], v[186:189], v[8:11]
	v_mfma_f32_16x16x32_bf16 v[4:7], v[206:209], v[198:201], v[4:7]
	v_mfma_f32_16x16x32_bf16 v[0:3], v[214:217], v[198:201], v[0:3]
	s_setprio 0
	s_barrier
	s_add_u32 s24, s24, 0x80000
	s_addc_u32 s25, s25, 0
	s_mov_b32 m0, s34
	ds_read_b128 v[166:169], v148 offset:32768
	ds_read_b128 v[170:173], v148 offset:33792
	ds_read_b128 v[174:177], v148 offset:34816
	ds_read_b128 v[178:181], v148 offset:35840
	ds_read_b128 v[182:185], v148 offset:36864
	ds_read_b128 v[186:189], v148 offset:37888
	ds_read_b128 v[190:193], v148 offset:38912
	ds_read_b128 v[198:201], v148 offset:39936
	global_load_lds_dwordx4 v134, s[24:25]
	s_mov_b32 m0, s35
	s_nop 0
	global_load_lds_dwordx4 v130, s[24:25]
	s_waitcnt lgkmcnt(8)
	s_barrier
; #define PG8_STAGE(bufoff, gbase, voff) do { _Pragma("unroll") for (int _i = 0; _i < 2; ++_i) \
;         __builtin_amdgcn_global_load_lds((const unsigned*)((const char*)(gbase) + (voff)[_i]), (LAS unsigned*)(lds + (bufoff) + ldsw + _i * 8192), 16, 0, 0); } while (0)
; #define PG8_LDA(dst, b, h) do { _Pragma("unroll") for (int m = 0; m < 4; ++m) _Pragma("unroll") for (int k = 0; k < 2; ++k) dst[m][k] = *(const LAS bf16x8*)(lds + PG8_SA(b, h) + aoff + m * 2048 + k * 1024); } while (0)
; #define PG8_LDB(dst, b, h) do { _Pragma("unroll") for (int n = 0; n < 2; ++n) _Pragma("unroll") for (int k = 0; k < 2; ++k) dst[n][k] = *(const LAS bf16x8*)(lds + PG8_SB(b, h) + boff + n * 2048 + k * 1024); } while (0)
; #define PG8_MMA(ai, bj, At, Bt) do { __builtin_amdgcn_s_setprio(1); _Pragma("unroll") for (int m = 0; m < 4; ++m) _Pragma("unroll") for (int n = 0; n < 2; ++n) _Pragma("unroll") for (int k = 0; k < 2; ++k) \
;         acc[ai][bj][m][n] = __builtin_amdgcn_mfma_f32_16x16x32_bf16(Bt[n][k], At[m][k], acc[ai][bj][m][n], 0, 0, 0); __builtin_amdgcn_s_setprio(0); } while (0)
; #define PG8_WAIT_V(n) asm volatile("s_waitcnt vmcnt(" #n ")" ::: "memory")
; #define PG8_WAIT_L(n) asm volatile("s_waitcnt lgkmcnt(" #n ")" ::: "memory")
; #define PG8_BAR __builtin_amdgcn_s_barrier()
; #define PG8_SCHED __builtin_amdgcn_sched_barrier(0)
; template <class Map, class Epi>
; DI void gemm_phase(LAS unsigned char* lds, const Map& MP, const Epi& E, const int nM, const int nN, const int K, const int lda, const int ldb) {
;     ...
;             PG8_WAIT_L(8); PG8_BAR; PG8_WAIT_L(0); PG8_MMA(0, 0, At, B0); PG8_BAR; PG8_SCHED;
;             PG8_LDB(B1, 1, 1); PG8_STAGE(PG8_SB(1, 0), b3, voffB);
;             PG8_BAR; PG8_WAIT_L(0); PG8_MMA(0, 1, At, B1); PG8_BAR;
;             PG8_LDA(At, 1, 1); PG8_STAGE(PG8_SA(1, 0), a3, voffA);
;             PG8_BAR; PG8_WAIT_L(0); PG8_MMA(1, 0, At, B0); PG8_BAR; PG8_SCHED;
;             PG8_STAGE(PG8_SB(1, 1), b3 + hstepB, voffB);
;             PG8_WAIT_V(6); PG8_BAR; PG8_MMA(1, 1, At, B1); PG8_BAR;
	s_setprio 1
	s_waitcnt lgkmcnt(7)
	v_mfma_f32_16x16x32_bf16 v[124:127], v[150:153], v[166:169], v[124:127]
	v_mfma_f32_16x16x32_bf16 v[120:123], v[158:161], v[166:169], v[120:123]
	s_waitcnt lgkmcnt(5)
	v_mfma_f32_16x16x32_bf16 v[116:119], v[150:153], v[174:177], v[116:119]
	v_mfma_f32_16x16x32_bf16 v[112:115], v[158:161], v[174:177], v[112:115]
	s_waitcnt lgkmcnt(3)
	v_mfma_f32_16x16x32_bf16 v[100:103], v[150:153], v[182:185], v[100:103]
	v_mfma_f32_16x16x32_bf16 v[96:99], v[158:161], v[182:185], v[96:99]
	s_waitcnt lgkmcnt(1)
	v_mfma_f32_16x16x32_bf16 v[84:87], v[150:153], v[190:193], v[84:87]
	v_mfma_f32_16x16x32_bf16 v[80:83], v[158:161], v[190:193], v[80:83]
	v_mfma_f32_16x16x32_bf16 v[124:127], v[154:157], v[170:173], v[124:127]
	v_mfma_f32_16x16x32_bf16 v[120:123], v[162:165], v[170:173], v[120:123]
	v_mfma_f32_16x16x32_bf16 v[116:119], v[154:157], v[178:181], v[116:119]
	v_mfma_f32_16x16x32_bf16 v[112:115], v[162:165], v[178:181], v[112:115]
	v_mfma_f32_16x16x32_bf16 v[100:103], v[154:157], v[186:189], v[100:103]
	v_mfma_f32_16x16x32_bf16 v[96:99], v[162:165], v[186:189], v[96:99]
	s_waitcnt lgkmcnt(0)
	v_mfma_f32_16x16x32_bf16 v[84:87], v[154:157], v[198:201], v[84:87]
	v_mfma_f32_16x16x32_bf16 v[80:83], v[162:165], v[198:201], v[80:83]
	s_setprio 0
	s_barrier
	s_add_i32 s24, 0, 0x1c000
	s_add_i32 s3, s3, s29
	v_add_u32_e32 v196, s24, v146
	v_lshl_add_u64 v[194:195], v[194:195], 0, s[8:9]
	s_mov_b32 m0, s3
	ds_read_b128 v[202:205], v196
	ds_read_b128 v[206:209], v196 offset:1024
	ds_read_b128 v[210:213], v196 offset:2048
	ds_read_b128 v[214:217], v196 offset:3072
	global_load_lds_dwordx4 v[194:195], off
	v_lshl_add_u64 v[194:195], v[218:219], 0, s[8:9]
	s_add_i32 m0, s3, 0x2000
	s_nop 0
	global_load_lds_dwordx4 v[194:195], off
	s_barrier
	s_setprio 1
	s_waitcnt lgkmcnt(3)
	v_mfma_f32_16x16x32_bf16 v[108:111], v[202:205], v[166:169], v[108:111]
	s_waitcnt lgkmcnt(1)
	v_mfma_f32_16x16x32_bf16 v[104:107], v[210:213], v[166:169], v[104:107]
	v_mfma_f32_16x16x32_bf16 v[92:95], v[202:205], v[174:177], v[92:95]
	v_mfma_f32_16x16x32_bf16 v[88:91], v[210:213], v[174:177], v[88:91]
	v_mfma_f32_16x16x32_bf16 v[76:79], v[202:205], v[182:185], v[76:79]
	v_mfma_f32_16x16x32_bf16 v[72:75], v[210:213], v[182:185], v[72:75]
	v_mfma_f32_16x16x32_bf16 v[68:71], v[202:205], v[190:193], v[68:71]
	v_mfma_f32_16x16x32_bf16 v[64:67], v[210:213], v[190:193], v[64:67]
	v_mfma_f32_16x16x32_bf16 v[108:111], v[206:209], v[170:173], v[108:111]
	s_waitcnt lgkmcnt(0)
	v_mfma_f32_16x16x32_bf16 v[104:107], v[214:217], v[170:173], v[104:107]
	v_mfma_f32_16x16x32_bf16 v[92:95], v[206:209], v[178:181], v[92:95]
	v_mfma_f32_16x16x32_bf16 v[88:91], v[214:217], v[178:181], v[88:91]
	v_mfma_f32_16x16x32_bf16 v[76:79], v[206:209], v[186:189], v[76:79]
	v_mfma_f32_16x16x32_bf16 v[72:75], v[214:217], v[186:189], v[72:75]
	v_mfma_f32_16x16x32_bf16 v[68:71], v[206:209], v[198:201], v[68:71]
	v_mfma_f32_16x16x32_bf16 v[64:67], v[214:217], v[198:201], v[64:67]
	s_setprio 0
	s_mov_b32 m0, s39
	v_lshl_add_u64 v[194:195], v[220:221], 0, s[8:9]
	s_barrier
	ds_read_b128 v[166:169], v148 offset:49152
	ds_read_b128 v[170:173], v148 offset:50176
	ds_read_b128 v[174:177], v148 offset:51200
	ds_read_b128 v[178:181], v148 offset:52224
	ds_read_b128 v[182:185], v148 offset:53248
	ds_read_b128 v[186:189], v148 offset:54272
	ds_read_b128 v[190:193], v148 offset:55296
	ds_read_b128 v[198:201], v148 offset:56320
	global_load_lds_dwordx4 v[194:195], off
	v_lshl_add_u64 v[194:195], v[222:223], 0, s[8:9]
	s_mov_b32 m0, s42
	s_nop 0
	global_load_lds_dwordx4 v[194:195], off
	s_waitcnt vmcnt(10)
	s_barrier
	s_setprio 1
	s_waitcnt lgkmcnt(7)
	v_mfma_f32_16x16x32_bf16 v[60:63], v[150:153], v[166:169], v[60:63]
	v_mfma_f32_16x16x32_bf16 v[56:59], v[158:161], v[166:169], v[56:59]
	s_waitcnt lgkmcnt(5)
	v_mfma_f32_16x16x32_bf16 v[52:55], v[150:153], v[174:177], v[52:55]
	v_mfma_f32_16x16x32_bf16 v[48:51], v[158:161], v[174:177], v[48:51]
	s_waitcnt lgkmcnt(3)
	v_mfma_f32_16x16x32_bf16 v[36:39], v[150:153], v[182:185], v[36:39]
	v_mfma_f32_16x16x32_bf16 v[32:35], v[158:161], v[182:185], v[32:35]
	s_waitcnt lgkmcnt(1)
	v_mfma_f32_16x16x32_bf16 v[20:23], v[150:153], v[190:193], v[20:23]
	v_mfma_f32_16x16x32_bf16 v[16:19], v[158:161], v[190:193], v[16:19]
	v_mfma_f32_16x16x32_bf16 v[60:63], v[154:157], v[170:173], v[60:63]
	v_mfma_f32_16x16x32_bf16 v[56:59], v[162:165], v[170:173], v[56:59]
	v_mfma_f32_16x16x32_bf16 v[52:55], v[154:157], v[178:181], v[52:55]
	v_mfma_f32_16x16x32_bf16 v[48:51], v[162:165], v[178:181], v[48:51]
	v_mfma_f32_16x16x32_bf16 v[36:39], v[154:157], v[186:189], v[36:39]
	v_mfma_f32_16x16x32_bf16 v[32:35], v[162:165], v[186:189], v[32:35]
	s_waitcnt lgkmcnt(0)
	v_mfma_f32_16x16x32_bf16 v[20:23], v[154:157], v[198:201], v[20:23]
	v_mfma_f32_16x16x32_bf16 v[16:19], v[162:165], v[198:201], v[16:19]
	s_setprio 0
	s_barrier
	s_add_u32 s22, s22, 0x80080
	s_addc_u32 s23, s23, 0
	s_add_i32 s3, s24, s29
	s_mov_b32 m0, s3
	s_nop 0
	global_load_lds_dwordx4 v132, s[22:23]
	s_add_i32 m0, s3, 0x2000
	s_nop 0
	global_load_lds_dwordx4 v128, s[22:23]
	s_waitcnt vmcnt(6)
	s_barrier
; DI unsigned pack2(float a, float b) { f32x2 v = {a, b}; hwbf16x2 r = __builtin_convertvector(v, hwbf16x2); return __builtin_bit_cast(unsigned, r); }
; #define PG8_MMA(ai, bj, At, Bt) do { __builtin_amdgcn_s_setprio(1); _Pragma("unroll") for (int m = 0; m < 4; ++m) _Pragma("unroll") for (int n = 0; n < 2; ++n) _Pragma("unroll") for (int k = 0; k < 2; ++k) \
;         acc[ai][bj][m][n] = __builtin_amdgcn_mfma_f32_16x16x32_bf16(Bt[n][k], At[m][k], acc[ai][bj][m][n], 0, 0, 0); __builtin_amdgcn_s_setprio(0); } while (0)
; #define PG8_WAIT_V(n) asm volatile("s_waitcnt vmcnt(" #n ")" ::: "memory")
; #define PG8_BAR __builtin_amdgcn_s_barrier()
;     DI void operator()(const f32x4 (&acc)[2][2][4][2], const Unit& u, int wr, int wc, int fr, int fq) const {
;         bf16_t* O = O1; int ldc = ldc1, pn = u.pn; if (pn >= split) { O = O2; ldc = ldc2; pn -= split; }
;         const int row0 = u.pm * BM + wr * 64 + fr, col0 = pn * BM + wc * 32 + 8 * fq;
; #pragma unroll
;         for (int ai = 0; ai < 2; ++ai)
; #pragma unroll
;             for (int m = 0; m < 4; ++m) { bf16_t* rowp = O + (size_t)(row0 + ai * HALF + m * 16) * ldc + col0;
; #pragma unroll
;                 for (int bj = 0; bj < 2; ++bj) { const f32x4 v0 = acc[ai][bj][m][0], v1 = acc[ai][bj][m][1];
;                     u32x4 o; o[0] = pack2(v0[0], v0[1]); o[1] = pack2(v0[2], v0[3]); o[2] = pack2(v1[0], v1[1]); o[3] = pack2(v1[2], v1[3]);
;                     *(u32x4*)(rowp + bj * HALF) = o; } }
; template <class Map, class Epi>
; DI void gemm_phase(LAS unsigned char* lds, const Map& MP, const Epi& E, const int nM, const int nN, const int K, const int lda, const int ldb) {
;     ...
;             PG8_WAIT_V(6); PG8_BAR; PG8_MMA(1, 1, At, B1); PG8_BAR;
;         }
;         { int frr = fr, fqq = fq; asm volatile("" : "+v"(frr), "+v"(fqq)); E(acc, cur, wr, wc, frr, fqq); }
	s_setprio 1
	v_mfma_f32_16x16x32_bf16 v[44:47], v[202:205], v[166:169], v[44:47]
	v_mfma_f32_16x16x32_bf16 v[40:43], v[210:213], v[166:169], v[40:43]
	ds_read_b128 v[150:153], v147
	v_mfma_f32_16x16x32_bf16 v[28:31], v[202:205], v[174:177], v[28:31]
	v_mfma_f32_16x16x32_bf16 v[24:27], v[210:213], v[174:177], v[24:27]
	ds_read_b128 v[154:157], v147 offset:1024
	v_mfma_f32_16x16x32_bf16 v[12:15], v[202:205], v[182:185], v[12:15]
	v_mfma_f32_16x16x32_bf16 v[8:11], v[210:213], v[182:185], v[8:11]
	ds_read_b128 v[158:161], v147 offset:2048
	v_mfma_f32_16x16x32_bf16 v[4:7], v[202:205], v[190:193], v[4:7]
	v_mfma_f32_16x16x32_bf16 v[0:3], v[210:213], v[190:193], v[0:3]
	ds_read_b128 v[162:165], v147 offset:3072
	v_mfma_f32_16x16x32_bf16 v[44:47], v[206:209], v[170:173], v[44:47]
	v_mfma_f32_16x16x32_bf16 v[40:43], v[214:217], v[170:173], v[40:43]
	v_mfma_f32_16x16x32_bf16 v[28:31], v[206:209], v[178:181], v[28:31]
	v_mfma_f32_16x16x32_bf16 v[24:27], v[214:217], v[178:181], v[24:27]
	v_mfma_f32_16x16x32_bf16 v[12:15], v[206:209], v[186:189], v[12:15]
	v_mfma_f32_16x16x32_bf16 v[8:11], v[214:217], v[186:189], v[8:11]
	v_mfma_f32_16x16x32_bf16 v[4:7], v[206:209], v[198:201], v[4:7]
	v_mfma_f32_16x16x32_bf16 v[0:3], v[214:217], v[198:201], v[0:3]
	s_setprio 0
	s_add_i32 s54, s54, 2
	s_add_u32 s52, s52, 0x100
	s_addc_u32 s53, s53, 0
	s_add_u32 s20, s20, 0x100
	s_addc_u32 s21, s21, 0
	s_cmp_gt_u32 s54, 29
	s_barrier
	s_cbranch_scc0 .LBB1_693
	s_waitcnt lgkmcnt(0)
	s_lshl_b32 s3, s10, 8
	v_mov_b32_e32 v150, v144
	v_mov_b32_e32 v151, v145
	s_add_i32 s3, s3, s37
	v_cvt_pk_bf16_f32 v68, v68, v69
	v_add_u32_e32 v154, s3, v150
	s_lshl_b32 s3, s47, 8
	s_or_b32 s3, s3, s38
	v_lshl_add_u32 v150, v151, 3, s3
	v_ashrrev_i32_e32 v151, 31, v150
	v_lshl_add_u64 v[150:151], v[150:151], 1, s[6:7]
	v_cvt_pk_bf16_f32 v69, v70, v71
	v_cvt_pk_bf16_f32 v70, v64, v65
	v_add_u32_e32 v64, 0x80, v154
	v_mad_i64_i32 v[152:153], s[20:21], v154, s46, v[150:151]
	v_cvt_pk_bf16_f32 v108, v108, v109
	v_cvt_pk_bf16_f32 v109, v110, v111
	v_cvt_pk_bf16_f32 v110, v104, v105
	v_cvt_pk_bf16_f32 v111, v106, v107
	v_add_u32_e32 v104, 16, v154
	v_mad_i64_i32 v[64:65], s[20:21], v64, s46, v[150:151]
	v_cvt_pk_bf16_f32 v44, v44, v45
	v_cvt_pk_bf16_f32 v45, v46, v47
	v_cvt_pk_bf16_f32 v46, v40, v41
	v_cvt_pk_bf16_f32 v47, v42, v43
	v_add_u32_e32 v40, 0x90, v154
	global_store_dwordx4 v[152:153], v[108:111], off offset:256
	v_cvt_pk_bf16_f32 v92, v92, v93
	v_cvt_pk_bf16_f32 v93, v94, v95
	v_mad_i64_i32 v[108:109], s[20:21], v104, s46, v[150:151]
	v_cvt_pk_bf16_f32 v94, v88, v89
	v_cvt_pk_bf16_f32 v95, v90, v91
	v_add_u32_e32 v88, 32, v154
	global_store_dwordx4 v[64:65], v[44:47], off offset:256
	v_cvt_pk_bf16_f32 v28, v28, v29
	v_cvt_pk_bf16_f32 v29, v30, v31
	v_mad_i64_i32 v[44:45], s[20:21], v40, s46, v[150:151]
	v_cvt_pk_bf16_f32 v30, v24, v25
	v_cvt_pk_bf16_f32 v31, v26, v27
	v_add_u32_e32 v24, 0xa0, v154
	global_store_dwordx4 v[108:109], v[92:95], off offset:256
	v_cvt_pk_bf16_f32 v76, v76, v77
	v_cvt_pk_bf16_f32 v77, v78, v79
	v_mad_i64_i32 v[92:93], s[20:21], v88, s46, v[150:151]
	v_cvt_pk_bf16_f32 v78, v72, v73
	v_cvt_pk_bf16_f32 v79, v74, v75
	v_add_u32_e32 v72, 48, v154
	global_store_dwordx4 v[44:45], v[28:31], off offset:256
	v_cvt_pk_bf16_f32 v12, v12, v13
	v_cvt_pk_bf16_f32 v13, v14, v15
	v_mad_i64_i32 v[28:29], s[20:21], v24, s46, v[150:151]
	v_cvt_pk_bf16_f32 v14, v8, v9
	v_cvt_pk_bf16_f32 v15, v10, v11
	v_add_u32_e32 v8, 0xb0, v154
	global_store_dwordx4 v[92:93], v[76:79], off offset:256
	global_store_dwordx4 v[28:29], v[12:15], off offset:256
	v_cvt_pk_bf16_f32 v124, v124, v125
	v_mad_i64_i32 v[76:77], s[20:21], v72, s46, v[150:151]
	v_mad_i64_i32 v[12:13], s[20:21], v8, s46, v[150:151]
	v_cvt_pk_bf16_f32 v125, v126, v127
	v_cvt_pk_bf16_f32 v126, v120, v121
	v_cvt_pk_bf16_f32 v127, v122, v123
	v_cvt_pk_bf16_f32 v104, v116, v117
	v_cvt_pk_bf16_f32 v105, v118, v119
	v_cvt_pk_bf16_f32 v106, v112, v113
	v_cvt_pk_bf16_f32 v107, v114, v115
	v_cvt_pk_bf16_f32 v88, v100, v101
	v_cvt_pk_bf16_f32 v89, v102, v103
	v_cvt_pk_bf16_f32 v90, v96, v97
	v_cvt_pk_bf16_f32 v91, v98, v99
	v_cvt_pk_bf16_f32 v72, v84, v85
	v_cvt_pk_bf16_f32 v73, v86, v87
	v_cvt_pk_bf16_f32 v74, v80, v81
	v_cvt_pk_bf16_f32 v75, v82, v83
	v_cvt_pk_bf16_f32 v71, v66, v67
	v_cvt_pk_bf16_f32 v60, v60, v61
	v_cvt_pk_bf16_f32 v61, v62, v63
	v_cvt_pk_bf16_f32 v62, v56, v57
	v_cvt_pk_bf16_f32 v63, v58, v59
	v_cvt_pk_bf16_f32 v40, v52, v53
	v_cvt_pk_bf16_f32 v41, v54, v55
	v_cvt_pk_bf16_f32 v42, v48, v49
	v_cvt_pk_bf16_f32 v43, v50, v51
	v_cvt_pk_bf16_f32 v24, v36, v37
	v_cvt_pk_bf16_f32 v25, v38, v39
	v_cvt_pk_bf16_f32 v26, v32, v33
	v_cvt_pk_bf16_f32 v27, v34, v35
	v_cvt_pk_bf16_f32 v8, v20, v21
	v_cvt_pk_bf16_f32 v9, v22, v23
	v_cvt_pk_bf16_f32 v10, v16, v17
	v_cvt_pk_bf16_f32 v11, v18, v19
	v_cvt_pk_bf16_f32 v4, v4, v5
	v_cvt_pk_bf16_f32 v5, v6, v7
	v_cvt_pk_bf16_f32 v6, v0, v1
	v_cvt_pk_bf16_f32 v7, v2, v3
	s_and_b64 vcc, exec, s[40:41]
	s_mov_b32 s47, s12
	s_mov_b32 s10, s14
	s_mov_b64 s[20:21], s[18:19]
	s_mov_b64 s[22:23], s[16:17]
	global_store_dwordx4 v[152:153], v[124:127], off
	global_store_dwordx4 v[108:109], v[104:107], off
	global_store_dwordx4 v[92:93], v[88:91], off
	global_store_dwordx4 v[76:77], v[72:75], off
	global_store_dwordx4 v[76:77], v[68:71], off offset:256
	global_store_dwordx4 v[64:65], v[60:63], off
	global_store_dwordx4 v[44:45], v[40:43], off
	global_store_dwordx4 v[28:29], v[24:27], off
	global_store_dwordx4 v[12:13], v[8:11], off
	global_store_dwordx4 v[12:13], v[4:7], off offset:256
	s_cbranch_vccz .LBB1_690
	s_waitcnt vmcnt(0)
	s_cmpk_gt_u32 s4, 0xff
	s_cbranch_scc1 .LBB1_697
	s_barrier

;     DI const char* a(const Unit& u) const { return (const char*)(A + (size_t)u.pm * BM * lda); }
;     DI const char* a(const Unit& u) const { return (const char*)(A + (size_t)u.pm * BM * 2048 + (u.pn >> 1) * 512); }
;     DI const char* a(const Unit& u) const { return (const char*)((u.pn < 12 ? A1 : A2) + (size_t)u.pm * BM * 512); }
; #define PG8_STAGE(bufoff, gbase, voff) do { _Pragma("unroll") for (int _i = 0; _i < 2; ++_i) \
;         __builtin_amdgcn_global_load_lds((const unsigned*)((const char*)(gbase) + (voff)[_i]), (LAS unsigned*)(lds + (bufoff) + ldsw + _i * 8192), 16, 0, 0); } while (0)
; #define PG8_LDA(dst, b, h) do { _Pragma("unroll") for (int m = 0; m < 4; ++m) _Pragma("unroll") for (int k = 0; k < 2; ++k) dst[m][k] = *(const LAS bf16x8*)(lds + PG8_SA(b, h) + aoff + m * 2048 + k * 1024); } while (0)
; #define PG8_LDB(dst, b, h) do { _Pragma("unroll") for (int n = 0; n < 2; ++n) _Pragma("unroll") for (int k = 0; k < 2; ++k) dst[n][k] = *(const LAS bf16x8*)(lds + PG8_SB(b, h) + boff + n * 2048 + k * 1024); } while (0)
; #define PG8_WAIT_L(n) asm volatile("s_waitcnt lgkmcnt(" #n ")" ::: "memory")
; template <class Map, class Epi>
; DI void gemm_phase(LAS unsigned char* lds, const Map& MP, const Epi& E, const int nM, const int nN, const int K, const int lda, const int ldb) {
;     ...
;         const bool has_next = sched_next(ui + 1, nM, nN, G, cblk, nxt);
;         const char* nA = has_next ? MP.a(nxt) : cA; const char* nB = has_next ? MP.b(nxt) : cB;
;         for (int t = 0; t < nt; t += 2) {
;             const bool last = (t == nt - 2);
;             const char* a1 = cA + (size_t)(t + 1) * kstep;
;             const char* a2 = last ? nA : cA + (size_t)(t + 2) * kstep; const char* b2 = last ? nB : cB + (size_t)(t + 2) * kstep;
;             const char* a3 = a2 + kstep; const char* b3 = b2 + kstep;
;             PG8_LDB(B0, 0, 0); PG8_SCHED; PG8_LDA(At, 0, 0); PG8_STAGE(PG8_SA(1, 1), a1 + hstepA, voffA);
;             PG8_WAIT_L(8); PG8_BAR; PG8_WAIT_L(0); PG8_MMA(0, 0, At, B0); PG8_BAR; PG8_SCHED;
;     ...
; #pragma unroll
;         for (int a = 0; a < 2; ++a)
; #pragma unroll
;             for (int b = 0; b < 2; ++b)
; #pragma unroll
;                 for (int m = 0; m < 4; ++m)
; #pragma unroll
;                     for (int n = 0; n < 2; ++n) acc[a][b][m][n] = (f32x4){0.f, 0.f, 0.f, 0.f};
;         cur = nxt; cA = nA; cB = nB; ++ui;
.LBB1_924:
	s_ashr_i32 s53, s52, 31
	s_lshl_b64 s[4:5], s[52:53], 20
	s_add_u32 s54, s18, s4
	v_cmp_lt_i64_e32 vcc, s[6:7], v[140:141]
	s_addc_u32 s55, s19, s5
	s_and_b64 s[4:5], vcc, exec
	s_cselect_b32 s4, s55, s13
	s_cselect_b32 s5, s54, s12
	s_ashr_i32 s47, s46, 31
	s_lshl_b64 s[6:7], s[46:47], 20
	s_add_u32 s6, s20, s6
	s_addc_u32 s7, s21, s7
	s_and_b64 s[14:15], vcc, exec
	s_cselect_b32 s37, s7, s11
	s_cselect_b32 s38, s6, s10
	s_add_u32 s39, s10, 0x100
	s_addc_u32 s47, s11, 0
	s_add_u32 s10, s12, 0x80080
	v_mov_b32_e32 v0, 0
	s_addc_u32 s11, s13, 0
	s_mov_b32 s48, -2
	v_mov_b32_e32 v1, v0
	v_mov_b32_e32 v2, v0
	v_mov_b32_e32 v3, v0
	v_mov_b32_e32 v4, v0
	v_mov_b32_e32 v5, v0
	v_mov_b32_e32 v6, v0
	v_mov_b32_e32 v7, v0
	v_mov_b32_e32 v16, v0
	v_mov_b32_e32 v17, v0
	v_mov_b32_e32 v18, v0
	v_mov_b32_e32 v19, v0
	v_mov_b32_e32 v20, v0
	v_mov_b32_e32 v21, v0
	v_mov_b32_e32 v22, v0
	v_mov_b32_e32 v23, v0
	v_mov_b32_e32 v32, v0
	v_mov_b32_e32 v33, v0
	v_mov_b32_e32 v34, v0
	v_mov_b32_e32 v35, v0
	v_mov_b32_e32 v36, v0
	v_mov_b32_e32 v37, v0
	v_mov_b32_e32 v38, v0
	v_mov_b32_e32 v39, v0
	v_mov_b32_e32 v48, v0
	v_mov_b32_e32 v49, v0
	v_mov_b32_e32 v50, v0
	v_mov_b32_e32 v51, v0
	v_mov_b32_e32 v52, v0
	v_mov_b32_e32 v53, v0
	v_mov_b32_e32 v54, v0
	v_mov_b32_e32 v55, v0
	v_mov_b32_e32 v8, v0
	v_mov_b32_e32 v9, v0
	v_mov_b32_e32 v10, v0
	v_mov_b32_e32 v11, v0
	v_mov_b32_e32 v12, v0
	v_mov_b32_e32 v13, v0
	v_mov_b32_e32 v14, v0
	v_mov_b32_e32 v15, v0
	v_mov_b32_e32 v24, v0
	v_mov_b32_e32 v25, v0
	v_mov_b32_e32 v26, v0
	v_mov_b32_e32 v27, v0
	v_mov_b32_e32 v28, v0
	v_mov_b32_e32 v29, v0
	v_mov_b32_e32 v30, v0
	v_mov_b32_e32 v31, v0
	v_mov_b32_e32 v40, v0
	v_mov_b32_e32 v41, v0
	v_mov_b32_e32 v42, v0
	v_mov_b32_e32 v43, v0
	v_mov_b32_e32 v44, v0
	v_mov_b32_e32 v45, v0
	v_mov_b32_e32 v46, v0
	v_mov_b32_e32 v47, v0
	v_mov_b32_e32 v56, v0
	v_mov_b32_e32 v57, v0
	v_mov_b32_e32 v58, v0
	v_mov_b32_e32 v59, v0
	v_mov_b32_e32 v60, v0
	v_mov_b32_e32 v61, v0
	v_mov_b32_e32 v62, v0
	v_mov_b32_e32 v63, v0
	v_mov_b32_e32 v64, v0
	v_mov_b32_e32 v65, v0
	v_mov_b32_e32 v66, v0
	v_mov_b32_e32 v67, v0
	v_mov_b32_e32 v68, v0
	v_mov_b32_e32 v69, v0
	v_mov_b32_e32 v70, v0
	v_mov_b32_e32 v71, v0
	v_mov_b32_e32 v80, v0
	v_mov_b32_e32 v81, v0
	v_mov_b32_e32 v82, v0
	v_mov_b32_e32 v83, v0
	v_mov_b32_e32 v84, v0
	v_mov_b32_e32 v85, v0
	v_mov_b32_e32 v86, v0
	v_mov_b32_e32 v87, v0
	v_mov_b32_e32 v96, v0
	v_mov_b32_e32 v97, v0
	v_mov_b32_e32 v98, v0
	v_mov_b32_e32 v99, v0
	v_mov_b32_e32 v100, v0
	v_mov_b32_e32 v101, v0
	v_mov_b32_e32 v102, v0
	v_mov_b32_e32 v103, v0
	v_mov_b32_e32 v112, v0
	v_mov_b32_e32 v113, v0
	v_mov_b32_e32 v114, v0
	v_mov_b32_e32 v115, v0
	v_mov_b32_e32 v116, v0
	v_mov_b32_e32 v117, v0
	v_mov_b32_e32 v118, v0
	v_mov_b32_e32 v119, v0
	v_mov_b32_e32 v72, v0
	v_mov_b32_e32 v73, v0
	v_mov_b32_e32 v74, v0
	v_mov_b32_e32 v75, v0
	v_mov_b32_e32 v76, v0
	v_mov_b32_e32 v77, v0
	v_mov_b32_e32 v78, v0
	v_mov_b32_e32 v79, v0
	v_mov_b32_e32 v88, v0
	v_mov_b32_e32 v89, v0
	v_mov_b32_e32 v90, v0
	v_mov_b32_e32 v91, v0
	v_mov_b32_e32 v92, v0
	v_mov_b32_e32 v93, v0
	v_mov_b32_e32 v94, v0
	v_mov_b32_e32 v95, v0
	v_mov_b32_e32 v104, v0
	v_mov_b32_e32 v105, v0
	v_mov_b32_e32 v106, v0
	v_mov_b32_e32 v107, v0
	v_mov_b32_e32 v108, v0
	v_mov_b32_e32 v109, v0
	v_mov_b32_e32 v110, v0
	v_mov_b32_e32 v111, v0
	v_mov_b32_e32 v120, v0
	v_mov_b32_e32 v121, v0
	v_mov_b32_e32 v122, v0
	v_mov_b32_e32 v123, v0
	v_mov_b32_e32 v124, v0
	v_mov_b32_e32 v125, v0
	v_mov_b32_e32 v126, v0
	v_mov_b32_e32 v127, v0
	ds_read_b128 v[152:155], v149
	ds_read_b128 v[156:159], v149 offset:1024
	ds_read_b128 v[160:163], v149 offset:2048
	ds_read_b128 v[164:167], v149 offset:3072
.LBB1_925:
	s_add_u32 s3, s10, 0xfff80080
	s_addc_u32 s12, s11, -1
	s_cmp_eq_u32 s48, 28
	s_cselect_b32 s15, s4, s12
	s_cselect_b32 s14, s5, s3
	s_cselect_b32 s13, s37, s47
	s_cselect_b32 s12, s38, s39
	s_add_i32 m0, s24, 0xc000
	ds_read_b128 v[168:171], v150
	ds_read_b128 v[172:175], v150 offset:1024
	ds_read_b128 v[176:179], v150 offset:2048
	ds_read_b128 v[180:183], v150 offset:3072
	ds_read_b128 v[184:187], v150 offset:4096
	ds_read_b128 v[188:191], v150 offset:5120
	ds_read_b128 v[192:195], v150 offset:6144
	ds_read_b128 v[198:201], v150 offset:7168
	global_load_lds_dwordx4 v138, s[10:11]
	s_add_i32 m0, s24, 0xe000
	s_nop 0
	global_load_lds_dwordx4 v136, s[10:11]
	s_waitcnt lgkmcnt(8)
	s_barrier
	s_setprio 1
	s_waitcnt lgkmcnt(7)
	v_mfma_f32_16x16x32_bf16 v[124:127], v[152:155], v[168:171], v[124:127]
	v_mfma_f32_16x16x32_bf16 v[120:123], v[160:163], v[168:171], v[120:123]
	s_waitcnt lgkmcnt(5)
	v_mfma_f32_16x16x32_bf16 v[108:111], v[152:155], v[176:179], v[108:111]
	v_mfma_f32_16x16x32_bf16 v[104:107], v[160:163], v[176:179], v[104:107]
	s_waitcnt lgkmcnt(3)
	v_mfma_f32_16x16x32_bf16 v[92:95], v[152:155], v[184:187], v[92:95]
	v_mfma_f32_16x16x32_bf16 v[88:91], v[160:163], v[184:187], v[88:91]
	s_waitcnt lgkmcnt(1)
	v_mfma_f32_16x16x32_bf16 v[76:79], v[152:155], v[192:195], v[76:79]
	v_mfma_f32_16x16x32_bf16 v[72:75], v[160:163], v[192:195], v[72:75]
	v_mfma_f32_16x16x32_bf16 v[124:127], v[156:159], v[172:175], v[124:127]
	v_mfma_f32_16x16x32_bf16 v[120:123], v[164:167], v[172:175], v[120:123]
	v_mfma_f32_16x16x32_bf16 v[108:111], v[156:159], v[180:183], v[108:111]
	v_mfma_f32_16x16x32_bf16 v[104:107], v[164:167], v[180:183], v[104:107]
	v_mfma_f32_16x16x32_bf16 v[92:95], v[156:159], v[188:191], v[92:95]
	v_mfma_f32_16x16x32_bf16 v[88:91], v[164:167], v[188:191], v[88:91]
	s_waitcnt lgkmcnt(0)
	v_mfma_f32_16x16x32_bf16 v[76:79], v[156:159], v[198:201], v[76:79]
	v_mfma_f32_16x16x32_bf16 v[72:75], v[164:167], v[198:201], v[72:75]
	s_setprio 0
	s_barrier
; #define PG8_STAGE(bufoff, gbase, voff) do { _Pragma("unroll") for (int _i = 0; _i < 2; ++_i) \
;         __builtin_amdgcn_global_load_lds((const unsigned*)((const char*)(gbase) + (voff)[_i]), (LAS unsigned*)(lds + (bufoff) + ldsw + _i * 8192), 16, 0, 0); } while (0)
; #define PG8_LDA(dst, b, h) do { _Pragma("unroll") for (int m = 0; m < 4; ++m) _Pragma("unroll") for (int k = 0; k < 2; ++k) dst[m][k] = *(const LAS bf16x8*)(lds + PG8_SA(b, h) + aoff + m * 2048 + k * 1024); } while (0)
; #define PG8_LDB(dst, b, h) do { _Pragma("unroll") for (int n = 0; n < 2; ++n) _Pragma("unroll") for (int k = 0; k < 2; ++k) dst[n][k] = *(const LAS bf16x8*)(lds + PG8_SB(b, h) + boff + n * 2048 + k * 1024); } while (0)
; #define PG8_MMA(ai, bj, At, Bt) do { __builtin_amdgcn_s_setprio(1); _Pragma("unroll") for (int m = 0; m < 4; ++m) _Pragma("unroll") for (int n = 0; n < 2; ++n) _Pragma("unroll") for (int k = 0; k < 2; ++k) \
;         acc[ai][bj][m][n] = __builtin_amdgcn_mfma_f32_16x16x32_bf16(Bt[n][k], At[m][k], acc[ai][bj][m][n], 0, 0, 0); __builtin_amdgcn_s_setprio(0); } while (0)
; #define PG8_WAIT_V(n) asm volatile("s_waitcnt vmcnt(" #n ")" ::: "memory")
; #define PG8_WAIT_L(n) asm volatile("s_waitcnt lgkmcnt(" #n ")" ::: "memory")
; #define PG8_BAR __builtin_amdgcn_s_barrier()
; #define PG8_SCHED __builtin_amdgcn_sched_barrier(0)
; template <class Map, class Epi>
; DI void gemm_phase(LAS unsigned char* lds, const Map& MP, const Epi& E, const int nM, const int nN, const int K, const int lda, const int ldb) {
;     ...
;             PG8_LDB(B1, 0, 1); PG8_STAGE(PG8_SB(0, 0), b2, voffB);
;             PG8_BAR; PG8_WAIT_L(0); PG8_MMA(0, 1, At, B1); PG8_BAR;
;             PG8_LDA(At, 0, 1); PG8_STAGE(PG8_SA(0, 0), a2, voffA);
;             PG8_BAR; PG8_WAIT_L(0); PG8_MMA(1, 0, At, B0); PG8_BAR; PG8_SCHED;
;             PG8_STAGE(PG8_SB(0, 1), b2 + hstepB, voffB);
;             PG8_WAIT_V(6); PG8_BAR; PG8_MMA(1, 1, At, B1); PG8_BAR;
;             PG8_LDB(B0, 1, 0); PG8_SCHED; PG8_LDA(At, 1, 0); PG8_STAGE(PG8_SA(0, 1), a2 + hstepA, voffA);
	s_add_i32 s3, s35, s22
	v_lshl_add_u64 v[144:145], s[12:13], 0, v[132:133]
	s_mov_b32 m0, s3
	ds_read_b128 v[202:205], v151
	ds_read_b128 v[206:209], v151 offset:1024
	ds_read_b128 v[210:213], v151 offset:2048
	ds_read_b128 v[214:217], v151 offset:3072
	global_load_lds_dwordx4 v[144:145], off
	v_lshl_add_u64 v[218:219], s[12:13], 0, v[128:129]
	s_add_i32 m0, s3, 0x2000
	s_nop 0
	global_load_lds_dwordx4 v[218:219], off
	s_barrier
	s_setprio 1
	s_waitcnt lgkmcnt(3)
	v_mfma_f32_16x16x32_bf16 v[116:119], v[202:205], v[168:171], v[116:119]
	s_waitcnt lgkmcnt(1)
	v_mfma_f32_16x16x32_bf16 v[112:115], v[210:213], v[168:171], v[112:115]
	v_mfma_f32_16x16x32_bf16 v[100:103], v[202:205], v[176:179], v[100:103]
	v_mfma_f32_16x16x32_bf16 v[96:99], v[210:213], v[176:179], v[96:99]
	v_mfma_f32_16x16x32_bf16 v[84:87], v[202:205], v[184:187], v[84:87]
	v_mfma_f32_16x16x32_bf16 v[80:83], v[210:213], v[184:187], v[80:83]
	v_mfma_f32_16x16x32_bf16 v[68:71], v[202:205], v[192:195], v[68:71]
	v_mfma_f32_16x16x32_bf16 v[64:67], v[210:213], v[192:195], v[64:67]
	v_mfma_f32_16x16x32_bf16 v[116:119], v[206:209], v[172:175], v[116:119]
	s_waitcnt lgkmcnt(0)
	v_mfma_f32_16x16x32_bf16 v[112:115], v[214:217], v[172:175], v[112:115]
	v_mfma_f32_16x16x32_bf16 v[100:103], v[206:209], v[180:183], v[100:103]
	v_mfma_f32_16x16x32_bf16 v[96:99], v[214:217], v[180:183], v[96:99]
	v_mfma_f32_16x16x32_bf16 v[84:87], v[206:209], v[188:191], v[84:87]
	v_mfma_f32_16x16x32_bf16 v[80:83], v[214:217], v[188:191], v[80:83]
	v_mfma_f32_16x16x32_bf16 v[68:71], v[206:209], v[198:201], v[68:71]
	v_mfma_f32_16x16x32_bf16 v[64:67], v[214:217], v[198:201], v[64:67]
	s_setprio 0
	s_mov_b32 m0, s24
	v_lshl_add_u64 v[220:221], s[14:15], 0, v[134:135]
	s_barrier
	ds_read_b128 v[168:171], v150 offset:16384
	ds_read_b128 v[172:175], v150 offset:17408
	ds_read_b128 v[176:179], v150 offset:18432
	ds_read_b128 v[180:183], v150 offset:19456
	ds_read_b128 v[184:187], v150 offset:20480
	ds_read_b128 v[188:191], v150 offset:21504
	ds_read_b128 v[192:195], v150 offset:22528
	ds_read_b128 v[198:201], v150 offset:23552
	global_load_lds_dwordx4 v[220:221], off
	v_lshl_add_u64 v[222:223], s[14:15], 0, v[130:131]
	s_mov_b32 m0, s9
	s_nop 0
	global_load_lds_dwordx4 v[222:223], off
	s_waitcnt vmcnt(10)
	s_barrier
	s_setprio 1
	s_waitcnt lgkmcnt(7)
	v_mfma_f32_16x16x32_bf16 v[60:63], v[152:155], v[168:171], v[60:63]
	v_mfma_f32_16x16x32_bf16 v[56:59], v[160:163], v[168:171], v[56:59]
	s_waitcnt lgkmcnt(5)
	v_mfma_f32_16x16x32_bf16 v[44:47], v[152:155], v[176:179], v[44:47]
	v_mfma_f32_16x16x32_bf16 v[40:43], v[160:163], v[176:179], v[40:43]
	s_waitcnt lgkmcnt(3)
	v_mfma_f32_16x16x32_bf16 v[28:31], v[152:155], v[184:187], v[28:31]
	v_mfma_f32_16x16x32_bf16 v[24:27], v[160:163], v[184:187], v[24:27]
	s_waitcnt lgkmcnt(1)
	v_mfma_f32_16x16x32_bf16 v[12:15], v[152:155], v[192:195], v[12:15]
	v_mfma_f32_16x16x32_bf16 v[8:11], v[160:163], v[192:195], v[8:11]
	v_mfma_f32_16x16x32_bf16 v[60:63], v[156:159], v[172:175], v[60:63]
	v_mfma_f32_16x16x32_bf16 v[56:59], v[164:167], v[172:175], v[56:59]
	v_mfma_f32_16x16x32_bf16 v[44:47], v[156:159], v[180:183], v[44:47]
	v_mfma_f32_16x16x32_bf16 v[40:43], v[164:167], v[180:183], v[40:43]
	v_mfma_f32_16x16x32_bf16 v[28:31], v[156:159], v[188:191], v[28:31]
	v_mfma_f32_16x16x32_bf16 v[24:27], v[164:167], v[188:191], v[24:27]
	s_waitcnt lgkmcnt(0)
	v_mfma_f32_16x16x32_bf16 v[12:15], v[156:159], v[198:201], v[12:15]
	v_mfma_f32_16x16x32_bf16 v[8:11], v[164:167], v[198:201], v[8:11]
	s_setprio 0
	s_barrier
	s_add_u32 s56, s12, 0x80000
	s_addc_u32 s57, s13, 0
	s_add_i32 s3, s36, s22
	s_mov_b32 m0, s3
	s_nop 0
	global_load_lds_dwordx4 v132, s[56:57]
	s_add_i32 m0, s3, 0x2000
	s_nop 0
	global_load_lds_dwordx4 v128, s[56:57]
	s_waitcnt vmcnt(6)
	s_barrier
	s_setprio 1
	v_mfma_f32_16x16x32_bf16 v[52:55], v[202:205], v[168:171], v[52:55]
	v_mfma_f32_16x16x32_bf16 v[48:51], v[210:213], v[168:171], v[48:51]
	s_add_i32 s3, 0, 0x18000
	v_add_u32_e32 v164, s3, v148
	ds_read_b128 v[152:155], v164
	v_mfma_f32_16x16x32_bf16 v[36:39], v[202:205], v[176:179], v[36:39]
	v_mfma_f32_16x16x32_bf16 v[32:35], v[210:213], v[176:179], v[32:35]
	ds_read_b128 v[156:159], v164 offset:1024
	v_mfma_f32_16x16x32_bf16 v[20:23], v[202:205], v[184:187], v[20:23]
	v_mfma_f32_16x16x32_bf16 v[16:19], v[210:213], v[184:187], v[16:19]
	ds_read_b128 v[160:163], v164 offset:2048
	v_mfma_f32_16x16x32_bf16 v[4:7], v[202:205], v[192:195], v[4:7]
	v_mfma_f32_16x16x32_bf16 v[0:3], v[210:213], v[192:195], v[0:3]
	ds_read_b128 v[164:167], v164 offset:3072
	v_mfma_f32_16x16x32_bf16 v[52:55], v[206:209], v[172:175], v[52:55]
	v_mfma_f32_16x16x32_bf16 v[48:51], v[214:217], v[172:175], v[48:51]
	v_mfma_f32_16x16x32_bf16 v[36:39], v[206:209], v[180:183], v[36:39]
	v_mfma_f32_16x16x32_bf16 v[32:35], v[214:217], v[180:183], v[32:35]
	v_mfma_f32_16x16x32_bf16 v[20:23], v[206:209], v[188:191], v[20:23]
	v_mfma_f32_16x16x32_bf16 v[16:19], v[214:217], v[188:191], v[16:19]
	v_mfma_f32_16x16x32_bf16 v[4:7], v[206:209], v[198:201], v[4:7]
	v_mfma_f32_16x16x32_bf16 v[0:3], v[214:217], v[198:201], v[0:3]
	s_setprio 0
	s_barrier
	s_add_u32 s14, s14, 0x80000
	s_addc_u32 s15, s15, 0
	s_mov_b32 m0, s25
	ds_read_b128 v[168:171], v150 offset:32768
	ds_read_b128 v[172:175], v150 offset:33792
	ds_read_b128 v[176:179], v150 offset:34816
	ds_read_b128 v[180:183], v150 offset:35840
	ds_read_b128 v[184:187], v150 offset:36864
	ds_read_b128 v[188:191], v150 offset:37888
	ds_read_b128 v[192:195], v150 offset:38912
	ds_read_b128 v[198:201], v150 offset:39936
	global_load_lds_dwordx4 v134, s[14:15]
	s_mov_b32 m0, s26
	s_nop 0
	global_load_lds_dwordx4 v130, s[14:15]
	s_waitcnt lgkmcnt(8)
	s_barrier
; #define PG8_STAGE(bufoff, gbase, voff) do { _Pragma("unroll") for (int _i = 0; _i < 2; ++_i) \
;         __builtin_amdgcn_global_load_lds((const unsigned*)((const char*)(gbase) + (voff)[_i]), (LAS unsigned*)(lds + (bufoff) + ldsw + _i * 8192), 16, 0, 0); } while (0)
; #define PG8_LDA(dst, b, h) do { _Pragma("unroll") for (int m = 0; m < 4; ++m) _Pragma("unroll") for (int k = 0; k < 2; ++k) dst[m][k] = *(const LAS bf16x8*)(lds + PG8_SA(b, h) + aoff + m * 2048 + k * 1024); } while (0)
; #define PG8_LDB(dst, b, h) do { _Pragma("unroll") for (int n = 0; n < 2; ++n) _Pragma("unroll") for (int k = 0; k < 2; ++k) dst[n][k] = *(const LAS bf16x8*)(lds + PG8_SB(b, h) + boff + n * 2048 + k * 1024); } while (0)
; #define PG8_MMA(ai, bj, At, Bt) do { __builtin_amdgcn_s_setprio(1); _Pragma("unroll") for (int m = 0; m < 4; ++m) _Pragma("unroll") for (int n = 0; n < 2; ++n) _Pragma("unroll") for (int k = 0; k < 2; ++k) \
;         acc[ai][bj][m][n] = __builtin_amdgcn_mfma_f32_16x16x32_bf16(Bt[n][k], At[m][k], acc[ai][bj][m][n], 0, 0, 0); __builtin_amdgcn_s_setprio(0); } while (0)
; #define PG8_WAIT_V(n) asm volatile("s_waitcnt vmcnt(" #n ")" ::: "memory")
; #define PG8_WAIT_L(n) asm volatile("s_waitcnt lgkmcnt(" #n ")" ::: "memory")
; #define PG8_BAR __builtin_amdgcn_s_barrier()
; #define PG8_SCHED __builtin_amdgcn_sched_barrier(0)
; template <class Map, class Epi>
; DI void gemm_phase(LAS unsigned char* lds, const Map& MP, const Epi& E, const int nM, const int nN, const int K, const int lda, const int ldb) {
;     ...
;             PG8_WAIT_L(8); PG8_BAR; PG8_WAIT_L(0); PG8_MMA(0, 0, At, B0); PG8_BAR; PG8_SCHED;
;             PG8_LDB(B1, 1, 1); PG8_STAGE(PG8_SB(1, 0), b3, voffB);
;             PG8_BAR; PG8_WAIT_L(0); PG8_MMA(0, 1, At, B1); PG8_BAR;
;             PG8_LDA(At, 1, 1); PG8_STAGE(PG8_SA(1, 0), a3, voffA);
;             PG8_BAR; PG8_WAIT_L(0); PG8_MMA(1, 0, At, B0); PG8_BAR; PG8_SCHED;
;             PG8_STAGE(PG8_SB(1, 1), b3 + hstepB, voffB);
;             PG8_WAIT_V(6); PG8_BAR; PG8_MMA(1, 1, At, B1); PG8_BAR;
	s_setprio 1
	s_waitcnt lgkmcnt(7)
	v_mfma_f32_16x16x32_bf16 v[124:127], v[152:155], v[168:171], v[124:127]
	v_mfma_f32_16x16x32_bf16 v[120:123], v[160:163], v[168:171], v[120:123]
	s_waitcnt lgkmcnt(5)
	v_mfma_f32_16x16x32_bf16 v[108:111], v[152:155], v[176:179], v[108:111]
	v_mfma_f32_16x16x32_bf16 v[104:107], v[160:163], v[176:179], v[104:107]
	s_waitcnt lgkmcnt(3)
	v_mfma_f32_16x16x32_bf16 v[92:95], v[152:155], v[184:187], v[92:95]
	v_mfma_f32_16x16x32_bf16 v[88:91], v[160:163], v[184:187], v[88:91]
	s_waitcnt lgkmcnt(1)
	v_mfma_f32_16x16x32_bf16 v[76:79], v[152:155], v[192:195], v[76:79]
	v_mfma_f32_16x16x32_bf16 v[72:75], v[160:163], v[192:195], v[72:75]
	v_mfma_f32_16x16x32_bf16 v[124:127], v[156:159], v[172:175], v[124:127]
	v_mfma_f32_16x16x32_bf16 v[120:123], v[164:167], v[172:175], v[120:123]
	v_mfma_f32_16x16x32_bf16 v[108:111], v[156:159], v[180:183], v[108:111]
	v_mfma_f32_16x16x32_bf16 v[104:107], v[164:167], v[180:183], v[104:107]
	v_mfma_f32_16x16x32_bf16 v[92:95], v[156:159], v[188:191], v[92:95]
	v_mfma_f32_16x16x32_bf16 v[88:91], v[164:167], v[188:191], v[88:91]
	s_waitcnt lgkmcnt(0)
	v_mfma_f32_16x16x32_bf16 v[76:79], v[156:159], v[198:201], v[76:79]
	v_mfma_f32_16x16x32_bf16 v[72:75], v[164:167], v[198:201], v[72:75]
	s_setprio 0
	s_barrier
	s_add_i32 s14, 0, 0x1c000
	s_add_i32 s3, s3, s22
	v_add_u32_e32 v196, s14, v148
	v_lshl_add_u64 v[144:145], v[144:145], 0, s[44:45]
	s_mov_b32 m0, s3
	ds_read_b128 v[202:205], v196
	ds_read_b128 v[206:209], v196 offset:1024
	ds_read_b128 v[210:213], v196 offset:2048
	ds_read_b128 v[214:217], v196 offset:3072
	global_load_lds_dwordx4 v[144:145], off
	v_lshl_add_u64 v[144:145], v[218:219], 0, s[44:45]
	s_add_i32 m0, s3, 0x2000
	s_nop 0
	global_load_lds_dwordx4 v[144:145], off
	s_barrier
	s_setprio 1
	s_waitcnt lgkmcnt(3)
	v_mfma_f32_16x16x32_bf16 v[116:119], v[202:205], v[168:171], v[116:119]
	s_waitcnt lgkmcnt(1)
	v_mfma_f32_16x16x32_bf16 v[112:115], v[210:213], v[168:171], v[112:115]
	v_mfma_f32_16x16x32_bf16 v[100:103], v[202:205], v[176:179], v[100:103]
	v_mfma_f32_16x16x32_bf16 v[96:99], v[210:213], v[176:179], v[96:99]
	v_mfma_f32_16x16x32_bf16 v[84:87], v[202:205], v[184:187], v[84:87]
	v_mfma_f32_16x16x32_bf16 v[80:83], v[210:213], v[184:187], v[80:83]
	v_mfma_f32_16x16x32_bf16 v[68:71], v[202:205], v[192:195], v[68:71]
	v_mfma_f32_16x16x32_bf16 v[64:67], v[210:213], v[192:195], v[64:67]
	v_mfma_f32_16x16x32_bf16 v[116:119], v[206:209], v[172:175], v[116:119]
	s_waitcnt lgkmcnt(0)
	v_mfma_f32_16x16x32_bf16 v[112:115], v[214:217], v[172:175], v[112:115]
	v_mfma_f32_16x16x32_bf16 v[100:103], v[206:209], v[180:183], v[100:103]
	v_mfma_f32_16x16x32_bf16 v[96:99], v[214:217], v[180:183], v[96:99]
	v_mfma_f32_16x16x32_bf16 v[84:87], v[206:209], v[188:191], v[84:87]
	v_mfma_f32_16x16x32_bf16 v[80:83], v[214:217], v[188:191], v[80:83]
	v_mfma_f32_16x16x32_bf16 v[68:71], v[206:209], v[198:201], v[68:71]
	v_mfma_f32_16x16x32_bf16 v[64:67], v[214:217], v[198:201], v[64:67]
	s_setprio 0
	s_mov_b32 m0, s30
	v_lshl_add_u64 v[144:145], v[220:221], 0, s[44:45]
	s_barrier
	ds_read_b128 v[168:171], v150 offset:49152
	ds_read_b128 v[172:175], v150 offset:50176
	ds_read_b128 v[176:179], v150 offset:51200
	ds_read_b128 v[180:183], v150 offset:52224
	ds_read_b128 v[184:187], v150 offset:53248
	ds_read_b128 v[188:191], v150 offset:54272
	ds_read_b128 v[192:195], v150 offset:55296
	ds_read_b128 v[198:201], v150 offset:56320
	global_load_lds_dwordx4 v[144:145], off
	v_lshl_add_u64 v[144:145], v[222:223], 0, s[44:45]
	s_mov_b32 m0, s31
	s_nop 0
	global_load_lds_dwordx4 v[144:145], off
	s_waitcnt vmcnt(10)
	s_barrier
	s_setprio 1
	s_waitcnt lgkmcnt(7)
	v_mfma_f32_16x16x32_bf16 v[60:63], v[152:155], v[168:171], v[60:63]
	v_mfma_f32_16x16x32_bf16 v[56:59], v[160:163], v[168:171], v[56:59]
	s_waitcnt lgkmcnt(5)
	v_mfma_f32_16x16x32_bf16 v[44:47], v[152:155], v[176:179], v[44:47]
	v_mfma_f32_16x16x32_bf16 v[40:43], v[160:163], v[176:179], v[40:43]
	s_waitcnt lgkmcnt(3)
	v_mfma_f32_16x16x32_bf16 v[28:31], v[152:155], v[184:187], v[28:31]
	v_mfma_f32_16x16x32_bf16 v[24:27], v[160:163], v[184:187], v[24:27]
	s_waitcnt lgkmcnt(1)
	v_mfma_f32_16x16x32_bf16 v[12:15], v[152:155], v[192:195], v[12:15]
	v_mfma_f32_16x16x32_bf16 v[8:11], v[160:163], v[192:195], v[8:11]
	v_mfma_f32_16x16x32_bf16 v[60:63], v[156:159], v[172:175], v[60:63]
	v_mfma_f32_16x16x32_bf16 v[56:59], v[164:167], v[172:175], v[56:59]
	v_mfma_f32_16x16x32_bf16 v[44:47], v[156:159], v[180:183], v[44:47]
	v_mfma_f32_16x16x32_bf16 v[40:43], v[164:167], v[180:183], v[40:43]
	v_mfma_f32_16x16x32_bf16 v[28:31], v[156:159], v[188:191], v[28:31]
	v_mfma_f32_16x16x32_bf16 v[24:27], v[164:167], v[188:191], v[24:27]
	s_waitcnt lgkmcnt(0)
	v_mfma_f32_16x16x32_bf16 v[12:15], v[156:159], v[198:201], v[12:15]
	v_mfma_f32_16x16x32_bf16 v[8:11], v[164:167], v[198:201], v[8:11]
	s_setprio 0
	s_barrier
	s_add_u32 s12, s12, 0x80080
	s_addc_u32 s13, s13, 0
	s_add_i32 s3, s14, s22
	s_mov_b32 m0, s3
	s_nop 0
	global_load_lds_dwordx4 v132, s[12:13]
	s_add_i32 m0, s3, 0x2000
	s_nop 0
	global_load_lds_dwordx4 v128, s[12:13]
	s_waitcnt vmcnt(6)
	s_barrier
; DI unsigned pack2(float a, float b) { f32x2 v = {a, b}; hwbf16x2 r = __builtin_convertvector(v, hwbf16x2); return __builtin_bit_cast(unsigned, r); }
; DI float bflo(unsigned w) { return __uint_as_float(w << 16); }
; DI float bfhi(unsigned w) { return __uint_as_float(w & 0xffff0000u); }
; #define PG8_LDA(dst, b, h) do { _Pragma("unroll") for (int m = 0; m < 4; ++m) _Pragma("unroll") for (int k = 0; k < 2; ++k) dst[m][k] = *(const LAS bf16x8*)(lds + PG8_SA(b, h) + aoff + m * 2048 + k * 1024); } while (0)
;     DI void operator()(const f32x4 (&acc)[2][2][4][2], const Unit& u, int wr, int wc, int fr, int fq) const {
;     ...
;             for (int m = 0; m < 4; ++m) { const size_t ro = (size_t)(row0 + ai * HALF + m * 16) * D + col0;
; #pragma unroll
;                 for (int bj = 0; bj < 2; ++bj) {
;                     f32x4 x0, x1;
;                     if constexpr (IB) { const u32x4 w = *(const u32x4*)((const bf16_t*)Xin + ro + bj * HALF);
;                         x0 = (f32x4){bflo(w[0]), bfhi(w[0]), bflo(w[1]), bfhi(w[1])}; x1 = (f32x4){bflo(w[2]), bfhi(w[2]), bflo(w[3]), bfhi(w[3])}; }
;                     else { x0 = *(const f32x4*)((const float*)Xin + ro + bj * HALF); x1 = *(const f32x4*)((const float*)Xin + ro + bj * HALF + 4); }
;                     x0 += acc[ai][bj][m][0] * sc[bj][0]; x1 += acc[ai][bj][m][1] * sc[bj][1];
;                     if constexpr (OB) { u32x4 o; o[0] = pack2(x0[0], x0[1]); o[1] = pack2(x0[2], x0[3]); o[2] = pack2(x1[0], x1[1]); o[3] = pack2(x1[2], x1[3]);
;                         *(u32x4*)((bf16_t*)Xout + ro + bj * HALF) = o; }
;                     else { *(f32x4*)((float*)Xout + ro + bj * HALF) = x0; *(f32x4*)((float*)Xout + ro + bj * HALF + 4) = x1; } } }
; template <class Map, class Epi>
; DI void gemm_phase(LAS unsigned char* lds, const Map& MP, const Epi& E, const int nM, const int nN, const int K, const int lda, const int ldb) {
;     ...
;             PG8_BAR; PG8_WAIT_L(0); PG8_MMA(0, 1, At, B1); PG8_BAR;
;             PG8_LDA(At, 1, 1); PG8_STAGE(PG8_SA(1, 0), a3, voffA);
;             PG8_BAR; PG8_WAIT_L(0); PG8_MMA(1, 0, At, B0); PG8_BAR; PG8_SCHED;
;             PG8_STAGE(PG8_SB(1, 1), b3 + hstepB, voffB);
;             PG8_WAIT_V(6); PG8_BAR; PG8_MMA(1, 1, At, B1); PG8_BAR;
;         }
;         { int frr = fr, fqq = fq; asm volatile("" : "+v"(frr), "+v"(fqq)); E(acc, cur, wr, wc, frr, fqq); }
	s_setprio 1
	v_mfma_f32_16x16x32_bf16 v[52:55], v[202:205], v[168:171], v[52:55]
	v_mfma_f32_16x16x32_bf16 v[48:51], v[210:213], v[168:171], v[48:51]
	ds_read_b128 v[152:155], v149
	v_mfma_f32_16x16x32_bf16 v[36:39], v[202:205], v[176:179], v[36:39]
	v_mfma_f32_16x16x32_bf16 v[32:35], v[210:213], v[176:179], v[32:35]
	ds_read_b128 v[156:159], v149 offset:1024
	v_mfma_f32_16x16x32_bf16 v[20:23], v[202:205], v[184:187], v[20:23]
	v_mfma_f32_16x16x32_bf16 v[16:19], v[210:213], v[184:187], v[16:19]
	ds_read_b128 v[160:163], v149 offset:2048
	v_mfma_f32_16x16x32_bf16 v[4:7], v[202:205], v[192:195], v[4:7]
	v_mfma_f32_16x16x32_bf16 v[0:3], v[210:213], v[192:195], v[0:3]
	ds_read_b128 v[164:167], v149 offset:3072
	v_mfma_f32_16x16x32_bf16 v[52:55], v[206:209], v[172:175], v[52:55]
	v_mfma_f32_16x16x32_bf16 v[48:51], v[214:217], v[172:175], v[48:51]
	v_mfma_f32_16x16x32_bf16 v[36:39], v[206:209], v[180:183], v[36:39]
	v_mfma_f32_16x16x32_bf16 v[32:35], v[214:217], v[180:183], v[32:35]
	v_mfma_f32_16x16x32_bf16 v[20:23], v[206:209], v[188:191], v[20:23]
	v_mfma_f32_16x16x32_bf16 v[16:19], v[214:217], v[188:191], v[16:19]
	v_mfma_f32_16x16x32_bf16 v[4:7], v[206:209], v[198:201], v[4:7]
	v_mfma_f32_16x16x32_bf16 v[0:3], v[214:217], v[198:201], v[0:3]
	s_setprio 0
	s_add_i32 s48, s48, 2
	s_add_u32 s39, s39, 0x100
	s_addc_u32 s47, s47, 0
	s_add_u32 s10, s10, 0x100
	s_addc_u32 s11, s11, 0
	s_cmp_gt_u32 s48, 29
	s_barrier
	s_cbranch_scc0 .LBB1_925
	s_waitcnt lgkmcnt(0)
	v_mov_b32_e32 v152, v147
	v_mov_b32_e32 v144, v146
	s_lshl_b32 s2, s2, 8
	s_or_b32 s2, s2, s29
	v_lshl_add_u32 v144, v144, 3, s2
	s_lshl_b32 s2, s8, 8
	s_add_i32 s2, s2, s28
	v_add_u32_e32 v152, s2, v152
	v_ashrrev_i32_e32 v153, 31, v152
	v_lshlrev_b64 v[152:153], 12, v[152:153]
	v_ashrrev_i32_e32 v145, 31, v144
	v_lshl_add_u64 v[152:153], s[42:43], 0, v[152:153]
	v_lshl_add_u64 v[144:145], v[144:145], 1, v[152:153]
	global_load_dwordx4 v[160:163], v[144:145], off
	global_load_dwordx4 v[164:167], v[144:145], off offset:256
	s_mov_b64 s[98:99], 0x10000
	v_lshl_add_u64 v[154:155], v[144:145], 0, s[98:99]
	global_load_dwordx4 v[168:171], v[154:155], off
	global_load_dwordx4 v[172:175], v[154:155], off offset:256
	s_mov_b64 s[98:99], 0x20000
	v_lshl_add_u64 v[154:155], v[144:145], 0, s[98:99]
	global_load_dwordx4 v[176:179], v[154:155], off
	global_load_dwordx4 v[180:183], v[154:155], off offset:256
	s_mov_b64 s[98:99], 0x30000
	v_lshl_add_u64 v[154:155], v[144:145], 0, s[98:99]
	global_load_dwordx4 v[184:187], v[154:155], off
	global_load_dwordx4 v[188:191], v[154:155], off offset:256
	s_mov_b64 s[98:99], 0x80000
	v_lshl_add_u64 v[154:155], v[144:145], 0, s[98:99]
	global_load_dwordx4 v[192:195], v[154:155], off
	global_load_dwordx4 v[198:201], v[154:155], off offset:256
	s_mov_b64 s[98:99], 0x90000
	v_lshl_add_u64 v[154:155], v[144:145], 0, s[98:99]
	global_load_dwordx4 v[202:205], v[154:155], off
	global_load_dwordx4 v[206:209], v[154:155], off offset:256
	s_mov_b64 s[98:99], 0xa0000
	v_lshl_add_u64 v[154:155], v[144:145], 0, s[98:99]
	global_load_dwordx4 v[210:213], v[154:155], off
	global_load_dwordx4 v[214:217], v[154:155], off offset:256
	s_mov_b64 s[98:99], 0xb0000
	v_lshl_add_u64 v[154:155], v[144:145], 0, s[98:99]
	global_load_dwordx4 v[248:251], v[154:155], off
	global_load_dwordx4 v[252:255], v[154:155], off offset:256
	s_waitcnt vmcnt(15)
	s_nop 1
	v_mov_b32_e32 v152, v160
	v_mov_b32_e32 v153, v161
	v_mov_b32_e32 v154, v162
	v_mov_b32_e32 v155, v163
	s_mov_b64 s[2:3], 0x10000
	s_mov_b32 s8, s52
	s_mov_b64 s[10:11], s[6:7]
	s_mov_b64 s[12:13], s[54:55]
	s_waitcnt lgkmcnt(0)
	v_lshlrev_b32_e32 v156, 16, v152
	v_and_b32_e32 v157, 0xffff0000, v152
	v_lshlrev_b32_e32 v152, 16, v153
	v_and_b32_e32 v153, 0xffff0000, v153
	v_lshlrev_b32_e32 v158, 16, v154
	v_and_b32_e32 v159, 0xffff0000, v154
	v_lshlrev_b32_e32 v154, 16, v155
	v_and_b32_e32 v155, 0xffff0000, v155
	v_pk_add_f32 v[126:127], v[126:127], v[152:153]
	v_pk_add_f32 v[124:125], v[124:125], v[156:157]
	v_pk_add_f32 v[152:153], v[122:123], v[154:155]
	v_pk_add_f32 v[122:123], v[120:121], v[158:159]
	v_cvt_pk_bf16_f32 v120, v124, v125
	v_cvt_pk_bf16_f32 v121, v126, v127
	v_cvt_pk_bf16_f32 v122, v122, v123
	v_cvt_pk_bf16_f32 v123, v152, v153
	global_store_dwordx4 v[144:145], v[120:123], off
	s_waitcnt vmcnt(15)
	s_nop 1
	v_mov_b32_e32 v120, v164
	v_mov_b32_e32 v121, v165
	v_mov_b32_e32 v122, v166
	v_mov_b32_e32 v123, v167
	s_waitcnt lgkmcnt(0)
	v_lshlrev_b32_e32 v124, 16, v120
	v_and_b32_e32 v125, 0xffff0000, v120
	v_lshlrev_b32_e32 v120, 16, v121
	v_and_b32_e32 v121, 0xffff0000, v121
	v_lshlrev_b32_e32 v126, 16, v122
	v_and_b32_e32 v127, 0xffff0000, v122
	v_lshlrev_b32_e32 v122, 16, v123
	v_and_b32_e32 v123, 0xffff0000, v123
	v_pk_add_f32 v[116:117], v[116:117], v[124:125]
	v_pk_add_f32 v[118:119], v[118:119], v[120:121]
	v_pk_add_f32 v[120:121], v[114:115], v[122:123]
	v_pk_add_f32 v[114:115], v[112:113], v[126:127]
	v_cvt_pk_bf16_f32 v112, v116, v117
	v_lshl_add_u64 v[116:117], v[144:145], 0, s[2:3]
	s_mov_b32 s2, 0x10000
	v_cvt_pk_bf16_f32 v113, v118, v119
	v_add_co_u32_e32 v118, vcc, s2, v144
	v_cvt_pk_bf16_f32 v114, v114, v115
	v_cvt_pk_bf16_f32 v115, v120, v121
	v_addc_co_u32_e32 v119, vcc, 0, v145, vcc
	global_store_dwordx4 v[144:145], v[112:115], off offset:256
	s_waitcnt vmcnt(15)
	s_nop 1
	v_mov_b32_e32 v112, v168
	v_mov_b32_e32 v113, v169
	v_mov_b32_e32 v114, v170
	v_mov_b32_e32 v115, v171
	s_mov_b64 s[2:3], 0x20000
	s_waitcnt lgkmcnt(0)
; DI unsigned pack2(float a, float b) { f32x2 v = {a, b}; hwbf16x2 r = __builtin_convertvector(v, hwbf16x2); return __builtin_bit_cast(unsigned, r); }
; DI float bflo(unsigned w) { return __uint_as_float(w << 16); }
; DI float bfhi(unsigned w) { return __uint_as_float(w & 0xffff0000u); }
;     DI void operator()(const f32x4 (&acc)[2][2][4][2], const Unit& u, int wr, int wc, int fr, int fq) const {
;     ...
;             for (int m = 0; m < 4; ++m) { const size_t ro = (size_t)(row0 + ai * HALF + m * 16) * D + col0;
; #pragma unroll
;                 for (int bj = 0; bj < 2; ++bj) {
;                     f32x4 x0, x1;
;                     if constexpr (IB) { const u32x4 w = *(const u32x4*)((const bf16_t*)Xin + ro + bj * HALF);
;                         x0 = (f32x4){bflo(w[0]), bfhi(w[0]), bflo(w[1]), bfhi(w[1])}; x1 = (f32x4){bflo(w[2]), bfhi(w[2]), bflo(w[3]), bfhi(w[3])}; }
;                     else { x0 = *(const f32x4*)((const float*)Xin + ro + bj * HALF); x1 = *(const f32x4*)((const float*)Xin + ro + bj * HALF + 4); }
;                     x0 += acc[ai][bj][m][0] * sc[bj][0]; x1 += acc[ai][bj][m][1] * sc[bj][1];
;                     if constexpr (OB) { u32x4 o; o[0] = pack2(x0[0], x0[1]); o[1] = pack2(x0[2], x0[3]); o[2] = pack2(x1[0], x1[1]); o[3] = pack2(x1[2], x1[3]);
;                         *(u32x4*)((bf16_t*)Xout + ro + bj * HALF) = o; }
;                     else { *(f32x4*)((float*)Xout + ro + bj * HALF) = x0; *(f32x4*)((float*)Xout + ro + bj * HALF + 4) = x1; } } }
	v_lshlrev_b32_e32 v120, 16, v112
	v_and_b32_e32 v121, 0xffff0000, v112
	v_lshlrev_b32_e32 v112, 16, v113
	v_and_b32_e32 v113, 0xffff0000, v113
	v_lshlrev_b32_e32 v122, 16, v114
	v_and_b32_e32 v123, 0xffff0000, v114
	v_lshlrev_b32_e32 v114, 16, v115
	v_and_b32_e32 v115, 0xffff0000, v115
	v_pk_add_f32 v[110:111], v[110:111], v[112:113]
	v_pk_add_f32 v[108:109], v[108:109], v[120:121]
	v_pk_add_f32 v[112:113], v[106:107], v[114:115]
	v_pk_add_f32 v[106:107], v[104:105], v[122:123]
	v_cvt_pk_bf16_f32 v104, v108, v109
	v_cvt_pk_bf16_f32 v105, v110, v111
	v_cvt_pk_bf16_f32 v106, v106, v107
	v_cvt_pk_bf16_f32 v107, v112, v113
	global_store_dwordx4 v[118:119], v[104:107], off
	s_waitcnt vmcnt(15)
	s_nop 1
	v_mov_b32_e32 v104, v172
	v_mov_b32_e32 v105, v173
	v_mov_b32_e32 v106, v174
	v_mov_b32_e32 v107, v175
	s_waitcnt lgkmcnt(0)
	v_lshlrev_b32_e32 v108, 16, v104
	v_and_b32_e32 v109, 0xffff0000, v104
	v_lshlrev_b32_e32 v104, 16, v105
	v_and_b32_e32 v105, 0xffff0000, v105
	v_lshlrev_b32_e32 v110, 16, v106
	v_and_b32_e32 v111, 0xffff0000, v106
	v_lshlrev_b32_e32 v106, 16, v107
	v_and_b32_e32 v107, 0xffff0000, v107
	v_pk_add_f32 v[100:101], v[100:101], v[108:109]
	v_pk_add_f32 v[102:103], v[102:103], v[104:105]
	v_pk_add_f32 v[104:105], v[98:99], v[106:107]
	v_pk_add_f32 v[98:99], v[96:97], v[110:111]
	v_cvt_pk_bf16_f32 v96, v100, v101
	v_lshl_add_u64 v[100:101], v[144:145], 0, s[2:3]
	s_mov_b32 s2, 0x20000
	v_cvt_pk_bf16_f32 v97, v102, v103
	v_add_co_u32_e32 v102, vcc, s2, v144
	v_cvt_pk_bf16_f32 v98, v98, v99
	v_cvt_pk_bf16_f32 v99, v104, v105
	v_addc_co_u32_e32 v103, vcc, 0, v145, vcc
	global_store_dwordx4 v[116:117], v[96:99], off offset:256
	s_waitcnt vmcnt(15)
	s_nop 1
	v_mov_b32_e32 v96, v176
	v_mov_b32_e32 v97, v177
	v_mov_b32_e32 v98, v178
	v_mov_b32_e32 v99, v179
	s_mov_b64 s[2:3], 0x30000
	s_waitcnt lgkmcnt(0)
	v_lshlrev_b32_e32 v104, 16, v96
	v_and_b32_e32 v105, 0xffff0000, v96
	v_lshlrev_b32_e32 v96, 16, v97
	v_and_b32_e32 v97, 0xffff0000, v97
	v_lshlrev_b32_e32 v106, 16, v98
	v_and_b32_e32 v107, 0xffff0000, v98
	v_lshlrev_b32_e32 v98, 16, v99
	v_and_b32_e32 v99, 0xffff0000, v99
	v_pk_add_f32 v[94:95], v[94:95], v[96:97]
	v_pk_add_f32 v[92:93], v[92:93], v[104:105]
	v_pk_add_f32 v[96:97], v[90:91], v[98:99]
	v_pk_add_f32 v[90:91], v[88:89], v[106:107]
	v_cvt_pk_bf16_f32 v88, v92, v93
	v_cvt_pk_bf16_f32 v89, v94, v95
	v_cvt_pk_bf16_f32 v90, v90, v91
	v_cvt_pk_bf16_f32 v91, v96, v97
	global_store_dwordx4 v[102:103], v[88:91], off
	s_waitcnt vmcnt(15)
	s_nop 1
	v_mov_b32_e32 v88, v180
	v_mov_b32_e32 v89, v181
	v_mov_b32_e32 v90, v182
	v_mov_b32_e32 v91, v183
	s_waitcnt lgkmcnt(0)
	v_lshlrev_b32_e32 v92, 16, v88
	v_and_b32_e32 v93, 0xffff0000, v88
	v_lshlrev_b32_e32 v88, 16, v89
	v_and_b32_e32 v89, 0xffff0000, v89
	v_lshlrev_b32_e32 v94, 16, v90
	v_and_b32_e32 v95, 0xffff0000, v90
	v_lshlrev_b32_e32 v90, 16, v91
	v_and_b32_e32 v91, 0xffff0000, v91
	v_pk_add_f32 v[86:87], v[86:87], v[88:89]
	v_pk_add_f32 v[84:85], v[84:85], v[92:93]
	v_pk_add_f32 v[88:89], v[82:83], v[90:91]
	v_pk_add_f32 v[82:83], v[80:81], v[94:95]
	v_cvt_pk_bf16_f32 v80, v84, v85
	v_cvt_pk_bf16_f32 v81, v86, v87
	v_cvt_pk_bf16_f32 v82, v82, v83
	v_cvt_pk_bf16_f32 v83, v88, v89
	global_store_dwordx4 v[100:101], v[80:83], off offset:256
	s_nop 1
	v_lshl_add_u64 v[80:81], v[144:145], 0, s[2:3]
	s_mov_b32 s2, 0x30000
	v_add_co_u32_e32 v86, vcc, s2, v144
	s_mov_b64 s[2:3], 0x80000
	s_nop 0
	v_addc_co_u32_e32 v87, vcc, 0, v145, vcc
	s_waitcnt vmcnt(15)
	s_nop 1
	v_mov_b32_e32 v82, v184
	v_mov_b32_e32 v83, v185
	v_mov_b32_e32 v84, v186
	v_mov_b32_e32 v85, v187
	s_waitcnt lgkmcnt(0)
	v_lshlrev_b32_e32 v88, 16, v82
	v_and_b32_e32 v89, 0xffff0000, v82
	v_lshlrev_b32_e32 v82, 16, v83
	v_and_b32_e32 v83, 0xffff0000, v83
	v_lshlrev_b32_e32 v90, 16, v84
	v_and_b32_e32 v91, 0xffff0000, v84
	v_lshlrev_b32_e32 v84, 16, v85
	v_and_b32_e32 v85, 0xffff0000, v85
	v_pk_add_f32 v[78:79], v[78:79], v[82:83]
	v_pk_add_f32 v[76:77], v[76:77], v[88:89]
	v_pk_add_f32 v[82:83], v[74:75], v[84:85]
	v_pk_add_f32 v[74:75], v[72:73], v[90:91]
	v_cvt_pk_bf16_f32 v72, v76, v77
	v_cvt_pk_bf16_f32 v73, v78, v79
	v_cvt_pk_bf16_f32 v74, v74, v75
	v_cvt_pk_bf16_f32 v75, v82, v83
	global_store_dwordx4 v[86:87], v[72:75], off
	s_waitcnt vmcnt(15)
	s_nop 1
	v_mov_b32_e32 v72, v188
	v_mov_b32_e32 v73, v189
	v_mov_b32_e32 v74, v190
	v_mov_b32_e32 v75, v191
	s_waitcnt lgkmcnt(0)
	v_lshlrev_b32_e32 v76, 16, v72
	v_and_b32_e32 v77, 0xffff0000, v72
	v_lshlrev_b32_e32 v72, 16, v73
	v_and_b32_e32 v73, 0xffff0000, v73
	v_lshlrev_b32_e32 v78, 16, v74
	v_and_b32_e32 v79, 0xffff0000, v74
	v_lshlrev_b32_e32 v74, 16, v75
	v_and_b32_e32 v75, 0xffff0000, v75
	v_pk_add_f32 v[70:71], v[70:71], v[72:73]
	v_pk_add_f32 v[68:69], v[68:69], v[76:77]
	v_pk_add_f32 v[72:73], v[66:67], v[74:75]
	v_pk_add_f32 v[66:67], v[64:65], v[78:79]
	v_cvt_pk_bf16_f32 v64, v68, v69
	v_cvt_pk_bf16_f32 v65, v70, v71
	v_cvt_pk_bf16_f32 v66, v66, v67
	v_cvt_pk_bf16_f32 v67, v72, v73
	global_store_dwordx4 v[80:81], v[64:67], off offset:256
	s_nop 1
	v_lshl_add_u64 v[64:65], v[144:145], 0, s[2:3]
	s_mov_b32 s2, 0x80000
	v_add_co_u32_e32 v70, vcc, s2, v144
	s_mov_b64 s[2:3], 0x90000
	s_nop 0
	v_addc_co_u32_e32 v71, vcc, 0, v145, vcc
	s_waitcnt vmcnt(15)
	s_nop 1
	v_mov_b32_e32 v66, v192
	v_mov_b32_e32 v67, v193
	v_mov_b32_e32 v68, v194
	v_mov_b32_e32 v69, v195
	s_waitcnt lgkmcnt(0)
; DI unsigned pack2(float a, float b) { f32x2 v = {a, b}; hwbf16x2 r = __builtin_convertvector(v, hwbf16x2); return __builtin_bit_cast(unsigned, r); }
; DI float bflo(unsigned w) { return __uint_as_float(w << 16); }
; DI float bfhi(unsigned w) { return __uint_as_float(w & 0xffff0000u); }
; #define PG8_WAIT_V(n) asm volatile("s_waitcnt vmcnt(" #n ")" ::: "memory")
; #define PG8_BAR __builtin_amdgcn_s_barrier()
;     DI void operator()(const f32x4 (&acc)[2][2][4][2], const Unit& u, int wr, int wc, int fr, int fq) const {
;     ...
;             for (int m = 0; m < 4; ++m) { const size_t ro = (size_t)(row0 + ai * HALF + m * 16) * D + col0;
; #pragma unroll
;                 for (int bj = 0; bj < 2; ++bj) {
;                     f32x4 x0, x1;
;                     if constexpr (IB) { const u32x4 w = *(const u32x4*)((const bf16_t*)Xin + ro + bj * HALF);
;                         x0 = (f32x4){bflo(w[0]), bfhi(w[0]), bflo(w[1]), bfhi(w[1])}; x1 = (f32x4){bflo(w[2]), bfhi(w[2]), bflo(w[3]), bfhi(w[3])}; }
;                     else { x0 = *(const f32x4*)((const float*)Xin + ro + bj * HALF); x1 = *(const f32x4*)((const float*)Xin + ro + bj * HALF + 4); }
;                     x0 += acc[ai][bj][m][0] * sc[bj][0]; x1 += acc[ai][bj][m][1] * sc[bj][1];
;                     if constexpr (OB) { u32x4 o; o[0] = pack2(x0[0], x0[1]); o[1] = pack2(x0[2], x0[3]); o[2] = pack2(x1[0], x1[1]); o[3] = pack2(x1[2], x1[3]);
;                         *(u32x4*)((bf16_t*)Xout + ro + bj * HALF) = o; }
;                     else { *(f32x4*)((float*)Xout + ro + bj * HALF) = x0; *(f32x4*)((float*)Xout + ro + bj * HALF + 4) = x1; } } }
; template <class Map, class Epi>
; DI void gemm_phase(LAS unsigned char* lds, const Map& MP, const Epi& E, const int nM, const int nN, const int K, const int lda, const int ldb) {
;     ...
;     PG8_WAIT_V(0);
;     if (wr == 0) PG8_BAR;
;     PG8_BAR;
	v_lshlrev_b32_e32 v72, 16, v66
	v_and_b32_e32 v73, 0xffff0000, v66
	v_lshlrev_b32_e32 v66, 16, v67
	v_and_b32_e32 v67, 0xffff0000, v67
	v_lshlrev_b32_e32 v74, 16, v68
	v_and_b32_e32 v75, 0xffff0000, v68
	v_lshlrev_b32_e32 v68, 16, v69
	v_and_b32_e32 v69, 0xffff0000, v69
	v_pk_add_f32 v[62:63], v[62:63], v[66:67]
	v_pk_add_f32 v[60:61], v[60:61], v[72:73]
	v_pk_add_f32 v[66:67], v[58:59], v[68:69]
	v_pk_add_f32 v[58:59], v[56:57], v[74:75]
	v_cvt_pk_bf16_f32 v56, v60, v61
	v_cvt_pk_bf16_f32 v57, v62, v63
	v_cvt_pk_bf16_f32 v58, v58, v59
	v_cvt_pk_bf16_f32 v59, v66, v67
	global_store_dwordx4 v[70:71], v[56:59], off
	s_waitcnt vmcnt(15)
	s_nop 1
	v_mov_b32_e32 v56, v198
	v_mov_b32_e32 v57, v199
	v_mov_b32_e32 v58, v200
	v_mov_b32_e32 v59, v201
	s_waitcnt lgkmcnt(0)
	v_lshlrev_b32_e32 v60, 16, v56
	v_and_b32_e32 v61, 0xffff0000, v56
	v_lshlrev_b32_e32 v56, 16, v57
	v_and_b32_e32 v57, 0xffff0000, v57
	v_lshlrev_b32_e32 v62, 16, v58
	v_and_b32_e32 v63, 0xffff0000, v58
	v_lshlrev_b32_e32 v58, 16, v59
	v_and_b32_e32 v59, 0xffff0000, v59
	v_pk_add_f32 v[54:55], v[54:55], v[56:57]
	v_pk_add_f32 v[52:53], v[52:53], v[60:61]
	v_pk_add_f32 v[56:57], v[50:51], v[58:59]
	v_pk_add_f32 v[50:51], v[48:49], v[62:63]
	v_cvt_pk_bf16_f32 v48, v52, v53
	v_cvt_pk_bf16_f32 v49, v54, v55
	v_cvt_pk_bf16_f32 v50, v50, v51
	v_cvt_pk_bf16_f32 v51, v56, v57
	global_store_dwordx4 v[64:65], v[48:51], off offset:256
	s_nop 1
	v_lshl_add_u64 v[48:49], v[144:145], 0, s[2:3]
	s_mov_b32 s2, 0x90000
	v_add_co_u32_e32 v54, vcc, s2, v144
	s_mov_b64 s[2:3], 0xa0000
	s_nop 0
	v_addc_co_u32_e32 v55, vcc, 0, v145, vcc
	s_waitcnt vmcnt(15)
	s_nop 1
	v_mov_b32_e32 v50, v202
	v_mov_b32_e32 v51, v203
	v_mov_b32_e32 v52, v204
	v_mov_b32_e32 v53, v205
	s_waitcnt lgkmcnt(0)
	v_lshlrev_b32_e32 v56, 16, v50
	v_and_b32_e32 v57, 0xffff0000, v50
	v_lshlrev_b32_e32 v50, 16, v51
	v_and_b32_e32 v51, 0xffff0000, v51
	v_lshlrev_b32_e32 v58, 16, v52
	v_and_b32_e32 v59, 0xffff0000, v52
	v_lshlrev_b32_e32 v52, 16, v53
	v_and_b32_e32 v53, 0xffff0000, v53
	v_pk_add_f32 v[46:47], v[46:47], v[50:51]
	v_pk_add_f32 v[44:45], v[44:45], v[56:57]
	v_pk_add_f32 v[50:51], v[42:43], v[52:53]
	v_pk_add_f32 v[42:43], v[40:41], v[58:59]
	v_cvt_pk_bf16_f32 v40, v44, v45
	v_cvt_pk_bf16_f32 v41, v46, v47
	v_cvt_pk_bf16_f32 v42, v42, v43
	v_cvt_pk_bf16_f32 v43, v50, v51
	global_store_dwordx4 v[54:55], v[40:43], off
	s_waitcnt vmcnt(15)
	s_nop 1
	v_mov_b32_e32 v40, v206
	v_mov_b32_e32 v41, v207
	v_mov_b32_e32 v42, v208
	v_mov_b32_e32 v43, v209
	s_waitcnt lgkmcnt(0)
	v_lshlrev_b32_e32 v44, 16, v40
	v_and_b32_e32 v45, 0xffff0000, v40
	v_lshlrev_b32_e32 v40, 16, v41
	v_and_b32_e32 v41, 0xffff0000, v41
	v_lshlrev_b32_e32 v46, 16, v42
	v_and_b32_e32 v47, 0xffff0000, v42
	v_lshlrev_b32_e32 v42, 16, v43
	v_and_b32_e32 v43, 0xffff0000, v43
	v_pk_add_f32 v[38:39], v[38:39], v[40:41]
	v_pk_add_f32 v[36:37], v[36:37], v[44:45]
	v_pk_add_f32 v[40:41], v[34:35], v[42:43]
	v_pk_add_f32 v[34:35], v[32:33], v[46:47]
	v_cvt_pk_bf16_f32 v32, v36, v37
	v_cvt_pk_bf16_f32 v33, v38, v39
	v_cvt_pk_bf16_f32 v34, v34, v35
	v_cvt_pk_bf16_f32 v35, v40, v41
	global_store_dwordx4 v[48:49], v[32:35], off offset:256
	s_nop 1
	v_lshl_add_u64 v[32:33], v[144:145], 0, s[2:3]
	s_mov_b32 s2, 0xa0000
	v_add_co_u32_e32 v38, vcc, s2, v144
	s_mov_b64 s[2:3], 0xb0000
	s_nop 0
	v_addc_co_u32_e32 v39, vcc, 0, v145, vcc
	s_waitcnt vmcnt(15)
	s_nop 1
	v_mov_b32_e32 v34, v210
	v_mov_b32_e32 v35, v211
	v_mov_b32_e32 v36, v212
	v_mov_b32_e32 v37, v213
	s_waitcnt lgkmcnt(0)
	v_lshlrev_b32_e32 v40, 16, v34
	v_and_b32_e32 v41, 0xffff0000, v34
	v_lshlrev_b32_e32 v34, 16, v35
	v_and_b32_e32 v35, 0xffff0000, v35
	v_lshlrev_b32_e32 v42, 16, v36
	v_and_b32_e32 v43, 0xffff0000, v36
	v_lshlrev_b32_e32 v36, 16, v37
	v_and_b32_e32 v37, 0xffff0000, v37
	v_pk_add_f32 v[30:31], v[30:31], v[34:35]
	v_pk_add_f32 v[28:29], v[28:29], v[40:41]
	v_pk_add_f32 v[34:35], v[26:27], v[36:37]
	v_pk_add_f32 v[26:27], v[24:25], v[42:43]
	v_cvt_pk_bf16_f32 v24, v28, v29
	v_cvt_pk_bf16_f32 v25, v30, v31
	v_cvt_pk_bf16_f32 v26, v26, v27
	v_cvt_pk_bf16_f32 v27, v34, v35
	global_store_dwordx4 v[38:39], v[24:27], off
	s_waitcnt vmcnt(15)
	s_nop 1
	v_mov_b32_e32 v24, v214
	v_mov_b32_e32 v25, v215
	v_mov_b32_e32 v26, v216
	v_mov_b32_e32 v27, v217
	s_waitcnt lgkmcnt(0)
	v_lshlrev_b32_e32 v28, 16, v24
	v_and_b32_e32 v29, 0xffff0000, v24
	v_lshlrev_b32_e32 v24, 16, v25
	v_and_b32_e32 v25, 0xffff0000, v25
	v_lshlrev_b32_e32 v30, 16, v26
	v_and_b32_e32 v31, 0xffff0000, v26
	v_lshlrev_b32_e32 v26, 16, v27
	v_and_b32_e32 v27, 0xffff0000, v27
	v_pk_add_f32 v[22:23], v[22:23], v[24:25]
	v_pk_add_f32 v[20:21], v[20:21], v[28:29]
	v_pk_add_f32 v[24:25], v[18:19], v[26:27]
	v_pk_add_f32 v[18:19], v[16:17], v[30:31]
	v_cvt_pk_bf16_f32 v16, v20, v21
	v_cvt_pk_bf16_f32 v17, v22, v23
	v_cvt_pk_bf16_f32 v18, v18, v19
	v_cvt_pk_bf16_f32 v19, v24, v25
	global_store_dwordx4 v[32:33], v[16:19], off offset:256
	s_nop 1
	v_lshl_add_u64 v[16:17], v[144:145], 0, s[2:3]
	s_mov_b32 s2, 0xb0000
	v_add_co_u32_e32 v22, vcc, s2, v144
	s_mov_b32 s2, s46
	s_nop 0
	v_addc_co_u32_e32 v23, vcc, 0, v145, vcc
	s_waitcnt vmcnt(15)
	s_nop 1
	v_mov_b32_e32 v18, v248
	v_mov_b32_e32 v19, v249
	v_mov_b32_e32 v20, v250
	v_mov_b32_e32 v21, v251
	s_and_b64 vcc, exec, s[40:41]
	s_waitcnt lgkmcnt(0)
	v_lshlrev_b32_e32 v24, 16, v18
	v_and_b32_e32 v25, 0xffff0000, v18
	v_lshlrev_b32_e32 v18, 16, v19
	v_and_b32_e32 v19, 0xffff0000, v19
	v_lshlrev_b32_e32 v26, 16, v20
	v_and_b32_e32 v27, 0xffff0000, v20
	v_lshlrev_b32_e32 v20, 16, v21
	v_and_b32_e32 v21, 0xffff0000, v21
	v_pk_add_f32 v[14:15], v[14:15], v[18:19]
	v_pk_add_f32 v[12:13], v[12:13], v[24:25]
	v_pk_add_f32 v[18:19], v[10:11], v[20:21]
	v_pk_add_f32 v[10:11], v[8:9], v[26:27]
	v_cvt_pk_bf16_f32 v8, v12, v13
	v_cvt_pk_bf16_f32 v9, v14, v15
	v_cvt_pk_bf16_f32 v10, v10, v11
	v_cvt_pk_bf16_f32 v11, v18, v19
	global_store_dwordx4 v[22:23], v[8:11], off
	s_waitcnt vmcnt(15)
	s_nop 1
	v_mov_b32_e32 v8, v252
	v_mov_b32_e32 v9, v253
	v_mov_b32_e32 v10, v254
	v_mov_b32_e32 v11, v255
	s_waitcnt lgkmcnt(0)
	v_lshlrev_b32_e32 v12, 16, v8
	v_and_b32_e32 v13, 0xffff0000, v8
	v_lshlrev_b32_e32 v8, 16, v9
	v_and_b32_e32 v9, 0xffff0000, v9
	v_lshlrev_b32_e32 v14, 16, v10
	v_and_b32_e32 v15, 0xffff0000, v10
	v_lshlrev_b32_e32 v10, 16, v11
	v_and_b32_e32 v11, 0xffff0000, v11
	v_pk_add_f32 v[6:7], v[6:7], v[8:9]
	v_pk_add_f32 v[4:5], v[4:5], v[12:13]
	v_pk_add_f32 v[8:9], v[2:3], v[10:11]
	v_pk_add_f32 v[2:3], v[0:1], v[14:15]
	v_cvt_pk_bf16_f32 v0, v4, v5
	v_cvt_pk_bf16_f32 v1, v6, v7
	v_cvt_pk_bf16_f32 v2, v2, v3
	v_cvt_pk_bf16_f32 v3, v8, v9
	global_store_dwordx4 v[16:17], v[0:3], off offset:256
	s_cbranch_vccz .LBB1_922
	s_waitcnt vmcnt(0)
	s_cmpk_gt_u32 s17, 0xff
	s_cbranch_scc1 .LBB1_929
	s_barrier

;     DI const char* a(const Unit& u) const { return (const char*)(A + (size_t)u.pm * BM * lda); }
;     DI const char* a(const Unit& u) const { return (const char*)(A + (size_t)u.pm * BM * 2048 + (u.pn >> 1) * 512); }
;     DI const char* a(const Unit& u) const { return (const char*)((u.pn < 12 ? A1 : A2) + (size_t)u.pm * BM * 512); }
; #define PG8_STAGE(bufoff, gbase, voff) do { _Pragma("unroll") for (int _i = 0; _i < 2; ++_i) \
;         __builtin_amdgcn_global_load_lds((const unsigned*)((const char*)(gbase) + (voff)[_i]), (LAS unsigned*)(lds + (bufoff) + ldsw + _i * 8192), 16, 0, 0); } while (0)
; #define PG8_LDA(dst, b, h) do { _Pragma("unroll") for (int m = 0; m < 4; ++m) _Pragma("unroll") for (int k = 0; k < 2; ++k) dst[m][k] = *(const LAS bf16x8*)(lds + PG8_SA(b, h) + aoff + m * 2048 + k * 1024); } while (0)
; #define PG8_LDB(dst, b, h) do { _Pragma("unroll") for (int n = 0; n < 2; ++n) _Pragma("unroll") for (int k = 0; k < 2; ++k) dst[n][k] = *(const LAS bf16x8*)(lds + PG8_SB(b, h) + boff + n * 2048 + k * 1024); } while (0)
; #define PG8_WAIT_L(n) asm volatile("s_waitcnt lgkmcnt(" #n ")" ::: "memory")
; template <class Map, class Epi>
; DI void gemm_phase(LAS unsigned char* lds, const Map& MP, const Epi& E, const int nM, const int nN, const int K, const int lda, const int ldb) {
;     ...
;         const bool has_next = sched_next(ui + 1, nM, nN, G, cblk, nxt);
;         const char* nA = has_next ? MP.a(nxt) : cA; const char* nB = has_next ? MP.b(nxt) : cB;
;         for (int t = 0; t < nt; t += 2) {
;             const bool last = (t == nt - 2);
;             const char* a1 = cA + (size_t)(t + 1) * kstep;
;             const char* a2 = last ? nA : cA + (size_t)(t + 2) * kstep; const char* b2 = last ? nB : cB + (size_t)(t + 2) * kstep;
;             const char* a3 = a2 + kstep; const char* b3 = b2 + kstep;
;             PG8_LDB(B0, 0, 0); PG8_SCHED; PG8_LDA(At, 0, 0); PG8_STAGE(PG8_SA(1, 1), a1 + hstepA, voffA);
;             PG8_WAIT_L(8); PG8_BAR; PG8_WAIT_L(0); PG8_MMA(0, 0, At, B0); PG8_BAR; PG8_SCHED;
;     ...
; #pragma unroll
;         for (int a = 0; a < 2; ++a)
; #pragma unroll
;             for (int b = 0; b < 2; ++b)
; #pragma unroll
;                 for (int m = 0; m < 4; ++m)
; #pragma unroll
;                     for (int n = 0; n < 2; ++n) acc[a][b][m][n] = (f32x4){0.f, 0.f, 0.f, 0.f};
;         cur = nxt; cA = nA; cB = nB; ++ui;
.LBB1_1068:
	s_ashr_i32 s23, s22, 31
	v_cmp_lt_i64_e32 vcc, s[26:27], v[180:181]
	s_lshl_b64 s[26:27], s[22:23], 20
	s_add_u32 s28, s34, s26
	s_addc_u32 s29, s35, s27
	s_and_b64 s[26:27], vcc, exec
	s_cselect_b32 s23, s29, s25
	s_cselect_b32 s58, s28, s24
	s_ashr_i32 s21, s20, 31
	s_lshl_b64 s[26:27], s[20:21], 20
	s_add_u32 s26, s36, s26
	s_addc_u32 s27, s37, s27
	s_and_b64 s[42:43], vcc, exec
	s_cselect_b32 s21, s27, s47
	s_cselect_b32 s59, s26, s46
	s_add_u32 vcc_lo, s46, 0x100
	s_addc_u32 vcc_hi, s47, 0
	s_add_u32 s42, s24, 0x80080
	v_mov_b32_e32 v0, 0
	s_addc_u32 s43, s25, 0
	s_mov_b32 s3, -2
	v_mov_b32_e32 v1, v0
	v_mov_b32_e32 v2, v0
	v_mov_b32_e32 v3, v0
	v_mov_b32_e32 v4, v0
	v_mov_b32_e32 v5, v0
	v_mov_b32_e32 v6, v0
	v_mov_b32_e32 v7, v0
	v_mov_b32_e32 v20, v0
	v_mov_b32_e32 v21, v0
	v_mov_b32_e32 v22, v0
	v_mov_b32_e32 v23, v0
	v_mov_b32_e32 v28, v0
	v_mov_b32_e32 v29, v0
	v_mov_b32_e32 v30, v0
	v_mov_b32_e32 v31, v0
	v_mov_b32_e32 v36, v0
	v_mov_b32_e32 v37, v0
	v_mov_b32_e32 v38, v0
	v_mov_b32_e32 v39, v0
	v_mov_b32_e32 v44, v0
	v_mov_b32_e32 v45, v0
	v_mov_b32_e32 v46, v0
	v_mov_b32_e32 v47, v0
	v_mov_b32_e32 v52, v0
	v_mov_b32_e32 v53, v0
	v_mov_b32_e32 v54, v0
	v_mov_b32_e32 v55, v0
	v_mov_b32_e32 v56, v0
	v_mov_b32_e32 v57, v0
	v_mov_b32_e32 v58, v0
	v_mov_b32_e32 v59, v0
	v_mov_b32_e32 v8, v0
	v_mov_b32_e32 v9, v0
	v_mov_b32_e32 v10, v0
	v_mov_b32_e32 v11, v0
	v_mov_b32_e32 v12, v0
	v_mov_b32_e32 v13, v0
	v_mov_b32_e32 v14, v0
	v_mov_b32_e32 v15, v0
	v_mov_b32_e32 v16, v0
	v_mov_b32_e32 v17, v0
	v_mov_b32_e32 v18, v0
	v_mov_b32_e32 v19, v0
	v_mov_b32_e32 v24, v0
	v_mov_b32_e32 v25, v0
	v_mov_b32_e32 v26, v0
	v_mov_b32_e32 v27, v0
	v_mov_b32_e32 v32, v0
	v_mov_b32_e32 v33, v0
	v_mov_b32_e32 v34, v0
	v_mov_b32_e32 v35, v0
	v_mov_b32_e32 v40, v0
	v_mov_b32_e32 v41, v0
	v_mov_b32_e32 v42, v0
	v_mov_b32_e32 v43, v0
	v_mov_b32_e32 v48, v0
	v_mov_b32_e32 v49, v0
	v_mov_b32_e32 v50, v0
	v_mov_b32_e32 v51, v0
	v_mov_b32_e32 v60, v0
	v_mov_b32_e32 v61, v0
	v_mov_b32_e32 v62, v0
	v_mov_b32_e32 v63, v0
	v_mov_b32_e32 v64, v0
	v_mov_b32_e32 v65, v0
	v_mov_b32_e32 v66, v0
	v_mov_b32_e32 v67, v0
	v_mov_b32_e32 v68, v0
	v_mov_b32_e32 v69, v0
	v_mov_b32_e32 v70, v0
	v_mov_b32_e32 v71, v0
	v_mov_b32_e32 v116, v0
	v_mov_b32_e32 v117, v0
	v_mov_b32_e32 v118, v0
	v_mov_b32_e32 v119, v0
	v_mov_b32_e32 v124, v0
	v_mov_b32_e32 v125, v0
	v_mov_b32_e32 v126, v0
	v_mov_b32_e32 v127, v0
	v_mov_b32_e32 v132, v0
	v_mov_b32_e32 v133, v0
	v_mov_b32_e32 v134, v0
	v_mov_b32_e32 v135, v0
	v_mov_b32_e32 v140, v0
	v_mov_b32_e32 v141, v0
	v_mov_b32_e32 v142, v0
	v_mov_b32_e32 v143, v0
	v_mov_b32_e32 v152, v0
	v_mov_b32_e32 v153, v0
	v_mov_b32_e32 v154, v0
	v_mov_b32_e32 v155, v0
	v_mov_b32_e32 v156, v0
	v_mov_b32_e32 v157, v0
	v_mov_b32_e32 v158, v0
	v_mov_b32_e32 v159, v0
	v_mov_b32_e32 v72, v0
	v_mov_b32_e32 v73, v0
	v_mov_b32_e32 v74, v0
	v_mov_b32_e32 v75, v0
	v_mov_b32_e32 v76, v0
	v_mov_b32_e32 v77, v0
	v_mov_b32_e32 v78, v0
	v_mov_b32_e32 v79, v0
	v_mov_b32_e32 v104, v0
	v_mov_b32_e32 v105, v0
	v_mov_b32_e32 v106, v0
	v_mov_b32_e32 v107, v0
	v_mov_b32_e32 v120, v0
	v_mov_b32_e32 v121, v0
	v_mov_b32_e32 v122, v0
	v_mov_b32_e32 v123, v0
	v_mov_b32_e32 v128, v0
	v_mov_b32_e32 v129, v0
	v_mov_b32_e32 v130, v0
	v_mov_b32_e32 v131, v0
	v_mov_b32_e32 v136, v0
	v_mov_b32_e32 v137, v0
	v_mov_b32_e32 v138, v0
	v_mov_b32_e32 v139, v0
	v_mov_b32_e32 v144, v0
	v_mov_b32_e32 v145, v0
	v_mov_b32_e32 v146, v0
	v_mov_b32_e32 v147, v0
	v_mov_b32_e32 v148, v0
	v_mov_b32_e32 v149, v0
	v_mov_b32_e32 v150, v0
	v_mov_b32_e32 v151, v0
	ds_read_b128 v[80:83], v189
	ds_read_b128 v[84:87], v189 offset:1024
	ds_read_b128 v[88:91], v189 offset:2048
	ds_read_b128 v[92:95], v189 offset:3072
.LBB1_1069:
	s_add_u32 s24, s42, 0xfff80080
	s_addc_u32 s25, s43, -1
	s_cmp_eq_u32 s3, 28
	s_cselect_b32 s47, s23, s25
	s_cselect_b32 s46, s58, s24
	s_cselect_b32 s25, s21, vcc_hi
	s_cselect_b32 s24, s59, vcc_lo
	s_add_i32 m0, s38, 0xc000
	ds_read_b128 v[96:99], v190
	ds_read_b128 v[100:103], v190 offset:1024
	ds_read_b128 v[108:111], v190 offset:2048
	ds_read_b128 v[112:115], v190 offset:3072
	ds_read_b128 v[160:163], v190 offset:4096
	ds_read_b128 v[164:167], v190 offset:5120
	ds_read_b128 v[198:201], v190 offset:6144
	ds_read_b128 v[202:205], v190 offset:7168
	global_load_lds_dwordx4 v178, s[42:43]
	s_add_i32 m0, s38, 0xe000
	s_nop 0
	global_load_lds_dwordx4 v176, s[42:43]
	s_waitcnt lgkmcnt(8)
	s_barrier
	s_setprio 1
	s_waitcnt lgkmcnt(7)
	v_mfma_f32_16x16x32_bf16 v[148:151], v[80:83], v[96:99], v[148:151]
	v_mfma_f32_16x16x32_bf16 v[144:147], v[88:91], v[96:99], v[144:147]
	s_waitcnt lgkmcnt(5)
	v_mfma_f32_16x16x32_bf16 v[136:139], v[80:83], v[108:111], v[136:139]
	v_mfma_f32_16x16x32_bf16 v[128:131], v[88:91], v[108:111], v[128:131]
	s_waitcnt lgkmcnt(3)
	v_mfma_f32_16x16x32_bf16 v[120:123], v[80:83], v[160:163], v[120:123]
	v_mfma_f32_16x16x32_bf16 v[104:107], v[88:91], v[160:163], v[104:107]
	s_waitcnt lgkmcnt(1)
	v_mfma_f32_16x16x32_bf16 v[76:79], v[80:83], v[198:201], v[76:79]
	v_mfma_f32_16x16x32_bf16 v[72:75], v[88:91], v[198:201], v[72:75]
	v_mfma_f32_16x16x32_bf16 v[148:151], v[84:87], v[100:103], v[148:151]
	v_mfma_f32_16x16x32_bf16 v[144:147], v[92:95], v[100:103], v[144:147]
	v_mfma_f32_16x16x32_bf16 v[136:139], v[84:87], v[112:115], v[136:139]
	v_mfma_f32_16x16x32_bf16 v[128:131], v[92:95], v[112:115], v[128:131]
	v_mfma_f32_16x16x32_bf16 v[120:123], v[84:87], v[164:167], v[120:123]
	v_mfma_f32_16x16x32_bf16 v[104:107], v[92:95], v[164:167], v[104:107]
	s_waitcnt lgkmcnt(0)
	v_mfma_f32_16x16x32_bf16 v[76:79], v[84:87], v[202:205], v[76:79]
	v_mfma_f32_16x16x32_bf16 v[72:75], v[92:95], v[202:205], v[72:75]
	s_setprio 0
	s_barrier
; #define PG8_STAGE(bufoff, gbase, voff) do { _Pragma("unroll") for (int _i = 0; _i < 2; ++_i) \
;         __builtin_amdgcn_global_load_lds((const unsigned*)((const char*)(gbase) + (voff)[_i]), (LAS unsigned*)(lds + (bufoff) + ldsw + _i * 8192), 16, 0, 0); } while (0)
; #define PG8_LDA(dst, b, h) do { _Pragma("unroll") for (int m = 0; m < 4; ++m) _Pragma("unroll") for (int k = 0; k < 2; ++k) dst[m][k] = *(const LAS bf16x8*)(lds + PG8_SA(b, h) + aoff + m * 2048 + k * 1024); } while (0)
; #define PG8_LDB(dst, b, h) do { _Pragma("unroll") for (int n = 0; n < 2; ++n) _Pragma("unroll") for (int k = 0; k < 2; ++k) dst[n][k] = *(const LAS bf16x8*)(lds + PG8_SB(b, h) + boff + n * 2048 + k * 1024); } while (0)
; #define PG8_MMA(ai, bj, At, Bt) do { __builtin_amdgcn_s_setprio(1); _Pragma("unroll") for (int m = 0; m < 4; ++m) _Pragma("unroll") for (int n = 0; n < 2; ++n) _Pragma("unroll") for (int k = 0; k < 2; ++k) \
;         acc[ai][bj][m][n] = __builtin_amdgcn_mfma_f32_16x16x32_bf16(Bt[n][k], At[m][k], acc[ai][bj][m][n], 0, 0, 0); __builtin_amdgcn_s_setprio(0); } while (0)
; #define PG8_WAIT_V(n) asm volatile("s_waitcnt vmcnt(" #n ")" ::: "memory")
; #define PG8_WAIT_L(n) asm volatile("s_waitcnt lgkmcnt(" #n ")" ::: "memory")
; #define PG8_BAR __builtin_amdgcn_s_barrier()
; #define PG8_SCHED __builtin_amdgcn_sched_barrier(0)
; template <class Map, class Epi>
; DI void gemm_phase(LAS unsigned char* lds, const Map& MP, const Epi& E, const int nM, const int nN, const int K, const int lda, const int ldb) {
;     ...
;             PG8_LDB(B1, 0, 1); PG8_STAGE(PG8_SB(0, 0), b2, voffB);
;             PG8_BAR; PG8_WAIT_L(0); PG8_MMA(0, 1, At, B1); PG8_BAR;
;             PG8_LDA(At, 0, 1); PG8_STAGE(PG8_SA(0, 0), a2, voffA);
;             PG8_BAR; PG8_WAIT_L(0); PG8_MMA(1, 0, At, B0); PG8_BAR; PG8_SCHED;
;             PG8_STAGE(PG8_SB(0, 1), b2 + hstepB, voffB);
;             PG8_WAIT_V(6); PG8_BAR; PG8_MMA(1, 1, At, B1); PG8_BAR;
;             PG8_LDB(B0, 1, 0); PG8_SCHED; PG8_LDA(At, 1, 0); PG8_STAGE(PG8_SA(0, 1), a2 + hstepA, voffA);
	s_add_i32 s68, s31, s66
	v_lshl_add_u64 v[184:185], s[24:25], 0, v[172:173]
	s_mov_b32 m0, s68
	ds_read_b128 v[206:209], v191
	ds_read_b128 v[210:213], v191 offset:1024
	ds_read_b128 v[214:217], v191 offset:2048
	ds_read_b128 v[218:221], v191 offset:3072
	global_load_lds_dwordx4 v[184:185], off
	v_lshl_add_u64 v[194:195], s[24:25], 0, v[168:169]
	s_add_i32 m0, s68, 0x2000
	s_nop 0
	global_load_lds_dwordx4 v[194:195], off
	s_barrier
	s_setprio 1
	s_waitcnt lgkmcnt(3)
	v_mfma_f32_16x16x32_bf16 v[156:159], v[206:209], v[96:99], v[156:159]
	s_waitcnt lgkmcnt(1)
	v_mfma_f32_16x16x32_bf16 v[96:99], v[214:217], v[96:99], v[152:155]
	v_mfma_f32_16x16x32_bf16 v[156:159], v[210:213], v[100:103], v[156:159]
	s_waitcnt lgkmcnt(0)
	v_mfma_f32_16x16x32_bf16 v[96:99], v[218:221], v[100:103], v[96:99]
	v_mfma_f32_16x16x32_bf16 v[100:103], v[206:209], v[108:111], v[140:143]
	v_mfma_f32_16x16x32_bf16 v[108:111], v[214:217], v[108:111], v[132:135]
	v_mfma_f32_16x16x32_bf16 v[116:119], v[214:217], v[160:163], v[116:119]
	v_mfma_f32_16x16x32_bf16 v[68:71], v[206:209], v[198:201], v[68:71]
	v_mfma_f32_16x16x32_bf16 v[64:67], v[214:217], v[198:201], v[64:67]
	v_mfma_f32_16x16x32_bf16 v[100:103], v[210:213], v[112:115], v[100:103]
	v_mfma_f32_16x16x32_bf16 v[108:111], v[218:221], v[112:115], v[108:111]
	v_mfma_f32_16x16x32_bf16 v[112:115], v[206:209], v[160:163], v[124:127]
	v_mfma_f32_16x16x32_bf16 v[116:119], v[218:221], v[164:167], v[116:119]
	v_mfma_f32_16x16x32_bf16 v[68:71], v[210:213], v[202:205], v[68:71]
	v_mfma_f32_16x16x32_bf16 v[64:67], v[218:221], v[202:205], v[64:67]
	v_mfma_f32_16x16x32_bf16 v[112:115], v[210:213], v[164:167], v[112:115]
	s_setprio 0
	s_mov_b32 m0, s38
	v_lshl_add_u64 v[226:227], s[46:47], 0, v[174:175]
	s_barrier
	ds_read_b128 v[124:127], v190 offset:16384
	ds_read_b128 v[132:135], v190 offset:17408
	ds_read_b128 v[140:143], v190 offset:18432
	ds_read_b128 v[152:155], v190 offset:19456
	ds_read_b128 v[160:163], v190 offset:20480
	ds_read_b128 v[164:167], v190 offset:21504
	ds_read_b128 v[198:201], v190 offset:22528
	ds_read_b128 v[202:205], v190 offset:23552
	global_load_lds_dwordx4 v[226:227], off
	v_lshl_add_u64 v[234:235], s[46:47], 0, v[170:171]
	s_mov_b32 m0, s39
	s_nop 0
	global_load_lds_dwordx4 v[234:235], off
	s_waitcnt vmcnt(10)
	s_barrier
	s_setprio 1
	s_waitcnt lgkmcnt(7)
	v_mfma_f32_16x16x32_bf16 v[60:63], v[80:83], v[124:127], v[60:63]
	v_mfma_f32_16x16x32_bf16 v[48:51], v[88:91], v[124:127], v[48:51]
	s_waitcnt lgkmcnt(5)
	v_mfma_f32_16x16x32_bf16 v[40:43], v[80:83], v[140:143], v[40:43]
	v_mfma_f32_16x16x32_bf16 v[32:35], v[88:91], v[140:143], v[32:35]
	s_waitcnt lgkmcnt(3)
	v_mfma_f32_16x16x32_bf16 v[24:27], v[80:83], v[160:163], v[24:27]
	v_mfma_f32_16x16x32_bf16 v[16:19], v[88:91], v[160:163], v[16:19]
	s_waitcnt lgkmcnt(1)
	v_mfma_f32_16x16x32_bf16 v[12:15], v[80:83], v[198:201], v[12:15]
	v_mfma_f32_16x16x32_bf16 v[8:11], v[88:91], v[198:201], v[8:11]
	v_mfma_f32_16x16x32_bf16 v[60:63], v[84:87], v[132:135], v[60:63]
	v_mfma_f32_16x16x32_bf16 v[48:51], v[92:95], v[132:135], v[48:51]
	v_mfma_f32_16x16x32_bf16 v[40:43], v[84:87], v[152:155], v[40:43]
	v_mfma_f32_16x16x32_bf16 v[32:35], v[92:95], v[152:155], v[32:35]
	v_mfma_f32_16x16x32_bf16 v[24:27], v[84:87], v[164:167], v[24:27]
	v_mfma_f32_16x16x32_bf16 v[16:19], v[92:95], v[164:167], v[16:19]
	s_waitcnt lgkmcnt(0)
	v_mfma_f32_16x16x32_bf16 v[12:15], v[84:87], v[202:205], v[12:15]
	v_mfma_f32_16x16x32_bf16 v[8:11], v[92:95], v[202:205], v[8:11]
	s_setprio 0
	s_barrier
	s_add_u32 s68, s24, 0x80000
	s_addc_u32 s69, s25, 0
	s_add_i32 s70, s2, s66
	s_mov_b32 m0, s70
	s_nop 0
	global_load_lds_dwordx4 v172, s[68:69]
	s_add_i32 m0, s70, 0x2000
	s_nop 0
	global_load_lds_dwordx4 v168, s[68:69]
	s_waitcnt vmcnt(6)
	s_barrier
	s_setprio 1
	v_mfma_f32_16x16x32_bf16 v[56:59], v[206:209], v[124:127], v[56:59]
	v_mfma_f32_16x16x32_bf16 v[52:55], v[214:217], v[124:127], v[52:55]
	s_add_i32 s68, 0, 0x18000
	v_add_u32_e32 v92, s68, v188
	ds_read_b128 v[80:83], v92
	v_mfma_f32_16x16x32_bf16 v[44:47], v[206:209], v[140:143], v[44:47]
	v_mfma_f32_16x16x32_bf16 v[36:39], v[214:217], v[140:143], v[36:39]
	ds_read_b128 v[84:87], v92 offset:1024
	v_mfma_f32_16x16x32_bf16 v[28:31], v[206:209], v[160:163], v[28:31]
	v_mfma_f32_16x16x32_bf16 v[20:23], v[214:217], v[160:163], v[20:23]
	ds_read_b128 v[88:91], v92 offset:2048
	v_mfma_f32_16x16x32_bf16 v[4:7], v[206:209], v[198:201], v[4:7]
	v_mfma_f32_16x16x32_bf16 v[0:3], v[214:217], v[198:201], v[0:3]
	ds_read_b128 v[92:95], v92 offset:3072
	v_mfma_f32_16x16x32_bf16 v[56:59], v[210:213], v[132:135], v[56:59]
	v_mfma_f32_16x16x32_bf16 v[52:55], v[218:221], v[132:135], v[52:55]
	v_mfma_f32_16x16x32_bf16 v[44:47], v[210:213], v[152:155], v[44:47]
	v_mfma_f32_16x16x32_bf16 v[36:39], v[218:221], v[152:155], v[36:39]
	v_mfma_f32_16x16x32_bf16 v[28:31], v[210:213], v[164:167], v[28:31]
	v_mfma_f32_16x16x32_bf16 v[20:23], v[218:221], v[164:167], v[20:23]
	v_mfma_f32_16x16x32_bf16 v[4:7], v[210:213], v[202:205], v[4:7]
	v_mfma_f32_16x16x32_bf16 v[0:3], v[218:221], v[202:205], v[0:3]
	s_setprio 0
	s_barrier
	s_add_u32 s46, s46, 0x80000
	s_addc_u32 s47, s47, 0
	s_mov_b32 m0, s56
	ds_read_b128 v[124:127], v190 offset:32768
	ds_read_b128 v[132:135], v190 offset:33792
	ds_read_b128 v[160:163], v190 offset:34816
	ds_read_b128 v[164:167], v190 offset:35840
	ds_read_b128 v[198:201], v190 offset:36864
	ds_read_b128 v[202:205], v190 offset:37888
	ds_read_b128 v[206:209], v190 offset:38912
	ds_read_b128 v[210:213], v190 offset:39936
	global_load_lds_dwordx4 v174, s[46:47]
	s_mov_b32 m0, s57
	s_nop 0
	global_load_lds_dwordx4 v170, s[46:47]
	s_waitcnt lgkmcnt(8)
	s_barrier
; #define PG8_STAGE(bufoff, gbase, voff) do { _Pragma("unroll") for (int _i = 0; _i < 2; ++_i) \
;         __builtin_amdgcn_global_load_lds((const unsigned*)((const char*)(gbase) + (voff)[_i]), (LAS unsigned*)(lds + (bufoff) + ldsw + _i * 8192), 16, 0, 0); } while (0)
; #define PG8_LDA(dst, b, h) do { _Pragma("unroll") for (int m = 0; m < 4; ++m) _Pragma("unroll") for (int k = 0; k < 2; ++k) dst[m][k] = *(const LAS bf16x8*)(lds + PG8_SA(b, h) + aoff + m * 2048 + k * 1024); } while (0)
; #define PG8_LDB(dst, b, h) do { _Pragma("unroll") for (int n = 0; n < 2; ++n) _Pragma("unroll") for (int k = 0; k < 2; ++k) dst[n][k] = *(const LAS bf16x8*)(lds + PG8_SB(b, h) + boff + n * 2048 + k * 1024); } while (0)
; #define PG8_MMA(ai, bj, At, Bt) do { __builtin_amdgcn_s_setprio(1); _Pragma("unroll") for (int m = 0; m < 4; ++m) _Pragma("unroll") for (int n = 0; n < 2; ++n) _Pragma("unroll") for (int k = 0; k < 2; ++k) \
;         acc[ai][bj][m][n] = __builtin_amdgcn_mfma_f32_16x16x32_bf16(Bt[n][k], At[m][k], acc[ai][bj][m][n], 0, 0, 0); __builtin_amdgcn_s_setprio(0); } while (0)
; #define PG8_WAIT_V(n) asm volatile("s_waitcnt vmcnt(" #n ")" ::: "memory")
; #define PG8_WAIT_L(n) asm volatile("s_waitcnt lgkmcnt(" #n ")" ::: "memory")
; #define PG8_BAR __builtin_amdgcn_s_barrier()
; #define PG8_SCHED __builtin_amdgcn_sched_barrier(0)
; template <class Map, class Epi>
; DI void gemm_phase(LAS unsigned char* lds, const Map& MP, const Epi& E, const int nM, const int nN, const int K, const int lda, const int ldb) {
;     ...
;             PG8_WAIT_L(8); PG8_BAR; PG8_WAIT_L(0); PG8_MMA(0, 0, At, B0); PG8_BAR; PG8_SCHED;
;             PG8_LDB(B1, 1, 1); PG8_STAGE(PG8_SB(1, 0), b3, voffB);
;             PG8_BAR; PG8_WAIT_L(0); PG8_MMA(0, 1, At, B1); PG8_BAR;
;             PG8_LDA(At, 1, 1); PG8_STAGE(PG8_SA(1, 0), a3, voffA);
;             PG8_BAR; PG8_WAIT_L(0); PG8_MMA(1, 0, At, B0); PG8_BAR; PG8_SCHED;
;             PG8_STAGE(PG8_SB(1, 1), b3 + hstepB, voffB);
;             PG8_WAIT_V(6); PG8_BAR; PG8_MMA(1, 1, At, B1); PG8_BAR;
	s_setprio 1
	s_waitcnt lgkmcnt(7)
	v_mfma_f32_16x16x32_bf16 v[140:143], v[80:83], v[124:127], v[148:151]
	s_waitcnt lgkmcnt(6)
	v_mfma_f32_16x16x32_bf16 v[148:151], v[84:87], v[132:135], v[140:143]
	v_mfma_f32_16x16x32_bf16 v[140:143], v[88:91], v[124:127], v[144:147]
	s_waitcnt lgkmcnt(5)
	v_mfma_f32_16x16x32_bf16 v[136:139], v[80:83], v[160:163], v[136:139]
	v_mfma_f32_16x16x32_bf16 v[128:131], v[88:91], v[160:163], v[128:131]
	s_waitcnt lgkmcnt(3)
	v_mfma_f32_16x16x32_bf16 v[120:123], v[80:83], v[198:201], v[120:123]
	v_mfma_f32_16x16x32_bf16 v[104:107], v[88:91], v[198:201], v[104:107]
	s_waitcnt lgkmcnt(1)
	v_mfma_f32_16x16x32_bf16 v[76:79], v[80:83], v[206:209], v[76:79]
	v_mfma_f32_16x16x32_bf16 v[72:75], v[88:91], v[206:209], v[72:75]
	v_mfma_f32_16x16x32_bf16 v[144:147], v[92:95], v[132:135], v[140:143]
	v_mfma_f32_16x16x32_bf16 v[136:139], v[84:87], v[164:167], v[136:139]
	v_mfma_f32_16x16x32_bf16 v[128:131], v[92:95], v[164:167], v[128:131]
	v_mfma_f32_16x16x32_bf16 v[120:123], v[84:87], v[202:205], v[120:123]
	v_mfma_f32_16x16x32_bf16 v[104:107], v[92:95], v[202:205], v[104:107]
	s_waitcnt lgkmcnt(0)
	v_mfma_f32_16x16x32_bf16 v[76:79], v[84:87], v[210:213], v[76:79]
	v_mfma_f32_16x16x32_bf16 v[72:75], v[92:95], v[210:213], v[72:75]
	s_setprio 0
	s_barrier
	s_add_i32 s46, 0, 0x1c000
	v_add_u32_e32 v140, s46, v188
	s_add_i32 s47, s68, s66
	ds_read_b128 v[214:217], v140
	ds_read_b128 v[218:221], v140 offset:1024
	ds_read_b128 v[222:225], v140 offset:2048
	ds_read_b128 v[230:233], v140 offset:3072
	v_lshl_add_u64 v[140:141], v[184:185], 0, s[14:15]
	s_mov_b32 m0, s47
	s_nop 0
	global_load_lds_dwordx4 v[140:141], off
	v_lshl_add_u64 v[140:141], v[194:195], 0, s[14:15]
	s_add_i32 m0, s47, 0x2000
	s_nop 0
	global_load_lds_dwordx4 v[140:141], off
	s_barrier
	s_setprio 1
	s_waitcnt lgkmcnt(1)
	v_mfma_f32_16x16x32_bf16 v[96:99], v[222:225], v[124:127], v[96:99]
	v_mfma_f32_16x16x32_bf16 v[140:143], v[214:217], v[124:127], v[156:159]
	s_waitcnt lgkmcnt(0)
	v_mfma_f32_16x16x32_bf16 v[152:155], v[230:233], v[132:135], v[96:99]
	v_mfma_f32_16x16x32_bf16 v[96:99], v[214:217], v[160:163], v[100:103]
	v_mfma_f32_16x16x32_bf16 v[156:159], v[218:221], v[132:135], v[140:143]
	v_mfma_f32_16x16x32_bf16 v[140:143], v[218:221], v[164:167], v[96:99]
	v_mfma_f32_16x16x32_bf16 v[96:99], v[222:225], v[160:163], v[108:111]
	v_mfma_f32_16x16x32_bf16 v[132:135], v[230:233], v[164:167], v[96:99]
	v_mfma_f32_16x16x32_bf16 v[96:99], v[214:217], v[198:201], v[112:115]
	v_mfma_f32_16x16x32_bf16 v[124:127], v[218:221], v[202:205], v[96:99]
	v_mfma_f32_16x16x32_bf16 v[96:99], v[222:225], v[198:201], v[116:119]
	v_mfma_f32_16x16x32_bf16 v[68:71], v[214:217], v[206:209], v[68:71]
	v_mfma_f32_16x16x32_bf16 v[64:67], v[222:225], v[206:209], v[64:67]
	v_mfma_f32_16x16x32_bf16 v[116:119], v[230:233], v[202:205], v[96:99]
	v_mfma_f32_16x16x32_bf16 v[68:71], v[218:221], v[210:213], v[68:71]
	v_mfma_f32_16x16x32_bf16 v[64:67], v[230:233], v[210:213], v[64:67]
	s_setprio 0
	s_mov_b32 m0, s63
	v_lshl_add_u64 v[184:185], v[226:227], 0, s[14:15]
	s_barrier
	ds_read_b128 v[96:99], v190 offset:49152
	ds_read_b128 v[100:103], v190 offset:50176
	ds_read_b128 v[108:111], v190 offset:51200
	ds_read_b128 v[112:115], v190 offset:52224
	ds_read_b128 v[160:163], v190 offset:53248
	ds_read_b128 v[164:167], v190 offset:54272
	ds_read_b128 v[198:201], v190 offset:55296
	ds_read_b128 v[202:205], v190 offset:56320
	global_load_lds_dwordx4 v[184:185], off
	v_lshl_add_u64 v[184:185], v[234:235], 0, s[14:15]
	s_mov_b32 m0, s4
	s_nop 0
	global_load_lds_dwordx4 v[184:185], off
	s_waitcnt vmcnt(10)
	s_barrier
	s_setprio 1
	s_waitcnt lgkmcnt(7)
	v_mfma_f32_16x16x32_bf16 v[60:63], v[80:83], v[96:99], v[60:63]
	v_mfma_f32_16x16x32_bf16 v[48:51], v[88:91], v[96:99], v[48:51]
	s_waitcnt lgkmcnt(5)
	v_mfma_f32_16x16x32_bf16 v[40:43], v[80:83], v[108:111], v[40:43]
	v_mfma_f32_16x16x32_bf16 v[32:35], v[88:91], v[108:111], v[32:35]
	s_waitcnt lgkmcnt(3)
	v_mfma_f32_16x16x32_bf16 v[24:27], v[80:83], v[160:163], v[24:27]
	v_mfma_f32_16x16x32_bf16 v[16:19], v[88:91], v[160:163], v[16:19]
	s_waitcnt lgkmcnt(1)
	v_mfma_f32_16x16x32_bf16 v[12:15], v[80:83], v[198:201], v[12:15]
	v_mfma_f32_16x16x32_bf16 v[8:11], v[88:91], v[198:201], v[8:11]
	v_mfma_f32_16x16x32_bf16 v[60:63], v[84:87], v[100:103], v[60:63]
	v_mfma_f32_16x16x32_bf16 v[48:51], v[92:95], v[100:103], v[48:51]
	v_mfma_f32_16x16x32_bf16 v[40:43], v[84:87], v[112:115], v[40:43]
	v_mfma_f32_16x16x32_bf16 v[32:35], v[92:95], v[112:115], v[32:35]
	v_mfma_f32_16x16x32_bf16 v[24:27], v[84:87], v[164:167], v[24:27]
	v_mfma_f32_16x16x32_bf16 v[16:19], v[92:95], v[164:167], v[16:19]
	s_waitcnt lgkmcnt(0)
	v_mfma_f32_16x16x32_bf16 v[12:15], v[84:87], v[202:205], v[12:15]
	v_mfma_f32_16x16x32_bf16 v[8:11], v[92:95], v[202:205], v[8:11]
	s_setprio 0
	s_barrier
	s_add_u32 s24, s24, 0x80080
	s_addc_u32 s25, s25, 0
	s_add_i32 s46, s46, s66
	s_mov_b32 m0, s46
	s_nop 0
	global_load_lds_dwordx4 v172, s[24:25]
	s_add_i32 m0, s46, 0x2000
	s_nop 0
	global_load_lds_dwordx4 v168, s[24:25]
	s_waitcnt vmcnt(6)
	s_barrier
; DI float dpp_ror1(float v)  { return __builtin_bit_cast(float, __builtin_amdgcn_update_dpp(0, __builtin_bit_cast(int, v), 0x121, 0xf, 0xf, false)); }
;     DI void operator()(const f32x4 (&acc)[2][2][4][2], const Unit& u, int wr, int wc, int fr, int fq) const {
;     ...
;         f32x4 w0[2], w1[2], w2[2], bb[2];
; #pragma unroll
;         for (int n = 0; n < 2; ++n) { w0[n] = *(const f32x4*)(cw + ch0 + 4 * n); w1[n] = *(const f32x4*)(cw + DFF + ch0 + 4 * n); w2[n] = *(const f32x4*)(cw + 2 * DFF + ch0 + 4 * n); bb[n] = *(const f32x4*)(cb + ch0 + 4 * n); }
; #pragma unroll
;         for (int ai = 0; ai < 2; ++ai)
; #pragma unroll
;             for (int m = 0; m < 4; ++m) {
;                 const bool efirst = (m == 0) && (fr == 0), elast = (m == 3) && (fr == 15);
;                 const int row = row0 + ai * HALF + m * 16;
;                 f32x4 gc[2];
; #pragma unroll
;                 for (int n = 0; n < 2; ++n) {
;                     const f32x4 g = acc[ai][0][m][n];
;                     const f32x4 gprev = acc[ai][0][m > 0 ? m - 1 : 0][n], gnext = acc[ai][0][m < 3 ? m + 1 : 3][n];
;                     f32x4 up, dn;
; #pragma unroll
;                     for (int e = 0; e < 4; ++e) {
;                         const float pu = (m > 0 && fr == 15) ? gprev[e] : g[e];
;                         const float pd = (m < 3 && fr == 0) ? gnext[e] : g[e];
;                         up[e] = dpp_ror1(pu); dn[e] = dpp_ror15(pd);
;                     }
;                     if (efirst) up = (f32x4){0.f, 0.f, 0.f, 0.f};
;                     if (elast) dn = (f32x4){0.f, 0.f, 0.f, 0.f};
;                     gc[n] = w0[n] * up + w1[n] * g + w2[n] * dn + bb[n];
;                 }
;                 if (efirst || elast) {
; template <class Map, class Epi>
; DI void gemm_phase(LAS unsigned char* lds, const Map& MP, const Epi& E, const int nM, const int nN, const int K, const int lda, const int ldb) {
;     ...
;             PG8_BAR; PG8_WAIT_L(0); PG8_MMA(0, 1, At, B1); PG8_BAR;
;             PG8_LDA(At, 1, 1); PG8_STAGE(PG8_SA(1, 0), a3, voffA);
;             PG8_BAR; PG8_WAIT_L(0); PG8_MMA(1, 0, At, B0); PG8_BAR; PG8_SCHED;
;             PG8_STAGE(PG8_SB(1, 1), b3 + hstepB, voffB);
;             PG8_WAIT_V(6); PG8_BAR; PG8_MMA(1, 1, At, B1); PG8_BAR;
;         }
;         { int frr = fr, fqq = fq; asm volatile("" : "+v"(frr), "+v"(fqq)); E(acc, cur, wr, wc, frr, fqq); }
	s_setprio 1
	v_mfma_f32_16x16x32_bf16 v[56:59], v[214:217], v[96:99], v[56:59]
	v_mfma_f32_16x16x32_bf16 v[52:55], v[222:225], v[96:99], v[52:55]
	ds_read_b128 v[80:83], v189
	v_mfma_f32_16x16x32_bf16 v[44:47], v[214:217], v[108:111], v[44:47]
	v_mfma_f32_16x16x32_bf16 v[36:39], v[222:225], v[108:111], v[36:39]
	ds_read_b128 v[84:87], v189 offset:1024
	v_mfma_f32_16x16x32_bf16 v[28:31], v[214:217], v[160:163], v[28:31]
	v_mfma_f32_16x16x32_bf16 v[20:23], v[222:225], v[160:163], v[20:23]
	ds_read_b128 v[88:91], v189 offset:2048
	v_mfma_f32_16x16x32_bf16 v[4:7], v[214:217], v[198:201], v[4:7]
	v_mfma_f32_16x16x32_bf16 v[0:3], v[222:225], v[198:201], v[0:3]
	ds_read_b128 v[92:95], v189 offset:3072
	v_mfma_f32_16x16x32_bf16 v[56:59], v[218:221], v[100:103], v[56:59]
	v_mfma_f32_16x16x32_bf16 v[52:55], v[230:233], v[100:103], v[52:55]
	v_mfma_f32_16x16x32_bf16 v[44:47], v[218:221], v[112:115], v[44:47]
	v_mfma_f32_16x16x32_bf16 v[36:39], v[230:233], v[112:115], v[36:39]
	v_mfma_f32_16x16x32_bf16 v[28:31], v[218:221], v[164:167], v[28:31]
	v_mfma_f32_16x16x32_bf16 v[20:23], v[230:233], v[164:167], v[20:23]
	v_mfma_f32_16x16x32_bf16 v[4:7], v[218:221], v[202:205], v[4:7]
	v_mfma_f32_16x16x32_bf16 v[0:3], v[230:233], v[202:205], v[0:3]
	s_setprio 0
	s_add_i32 s3, s3, 2
	s_add_u32 vcc_lo, vcc_lo, 0x100
	s_addc_u32 vcc_hi, vcc_hi, 0
	s_add_u32 s42, s42, 0x100
	s_addc_u32 s43, s43, 0
	s_cmp_gt_u32 s3, 29
	s_barrier
	s_cbranch_scc0 .LBB1_1069
	s_waitcnt lgkmcnt(0)
	s_lshl_b32 s21, s45, 7
	v_mov_b32_e32 v194, v186
	v_mov_b32_e32 v80, v187
	s_or_b32 s21, s21, s62
	v_mov_b32_e32 v160, 0
	v_lshl_add_u32 v184, v80, 3, s21
	v_ashrrev_i32_e32 v185, 31, v184
	v_lshlrev_b64 v[80:81], 2, v[184:185]
	v_lshl_add_u64 v[84:85], s[6:7], 0, v[80:81]
	v_lshl_add_u64 v[88:89], s[16:17], 0, v[80:81]
	v_lshl_add_u64 v[92:93], s[18:19], 0, v[80:81]
	v_lshl_add_u64 v[112:113], s[52:53], 0, v[80:81]
	global_load_dwordx4 v[80:83], v[84:85], off offset:16
	global_load_dwordx4 v[96:99], v[84:85], off
	s_nop 0
	global_load_dwordx4 v[84:87], v[88:89], off offset:16
	global_load_dwordx4 v[100:103], v[88:89], off
	s_nop 0
	global_load_dwordx4 v[88:91], v[92:93], off offset:16
	global_load_dwordx4 v[108:111], v[92:93], off
	s_nop 0
	global_load_dwordx4 v[92:95], v[112:113], off offset:16
	s_nop 0
	global_load_dwordx4 v[112:115], v[112:113], off
	v_cmp_eq_u32_e32 vcc, 0, v194
	v_mov_b32_e32 v164, 0
	v_mov_b32_e32 v195, 0
	v_cndmask_b32_e32 v161, v148, v136, vcc
	v_cndmask_b32_e32 v162, v149, v137, vcc
	v_cndmask_b32_e32 v163, v150, v138, vcc
	v_mov_b32_dpp v160, v161 row_ror:15 row_mask:0xf bank_mask:0xf
	v_mov_b32_e32 v161, 0
	v_mov_b32_e32 v166, 0
	v_mov_b32_e32 v167, 0
	v_mov_b32_dpp v161, v162 row_ror:15 row_mask:0xf bank_mask:0xf
	v_mov_b32_e32 v162, 0
	v_mov_b32_dpp v164, v150 row_ror:1 row_mask:0xf bank_mask:0xf
	v_cndmask_b32_e32 v165, v151, v139, vcc
	v_mov_b32_dpp v162, v163 row_ror:15 row_mask:0xf bank_mask:0xf
	v_mov_b32_dpp v195, v151 row_ror:1 row_mask:0xf bank_mask:0xf
	v_mov_b32_e32 v163, 0
	v_mov_b32_dpp v166, v148 row_ror:1 row_mask:0xf bank_mask:0xf
	v_mov_b32_dpp v167, v149 row_ror:1 row_mask:0xf bank_mask:0xf
	v_mov_b32_dpp v163, v165 row_ror:15 row_mask:0xf bank_mask:0xf
	v_cndmask_b32_e64 v165, v195, 0, vcc
	v_cndmask_b32_e64 v164, v164, 0, vcc
	v_cndmask_b32_e64 v167, v167, 0, vcc
	v_cndmask_b32_e64 v166, v166, 0, vcc
	v_mov_b32_e32 v195, 0
	v_mov_b32_e32 v196, 0
	v_mov_b32_e32 v198, 0
	v_mov_b32_e32 v200, 0
	v_mov_b32_dpp v195, v144 row_ror:1 row_mask:0xf bank_mask:0xf
	v_mov_b32_dpp v196, v145 row_ror:1 row_mask:0xf bank_mask:0xf
	v_mov_b32_dpp v198, v146 row_ror:1 row_mask:0xf bank_mask:0xf
	v_cndmask_b32_e32 v199, v147, v131, vcc
	v_mov_b32_dpp v200, v147 row_ror:1 row_mask:0xf bank_mask:0xf
	v_cndmask_b32_e64 v198, v198, 0, vcc
	v_cndmask_b32_e64 v201, v196, 0, vcc
	s_lshl_b32 s3, s44, 8
	s_add_i32 s3, s3, s49
	v_add_u32_e32 v193, s3, v194
	v_cmp_ne_u32_e64 s[46:47], 0, v194
	s_waitcnt vmcnt(0)
	v_pk_mul_f32 v[164:165], v[98:99], v[164:165]
	v_pk_mul_f32 v[166:167], v[96:97], v[166:167]
	v_pk_fma_f32 v[164:165], v[150:151], v[102:103], v[164:165]
	v_pk_fma_f32 v[166:167], v[148:149], v[100:101], v[166:167]
	v_pk_fma_f32 v[162:163], v[110:111], v[162:163], v[164:165]
	v_cndmask_b32_e32 v165, v144, v128, vcc
	v_mov_b32_e32 v164, 0
	v_pk_fma_f32 v[160:161], v[108:109], v[160:161], v[166:167]
	v_cndmask_b32_e32 v166, v145, v129, vcc
	v_mov_b32_dpp v164, v165 row_ror:15 row_mask:0xf bank_mask:0xf
	v_mov_b32_e32 v165, 0
	v_cndmask_b32_e32 v167, v146, v130, vcc
	v_pk_add_f32 v[162:163], v[114:115], v[162:163]
	v_mov_b32_dpp v165, v166 row_ror:15 row_mask:0xf bank_mask:0xf
	v_mov_b32_e32 v166, 0
	v_pk_add_f32 v[160:161], v[112:113], v[160:161]
	s_nop 0
	v_mov_b32_dpp v166, v167 row_ror:15 row_mask:0xf bank_mask:0xf
	v_mov_b32_e32 v167, 0
	s_nop 1
	v_mov_b32_dpp v167, v199 row_ror:15 row_mask:0xf bank_mask:0xf
	v_cndmask_b32_e64 v199, v200, 0, vcc
	v_cndmask_b32_e64 v200, v195, 0, vcc
	v_pk_mul_f32 v[200:201], v[80:81], v[200:201]
	v_pk_mul_f32 v[198:199], v[82:83], v[198:199]
	v_pk_fma_f32 v[200:201], v[144:145], v[84:85], v[200:201]
	v_pk_fma_f32 v[198:199], v[146:147], v[86:87], v[198:199]
	v_pk_fma_f32 v[164:165], v[88:89], v[164:165], v[200:201]
	v_pk_fma_f32 v[166:167], v[90:91], v[166:167], v[198:199]
	v_pk_add_f32 v[164:165], v[92:93], v[164:165]
	v_pk_add_f32 v[166:167], v[94:95], v[166:167]
	s_and_saveexec_b64 s[24:25], s[46:47]
	s_xor_b64 s[24:25], exec, s[24:25]
	s_cbranch_execz .LBB1_1072
; DI unsigned pack2(float a, float b) { f32x2 v = {a, b}; hwbf16x2 r = __builtin_convertvector(v, hwbf16x2); return __builtin_bit_cast(unsigned, r); }
; DI float silu_mul(float g, float v) { return g * v * __builtin_amdgcn_rcpf(1.0f + __builtin_amdgcn_exp2f(-LOG2E * g)); }
;     DI void operator()(const f32x4 (&acc)[2][2][4][2], const Unit& u, int wr, int wc, int fr, int fq) const {
;     ...
;                     const f32x4 v0 = acc[ai][1][m][0], v1 = acc[ai][1][m][1];
;                     u32x4 o;
;                     o[0] = pack2(silu_mul(gc[0][0], v0[0]), silu_mul(gc[0][1], v0[1])); o[1] = pack2(silu_mul(gc[0][2], v0[2]), silu_mul(gc[0][3], v0[3]));
;                     o[2] = pack2(silu_mul(gc[1][0], v1[0]), silu_mul(gc[1][1], v1[1])); o[3] = pack2(silu_mul(gc[1][2], v1[2]), silu_mul(gc[1][3], v1[3]));
;                     *(u32x4*)(ACT + (size_t)row * DFF + ch0) = o;
	v_mul_f32_e32 v195, 0xbfb8aa3b, v160
	v_exp_f32_e32 v195, v195
	v_mul_f32_e32 v196, 0xbfb8aa3b, v161
	v_exp_f32_e32 v196, v196
	v_pk_mul_f32 v[160:161], v[156:157], v[160:161]
	v_add_f32_e32 v195, 1.0, v195
	v_rcp_f32_e32 v198, v195
	v_add_f32_e32 v196, 1.0, v196
	v_mul_f32_e32 v195, 0xbfb8aa3b, v162
	v_rcp_f32_e32 v199, v196
	v_exp_f32_e32 v195, v195
	v_mul_f32_e32 v196, 0xbfb8aa3b, v163
	v_exp_f32_e32 v196, v196
	v_pk_mul_f32 v[160:161], v[160:161], v[198:199]
	v_add_f32_e32 v195, 1.0, v195
	v_rcp_f32_e32 v200, v195
	v_add_f32_e32 v195, 1.0, v196
	v_rcp_f32_e32 v201, v195
	v_cvt_pk_bf16_f32 v160, v160, v161
	v_mul_f32_e32 v161, 0xbfb8aa3b, v164
	v_exp_f32_e32 v195, v161
	v_mul_f32_e32 v161, 0xbfb8aa3b, v165
	v_exp_f32_e32 v196, v161
	v_pk_mul_f32 v[162:163], v[158:159], v[162:163]
	v_pk_mul_f32 v[164:165], v[152:153], v[164:165]
	v_pk_mul_f32 v[162:163], v[162:163], v[200:201]
	s_nop 0
	v_cvt_pk_bf16_f32 v161, v162, v163
	v_add_f32_e32 v162, 1.0, v195
	v_mul_f32_e32 v195, 0xbfb8aa3b, v166
	v_add_f32_e32 v163, 1.0, v196
	v_exp_f32_e32 v195, v195
	v_mul_f32_e32 v196, 0xbfb8aa3b, v167
	v_exp_f32_e32 v196, v196
	v_rcp_f32_e32 v162, v162
	v_add_f32_e32 v195, 1.0, v195
	v_rcp_f32_e32 v198, v195
	v_add_f32_e32 v195, 1.0, v196
	v_rcp_f32_e32 v163, v163
	v_rcp_f32_e32 v199, v195
	v_pk_mul_f32 v[166:167], v[154:155], v[166:167]
	v_pk_mul_f32 v[162:163], v[164:165], v[162:163]
	v_pk_mul_f32 v[164:165], v[166:167], v[198:199]
	v_cvt_pk_bf16_f32 v162, v162, v163
	v_cvt_pk_bf16_f32 v163, v164, v165
	v_mov_b64_e32 v[164:165], s[54:55]
	v_mad_i64_i32 v[164:165], s[42:43], v193, s60, v[164:165]
	v_lshl_add_u64 v[164:165], v[184:185], 1, v[164:165]
	global_store_dwordx4 v[164:165], v[160:163], off

; #define PG8_STAGE(bufoff, gbase, voff) do { _Pragma("unroll") for (int _i = 0; _i < 2; ++_i) \
;         __builtin_amdgcn_global_load_lds((const unsigned*)((const char*)(gbase) + (voff)[_i]), (LAS unsigned*)(lds + (bufoff) + ldsw + _i * 8192), 16, 0, 0); } while (0)
; #define PG8_LDA(dst, b, h) do { _Pragma("unroll") for (int m = 0; m < 4; ++m) _Pragma("unroll") for (int k = 0; k < 2; ++k) dst[m][k] = *(const LAS bf16x8*)(lds + PG8_SA(b, h) + aoff + m * 2048 + k * 1024); } while (0)
; #define PG8_LDB(dst, b, h) do { _Pragma("unroll") for (int n = 0; n < 2; ++n) _Pragma("unroll") for (int k = 0; k < 2; ++k) dst[n][k] = *(const LAS bf16x8*)(lds + PG8_SB(b, h) + boff + n * 2048 + k * 1024); } while (0)
; #define PG8_MMA(ai, bj, At, Bt) do { __builtin_amdgcn_s_setprio(1); _Pragma("unroll") for (int m = 0; m < 4; ++m) _Pragma("unroll") for (int n = 0; n < 2; ++n) _Pragma("unroll") for (int k = 0; k < 2; ++k) \
;         acc[ai][bj][m][n] = __builtin_amdgcn_mfma_f32_16x16x32_bf16(Bt[n][k], At[m][k], acc[ai][bj][m][n], 0, 0, 0); __builtin_amdgcn_s_setprio(0); } while (0)
; #define PG8_WAIT_V(n) asm volatile("s_waitcnt vmcnt(" #n ")" ::: "memory")
; #define PG8_WAIT_L(n) asm volatile("s_waitcnt lgkmcnt(" #n ")" ::: "memory")
; #define PG8_BAR __builtin_amdgcn_s_barrier()
; #define PG8_SCHED __builtin_amdgcn_sched_barrier(0)
; template <class Map, class Epi>
; DI void gemm_phase(LAS unsigned char* lds, const Map& MP, const Epi& E, const int nM, const int nN, const int K, const int lda, const int ldb) {
;     ...
;             PG8_LDB(B0, 0, 0); PG8_SCHED; PG8_LDA(At, 0, 0); PG8_STAGE(PG8_SA(1, 1), a1 + hstepA, voffA);
;             PG8_WAIT_L(8); PG8_BAR; PG8_WAIT_L(0); PG8_MMA(0, 0, At, B0); PG8_BAR; PG8_SCHED;
;             PG8_LDB(B1, 0, 1); PG8_STAGE(PG8_SB(0, 0), b2, voffB);
;             PG8_BAR; PG8_WAIT_L(0); PG8_MMA(0, 1, At, B1); PG8_BAR;
;             PG8_LDA(At, 0, 1); PG8_STAGE(PG8_SA(0, 0), a2, voffA);
;             PG8_BAR; PG8_WAIT_L(0); PG8_MMA(1, 0, At, B0); PG8_BAR; PG8_SCHED;
;             PG8_STAGE(PG8_SB(0, 1), b2 + hstepB, voffB);
;             PG8_WAIT_V(6); PG8_BAR; PG8_MMA(1, 1, At, B1); PG8_BAR;
;             PG8_LDB(B0, 1, 0); PG8_SCHED; PG8_LDA(At, 1, 0); PG8_STAGE(PG8_SA(0, 1), a2 + hstepA, voffA);
.LBB1_1239:
	s_add_u32 s10, s8, 0x100
	s_addc_u32 s11, s9, 0
	s_cmpk_eq_i32 s3, 0x54
	s_cselect_b32 s15, s43, s11
	s_cselect_b32 s14, s42, s10
	s_cselect_b32 s13, s7, s38
	s_cselect_b32 s12, s6, s5
	s_add_i32 m0, s24, 0xc000
	ds_read_b128 v[168:171], v150
	ds_read_b128 v[172:175], v150 offset:1024
	ds_read_b128 v[176:179], v150 offset:2048
	ds_read_b128 v[180:183], v150 offset:3072
	ds_read_b128 v[184:187], v150 offset:4096
	ds_read_b128 v[188:191], v150 offset:5120
	ds_read_b128 v[192:195], v150 offset:6144
	ds_read_b128 v[198:201], v150 offset:7168
	global_load_lds_dwordx4 v138, s[8:9]
	s_add_i32 m0, s24, 0xe000
	s_nop 0
	global_load_lds_dwordx4 v136, s[8:9]
	s_waitcnt lgkmcnt(8)
	s_barrier
	s_setprio 1
	s_waitcnt lgkmcnt(7)
	v_mfma_f32_16x16x32_bf16 v[124:127], v[152:155], v[168:171], v[124:127]
	v_mfma_f32_16x16x32_bf16 v[120:123], v[160:163], v[168:171], v[120:123]
	s_waitcnt lgkmcnt(5)
	v_mfma_f32_16x16x32_bf16 v[108:111], v[152:155], v[176:179], v[108:111]
	v_mfma_f32_16x16x32_bf16 v[104:107], v[160:163], v[176:179], v[104:107]
	s_waitcnt lgkmcnt(3)
	v_mfma_f32_16x16x32_bf16 v[92:95], v[152:155], v[184:187], v[92:95]
	v_mfma_f32_16x16x32_bf16 v[88:91], v[160:163], v[184:187], v[88:91]
	s_waitcnt lgkmcnt(1)
	v_mfma_f32_16x16x32_bf16 v[76:79], v[152:155], v[192:195], v[76:79]
	v_mfma_f32_16x16x32_bf16 v[72:75], v[160:163], v[192:195], v[72:75]
	v_mfma_f32_16x16x32_bf16 v[124:127], v[156:159], v[172:175], v[124:127]
	v_mfma_f32_16x16x32_bf16 v[120:123], v[164:167], v[172:175], v[120:123]
	v_mfma_f32_16x16x32_bf16 v[108:111], v[156:159], v[180:183], v[108:111]
	v_mfma_f32_16x16x32_bf16 v[104:107], v[164:167], v[180:183], v[104:107]
	v_mfma_f32_16x16x32_bf16 v[92:95], v[156:159], v[188:191], v[92:95]
	v_mfma_f32_16x16x32_bf16 v[88:91], v[164:167], v[188:191], v[88:91]
	s_waitcnt lgkmcnt(0)
	v_mfma_f32_16x16x32_bf16 v[76:79], v[156:159], v[198:201], v[76:79]
	v_mfma_f32_16x16x32_bf16 v[72:75], v[164:167], v[198:201], v[72:75]
	s_setprio 0
	s_barrier
	s_add_i32 s8, s35, s22
	v_lshl_add_u64 v[144:145], s[12:13], 0, v[132:133]
	s_mov_b32 m0, s8
	ds_read_b128 v[202:205], v151
	ds_read_b128 v[206:209], v151 offset:1024
	ds_read_b128 v[210:213], v151 offset:2048
	ds_read_b128 v[214:217], v151 offset:3072
	global_load_lds_dwordx4 v[144:145], off
	v_lshl_add_u64 v[218:219], s[12:13], 0, v[128:129]
	s_add_i32 m0, s8, 0x2000
	s_nop 0
	global_load_lds_dwordx4 v[218:219], off
	s_barrier
	s_setprio 1
	s_waitcnt lgkmcnt(3)
	v_mfma_f32_16x16x32_bf16 v[116:119], v[202:205], v[168:171], v[116:119]
	s_waitcnt lgkmcnt(1)
	v_mfma_f32_16x16x32_bf16 v[112:115], v[210:213], v[168:171], v[112:115]
	v_mfma_f32_16x16x32_bf16 v[100:103], v[202:205], v[176:179], v[100:103]
	v_mfma_f32_16x16x32_bf16 v[96:99], v[210:213], v[176:179], v[96:99]
	v_mfma_f32_16x16x32_bf16 v[84:87], v[202:205], v[184:187], v[84:87]
	v_mfma_f32_16x16x32_bf16 v[80:83], v[210:213], v[184:187], v[80:83]
	v_mfma_f32_16x16x32_bf16 v[68:71], v[202:205], v[192:195], v[68:71]
	v_mfma_f32_16x16x32_bf16 v[64:67], v[210:213], v[192:195], v[64:67]
	v_mfma_f32_16x16x32_bf16 v[116:119], v[206:209], v[172:175], v[116:119]
	s_waitcnt lgkmcnt(0)
	v_mfma_f32_16x16x32_bf16 v[112:115], v[214:217], v[172:175], v[112:115]
	v_mfma_f32_16x16x32_bf16 v[100:103], v[206:209], v[180:183], v[100:103]
	v_mfma_f32_16x16x32_bf16 v[96:99], v[214:217], v[180:183], v[96:99]
	v_mfma_f32_16x16x32_bf16 v[84:87], v[206:209], v[188:191], v[84:87]
	v_mfma_f32_16x16x32_bf16 v[80:83], v[214:217], v[188:191], v[80:83]
	v_mfma_f32_16x16x32_bf16 v[68:71], v[206:209], v[198:201], v[68:71]
	v_mfma_f32_16x16x32_bf16 v[64:67], v[214:217], v[198:201], v[64:67]
	s_setprio 0
	s_mov_b32 m0, s24
	v_lshl_add_u64 v[220:221], s[14:15], 0, v[134:135]
	s_barrier
	ds_read_b128 v[168:171], v150 offset:16384
	ds_read_b128 v[172:175], v150 offset:17408
	ds_read_b128 v[176:179], v150 offset:18432
	ds_read_b128 v[180:183], v150 offset:19456
	ds_read_b128 v[184:187], v150 offset:20480
	ds_read_b128 v[188:191], v150 offset:21504
	ds_read_b128 v[192:195], v150 offset:22528
	ds_read_b128 v[198:201], v150 offset:23552
	global_load_lds_dwordx4 v[220:221], off
	v_lshl_add_u64 v[222:223], s[14:15], 0, v[130:131]
	s_mov_b32 m0, s25
	s_nop 0
	global_load_lds_dwordx4 v[222:223], off
	s_waitcnt vmcnt(10)
	s_barrier
	s_setprio 1
	s_waitcnt lgkmcnt(7)
	v_mfma_f32_16x16x32_bf16 v[60:63], v[152:155], v[168:171], v[60:63]
	v_mfma_f32_16x16x32_bf16 v[56:59], v[160:163], v[168:171], v[56:59]
	s_waitcnt lgkmcnt(5)
	v_mfma_f32_16x16x32_bf16 v[44:47], v[152:155], v[176:179], v[44:47]
	v_mfma_f32_16x16x32_bf16 v[40:43], v[160:163], v[176:179], v[40:43]
	s_waitcnt lgkmcnt(3)
	v_mfma_f32_16x16x32_bf16 v[28:31], v[152:155], v[184:187], v[28:31]
	v_mfma_f32_16x16x32_bf16 v[24:27], v[160:163], v[184:187], v[24:27]
	s_waitcnt lgkmcnt(1)
	v_mfma_f32_16x16x32_bf16 v[12:15], v[152:155], v[192:195], v[12:15]
	v_mfma_f32_16x16x32_bf16 v[8:11], v[160:163], v[192:195], v[8:11]
	v_mfma_f32_16x16x32_bf16 v[60:63], v[156:159], v[172:175], v[60:63]
	v_mfma_f32_16x16x32_bf16 v[56:59], v[164:167], v[172:175], v[56:59]
	v_mfma_f32_16x16x32_bf16 v[44:47], v[156:159], v[180:183], v[44:47]
	v_mfma_f32_16x16x32_bf16 v[40:43], v[164:167], v[180:183], v[40:43]
	v_mfma_f32_16x16x32_bf16 v[28:31], v[156:159], v[188:191], v[28:31]
	v_mfma_f32_16x16x32_bf16 v[24:27], v[164:167], v[188:191], v[24:27]
	s_waitcnt lgkmcnt(0)
	v_mfma_f32_16x16x32_bf16 v[12:15], v[156:159], v[198:201], v[12:15]
	v_mfma_f32_16x16x32_bf16 v[8:11], v[164:167], v[198:201], v[8:11]
	s_setprio 0
	s_barrier
	s_add_u32 s8, s12, 0x160000
	s_addc_u32 s9, s13, 0
	s_add_i32 s39, s36, s22
	s_mov_b32 m0, s39
	s_nop 0
	global_load_lds_dwordx4 v132, s[8:9]
	s_add_i32 m0, s39, 0x2000
	s_nop 0
	global_load_lds_dwordx4 v128, s[8:9]
	s_waitcnt vmcnt(6)
	s_barrier
; #define PG8_STAGE(bufoff, gbase, voff) do { _Pragma("unroll") for (int _i = 0; _i < 2; ++_i) \
;         __builtin_amdgcn_global_load_lds((const unsigned*)((const char*)(gbase) + (voff)[_i]), (LAS unsigned*)(lds + (bufoff) + ldsw + _i * 8192), 16, 0, 0); } while (0)
; #define PG8_LDA(dst, b, h) do { _Pragma("unroll") for (int m = 0; m < 4; ++m) _Pragma("unroll") for (int k = 0; k < 2; ++k) dst[m][k] = *(const LAS bf16x8*)(lds + PG8_SA(b, h) + aoff + m * 2048 + k * 1024); } while (0)
; #define PG8_LDB(dst, b, h) do { _Pragma("unroll") for (int n = 0; n < 2; ++n) _Pragma("unroll") for (int k = 0; k < 2; ++k) dst[n][k] = *(const LAS bf16x8*)(lds + PG8_SB(b, h) + boff + n * 2048 + k * 1024); } while (0)
; #define PG8_MMA(ai, bj, At, Bt) do { __builtin_amdgcn_s_setprio(1); _Pragma("unroll") for (int m = 0; m < 4; ++m) _Pragma("unroll") for (int n = 0; n < 2; ++n) _Pragma("unroll") for (int k = 0; k < 2; ++k) \
;         acc[ai][bj][m][n] = __builtin_amdgcn_mfma_f32_16x16x32_bf16(Bt[n][k], At[m][k], acc[ai][bj][m][n], 0, 0, 0); __builtin_amdgcn_s_setprio(0); } while (0)
; #define PG8_WAIT_V(n) asm volatile("s_waitcnt vmcnt(" #n ")" ::: "memory")
; #define PG8_WAIT_L(n) asm volatile("s_waitcnt lgkmcnt(" #n ")" ::: "memory")
; #define PG8_BAR __builtin_amdgcn_s_barrier()
; #define PG8_SCHED __builtin_amdgcn_sched_barrier(0)
; template <class Map, class Epi>
; DI void gemm_phase(LAS unsigned char* lds, const Map& MP, const Epi& E, const int nM, const int nN, const int K, const int lda, const int ldb) {
;     ...
;             PG8_BAR; PG8_WAIT_L(0); PG8_MMA(1, 0, At, B0); PG8_BAR; PG8_SCHED;
;             PG8_STAGE(PG8_SB(0, 1), b2 + hstepB, voffB);
;             PG8_WAIT_V(6); PG8_BAR; PG8_MMA(1, 1, At, B1); PG8_BAR;
;             PG8_LDB(B0, 1, 0); PG8_SCHED; PG8_LDA(At, 1, 0); PG8_STAGE(PG8_SA(0, 1), a2 + hstepA, voffA);
;             PG8_WAIT_L(8); PG8_BAR; PG8_WAIT_L(0); PG8_MMA(0, 0, At, B0); PG8_BAR; PG8_SCHED;
;             PG8_LDB(B1, 1, 1); PG8_STAGE(PG8_SB(1, 0), b3, voffB);
;             PG8_BAR; PG8_WAIT_L(0); PG8_MMA(0, 1, At, B1); PG8_BAR;
;             PG8_LDA(At, 1, 1); PG8_STAGE(PG8_SA(1, 0), a3, voffA);
;             PG8_BAR; PG8_WAIT_L(0); PG8_MMA(1, 0, At, B0); PG8_BAR; PG8_SCHED;
	s_setprio 1
	v_mfma_f32_16x16x32_bf16 v[52:55], v[202:205], v[168:171], v[52:55]
	v_mfma_f32_16x16x32_bf16 v[48:51], v[210:213], v[168:171], v[48:51]
	s_add_i32 s39, 0, 0x18000
	v_add_u32_e32 v164, s39, v148
	ds_read_b128 v[152:155], v164
	v_mfma_f32_16x16x32_bf16 v[36:39], v[202:205], v[176:179], v[36:39]
	v_mfma_f32_16x16x32_bf16 v[32:35], v[210:213], v[176:179], v[32:35]
	ds_read_b128 v[156:159], v164 offset:1024
	v_mfma_f32_16x16x32_bf16 v[20:23], v[202:205], v[184:187], v[20:23]
	v_mfma_f32_16x16x32_bf16 v[16:19], v[210:213], v[184:187], v[16:19]
	ds_read_b128 v[160:163], v164 offset:2048
	v_mfma_f32_16x16x32_bf16 v[4:7], v[202:205], v[192:195], v[4:7]
	v_mfma_f32_16x16x32_bf16 v[0:3], v[210:213], v[192:195], v[0:3]
	ds_read_b128 v[164:167], v164 offset:3072
	v_mfma_f32_16x16x32_bf16 v[52:55], v[206:209], v[172:175], v[52:55]
	v_mfma_f32_16x16x32_bf16 v[48:51], v[214:217], v[172:175], v[48:51]
	v_mfma_f32_16x16x32_bf16 v[36:39], v[206:209], v[180:183], v[36:39]
	v_mfma_f32_16x16x32_bf16 v[32:35], v[214:217], v[180:183], v[32:35]
	v_mfma_f32_16x16x32_bf16 v[20:23], v[206:209], v[188:191], v[20:23]
	v_mfma_f32_16x16x32_bf16 v[16:19], v[214:217], v[188:191], v[16:19]
	v_mfma_f32_16x16x32_bf16 v[4:7], v[206:209], v[198:201], v[4:7]
	v_mfma_f32_16x16x32_bf16 v[0:3], v[214:217], v[198:201], v[0:3]
	s_setprio 0
	s_barrier
	s_add_u32 s8, s14, 0x160000
	s_addc_u32 s9, s15, 0
	s_mov_b32 m0, s26
	ds_read_b128 v[168:171], v150 offset:32768
	ds_read_b128 v[172:175], v150 offset:33792
	ds_read_b128 v[176:179], v150 offset:34816
	ds_read_b128 v[180:183], v150 offset:35840
	ds_read_b128 v[184:187], v150 offset:36864
	ds_read_b128 v[188:191], v150 offset:37888
	ds_read_b128 v[192:195], v150 offset:38912
	ds_read_b128 v[198:201], v150 offset:39936
	global_load_lds_dwordx4 v134, s[8:9]
	s_mov_b32 m0, s27
	s_nop 0
	global_load_lds_dwordx4 v130, s[8:9]
	s_waitcnt lgkmcnt(8)
	s_barrier
	s_setprio 1
	s_waitcnt lgkmcnt(7)
	v_mfma_f32_16x16x32_bf16 v[124:127], v[152:155], v[168:171], v[124:127]
	v_mfma_f32_16x16x32_bf16 v[120:123], v[160:163], v[168:171], v[120:123]
	s_waitcnt lgkmcnt(5)
	v_mfma_f32_16x16x32_bf16 v[108:111], v[152:155], v[176:179], v[108:111]
	v_mfma_f32_16x16x32_bf16 v[104:107], v[160:163], v[176:179], v[104:107]
	s_waitcnt lgkmcnt(3)
	v_mfma_f32_16x16x32_bf16 v[92:95], v[152:155], v[184:187], v[92:95]
	v_mfma_f32_16x16x32_bf16 v[88:91], v[160:163], v[184:187], v[88:91]
	s_waitcnt lgkmcnt(1)
	v_mfma_f32_16x16x32_bf16 v[76:79], v[152:155], v[192:195], v[76:79]
	v_mfma_f32_16x16x32_bf16 v[72:75], v[160:163], v[192:195], v[72:75]
	v_mfma_f32_16x16x32_bf16 v[124:127], v[156:159], v[172:175], v[124:127]
	v_mfma_f32_16x16x32_bf16 v[120:123], v[164:167], v[172:175], v[120:123]
	v_mfma_f32_16x16x32_bf16 v[108:111], v[156:159], v[180:183], v[108:111]
	v_mfma_f32_16x16x32_bf16 v[104:107], v[164:167], v[180:183], v[104:107]
	v_mfma_f32_16x16x32_bf16 v[92:95], v[156:159], v[188:191], v[92:95]
	v_mfma_f32_16x16x32_bf16 v[88:91], v[164:167], v[188:191], v[88:91]
	s_waitcnt lgkmcnt(0)
	v_mfma_f32_16x16x32_bf16 v[76:79], v[156:159], v[198:201], v[76:79]
	v_mfma_f32_16x16x32_bf16 v[72:75], v[164:167], v[198:201], v[72:75]
	s_setprio 0
	s_barrier
	s_add_i32 s14, 0, 0x1c000
	s_add_i32 s8, s39, s22
	v_add_u32_e32 v196, s14, v148
	v_lshl_add_u64 v[144:145], v[144:145], 0, s[52:53]
	s_mov_b32 m0, s8
	ds_read_b128 v[202:205], v196
	ds_read_b128 v[206:209], v196 offset:1024
	ds_read_b128 v[210:213], v196 offset:2048
	ds_read_b128 v[214:217], v196 offset:3072
	global_load_lds_dwordx4 v[144:145], off
	v_lshl_add_u64 v[144:145], v[218:219], 0, s[52:53]
	s_add_i32 m0, s8, 0x2000
	s_nop 0
	global_load_lds_dwordx4 v[144:145], off
	s_barrier
	s_setprio 1
	s_waitcnt lgkmcnt(3)
	v_mfma_f32_16x16x32_bf16 v[116:119], v[202:205], v[168:171], v[116:119]
	s_waitcnt lgkmcnt(1)
	v_mfma_f32_16x16x32_bf16 v[112:115], v[210:213], v[168:171], v[112:115]
	v_mfma_f32_16x16x32_bf16 v[100:103], v[202:205], v[176:179], v[100:103]
	v_mfma_f32_16x16x32_bf16 v[96:99], v[210:213], v[176:179], v[96:99]
	v_mfma_f32_16x16x32_bf16 v[84:87], v[202:205], v[184:187], v[84:87]
	v_mfma_f32_16x16x32_bf16 v[80:83], v[210:213], v[184:187], v[80:83]
	v_mfma_f32_16x16x32_bf16 v[68:71], v[202:205], v[192:195], v[68:71]
	v_mfma_f32_16x16x32_bf16 v[64:67], v[210:213], v[192:195], v[64:67]
	v_mfma_f32_16x16x32_bf16 v[116:119], v[206:209], v[172:175], v[116:119]
	s_waitcnt lgkmcnt(0)
	v_mfma_f32_16x16x32_bf16 v[112:115], v[214:217], v[172:175], v[112:115]
	v_mfma_f32_16x16x32_bf16 v[100:103], v[206:209], v[180:183], v[100:103]
	v_mfma_f32_16x16x32_bf16 v[96:99], v[214:217], v[180:183], v[96:99]
	v_mfma_f32_16x16x32_bf16 v[84:87], v[206:209], v[188:191], v[84:87]
	v_mfma_f32_16x16x32_bf16 v[80:83], v[214:217], v[188:191], v[80:83]
	v_mfma_f32_16x16x32_bf16 v[68:71], v[206:209], v[198:201], v[68:71]
	v_mfma_f32_16x16x32_bf16 v[64:67], v[214:217], v[198:201], v[64:67]
	s_setprio 0
	s_mov_b32 m0, s30
	v_lshl_add_u64 v[144:145], v[220:221], 0, s[52:53]
	s_barrier
	ds_read_b128 v[168:171], v150 offset:49152
	ds_read_b128 v[172:175], v150 offset:50176
	ds_read_b128 v[176:179], v150 offset:51200
	ds_read_b128 v[180:183], v150 offset:52224
	ds_read_b128 v[184:187], v150 offset:53248
	ds_read_b128 v[188:191], v150 offset:54272
	ds_read_b128 v[192:195], v150 offset:55296
	ds_read_b128 v[198:201], v150 offset:56320
	global_load_lds_dwordx4 v[144:145], off
	v_lshl_add_u64 v[144:145], v[222:223], 0, s[52:53]
	s_mov_b32 m0, s31
	s_nop 0
	global_load_lds_dwordx4 v[144:145], off
	s_waitcnt vmcnt(10)
	s_barrier
; DI unsigned pack2(float a, float b) { f32x2 v = {a, b}; hwbf16x2 r = __builtin_convertvector(v, hwbf16x2); return __builtin_bit_cast(unsigned, r); }
; DI float bflo(unsigned w) { return __uint_as_float(w << 16); }
; DI float bfhi(unsigned w) { return __uint_as_float(w & 0xffff0000u); }
; #define PG8_LDA(dst, b, h) do { _Pragma("unroll") for (int m = 0; m < 4; ++m) _Pragma("unroll") for (int k = 0; k < 2; ++k) dst[m][k] = *(const LAS bf16x8*)(lds + PG8_SA(b, h) + aoff + m * 2048 + k * 1024); } while (0)
;     DI void operator()(const f32x4 (&acc)[2][2][4][2], const Unit& u, int wr, int wc, int fr, int fq) const {
;     ...
;             for (int m = 0; m < 4; ++m) { const size_t ro = (size_t)(row0 + ai * HALF + m * 16) * D + col0;
; #pragma unroll
;                 for (int bj = 0; bj < 2; ++bj) {
;                     f32x4 x0, x1;
;                     if constexpr (IB) { const u32x4 w = *(const u32x4*)((const bf16_t*)Xin + ro + bj * HALF);
;                         x0 = (f32x4){bflo(w[0]), bfhi(w[0]), bflo(w[1]), bfhi(w[1])}; x1 = (f32x4){bflo(w[2]), bfhi(w[2]), bflo(w[3]), bfhi(w[3])}; }
;                     else { x0 = *(const f32x4*)((const float*)Xin + ro + bj * HALF); x1 = *(const f32x4*)((const float*)Xin + ro + bj * HALF + 4); }
;                     x0 += acc[ai][bj][m][0] * sc[bj][0]; x1 += acc[ai][bj][m][1] * sc[bj][1];
;                     if constexpr (OB) { u32x4 o; o[0] = pack2(x0[0], x0[1]); o[1] = pack2(x0[2], x0[3]); o[2] = pack2(x1[0], x1[1]); o[3] = pack2(x1[2], x1[3]);
;                         *(u32x4*)((bf16_t*)Xout + ro + bj * HALF) = o; }
;                     else { *(f32x4*)((float*)Xout + ro + bj * HALF) = x0; *(f32x4*)((float*)Xout + ro + bj * HALF + 4) = x1; } } }
; template <class Map, class Epi>
; DI void gemm_phase(LAS unsigned char* lds, const Map& MP, const Epi& E, const int nM, const int nN, const int K, const int lda, const int ldb) {
;     ...
;             PG8_BAR; PG8_WAIT_L(0); PG8_MMA(0, 1, At, B1); PG8_BAR;
;             PG8_LDA(At, 1, 1); PG8_STAGE(PG8_SA(1, 0), a3, voffA);
;             PG8_BAR; PG8_WAIT_L(0); PG8_MMA(1, 0, At, B0); PG8_BAR; PG8_SCHED;
;             PG8_STAGE(PG8_SB(1, 1), b3 + hstepB, voffB);
;             PG8_WAIT_V(6); PG8_BAR; PG8_MMA(1, 1, At, B1); PG8_BAR;
;         }
;         { int frr = fr, fqq = fq; asm volatile("" : "+v"(frr), "+v"(fqq)); E(acc, cur, wr, wc, frr, fqq); }
	s_setprio 1
	s_waitcnt lgkmcnt(7)
	v_mfma_f32_16x16x32_bf16 v[60:63], v[152:155], v[168:171], v[60:63]
	v_mfma_f32_16x16x32_bf16 v[56:59], v[160:163], v[168:171], v[56:59]
	s_waitcnt lgkmcnt(5)
	v_mfma_f32_16x16x32_bf16 v[44:47], v[152:155], v[176:179], v[44:47]
	v_mfma_f32_16x16x32_bf16 v[40:43], v[160:163], v[176:179], v[40:43]
	s_waitcnt lgkmcnt(3)
	v_mfma_f32_16x16x32_bf16 v[28:31], v[152:155], v[184:187], v[28:31]
	v_mfma_f32_16x16x32_bf16 v[24:27], v[160:163], v[184:187], v[24:27]
	s_waitcnt lgkmcnt(1)
	v_mfma_f32_16x16x32_bf16 v[12:15], v[152:155], v[192:195], v[12:15]
	v_mfma_f32_16x16x32_bf16 v[8:11], v[160:163], v[192:195], v[8:11]
	v_mfma_f32_16x16x32_bf16 v[60:63], v[156:159], v[172:175], v[60:63]
	v_mfma_f32_16x16x32_bf16 v[56:59], v[164:167], v[172:175], v[56:59]
	v_mfma_f32_16x16x32_bf16 v[44:47], v[156:159], v[180:183], v[44:47]
	v_mfma_f32_16x16x32_bf16 v[40:43], v[164:167], v[180:183], v[40:43]
	v_mfma_f32_16x16x32_bf16 v[28:31], v[156:159], v[188:191], v[28:31]
	v_mfma_f32_16x16x32_bf16 v[24:27], v[164:167], v[188:191], v[24:27]
	s_waitcnt lgkmcnt(0)
	v_mfma_f32_16x16x32_bf16 v[12:15], v[156:159], v[198:201], v[12:15]
	v_mfma_f32_16x16x32_bf16 v[8:11], v[164:167], v[198:201], v[8:11]
	s_setprio 0
	s_barrier
	s_add_u32 s8, s12, 0x160080
	s_addc_u32 s9, s13, 0
	s_add_i32 s12, s14, s22
	s_mov_b32 m0, s12
	s_nop 0
	global_load_lds_dwordx4 v132, s[8:9]
	s_add_i32 m0, s12, 0x2000
	s_nop 0
	global_load_lds_dwordx4 v128, s[8:9]
	s_waitcnt vmcnt(6)
	s_barrier
	s_setprio 1
	v_mfma_f32_16x16x32_bf16 v[52:55], v[202:205], v[168:171], v[52:55]
	v_mfma_f32_16x16x32_bf16 v[48:51], v[210:213], v[168:171], v[48:51]
	ds_read_b128 v[152:155], v149
	v_mfma_f32_16x16x32_bf16 v[36:39], v[202:205], v[176:179], v[36:39]
	v_mfma_f32_16x16x32_bf16 v[32:35], v[210:213], v[176:179], v[32:35]
	ds_read_b128 v[156:159], v149 offset:1024
	v_mfma_f32_16x16x32_bf16 v[20:23], v[202:205], v[184:187], v[20:23]
	v_mfma_f32_16x16x32_bf16 v[16:19], v[210:213], v[184:187], v[16:19]
	ds_read_b128 v[160:163], v149 offset:2048
	v_mfma_f32_16x16x32_bf16 v[4:7], v[202:205], v[192:195], v[4:7]
	v_mfma_f32_16x16x32_bf16 v[0:3], v[210:213], v[192:195], v[0:3]
	ds_read_b128 v[164:167], v149 offset:3072
	v_mfma_f32_16x16x32_bf16 v[52:55], v[206:209], v[172:175], v[52:55]
	v_mfma_f32_16x16x32_bf16 v[48:51], v[214:217], v[172:175], v[48:51]
	v_mfma_f32_16x16x32_bf16 v[36:39], v[206:209], v[180:183], v[36:39]
	v_mfma_f32_16x16x32_bf16 v[32:35], v[214:217], v[180:183], v[32:35]
	v_mfma_f32_16x16x32_bf16 v[20:23], v[206:209], v[188:191], v[20:23]
	v_mfma_f32_16x16x32_bf16 v[16:19], v[214:217], v[188:191], v[16:19]
	v_mfma_f32_16x16x32_bf16 v[4:7], v[206:209], v[198:201], v[4:7]
	v_mfma_f32_16x16x32_bf16 v[0:3], v[214:217], v[198:201], v[0:3]
	s_setprio 0
	s_add_i32 s3, s3, 2
	s_add_u32 s5, s5, 0x100
	s_addc_u32 s38, s38, 0
	s_cmpk_gt_u32 s3, 0x55
	s_mov_b64 s[8:9], s[10:11]
	s_barrier
	s_cbranch_scc0 .LBB1_1239
	s_waitcnt lgkmcnt(0)
	v_mov_b32_e32 v152, v147
	v_mov_b32_e32 v144, v146
	s_lshl_b32 s2, s2, 8
	s_add_i32 s2, s2, s29
	s_lshl_b32 s3, s4, 8
	v_add_u32_e32 v152, s2, v152
	s_or_b32 s3, s3, s54
	v_ashrrev_i32_e32 v153, 31, v152
	v_lshl_add_u32 v144, v144, 3, s3
	v_lshlrev_b64 v[152:153], 12, v[152:153]
	v_ashrrev_i32_e32 v145, 31, v144
	v_lshl_add_u64 v[152:153], s[46:47], 0, v[152:153]
	v_lshl_add_u64 v[144:145], v[144:145], 1, v[152:153]
	global_load_dwordx4 v[160:163], v[144:145], off
	global_load_dwordx4 v[164:167], v[144:145], off offset:256
	s_mov_b64 s[98:99], 0x10000
	v_lshl_add_u64 v[154:155], v[144:145], 0, s[98:99]
	global_load_dwordx4 v[168:171], v[154:155], off
	global_load_dwordx4 v[172:175], v[154:155], off offset:256
	s_mov_b64 s[98:99], 0x20000
	v_lshl_add_u64 v[154:155], v[144:145], 0, s[98:99]
	global_load_dwordx4 v[176:179], v[154:155], off
	global_load_dwordx4 v[180:183], v[154:155], off offset:256
	s_mov_b64 s[98:99], 0x30000
	v_lshl_add_u64 v[154:155], v[144:145], 0, s[98:99]
	global_load_dwordx4 v[184:187], v[154:155], off
	global_load_dwordx4 v[188:191], v[154:155], off offset:256
	s_mov_b64 s[98:99], 0x80000
	v_lshl_add_u64 v[154:155], v[144:145], 0, s[98:99]
	global_load_dwordx4 v[192:195], v[154:155], off
	global_load_dwordx4 v[198:201], v[154:155], off offset:256
	s_mov_b64 s[98:99], 0x90000
	v_lshl_add_u64 v[154:155], v[144:145], 0, s[98:99]
	global_load_dwordx4 v[202:205], v[154:155], off
	global_load_dwordx4 v[206:209], v[154:155], off offset:256
	s_mov_b64 s[98:99], 0xa0000
	v_lshl_add_u64 v[154:155], v[144:145], 0, s[98:99]
	global_load_dwordx4 v[210:213], v[154:155], off
	global_load_dwordx4 v[214:217], v[154:155], off offset:256
	s_mov_b64 s[98:99], 0xb0000
	v_lshl_add_u64 v[154:155], v[144:145], 0, s[98:99]
	global_load_dwordx4 v[248:251], v[154:155], off
	global_load_dwordx4 v[252:255], v[154:155], off offset:256
	s_waitcnt vmcnt(15)
	s_nop 1
	v_mov_b32_e32 v152, v160
	v_mov_b32_e32 v153, v161
	v_mov_b32_e32 v154, v162
	v_mov_b32_e32 v155, v163
	s_mov_b64 s[2:3], 0x10000
	s_mov_b32 s4, s37
	s_mov_b64 s[10:11], s[6:7]
	s_mov_b64 s[8:9], s[42:43]
	s_waitcnt lgkmcnt(0)
	v_lshlrev_b32_e32 v156, 16, v152
	v_and_b32_e32 v157, 0xffff0000, v152
	v_lshlrev_b32_e32 v152, 16, v153
	v_and_b32_e32 v153, 0xffff0000, v153
	v_lshlrev_b32_e32 v158, 16, v154
	v_and_b32_e32 v159, 0xffff0000, v154
	v_lshlrev_b32_e32 v154, 16, v155
	v_and_b32_e32 v155, 0xffff0000, v155
	v_pk_add_f32 v[126:127], v[126:127], v[152:153]
	v_pk_add_f32 v[124:125], v[124:125], v[156:157]
	v_pk_add_f32 v[152:153], v[122:123], v[154:155]
	v_pk_add_f32 v[122:123], v[120:121], v[158:159]
	v_cvt_pk_bf16_f32 v120, v124, v125
	v_cvt_pk_bf16_f32 v121, v126, v127
	v_cvt_pk_bf16_f32 v122, v122, v123
	v_cvt_pk_bf16_f32 v123, v152, v153
	global_store_dwordx4 v[144:145], v[120:123], off
	s_waitcnt vmcnt(15)
; DI unsigned pack2(float a, float b) { f32x2 v = {a, b}; hwbf16x2 r = __builtin_convertvector(v, hwbf16x2); return __builtin_bit_cast(unsigned, r); }
; DI float bflo(unsigned w) { return __uint_as_float(w << 16); }
; DI float bfhi(unsigned w) { return __uint_as_float(w & 0xffff0000u); }
;     DI void operator()(const f32x4 (&acc)[2][2][4][2], const Unit& u, int wr, int wc, int fr, int fq) const {
;     ...
;             for (int m = 0; m < 4; ++m) { const size_t ro = (size_t)(row0 + ai * HALF + m * 16) * D + col0;
; #pragma unroll
;                 for (int bj = 0; bj < 2; ++bj) {
;                     f32x4 x0, x1;
;                     if constexpr (IB) { const u32x4 w = *(const u32x4*)((const bf16_t*)Xin + ro + bj * HALF);
;                         x0 = (f32x4){bflo(w[0]), bfhi(w[0]), bflo(w[1]), bfhi(w[1])}; x1 = (f32x4){bflo(w[2]), bfhi(w[2]), bflo(w[3]), bfhi(w[3])}; }
;                     else { x0 = *(const f32x4*)((const float*)Xin + ro + bj * HALF); x1 = *(const f32x4*)((const float*)Xin + ro + bj * HALF + 4); }
;                     x0 += acc[ai][bj][m][0] * sc[bj][0]; x1 += acc[ai][bj][m][1] * sc[bj][1];
;                     if constexpr (OB) { u32x4 o; o[0] = pack2(x0[0], x0[1]); o[1] = pack2(x0[2], x0[3]); o[2] = pack2(x1[0], x1[1]); o[3] = pack2(x1[2], x1[3]);
;                         *(u32x4*)((bf16_t*)Xout + ro + bj * HALF) = o; }
;                     else { *(f32x4*)((float*)Xout + ro + bj * HALF) = x0; *(f32x4*)((float*)Xout + ro + bj * HALF + 4) = x1; } } }
	s_nop 1
	v_mov_b32_e32 v120, v164
	v_mov_b32_e32 v121, v165
	v_mov_b32_e32 v122, v166
	v_mov_b32_e32 v123, v167
	s_waitcnt lgkmcnt(0)
	v_lshlrev_b32_e32 v124, 16, v120
	v_and_b32_e32 v125, 0xffff0000, v120
	v_lshlrev_b32_e32 v120, 16, v121
	v_and_b32_e32 v121, 0xffff0000, v121
	v_lshlrev_b32_e32 v126, 16, v122
	v_and_b32_e32 v127, 0xffff0000, v122
	v_lshlrev_b32_e32 v122, 16, v123
	v_and_b32_e32 v123, 0xffff0000, v123
	v_pk_add_f32 v[116:117], v[116:117], v[124:125]
	v_pk_add_f32 v[118:119], v[118:119], v[120:121]
	v_pk_add_f32 v[120:121], v[114:115], v[122:123]
	v_pk_add_f32 v[114:115], v[112:113], v[126:127]
	v_cvt_pk_bf16_f32 v112, v116, v117
	v_lshl_add_u64 v[116:117], v[144:145], 0, s[2:3]
	s_mov_b32 s2, 0x10000
	v_cvt_pk_bf16_f32 v113, v118, v119
	v_add_co_u32_e32 v118, vcc, s2, v144
	v_cvt_pk_bf16_f32 v114, v114, v115
	v_cvt_pk_bf16_f32 v115, v120, v121
	v_addc_co_u32_e32 v119, vcc, 0, v145, vcc
	global_store_dwordx4 v[144:145], v[112:115], off offset:256
	s_waitcnt vmcnt(15)
	s_nop 1
	v_mov_b32_e32 v112, v168
	v_mov_b32_e32 v113, v169
	v_mov_b32_e32 v114, v170
	v_mov_b32_e32 v115, v171
	s_mov_b64 s[2:3], 0x20000
	s_waitcnt lgkmcnt(0)
	v_lshlrev_b32_e32 v120, 16, v112
	v_and_b32_e32 v121, 0xffff0000, v112
	v_lshlrev_b32_e32 v112, 16, v113
	v_and_b32_e32 v113, 0xffff0000, v113
	v_lshlrev_b32_e32 v122, 16, v114
	v_and_b32_e32 v123, 0xffff0000, v114
	v_lshlrev_b32_e32 v114, 16, v115
	v_and_b32_e32 v115, 0xffff0000, v115
	v_pk_add_f32 v[110:111], v[110:111], v[112:113]
	v_pk_add_f32 v[108:109], v[108:109], v[120:121]
	v_pk_add_f32 v[112:113], v[106:107], v[114:115]
	v_pk_add_f32 v[106:107], v[104:105], v[122:123]
	v_cvt_pk_bf16_f32 v104, v108, v109
	v_cvt_pk_bf16_f32 v105, v110, v111
	v_cvt_pk_bf16_f32 v106, v106, v107
	v_cvt_pk_bf16_f32 v107, v112, v113
	global_store_dwordx4 v[118:119], v[104:107], off
	s_waitcnt vmcnt(15)
	s_nop 1
	v_mov_b32_e32 v104, v172
	v_mov_b32_e32 v105, v173
	v_mov_b32_e32 v106, v174
	v_mov_b32_e32 v107, v175
	s_waitcnt lgkmcnt(0)
	v_lshlrev_b32_e32 v108, 16, v104
	v_and_b32_e32 v109, 0xffff0000, v104
	v_lshlrev_b32_e32 v104, 16, v105
	v_and_b32_e32 v105, 0xffff0000, v105
	v_lshlrev_b32_e32 v110, 16, v106
	v_and_b32_e32 v111, 0xffff0000, v106
	v_lshlrev_b32_e32 v106, 16, v107
	v_and_b32_e32 v107, 0xffff0000, v107
	v_pk_add_f32 v[100:101], v[100:101], v[108:109]
	v_pk_add_f32 v[102:103], v[102:103], v[104:105]
	v_pk_add_f32 v[104:105], v[98:99], v[106:107]
	v_pk_add_f32 v[98:99], v[96:97], v[110:111]
	v_cvt_pk_bf16_f32 v96, v100, v101
	v_lshl_add_u64 v[100:101], v[144:145], 0, s[2:3]
	s_mov_b32 s2, 0x20000
	v_cvt_pk_bf16_f32 v97, v102, v103
	v_add_co_u32_e32 v102, vcc, s2, v144
	v_cvt_pk_bf16_f32 v98, v98, v99
	v_cvt_pk_bf16_f32 v99, v104, v105
	v_addc_co_u32_e32 v103, vcc, 0, v145, vcc
	global_store_dwordx4 v[116:117], v[96:99], off offset:256
	s_waitcnt vmcnt(15)
	s_nop 1
	v_mov_b32_e32 v96, v176
	v_mov_b32_e32 v97, v177
	v_mov_b32_e32 v98, v178
	v_mov_b32_e32 v99, v179
	s_mov_b64 s[2:3], 0x30000
	s_waitcnt lgkmcnt(0)
	v_lshlrev_b32_e32 v104, 16, v96
	v_and_b32_e32 v105, 0xffff0000, v96
	v_lshlrev_b32_e32 v96, 16, v97
	v_and_b32_e32 v97, 0xffff0000, v97
	v_lshlrev_b32_e32 v106, 16, v98
	v_and_b32_e32 v107, 0xffff0000, v98
	v_lshlrev_b32_e32 v98, 16, v99
	v_and_b32_e32 v99, 0xffff0000, v99
	v_pk_add_f32 v[94:95], v[94:95], v[96:97]
	v_pk_add_f32 v[92:93], v[92:93], v[104:105]
	v_pk_add_f32 v[96:97], v[90:91], v[98:99]
	v_pk_add_f32 v[90:91], v[88:89], v[106:107]
	v_cvt_pk_bf16_f32 v88, v92, v93
	v_cvt_pk_bf16_f32 v89, v94, v95
	v_cvt_pk_bf16_f32 v90, v90, v91
	v_cvt_pk_bf16_f32 v91, v96, v97
	global_store_dwordx4 v[102:103], v[88:91], off
	s_waitcnt vmcnt(15)
	s_nop 1
	v_mov_b32_e32 v88, v180
	v_mov_b32_e32 v89, v181
	v_mov_b32_e32 v90, v182
	v_mov_b32_e32 v91, v183
	s_waitcnt lgkmcnt(0)
	v_lshlrev_b32_e32 v92, 16, v88
	v_and_b32_e32 v93, 0xffff0000, v88
	v_lshlrev_b32_e32 v88, 16, v89
	v_and_b32_e32 v89, 0xffff0000, v89
	v_lshlrev_b32_e32 v94, 16, v90
	v_and_b32_e32 v95, 0xffff0000, v90
	v_lshlrev_b32_e32 v90, 16, v91
	v_and_b32_e32 v91, 0xffff0000, v91
	v_pk_add_f32 v[86:87], v[86:87], v[88:89]
	v_pk_add_f32 v[84:85], v[84:85], v[92:93]
	v_pk_add_f32 v[88:89], v[82:83], v[90:91]
	v_pk_add_f32 v[82:83], v[80:81], v[94:95]
	v_cvt_pk_bf16_f32 v80, v84, v85
	v_cvt_pk_bf16_f32 v81, v86, v87
	v_cvt_pk_bf16_f32 v82, v82, v83
	v_cvt_pk_bf16_f32 v83, v88, v89
	global_store_dwordx4 v[100:101], v[80:83], off offset:256
	s_nop 1
	v_lshl_add_u64 v[80:81], v[144:145], 0, s[2:3]
	s_mov_b32 s2, 0x30000
	v_add_co_u32_e32 v86, vcc, s2, v144
	s_mov_b64 s[2:3], 0x80000
	s_nop 0
	v_addc_co_u32_e32 v87, vcc, 0, v145, vcc
	s_waitcnt vmcnt(15)
	s_nop 1
	v_mov_b32_e32 v82, v184
	v_mov_b32_e32 v83, v185
	v_mov_b32_e32 v84, v186
	v_mov_b32_e32 v85, v187
	s_waitcnt lgkmcnt(0)
	v_lshlrev_b32_e32 v88, 16, v82
	v_and_b32_e32 v89, 0xffff0000, v82
	v_lshlrev_b32_e32 v82, 16, v83
	v_and_b32_e32 v83, 0xffff0000, v83
	v_lshlrev_b32_e32 v90, 16, v84
	v_and_b32_e32 v91, 0xffff0000, v84
	v_lshlrev_b32_e32 v84, 16, v85
	v_and_b32_e32 v85, 0xffff0000, v85
	v_pk_add_f32 v[78:79], v[78:79], v[82:83]
	v_pk_add_f32 v[76:77], v[76:77], v[88:89]
	v_pk_add_f32 v[82:83], v[74:75], v[84:85]
	v_pk_add_f32 v[74:75], v[72:73], v[90:91]
	v_cvt_pk_bf16_f32 v72, v76, v77
	v_cvt_pk_bf16_f32 v73, v78, v79
	v_cvt_pk_bf16_f32 v74, v74, v75
	v_cvt_pk_bf16_f32 v75, v82, v83
	global_store_dwordx4 v[86:87], v[72:75], off
	s_waitcnt vmcnt(15)
	s_nop 1
	v_mov_b32_e32 v72, v188
	v_mov_b32_e32 v73, v189
	v_mov_b32_e32 v74, v190
	v_mov_b32_e32 v75, v191
	s_waitcnt lgkmcnt(0)
; DI unsigned pack2(float a, float b) { f32x2 v = {a, b}; hwbf16x2 r = __builtin_convertvector(v, hwbf16x2); return __builtin_bit_cast(unsigned, r); }
; DI float bflo(unsigned w) { return __uint_as_float(w << 16); }
; DI float bfhi(unsigned w) { return __uint_as_float(w & 0xffff0000u); }
;     DI void operator()(const f32x4 (&acc)[2][2][4][2], const Unit& u, int wr, int wc, int fr, int fq) const {
;     ...
;             for (int m = 0; m < 4; ++m) { const size_t ro = (size_t)(row0 + ai * HALF + m * 16) * D + col0;
; #pragma unroll
;                 for (int bj = 0; bj < 2; ++bj) {
;                     f32x4 x0, x1;
;                     if constexpr (IB) { const u32x4 w = *(const u32x4*)((const bf16_t*)Xin + ro + bj * HALF);
;                         x0 = (f32x4){bflo(w[0]), bfhi(w[0]), bflo(w[1]), bfhi(w[1])}; x1 = (f32x4){bflo(w[2]), bfhi(w[2]), bflo(w[3]), bfhi(w[3])}; }
;                     else { x0 = *(const f32x4*)((const float*)Xin + ro + bj * HALF); x1 = *(const f32x4*)((const float*)Xin + ro + bj * HALF + 4); }
;                     x0 += acc[ai][bj][m][0] * sc[bj][0]; x1 += acc[ai][bj][m][1] * sc[bj][1];
;                     if constexpr (OB) { u32x4 o; o[0] = pack2(x0[0], x0[1]); o[1] = pack2(x0[2], x0[3]); o[2] = pack2(x1[0], x1[1]); o[3] = pack2(x1[2], x1[3]);
;                         *(u32x4*)((bf16_t*)Xout + ro + bj * HALF) = o; }
;                     else { *(f32x4*)((float*)Xout + ro + bj * HALF) = x0; *(f32x4*)((float*)Xout + ro + bj * HALF + 4) = x1; } } }
	v_lshlrev_b32_e32 v76, 16, v72
	v_and_b32_e32 v77, 0xffff0000, v72
	v_lshlrev_b32_e32 v72, 16, v73
	v_and_b32_e32 v73, 0xffff0000, v73
	v_lshlrev_b32_e32 v78, 16, v74
	v_and_b32_e32 v79, 0xffff0000, v74
	v_lshlrev_b32_e32 v74, 16, v75
	v_and_b32_e32 v75, 0xffff0000, v75
	v_pk_add_f32 v[70:71], v[70:71], v[72:73]
	v_pk_add_f32 v[68:69], v[68:69], v[76:77]
	v_pk_add_f32 v[72:73], v[66:67], v[74:75]
	v_pk_add_f32 v[66:67], v[64:65], v[78:79]
	v_cvt_pk_bf16_f32 v64, v68, v69
	v_cvt_pk_bf16_f32 v65, v70, v71
	v_cvt_pk_bf16_f32 v66, v66, v67
	v_cvt_pk_bf16_f32 v67, v72, v73
	global_store_dwordx4 v[80:81], v[64:67], off offset:256
	s_nop 1
	v_lshl_add_u64 v[64:65], v[144:145], 0, s[2:3]
	s_mov_b32 s2, 0x80000
	v_add_co_u32_e32 v70, vcc, s2, v144
	s_mov_b64 s[2:3], 0x90000
	s_nop 0
	v_addc_co_u32_e32 v71, vcc, 0, v145, vcc
	s_waitcnt vmcnt(15)
	s_nop 1
	v_mov_b32_e32 v66, v192
	v_mov_b32_e32 v67, v193
	v_mov_b32_e32 v68, v194
	v_mov_b32_e32 v69, v195
	s_waitcnt lgkmcnt(0)
	v_lshlrev_b32_e32 v72, 16, v66
	v_and_b32_e32 v73, 0xffff0000, v66
	v_lshlrev_b32_e32 v66, 16, v67
	v_and_b32_e32 v67, 0xffff0000, v67
	v_lshlrev_b32_e32 v74, 16, v68
	v_and_b32_e32 v75, 0xffff0000, v68
	v_lshlrev_b32_e32 v68, 16, v69
	v_and_b32_e32 v69, 0xffff0000, v69
	v_pk_add_f32 v[62:63], v[62:63], v[66:67]
	v_pk_add_f32 v[60:61], v[60:61], v[72:73]
	v_pk_add_f32 v[66:67], v[58:59], v[68:69]
	v_pk_add_f32 v[58:59], v[56:57], v[74:75]
	v_cvt_pk_bf16_f32 v56, v60, v61
	v_cvt_pk_bf16_f32 v57, v62, v63
	v_cvt_pk_bf16_f32 v58, v58, v59
	v_cvt_pk_bf16_f32 v59, v66, v67
	global_store_dwordx4 v[70:71], v[56:59], off
	s_waitcnt vmcnt(15)
	s_nop 1
	v_mov_b32_e32 v56, v198
	v_mov_b32_e32 v57, v199
	v_mov_b32_e32 v58, v200
	v_mov_b32_e32 v59, v201
	s_waitcnt lgkmcnt(0)
	v_lshlrev_b32_e32 v60, 16, v56
	v_and_b32_e32 v61, 0xffff0000, v56
	v_lshlrev_b32_e32 v56, 16, v57
	v_and_b32_e32 v57, 0xffff0000, v57
	v_lshlrev_b32_e32 v62, 16, v58
	v_and_b32_e32 v63, 0xffff0000, v58
	v_lshlrev_b32_e32 v58, 16, v59
	v_and_b32_e32 v59, 0xffff0000, v59
	v_pk_add_f32 v[54:55], v[54:55], v[56:57]
	v_pk_add_f32 v[52:53], v[52:53], v[60:61]
	v_pk_add_f32 v[56:57], v[50:51], v[58:59]
	v_pk_add_f32 v[50:51], v[48:49], v[62:63]
	v_cvt_pk_bf16_f32 v48, v52, v53
	v_cvt_pk_bf16_f32 v49, v54, v55
	v_cvt_pk_bf16_f32 v50, v50, v51
	v_cvt_pk_bf16_f32 v51, v56, v57
	global_store_dwordx4 v[64:65], v[48:51], off offset:256
	s_nop 1
	v_lshl_add_u64 v[48:49], v[144:145], 0, s[2:3]
	s_mov_b32 s2, 0x90000
	v_add_co_u32_e32 v54, vcc, s2, v144
	s_mov_b64 s[2:3], 0xa0000
	s_nop 0
	v_addc_co_u32_e32 v55, vcc, 0, v145, vcc
	s_waitcnt vmcnt(15)
	s_nop 1
	v_mov_b32_e32 v50, v202
	v_mov_b32_e32 v51, v203
	v_mov_b32_e32 v52, v204
	v_mov_b32_e32 v53, v205
	s_waitcnt lgkmcnt(0)
	v_lshlrev_b32_e32 v56, 16, v50
	v_and_b32_e32 v57, 0xffff0000, v50
	v_lshlrev_b32_e32 v50, 16, v51
	v_and_b32_e32 v51, 0xffff0000, v51
	v_lshlrev_b32_e32 v58, 16, v52
	v_and_b32_e32 v59, 0xffff0000, v52
	v_lshlrev_b32_e32 v52, 16, v53
	v_and_b32_e32 v53, 0xffff0000, v53
	v_pk_add_f32 v[46:47], v[46:47], v[50:51]
	v_pk_add_f32 v[44:45], v[44:45], v[56:57]
	v_pk_add_f32 v[50:51], v[42:43], v[52:53]
	v_pk_add_f32 v[42:43], v[40:41], v[58:59]
	v_cvt_pk_bf16_f32 v40, v44, v45
	v_cvt_pk_bf16_f32 v41, v46, v47
	v_cvt_pk_bf16_f32 v42, v42, v43
	v_cvt_pk_bf16_f32 v43, v50, v51
	global_store_dwordx4 v[54:55], v[40:43], off
	s_waitcnt vmcnt(15)
	s_nop 1
	v_mov_b32_e32 v40, v206
	v_mov_b32_e32 v41, v207
	v_mov_b32_e32 v42, v208
	v_mov_b32_e32 v43, v209
	s_waitcnt lgkmcnt(0)
; DI unsigned pack2(float a, float b) { f32x2 v = {a, b}; hwbf16x2 r = __builtin_convertvector(v, hwbf16x2); return __builtin_bit_cast(unsigned, r); }
; DI float bflo(unsigned w) { return __uint_as_float(w << 16); }
; DI float bfhi(unsigned w) { return __uint_as_float(w & 0xffff0000u); }
; #define PG8_WAIT_V(n) asm volatile("s_waitcnt vmcnt(" #n ")" ::: "memory")
; #define PG8_BAR __builtin_amdgcn_s_barrier()
;     DI void operator()(const f32x4 (&acc)[2][2][4][2], const Unit& u, int wr, int wc, int fr, int fq) const {
;     ...
;             for (int m = 0; m < 4; ++m) { const size_t ro = (size_t)(row0 + ai * HALF + m * 16) * D + col0;
; #pragma unroll
;                 for (int bj = 0; bj < 2; ++bj) {
;                     f32x4 x0, x1;
;                     if constexpr (IB) { const u32x4 w = *(const u32x4*)((const bf16_t*)Xin + ro + bj * HALF);
;                         x0 = (f32x4){bflo(w[0]), bfhi(w[0]), bflo(w[1]), bfhi(w[1])}; x1 = (f32x4){bflo(w[2]), bfhi(w[2]), bflo(w[3]), bfhi(w[3])}; }
;                     else { x0 = *(const f32x4*)((const float*)Xin + ro + bj * HALF); x1 = *(const f32x4*)((const float*)Xin + ro + bj * HALF + 4); }
;                     x0 += acc[ai][bj][m][0] * sc[bj][0]; x1 += acc[ai][bj][m][1] * sc[bj][1];
;                     if constexpr (OB) { u32x4 o; o[0] = pack2(x0[0], x0[1]); o[1] = pack2(x0[2], x0[3]); o[2] = pack2(x1[0], x1[1]); o[3] = pack2(x1[2], x1[3]);
;                         *(u32x4*)((bf16_t*)Xout + ro + bj * HALF) = o; }
;                     else { *(f32x4*)((float*)Xout + ro + bj * HALF) = x0; *(f32x4*)((float*)Xout + ro + bj * HALF + 4) = x1; } } }
; template <class Map, class Epi>
; DI void gemm_phase(LAS unsigned char* lds, const Map& MP, const Epi& E, const int nM, const int nN, const int K, const int lda, const int ldb) {
;     ...
;     PG8_WAIT_V(0);
;     if (wr == 0) PG8_BAR;
;     PG8_BAR;
	v_lshlrev_b32_e32 v44, 16, v40
	v_and_b32_e32 v45, 0xffff0000, v40
	v_lshlrev_b32_e32 v40, 16, v41
	v_and_b32_e32 v41, 0xffff0000, v41
	v_lshlrev_b32_e32 v46, 16, v42
	v_and_b32_e32 v47, 0xffff0000, v42
	v_lshlrev_b32_e32 v42, 16, v43
	v_and_b32_e32 v43, 0xffff0000, v43
	v_pk_add_f32 v[38:39], v[38:39], v[40:41]
	v_pk_add_f32 v[36:37], v[36:37], v[44:45]
	v_pk_add_f32 v[40:41], v[34:35], v[42:43]
	v_pk_add_f32 v[34:35], v[32:33], v[46:47]
	v_cvt_pk_bf16_f32 v32, v36, v37
	v_cvt_pk_bf16_f32 v33, v38, v39
	v_cvt_pk_bf16_f32 v34, v34, v35
	v_cvt_pk_bf16_f32 v35, v40, v41
	global_store_dwordx4 v[48:49], v[32:35], off offset:256
	s_nop 1
	v_lshl_add_u64 v[32:33], v[144:145], 0, s[2:3]
	s_mov_b32 s2, 0xa0000
	v_add_co_u32_e32 v38, vcc, s2, v144
	s_mov_b64 s[2:3], 0xb0000
	s_nop 0
	v_addc_co_u32_e32 v39, vcc, 0, v145, vcc
	s_waitcnt vmcnt(15)
	s_nop 1
	v_mov_b32_e32 v34, v210
	v_mov_b32_e32 v35, v211
	v_mov_b32_e32 v36, v212
	v_mov_b32_e32 v37, v213
	s_waitcnt lgkmcnt(0)
	v_lshlrev_b32_e32 v40, 16, v34
	v_and_b32_e32 v41, 0xffff0000, v34
	v_lshlrev_b32_e32 v34, 16, v35
	v_and_b32_e32 v35, 0xffff0000, v35
	v_lshlrev_b32_e32 v42, 16, v36
	v_and_b32_e32 v43, 0xffff0000, v36
	v_lshlrev_b32_e32 v36, 16, v37
	v_and_b32_e32 v37, 0xffff0000, v37
	v_pk_add_f32 v[30:31], v[30:31], v[34:35]
	v_pk_add_f32 v[28:29], v[28:29], v[40:41]
	v_pk_add_f32 v[34:35], v[26:27], v[36:37]
	v_pk_add_f32 v[26:27], v[24:25], v[42:43]
	v_cvt_pk_bf16_f32 v24, v28, v29
	v_cvt_pk_bf16_f32 v25, v30, v31
	v_cvt_pk_bf16_f32 v26, v26, v27
	v_cvt_pk_bf16_f32 v27, v34, v35
	global_store_dwordx4 v[38:39], v[24:27], off
	s_waitcnt vmcnt(15)
	s_nop 1
	v_mov_b32_e32 v24, v214
	v_mov_b32_e32 v25, v215
	v_mov_b32_e32 v26, v216
	v_mov_b32_e32 v27, v217
	s_waitcnt lgkmcnt(0)
	v_lshlrev_b32_e32 v28, 16, v24
	v_and_b32_e32 v29, 0xffff0000, v24
	v_lshlrev_b32_e32 v24, 16, v25
	v_and_b32_e32 v25, 0xffff0000, v25
	v_lshlrev_b32_e32 v30, 16, v26
	v_and_b32_e32 v31, 0xffff0000, v26
	v_lshlrev_b32_e32 v26, 16, v27
	v_and_b32_e32 v27, 0xffff0000, v27
	v_pk_add_f32 v[22:23], v[22:23], v[24:25]
	v_pk_add_f32 v[20:21], v[20:21], v[28:29]
	v_pk_add_f32 v[24:25], v[18:19], v[26:27]
	v_pk_add_f32 v[18:19], v[16:17], v[30:31]
	v_cvt_pk_bf16_f32 v16, v20, v21
	v_cvt_pk_bf16_f32 v17, v22, v23
	v_cvt_pk_bf16_f32 v18, v18, v19
	v_cvt_pk_bf16_f32 v19, v24, v25
	global_store_dwordx4 v[32:33], v[16:19], off offset:256
	s_nop 1
	v_lshl_add_u64 v[16:17], v[144:145], 0, s[2:3]
	s_mov_b32 s2, 0xb0000
	v_add_co_u32_e32 v22, vcc, s2, v144
	s_mov_b32 s2, s55
	s_nop 0
	v_addc_co_u32_e32 v23, vcc, 0, v145, vcc
	s_waitcnt vmcnt(15)
	s_nop 1
	v_mov_b32_e32 v18, v248
	v_mov_b32_e32 v19, v249
	v_mov_b32_e32 v20, v250
	v_mov_b32_e32 v21, v251
	s_and_b64 vcc, exec, s[40:41]
	s_waitcnt lgkmcnt(0)
	v_lshlrev_b32_e32 v24, 16, v18
	v_and_b32_e32 v25, 0xffff0000, v18
	v_lshlrev_b32_e32 v18, 16, v19
	v_and_b32_e32 v19, 0xffff0000, v19
	v_lshlrev_b32_e32 v26, 16, v20
	v_and_b32_e32 v27, 0xffff0000, v20
	v_lshlrev_b32_e32 v20, 16, v21
	v_and_b32_e32 v21, 0xffff0000, v21
	v_pk_add_f32 v[14:15], v[14:15], v[18:19]
	v_pk_add_f32 v[12:13], v[12:13], v[24:25]
	v_pk_add_f32 v[18:19], v[10:11], v[20:21]
	v_pk_add_f32 v[10:11], v[8:9], v[26:27]
	v_cvt_pk_bf16_f32 v8, v12, v13
	v_cvt_pk_bf16_f32 v9, v14, v15
	v_cvt_pk_bf16_f32 v10, v10, v11
	v_cvt_pk_bf16_f32 v11, v18, v19
	global_store_dwordx4 v[22:23], v[8:11], off
	s_waitcnt vmcnt(15)
	s_nop 1
	v_mov_b32_e32 v8, v252
	v_mov_b32_e32 v9, v253
	v_mov_b32_e32 v10, v254
	v_mov_b32_e32 v11, v255
	s_waitcnt lgkmcnt(0)
	v_lshlrev_b32_e32 v12, 16, v8
	v_and_b32_e32 v13, 0xffff0000, v8
	v_lshlrev_b32_e32 v8, 16, v9
	v_and_b32_e32 v9, 0xffff0000, v9
	v_lshlrev_b32_e32 v14, 16, v10
	v_and_b32_e32 v15, 0xffff0000, v10
	v_lshlrev_b32_e32 v10, 16, v11
	v_and_b32_e32 v11, 0xffff0000, v11
	v_pk_add_f32 v[6:7], v[6:7], v[8:9]
	v_pk_add_f32 v[4:5], v[4:5], v[12:13]
	v_pk_add_f32 v[8:9], v[2:3], v[10:11]
	v_pk_add_f32 v[2:3], v[0:1], v[14:15]
	v_cvt_pk_bf16_f32 v0, v4, v5
	v_cvt_pk_bf16_f32 v1, v6, v7
	v_cvt_pk_bf16_f32 v2, v2, v3
	v_cvt_pk_bf16_f32 v3, v8, v9
	global_store_dwordx4 v[16:17], v[0:3], off offset:256
	s_cbranch_vccz .LBB1_1232
	s_waitcnt vmcnt(0)
	s_cmpk_gt_u32 s17, 0xff
	s_cbranch_scc1 .LBB1_1243
	s_barrier

;     DI const char* a(const Unit& u) const { return (const char*)(A + (size_t)u.pm * BM * lda); }
;     DI const char* a(const Unit& u) const { return (const char*)(A + (size_t)u.pm * BM * 2048 + (u.pn >> 1) * 512); }
;     DI const char* a(const Unit& u) const { return (const char*)((u.pn < 12 ? A1 : A2) + (size_t)u.pm * BM * 512); }
; #define PG8_STAGE(bufoff, gbase, voff) do { _Pragma("unroll") for (int _i = 0; _i < 2; ++_i) \
;         __builtin_amdgcn_global_load_lds((const unsigned*)((const char*)(gbase) + (voff)[_i]), (LAS unsigned*)(lds + (bufoff) + ldsw + _i * 8192), 16, 0, 0); } while (0)
; #define PG8_LDA(dst, b, h) do { _Pragma("unroll") for (int m = 0; m < 4; ++m) _Pragma("unroll") for (int k = 0; k < 2; ++k) dst[m][k] = *(const LAS bf16x8*)(lds + PG8_SA(b, h) + aoff + m * 2048 + k * 1024); } while (0)
; #define PG8_LDB(dst, b, h) do { _Pragma("unroll") for (int n = 0; n < 2; ++n) _Pragma("unroll") for (int k = 0; k < 2; ++k) dst[n][k] = *(const LAS bf16x8*)(lds + PG8_SB(b, h) + boff + n * 2048 + k * 1024); } while (0)
; #define PG8_WAIT_L(n) asm volatile("s_waitcnt lgkmcnt(" #n ")" ::: "memory")
; template <class Map, class Epi>
; DI void gemm_phase(LAS unsigned char* lds, const Map& MP, const Epi& E, const int nM, const int nN, const int K, const int lda, const int ldb) {
;     ...
;         const bool has_next = sched_next(ui + 1, nM, nN, G, cblk, nxt);
;         const char* nA = has_next ? MP.a(nxt) : cA; const char* nB = has_next ? MP.b(nxt) : cB;
;         for (int t = 0; t < nt; t += 2) {
;             const bool last = (t == nt - 2);
;             const char* a1 = cA + (size_t)(t + 1) * kstep;
;             const char* a2 = last ? nA : cA + (size_t)(t + 2) * kstep; const char* b2 = last ? nB : cB + (size_t)(t + 2) * kstep;
;             const char* a3 = a2 + kstep; const char* b3 = b2 + kstep;
;             PG8_LDB(B0, 0, 0); PG8_SCHED; PG8_LDA(At, 0, 0); PG8_STAGE(PG8_SA(1, 1), a1 + hstepA, voffA);
;             PG8_WAIT_L(8); PG8_BAR; PG8_WAIT_L(0); PG8_MMA(0, 0, At, B0); PG8_BAR; PG8_SCHED;
;     ...
; #pragma unroll
;         for (int a = 0; a < 2; ++a)
; #pragma unroll
;             for (int b = 0; b < 2; ++b)
; #pragma unroll
;                 for (int m = 0; m < 4; ++m)
; #pragma unroll
;                     for (int n = 0; n < 2; ++n) acc[a][b][m][n] = (f32x4){0.f, 0.f, 0.f, 0.f};
;         cur = nxt; cA = nA; cB = nB; ++ui;
.LBB1_1381:
	s_ashr_i32 s15, s14, 31
	v_cmp_lt_i64_e32 vcc, s[16:17], v[140:141]
	s_lshl_b64 s[16:17], s[14:15], 20
	s_add_u32 s16, s5, s16
	s_addc_u32 s17, s26, s17
	s_and_b64 s[18:19], vcc, exec
	s_cselect_b32 s15, s17, s23
	s_cselect_b32 s48, s16, s22
	s_ashr_i32 s13, s12, 31
	s_lshl_b64 s[18:19], s[12:13], 20
	s_add_u32 s18, s27, s18
	s_addc_u32 s19, s28, s19
	s_and_b64 s[24:25], vcc, exec
	s_cselect_b32 s13, s19, s21
	s_cselect_b32 s49, s18, s20
	s_add_u32 s52, s20, 0x100
	s_addc_u32 s53, s21, 0
	s_add_u32 s20, s22, 0x80080
	v_mov_b32_e32 v0, 0
	s_addc_u32 s21, s23, 0
	s_mov_b32 s3, -2
	v_mov_b32_e32 v1, v0
	v_mov_b32_e32 v2, v0
	v_mov_b32_e32 v3, v0
	v_mov_b32_e32 v4, v0
	v_mov_b32_e32 v5, v0
	v_mov_b32_e32 v6, v0
	v_mov_b32_e32 v7, v0
	v_mov_b32_e32 v8, v0
	v_mov_b32_e32 v9, v0
	v_mov_b32_e32 v10, v0
	v_mov_b32_e32 v11, v0
	v_mov_b32_e32 v12, v0
	v_mov_b32_e32 v13, v0
	v_mov_b32_e32 v14, v0
	v_mov_b32_e32 v15, v0
	v_mov_b32_e32 v24, v0
	v_mov_b32_e32 v25, v0
	v_mov_b32_e32 v26, v0
	v_mov_b32_e32 v27, v0
	v_mov_b32_e32 v28, v0
	v_mov_b32_e32 v29, v0
	v_mov_b32_e32 v30, v0
	v_mov_b32_e32 v31, v0
	v_mov_b32_e32 v40, v0
	v_mov_b32_e32 v41, v0
	v_mov_b32_e32 v42, v0
	v_mov_b32_e32 v43, v0
	v_mov_b32_e32 v44, v0
	v_mov_b32_e32 v45, v0
	v_mov_b32_e32 v46, v0
	v_mov_b32_e32 v47, v0
	v_mov_b32_e32 v16, v0
	v_mov_b32_e32 v17, v0
	v_mov_b32_e32 v18, v0
	v_mov_b32_e32 v19, v0
	v_mov_b32_e32 v20, v0
	v_mov_b32_e32 v21, v0
	v_mov_b32_e32 v22, v0
	v_mov_b32_e32 v23, v0
	v_mov_b32_e32 v32, v0
	v_mov_b32_e32 v33, v0
	v_mov_b32_e32 v34, v0
	v_mov_b32_e32 v35, v0
	v_mov_b32_e32 v36, v0
	v_mov_b32_e32 v37, v0
	v_mov_b32_e32 v38, v0
	v_mov_b32_e32 v39, v0
	v_mov_b32_e32 v48, v0
	v_mov_b32_e32 v49, v0
	v_mov_b32_e32 v50, v0
	v_mov_b32_e32 v51, v0
	v_mov_b32_e32 v52, v0
	v_mov_b32_e32 v53, v0
	v_mov_b32_e32 v54, v0
	v_mov_b32_e32 v55, v0
	v_mov_b32_e32 v56, v0
	v_mov_b32_e32 v57, v0
	v_mov_b32_e32 v58, v0
	v_mov_b32_e32 v59, v0
	v_mov_b32_e32 v60, v0
	v_mov_b32_e32 v61, v0
	v_mov_b32_e32 v62, v0
	v_mov_b32_e32 v63, v0
	v_mov_b32_e32 v64, v0
	v_mov_b32_e32 v65, v0
	v_mov_b32_e32 v66, v0
	v_mov_b32_e32 v67, v0
	v_mov_b32_e32 v68, v0
	v_mov_b32_e32 v69, v0
	v_mov_b32_e32 v70, v0
	v_mov_b32_e32 v71, v0
	v_mov_b32_e32 v72, v0
	v_mov_b32_e32 v73, v0
	v_mov_b32_e32 v74, v0
	v_mov_b32_e32 v75, v0
	v_mov_b32_e32 v76, v0
	v_mov_b32_e32 v77, v0
	v_mov_b32_e32 v78, v0
	v_mov_b32_e32 v79, v0
	v_mov_b32_e32 v88, v0
	v_mov_b32_e32 v89, v0
	v_mov_b32_e32 v90, v0
	v_mov_b32_e32 v91, v0
	v_mov_b32_e32 v92, v0
	v_mov_b32_e32 v93, v0
	v_mov_b32_e32 v94, v0
	v_mov_b32_e32 v95, v0
	v_mov_b32_e32 v104, v0
	v_mov_b32_e32 v105, v0
	v_mov_b32_e32 v106, v0
	v_mov_b32_e32 v107, v0
	v_mov_b32_e32 v108, v0
	v_mov_b32_e32 v109, v0
	v_mov_b32_e32 v110, v0
	v_mov_b32_e32 v111, v0
	v_mov_b32_e32 v80, v0
	v_mov_b32_e32 v81, v0
	v_mov_b32_e32 v82, v0
	v_mov_b32_e32 v83, v0
	v_mov_b32_e32 v84, v0
	v_mov_b32_e32 v85, v0
	v_mov_b32_e32 v86, v0
	v_mov_b32_e32 v87, v0
	v_mov_b32_e32 v96, v0
	v_mov_b32_e32 v97, v0
	v_mov_b32_e32 v98, v0
	v_mov_b32_e32 v99, v0
	v_mov_b32_e32 v100, v0
	v_mov_b32_e32 v101, v0
	v_mov_b32_e32 v102, v0
	v_mov_b32_e32 v103, v0
	v_mov_b32_e32 v112, v0
	v_mov_b32_e32 v113, v0
	v_mov_b32_e32 v114, v0
	v_mov_b32_e32 v115, v0
	v_mov_b32_e32 v116, v0
	v_mov_b32_e32 v117, v0
	v_mov_b32_e32 v118, v0
	v_mov_b32_e32 v119, v0
	v_mov_b32_e32 v120, v0
	v_mov_b32_e32 v121, v0
	v_mov_b32_e32 v122, v0
	v_mov_b32_e32 v123, v0
	v_mov_b32_e32 v124, v0
	v_mov_b32_e32 v125, v0
	v_mov_b32_e32 v126, v0
	v_mov_b32_e32 v127, v0
	ds_read_b128 v[150:153], v147
	ds_read_b128 v[154:157], v147 offset:1024
	ds_read_b128 v[158:161], v147 offset:2048
	ds_read_b128 v[162:165], v147 offset:3072
.LBB1_1382:
	s_add_u32 s22, s20, 0xfff80080
	s_addc_u32 s23, s21, -1
	s_cmp_eq_u32 s3, 28
	s_cselect_b32 s25, s15, s23
	s_cselect_b32 s24, s48, s22
	s_cselect_b32 s23, s13, s53
	s_cselect_b32 s22, s49, s52
	s_add_i32 m0, s31, 0xc000
	ds_read_b128 v[166:169], v148
	ds_read_b128 v[170:173], v148 offset:1024
	ds_read_b128 v[174:177], v148 offset:2048
	ds_read_b128 v[178:181], v148 offset:3072
	ds_read_b128 v[182:185], v148 offset:4096
	ds_read_b128 v[186:189], v148 offset:5120
	ds_read_b128 v[190:193], v148 offset:6144
	ds_read_b128 v[198:201], v148 offset:7168
	global_load_lds_dwordx4 v138, s[20:21]
	s_add_i32 m0, s31, 0xe000
	s_nop 0
	global_load_lds_dwordx4 v136, s[20:21]
	s_waitcnt lgkmcnt(8)
	s_barrier
	s_setprio 1
	s_waitcnt lgkmcnt(7)
	v_mfma_f32_16x16x32_bf16 v[124:127], v[150:153], v[166:169], v[124:127]
	v_mfma_f32_16x16x32_bf16 v[120:123], v[158:161], v[166:169], v[120:123]
	s_waitcnt lgkmcnt(5)
	v_mfma_f32_16x16x32_bf16 v[116:119], v[150:153], v[174:177], v[116:119]
	v_mfma_f32_16x16x32_bf16 v[112:115], v[158:161], v[174:177], v[112:115]
	s_waitcnt lgkmcnt(3)
	v_mfma_f32_16x16x32_bf16 v[100:103], v[150:153], v[182:185], v[100:103]
	v_mfma_f32_16x16x32_bf16 v[96:99], v[158:161], v[182:185], v[96:99]
	s_waitcnt lgkmcnt(1)
	v_mfma_f32_16x16x32_bf16 v[84:87], v[150:153], v[190:193], v[84:87]
	v_mfma_f32_16x16x32_bf16 v[80:83], v[158:161], v[190:193], v[80:83]
	v_mfma_f32_16x16x32_bf16 v[124:127], v[154:157], v[170:173], v[124:127]
	v_mfma_f32_16x16x32_bf16 v[120:123], v[162:165], v[170:173], v[120:123]
	v_mfma_f32_16x16x32_bf16 v[116:119], v[154:157], v[178:181], v[116:119]
	v_mfma_f32_16x16x32_bf16 v[112:115], v[162:165], v[178:181], v[112:115]
	v_mfma_f32_16x16x32_bf16 v[100:103], v[154:157], v[186:189], v[100:103]
	v_mfma_f32_16x16x32_bf16 v[96:99], v[162:165], v[186:189], v[96:99]
	s_waitcnt lgkmcnt(0)
	v_mfma_f32_16x16x32_bf16 v[84:87], v[154:157], v[198:201], v[84:87]
	v_mfma_f32_16x16x32_bf16 v[80:83], v[162:165], v[198:201], v[80:83]
	s_setprio 0
	s_barrier
; #define PG8_STAGE(bufoff, gbase, voff) do { _Pragma("unroll") for (int _i = 0; _i < 2; ++_i) \
;         __builtin_amdgcn_global_load_lds((const unsigned*)((const char*)(gbase) + (voff)[_i]), (LAS unsigned*)(lds + (bufoff) + ldsw + _i * 8192), 16, 0, 0); } while (0)
; #define PG8_LDA(dst, b, h) do { _Pragma("unroll") for (int m = 0; m < 4; ++m) _Pragma("unroll") for (int k = 0; k < 2; ++k) dst[m][k] = *(const LAS bf16x8*)(lds + PG8_SA(b, h) + aoff + m * 2048 + k * 1024); } while (0)
; #define PG8_LDB(dst, b, h) do { _Pragma("unroll") for (int n = 0; n < 2; ++n) _Pragma("unroll") for (int k = 0; k < 2; ++k) dst[n][k] = *(const LAS bf16x8*)(lds + PG8_SB(b, h) + boff + n * 2048 + k * 1024); } while (0)
; #define PG8_MMA(ai, bj, At, Bt) do { __builtin_amdgcn_s_setprio(1); _Pragma("unroll") for (int m = 0; m < 4; ++m) _Pragma("unroll") for (int n = 0; n < 2; ++n) _Pragma("unroll") for (int k = 0; k < 2; ++k) \
;         acc[ai][bj][m][n] = __builtin_amdgcn_mfma_f32_16x16x32_bf16(Bt[n][k], At[m][k], acc[ai][bj][m][n], 0, 0, 0); __builtin_amdgcn_s_setprio(0); } while (0)
; #define PG8_WAIT_V(n) asm volatile("s_waitcnt vmcnt(" #n ")" ::: "memory")
; #define PG8_WAIT_L(n) asm volatile("s_waitcnt lgkmcnt(" #n ")" ::: "memory")
; #define PG8_BAR __builtin_amdgcn_s_barrier()
; #define PG8_SCHED __builtin_amdgcn_sched_barrier(0)
; template <class Map, class Epi>
; DI void gemm_phase(LAS unsigned char* lds, const Map& MP, const Epi& E, const int nM, const int nN, const int K, const int lda, const int ldb) {
;     ...
;             PG8_LDB(B1, 0, 1); PG8_STAGE(PG8_SB(0, 0), b2, voffB);
;             PG8_BAR; PG8_WAIT_L(0); PG8_MMA(0, 1, At, B1); PG8_BAR;
;             PG8_LDA(At, 0, 1); PG8_STAGE(PG8_SA(0, 0), a2, voffA);
;             PG8_BAR; PG8_WAIT_L(0); PG8_MMA(1, 0, At, B0); PG8_BAR; PG8_SCHED;
;             PG8_STAGE(PG8_SB(0, 1), b2 + hstepB, voffB);
;             PG8_WAIT_V(6); PG8_BAR; PG8_MMA(1, 1, At, B1); PG8_BAR;
;             PG8_LDB(B0, 1, 0); PG8_SCHED; PG8_LDA(At, 1, 0); PG8_STAGE(PG8_SA(0, 1), a2 + hstepA, voffA);
	s_add_i32 s54, s44, s29
	v_lshl_add_u64 v[194:195], s[22:23], 0, v[132:133]
	s_mov_b32 m0, s54
	ds_read_b128 v[202:205], v149
	ds_read_b128 v[206:209], v149 offset:1024
	ds_read_b128 v[210:213], v149 offset:2048
	ds_read_b128 v[214:217], v149 offset:3072
	global_load_lds_dwordx4 v[194:195], off
	v_lshl_add_u64 v[218:219], s[22:23], 0, v[128:129]
	s_add_i32 m0, s54, 0x2000
	s_nop 0
	global_load_lds_dwordx4 v[218:219], off
	s_barrier
	s_setprio 1
	s_waitcnt lgkmcnt(3)
	v_mfma_f32_16x16x32_bf16 v[108:111], v[202:205], v[166:169], v[108:111]
	s_waitcnt lgkmcnt(1)
	v_mfma_f32_16x16x32_bf16 v[104:107], v[210:213], v[166:169], v[104:107]
	v_mfma_f32_16x16x32_bf16 v[92:95], v[202:205], v[174:177], v[92:95]
	v_mfma_f32_16x16x32_bf16 v[88:91], v[210:213], v[174:177], v[88:91]
	v_mfma_f32_16x16x32_bf16 v[76:79], v[202:205], v[182:185], v[76:79]
	v_mfma_f32_16x16x32_bf16 v[72:75], v[210:213], v[182:185], v[72:75]
	v_mfma_f32_16x16x32_bf16 v[68:71], v[202:205], v[190:193], v[68:71]
	v_mfma_f32_16x16x32_bf16 v[64:67], v[210:213], v[190:193], v[64:67]
	v_mfma_f32_16x16x32_bf16 v[108:111], v[206:209], v[170:173], v[108:111]
	s_waitcnt lgkmcnt(0)
	v_mfma_f32_16x16x32_bf16 v[104:107], v[214:217], v[170:173], v[104:107]
	v_mfma_f32_16x16x32_bf16 v[92:95], v[206:209], v[178:181], v[92:95]
	v_mfma_f32_16x16x32_bf16 v[88:91], v[214:217], v[178:181], v[88:91]
	v_mfma_f32_16x16x32_bf16 v[76:79], v[206:209], v[186:189], v[76:79]
	v_mfma_f32_16x16x32_bf16 v[72:75], v[214:217], v[186:189], v[72:75]
	v_mfma_f32_16x16x32_bf16 v[68:71], v[206:209], v[198:201], v[68:71]
	v_mfma_f32_16x16x32_bf16 v[64:67], v[214:217], v[198:201], v[64:67]
	s_setprio 0
	s_mov_b32 m0, s31
	v_lshl_add_u64 v[220:221], s[24:25], 0, v[134:135]
	s_barrier
	ds_read_b128 v[166:169], v148 offset:16384
	ds_read_b128 v[170:173], v148 offset:17408
	ds_read_b128 v[174:177], v148 offset:18432
	ds_read_b128 v[178:181], v148 offset:19456
	ds_read_b128 v[182:185], v148 offset:20480
	ds_read_b128 v[186:189], v148 offset:21504
	ds_read_b128 v[190:193], v148 offset:22528
	ds_read_b128 v[198:201], v148 offset:23552
	global_load_lds_dwordx4 v[220:221], off
	v_lshl_add_u64 v[222:223], s[24:25], 0, v[130:131]
	s_mov_b32 m0, s11
	s_nop 0
	global_load_lds_dwordx4 v[222:223], off
	s_waitcnt vmcnt(10)
	s_barrier
	s_setprio 1
	s_waitcnt lgkmcnt(7)
	v_mfma_f32_16x16x32_bf16 v[60:63], v[150:153], v[166:169], v[60:63]
	v_mfma_f32_16x16x32_bf16 v[56:59], v[158:161], v[166:169], v[56:59]
	s_waitcnt lgkmcnt(5)
	v_mfma_f32_16x16x32_bf16 v[52:55], v[150:153], v[174:177], v[52:55]
	v_mfma_f32_16x16x32_bf16 v[48:51], v[158:161], v[174:177], v[48:51]
	s_waitcnt lgkmcnt(3)
	v_mfma_f32_16x16x32_bf16 v[36:39], v[150:153], v[182:185], v[36:39]
	v_mfma_f32_16x16x32_bf16 v[32:35], v[158:161], v[182:185], v[32:35]
	s_waitcnt lgkmcnt(1)
	v_mfma_f32_16x16x32_bf16 v[20:23], v[150:153], v[190:193], v[20:23]
	v_mfma_f32_16x16x32_bf16 v[16:19], v[158:161], v[190:193], v[16:19]
	v_mfma_f32_16x16x32_bf16 v[60:63], v[154:157], v[170:173], v[60:63]
	v_mfma_f32_16x16x32_bf16 v[56:59], v[162:165], v[170:173], v[56:59]
	v_mfma_f32_16x16x32_bf16 v[52:55], v[154:157], v[178:181], v[52:55]
	v_mfma_f32_16x16x32_bf16 v[48:51], v[162:165], v[178:181], v[48:51]
	v_mfma_f32_16x16x32_bf16 v[36:39], v[154:157], v[186:189], v[36:39]
	v_mfma_f32_16x16x32_bf16 v[32:35], v[162:165], v[186:189], v[32:35]
	s_waitcnt lgkmcnt(0)
	v_mfma_f32_16x16x32_bf16 v[20:23], v[154:157], v[198:201], v[20:23]
	v_mfma_f32_16x16x32_bf16 v[16:19], v[162:165], v[198:201], v[16:19]
	s_setprio 0
	s_barrier
	s_add_u32 s54, s22, 0x80000
	s_addc_u32 s55, s23, 0
	s_add_i32 s56, s45, s29
	s_mov_b32 m0, s56
	s_nop 0
	global_load_lds_dwordx4 v132, s[54:55]
	s_add_i32 m0, s56, 0x2000
	s_nop 0
	global_load_lds_dwordx4 v128, s[54:55]
	s_waitcnt vmcnt(6)
	s_barrier
	s_setprio 1
	v_mfma_f32_16x16x32_bf16 v[44:47], v[202:205], v[166:169], v[44:47]
	v_mfma_f32_16x16x32_bf16 v[40:43], v[210:213], v[166:169], v[40:43]
	s_add_i32 s54, 0, 0x18000
	v_add_u32_e32 v162, s54, v146
	ds_read_b128 v[150:153], v162
	v_mfma_f32_16x16x32_bf16 v[28:31], v[202:205], v[174:177], v[28:31]
	v_mfma_f32_16x16x32_bf16 v[24:27], v[210:213], v[174:177], v[24:27]
	ds_read_b128 v[154:157], v162 offset:1024
	v_mfma_f32_16x16x32_bf16 v[12:15], v[202:205], v[182:185], v[12:15]
	v_mfma_f32_16x16x32_bf16 v[8:11], v[210:213], v[182:185], v[8:11]
	ds_read_b128 v[158:161], v162 offset:2048
	v_mfma_f32_16x16x32_bf16 v[4:7], v[202:205], v[190:193], v[4:7]
	v_mfma_f32_16x16x32_bf16 v[0:3], v[210:213], v[190:193], v[0:3]
	ds_read_b128 v[162:165], v162 offset:3072
	v_mfma_f32_16x16x32_bf16 v[44:47], v[206:209], v[170:173], v[44:47]
	v_mfma_f32_16x16x32_bf16 v[40:43], v[214:217], v[170:173], v[40:43]
	v_mfma_f32_16x16x32_bf16 v[28:31], v[206:209], v[178:181], v[28:31]
	v_mfma_f32_16x16x32_bf16 v[24:27], v[214:217], v[178:181], v[24:27]
	v_mfma_f32_16x16x32_bf16 v[12:15], v[206:209], v[186:189], v[12:15]
	v_mfma_f32_16x16x32_bf16 v[8:11], v[214:217], v[186:189], v[8:11]
	v_mfma_f32_16x16x32_bf16 v[4:7], v[206:209], v[198:201], v[4:7]
	v_mfma_f32_16x16x32_bf16 v[0:3], v[214:217], v[198:201], v[0:3]
	s_setprio 0
	s_barrier
	s_add_u32 s24, s24, 0x80000
	s_addc_u32 s25, s25, 0
	s_mov_b32 m0, s34
	ds_read_b128 v[166:169], v148 offset:32768
	ds_read_b128 v[170:173], v148 offset:33792
	ds_read_b128 v[174:177], v148 offset:34816
	ds_read_b128 v[178:181], v148 offset:35840
	ds_read_b128 v[182:185], v148 offset:36864
	ds_read_b128 v[186:189], v148 offset:37888
	ds_read_b128 v[190:193], v148 offset:38912
	ds_read_b128 v[198:201], v148 offset:39936
	global_load_lds_dwordx4 v134, s[24:25]
	s_mov_b32 m0, s35
	s_nop 0
	global_load_lds_dwordx4 v130, s[24:25]
	s_waitcnt lgkmcnt(8)
	s_barrier
; #define PG8_STAGE(bufoff, gbase, voff) do { _Pragma("unroll") for (int _i = 0; _i < 2; ++_i) \
;         __builtin_amdgcn_global_load_lds((const unsigned*)((const char*)(gbase) + (voff)[_i]), (LAS unsigned*)(lds + (bufoff) + ldsw + _i * 8192), 16, 0, 0); } while (0)
; #define PG8_LDA(dst, b, h) do { _Pragma("unroll") for (int m = 0; m < 4; ++m) _Pragma("unroll") for (int k = 0; k < 2; ++k) dst[m][k] = *(const LAS bf16x8*)(lds + PG8_SA(b, h) + aoff + m * 2048 + k * 1024); } while (0)
; #define PG8_LDB(dst, b, h) do { _Pragma("unroll") for (int n = 0; n < 2; ++n) _Pragma("unroll") for (int k = 0; k < 2; ++k) dst[n][k] = *(const LAS bf16x8*)(lds + PG8_SB(b, h) + boff + n * 2048 + k * 1024); } while (0)
; #define PG8_MMA(ai, bj, At, Bt) do { __builtin_amdgcn_s_setprio(1); _Pragma("unroll") for (int m = 0; m < 4; ++m) _Pragma("unroll") for (int n = 0; n < 2; ++n) _Pragma("unroll") for (int k = 0; k < 2; ++k) \
;         acc[ai][bj][m][n] = __builtin_amdgcn_mfma_f32_16x16x32_bf16(Bt[n][k], At[m][k], acc[ai][bj][m][n], 0, 0, 0); __builtin_amdgcn_s_setprio(0); } while (0)
; #define PG8_WAIT_V(n) asm volatile("s_waitcnt vmcnt(" #n ")" ::: "memory")
; #define PG8_WAIT_L(n) asm volatile("s_waitcnt lgkmcnt(" #n ")" ::: "memory")
; #define PG8_BAR __builtin_amdgcn_s_barrier()
; #define PG8_SCHED __builtin_amdgcn_sched_barrier(0)
; template <class Map, class Epi>
; DI void gemm_phase(LAS unsigned char* lds, const Map& MP, const Epi& E, const int nM, const int nN, const int K, const int lda, const int ldb) {
;     ...
;             PG8_WAIT_L(8); PG8_BAR; PG8_WAIT_L(0); PG8_MMA(0, 0, At, B0); PG8_BAR; PG8_SCHED;
;             PG8_LDB(B1, 1, 1); PG8_STAGE(PG8_SB(1, 0), b3, voffB);
;             PG8_BAR; PG8_WAIT_L(0); PG8_MMA(0, 1, At, B1); PG8_BAR;
;             PG8_LDA(At, 1, 1); PG8_STAGE(PG8_SA(1, 0), a3, voffA);
;             PG8_BAR; PG8_WAIT_L(0); PG8_MMA(1, 0, At, B0); PG8_BAR; PG8_SCHED;
;             PG8_STAGE(PG8_SB(1, 1), b3 + hstepB, voffB);
;             PG8_WAIT_V(6); PG8_BAR; PG8_MMA(1, 1, At, B1); PG8_BAR;
	s_setprio 1
	s_waitcnt lgkmcnt(7)
	v_mfma_f32_16x16x32_bf16 v[124:127], v[150:153], v[166:169], v[124:127]
	v_mfma_f32_16x16x32_bf16 v[120:123], v[158:161], v[166:169], v[120:123]
	s_waitcnt lgkmcnt(5)
	v_mfma_f32_16x16x32_bf16 v[116:119], v[150:153], v[174:177], v[116:119]
	v_mfma_f32_16x16x32_bf16 v[112:115], v[158:161], v[174:177], v[112:115]
	s_waitcnt lgkmcnt(3)
	v_mfma_f32_16x16x32_bf16 v[100:103], v[150:153], v[182:185], v[100:103]
	v_mfma_f32_16x16x32_bf16 v[96:99], v[158:161], v[182:185], v[96:99]
	s_waitcnt lgkmcnt(1)
	v_mfma_f32_16x16x32_bf16 v[84:87], v[150:153], v[190:193], v[84:87]
	v_mfma_f32_16x16x32_bf16 v[80:83], v[158:161], v[190:193], v[80:83]
	v_mfma_f32_16x16x32_bf16 v[124:127], v[154:157], v[170:173], v[124:127]
	v_mfma_f32_16x16x32_bf16 v[120:123], v[162:165], v[170:173], v[120:123]
	v_mfma_f32_16x16x32_bf16 v[116:119], v[154:157], v[178:181], v[116:119]
	v_mfma_f32_16x16x32_bf16 v[112:115], v[162:165], v[178:181], v[112:115]
	v_mfma_f32_16x16x32_bf16 v[100:103], v[154:157], v[186:189], v[100:103]
	v_mfma_f32_16x16x32_bf16 v[96:99], v[162:165], v[186:189], v[96:99]
	s_waitcnt lgkmcnt(0)
	v_mfma_f32_16x16x32_bf16 v[84:87], v[154:157], v[198:201], v[84:87]
	v_mfma_f32_16x16x32_bf16 v[80:83], v[162:165], v[198:201], v[80:83]
	s_setprio 0
	s_barrier
	s_add_i32 s24, 0, 0x1c000
	s_add_i32 s25, s54, s29
	v_add_u32_e32 v196, s24, v146
	v_lshl_add_u64 v[194:195], v[194:195], 0, s[8:9]
	s_mov_b32 m0, s25
	ds_read_b128 v[202:205], v196
	ds_read_b128 v[206:209], v196 offset:1024
	ds_read_b128 v[210:213], v196 offset:2048
	ds_read_b128 v[214:217], v196 offset:3072
	global_load_lds_dwordx4 v[194:195], off
	v_lshl_add_u64 v[194:195], v[218:219], 0, s[8:9]
	s_add_i32 m0, s25, 0x2000
	s_nop 0
	global_load_lds_dwordx4 v[194:195], off
	s_barrier
	s_setprio 1
	s_waitcnt lgkmcnt(3)
	v_mfma_f32_16x16x32_bf16 v[108:111], v[202:205], v[166:169], v[108:111]
	s_waitcnt lgkmcnt(1)
	v_mfma_f32_16x16x32_bf16 v[104:107], v[210:213], v[166:169], v[104:107]
	v_mfma_f32_16x16x32_bf16 v[92:95], v[202:205], v[174:177], v[92:95]
	v_mfma_f32_16x16x32_bf16 v[88:91], v[210:213], v[174:177], v[88:91]
	v_mfma_f32_16x16x32_bf16 v[76:79], v[202:205], v[182:185], v[76:79]
	v_mfma_f32_16x16x32_bf16 v[72:75], v[210:213], v[182:185], v[72:75]
	v_mfma_f32_16x16x32_bf16 v[68:71], v[202:205], v[190:193], v[68:71]
	v_mfma_f32_16x16x32_bf16 v[64:67], v[210:213], v[190:193], v[64:67]
	v_mfma_f32_16x16x32_bf16 v[108:111], v[206:209], v[170:173], v[108:111]
	s_waitcnt lgkmcnt(0)
	v_mfma_f32_16x16x32_bf16 v[104:107], v[214:217], v[170:173], v[104:107]
	v_mfma_f32_16x16x32_bf16 v[92:95], v[206:209], v[178:181], v[92:95]
	v_mfma_f32_16x16x32_bf16 v[88:91], v[214:217], v[178:181], v[88:91]
	v_mfma_f32_16x16x32_bf16 v[76:79], v[206:209], v[186:189], v[76:79]
	v_mfma_f32_16x16x32_bf16 v[72:75], v[214:217], v[186:189], v[72:75]
	v_mfma_f32_16x16x32_bf16 v[68:71], v[206:209], v[198:201], v[68:71]
	v_mfma_f32_16x16x32_bf16 v[64:67], v[214:217], v[198:201], v[64:67]
	s_setprio 0
	s_mov_b32 m0, s39
	v_lshl_add_u64 v[194:195], v[220:221], 0, s[8:9]
	s_barrier
	ds_read_b128 v[166:169], v148 offset:49152
	ds_read_b128 v[170:173], v148 offset:50176
	ds_read_b128 v[174:177], v148 offset:51200
	ds_read_b128 v[178:181], v148 offset:52224
	ds_read_b128 v[182:185], v148 offset:53248
	ds_read_b128 v[186:189], v148 offset:54272
	ds_read_b128 v[190:193], v148 offset:55296
	ds_read_b128 v[198:201], v148 offset:56320
	global_load_lds_dwordx4 v[194:195], off
	v_lshl_add_u64 v[194:195], v[222:223], 0, s[8:9]
	s_mov_b32 m0, s42
	s_nop 0
	global_load_lds_dwordx4 v[194:195], off
	s_waitcnt vmcnt(10)
	s_barrier
	s_setprio 1
	s_waitcnt lgkmcnt(7)
	v_mfma_f32_16x16x32_bf16 v[60:63], v[150:153], v[166:169], v[60:63]
	v_mfma_f32_16x16x32_bf16 v[56:59], v[158:161], v[166:169], v[56:59]
	s_waitcnt lgkmcnt(5)
	v_mfma_f32_16x16x32_bf16 v[52:55], v[150:153], v[174:177], v[52:55]
	v_mfma_f32_16x16x32_bf16 v[48:51], v[158:161], v[174:177], v[48:51]
	s_waitcnt lgkmcnt(3)
	v_mfma_f32_16x16x32_bf16 v[36:39], v[150:153], v[182:185], v[36:39]
	v_mfma_f32_16x16x32_bf16 v[32:35], v[158:161], v[182:185], v[32:35]
	s_waitcnt lgkmcnt(1)
	v_mfma_f32_16x16x32_bf16 v[20:23], v[150:153], v[190:193], v[20:23]
	v_mfma_f32_16x16x32_bf16 v[16:19], v[158:161], v[190:193], v[16:19]
	v_mfma_f32_16x16x32_bf16 v[60:63], v[154:157], v[170:173], v[60:63]
	v_mfma_f32_16x16x32_bf16 v[56:59], v[162:165], v[170:173], v[56:59]
	v_mfma_f32_16x16x32_bf16 v[52:55], v[154:157], v[178:181], v[52:55]
	v_mfma_f32_16x16x32_bf16 v[48:51], v[162:165], v[178:181], v[48:51]
	v_mfma_f32_16x16x32_bf16 v[36:39], v[154:157], v[186:189], v[36:39]
	v_mfma_f32_16x16x32_bf16 v[32:35], v[162:165], v[186:189], v[32:35]
	s_waitcnt lgkmcnt(0)
	v_mfma_f32_16x16x32_bf16 v[20:23], v[154:157], v[198:201], v[20:23]
	v_mfma_f32_16x16x32_bf16 v[16:19], v[162:165], v[198:201], v[16:19]
	s_setprio 0
	s_barrier
	s_add_u32 s22, s22, 0x80080
	s_addc_u32 s23, s23, 0
	s_add_i32 s24, s24, s29
	s_mov_b32 m0, s24
	s_nop 0
	global_load_lds_dwordx4 v132, s[22:23]
	s_add_i32 m0, s24, 0x2000
	s_nop 0
	global_load_lds_dwordx4 v128, s[22:23]
	s_waitcnt vmcnt(6)
	s_barrier
; DI unsigned pack2(float a, float b) { f32x2 v = {a, b}; hwbf16x2 r = __builtin_convertvector(v, hwbf16x2); return __builtin_bit_cast(unsigned, r); }
; #define PG8_STAGE(bufoff, gbase, voff) do { _Pragma("unroll") for (int _i = 0; _i < 2; ++_i) \
;         __builtin_amdgcn_global_load_lds((const unsigned*)((const char*)(gbase) + (voff)[_i]), (LAS unsigned*)(lds + (bufoff) + ldsw + _i * 8192), 16, 0, 0); } while (0)
; #define PG8_LDA(dst, b, h) do { _Pragma("unroll") for (int m = 0; m < 4; ++m) _Pragma("unroll") for (int k = 0; k < 2; ++k) dst[m][k] = *(const LAS bf16x8*)(lds + PG8_SA(b, h) + aoff + m * 2048 + k * 1024); } while (0)
; #define PG8_WAIT_V(n) asm volatile("s_waitcnt vmcnt(" #n ")" ::: "memory")
; #define PG8_WAIT_L(n) asm volatile("s_waitcnt lgkmcnt(" #n ")" ::: "memory")
; #define PG8_BAR __builtin_amdgcn_s_barrier()
; #define PG8_SCHED __builtin_amdgcn_sched_barrier(0)
;     DI void operator()(const f32x4 (&acc)[2][2][4][2], const Unit& u, int wr, int wc, int fr, int fq) const {
;         bf16_t* O = O1; int ldc = ldc1, pn = u.pn; if (pn >= split) { O = O2; ldc = ldc2; pn -= split; }
;         const int row0 = u.pm * BM + wr * 64 + fr, col0 = pn * BM + wc * 32 + 8 * fq;
; #pragma unroll
;         for (int ai = 0; ai < 2; ++ai)
; #pragma unroll
;             for (int m = 0; m < 4; ++m) { bf16_t* rowp = O + (size_t)(row0 + ai * HALF + m * 16) * ldc + col0;
; #pragma unroll
;                 for (int bj = 0; bj < 2; ++bj) { const f32x4 v0 = acc[ai][bj][m][0], v1 = acc[ai][bj][m][1];
;                     u32x4 o; o[0] = pack2(v0[0], v0[1]); o[1] = pack2(v0[2], v0[3]); o[2] = pack2(v1[0], v1[1]); o[3] = pack2(v1[2], v1[3]);
;                     *(u32x4*)(rowp + bj * HALF) = o; } }
; template <class Map, class Epi>
; DI void gemm_phase(LAS unsigned char* lds, const Map& MP, const Epi& E, const int nM, const int nN, const int K, const int lda, const int ldb) {
;     ...
;             PG8_BAR; PG8_WAIT_L(0); PG8_MMA(0, 1, At, B1); PG8_BAR;
;             PG8_LDA(At, 1, 1); PG8_STAGE(PG8_SA(1, 0), a3, voffA);
;             PG8_BAR; PG8_WAIT_L(0); PG8_MMA(1, 0, At, B0); PG8_BAR; PG8_SCHED;
;             PG8_STAGE(PG8_SB(1, 1), b3 + hstepB, voffB);
;             PG8_WAIT_V(6); PG8_BAR; PG8_MMA(1, 1, At, B1); PG8_BAR;
;         }
;         { int frr = fr, fqq = fq; asm volatile("" : "+v"(frr), "+v"(fqq)); E(acc, cur, wr, wc, frr, fqq); }
	s_setprio 1
	v_mfma_f32_16x16x32_bf16 v[44:47], v[202:205], v[166:169], v[44:47]
	v_mfma_f32_16x16x32_bf16 v[40:43], v[210:213], v[166:169], v[40:43]
	ds_read_b128 v[150:153], v147
	v_mfma_f32_16x16x32_bf16 v[28:31], v[202:205], v[174:177], v[28:31]
	v_mfma_f32_16x16x32_bf16 v[24:27], v[210:213], v[174:177], v[24:27]
	ds_read_b128 v[154:157], v147 offset:1024
	v_mfma_f32_16x16x32_bf16 v[12:15], v[202:205], v[182:185], v[12:15]
	v_mfma_f32_16x16x32_bf16 v[8:11], v[210:213], v[182:185], v[8:11]
	ds_read_b128 v[158:161], v147 offset:2048
	v_mfma_f32_16x16x32_bf16 v[4:7], v[202:205], v[190:193], v[4:7]
	v_mfma_f32_16x16x32_bf16 v[0:3], v[210:213], v[190:193], v[0:3]
	ds_read_b128 v[162:165], v147 offset:3072
	v_mfma_f32_16x16x32_bf16 v[44:47], v[206:209], v[170:173], v[44:47]
	v_mfma_f32_16x16x32_bf16 v[40:43], v[214:217], v[170:173], v[40:43]
	v_mfma_f32_16x16x32_bf16 v[28:31], v[206:209], v[178:181], v[28:31]
	v_mfma_f32_16x16x32_bf16 v[24:27], v[214:217], v[178:181], v[24:27]
	v_mfma_f32_16x16x32_bf16 v[12:15], v[206:209], v[186:189], v[12:15]
	v_mfma_f32_16x16x32_bf16 v[8:11], v[214:217], v[186:189], v[8:11]
	v_mfma_f32_16x16x32_bf16 v[4:7], v[206:209], v[198:201], v[4:7]
	v_mfma_f32_16x16x32_bf16 v[0:3], v[214:217], v[198:201], v[0:3]
	s_setprio 0
	s_add_i32 s3, s3, 2
	s_add_u32 s52, s52, 0x100
	s_addc_u32 s53, s53, 0
	s_add_u32 s20, s20, 0x100
	s_addc_u32 s21, s21, 0
	s_cmp_gt_u32 s3, 29
	s_barrier
	s_cbranch_scc0 .LBB1_1382
	s_waitcnt lgkmcnt(0)
	s_lshl_b32 s3, s10, 8
	v_mov_b32_e32 v150, v144
	v_mov_b32_e32 v151, v145
	s_add_i32 s3, s3, s37
	v_cvt_pk_bf16_f32 v68, v68, v69
	v_add_u32_e32 v154, s3, v150
	s_lshl_b32 s3, s47, 8
	s_or_b32 s3, s3, s38
	v_lshl_add_u32 v150, v151, 3, s3
	v_ashrrev_i32_e32 v151, 31, v150
	v_lshl_add_u64 v[150:151], v[150:151], 1, s[6:7]
	v_cvt_pk_bf16_f32 v69, v70, v71
	v_cvt_pk_bf16_f32 v70, v64, v65
	v_add_u32_e32 v64, 0x80, v154
	v_mad_i64_i32 v[152:153], s[20:21], v154, s46, v[150:151]
	v_cvt_pk_bf16_f32 v108, v108, v109
	v_cvt_pk_bf16_f32 v109, v110, v111
	v_cvt_pk_bf16_f32 v110, v104, v105
	v_cvt_pk_bf16_f32 v111, v106, v107
	v_add_u32_e32 v104, 16, v154
	v_mad_i64_i32 v[64:65], s[20:21], v64, s46, v[150:151]
	v_cvt_pk_bf16_f32 v44, v44, v45
	v_cvt_pk_bf16_f32 v45, v46, v47
	v_cvt_pk_bf16_f32 v46, v40, v41
	v_cvt_pk_bf16_f32 v47, v42, v43
	v_add_u32_e32 v40, 0x90, v154
	global_store_dwordx4 v[152:153], v[108:111], off offset:256
	v_cvt_pk_bf16_f32 v92, v92, v93
	v_cvt_pk_bf16_f32 v93, v94, v95
	v_mad_i64_i32 v[108:109], s[20:21], v104, s46, v[150:151]
	v_cvt_pk_bf16_f32 v94, v88, v89
	v_cvt_pk_bf16_f32 v95, v90, v91
	v_add_u32_e32 v88, 32, v154
	global_store_dwordx4 v[64:65], v[44:47], off offset:256
	v_cvt_pk_bf16_f32 v28, v28, v29
	v_cvt_pk_bf16_f32 v29, v30, v31
	v_mad_i64_i32 v[44:45], s[20:21], v40, s46, v[150:151]
	v_cvt_pk_bf16_f32 v30, v24, v25
	v_cvt_pk_bf16_f32 v31, v26, v27
	v_add_u32_e32 v24, 0xa0, v154
	global_store_dwordx4 v[108:109], v[92:95], off offset:256
	v_cvt_pk_bf16_f32 v76, v76, v77
	v_cvt_pk_bf16_f32 v77, v78, v79
	v_mad_i64_i32 v[92:93], s[20:21], v88, s46, v[150:151]
	v_cvt_pk_bf16_f32 v78, v72, v73
	v_cvt_pk_bf16_f32 v79, v74, v75
	v_add_u32_e32 v72, 48, v154
	global_store_dwordx4 v[44:45], v[28:31], off offset:256
	v_cvt_pk_bf16_f32 v12, v12, v13
	v_cvt_pk_bf16_f32 v13, v14, v15
	v_mad_i64_i32 v[28:29], s[20:21], v24, s46, v[150:151]
	v_cvt_pk_bf16_f32 v14, v8, v9
	v_cvt_pk_bf16_f32 v15, v10, v11
	v_add_u32_e32 v8, 0xb0, v154
	global_store_dwordx4 v[92:93], v[76:79], off offset:256
	global_store_dwordx4 v[28:29], v[12:15], off offset:256
	v_cvt_pk_bf16_f32 v124, v124, v125
	v_mad_i64_i32 v[76:77], s[20:21], v72, s46, v[150:151]
	v_mad_i64_i32 v[12:13], s[20:21], v8, s46, v[150:151]
	v_cvt_pk_bf16_f32 v125, v126, v127
	v_cvt_pk_bf16_f32 v126, v120, v121
	v_cvt_pk_bf16_f32 v127, v122, v123
	v_cvt_pk_bf16_f32 v104, v116, v117
	v_cvt_pk_bf16_f32 v105, v118, v119
	v_cvt_pk_bf16_f32 v106, v112, v113
	v_cvt_pk_bf16_f32 v107, v114, v115
	v_cvt_pk_bf16_f32 v88, v100, v101
	v_cvt_pk_bf16_f32 v89, v102, v103
	v_cvt_pk_bf16_f32 v90, v96, v97
	v_cvt_pk_bf16_f32 v91, v98, v99
	v_cvt_pk_bf16_f32 v72, v84, v85
	v_cvt_pk_bf16_f32 v73, v86, v87
	v_cvt_pk_bf16_f32 v74, v80, v81
	v_cvt_pk_bf16_f32 v75, v82, v83
	v_cvt_pk_bf16_f32 v71, v66, v67
	v_cvt_pk_bf16_f32 v60, v60, v61
	v_cvt_pk_bf16_f32 v61, v62, v63
	v_cvt_pk_bf16_f32 v62, v56, v57
	v_cvt_pk_bf16_f32 v63, v58, v59
	v_cvt_pk_bf16_f32 v40, v52, v53
	v_cvt_pk_bf16_f32 v41, v54, v55
	v_cvt_pk_bf16_f32 v42, v48, v49
	v_cvt_pk_bf16_f32 v43, v50, v51
	v_cvt_pk_bf16_f32 v24, v36, v37
	v_cvt_pk_bf16_f32 v25, v38, v39
	v_cvt_pk_bf16_f32 v26, v32, v33
	v_cvt_pk_bf16_f32 v27, v34, v35
	v_cvt_pk_bf16_f32 v8, v20, v21
	v_cvt_pk_bf16_f32 v9, v22, v23
	v_cvt_pk_bf16_f32 v10, v16, v17
	v_cvt_pk_bf16_f32 v11, v18, v19
	v_cvt_pk_bf16_f32 v4, v4, v5
	v_cvt_pk_bf16_f32 v5, v6, v7
	v_cvt_pk_bf16_f32 v6, v0, v1
	v_cvt_pk_bf16_f32 v7, v2, v3
	s_and_b64 vcc, exec, s[40:41]
	s_mov_b32 s47, s12
	s_mov_b32 s10, s14
	s_mov_b64 s[20:21], s[18:19]
	s_mov_b64 s[22:23], s[16:17]
	global_store_dwordx4 v[152:153], v[124:127], off
	global_store_dwordx4 v[108:109], v[104:107], off
	global_store_dwordx4 v[92:93], v[88:91], off
	global_store_dwordx4 v[76:77], v[72:75], off
	global_store_dwordx4 v[76:77], v[68:71], off offset:256
	global_store_dwordx4 v[64:65], v[60:63], off
	global_store_dwordx4 v[44:45], v[40:43], off
	global_store_dwordx4 v[28:29], v[24:27], off
	global_store_dwordx4 v[12:13], v[8:11], off
	global_store_dwordx4 v[12:13], v[4:7], off offset:256
	s_cbranch_vccz .LBB1_1379
	s_waitcnt vmcnt(0)
	s_cmpk_gt_u32 s4, 0xff
	s_cbranch_scc1 .LBB1_1386
	s_barrier

;     DI const char* a(const Unit& u) const { return (const char*)(A + (size_t)u.pm * BM * lda); }
;     DI const char* a(const Unit& u) const { return (const char*)(A + (size_t)u.pm * BM * 2048 + (u.pn >> 1) * 512); }
; #define PG8_STAGE(bufoff, gbase, voff) do { _Pragma("unroll") for (int _i = 0; _i < 2; ++_i) \
;         __builtin_amdgcn_global_load_lds((const unsigned*)((const char*)(gbase) + (voff)[_i]), (LAS unsigned*)(lds + (bufoff) + ldsw + _i * 8192), 16, 0, 0); } while (0)
; #define PG8_LDA(dst, b, h) do { _Pragma("unroll") for (int m = 0; m < 4; ++m) _Pragma("unroll") for (int k = 0; k < 2; ++k) dst[m][k] = *(const LAS bf16x8*)(lds + PG8_SA(b, h) + aoff + m * 2048 + k * 1024); } while (0)
; #define PG8_LDB(dst, b, h) do { _Pragma("unroll") for (int n = 0; n < 2; ++n) _Pragma("unroll") for (int k = 0; k < 2; ++k) dst[n][k] = *(const LAS bf16x8*)(lds + PG8_SB(b, h) + boff + n * 2048 + k * 1024); } while (0)
; #define PG8_MMA(ai, bj, At, Bt) do { __builtin_amdgcn_s_setprio(1); _Pragma("unroll") for (int m = 0; m < 4; ++m) _Pragma("unroll") for (int n = 0; n < 2; ++n) _Pragma("unroll") for (int k = 0; k < 2; ++k) \
;         acc[ai][bj][m][n] = __builtin_amdgcn_mfma_f32_16x16x32_bf16(Bt[n][k], At[m][k], acc[ai][bj][m][n], 0, 0, 0); __builtin_amdgcn_s_setprio(0); } while (0)
; #define PG8_BAR __builtin_amdgcn_s_barrier()
;     DI const char* a(const Unit& u) const { return (const char*)((u.pn < 12 ? A1 : A2) + (size_t)u.pm * BM * 512); }
; template <class Map, class Epi>
; DI void gemm_phase(LAS unsigned char* lds, const Map& MP, const Epi& E, const int nM, const int nN, const int K, const int lda, const int ldb) {
;     ...
;         const bool has_next = sched_next(ui + 1, nM, nN, G, cblk, nxt);
;         const char* nA = has_next ? MP.a(nxt) : cA; const char* nB = has_next ? MP.b(nxt) : cB;
;         for (int t = 0; t < nt; t += 2) {
;             const bool last = (t == nt - 2);
;             const char* a1 = cA + (size_t)(t + 1) * kstep;
;             const char* a2 = last ? nA : cA + (size_t)(t + 2) * kstep; const char* b2 = last ? nB : cB + (size_t)(t + 2) * kstep;
;             const char* a3 = a2 + kstep; const char* b3 = b2 + kstep;
;             PG8_LDB(B0, 0, 0); PG8_SCHED; PG8_LDA(At, 0, 0); PG8_STAGE(PG8_SA(1, 1), a1 + hstepA, voffA);
;             PG8_WAIT_L(8); PG8_BAR; PG8_WAIT_L(0); PG8_MMA(0, 0, At, B0); PG8_BAR; PG8_SCHED;
.LBB1_1528:
	s_add_i32 s3, s49, -12
	s_cmp_lt_i32 s49, 12
	s_cselect_b32 s53, s27, s29
	s_cselect_b32 s54, s28, s30
	s_ashr_i32 s13, s49, 31
	s_cmp_lt_i32 s49, 12
	s_cselect_b32 s22, s24, s26
	s_cselect_b32 s23, s5, s25
	s_cselect_b32 s17, s13, 0
	s_cselect_b32 s16, s49, s3
	s_ashr_i32 s13, s12, 31
	v_cmp_lt_i64_e32 vcc, s[14:15], v[140:141]
	s_lshl_b64 s[14:15], s[12:13], 18
	s_add_u32 s14, s23, s14
	s_addc_u32 s15, s22, s15
	s_and_b64 s[22:23], vcc, exec
	s_cselect_b32 s13, s15, s21
	s_cselect_b32 s52, s14, s20
	s_lshl_b64 s[16:17], s[16:17], 18
	s_add_u32 s16, s53, s16
	s_addc_u32 s17, s54, s17
	s_and_b64 s[22:23], vcc, exec
	s_cselect_b32 s53, s17, s19
	s_cselect_b32 s54, s16, s18
	s_add_u32 s55, s18, 0x100
	s_addc_u32 s56, s19, 0
	s_add_u32 s18, s20, 0x20080
	v_mov_b32_e32 v0, 0
	s_addc_u32 s19, s21, 0
	s_mov_b32 s3, -2
	v_mov_b32_e32 v1, v0
	v_mov_b32_e32 v2, v0
	v_mov_b32_e32 v3, v0
	v_mov_b32_e32 v4, v0
	v_mov_b32_e32 v5, v0
	v_mov_b32_e32 v6, v0
	v_mov_b32_e32 v7, v0
	v_mov_b32_e32 v8, v0
	v_mov_b32_e32 v9, v0
	v_mov_b32_e32 v10, v0
	v_mov_b32_e32 v11, v0
	v_mov_b32_e32 v12, v0
	v_mov_b32_e32 v13, v0
	v_mov_b32_e32 v14, v0
	v_mov_b32_e32 v15, v0
	v_mov_b32_e32 v24, v0
	v_mov_b32_e32 v25, v0
	v_mov_b32_e32 v26, v0
	v_mov_b32_e32 v27, v0
	v_mov_b32_e32 v28, v0
	v_mov_b32_e32 v29, v0
	v_mov_b32_e32 v30, v0
	v_mov_b32_e32 v31, v0
	v_mov_b32_e32 v40, v0
	v_mov_b32_e32 v41, v0
	v_mov_b32_e32 v42, v0
	v_mov_b32_e32 v43, v0
	v_mov_b32_e32 v44, v0
	v_mov_b32_e32 v45, v0
	v_mov_b32_e32 v46, v0
	v_mov_b32_e32 v47, v0
	v_mov_b32_e32 v16, v0
	v_mov_b32_e32 v17, v0
	v_mov_b32_e32 v18, v0
	v_mov_b32_e32 v19, v0
	v_mov_b32_e32 v20, v0
	v_mov_b32_e32 v21, v0
	v_mov_b32_e32 v22, v0
	v_mov_b32_e32 v23, v0
	v_mov_b32_e32 v32, v0
	v_mov_b32_e32 v33, v0
	v_mov_b32_e32 v34, v0
	v_mov_b32_e32 v35, v0
	v_mov_b32_e32 v36, v0
	v_mov_b32_e32 v37, v0
	v_mov_b32_e32 v38, v0
	v_mov_b32_e32 v39, v0
	v_mov_b32_e32 v48, v0
	v_mov_b32_e32 v49, v0
	v_mov_b32_e32 v50, v0
	v_mov_b32_e32 v51, v0
	v_mov_b32_e32 v52, v0
	v_mov_b32_e32 v53, v0
	v_mov_b32_e32 v54, v0
	v_mov_b32_e32 v55, v0
	v_mov_b32_e32 v56, v0
	v_mov_b32_e32 v57, v0
	v_mov_b32_e32 v58, v0
	v_mov_b32_e32 v59, v0
	v_mov_b32_e32 v60, v0
	v_mov_b32_e32 v61, v0
	v_mov_b32_e32 v62, v0
	v_mov_b32_e32 v63, v0
	v_mov_b32_e32 v64, v0
	v_mov_b32_e32 v65, v0
	v_mov_b32_e32 v66, v0
	v_mov_b32_e32 v67, v0
	v_mov_b32_e32 v68, v0
	v_mov_b32_e32 v69, v0
	v_mov_b32_e32 v70, v0
	v_mov_b32_e32 v71, v0
	v_mov_b32_e32 v72, v0
	v_mov_b32_e32 v73, v0
	v_mov_b32_e32 v74, v0
	v_mov_b32_e32 v75, v0
	v_mov_b32_e32 v76, v0
	v_mov_b32_e32 v77, v0
	v_mov_b32_e32 v78, v0
	v_mov_b32_e32 v79, v0
	v_mov_b32_e32 v88, v0
	v_mov_b32_e32 v89, v0
	v_mov_b32_e32 v90, v0
	v_mov_b32_e32 v91, v0
	v_mov_b32_e32 v92, v0
	v_mov_b32_e32 v93, v0
	v_mov_b32_e32 v94, v0
	v_mov_b32_e32 v95, v0
	v_mov_b32_e32 v104, v0
	v_mov_b32_e32 v105, v0
	v_mov_b32_e32 v106, v0
	v_mov_b32_e32 v107, v0
	v_mov_b32_e32 v108, v0
	v_mov_b32_e32 v109, v0
	v_mov_b32_e32 v110, v0
	v_mov_b32_e32 v111, v0
	v_mov_b32_e32 v80, v0
	v_mov_b32_e32 v81, v0
	v_mov_b32_e32 v82, v0
	v_mov_b32_e32 v83, v0
	v_mov_b32_e32 v84, v0
	v_mov_b32_e32 v85, v0
	v_mov_b32_e32 v86, v0
	v_mov_b32_e32 v87, v0
	v_mov_b32_e32 v96, v0
	v_mov_b32_e32 v97, v0
	v_mov_b32_e32 v98, v0
	v_mov_b32_e32 v99, v0
	v_mov_b32_e32 v100, v0
	v_mov_b32_e32 v101, v0
	v_mov_b32_e32 v102, v0
	v_mov_b32_e32 v103, v0
	v_mov_b32_e32 v112, v0
	v_mov_b32_e32 v113, v0
	v_mov_b32_e32 v114, v0
	v_mov_b32_e32 v115, v0
	v_mov_b32_e32 v116, v0
	v_mov_b32_e32 v117, v0
	v_mov_b32_e32 v118, v0
	v_mov_b32_e32 v119, v0
	v_mov_b32_e32 v120, v0
	v_mov_b32_e32 v121, v0
	v_mov_b32_e32 v122, v0
	v_mov_b32_e32 v123, v0
	v_mov_b32_e32 v124, v0
	v_mov_b32_e32 v125, v0
	v_mov_b32_e32 v126, v0
	v_mov_b32_e32 v127, v0
	ds_read_b128 v[150:153], v147
	ds_read_b128 v[154:157], v147 offset:1024
	ds_read_b128 v[158:161], v147 offset:2048
	ds_read_b128 v[162:165], v147 offset:3072
.LBB1_1529:
	s_add_u32 s20, s18, 0xfffe0080
	s_addc_u32 s21, s19, -1
	s_cmp_eq_u32 s3, 4
	s_cselect_b32 s23, s13, s21
	s_cselect_b32 s22, s52, s20
	s_cselect_b32 s21, s53, s56
	s_cselect_b32 s20, s54, s55
	s_add_i32 m0, s11, 0xc000
	ds_read_b128 v[166:169], v148
	ds_read_b128 v[170:173], v148 offset:1024
	ds_read_b128 v[174:177], v148 offset:2048
	ds_read_b128 v[178:181], v148 offset:3072
	ds_read_b128 v[182:185], v148 offset:4096
	ds_read_b128 v[186:189], v148 offset:5120
	ds_read_b128 v[190:193], v148 offset:6144
	ds_read_b128 v[198:201], v148 offset:7168
	global_load_lds_dwordx4 v138, s[18:19]
	s_add_i32 m0, s11, 0xe000
	s_nop 0
	global_load_lds_dwordx4 v136, s[18:19]
	s_waitcnt lgkmcnt(8)
	s_barrier
	s_setprio 1
	s_waitcnt lgkmcnt(7)
	v_mfma_f32_16x16x32_bf16 v[124:127], v[150:153], v[166:169], v[124:127]
	v_mfma_f32_16x16x32_bf16 v[120:123], v[158:161], v[166:169], v[120:123]
	s_waitcnt lgkmcnt(5)
	v_mfma_f32_16x16x32_bf16 v[116:119], v[150:153], v[174:177], v[116:119]
	v_mfma_f32_16x16x32_bf16 v[112:115], v[158:161], v[174:177], v[112:115]
	s_waitcnt lgkmcnt(3)
	v_mfma_f32_16x16x32_bf16 v[100:103], v[150:153], v[182:185], v[100:103]
	v_mfma_f32_16x16x32_bf16 v[96:99], v[158:161], v[182:185], v[96:99]
	s_waitcnt lgkmcnt(1)
	v_mfma_f32_16x16x32_bf16 v[84:87], v[150:153], v[190:193], v[84:87]
	v_mfma_f32_16x16x32_bf16 v[80:83], v[158:161], v[190:193], v[80:83]
	v_mfma_f32_16x16x32_bf16 v[124:127], v[154:157], v[170:173], v[124:127]
	v_mfma_f32_16x16x32_bf16 v[120:123], v[162:165], v[170:173], v[120:123]
	v_mfma_f32_16x16x32_bf16 v[116:119], v[154:157], v[178:181], v[116:119]
	v_mfma_f32_16x16x32_bf16 v[112:115], v[162:165], v[178:181], v[112:115]
	v_mfma_f32_16x16x32_bf16 v[100:103], v[154:157], v[186:189], v[100:103]
	v_mfma_f32_16x16x32_bf16 v[96:99], v[162:165], v[186:189], v[96:99]
	s_waitcnt lgkmcnt(0)
	v_mfma_f32_16x16x32_bf16 v[84:87], v[154:157], v[198:201], v[84:87]
	v_mfma_f32_16x16x32_bf16 v[80:83], v[162:165], v[198:201], v[80:83]
	s_setprio 0
	s_barrier
; #define PG8_STAGE(bufoff, gbase, voff) do { _Pragma("unroll") for (int _i = 0; _i < 2; ++_i) \
;         __builtin_amdgcn_global_load_lds((const unsigned*)((const char*)(gbase) + (voff)[_i]), (LAS unsigned*)(lds + (bufoff) + ldsw + _i * 8192), 16, 0, 0); } while (0)
; #define PG8_LDA(dst, b, h) do { _Pragma("unroll") for (int m = 0; m < 4; ++m) _Pragma("unroll") for (int k = 0; k < 2; ++k) dst[m][k] = *(const LAS bf16x8*)(lds + PG8_SA(b, h) + aoff + m * 2048 + k * 1024); } while (0)
; #define PG8_LDB(dst, b, h) do { _Pragma("unroll") for (int n = 0; n < 2; ++n) _Pragma("unroll") for (int k = 0; k < 2; ++k) dst[n][k] = *(const LAS bf16x8*)(lds + PG8_SB(b, h) + boff + n * 2048 + k * 1024); } while (0)
; #define PG8_MMA(ai, bj, At, Bt) do { __builtin_amdgcn_s_setprio(1); _Pragma("unroll") for (int m = 0; m < 4; ++m) _Pragma("unroll") for (int n = 0; n < 2; ++n) _Pragma("unroll") for (int k = 0; k < 2; ++k) \
;         acc[ai][bj][m][n] = __builtin_amdgcn_mfma_f32_16x16x32_bf16(Bt[n][k], At[m][k], acc[ai][bj][m][n], 0, 0, 0); __builtin_amdgcn_s_setprio(0); } while (0)
; #define PG8_WAIT_V(n) asm volatile("s_waitcnt vmcnt(" #n ")" ::: "memory")
; #define PG8_WAIT_L(n) asm volatile("s_waitcnt lgkmcnt(" #n ")" ::: "memory")
; #define PG8_BAR __builtin_amdgcn_s_barrier()
; #define PG8_SCHED __builtin_amdgcn_sched_barrier(0)
; template <class Map, class Epi>
; DI void gemm_phase(LAS unsigned char* lds, const Map& MP, const Epi& E, const int nM, const int nN, const int K, const int lda, const int ldb) {
;     ...
;             PG8_LDB(B1, 0, 1); PG8_STAGE(PG8_SB(0, 0), b2, voffB);
;             PG8_BAR; PG8_WAIT_L(0); PG8_MMA(0, 1, At, B1); PG8_BAR;
;             PG8_LDA(At, 0, 1); PG8_STAGE(PG8_SA(0, 0), a2, voffA);
;             PG8_BAR; PG8_WAIT_L(0); PG8_MMA(1, 0, At, B0); PG8_BAR; PG8_SCHED;
;             PG8_STAGE(PG8_SB(0, 1), b2 + hstepB, voffB);
;             PG8_WAIT_V(6); PG8_BAR; PG8_MMA(1, 1, At, B1); PG8_BAR;
;             PG8_LDB(B0, 1, 0); PG8_SCHED; PG8_LDA(At, 1, 0); PG8_STAGE(PG8_SA(0, 1), a2 + hstepA, voffA);
	s_add_i32 s57, s47, s31
	v_lshl_add_u64 v[194:195], s[20:21], 0, v[132:133]
	s_mov_b32 m0, s57
	ds_read_b128 v[202:205], v149
	ds_read_b128 v[206:209], v149 offset:1024
	ds_read_b128 v[210:213], v149 offset:2048
	ds_read_b128 v[214:217], v149 offset:3072
	global_load_lds_dwordx4 v[194:195], off
	v_lshl_add_u64 v[218:219], s[20:21], 0, v[128:129]
	s_add_i32 m0, s57, 0x2000
	s_nop 0
	global_load_lds_dwordx4 v[218:219], off
	s_barrier
	s_setprio 1
	s_waitcnt lgkmcnt(3)
	v_mfma_f32_16x16x32_bf16 v[108:111], v[202:205], v[166:169], v[108:111]
	s_waitcnt lgkmcnt(1)
	v_mfma_f32_16x16x32_bf16 v[104:107], v[210:213], v[166:169], v[104:107]
	v_mfma_f32_16x16x32_bf16 v[92:95], v[202:205], v[174:177], v[92:95]
	v_mfma_f32_16x16x32_bf16 v[88:91], v[210:213], v[174:177], v[88:91]
	v_mfma_f32_16x16x32_bf16 v[76:79], v[202:205], v[182:185], v[76:79]
	v_mfma_f32_16x16x32_bf16 v[72:75], v[210:213], v[182:185], v[72:75]
	v_mfma_f32_16x16x32_bf16 v[68:71], v[202:205], v[190:193], v[68:71]
	v_mfma_f32_16x16x32_bf16 v[64:67], v[210:213], v[190:193], v[64:67]
	v_mfma_f32_16x16x32_bf16 v[108:111], v[206:209], v[170:173], v[108:111]
	s_waitcnt lgkmcnt(0)
	v_mfma_f32_16x16x32_bf16 v[104:107], v[214:217], v[170:173], v[104:107]
	v_mfma_f32_16x16x32_bf16 v[92:95], v[206:209], v[178:181], v[92:95]
	v_mfma_f32_16x16x32_bf16 v[88:91], v[214:217], v[178:181], v[88:91]
	v_mfma_f32_16x16x32_bf16 v[76:79], v[206:209], v[186:189], v[76:79]
	v_mfma_f32_16x16x32_bf16 v[72:75], v[214:217], v[186:189], v[72:75]
	v_mfma_f32_16x16x32_bf16 v[68:71], v[206:209], v[198:201], v[68:71]
	v_mfma_f32_16x16x32_bf16 v[64:67], v[214:217], v[198:201], v[64:67]
	s_setprio 0
	s_mov_b32 m0, s11
	v_lshl_add_u64 v[220:221], s[22:23], 0, v[134:135]
	s_barrier
	ds_read_b128 v[166:169], v148 offset:16384
	ds_read_b128 v[170:173], v148 offset:17408
	ds_read_b128 v[174:177], v148 offset:18432
	ds_read_b128 v[178:181], v148 offset:19456
	ds_read_b128 v[182:185], v148 offset:20480
	ds_read_b128 v[186:189], v148 offset:21504
	ds_read_b128 v[190:193], v148 offset:22528
	ds_read_b128 v[198:201], v148 offset:23552
	global_load_lds_dwordx4 v[220:221], off
	v_lshl_add_u64 v[222:223], s[22:23], 0, v[130:131]
	s_mov_b32 m0, s35
	s_nop 0
	global_load_lds_dwordx4 v[222:223], off
	s_waitcnt vmcnt(10)
	s_barrier
	s_setprio 1
	s_waitcnt lgkmcnt(7)
	v_mfma_f32_16x16x32_bf16 v[60:63], v[150:153], v[166:169], v[60:63]
	v_mfma_f32_16x16x32_bf16 v[56:59], v[158:161], v[166:169], v[56:59]
	s_waitcnt lgkmcnt(5)
	v_mfma_f32_16x16x32_bf16 v[52:55], v[150:153], v[174:177], v[52:55]
	v_mfma_f32_16x16x32_bf16 v[48:51], v[158:161], v[174:177], v[48:51]
	s_waitcnt lgkmcnt(3)
	v_mfma_f32_16x16x32_bf16 v[36:39], v[150:153], v[182:185], v[36:39]
	v_mfma_f32_16x16x32_bf16 v[32:35], v[158:161], v[182:185], v[32:35]
	s_waitcnt lgkmcnt(1)
	v_mfma_f32_16x16x32_bf16 v[20:23], v[150:153], v[190:193], v[20:23]
	v_mfma_f32_16x16x32_bf16 v[16:19], v[158:161], v[190:193], v[16:19]
	v_mfma_f32_16x16x32_bf16 v[60:63], v[154:157], v[170:173], v[60:63]
	v_mfma_f32_16x16x32_bf16 v[56:59], v[162:165], v[170:173], v[56:59]
	v_mfma_f32_16x16x32_bf16 v[52:55], v[154:157], v[178:181], v[52:55]
	v_mfma_f32_16x16x32_bf16 v[48:51], v[162:165], v[178:181], v[48:51]
	v_mfma_f32_16x16x32_bf16 v[36:39], v[154:157], v[186:189], v[36:39]
	v_mfma_f32_16x16x32_bf16 v[32:35], v[162:165], v[186:189], v[32:35]
	s_waitcnt lgkmcnt(0)
	v_mfma_f32_16x16x32_bf16 v[20:23], v[154:157], v[198:201], v[20:23]
	v_mfma_f32_16x16x32_bf16 v[16:19], v[162:165], v[198:201], v[16:19]
	s_setprio 0
	s_barrier
	s_add_u32 s58, s20, 0x20000
	s_addc_u32 s59, s21, 0
	s_add_i32 s57, s48, s31
	s_mov_b32 m0, s57
	s_nop 0
	global_load_lds_dwordx4 v132, s[58:59]
	s_add_i32 m0, s57, 0x2000
	s_nop 0
	global_load_lds_dwordx4 v128, s[58:59]
	s_waitcnt vmcnt(6)
	s_barrier
	s_setprio 1
	v_mfma_f32_16x16x32_bf16 v[44:47], v[202:205], v[166:169], v[44:47]
	v_mfma_f32_16x16x32_bf16 v[40:43], v[210:213], v[166:169], v[40:43]
	s_add_i32 s57, 0, 0x18000
	v_add_u32_e32 v162, s57, v146
	ds_read_b128 v[150:153], v162
	v_mfma_f32_16x16x32_bf16 v[28:31], v[202:205], v[174:177], v[28:31]
	v_mfma_f32_16x16x32_bf16 v[24:27], v[210:213], v[174:177], v[24:27]
	ds_read_b128 v[154:157], v162 offset:1024
	v_mfma_f32_16x16x32_bf16 v[12:15], v[202:205], v[182:185], v[12:15]
	v_mfma_f32_16x16x32_bf16 v[8:11], v[210:213], v[182:185], v[8:11]
	ds_read_b128 v[158:161], v162 offset:2048
	v_mfma_f32_16x16x32_bf16 v[4:7], v[202:205], v[190:193], v[4:7]
	v_mfma_f32_16x16x32_bf16 v[0:3], v[210:213], v[190:193], v[0:3]
	ds_read_b128 v[162:165], v162 offset:3072
	v_mfma_f32_16x16x32_bf16 v[44:47], v[206:209], v[170:173], v[44:47]
	v_mfma_f32_16x16x32_bf16 v[40:43], v[214:217], v[170:173], v[40:43]
	v_mfma_f32_16x16x32_bf16 v[28:31], v[206:209], v[178:181], v[28:31]
	v_mfma_f32_16x16x32_bf16 v[24:27], v[214:217], v[178:181], v[24:27]
	v_mfma_f32_16x16x32_bf16 v[12:15], v[206:209], v[186:189], v[12:15]
	v_mfma_f32_16x16x32_bf16 v[8:11], v[214:217], v[186:189], v[8:11]
	v_mfma_f32_16x16x32_bf16 v[4:7], v[206:209], v[198:201], v[4:7]
	v_mfma_f32_16x16x32_bf16 v[0:3], v[214:217], v[198:201], v[0:3]
	s_setprio 0
	s_barrier
	s_add_u32 s22, s22, 0x20000
	s_addc_u32 s23, s23, 0
	s_mov_b32 m0, s36
	ds_read_b128 v[166:169], v148 offset:32768
	ds_read_b128 v[170:173], v148 offset:33792
	ds_read_b128 v[174:177], v148 offset:34816
	ds_read_b128 v[178:181], v148 offset:35840
	ds_read_b128 v[182:185], v148 offset:36864
	ds_read_b128 v[186:189], v148 offset:37888
	ds_read_b128 v[190:193], v148 offset:38912
	ds_read_b128 v[198:201], v148 offset:39936
	global_load_lds_dwordx4 v134, s[22:23]
	s_mov_b32 m0, s37
	s_nop 0
	global_load_lds_dwordx4 v130, s[22:23]
	s_waitcnt lgkmcnt(8)
	s_barrier
; #define PG8_STAGE(bufoff, gbase, voff) do { _Pragma("unroll") for (int _i = 0; _i < 2; ++_i) \
;         __builtin_amdgcn_global_load_lds((const unsigned*)((const char*)(gbase) + (voff)[_i]), (LAS unsigned*)(lds + (bufoff) + ldsw + _i * 8192), 16, 0, 0); } while (0)
; #define PG8_LDA(dst, b, h) do { _Pragma("unroll") for (int m = 0; m < 4; ++m) _Pragma("unroll") for (int k = 0; k < 2; ++k) dst[m][k] = *(const LAS bf16x8*)(lds + PG8_SA(b, h) + aoff + m * 2048 + k * 1024); } while (0)
; #define PG8_LDB(dst, b, h) do { _Pragma("unroll") for (int n = 0; n < 2; ++n) _Pragma("unroll") for (int k = 0; k < 2; ++k) dst[n][k] = *(const LAS bf16x8*)(lds + PG8_SB(b, h) + boff + n * 2048 + k * 1024); } while (0)
; #define PG8_MMA(ai, bj, At, Bt) do { __builtin_amdgcn_s_setprio(1); _Pragma("unroll") for (int m = 0; m < 4; ++m) _Pragma("unroll") for (int n = 0; n < 2; ++n) _Pragma("unroll") for (int k = 0; k < 2; ++k) \
;         acc[ai][bj][m][n] = __builtin_amdgcn_mfma_f32_16x16x32_bf16(Bt[n][k], At[m][k], acc[ai][bj][m][n], 0, 0, 0); __builtin_amdgcn_s_setprio(0); } while (0)
; #define PG8_WAIT_V(n) asm volatile("s_waitcnt vmcnt(" #n ")" ::: "memory")
; #define PG8_WAIT_L(n) asm volatile("s_waitcnt lgkmcnt(" #n ")" ::: "memory")
; #define PG8_BAR __builtin_amdgcn_s_barrier()
; #define PG8_SCHED __builtin_amdgcn_sched_barrier(0)
; template <class Map, class Epi>
; DI void gemm_phase(LAS unsigned char* lds, const Map& MP, const Epi& E, const int nM, const int nN, const int K, const int lda, const int ldb) {
;     ...
;             PG8_WAIT_L(8); PG8_BAR; PG8_WAIT_L(0); PG8_MMA(0, 0, At, B0); PG8_BAR; PG8_SCHED;
;             PG8_LDB(B1, 1, 1); PG8_STAGE(PG8_SB(1, 0), b3, voffB);
;             PG8_BAR; PG8_WAIT_L(0); PG8_MMA(0, 1, At, B1); PG8_BAR;
;             PG8_LDA(At, 1, 1); PG8_STAGE(PG8_SA(1, 0), a3, voffA);
;             PG8_BAR; PG8_WAIT_L(0); PG8_MMA(1, 0, At, B0); PG8_BAR; PG8_SCHED;
;             PG8_STAGE(PG8_SB(1, 1), b3 + hstepB, voffB);
;             PG8_WAIT_V(6); PG8_BAR; PG8_MMA(1, 1, At, B1); PG8_BAR;
	s_setprio 1
	s_waitcnt lgkmcnt(7)
	v_mfma_f32_16x16x32_bf16 v[124:127], v[150:153], v[166:169], v[124:127]
	v_mfma_f32_16x16x32_bf16 v[120:123], v[158:161], v[166:169], v[120:123]
	s_waitcnt lgkmcnt(5)
	v_mfma_f32_16x16x32_bf16 v[116:119], v[150:153], v[174:177], v[116:119]
	v_mfma_f32_16x16x32_bf16 v[112:115], v[158:161], v[174:177], v[112:115]
	s_waitcnt lgkmcnt(3)
	v_mfma_f32_16x16x32_bf16 v[100:103], v[150:153], v[182:185], v[100:103]
	v_mfma_f32_16x16x32_bf16 v[96:99], v[158:161], v[182:185], v[96:99]
	s_waitcnt lgkmcnt(1)
	v_mfma_f32_16x16x32_bf16 v[84:87], v[150:153], v[190:193], v[84:87]
	v_mfma_f32_16x16x32_bf16 v[80:83], v[158:161], v[190:193], v[80:83]
	v_mfma_f32_16x16x32_bf16 v[124:127], v[154:157], v[170:173], v[124:127]
	v_mfma_f32_16x16x32_bf16 v[120:123], v[162:165], v[170:173], v[120:123]
	v_mfma_f32_16x16x32_bf16 v[116:119], v[154:157], v[178:181], v[116:119]
	v_mfma_f32_16x16x32_bf16 v[112:115], v[162:165], v[178:181], v[112:115]
	v_mfma_f32_16x16x32_bf16 v[100:103], v[154:157], v[186:189], v[100:103]
	v_mfma_f32_16x16x32_bf16 v[96:99], v[162:165], v[186:189], v[96:99]
	s_waitcnt lgkmcnt(0)
	v_mfma_f32_16x16x32_bf16 v[84:87], v[154:157], v[198:201], v[84:87]
	v_mfma_f32_16x16x32_bf16 v[80:83], v[162:165], v[198:201], v[80:83]
	s_setprio 0
	s_barrier
	s_add_i32 s22, 0, 0x1c000
	s_add_i32 s23, s57, s31
	v_add_u32_e32 v196, s22, v146
	v_lshl_add_u64 v[194:195], v[194:195], 0, s[8:9]
	s_mov_b32 m0, s23
	ds_read_b128 v[202:205], v196
	ds_read_b128 v[206:209], v196 offset:1024
	ds_read_b128 v[210:213], v196 offset:2048
	ds_read_b128 v[214:217], v196 offset:3072
	global_load_lds_dwordx4 v[194:195], off
	v_lshl_add_u64 v[194:195], v[218:219], 0, s[8:9]
	s_add_i32 m0, s23, 0x2000
	s_nop 0
	global_load_lds_dwordx4 v[194:195], off
	s_barrier
	s_setprio 1
	s_waitcnt lgkmcnt(3)
	v_mfma_f32_16x16x32_bf16 v[108:111], v[202:205], v[166:169], v[108:111]
	s_waitcnt lgkmcnt(1)
	v_mfma_f32_16x16x32_bf16 v[104:107], v[210:213], v[166:169], v[104:107]
	v_mfma_f32_16x16x32_bf16 v[92:95], v[202:205], v[174:177], v[92:95]
	v_mfma_f32_16x16x32_bf16 v[88:91], v[210:213], v[174:177], v[88:91]
	v_mfma_f32_16x16x32_bf16 v[76:79], v[202:205], v[182:185], v[76:79]
	v_mfma_f32_16x16x32_bf16 v[72:75], v[210:213], v[182:185], v[72:75]
	v_mfma_f32_16x16x32_bf16 v[68:71], v[202:205], v[190:193], v[68:71]
	v_mfma_f32_16x16x32_bf16 v[64:67], v[210:213], v[190:193], v[64:67]
	v_mfma_f32_16x16x32_bf16 v[108:111], v[206:209], v[170:173], v[108:111]
	s_waitcnt lgkmcnt(0)
	v_mfma_f32_16x16x32_bf16 v[104:107], v[214:217], v[170:173], v[104:107]
	v_mfma_f32_16x16x32_bf16 v[92:95], v[206:209], v[178:181], v[92:95]
	v_mfma_f32_16x16x32_bf16 v[88:91], v[214:217], v[178:181], v[88:91]
	v_mfma_f32_16x16x32_bf16 v[76:79], v[206:209], v[186:189], v[76:79]
	v_mfma_f32_16x16x32_bf16 v[72:75], v[214:217], v[186:189], v[72:75]
	v_mfma_f32_16x16x32_bf16 v[68:71], v[206:209], v[198:201], v[68:71]
	v_mfma_f32_16x16x32_bf16 v[64:67], v[214:217], v[198:201], v[64:67]
	s_setprio 0
	s_mov_b32 m0, s43
	v_lshl_add_u64 v[194:195], v[220:221], 0, s[8:9]
	s_barrier
	ds_read_b128 v[166:169], v148 offset:49152
	ds_read_b128 v[170:173], v148 offset:50176
	ds_read_b128 v[174:177], v148 offset:51200
	ds_read_b128 v[178:181], v148 offset:52224
	ds_read_b128 v[182:185], v148 offset:53248
	ds_read_b128 v[186:189], v148 offset:54272
	ds_read_b128 v[190:193], v148 offset:55296
	ds_read_b128 v[198:201], v148 offset:56320
	global_load_lds_dwordx4 v[194:195], off
	v_lshl_add_u64 v[194:195], v[222:223], 0, s[8:9]
	s_mov_b32 m0, s44
	s_nop 0
	global_load_lds_dwordx4 v[194:195], off
	s_waitcnt vmcnt(10)
	s_barrier
	s_setprio 1
	s_waitcnt lgkmcnt(7)
	v_mfma_f32_16x16x32_bf16 v[60:63], v[150:153], v[166:169], v[60:63]
	v_mfma_f32_16x16x32_bf16 v[56:59], v[158:161], v[166:169], v[56:59]
	s_waitcnt lgkmcnt(5)
	v_mfma_f32_16x16x32_bf16 v[52:55], v[150:153], v[174:177], v[52:55]
	v_mfma_f32_16x16x32_bf16 v[48:51], v[158:161], v[174:177], v[48:51]
	s_waitcnt lgkmcnt(3)
	v_mfma_f32_16x16x32_bf16 v[36:39], v[150:153], v[182:185], v[36:39]
	v_mfma_f32_16x16x32_bf16 v[32:35], v[158:161], v[182:185], v[32:35]
	s_waitcnt lgkmcnt(1)
	v_mfma_f32_16x16x32_bf16 v[20:23], v[150:153], v[190:193], v[20:23]
	v_mfma_f32_16x16x32_bf16 v[16:19], v[158:161], v[190:193], v[16:19]
	v_mfma_f32_16x16x32_bf16 v[60:63], v[154:157], v[170:173], v[60:63]
	v_mfma_f32_16x16x32_bf16 v[56:59], v[162:165], v[170:173], v[56:59]
	v_mfma_f32_16x16x32_bf16 v[52:55], v[154:157], v[178:181], v[52:55]
	v_mfma_f32_16x16x32_bf16 v[48:51], v[162:165], v[178:181], v[48:51]
	v_mfma_f32_16x16x32_bf16 v[36:39], v[154:157], v[186:189], v[36:39]
	v_mfma_f32_16x16x32_bf16 v[32:35], v[162:165], v[186:189], v[32:35]
	s_waitcnt lgkmcnt(0)
	v_mfma_f32_16x16x32_bf16 v[20:23], v[154:157], v[198:201], v[20:23]
	v_mfma_f32_16x16x32_bf16 v[16:19], v[162:165], v[198:201], v[16:19]
	s_setprio 0
	s_barrier
	s_add_u32 s20, s20, 0x20080
	s_addc_u32 s21, s21, 0
	s_add_i32 s22, s22, s31
	s_mov_b32 m0, s22
	s_nop 0
	global_load_lds_dwordx4 v132, s[20:21]
	s_add_i32 m0, s22, 0x2000
	s_nop 0
	global_load_lds_dwordx4 v128, s[20:21]
	s_waitcnt vmcnt(6)
	s_barrier
; DI unsigned pack2(float a, float b) { f32x2 v = {a, b}; hwbf16x2 r = __builtin_convertvector(v, hwbf16x2); return __builtin_bit_cast(unsigned, r); }
; #define PG8_MMA(ai, bj, At, Bt) do { __builtin_amdgcn_s_setprio(1); _Pragma("unroll") for (int m = 0; m < 4; ++m) _Pragma("unroll") for (int n = 0; n < 2; ++n) _Pragma("unroll") for (int k = 0; k < 2; ++k) \
;         acc[ai][bj][m][n] = __builtin_amdgcn_mfma_f32_16x16x32_bf16(Bt[n][k], At[m][k], acc[ai][bj][m][n], 0, 0, 0); __builtin_amdgcn_s_setprio(0); } while (0)
; #define PG8_WAIT_V(n) asm volatile("s_waitcnt vmcnt(" #n ")" ::: "memory")
; #define PG8_BAR __builtin_amdgcn_s_barrier()
;     DI void operator()(const f32x4 (&acc)[2][2][4][2], const Unit& u, int wr, int wc, int fr, int fq) const {
;         bf16_t* O = O1; int ldc = ldc1, pn = u.pn; if (pn >= split) { O = O2; ldc = ldc2; pn -= split; }
;         const int row0 = u.pm * BM + wr * 64 + fr, col0 = pn * BM + wc * 32 + 8 * fq;
; #pragma unroll
;         for (int ai = 0; ai < 2; ++ai)
; #pragma unroll
;             for (int m = 0; m < 4; ++m) { bf16_t* rowp = O + (size_t)(row0 + ai * HALF + m * 16) * ldc + col0;
; #pragma unroll
;                 for (int bj = 0; bj < 2; ++bj) { const f32x4 v0 = acc[ai][bj][m][0], v1 = acc[ai][bj][m][1];
;                     u32x4 o; o[0] = pack2(v0[0], v0[1]); o[1] = pack2(v0[2], v0[3]); o[2] = pack2(v1[0], v1[1]); o[3] = pack2(v1[2], v1[3]);
;                     *(u32x4*)(rowp + bj * HALF) = o; } }
;     }
; template <class Map, class Epi>
; DI void gemm_phase(LAS unsigned char* lds, const Map& MP, const Epi& E, const int nM, const int nN, const int K, const int lda, const int ldb) {
;     ...
;             PG8_WAIT_V(6); PG8_BAR; PG8_MMA(1, 1, At, B1); PG8_BAR;
;         }
;         { int frr = fr, fqq = fq; asm volatile("" : "+v"(frr), "+v"(fqq)); E(acc, cur, wr, wc, frr, fqq); }
;         if (!has_next) break;
	s_setprio 1
	v_mfma_f32_16x16x32_bf16 v[44:47], v[202:205], v[166:169], v[44:47]
	v_mfma_f32_16x16x32_bf16 v[40:43], v[210:213], v[166:169], v[40:43]
	ds_read_b128 v[150:153], v147
	v_mfma_f32_16x16x32_bf16 v[28:31], v[202:205], v[174:177], v[28:31]
	v_mfma_f32_16x16x32_bf16 v[24:27], v[210:213], v[174:177], v[24:27]
	ds_read_b128 v[154:157], v147 offset:1024
	v_mfma_f32_16x16x32_bf16 v[12:15], v[202:205], v[182:185], v[12:15]
	v_mfma_f32_16x16x32_bf16 v[8:11], v[210:213], v[182:185], v[8:11]
	ds_read_b128 v[158:161], v147 offset:2048
	v_mfma_f32_16x16x32_bf16 v[4:7], v[202:205], v[190:193], v[4:7]
	v_mfma_f32_16x16x32_bf16 v[0:3], v[210:213], v[190:193], v[0:3]
	ds_read_b128 v[162:165], v147 offset:3072
	v_mfma_f32_16x16x32_bf16 v[44:47], v[206:209], v[170:173], v[44:47]
	v_mfma_f32_16x16x32_bf16 v[40:43], v[214:217], v[170:173], v[40:43]
	v_mfma_f32_16x16x32_bf16 v[28:31], v[206:209], v[178:181], v[28:31]
	v_mfma_f32_16x16x32_bf16 v[24:27], v[214:217], v[178:181], v[24:27]
	v_mfma_f32_16x16x32_bf16 v[12:15], v[206:209], v[186:189], v[12:15]
	v_mfma_f32_16x16x32_bf16 v[8:11], v[214:217], v[186:189], v[8:11]
	v_mfma_f32_16x16x32_bf16 v[4:7], v[206:209], v[198:201], v[4:7]
	v_mfma_f32_16x16x32_bf16 v[0:3], v[214:217], v[198:201], v[0:3]
	s_setprio 0
	s_add_i32 s3, s3, 2
	s_add_u32 s55, s55, 0x100
	s_addc_u32 s56, s56, 0
	s_add_u32 s18, s18, 0x100
	s_addc_u32 s19, s19, 0
	s_cmp_gt_u32 s3, 5
	s_barrier
	s_cbranch_scc0 .LBB1_1529
	s_waitcnt lgkmcnt(0)
	s_cmp_lt_i32 s45, 12
	s_cselect_b32 s3, 0, -12
	s_mov_b32 s13, 0x1e510000
	s_movk_i32 s18, 0xc00
	s_cselect_b32 s13, s13, 0x2a510000
	s_cselect_b32 s20, s18, 0x1000
	s_add_i32 s3, s3, s45
	s_add_u32 s18, s6, s13
	v_mov_b32_e32 v150, v144
	v_mov_b32_e32 v151, v145
	s_addc_u32 s19, s7, 0
	s_lshl_b32 s10, s10, 8
	s_lshl_b32 s3, s3, 8
	s_add_i32 s10, s10, s39
	s_or_b32 s3, s3, s42
	v_add_u32_e32 v154, s10, v150
	v_lshl_add_u32 v150, v151, 3, s3
	v_ashrrev_i32_e32 v151, 31, v150
	v_lshl_add_u64 v[150:151], v[150:151], 1, s[18:19]
	v_mad_i64_i32 v[152:153], s[18:19], s20, v154, 0
	v_cvt_pk_bf16_f32 v108, v108, v109
	v_cvt_pk_bf16_f32 v109, v110, v111
	v_cvt_pk_bf16_f32 v110, v104, v105
	v_add_u32_e32 v104, 16, v154
	v_lshl_add_u64 v[152:153], v[152:153], 1, v[150:151]
	v_cvt_pk_bf16_f32 v111, v106, v107
	v_mad_i64_i32 v[104:105], s[18:19], s20, v104, 0
	v_cvt_pk_bf16_f32 v92, v92, v93
	v_cvt_pk_bf16_f32 v93, v94, v95
	v_cvt_pk_bf16_f32 v94, v88, v89
	v_add_u32_e32 v88, 32, v154
	v_cvt_pk_bf16_f32 v124, v124, v125
	v_cvt_pk_bf16_f32 v125, v126, v127
	v_cvt_pk_bf16_f32 v126, v120, v121
	v_cvt_pk_bf16_f32 v127, v122, v123
	global_store_dwordx4 v[152:153], v[108:111], off offset:256
	v_cvt_pk_bf16_f32 v95, v90, v91
	v_mad_i64_i32 v[88:89], s[18:19], s20, v88, 0
	v_lshl_add_u64 v[108:109], v[104:105], 1, v[150:151]
	v_cvt_pk_bf16_f32 v76, v76, v77
	v_cvt_pk_bf16_f32 v77, v78, v79
	v_cvt_pk_bf16_f32 v78, v72, v73
	v_add_u32_e32 v72, 48, v154
	v_cvt_pk_bf16_f32 v68, v68, v69
	v_cvt_pk_bf16_f32 v69, v70, v71
	v_cvt_pk_bf16_f32 v70, v64, v65
	v_add_u32_e32 v64, 0x80, v154
	global_store_dwordx4 v[152:153], v[124:127], off
	v_cvt_pk_bf16_f32 v104, v116, v117
	v_cvt_pk_bf16_f32 v105, v118, v119
	v_cvt_pk_bf16_f32 v106, v112, v113
	v_cvt_pk_bf16_f32 v107, v114, v115
	global_store_dwordx4 v[108:109], v[92:95], off offset:256
	v_cvt_pk_bf16_f32 v79, v74, v75
	v_mad_i64_i32 v[72:73], s[18:19], s20, v72, 0
	v_lshl_add_u64 v[92:93], v[88:89], 1, v[150:151]
	v_mad_i64_i32 v[64:65], s[18:19], s20, v64, 0
	v_cvt_pk_bf16_f32 v44, v44, v45
	v_cvt_pk_bf16_f32 v45, v46, v47
	v_cvt_pk_bf16_f32 v46, v40, v41
	v_add_u32_e32 v40, 0x90, v154
	global_store_dwordx4 v[108:109], v[104:107], off
	v_cvt_pk_bf16_f32 v88, v100, v101
	v_cvt_pk_bf16_f32 v89, v102, v103
	v_cvt_pk_bf16_f32 v90, v96, v97
	v_cvt_pk_bf16_f32 v91, v98, v99
	global_store_dwordx4 v[92:93], v[76:79], off offset:256
	v_cvt_pk_bf16_f32 v74, v80, v81
	v_cvt_pk_bf16_f32 v75, v82, v83
	v_lshl_add_u64 v[76:77], v[72:73], 1, v[150:151]
	v_cvt_pk_bf16_f32 v72, v84, v85
	v_cvt_pk_bf16_f32 v73, v86, v87
	v_cvt_pk_bf16_f32 v71, v66, v67
	v_lshl_add_u64 v[64:65], v[64:65], 1, v[150:151]
	v_cvt_pk_bf16_f32 v47, v42, v43
	v_mad_i64_i32 v[40:41], s[18:19], s20, v40, 0
	v_cvt_pk_bf16_f32 v28, v28, v29
	v_cvt_pk_bf16_f32 v29, v30, v31
	v_cvt_pk_bf16_f32 v30, v24, v25
	v_add_u32_e32 v24, 0xa0, v154
	global_store_dwordx4 v[92:93], v[88:91], off
	global_store_dwordx4 v[76:77], v[72:75], off
	global_store_dwordx4 v[76:77], v[68:71], off offset:256
	v_cvt_pk_bf16_f32 v60, v60, v61
	v_cvt_pk_bf16_f32 v61, v62, v63
	v_cvt_pk_bf16_f32 v62, v56, v57
	v_cvt_pk_bf16_f32 v63, v58, v59
	global_store_dwordx4 v[64:65], v[44:47], off offset:256
	v_cvt_pk_bf16_f32 v31, v26, v27
	v_mad_i64_i32 v[24:25], s[18:19], s20, v24, 0
	v_lshl_add_u64 v[44:45], v[40:41], 1, v[150:151]
	v_cvt_pk_bf16_f32 v12, v12, v13
	v_cvt_pk_bf16_f32 v13, v14, v15
	v_cvt_pk_bf16_f32 v14, v8, v9
	v_add_u32_e32 v8, 0xb0, v154
	global_store_dwordx4 v[64:65], v[60:63], off
	v_cvt_pk_bf16_f32 v40, v52, v53
	v_cvt_pk_bf16_f32 v41, v54, v55
	v_cvt_pk_bf16_f32 v42, v48, v49
	v_cvt_pk_bf16_f32 v43, v50, v51
	global_store_dwordx4 v[44:45], v[28:31], off offset:256
	v_cvt_pk_bf16_f32 v15, v10, v11
	v_mad_i64_i32 v[8:9], s[18:19], s20, v8, 0
	v_lshl_add_u64 v[28:29], v[24:25], 1, v[150:151]
	global_store_dwordx4 v[44:45], v[40:43], off
	v_cvt_pk_bf16_f32 v24, v36, v37
	v_cvt_pk_bf16_f32 v25, v38, v39
	v_cvt_pk_bf16_f32 v26, v32, v33
	v_cvt_pk_bf16_f32 v27, v34, v35
	global_store_dwordx4 v[28:29], v[12:15], off offset:256
	v_cvt_pk_bf16_f32 v10, v16, v17
	v_cvt_pk_bf16_f32 v11, v18, v19
	v_lshl_add_u64 v[12:13], v[8:9], 1, v[150:151]
	v_cvt_pk_bf16_f32 v8, v20, v21
	v_cvt_pk_bf16_f32 v9, v22, v23
	v_cvt_pk_bf16_f32 v4, v4, v5
	v_cvt_pk_bf16_f32 v5, v6, v7
	v_cvt_pk_bf16_f32 v6, v0, v1
	v_cvt_pk_bf16_f32 v7, v2, v3
	s_and_b64 vcc, exec, s[40:41]
	s_mov_b32 s45, s49
	s_mov_b32 s10, s12
	s_mov_b64 s[18:19], s[16:17]
	s_mov_b64 s[20:21], s[14:15]
	global_store_dwordx4 v[28:29], v[24:27], off
	global_store_dwordx4 v[12:13], v[8:11], off
	global_store_dwordx4 v[12:13], v[4:7], off offset:256
	s_cbranch_vccz .LBB1_1526
	s_waitcnt vmcnt(0)
	s_cmpk_gt_u32 s4, 0xff
	s_cbranch_scc1 .LBB1_1533
	s_barrier

;     DI const char* a(const Unit& u) const { return (const char*)(A + (size_t)u.pm * BM * lda); }
;     DI const char* a(const Unit& u) const { return (const char*)(A + (size_t)u.pm * BM * 2048 + (u.pn >> 1) * 512); }
;     DI const char* a(const Unit& u) const { return (const char*)((u.pn < 12 ? A1 : A2) + (size_t)u.pm * BM * 512); }
; #define PG8_STAGE(bufoff, gbase, voff) do { _Pragma("unroll") for (int _i = 0; _i < 2; ++_i) \
;         __builtin_amdgcn_global_load_lds((const unsigned*)((const char*)(gbase) + (voff)[_i]), (LAS unsigned*)(lds + (bufoff) + ldsw + _i * 8192), 16, 0, 0); } while (0)
; #define PG8_LDA(dst, b, h) do { _Pragma("unroll") for (int m = 0; m < 4; ++m) _Pragma("unroll") for (int k = 0; k < 2; ++k) dst[m][k] = *(const LAS bf16x8*)(lds + PG8_SA(b, h) + aoff + m * 2048 + k * 1024); } while (0)
; #define PG8_LDB(dst, b, h) do { _Pragma("unroll") for (int n = 0; n < 2; ++n) _Pragma("unroll") for (int k = 0; k < 2; ++k) dst[n][k] = *(const LAS bf16x8*)(lds + PG8_SB(b, h) + boff + n * 2048 + k * 1024); } while (0)
; #define PG8_WAIT_L(n) asm volatile("s_waitcnt lgkmcnt(" #n ")" ::: "memory")
; template <class Map, class Epi>
; DI void gemm_phase(LAS unsigned char* lds, const Map& MP, const Epi& E, const int nM, const int nN, const int K, const int lda, const int ldb) {
;     ...
;         const bool has_next = sched_next(ui + 1, nM, nN, G, cblk, nxt);
;         const char* nA = has_next ? MP.a(nxt) : cA; const char* nB = has_next ? MP.b(nxt) : cB;
;         for (int t = 0; t < nt; t += 2) {
;             const bool last = (t == nt - 2);
;             const char* a1 = cA + (size_t)(t + 1) * kstep;
;             const char* a2 = last ? nA : cA + (size_t)(t + 2) * kstep; const char* b2 = last ? nB : cB + (size_t)(t + 2) * kstep;
;             const char* a3 = a2 + kstep; const char* b3 = b2 + kstep;
;             PG8_LDB(B0, 0, 0); PG8_SCHED; PG8_LDA(At, 0, 0); PG8_STAGE(PG8_SA(1, 1), a1 + hstepA, voffA);
;             PG8_WAIT_L(8); PG8_BAR; PG8_WAIT_L(0); PG8_MMA(0, 0, At, B0); PG8_BAR; PG8_SCHED;
;     ...
;         for (int a = 0; a < 2; ++a)
; #pragma unroll
;             for (int b = 0; b < 2; ++b)
; #pragma unroll
;                 for (int m = 0; m < 4; ++m)
; #pragma unroll
;                     for (int n = 0; n < 2; ++n) acc[a][b][m][n] = (f32x4){0.f, 0.f, 0.f, 0.f};
;         cur = nxt; cA = nA; cB = nB; ++ui;
.LBB1_1763:
	s_ashr_i32 s47, s46, 31
	v_cmp_lt_i64_e32 vcc, s[6:7], v[140:141]
	s_lshl_b64 s[6:7], s[46:47], 20
	s_add_u32 s52, s18, s6
	s_addc_u32 s53, s19, s7
	s_and_b64 s[6:7], vcc, exec
	s_cselect_b32 s37, s53, s13
	s_cselect_b32 s38, s52, s12
	s_ashr_i32 s45, s44, 31
	s_lshl_b64 s[6:7], s[44:45], 20
	s_add_u32 s6, s20, s6
	s_addc_u32 s7, s21, s7
	s_and_b64 s[14:15], vcc, exec
	s_cselect_b32 s39, s7, s11
	s_cselect_b32 s45, s6, s10
	s_add_u32 s47, s10, 0x100
	s_addc_u32 s48, s11, 0
	s_add_u32 s10, s12, 0x80080
	v_mov_b32_e32 v0, 0
	s_addc_u32 s11, s13, 0
	s_mov_b32 s3, -2
	v_mov_b32_e32 v1, v0
	v_mov_b32_e32 v2, v0
	v_mov_b32_e32 v3, v0
	v_mov_b32_e32 v4, v0
	v_mov_b32_e32 v5, v0
	v_mov_b32_e32 v6, v0
	v_mov_b32_e32 v7, v0
	v_mov_b32_e32 v16, v0
	v_mov_b32_e32 v17, v0
	v_mov_b32_e32 v18, v0
	v_mov_b32_e32 v19, v0
	v_mov_b32_e32 v20, v0
	v_mov_b32_e32 v21, v0
	v_mov_b32_e32 v22, v0
	v_mov_b32_e32 v23, v0
	v_mov_b32_e32 v32, v0
	v_mov_b32_e32 v33, v0
	v_mov_b32_e32 v34, v0
	v_mov_b32_e32 v35, v0
	v_mov_b32_e32 v36, v0
	v_mov_b32_e32 v37, v0
	v_mov_b32_e32 v38, v0
	v_mov_b32_e32 v39, v0
	v_mov_b32_e32 v48, v0
	v_mov_b32_e32 v49, v0
	v_mov_b32_e32 v50, v0
	v_mov_b32_e32 v51, v0
	v_mov_b32_e32 v52, v0
	v_mov_b32_e32 v53, v0
	v_mov_b32_e32 v54, v0
	v_mov_b32_e32 v55, v0
	v_mov_b32_e32 v8, v0
	v_mov_b32_e32 v9, v0
	v_mov_b32_e32 v10, v0
	v_mov_b32_e32 v11, v0
	v_mov_b32_e32 v12, v0
	v_mov_b32_e32 v13, v0
	v_mov_b32_e32 v14, v0
	v_mov_b32_e32 v15, v0
	v_mov_b32_e32 v24, v0
	v_mov_b32_e32 v25, v0
	v_mov_b32_e32 v26, v0
	v_mov_b32_e32 v27, v0
	v_mov_b32_e32 v28, v0
	v_mov_b32_e32 v29, v0
	v_mov_b32_e32 v30, v0
	v_mov_b32_e32 v31, v0
	v_mov_b32_e32 v40, v0
	v_mov_b32_e32 v41, v0
	v_mov_b32_e32 v42, v0
	v_mov_b32_e32 v43, v0
	v_mov_b32_e32 v44, v0
	v_mov_b32_e32 v45, v0
	v_mov_b32_e32 v46, v0
	v_mov_b32_e32 v47, v0
	v_mov_b32_e32 v56, v0
	v_mov_b32_e32 v57, v0
	v_mov_b32_e32 v58, v0
	v_mov_b32_e32 v59, v0
	v_mov_b32_e32 v60, v0
	v_mov_b32_e32 v61, v0
	v_mov_b32_e32 v62, v0
	v_mov_b32_e32 v63, v0
	v_mov_b32_e32 v64, v0
	v_mov_b32_e32 v65, v0
	v_mov_b32_e32 v66, v0
	v_mov_b32_e32 v67, v0
	v_mov_b32_e32 v68, v0
	v_mov_b32_e32 v69, v0
	v_mov_b32_e32 v70, v0
	v_mov_b32_e32 v71, v0
	v_mov_b32_e32 v80, v0
	v_mov_b32_e32 v81, v0
	v_mov_b32_e32 v82, v0
	v_mov_b32_e32 v83, v0
	v_mov_b32_e32 v84, v0
	v_mov_b32_e32 v85, v0
	v_mov_b32_e32 v86, v0
	v_mov_b32_e32 v87, v0
	v_mov_b32_e32 v96, v0
	v_mov_b32_e32 v97, v0
	v_mov_b32_e32 v98, v0
	v_mov_b32_e32 v99, v0
	v_mov_b32_e32 v100, v0
	v_mov_b32_e32 v101, v0
	v_mov_b32_e32 v102, v0
	v_mov_b32_e32 v103, v0
	v_mov_b32_e32 v112, v0
	v_mov_b32_e32 v113, v0
	v_mov_b32_e32 v114, v0
	v_mov_b32_e32 v115, v0
	v_mov_b32_e32 v116, v0
	v_mov_b32_e32 v117, v0
	v_mov_b32_e32 v118, v0
	v_mov_b32_e32 v119, v0
	v_mov_b32_e32 v72, v0
	v_mov_b32_e32 v73, v0
	v_mov_b32_e32 v74, v0
	v_mov_b32_e32 v75, v0
	v_mov_b32_e32 v76, v0
	v_mov_b32_e32 v77, v0
	v_mov_b32_e32 v78, v0
	v_mov_b32_e32 v79, v0
	v_mov_b32_e32 v88, v0
	v_mov_b32_e32 v89, v0
	v_mov_b32_e32 v90, v0
	v_mov_b32_e32 v91, v0
	v_mov_b32_e32 v92, v0
	v_mov_b32_e32 v93, v0
	v_mov_b32_e32 v94, v0
	v_mov_b32_e32 v95, v0
	v_mov_b32_e32 v104, v0
	v_mov_b32_e32 v105, v0
	v_mov_b32_e32 v106, v0
	v_mov_b32_e32 v107, v0
	v_mov_b32_e32 v108, v0
	v_mov_b32_e32 v109, v0
	v_mov_b32_e32 v110, v0
	v_mov_b32_e32 v111, v0
	v_mov_b32_e32 v120, v0
	v_mov_b32_e32 v121, v0
	v_mov_b32_e32 v122, v0
	v_mov_b32_e32 v123, v0
	v_mov_b32_e32 v124, v0
	v_mov_b32_e32 v125, v0
	v_mov_b32_e32 v126, v0
	v_mov_b32_e32 v127, v0
	ds_read_b128 v[152:155], v149
	ds_read_b128 v[156:159], v149 offset:1024
	ds_read_b128 v[160:163], v149 offset:2048
	ds_read_b128 v[164:167], v149 offset:3072
.LBB1_1764:
	s_add_u32 s12, s10, 0xfff80080
	s_addc_u32 s13, s11, -1
	s_cmp_eq_u32 s3, 28
	s_cselect_b32 s15, s37, s13
	s_cselect_b32 s14, s38, s12
	s_cselect_b32 s13, s39, s48
	s_cselect_b32 s12, s45, s47
	s_add_i32 m0, s24, 0xc000
	ds_read_b128 v[168:171], v150
	ds_read_b128 v[172:175], v150 offset:1024
	ds_read_b128 v[176:179], v150 offset:2048
	ds_read_b128 v[180:183], v150 offset:3072
	ds_read_b128 v[184:187], v150 offset:4096
	ds_read_b128 v[188:191], v150 offset:5120
	ds_read_b128 v[192:195], v150 offset:6144
	ds_read_b128 v[198:201], v150 offset:7168
	global_load_lds_dwordx4 v138, s[10:11]
	s_add_i32 m0, s24, 0xe000
	s_nop 0
	global_load_lds_dwordx4 v136, s[10:11]
	s_waitcnt lgkmcnt(8)
	s_barrier
	s_setprio 1
	s_waitcnt lgkmcnt(7)
	v_mfma_f32_16x16x32_bf16 v[124:127], v[152:155], v[168:171], v[124:127]
	v_mfma_f32_16x16x32_bf16 v[120:123], v[160:163], v[168:171], v[120:123]
	s_waitcnt lgkmcnt(5)
	v_mfma_f32_16x16x32_bf16 v[108:111], v[152:155], v[176:179], v[108:111]
	v_mfma_f32_16x16x32_bf16 v[104:107], v[160:163], v[176:179], v[104:107]
	s_waitcnt lgkmcnt(3)
	v_mfma_f32_16x16x32_bf16 v[92:95], v[152:155], v[184:187], v[92:95]
	v_mfma_f32_16x16x32_bf16 v[88:91], v[160:163], v[184:187], v[88:91]
	s_waitcnt lgkmcnt(1)
	v_mfma_f32_16x16x32_bf16 v[76:79], v[152:155], v[192:195], v[76:79]
	v_mfma_f32_16x16x32_bf16 v[72:75], v[160:163], v[192:195], v[72:75]
	v_mfma_f32_16x16x32_bf16 v[124:127], v[156:159], v[172:175], v[124:127]
	v_mfma_f32_16x16x32_bf16 v[120:123], v[164:167], v[172:175], v[120:123]
	v_mfma_f32_16x16x32_bf16 v[108:111], v[156:159], v[180:183], v[108:111]
	v_mfma_f32_16x16x32_bf16 v[104:107], v[164:167], v[180:183], v[104:107]
	v_mfma_f32_16x16x32_bf16 v[92:95], v[156:159], v[188:191], v[92:95]
	v_mfma_f32_16x16x32_bf16 v[88:91], v[164:167], v[188:191], v[88:91]
	s_waitcnt lgkmcnt(0)
	v_mfma_f32_16x16x32_bf16 v[76:79], v[156:159], v[198:201], v[76:79]
	v_mfma_f32_16x16x32_bf16 v[72:75], v[164:167], v[198:201], v[72:75]
	s_setprio 0
	s_barrier
; #define PG8_STAGE(bufoff, gbase, voff) do { _Pragma("unroll") for (int _i = 0; _i < 2; ++_i) \
;         __builtin_amdgcn_global_load_lds((const unsigned*)((const char*)(gbase) + (voff)[_i]), (LAS unsigned*)(lds + (bufoff) + ldsw + _i * 8192), 16, 0, 0); } while (0)
; #define PG8_LDA(dst, b, h) do { _Pragma("unroll") for (int m = 0; m < 4; ++m) _Pragma("unroll") for (int k = 0; k < 2; ++k) dst[m][k] = *(const LAS bf16x8*)(lds + PG8_SA(b, h) + aoff + m * 2048 + k * 1024); } while (0)
; #define PG8_LDB(dst, b, h) do { _Pragma("unroll") for (int n = 0; n < 2; ++n) _Pragma("unroll") for (int k = 0; k < 2; ++k) dst[n][k] = *(const LAS bf16x8*)(lds + PG8_SB(b, h) + boff + n * 2048 + k * 1024); } while (0)
; #define PG8_MMA(ai, bj, At, Bt) do { __builtin_amdgcn_s_setprio(1); _Pragma("unroll") for (int m = 0; m < 4; ++m) _Pragma("unroll") for (int n = 0; n < 2; ++n) _Pragma("unroll") for (int k = 0; k < 2; ++k) \
;         acc[ai][bj][m][n] = __builtin_amdgcn_mfma_f32_16x16x32_bf16(Bt[n][k], At[m][k], acc[ai][bj][m][n], 0, 0, 0); __builtin_amdgcn_s_setprio(0); } while (0)
; #define PG8_WAIT_V(n) asm volatile("s_waitcnt vmcnt(" #n ")" ::: "memory")
; #define PG8_WAIT_L(n) asm volatile("s_waitcnt lgkmcnt(" #n ")" ::: "memory")
; #define PG8_BAR __builtin_amdgcn_s_barrier()
; #define PG8_SCHED __builtin_amdgcn_sched_barrier(0)
; template <class Map, class Epi>
; DI void gemm_phase(LAS unsigned char* lds, const Map& MP, const Epi& E, const int nM, const int nN, const int K, const int lda, const int ldb) {
;     ...
;             PG8_LDB(B1, 0, 1); PG8_STAGE(PG8_SB(0, 0), b2, voffB);
;             PG8_BAR; PG8_WAIT_L(0); PG8_MMA(0, 1, At, B1); PG8_BAR;
;             PG8_LDA(At, 0, 1); PG8_STAGE(PG8_SA(0, 0), a2, voffA);
;             PG8_BAR; PG8_WAIT_L(0); PG8_MMA(1, 0, At, B0); PG8_BAR; PG8_SCHED;
;             PG8_STAGE(PG8_SB(0, 1), b2 + hstepB, voffB);
;             PG8_WAIT_V(6); PG8_BAR; PG8_MMA(1, 1, At, B1); PG8_BAR;
;             PG8_LDB(B0, 1, 0); PG8_SCHED; PG8_LDA(At, 1, 0); PG8_STAGE(PG8_SA(0, 1), a2 + hstepA, voffA);
	s_add_i32 s49, s35, s22
	v_lshl_add_u64 v[144:145], s[12:13], 0, v[132:133]
	s_mov_b32 m0, s49
	ds_read_b128 v[202:205], v151
	ds_read_b128 v[206:209], v151 offset:1024
	ds_read_b128 v[210:213], v151 offset:2048
	ds_read_b128 v[214:217], v151 offset:3072
	global_load_lds_dwordx4 v[144:145], off
	v_lshl_add_u64 v[218:219], s[12:13], 0, v[128:129]
	s_add_i32 m0, s49, 0x2000
	s_nop 0
	global_load_lds_dwordx4 v[218:219], off
	s_barrier
	s_setprio 1
	s_waitcnt lgkmcnt(3)
	v_mfma_f32_16x16x32_bf16 v[116:119], v[202:205], v[168:171], v[116:119]
	s_waitcnt lgkmcnt(1)
	v_mfma_f32_16x16x32_bf16 v[112:115], v[210:213], v[168:171], v[112:115]
	v_mfma_f32_16x16x32_bf16 v[100:103], v[202:205], v[176:179], v[100:103]
	v_mfma_f32_16x16x32_bf16 v[96:99], v[210:213], v[176:179], v[96:99]
	v_mfma_f32_16x16x32_bf16 v[84:87], v[202:205], v[184:187], v[84:87]
	v_mfma_f32_16x16x32_bf16 v[80:83], v[210:213], v[184:187], v[80:83]
	v_mfma_f32_16x16x32_bf16 v[68:71], v[202:205], v[192:195], v[68:71]
	v_mfma_f32_16x16x32_bf16 v[64:67], v[210:213], v[192:195], v[64:67]
	v_mfma_f32_16x16x32_bf16 v[116:119], v[206:209], v[172:175], v[116:119]
	s_waitcnt lgkmcnt(0)
	v_mfma_f32_16x16x32_bf16 v[112:115], v[214:217], v[172:175], v[112:115]
	v_mfma_f32_16x16x32_bf16 v[100:103], v[206:209], v[180:183], v[100:103]
	v_mfma_f32_16x16x32_bf16 v[96:99], v[214:217], v[180:183], v[96:99]
	v_mfma_f32_16x16x32_bf16 v[84:87], v[206:209], v[188:191], v[84:87]
	v_mfma_f32_16x16x32_bf16 v[80:83], v[214:217], v[188:191], v[80:83]
	v_mfma_f32_16x16x32_bf16 v[68:71], v[206:209], v[198:201], v[68:71]
	v_mfma_f32_16x16x32_bf16 v[64:67], v[214:217], v[198:201], v[64:67]
	s_setprio 0
	s_mov_b32 m0, s24
	v_lshl_add_u64 v[220:221], s[14:15], 0, v[134:135]
	s_barrier
	ds_read_b128 v[168:171], v150 offset:16384
	ds_read_b128 v[172:175], v150 offset:17408
	ds_read_b128 v[176:179], v150 offset:18432
	ds_read_b128 v[180:183], v150 offset:19456
	ds_read_b128 v[184:187], v150 offset:20480
	ds_read_b128 v[188:191], v150 offset:21504
	ds_read_b128 v[192:195], v150 offset:22528
	ds_read_b128 v[198:201], v150 offset:23552
	global_load_lds_dwordx4 v[220:221], off
	v_lshl_add_u64 v[222:223], s[14:15], 0, v[130:131]
	s_mov_b32 m0, s9
	s_nop 0
	global_load_lds_dwordx4 v[222:223], off
	s_waitcnt vmcnt(10)
	s_barrier
	s_setprio 1
	s_waitcnt lgkmcnt(7)
	v_mfma_f32_16x16x32_bf16 v[60:63], v[152:155], v[168:171], v[60:63]
	v_mfma_f32_16x16x32_bf16 v[56:59], v[160:163], v[168:171], v[56:59]
	s_waitcnt lgkmcnt(5)
	v_mfma_f32_16x16x32_bf16 v[44:47], v[152:155], v[176:179], v[44:47]
	v_mfma_f32_16x16x32_bf16 v[40:43], v[160:163], v[176:179], v[40:43]
	s_waitcnt lgkmcnt(3)
	v_mfma_f32_16x16x32_bf16 v[28:31], v[152:155], v[184:187], v[28:31]
	v_mfma_f32_16x16x32_bf16 v[24:27], v[160:163], v[184:187], v[24:27]
	s_waitcnt lgkmcnt(1)
	v_mfma_f32_16x16x32_bf16 v[12:15], v[152:155], v[192:195], v[12:15]
	v_mfma_f32_16x16x32_bf16 v[8:11], v[160:163], v[192:195], v[8:11]
	v_mfma_f32_16x16x32_bf16 v[60:63], v[156:159], v[172:175], v[60:63]
	v_mfma_f32_16x16x32_bf16 v[56:59], v[164:167], v[172:175], v[56:59]
	v_mfma_f32_16x16x32_bf16 v[44:47], v[156:159], v[180:183], v[44:47]
	v_mfma_f32_16x16x32_bf16 v[40:43], v[164:167], v[180:183], v[40:43]
	v_mfma_f32_16x16x32_bf16 v[28:31], v[156:159], v[188:191], v[28:31]
	v_mfma_f32_16x16x32_bf16 v[24:27], v[164:167], v[188:191], v[24:27]
	s_waitcnt lgkmcnt(0)
	v_mfma_f32_16x16x32_bf16 v[12:15], v[156:159], v[198:201], v[12:15]
	v_mfma_f32_16x16x32_bf16 v[8:11], v[164:167], v[198:201], v[8:11]
	s_setprio 0
	s_barrier
	s_add_u32 s54, s12, 0x80000
	s_addc_u32 s55, s13, 0
	s_add_i32 s49, s36, s22
	s_mov_b32 m0, s49
	s_nop 0
	global_load_lds_dwordx4 v132, s[54:55]
	s_add_i32 m0, s49, 0x2000
	s_nop 0
	global_load_lds_dwordx4 v128, s[54:55]
	s_waitcnt vmcnt(6)
	s_barrier
	s_setprio 1
	v_mfma_f32_16x16x32_bf16 v[52:55], v[202:205], v[168:171], v[52:55]
	v_mfma_f32_16x16x32_bf16 v[48:51], v[210:213], v[168:171], v[48:51]
	s_add_i32 s49, 0, 0x18000
	v_add_u32_e32 v164, s49, v148
	ds_read_b128 v[152:155], v164
	v_mfma_f32_16x16x32_bf16 v[36:39], v[202:205], v[176:179], v[36:39]
	v_mfma_f32_16x16x32_bf16 v[32:35], v[210:213], v[176:179], v[32:35]
	ds_read_b128 v[156:159], v164 offset:1024
	v_mfma_f32_16x16x32_bf16 v[20:23], v[202:205], v[184:187], v[20:23]
	v_mfma_f32_16x16x32_bf16 v[16:19], v[210:213], v[184:187], v[16:19]
	ds_read_b128 v[160:163], v164 offset:2048
	v_mfma_f32_16x16x32_bf16 v[4:7], v[202:205], v[192:195], v[4:7]
	v_mfma_f32_16x16x32_bf16 v[0:3], v[210:213], v[192:195], v[0:3]
	ds_read_b128 v[164:167], v164 offset:3072
	v_mfma_f32_16x16x32_bf16 v[52:55], v[206:209], v[172:175], v[52:55]
	v_mfma_f32_16x16x32_bf16 v[48:51], v[214:217], v[172:175], v[48:51]
	v_mfma_f32_16x16x32_bf16 v[36:39], v[206:209], v[180:183], v[36:39]
	v_mfma_f32_16x16x32_bf16 v[32:35], v[214:217], v[180:183], v[32:35]
	v_mfma_f32_16x16x32_bf16 v[20:23], v[206:209], v[188:191], v[20:23]
	v_mfma_f32_16x16x32_bf16 v[16:19], v[214:217], v[188:191], v[16:19]
	v_mfma_f32_16x16x32_bf16 v[4:7], v[206:209], v[198:201], v[4:7]
	v_mfma_f32_16x16x32_bf16 v[0:3], v[214:217], v[198:201], v[0:3]
	s_setprio 0
	s_barrier
	s_add_u32 s14, s14, 0x80000
	s_addc_u32 s15, s15, 0
	s_mov_b32 m0, s25
	ds_read_b128 v[168:171], v150 offset:32768
	ds_read_b128 v[172:175], v150 offset:33792
	ds_read_b128 v[176:179], v150 offset:34816
	ds_read_b128 v[180:183], v150 offset:35840
	ds_read_b128 v[184:187], v150 offset:36864
	ds_read_b128 v[188:191], v150 offset:37888
	ds_read_b128 v[192:195], v150 offset:38912
	ds_read_b128 v[198:201], v150 offset:39936
	global_load_lds_dwordx4 v134, s[14:15]
	s_mov_b32 m0, s26
	s_nop 0
	global_load_lds_dwordx4 v130, s[14:15]
	s_waitcnt lgkmcnt(8)
	s_barrier
; #define PG8_STAGE(bufoff, gbase, voff) do { _Pragma("unroll") for (int _i = 0; _i < 2; ++_i) \
;         __builtin_amdgcn_global_load_lds((const unsigned*)((const char*)(gbase) + (voff)[_i]), (LAS unsigned*)(lds + (bufoff) + ldsw + _i * 8192), 16, 0, 0); } while (0)
; #define PG8_LDA(dst, b, h) do { _Pragma("unroll") for (int m = 0; m < 4; ++m) _Pragma("unroll") for (int k = 0; k < 2; ++k) dst[m][k] = *(const LAS bf16x8*)(lds + PG8_SA(b, h) + aoff + m * 2048 + k * 1024); } while (0)
; #define PG8_LDB(dst, b, h) do { _Pragma("unroll") for (int n = 0; n < 2; ++n) _Pragma("unroll") for (int k = 0; k < 2; ++k) dst[n][k] = *(const LAS bf16x8*)(lds + PG8_SB(b, h) + boff + n * 2048 + k * 1024); } while (0)
; #define PG8_MMA(ai, bj, At, Bt) do { __builtin_amdgcn_s_setprio(1); _Pragma("unroll") for (int m = 0; m < 4; ++m) _Pragma("unroll") for (int n = 0; n < 2; ++n) _Pragma("unroll") for (int k = 0; k < 2; ++k) \
;         acc[ai][bj][m][n] = __builtin_amdgcn_mfma_f32_16x16x32_bf16(Bt[n][k], At[m][k], acc[ai][bj][m][n], 0, 0, 0); __builtin_amdgcn_s_setprio(0); } while (0)
; #define PG8_WAIT_V(n) asm volatile("s_waitcnt vmcnt(" #n ")" ::: "memory")
; #define PG8_WAIT_L(n) asm volatile("s_waitcnt lgkmcnt(" #n ")" ::: "memory")
; #define PG8_BAR __builtin_amdgcn_s_barrier()
; #define PG8_SCHED __builtin_amdgcn_sched_barrier(0)
; template <class Map, class Epi>
; DI void gemm_phase(LAS unsigned char* lds, const Map& MP, const Epi& E, const int nM, const int nN, const int K, const int lda, const int ldb) {
;     ...
;             PG8_WAIT_L(8); PG8_BAR; PG8_WAIT_L(0); PG8_MMA(0, 0, At, B0); PG8_BAR; PG8_SCHED;
;             PG8_LDB(B1, 1, 1); PG8_STAGE(PG8_SB(1, 0), b3, voffB);
;             PG8_BAR; PG8_WAIT_L(0); PG8_MMA(0, 1, At, B1); PG8_BAR;
;             PG8_LDA(At, 1, 1); PG8_STAGE(PG8_SA(1, 0), a3, voffA);
;             PG8_BAR; PG8_WAIT_L(0); PG8_MMA(1, 0, At, B0); PG8_BAR; PG8_SCHED;
;             PG8_STAGE(PG8_SB(1, 1), b3 + hstepB, voffB);
;             PG8_WAIT_V(6); PG8_BAR; PG8_MMA(1, 1, At, B1); PG8_BAR;
	s_setprio 1
	s_waitcnt lgkmcnt(7)
	v_mfma_f32_16x16x32_bf16 v[124:127], v[152:155], v[168:171], v[124:127]
	v_mfma_f32_16x16x32_bf16 v[120:123], v[160:163], v[168:171], v[120:123]
	s_waitcnt lgkmcnt(5)
	v_mfma_f32_16x16x32_bf16 v[108:111], v[152:155], v[176:179], v[108:111]
	v_mfma_f32_16x16x32_bf16 v[104:107], v[160:163], v[176:179], v[104:107]
	s_waitcnt lgkmcnt(3)
	v_mfma_f32_16x16x32_bf16 v[92:95], v[152:155], v[184:187], v[92:95]
	v_mfma_f32_16x16x32_bf16 v[88:91], v[160:163], v[184:187], v[88:91]
	s_waitcnt lgkmcnt(1)
	v_mfma_f32_16x16x32_bf16 v[76:79], v[152:155], v[192:195], v[76:79]
	v_mfma_f32_16x16x32_bf16 v[72:75], v[160:163], v[192:195], v[72:75]
	v_mfma_f32_16x16x32_bf16 v[124:127], v[156:159], v[172:175], v[124:127]
	v_mfma_f32_16x16x32_bf16 v[120:123], v[164:167], v[172:175], v[120:123]
	v_mfma_f32_16x16x32_bf16 v[108:111], v[156:159], v[180:183], v[108:111]
	v_mfma_f32_16x16x32_bf16 v[104:107], v[164:167], v[180:183], v[104:107]
	v_mfma_f32_16x16x32_bf16 v[92:95], v[156:159], v[188:191], v[92:95]
	v_mfma_f32_16x16x32_bf16 v[88:91], v[164:167], v[188:191], v[88:91]
	s_waitcnt lgkmcnt(0)
	v_mfma_f32_16x16x32_bf16 v[76:79], v[156:159], v[198:201], v[76:79]
	v_mfma_f32_16x16x32_bf16 v[72:75], v[164:167], v[198:201], v[72:75]
	s_setprio 0
	s_barrier
	s_add_i32 s14, 0, 0x1c000
	s_add_i32 s15, s49, s22
	v_add_u32_e32 v196, s14, v148
	v_lshl_add_u64 v[144:145], v[144:145], 0, s[42:43]
	s_mov_b32 m0, s15
	ds_read_b128 v[202:205], v196
	ds_read_b128 v[206:209], v196 offset:1024
	ds_read_b128 v[210:213], v196 offset:2048
	ds_read_b128 v[214:217], v196 offset:3072
	global_load_lds_dwordx4 v[144:145], off
	v_lshl_add_u64 v[144:145], v[218:219], 0, s[42:43]
	s_add_i32 m0, s15, 0x2000
	s_nop 0
	global_load_lds_dwordx4 v[144:145], off
	s_barrier
	s_setprio 1
	s_waitcnt lgkmcnt(3)
	v_mfma_f32_16x16x32_bf16 v[116:119], v[202:205], v[168:171], v[116:119]
	s_waitcnt lgkmcnt(1)
	v_mfma_f32_16x16x32_bf16 v[112:115], v[210:213], v[168:171], v[112:115]
	v_mfma_f32_16x16x32_bf16 v[100:103], v[202:205], v[176:179], v[100:103]
	v_mfma_f32_16x16x32_bf16 v[96:99], v[210:213], v[176:179], v[96:99]
	v_mfma_f32_16x16x32_bf16 v[84:87], v[202:205], v[184:187], v[84:87]
	v_mfma_f32_16x16x32_bf16 v[80:83], v[210:213], v[184:187], v[80:83]
	v_mfma_f32_16x16x32_bf16 v[68:71], v[202:205], v[192:195], v[68:71]
	v_mfma_f32_16x16x32_bf16 v[64:67], v[210:213], v[192:195], v[64:67]
	v_mfma_f32_16x16x32_bf16 v[116:119], v[206:209], v[172:175], v[116:119]
	s_waitcnt lgkmcnt(0)
	v_mfma_f32_16x16x32_bf16 v[112:115], v[214:217], v[172:175], v[112:115]
	v_mfma_f32_16x16x32_bf16 v[100:103], v[206:209], v[180:183], v[100:103]
	v_mfma_f32_16x16x32_bf16 v[96:99], v[214:217], v[180:183], v[96:99]
	v_mfma_f32_16x16x32_bf16 v[84:87], v[206:209], v[188:191], v[84:87]
	v_mfma_f32_16x16x32_bf16 v[80:83], v[214:217], v[188:191], v[80:83]
	v_mfma_f32_16x16x32_bf16 v[68:71], v[206:209], v[198:201], v[68:71]
	v_mfma_f32_16x16x32_bf16 v[64:67], v[214:217], v[198:201], v[64:67]
	s_setprio 0
	s_mov_b32 m0, s30
	v_lshl_add_u64 v[144:145], v[220:221], 0, s[42:43]
	s_barrier
	ds_read_b128 v[168:171], v150 offset:49152
	ds_read_b128 v[172:175], v150 offset:50176
	ds_read_b128 v[176:179], v150 offset:51200
	ds_read_b128 v[180:183], v150 offset:52224
	ds_read_b128 v[184:187], v150 offset:53248
	ds_read_b128 v[188:191], v150 offset:54272
	ds_read_b128 v[192:195], v150 offset:55296
	ds_read_b128 v[198:201], v150 offset:56320
	global_load_lds_dwordx4 v[144:145], off
	v_lshl_add_u64 v[144:145], v[222:223], 0, s[42:43]
	s_mov_b32 m0, s31
	s_nop 0
	global_load_lds_dwordx4 v[144:145], off
	s_waitcnt vmcnt(10)
	s_barrier
	s_setprio 1
	s_waitcnt lgkmcnt(7)
	v_mfma_f32_16x16x32_bf16 v[60:63], v[152:155], v[168:171], v[60:63]
	v_mfma_f32_16x16x32_bf16 v[56:59], v[160:163], v[168:171], v[56:59]
	s_waitcnt lgkmcnt(5)
	v_mfma_f32_16x16x32_bf16 v[44:47], v[152:155], v[176:179], v[44:47]
	v_mfma_f32_16x16x32_bf16 v[40:43], v[160:163], v[176:179], v[40:43]
	s_waitcnt lgkmcnt(3)
	v_mfma_f32_16x16x32_bf16 v[28:31], v[152:155], v[184:187], v[28:31]
	v_mfma_f32_16x16x32_bf16 v[24:27], v[160:163], v[184:187], v[24:27]
	s_waitcnt lgkmcnt(1)
	v_mfma_f32_16x16x32_bf16 v[12:15], v[152:155], v[192:195], v[12:15]
	v_mfma_f32_16x16x32_bf16 v[8:11], v[160:163], v[192:195], v[8:11]
	v_mfma_f32_16x16x32_bf16 v[60:63], v[156:159], v[172:175], v[60:63]
	v_mfma_f32_16x16x32_bf16 v[56:59], v[164:167], v[172:175], v[56:59]
	v_mfma_f32_16x16x32_bf16 v[44:47], v[156:159], v[180:183], v[44:47]
	v_mfma_f32_16x16x32_bf16 v[40:43], v[164:167], v[180:183], v[40:43]
	v_mfma_f32_16x16x32_bf16 v[28:31], v[156:159], v[188:191], v[28:31]
	v_mfma_f32_16x16x32_bf16 v[24:27], v[164:167], v[188:191], v[24:27]
	s_waitcnt lgkmcnt(0)
	v_mfma_f32_16x16x32_bf16 v[12:15], v[156:159], v[198:201], v[12:15]
	v_mfma_f32_16x16x32_bf16 v[8:11], v[164:167], v[198:201], v[8:11]
	s_setprio 0
	s_barrier
	s_add_u32 s12, s12, 0x80080
	s_addc_u32 s13, s13, 0
	s_add_i32 s14, s14, s22
	s_mov_b32 m0, s14
	s_nop 0
	global_load_lds_dwordx4 v132, s[12:13]
	s_add_i32 m0, s14, 0x2000
	s_nop 0
	global_load_lds_dwordx4 v128, s[12:13]
	s_waitcnt vmcnt(6)
	s_barrier
; DI unsigned pack2(float a, float b) { f32x2 v = {a, b}; hwbf16x2 r = __builtin_convertvector(v, hwbf16x2); return __builtin_bit_cast(unsigned, r); }
; DI float bflo(unsigned w) { return __uint_as_float(w << 16); }
; DI float bfhi(unsigned w) { return __uint_as_float(w & 0xffff0000u); }
; #define PG8_MMA(ai, bj, At, Bt) do { __builtin_amdgcn_s_setprio(1); _Pragma("unroll") for (int m = 0; m < 4; ++m) _Pragma("unroll") for (int n = 0; n < 2; ++n) _Pragma("unroll") for (int k = 0; k < 2; ++k) \
;         acc[ai][bj][m][n] = __builtin_amdgcn_mfma_f32_16x16x32_bf16(Bt[n][k], At[m][k], acc[ai][bj][m][n], 0, 0, 0); __builtin_amdgcn_s_setprio(0); } while (0)
; #define PG8_BAR __builtin_amdgcn_s_barrier()
;     DI void operator()(const f32x4 (&acc)[2][2][4][2], const Unit& u, int wr, int wc, int fr, int fq) const {
;     ...
;         for (int ai = 0; ai < 2; ++ai)
; #pragma unroll
;             for (int m = 0; m < 4; ++m) { const size_t ro = (size_t)(row0 + ai * HALF + m * 16) * D + col0;
; #pragma unroll
;                 for (int bj = 0; bj < 2; ++bj) {
;                     f32x4 x0, x1;
;                     if constexpr (IB) { const u32x4 w = *(const u32x4*)((const bf16_t*)Xin + ro + bj * HALF);
;                         x0 = (f32x4){bflo(w[0]), bfhi(w[0]), bflo(w[1]), bfhi(w[1])}; x1 = (f32x4){bflo(w[2]), bfhi(w[2]), bflo(w[3]), bfhi(w[3])}; }
;                     else { x0 = *(const f32x4*)((const float*)Xin + ro + bj * HALF); x1 = *(const f32x4*)((const float*)Xin + ro + bj * HALF + 4); }
;                     x0 += acc[ai][bj][m][0] * sc[bj][0]; x1 += acc[ai][bj][m][1] * sc[bj][1];
;                     if constexpr (OB) { u32x4 o; o[0] = pack2(x0[0], x0[1]); o[1] = pack2(x0[2], x0[3]); o[2] = pack2(x1[0], x1[1]); o[3] = pack2(x1[2], x1[3]);
;                         *(u32x4*)((bf16_t*)Xout + ro + bj * HALF) = o; }
;                     else { *(f32x4*)((float*)Xout + ro + bj * HALF) = x0; *(f32x4*)((float*)Xout + ro + bj * HALF + 4) = x1; } } }
; template <class Map, class Epi>
; DI void gemm_phase(LAS unsigned char* lds, const Map& MP, const Epi& E, const int nM, const int nN, const int K, const int lda, const int ldb) {
;     ...
;             PG8_WAIT_V(6); PG8_BAR; PG8_MMA(1, 1, At, B1); PG8_BAR;
;         }
;         { int frr = fr, fqq = fq; asm volatile("" : "+v"(frr), "+v"(fqq)); E(acc, cur, wr, wc, frr, fqq); }
;         if (!has_next) break;
	s_setprio 1
	v_mfma_f32_16x16x32_bf16 v[52:55], v[202:205], v[168:171], v[52:55]
	v_mfma_f32_16x16x32_bf16 v[48:51], v[210:213], v[168:171], v[48:51]
	ds_read_b128 v[152:155], v149
	v_mfma_f32_16x16x32_bf16 v[36:39], v[202:205], v[176:179], v[36:39]
	v_mfma_f32_16x16x32_bf16 v[32:35], v[210:213], v[176:179], v[32:35]
	ds_read_b128 v[156:159], v149 offset:1024
	v_mfma_f32_16x16x32_bf16 v[20:23], v[202:205], v[184:187], v[20:23]
	v_mfma_f32_16x16x32_bf16 v[16:19], v[210:213], v[184:187], v[16:19]
	ds_read_b128 v[160:163], v149 offset:2048
	v_mfma_f32_16x16x32_bf16 v[4:7], v[202:205], v[192:195], v[4:7]
	v_mfma_f32_16x16x32_bf16 v[0:3], v[210:213], v[192:195], v[0:3]
	ds_read_b128 v[164:167], v149 offset:3072
	v_mfma_f32_16x16x32_bf16 v[52:55], v[206:209], v[172:175], v[52:55]
	v_mfma_f32_16x16x32_bf16 v[48:51], v[214:217], v[172:175], v[48:51]
	v_mfma_f32_16x16x32_bf16 v[36:39], v[206:209], v[180:183], v[36:39]
	v_mfma_f32_16x16x32_bf16 v[32:35], v[214:217], v[180:183], v[32:35]
	v_mfma_f32_16x16x32_bf16 v[20:23], v[206:209], v[188:191], v[20:23]
	v_mfma_f32_16x16x32_bf16 v[16:19], v[214:217], v[188:191], v[16:19]
	v_mfma_f32_16x16x32_bf16 v[4:7], v[206:209], v[198:201], v[4:7]
	v_mfma_f32_16x16x32_bf16 v[0:3], v[214:217], v[198:201], v[0:3]
	s_setprio 0
	s_add_i32 s3, s3, 2
	s_add_u32 s47, s47, 0x100
	s_addc_u32 s48, s48, 0
	s_add_u32 s10, s10, 0x100
	s_addc_u32 s11, s11, 0
	s_cmp_gt_u32 s3, 29
	s_barrier
	s_cbranch_scc0 .LBB1_1764
	s_waitcnt lgkmcnt(0)
	v_mov_b32_e32 v152, v147
	v_mov_b32_e32 v144, v146
	s_lshl_b32 s2, s2, 8
	s_or_b32 s2, s2, s29
	v_lshl_add_u32 v144, v144, 3, s2
	s_lshl_b32 s2, s8, 8
	s_add_i32 s2, s2, s28
	v_add_u32_e32 v152, s2, v152
	v_ashrrev_i32_e32 v153, 31, v152
	v_lshlrev_b64 v[152:153], 12, v[152:153]
	v_ashrrev_i32_e32 v145, 31, v144
	v_lshl_add_u64 v[152:153], s[4:5], 0, v[152:153]
	v_lshl_add_u64 v[144:145], v[144:145], 1, v[152:153]
	global_load_dwordx4 v[160:163], v[144:145], off
	global_load_dwordx4 v[164:167], v[144:145], off offset:256
	s_mov_b64 s[98:99], 0x10000
	v_lshl_add_u64 v[154:155], v[144:145], 0, s[98:99]
	global_load_dwordx4 v[168:171], v[154:155], off
	global_load_dwordx4 v[172:175], v[154:155], off offset:256
	s_mov_b64 s[98:99], 0x20000
	v_lshl_add_u64 v[154:155], v[144:145], 0, s[98:99]
	global_load_dwordx4 v[176:179], v[154:155], off
	global_load_dwordx4 v[180:183], v[154:155], off offset:256
	s_mov_b64 s[98:99], 0x30000
	v_lshl_add_u64 v[154:155], v[144:145], 0, s[98:99]
	global_load_dwordx4 v[184:187], v[154:155], off
	global_load_dwordx4 v[188:191], v[154:155], off offset:256
	s_mov_b64 s[98:99], 0x80000
	v_lshl_add_u64 v[154:155], v[144:145], 0, s[98:99]
	global_load_dwordx4 v[192:195], v[154:155], off
	global_load_dwordx4 v[198:201], v[154:155], off offset:256
	s_mov_b64 s[98:99], 0x90000
	v_lshl_add_u64 v[154:155], v[144:145], 0, s[98:99]
	global_load_dwordx4 v[202:205], v[154:155], off
	global_load_dwordx4 v[206:209], v[154:155], off offset:256
	s_mov_b64 s[98:99], 0xa0000
	v_lshl_add_u64 v[154:155], v[144:145], 0, s[98:99]
	global_load_dwordx4 v[210:213], v[154:155], off
	global_load_dwordx4 v[214:217], v[154:155], off offset:256
	s_mov_b64 s[98:99], 0xb0000
	v_lshl_add_u64 v[154:155], v[144:145], 0, s[98:99]
	global_load_dwordx4 v[248:251], v[154:155], off
	global_load_dwordx4 v[252:255], v[154:155], off offset:256
	s_waitcnt vmcnt(15)
	s_nop 1
	v_mov_b32_e32 v152, v160
	v_mov_b32_e32 v153, v161
	v_mov_b32_e32 v154, v162
	v_mov_b32_e32 v155, v163
	s_mov_b64 s[2:3], 0x10000
	s_mov_b32 s8, s46
	s_mov_b64 s[10:11], s[6:7]
	s_mov_b64 s[12:13], s[52:53]
	s_waitcnt lgkmcnt(0)
	v_lshlrev_b32_e32 v156, 16, v152
	v_and_b32_e32 v157, 0xffff0000, v152
	v_lshlrev_b32_e32 v152, 16, v153
	v_and_b32_e32 v153, 0xffff0000, v153
	v_lshlrev_b32_e32 v158, 16, v154
	v_and_b32_e32 v159, 0xffff0000, v154
	v_lshlrev_b32_e32 v154, 16, v155
	v_and_b32_e32 v155, 0xffff0000, v155
	v_pk_add_f32 v[126:127], v[126:127], v[152:153]
	v_pk_add_f32 v[124:125], v[124:125], v[156:157]
	v_pk_add_f32 v[152:153], v[122:123], v[154:155]
	v_pk_add_f32 v[122:123], v[120:121], v[158:159]
	v_cvt_pk_bf16_f32 v120, v124, v125
	v_cvt_pk_bf16_f32 v121, v126, v127
	v_cvt_pk_bf16_f32 v122, v122, v123
	v_cvt_pk_bf16_f32 v123, v152, v153
	global_store_dwordx4 v[144:145], v[120:123], off
	s_waitcnt vmcnt(15)
	s_nop 1
	v_mov_b32_e32 v120, v164
	v_mov_b32_e32 v121, v165
	v_mov_b32_e32 v122, v166
	v_mov_b32_e32 v123, v167
	s_waitcnt lgkmcnt(0)
	v_lshlrev_b32_e32 v124, 16, v120
	v_and_b32_e32 v125, 0xffff0000, v120
	v_lshlrev_b32_e32 v120, 16, v121
	v_and_b32_e32 v121, 0xffff0000, v121
	v_lshlrev_b32_e32 v126, 16, v122
	v_and_b32_e32 v127, 0xffff0000, v122
	v_lshlrev_b32_e32 v122, 16, v123
	v_and_b32_e32 v123, 0xffff0000, v123
	v_pk_add_f32 v[116:117], v[116:117], v[124:125]
	v_pk_add_f32 v[118:119], v[118:119], v[120:121]
	v_pk_add_f32 v[120:121], v[114:115], v[122:123]
	v_pk_add_f32 v[114:115], v[112:113], v[126:127]
	v_cvt_pk_bf16_f32 v112, v116, v117
	v_lshl_add_u64 v[116:117], v[144:145], 0, s[2:3]
	s_mov_b32 s2, 0x10000
	v_cvt_pk_bf16_f32 v113, v118, v119
	v_add_co_u32_e32 v118, vcc, s2, v144
	v_cvt_pk_bf16_f32 v114, v114, v115
	v_cvt_pk_bf16_f32 v115, v120, v121
	v_addc_co_u32_e32 v119, vcc, 0, v145, vcc
	global_store_dwordx4 v[144:145], v[112:115], off offset:256
	s_waitcnt vmcnt(15)
	s_nop 1
	v_mov_b32_e32 v112, v168
	v_mov_b32_e32 v113, v169
	v_mov_b32_e32 v114, v170
	v_mov_b32_e32 v115, v171
	s_mov_b64 s[2:3], 0x20000
	s_waitcnt lgkmcnt(0)
; DI unsigned pack2(float a, float b) { f32x2 v = {a, b}; hwbf16x2 r = __builtin_convertvector(v, hwbf16x2); return __builtin_bit_cast(unsigned, r); }
; DI float bflo(unsigned w) { return __uint_as_float(w << 16); }
; DI float bfhi(unsigned w) { return __uint_as_float(w & 0xffff0000u); }
;     DI void operator()(const f32x4 (&acc)[2][2][4][2], const Unit& u, int wr, int wc, int fr, int fq) const {
;     ...
;         for (int ai = 0; ai < 2; ++ai)
; #pragma unroll
;             for (int m = 0; m < 4; ++m) { const size_t ro = (size_t)(row0 + ai * HALF + m * 16) * D + col0;
; #pragma unroll
;                 for (int bj = 0; bj < 2; ++bj) {
;                     f32x4 x0, x1;
;                     if constexpr (IB) { const u32x4 w = *(const u32x4*)((const bf16_t*)Xin + ro + bj * HALF);
;                         x0 = (f32x4){bflo(w[0]), bfhi(w[0]), bflo(w[1]), bfhi(w[1])}; x1 = (f32x4){bflo(w[2]), bfhi(w[2]), bflo(w[3]), bfhi(w[3])}; }
;                     else { x0 = *(const f32x4*)((const float*)Xin + ro + bj * HALF); x1 = *(const f32x4*)((const float*)Xin + ro + bj * HALF + 4); }
;                     x0 += acc[ai][bj][m][0] * sc[bj][0]; x1 += acc[ai][bj][m][1] * sc[bj][1];
;                     if constexpr (OB) { u32x4 o; o[0] = pack2(x0[0], x0[1]); o[1] = pack2(x0[2], x0[3]); o[2] = pack2(x1[0], x1[1]); o[3] = pack2(x1[2], x1[3]);
;                         *(u32x4*)((bf16_t*)Xout + ro + bj * HALF) = o; }
;                     else { *(f32x4*)((float*)Xout + ro + bj * HALF) = x0; *(f32x4*)((float*)Xout + ro + bj * HALF + 4) = x1; } } }
	v_lshlrev_b32_e32 v120, 16, v112
	v_and_b32_e32 v121, 0xffff0000, v112
	v_lshlrev_b32_e32 v112, 16, v113
	v_and_b32_e32 v113, 0xffff0000, v113
	v_lshlrev_b32_e32 v122, 16, v114
	v_and_b32_e32 v123, 0xffff0000, v114
	v_lshlrev_b32_e32 v114, 16, v115
	v_and_b32_e32 v115, 0xffff0000, v115
	v_pk_add_f32 v[110:111], v[110:111], v[112:113]
	v_pk_add_f32 v[108:109], v[108:109], v[120:121]
	v_pk_add_f32 v[112:113], v[106:107], v[114:115]
	v_pk_add_f32 v[106:107], v[104:105], v[122:123]
	v_cvt_pk_bf16_f32 v104, v108, v109
	v_cvt_pk_bf16_f32 v105, v110, v111
	v_cvt_pk_bf16_f32 v106, v106, v107
	v_cvt_pk_bf16_f32 v107, v112, v113
	global_store_dwordx4 v[118:119], v[104:107], off
	s_waitcnt vmcnt(15)
	s_nop 1
	v_mov_b32_e32 v104, v172
	v_mov_b32_e32 v105, v173
	v_mov_b32_e32 v106, v174
	v_mov_b32_e32 v107, v175
	s_waitcnt lgkmcnt(0)
	v_lshlrev_b32_e32 v108, 16, v104
	v_and_b32_e32 v109, 0xffff0000, v104
	v_lshlrev_b32_e32 v104, 16, v105
	v_and_b32_e32 v105, 0xffff0000, v105
	v_lshlrev_b32_e32 v110, 16, v106
	v_and_b32_e32 v111, 0xffff0000, v106
	v_lshlrev_b32_e32 v106, 16, v107
	v_and_b32_e32 v107, 0xffff0000, v107
	v_pk_add_f32 v[100:101], v[100:101], v[108:109]
	v_pk_add_f32 v[102:103], v[102:103], v[104:105]
	v_pk_add_f32 v[104:105], v[98:99], v[106:107]
	v_pk_add_f32 v[98:99], v[96:97], v[110:111]
	v_cvt_pk_bf16_f32 v96, v100, v101
	v_lshl_add_u64 v[100:101], v[144:145], 0, s[2:3]
	s_mov_b32 s2, 0x20000
	v_cvt_pk_bf16_f32 v97, v102, v103
	v_add_co_u32_e32 v102, vcc, s2, v144
	v_cvt_pk_bf16_f32 v98, v98, v99
	v_cvt_pk_bf16_f32 v99, v104, v105
	v_addc_co_u32_e32 v103, vcc, 0, v145, vcc
	global_store_dwordx4 v[116:117], v[96:99], off offset:256
	s_waitcnt vmcnt(15)
	s_nop 1
	v_mov_b32_e32 v96, v176
	v_mov_b32_e32 v97, v177
	v_mov_b32_e32 v98, v178
	v_mov_b32_e32 v99, v179
	s_mov_b64 s[2:3], 0x30000
	s_waitcnt lgkmcnt(0)
	v_lshlrev_b32_e32 v104, 16, v96
	v_and_b32_e32 v105, 0xffff0000, v96
	v_lshlrev_b32_e32 v96, 16, v97
	v_and_b32_e32 v97, 0xffff0000, v97
	v_lshlrev_b32_e32 v106, 16, v98
	v_and_b32_e32 v107, 0xffff0000, v98
	v_lshlrev_b32_e32 v98, 16, v99
	v_and_b32_e32 v99, 0xffff0000, v99
	v_pk_add_f32 v[94:95], v[94:95], v[96:97]
	v_pk_add_f32 v[92:93], v[92:93], v[104:105]
	v_pk_add_f32 v[96:97], v[90:91], v[98:99]
	v_pk_add_f32 v[90:91], v[88:89], v[106:107]
	v_cvt_pk_bf16_f32 v88, v92, v93
	v_cvt_pk_bf16_f32 v89, v94, v95
	v_cvt_pk_bf16_f32 v90, v90, v91
	v_cvt_pk_bf16_f32 v91, v96, v97
	global_store_dwordx4 v[102:103], v[88:91], off
	s_waitcnt vmcnt(15)
	s_nop 1
	v_mov_b32_e32 v88, v180
	v_mov_b32_e32 v89, v181
	v_mov_b32_e32 v90, v182
	v_mov_b32_e32 v91, v183
	s_waitcnt lgkmcnt(0)
	v_lshlrev_b32_e32 v92, 16, v88
	v_and_b32_e32 v93, 0xffff0000, v88
	v_lshlrev_b32_e32 v88, 16, v89
	v_and_b32_e32 v89, 0xffff0000, v89
	v_lshlrev_b32_e32 v94, 16, v90
	v_and_b32_e32 v95, 0xffff0000, v90
	v_lshlrev_b32_e32 v90, 16, v91
	v_and_b32_e32 v91, 0xffff0000, v91
	v_pk_add_f32 v[86:87], v[86:87], v[88:89]
	v_pk_add_f32 v[84:85], v[84:85], v[92:93]
	v_pk_add_f32 v[88:89], v[82:83], v[90:91]
	v_pk_add_f32 v[82:83], v[80:81], v[94:95]
	v_cvt_pk_bf16_f32 v80, v84, v85
	v_cvt_pk_bf16_f32 v81, v86, v87
	v_cvt_pk_bf16_f32 v82, v82, v83
	v_cvt_pk_bf16_f32 v83, v88, v89
	global_store_dwordx4 v[100:101], v[80:83], off offset:256
	s_nop 1
	v_lshl_add_u64 v[80:81], v[144:145], 0, s[2:3]
	s_mov_b32 s2, 0x30000
	v_add_co_u32_e32 v86, vcc, s2, v144
	s_mov_b64 s[2:3], 0x80000
	s_nop 0
	v_addc_co_u32_e32 v87, vcc, 0, v145, vcc
	s_waitcnt vmcnt(15)
	s_nop 1
	v_mov_b32_e32 v82, v184
	v_mov_b32_e32 v83, v185
	v_mov_b32_e32 v84, v186
	v_mov_b32_e32 v85, v187
	s_waitcnt lgkmcnt(0)
	v_lshlrev_b32_e32 v88, 16, v82
	v_and_b32_e32 v89, 0xffff0000, v82
	v_lshlrev_b32_e32 v82, 16, v83
	v_and_b32_e32 v83, 0xffff0000, v83
	v_lshlrev_b32_e32 v90, 16, v84
	v_and_b32_e32 v91, 0xffff0000, v84
	v_lshlrev_b32_e32 v84, 16, v85
	v_and_b32_e32 v85, 0xffff0000, v85
	v_pk_add_f32 v[78:79], v[78:79], v[82:83]
	v_pk_add_f32 v[76:77], v[76:77], v[88:89]
	v_pk_add_f32 v[82:83], v[74:75], v[84:85]
	v_pk_add_f32 v[74:75], v[72:73], v[90:91]
	v_cvt_pk_bf16_f32 v72, v76, v77
	v_cvt_pk_bf16_f32 v73, v78, v79
	v_cvt_pk_bf16_f32 v74, v74, v75
	v_cvt_pk_bf16_f32 v75, v82, v83
	global_store_dwordx4 v[86:87], v[72:75], off
	s_waitcnt vmcnt(15)
	s_nop 1
	v_mov_b32_e32 v72, v188
	v_mov_b32_e32 v73, v189
	v_mov_b32_e32 v74, v190
	v_mov_b32_e32 v75, v191
	s_waitcnt lgkmcnt(0)
	v_lshlrev_b32_e32 v76, 16, v72
	v_and_b32_e32 v77, 0xffff0000, v72
	v_lshlrev_b32_e32 v72, 16, v73
	v_and_b32_e32 v73, 0xffff0000, v73
	v_lshlrev_b32_e32 v78, 16, v74
	v_and_b32_e32 v79, 0xffff0000, v74
	v_lshlrev_b32_e32 v74, 16, v75
	v_and_b32_e32 v75, 0xffff0000, v75
	v_pk_add_f32 v[70:71], v[70:71], v[72:73]
	v_pk_add_f32 v[68:69], v[68:69], v[76:77]
	v_pk_add_f32 v[72:73], v[66:67], v[74:75]
	v_pk_add_f32 v[66:67], v[64:65], v[78:79]
	v_cvt_pk_bf16_f32 v64, v68, v69
	v_cvt_pk_bf16_f32 v65, v70, v71
	v_cvt_pk_bf16_f32 v66, v66, v67
	v_cvt_pk_bf16_f32 v67, v72, v73
	global_store_dwordx4 v[80:81], v[64:67], off offset:256
	s_nop 1
	v_lshl_add_u64 v[64:65], v[144:145], 0, s[2:3]
	s_mov_b32 s2, 0x80000
	v_add_co_u32_e32 v70, vcc, s2, v144
	s_mov_b64 s[2:3], 0x90000
	s_nop 0
	v_addc_co_u32_e32 v71, vcc, 0, v145, vcc
	s_waitcnt vmcnt(15)
	s_nop 1
	v_mov_b32_e32 v66, v192
	v_mov_b32_e32 v67, v193
	v_mov_b32_e32 v68, v194
	v_mov_b32_e32 v69, v195
	s_waitcnt lgkmcnt(0)
; DI unsigned pack2(float a, float b) { f32x2 v = {a, b}; hwbf16x2 r = __builtin_convertvector(v, hwbf16x2); return __builtin_bit_cast(unsigned, r); }
; DI float bflo(unsigned w) { return __uint_as_float(w << 16); }
; DI float bfhi(unsigned w) { return __uint_as_float(w & 0xffff0000u); }
; #define PG8_WAIT_V(n) asm volatile("s_waitcnt vmcnt(" #n ")" ::: "memory")
; #define PG8_BAR __builtin_amdgcn_s_barrier()
;     DI void operator()(const f32x4 (&acc)[2][2][4][2], const Unit& u, int wr, int wc, int fr, int fq) const {
;     ...
;         for (int ai = 0; ai < 2; ++ai)
; #pragma unroll
;             for (int m = 0; m < 4; ++m) { const size_t ro = (size_t)(row0 + ai * HALF + m * 16) * D + col0;
; #pragma unroll
;                 for (int bj = 0; bj < 2; ++bj) {
;                     f32x4 x0, x1;
;                     if constexpr (IB) { const u32x4 w = *(const u32x4*)((const bf16_t*)Xin + ro + bj * HALF);
;                         x0 = (f32x4){bflo(w[0]), bfhi(w[0]), bflo(w[1]), bfhi(w[1])}; x1 = (f32x4){bflo(w[2]), bfhi(w[2]), bflo(w[3]), bfhi(w[3])}; }
;                     else { x0 = *(const f32x4*)((const float*)Xin + ro + bj * HALF); x1 = *(const f32x4*)((const float*)Xin + ro + bj * HALF + 4); }
;                     x0 += acc[ai][bj][m][0] * sc[bj][0]; x1 += acc[ai][bj][m][1] * sc[bj][1];
;                     if constexpr (OB) { u32x4 o; o[0] = pack2(x0[0], x0[1]); o[1] = pack2(x0[2], x0[3]); o[2] = pack2(x1[0], x1[1]); o[3] = pack2(x1[2], x1[3]);
;                         *(u32x4*)((bf16_t*)Xout + ro + bj * HALF) = o; }
;                     else { *(f32x4*)((float*)Xout + ro + bj * HALF) = x0; *(f32x4*)((float*)Xout + ro + bj * HALF + 4) = x1; } } }
; template <class Map, class Epi>
; DI void gemm_phase(LAS unsigned char* lds, const Map& MP, const Epi& E, const int nM, const int nN, const int K, const int lda, const int ldb) {
;     ...
;     PG8_WAIT_V(0);
;     if (wr == 0) PG8_BAR;
;     PG8_BAR;
	v_lshlrev_b32_e32 v72, 16, v66
	v_and_b32_e32 v73, 0xffff0000, v66
	v_lshlrev_b32_e32 v66, 16, v67
	v_and_b32_e32 v67, 0xffff0000, v67
	v_lshlrev_b32_e32 v74, 16, v68
	v_and_b32_e32 v75, 0xffff0000, v68
	v_lshlrev_b32_e32 v68, 16, v69
	v_and_b32_e32 v69, 0xffff0000, v69
	v_pk_add_f32 v[62:63], v[62:63], v[66:67]
	v_pk_add_f32 v[60:61], v[60:61], v[72:73]
	v_pk_add_f32 v[66:67], v[58:59], v[68:69]
	v_pk_add_f32 v[58:59], v[56:57], v[74:75]
	v_cvt_pk_bf16_f32 v56, v60, v61
	v_cvt_pk_bf16_f32 v57, v62, v63
	v_cvt_pk_bf16_f32 v58, v58, v59
	v_cvt_pk_bf16_f32 v59, v66, v67
	global_store_dwordx4 v[70:71], v[56:59], off
	s_waitcnt vmcnt(15)
	s_nop 1
	v_mov_b32_e32 v56, v198
	v_mov_b32_e32 v57, v199
	v_mov_b32_e32 v58, v200
	v_mov_b32_e32 v59, v201
	s_waitcnt lgkmcnt(0)
	v_lshlrev_b32_e32 v60, 16, v56
	v_and_b32_e32 v61, 0xffff0000, v56
	v_lshlrev_b32_e32 v56, 16, v57
	v_and_b32_e32 v57, 0xffff0000, v57
	v_lshlrev_b32_e32 v62, 16, v58
	v_and_b32_e32 v63, 0xffff0000, v58
	v_lshlrev_b32_e32 v58, 16, v59
	v_and_b32_e32 v59, 0xffff0000, v59
	v_pk_add_f32 v[54:55], v[54:55], v[56:57]
	v_pk_add_f32 v[52:53], v[52:53], v[60:61]
	v_pk_add_f32 v[56:57], v[50:51], v[58:59]
	v_pk_add_f32 v[50:51], v[48:49], v[62:63]
	v_cvt_pk_bf16_f32 v48, v52, v53
	v_cvt_pk_bf16_f32 v49, v54, v55
	v_cvt_pk_bf16_f32 v50, v50, v51
	v_cvt_pk_bf16_f32 v51, v56, v57
	global_store_dwordx4 v[64:65], v[48:51], off offset:256
	s_nop 1
	v_lshl_add_u64 v[48:49], v[144:145], 0, s[2:3]
	s_mov_b32 s2, 0x90000
	v_add_co_u32_e32 v54, vcc, s2, v144
	s_mov_b64 s[2:3], 0xa0000
	s_nop 0
	v_addc_co_u32_e32 v55, vcc, 0, v145, vcc
	s_waitcnt vmcnt(15)
	s_nop 1
	v_mov_b32_e32 v50, v202
	v_mov_b32_e32 v51, v203
	v_mov_b32_e32 v52, v204
	v_mov_b32_e32 v53, v205
	s_waitcnt lgkmcnt(0)
	v_lshlrev_b32_e32 v56, 16, v50
	v_and_b32_e32 v57, 0xffff0000, v50
	v_lshlrev_b32_e32 v50, 16, v51
	v_and_b32_e32 v51, 0xffff0000, v51
	v_lshlrev_b32_e32 v58, 16, v52
	v_and_b32_e32 v59, 0xffff0000, v52
	v_lshlrev_b32_e32 v52, 16, v53
	v_and_b32_e32 v53, 0xffff0000, v53
	v_pk_add_f32 v[46:47], v[46:47], v[50:51]
	v_pk_add_f32 v[44:45], v[44:45], v[56:57]
	v_pk_add_f32 v[50:51], v[42:43], v[52:53]
	v_pk_add_f32 v[42:43], v[40:41], v[58:59]
	v_cvt_pk_bf16_f32 v40, v44, v45
	v_cvt_pk_bf16_f32 v41, v46, v47
	v_cvt_pk_bf16_f32 v42, v42, v43
	v_cvt_pk_bf16_f32 v43, v50, v51
	global_store_dwordx4 v[54:55], v[40:43], off
	s_waitcnt vmcnt(15)
	s_nop 1
	v_mov_b32_e32 v40, v206
	v_mov_b32_e32 v41, v207
	v_mov_b32_e32 v42, v208
	v_mov_b32_e32 v43, v209
	s_waitcnt lgkmcnt(0)
	v_lshlrev_b32_e32 v44, 16, v40
	v_and_b32_e32 v45, 0xffff0000, v40
	v_lshlrev_b32_e32 v40, 16, v41
	v_and_b32_e32 v41, 0xffff0000, v41
	v_lshlrev_b32_e32 v46, 16, v42
	v_and_b32_e32 v47, 0xffff0000, v42
	v_lshlrev_b32_e32 v42, 16, v43
	v_and_b32_e32 v43, 0xffff0000, v43
	v_pk_add_f32 v[38:39], v[38:39], v[40:41]
	v_pk_add_f32 v[36:37], v[36:37], v[44:45]
	v_pk_add_f32 v[40:41], v[34:35], v[42:43]
	v_pk_add_f32 v[34:35], v[32:33], v[46:47]
	v_cvt_pk_bf16_f32 v32, v36, v37
	v_cvt_pk_bf16_f32 v33, v38, v39
	v_cvt_pk_bf16_f32 v34, v34, v35
	v_cvt_pk_bf16_f32 v35, v40, v41
	global_store_dwordx4 v[48:49], v[32:35], off offset:256
	s_nop 1
	v_lshl_add_u64 v[32:33], v[144:145], 0, s[2:3]
	s_mov_b32 s2, 0xa0000
	v_add_co_u32_e32 v38, vcc, s2, v144
	s_mov_b64 s[2:3], 0xb0000
	s_nop 0
	v_addc_co_u32_e32 v39, vcc, 0, v145, vcc
	s_waitcnt vmcnt(15)
	s_nop 1
	v_mov_b32_e32 v34, v210
	v_mov_b32_e32 v35, v211
	v_mov_b32_e32 v36, v212
	v_mov_b32_e32 v37, v213
	s_waitcnt lgkmcnt(0)
	v_lshlrev_b32_e32 v40, 16, v34
	v_and_b32_e32 v41, 0xffff0000, v34
	v_lshlrev_b32_e32 v34, 16, v35
	v_and_b32_e32 v35, 0xffff0000, v35
	v_lshlrev_b32_e32 v42, 16, v36
	v_and_b32_e32 v43, 0xffff0000, v36
	v_lshlrev_b32_e32 v36, 16, v37
	v_and_b32_e32 v37, 0xffff0000, v37
	v_pk_add_f32 v[30:31], v[30:31], v[34:35]
	v_pk_add_f32 v[28:29], v[28:29], v[40:41]
	v_pk_add_f32 v[34:35], v[26:27], v[36:37]
	v_pk_add_f32 v[26:27], v[24:25], v[42:43]
	v_cvt_pk_bf16_f32 v24, v28, v29
	v_cvt_pk_bf16_f32 v25, v30, v31
	v_cvt_pk_bf16_f32 v26, v26, v27
	v_cvt_pk_bf16_f32 v27, v34, v35
	global_store_dwordx4 v[38:39], v[24:27], off
	s_waitcnt vmcnt(15)
	s_nop 1
	v_mov_b32_e32 v24, v214
	v_mov_b32_e32 v25, v215
	v_mov_b32_e32 v26, v216
	v_mov_b32_e32 v27, v217
	s_waitcnt lgkmcnt(0)
	v_lshlrev_b32_e32 v28, 16, v24
	v_and_b32_e32 v29, 0xffff0000, v24
	v_lshlrev_b32_e32 v24, 16, v25
	v_and_b32_e32 v25, 0xffff0000, v25
	v_lshlrev_b32_e32 v30, 16, v26
	v_and_b32_e32 v31, 0xffff0000, v26
	v_lshlrev_b32_e32 v26, 16, v27
	v_and_b32_e32 v27, 0xffff0000, v27
	v_pk_add_f32 v[22:23], v[22:23], v[24:25]
	v_pk_add_f32 v[20:21], v[20:21], v[28:29]
	v_pk_add_f32 v[24:25], v[18:19], v[26:27]
	v_pk_add_f32 v[18:19], v[16:17], v[30:31]
	v_cvt_pk_bf16_f32 v16, v20, v21
	v_cvt_pk_bf16_f32 v17, v22, v23
	v_cvt_pk_bf16_f32 v18, v18, v19
	v_cvt_pk_bf16_f32 v19, v24, v25
	global_store_dwordx4 v[32:33], v[16:19], off offset:256
	s_nop 1
	v_lshl_add_u64 v[16:17], v[144:145], 0, s[2:3]
	s_mov_b32 s2, 0xb0000
	v_add_co_u32_e32 v22, vcc, s2, v144
	s_mov_b32 s2, s44
	s_nop 0
	v_addc_co_u32_e32 v23, vcc, 0, v145, vcc
	s_waitcnt vmcnt(15)
	s_nop 1
	v_mov_b32_e32 v18, v248
	v_mov_b32_e32 v19, v249
	v_mov_b32_e32 v20, v250
	v_mov_b32_e32 v21, v251
	s_and_b64 vcc, exec, s[40:41]
	s_waitcnt lgkmcnt(0)
	v_lshlrev_b32_e32 v24, 16, v18
	v_and_b32_e32 v25, 0xffff0000, v18
	v_lshlrev_b32_e32 v18, 16, v19
	v_and_b32_e32 v19, 0xffff0000, v19
	v_lshlrev_b32_e32 v26, 16, v20
	v_and_b32_e32 v27, 0xffff0000, v20
	v_lshlrev_b32_e32 v20, 16, v21
	v_and_b32_e32 v21, 0xffff0000, v21
	v_pk_add_f32 v[14:15], v[14:15], v[18:19]
	v_pk_add_f32 v[12:13], v[12:13], v[24:25]
	v_pk_add_f32 v[18:19], v[10:11], v[20:21]
	v_pk_add_f32 v[10:11], v[8:9], v[26:27]
	v_cvt_pk_bf16_f32 v8, v12, v13
	v_cvt_pk_bf16_f32 v9, v14, v15
	v_cvt_pk_bf16_f32 v10, v10, v11
	v_cvt_pk_bf16_f32 v11, v18, v19
	global_store_dwordx4 v[22:23], v[8:11], off
	s_waitcnt vmcnt(15)
	s_nop 1
	v_mov_b32_e32 v8, v252
	v_mov_b32_e32 v9, v253
	v_mov_b32_e32 v10, v254
	v_mov_b32_e32 v11, v255
	s_waitcnt lgkmcnt(0)
	v_lshlrev_b32_e32 v12, 16, v8
	v_and_b32_e32 v13, 0xffff0000, v8
	v_lshlrev_b32_e32 v8, 16, v9
	v_and_b32_e32 v9, 0xffff0000, v9
	v_lshlrev_b32_e32 v14, 16, v10
	v_and_b32_e32 v15, 0xffff0000, v10
	v_lshlrev_b32_e32 v10, 16, v11
	v_and_b32_e32 v11, 0xffff0000, v11
	v_pk_add_f32 v[6:7], v[6:7], v[8:9]
	v_pk_add_f32 v[4:5], v[4:5], v[12:13]
	v_pk_add_f32 v[8:9], v[2:3], v[10:11]
	v_pk_add_f32 v[2:3], v[0:1], v[14:15]
	v_cvt_pk_bf16_f32 v0, v4, v5
	v_cvt_pk_bf16_f32 v1, v6, v7
	v_cvt_pk_bf16_f32 v2, v2, v3
	v_cvt_pk_bf16_f32 v3, v8, v9
	global_store_dwordx4 v[16:17], v[0:3], off offset:256
	s_cbranch_vccz .LBB1_1761
	s_waitcnt vmcnt(0)
	s_cmpk_gt_u32 s17, 0xff
	s_cbranch_scc1 .LBB1_1768
	s_barrier

;     DI const char* a(const Unit& u) const { return (const char*)(A + (size_t)u.pm * BM * lda); }
;     DI const char* a(const Unit& u) const { return (const char*)(A + (size_t)u.pm * BM * 2048 + (u.pn >> 1) * 512); }
;     DI const char* a(const Unit& u) const { return (const char*)((u.pn < 12 ? A1 : A2) + (size_t)u.pm * BM * 512); }
; #define PG8_STAGE(bufoff, gbase, voff) do { _Pragma("unroll") for (int _i = 0; _i < 2; ++_i) \
;         __builtin_amdgcn_global_load_lds((const unsigned*)((const char*)(gbase) + (voff)[_i]), (LAS unsigned*)(lds + (bufoff) + ldsw + _i * 8192), 16, 0, 0); } while (0)
; #define PG8_LDA(dst, b, h) do { _Pragma("unroll") for (int m = 0; m < 4; ++m) _Pragma("unroll") for (int k = 0; k < 2; ++k) dst[m][k] = *(const LAS bf16x8*)(lds + PG8_SA(b, h) + aoff + m * 2048 + k * 1024); } while (0)
; #define PG8_LDB(dst, b, h) do { _Pragma("unroll") for (int n = 0; n < 2; ++n) _Pragma("unroll") for (int k = 0; k < 2; ++k) dst[n][k] = *(const LAS bf16x8*)(lds + PG8_SB(b, h) + boff + n * 2048 + k * 1024); } while (0)
; #define PG8_WAIT_L(n) asm volatile("s_waitcnt lgkmcnt(" #n ")" ::: "memory")
; template <class Map, class Epi>
; DI void gemm_phase(LAS unsigned char* lds, const Map& MP, const Epi& E, const int nM, const int nN, const int K, const int lda, const int ldb) {
;     ...
;         const bool has_next = sched_next(ui + 1, nM, nN, G, cblk, nxt);
;         const char* nA = has_next ? MP.a(nxt) : cA; const char* nB = has_next ? MP.b(nxt) : cB;
;         for (int t = 0; t < nt; t += 2) {
;             const bool last = (t == nt - 2);
;             const char* a1 = cA + (size_t)(t + 1) * kstep;
;             const char* a2 = last ? nA : cA + (size_t)(t + 2) * kstep; const char* b2 = last ? nB : cB + (size_t)(t + 2) * kstep;
;             const char* a3 = a2 + kstep; const char* b3 = b2 + kstep;
;             PG8_LDB(B0, 0, 0); PG8_SCHED; PG8_LDA(At, 0, 0); PG8_STAGE(PG8_SA(1, 1), a1 + hstepA, voffA);
;             PG8_WAIT_L(8); PG8_BAR; PG8_WAIT_L(0); PG8_MMA(0, 0, At, B0); PG8_BAR; PG8_SCHED;
;     ...
;         for (int a = 0; a < 2; ++a)
; #pragma unroll
;             for (int b = 0; b < 2; ++b)
; #pragma unroll
;                 for (int m = 0; m < 4; ++m)
; #pragma unroll
;                     for (int n = 0; n < 2; ++n) acc[a][b][m][n] = (f32x4){0.f, 0.f, 0.f, 0.f};
;         cur = nxt; cA = nA; cB = nB; ++ui;
.LBB1_1907:
	s_ashr_i32 s23, s22, 31
	v_cmp_lt_i64_e32 vcc, s[24:25], v[180:181]
	s_lshl_b64 s[24:25], s[22:23], 20
	s_add_u32 s24, s34, s24
	s_addc_u32 s25, s35, s25
	s_and_b64 s[26:27], vcc, exec
	s_cselect_b32 s23, s25, s29
	s_cselect_b32 s58, s24, s28
	s_ashr_i32 s21, s20, 31
	s_lshl_b64 s[26:27], s[20:21], 20
	s_add_u32 s26, s36, s26
	s_addc_u32 s27, s37, s27
	s_and_b64 s[42:43], vcc, exec
	s_cselect_b32 s21, s27, s47
	s_cselect_b32 s59, s26, s46
	s_add_u32 vcc_lo, s46, 0x100
	s_addc_u32 vcc_hi, s47, 0
	s_add_u32 s42, s28, 0x80080
	v_mov_b32_e32 v0, 0
	s_addc_u32 s43, s29, 0
	s_mov_b32 s3, -2
	v_mov_b32_e32 v1, v0
	v_mov_b32_e32 v2, v0
	v_mov_b32_e32 v3, v0
	v_mov_b32_e32 v4, v0
	v_mov_b32_e32 v5, v0
	v_mov_b32_e32 v6, v0
	v_mov_b32_e32 v7, v0
	v_mov_b32_e32 v20, v0
	v_mov_b32_e32 v21, v0
	v_mov_b32_e32 v22, v0
	v_mov_b32_e32 v23, v0
	v_mov_b32_e32 v28, v0
	v_mov_b32_e32 v29, v0
	v_mov_b32_e32 v30, v0
	v_mov_b32_e32 v31, v0
	v_mov_b32_e32 v36, v0
	v_mov_b32_e32 v37, v0
	v_mov_b32_e32 v38, v0
	v_mov_b32_e32 v39, v0
	v_mov_b32_e32 v44, v0
	v_mov_b32_e32 v45, v0
	v_mov_b32_e32 v46, v0
	v_mov_b32_e32 v47, v0
	v_mov_b32_e32 v52, v0
	v_mov_b32_e32 v53, v0
	v_mov_b32_e32 v54, v0
	v_mov_b32_e32 v55, v0
	v_mov_b32_e32 v56, v0
	v_mov_b32_e32 v57, v0
	v_mov_b32_e32 v58, v0
	v_mov_b32_e32 v59, v0
	v_mov_b32_e32 v8, v0
	v_mov_b32_e32 v9, v0
	v_mov_b32_e32 v10, v0
	v_mov_b32_e32 v11, v0
	v_mov_b32_e32 v12, v0
	v_mov_b32_e32 v13, v0
	v_mov_b32_e32 v14, v0
	v_mov_b32_e32 v15, v0
	v_mov_b32_e32 v16, v0
	v_mov_b32_e32 v17, v0
	v_mov_b32_e32 v18, v0
	v_mov_b32_e32 v19, v0
	v_mov_b32_e32 v24, v0
	v_mov_b32_e32 v25, v0
	v_mov_b32_e32 v26, v0
	v_mov_b32_e32 v27, v0
	v_mov_b32_e32 v32, v0
	v_mov_b32_e32 v33, v0
	v_mov_b32_e32 v34, v0
	v_mov_b32_e32 v35, v0
	v_mov_b32_e32 v40, v0
	v_mov_b32_e32 v41, v0
	v_mov_b32_e32 v42, v0
	v_mov_b32_e32 v43, v0
	v_mov_b32_e32 v48, v0
	v_mov_b32_e32 v49, v0
	v_mov_b32_e32 v50, v0
	v_mov_b32_e32 v51, v0
	v_mov_b32_e32 v60, v0
	v_mov_b32_e32 v61, v0
	v_mov_b32_e32 v62, v0
	v_mov_b32_e32 v63, v0
	v_mov_b32_e32 v64, v0
	v_mov_b32_e32 v65, v0
	v_mov_b32_e32 v66, v0
	v_mov_b32_e32 v67, v0
	v_mov_b32_e32 v68, v0
	v_mov_b32_e32 v69, v0
	v_mov_b32_e32 v70, v0
	v_mov_b32_e32 v71, v0
	v_mov_b32_e32 v116, v0
	v_mov_b32_e32 v117, v0
	v_mov_b32_e32 v118, v0
	v_mov_b32_e32 v119, v0
	v_mov_b32_e32 v124, v0
	v_mov_b32_e32 v125, v0
	v_mov_b32_e32 v126, v0
	v_mov_b32_e32 v127, v0
	v_mov_b32_e32 v132, v0
	v_mov_b32_e32 v133, v0
	v_mov_b32_e32 v134, v0
	v_mov_b32_e32 v135, v0
	v_mov_b32_e32 v140, v0
	v_mov_b32_e32 v141, v0
	v_mov_b32_e32 v142, v0
	v_mov_b32_e32 v143, v0
	v_mov_b32_e32 v152, v0
	v_mov_b32_e32 v153, v0
	v_mov_b32_e32 v154, v0
	v_mov_b32_e32 v155, v0
	v_mov_b32_e32 v156, v0
	v_mov_b32_e32 v157, v0
	v_mov_b32_e32 v158, v0
	v_mov_b32_e32 v159, v0
	v_mov_b32_e32 v72, v0
	v_mov_b32_e32 v73, v0
	v_mov_b32_e32 v74, v0
	v_mov_b32_e32 v75, v0
	v_mov_b32_e32 v76, v0
	v_mov_b32_e32 v77, v0
	v_mov_b32_e32 v78, v0
	v_mov_b32_e32 v79, v0
	v_mov_b32_e32 v104, v0
	v_mov_b32_e32 v105, v0
	v_mov_b32_e32 v106, v0
	v_mov_b32_e32 v107, v0
	v_mov_b32_e32 v120, v0
	v_mov_b32_e32 v121, v0
	v_mov_b32_e32 v122, v0
	v_mov_b32_e32 v123, v0
	v_mov_b32_e32 v128, v0
	v_mov_b32_e32 v129, v0
	v_mov_b32_e32 v130, v0
	v_mov_b32_e32 v131, v0
	v_mov_b32_e32 v136, v0
	v_mov_b32_e32 v137, v0
	v_mov_b32_e32 v138, v0
	v_mov_b32_e32 v139, v0
	v_mov_b32_e32 v144, v0
	v_mov_b32_e32 v145, v0
	v_mov_b32_e32 v146, v0
	v_mov_b32_e32 v147, v0
	v_mov_b32_e32 v148, v0
	v_mov_b32_e32 v149, v0
	v_mov_b32_e32 v150, v0
	v_mov_b32_e32 v151, v0
	ds_read_b128 v[80:83], v189
	ds_read_b128 v[84:87], v189 offset:1024
	ds_read_b128 v[88:91], v189 offset:2048
	ds_read_b128 v[92:95], v189 offset:3072
.LBB1_1908:
	s_add_u32 s28, s42, 0xfff80080
	s_addc_u32 s29, s43, -1
	s_cmp_eq_u32 s3, 28
	s_cselect_b32 s47, s23, s29
	s_cselect_b32 s46, s58, s28
	s_cselect_b32 s29, s21, vcc_hi
	s_cselect_b32 s28, s59, vcc_lo
	s_add_i32 m0, s38, 0xc000
	ds_read_b128 v[96:99], v190
	ds_read_b128 v[100:103], v190 offset:1024
	ds_read_b128 v[108:111], v190 offset:2048
	ds_read_b128 v[112:115], v190 offset:3072
	ds_read_b128 v[160:163], v190 offset:4096
	ds_read_b128 v[164:167], v190 offset:5120
	ds_read_b128 v[198:201], v190 offset:6144
	ds_read_b128 v[202:205], v190 offset:7168
	global_load_lds_dwordx4 v178, s[42:43]
	s_add_i32 m0, s38, 0xe000
	s_nop 0
	global_load_lds_dwordx4 v176, s[42:43]
	s_waitcnt lgkmcnt(8)
	s_barrier
	s_setprio 1
	s_waitcnt lgkmcnt(7)
	v_mfma_f32_16x16x32_bf16 v[148:151], v[80:83], v[96:99], v[148:151]
	v_mfma_f32_16x16x32_bf16 v[144:147], v[88:91], v[96:99], v[144:147]
	s_waitcnt lgkmcnt(5)
	v_mfma_f32_16x16x32_bf16 v[136:139], v[80:83], v[108:111], v[136:139]
	v_mfma_f32_16x16x32_bf16 v[128:131], v[88:91], v[108:111], v[128:131]
	s_waitcnt lgkmcnt(3)
	v_mfma_f32_16x16x32_bf16 v[120:123], v[80:83], v[160:163], v[120:123]
	v_mfma_f32_16x16x32_bf16 v[104:107], v[88:91], v[160:163], v[104:107]
	s_waitcnt lgkmcnt(1)
	v_mfma_f32_16x16x32_bf16 v[76:79], v[80:83], v[198:201], v[76:79]
	v_mfma_f32_16x16x32_bf16 v[72:75], v[88:91], v[198:201], v[72:75]
	v_mfma_f32_16x16x32_bf16 v[148:151], v[84:87], v[100:103], v[148:151]
	v_mfma_f32_16x16x32_bf16 v[144:147], v[92:95], v[100:103], v[144:147]
	v_mfma_f32_16x16x32_bf16 v[136:139], v[84:87], v[112:115], v[136:139]
	v_mfma_f32_16x16x32_bf16 v[128:131], v[92:95], v[112:115], v[128:131]
	v_mfma_f32_16x16x32_bf16 v[120:123], v[84:87], v[164:167], v[120:123]
	v_mfma_f32_16x16x32_bf16 v[104:107], v[92:95], v[164:167], v[104:107]
	s_waitcnt lgkmcnt(0)
	v_mfma_f32_16x16x32_bf16 v[76:79], v[84:87], v[202:205], v[76:79]
	v_mfma_f32_16x16x32_bf16 v[72:75], v[92:95], v[202:205], v[72:75]
	s_setprio 0
	s_barrier
; #define PG8_STAGE(bufoff, gbase, voff) do { _Pragma("unroll") for (int _i = 0; _i < 2; ++_i) \
;         __builtin_amdgcn_global_load_lds((const unsigned*)((const char*)(gbase) + (voff)[_i]), (LAS unsigned*)(lds + (bufoff) + ldsw + _i * 8192), 16, 0, 0); } while (0)
; #define PG8_LDA(dst, b, h) do { _Pragma("unroll") for (int m = 0; m < 4; ++m) _Pragma("unroll") for (int k = 0; k < 2; ++k) dst[m][k] = *(const LAS bf16x8*)(lds + PG8_SA(b, h) + aoff + m * 2048 + k * 1024); } while (0)
; #define PG8_LDB(dst, b, h) do { _Pragma("unroll") for (int n = 0; n < 2; ++n) _Pragma("unroll") for (int k = 0; k < 2; ++k) dst[n][k] = *(const LAS bf16x8*)(lds + PG8_SB(b, h) + boff + n * 2048 + k * 1024); } while (0)
; #define PG8_MMA(ai, bj, At, Bt) do { __builtin_amdgcn_s_setprio(1); _Pragma("unroll") for (int m = 0; m < 4; ++m) _Pragma("unroll") for (int n = 0; n < 2; ++n) _Pragma("unroll") for (int k = 0; k < 2; ++k) \
;         acc[ai][bj][m][n] = __builtin_amdgcn_mfma_f32_16x16x32_bf16(Bt[n][k], At[m][k], acc[ai][bj][m][n], 0, 0, 0); __builtin_amdgcn_s_setprio(0); } while (0)
; #define PG8_WAIT_V(n) asm volatile("s_waitcnt vmcnt(" #n ")" ::: "memory")
; #define PG8_WAIT_L(n) asm volatile("s_waitcnt lgkmcnt(" #n ")" ::: "memory")
; #define PG8_BAR __builtin_amdgcn_s_barrier()
; #define PG8_SCHED __builtin_amdgcn_sched_barrier(0)
; template <class Map, class Epi>
; DI void gemm_phase(LAS unsigned char* lds, const Map& MP, const Epi& E, const int nM, const int nN, const int K, const int lda, const int ldb) {
;     ...
;             PG8_LDB(B1, 0, 1); PG8_STAGE(PG8_SB(0, 0), b2, voffB);
;             PG8_BAR; PG8_WAIT_L(0); PG8_MMA(0, 1, At, B1); PG8_BAR;
;             PG8_LDA(At, 0, 1); PG8_STAGE(PG8_SA(0, 0), a2, voffA);
;             PG8_BAR; PG8_WAIT_L(0); PG8_MMA(1, 0, At, B0); PG8_BAR; PG8_SCHED;
;             PG8_STAGE(PG8_SB(0, 1), b2 + hstepB, voffB);
;             PG8_WAIT_V(6); PG8_BAR; PG8_MMA(1, 1, At, B1); PG8_BAR;
;             PG8_LDB(B0, 1, 0); PG8_SCHED; PG8_LDA(At, 1, 0); PG8_STAGE(PG8_SA(0, 1), a2 + hstepA, voffA);
	s_add_i32 s68, s2, s54
	v_lshl_add_u64 v[184:185], s[28:29], 0, v[172:173]
	s_mov_b32 m0, s68
	ds_read_b128 v[206:209], v191
	ds_read_b128 v[210:213], v191 offset:1024
	ds_read_b128 v[214:217], v191 offset:2048
	ds_read_b128 v[218:221], v191 offset:3072
	global_load_lds_dwordx4 v[184:185], off
	v_lshl_add_u64 v[194:195], s[28:29], 0, v[168:169]
	s_add_i32 m0, s68, 0x2000
	s_nop 0
	global_load_lds_dwordx4 v[194:195], off
	s_barrier
	s_setprio 1
	s_waitcnt lgkmcnt(3)
	v_mfma_f32_16x16x32_bf16 v[156:159], v[206:209], v[96:99], v[156:159]
	s_waitcnt lgkmcnt(1)
	v_mfma_f32_16x16x32_bf16 v[96:99], v[214:217], v[96:99], v[152:155]
	v_mfma_f32_16x16x32_bf16 v[156:159], v[210:213], v[100:103], v[156:159]
	s_waitcnt lgkmcnt(0)
	v_mfma_f32_16x16x32_bf16 v[96:99], v[218:221], v[100:103], v[96:99]
	v_mfma_f32_16x16x32_bf16 v[100:103], v[206:209], v[108:111], v[140:143]
	v_mfma_f32_16x16x32_bf16 v[108:111], v[214:217], v[108:111], v[132:135]
	v_mfma_f32_16x16x32_bf16 v[116:119], v[214:217], v[160:163], v[116:119]
	v_mfma_f32_16x16x32_bf16 v[68:71], v[206:209], v[198:201], v[68:71]
	v_mfma_f32_16x16x32_bf16 v[64:67], v[214:217], v[198:201], v[64:67]
	v_mfma_f32_16x16x32_bf16 v[100:103], v[210:213], v[112:115], v[100:103]
	v_mfma_f32_16x16x32_bf16 v[108:111], v[218:221], v[112:115], v[108:111]
	v_mfma_f32_16x16x32_bf16 v[112:115], v[206:209], v[160:163], v[124:127]
	v_mfma_f32_16x16x32_bf16 v[116:119], v[218:221], v[164:167], v[116:119]
	v_mfma_f32_16x16x32_bf16 v[68:71], v[210:213], v[202:205], v[68:71]
	v_mfma_f32_16x16x32_bf16 v[64:67], v[218:221], v[202:205], v[64:67]
	v_mfma_f32_16x16x32_bf16 v[112:115], v[210:213], v[164:167], v[112:115]
	s_setprio 0
	s_mov_b32 m0, s38
	v_lshl_add_u64 v[226:227], s[46:47], 0, v[174:175]
	s_barrier
	ds_read_b128 v[124:127], v190 offset:16384
	ds_read_b128 v[132:135], v190 offset:17408
	ds_read_b128 v[140:143], v190 offset:18432
	ds_read_b128 v[152:155], v190 offset:19456
	ds_read_b128 v[160:163], v190 offset:20480
	ds_read_b128 v[164:167], v190 offset:21504
	ds_read_b128 v[198:201], v190 offset:22528
	ds_read_b128 v[202:205], v190 offset:23552
	global_load_lds_dwordx4 v[226:227], off
	v_lshl_add_u64 v[234:235], s[46:47], 0, v[170:171]
	s_mov_b32 m0, s39
	s_nop 0
	global_load_lds_dwordx4 v[234:235], off
	s_waitcnt vmcnt(10)
	s_barrier
	s_setprio 1
	s_waitcnt lgkmcnt(7)
	v_mfma_f32_16x16x32_bf16 v[60:63], v[80:83], v[124:127], v[60:63]
	v_mfma_f32_16x16x32_bf16 v[48:51], v[88:91], v[124:127], v[48:51]
	s_waitcnt lgkmcnt(5)
	v_mfma_f32_16x16x32_bf16 v[40:43], v[80:83], v[140:143], v[40:43]
	v_mfma_f32_16x16x32_bf16 v[32:35], v[88:91], v[140:143], v[32:35]
	s_waitcnt lgkmcnt(3)
	v_mfma_f32_16x16x32_bf16 v[24:27], v[80:83], v[160:163], v[24:27]
	v_mfma_f32_16x16x32_bf16 v[16:19], v[88:91], v[160:163], v[16:19]
	s_waitcnt lgkmcnt(1)
	v_mfma_f32_16x16x32_bf16 v[12:15], v[80:83], v[198:201], v[12:15]
	v_mfma_f32_16x16x32_bf16 v[8:11], v[88:91], v[198:201], v[8:11]
	v_mfma_f32_16x16x32_bf16 v[60:63], v[84:87], v[132:135], v[60:63]
	v_mfma_f32_16x16x32_bf16 v[48:51], v[92:95], v[132:135], v[48:51]
	v_mfma_f32_16x16x32_bf16 v[40:43], v[84:87], v[152:155], v[40:43]
	v_mfma_f32_16x16x32_bf16 v[32:35], v[92:95], v[152:155], v[32:35]
	v_mfma_f32_16x16x32_bf16 v[24:27], v[84:87], v[164:167], v[24:27]
	v_mfma_f32_16x16x32_bf16 v[16:19], v[92:95], v[164:167], v[16:19]
	s_waitcnt lgkmcnt(0)
	v_mfma_f32_16x16x32_bf16 v[12:15], v[84:87], v[202:205], v[12:15]
	v_mfma_f32_16x16x32_bf16 v[8:11], v[92:95], v[202:205], v[8:11]
	s_setprio 0
	s_barrier
	s_add_u32 s68, s28, 0x80000
	s_addc_u32 s69, s29, 0
	s_add_i32 s70, s31, s54
	s_mov_b32 m0, s70
	s_nop 0
	global_load_lds_dwordx4 v172, s[68:69]
	s_add_i32 m0, s70, 0x2000
	s_nop 0
	global_load_lds_dwordx4 v168, s[68:69]
	s_waitcnt vmcnt(6)
	s_barrier
	s_setprio 1
	v_mfma_f32_16x16x32_bf16 v[56:59], v[206:209], v[124:127], v[56:59]
	v_mfma_f32_16x16x32_bf16 v[52:55], v[214:217], v[124:127], v[52:55]
	s_add_i32 s68, 0, 0x18000
	v_add_u32_e32 v92, s68, v188
	ds_read_b128 v[80:83], v92
	v_mfma_f32_16x16x32_bf16 v[44:47], v[206:209], v[140:143], v[44:47]
	v_mfma_f32_16x16x32_bf16 v[36:39], v[214:217], v[140:143], v[36:39]
	ds_read_b128 v[84:87], v92 offset:1024
	v_mfma_f32_16x16x32_bf16 v[28:31], v[206:209], v[160:163], v[28:31]
	v_mfma_f32_16x16x32_bf16 v[20:23], v[214:217], v[160:163], v[20:23]
	ds_read_b128 v[88:91], v92 offset:2048
	v_mfma_f32_16x16x32_bf16 v[4:7], v[206:209], v[198:201], v[4:7]
	v_mfma_f32_16x16x32_bf16 v[0:3], v[214:217], v[198:201], v[0:3]
	ds_read_b128 v[92:95], v92 offset:3072
	v_mfma_f32_16x16x32_bf16 v[56:59], v[210:213], v[132:135], v[56:59]
	v_mfma_f32_16x16x32_bf16 v[52:55], v[218:221], v[132:135], v[52:55]
	v_mfma_f32_16x16x32_bf16 v[44:47], v[210:213], v[152:155], v[44:47]
	v_mfma_f32_16x16x32_bf16 v[36:39], v[218:221], v[152:155], v[36:39]
	v_mfma_f32_16x16x32_bf16 v[28:31], v[210:213], v[164:167], v[28:31]
	v_mfma_f32_16x16x32_bf16 v[20:23], v[218:221], v[164:167], v[20:23]
	v_mfma_f32_16x16x32_bf16 v[4:7], v[210:213], v[202:205], v[4:7]
	v_mfma_f32_16x16x32_bf16 v[0:3], v[218:221], v[202:205], v[0:3]
	s_setprio 0
	s_barrier
	s_add_u32 s46, s46, 0x80000
	s_addc_u32 s47, s47, 0
	s_mov_b32 m0, s56
	ds_read_b128 v[124:127], v190 offset:32768
	ds_read_b128 v[132:135], v190 offset:33792
	ds_read_b128 v[160:163], v190 offset:34816
	ds_read_b128 v[164:167], v190 offset:35840
	ds_read_b128 v[198:201], v190 offset:36864
	ds_read_b128 v[202:205], v190 offset:37888
	ds_read_b128 v[206:209], v190 offset:38912
	ds_read_b128 v[210:213], v190 offset:39936
	global_load_lds_dwordx4 v174, s[46:47]
	s_mov_b32 m0, s57
	s_nop 0
	global_load_lds_dwordx4 v170, s[46:47]
	s_waitcnt lgkmcnt(8)
	s_barrier
; #define PG8_STAGE(bufoff, gbase, voff) do { _Pragma("unroll") for (int _i = 0; _i < 2; ++_i) \
;         __builtin_amdgcn_global_load_lds((const unsigned*)((const char*)(gbase) + (voff)[_i]), (LAS unsigned*)(lds + (bufoff) + ldsw + _i * 8192), 16, 0, 0); } while (0)
; #define PG8_LDA(dst, b, h) do { _Pragma("unroll") for (int m = 0; m < 4; ++m) _Pragma("unroll") for (int k = 0; k < 2; ++k) dst[m][k] = *(const LAS bf16x8*)(lds + PG8_SA(b, h) + aoff + m * 2048 + k * 1024); } while (0)
; #define PG8_LDB(dst, b, h) do { _Pragma("unroll") for (int n = 0; n < 2; ++n) _Pragma("unroll") for (int k = 0; k < 2; ++k) dst[n][k] = *(const LAS bf16x8*)(lds + PG8_SB(b, h) + boff + n * 2048 + k * 1024); } while (0)
; #define PG8_MMA(ai, bj, At, Bt) do { __builtin_amdgcn_s_setprio(1); _Pragma("unroll") for (int m = 0; m < 4; ++m) _Pragma("unroll") for (int n = 0; n < 2; ++n) _Pragma("unroll") for (int k = 0; k < 2; ++k) \
;         acc[ai][bj][m][n] = __builtin_amdgcn_mfma_f32_16x16x32_bf16(Bt[n][k], At[m][k], acc[ai][bj][m][n], 0, 0, 0); __builtin_amdgcn_s_setprio(0); } while (0)
; #define PG8_WAIT_V(n) asm volatile("s_waitcnt vmcnt(" #n ")" ::: "memory")
; #define PG8_WAIT_L(n) asm volatile("s_waitcnt lgkmcnt(" #n ")" ::: "memory")
; #define PG8_BAR __builtin_amdgcn_s_barrier()
; #define PG8_SCHED __builtin_amdgcn_sched_barrier(0)
; template <class Map, class Epi>
; DI void gemm_phase(LAS unsigned char* lds, const Map& MP, const Epi& E, const int nM, const int nN, const int K, const int lda, const int ldb) {
;     ...
;             PG8_WAIT_L(8); PG8_BAR; PG8_WAIT_L(0); PG8_MMA(0, 0, At, B0); PG8_BAR; PG8_SCHED;
;             PG8_LDB(B1, 1, 1); PG8_STAGE(PG8_SB(1, 0), b3, voffB);
;             PG8_BAR; PG8_WAIT_L(0); PG8_MMA(0, 1, At, B1); PG8_BAR;
;             PG8_LDA(At, 1, 1); PG8_STAGE(PG8_SA(1, 0), a3, voffA);
;             PG8_BAR; PG8_WAIT_L(0); PG8_MMA(1, 0, At, B0); PG8_BAR; PG8_SCHED;
;             PG8_STAGE(PG8_SB(1, 1), b3 + hstepB, voffB);
;             PG8_WAIT_V(6); PG8_BAR; PG8_MMA(1, 1, At, B1); PG8_BAR;
	s_setprio 1
	s_waitcnt lgkmcnt(7)
	v_mfma_f32_16x16x32_bf16 v[140:143], v[80:83], v[124:127], v[148:151]
	s_waitcnt lgkmcnt(6)
	v_mfma_f32_16x16x32_bf16 v[148:151], v[84:87], v[132:135], v[140:143]
	v_mfma_f32_16x16x32_bf16 v[140:143], v[88:91], v[124:127], v[144:147]
	s_waitcnt lgkmcnt(5)
	v_mfma_f32_16x16x32_bf16 v[136:139], v[80:83], v[160:163], v[136:139]
	v_mfma_f32_16x16x32_bf16 v[128:131], v[88:91], v[160:163], v[128:131]
	s_waitcnt lgkmcnt(3)
	v_mfma_f32_16x16x32_bf16 v[120:123], v[80:83], v[198:201], v[120:123]
	v_mfma_f32_16x16x32_bf16 v[104:107], v[88:91], v[198:201], v[104:107]
	s_waitcnt lgkmcnt(1)
	v_mfma_f32_16x16x32_bf16 v[76:79], v[80:83], v[206:209], v[76:79]
	v_mfma_f32_16x16x32_bf16 v[72:75], v[88:91], v[206:209], v[72:75]
	v_mfma_f32_16x16x32_bf16 v[144:147], v[92:95], v[132:135], v[140:143]
	v_mfma_f32_16x16x32_bf16 v[136:139], v[84:87], v[164:167], v[136:139]
	v_mfma_f32_16x16x32_bf16 v[128:131], v[92:95], v[164:167], v[128:131]
	v_mfma_f32_16x16x32_bf16 v[120:123], v[84:87], v[202:205], v[120:123]
	v_mfma_f32_16x16x32_bf16 v[104:107], v[92:95], v[202:205], v[104:107]
	s_waitcnt lgkmcnt(0)
	v_mfma_f32_16x16x32_bf16 v[76:79], v[84:87], v[210:213], v[76:79]
	v_mfma_f32_16x16x32_bf16 v[72:75], v[92:95], v[210:213], v[72:75]
	s_setprio 0
	s_barrier
	s_add_i32 s46, 0, 0x1c000
	v_add_u32_e32 v140, s46, v188
	s_add_i32 s47, s68, s54
	ds_read_b128 v[214:217], v140
	ds_read_b128 v[218:221], v140 offset:1024
	ds_read_b128 v[222:225], v140 offset:2048
	ds_read_b128 v[230:233], v140 offset:3072
	v_lshl_add_u64 v[140:141], v[184:185], 0, s[14:15]
	s_mov_b32 m0, s47
	s_nop 0
	global_load_lds_dwordx4 v[140:141], off
	v_lshl_add_u64 v[140:141], v[194:195], 0, s[14:15]
	s_add_i32 m0, s47, 0x2000
	s_nop 0
	global_load_lds_dwordx4 v[140:141], off
	s_barrier
	s_setprio 1
	s_waitcnt lgkmcnt(1)
	v_mfma_f32_16x16x32_bf16 v[96:99], v[222:225], v[124:127], v[96:99]
	v_mfma_f32_16x16x32_bf16 v[140:143], v[214:217], v[124:127], v[156:159]
	s_waitcnt lgkmcnt(0)
	v_mfma_f32_16x16x32_bf16 v[152:155], v[230:233], v[132:135], v[96:99]
	v_mfma_f32_16x16x32_bf16 v[96:99], v[214:217], v[160:163], v[100:103]
	v_mfma_f32_16x16x32_bf16 v[156:159], v[218:221], v[132:135], v[140:143]
	v_mfma_f32_16x16x32_bf16 v[140:143], v[218:221], v[164:167], v[96:99]
	v_mfma_f32_16x16x32_bf16 v[96:99], v[222:225], v[160:163], v[108:111]
	v_mfma_f32_16x16x32_bf16 v[132:135], v[230:233], v[164:167], v[96:99]
	v_mfma_f32_16x16x32_bf16 v[96:99], v[214:217], v[198:201], v[112:115]
	v_mfma_f32_16x16x32_bf16 v[124:127], v[218:221], v[202:205], v[96:99]
	v_mfma_f32_16x16x32_bf16 v[96:99], v[222:225], v[198:201], v[116:119]
	v_mfma_f32_16x16x32_bf16 v[68:71], v[214:217], v[206:209], v[68:71]
	v_mfma_f32_16x16x32_bf16 v[64:67], v[222:225], v[206:209], v[64:67]
	v_mfma_f32_16x16x32_bf16 v[116:119], v[230:233], v[202:205], v[96:99]
	v_mfma_f32_16x16x32_bf16 v[68:71], v[218:221], v[210:213], v[68:71]
	v_mfma_f32_16x16x32_bf16 v[64:67], v[230:233], v[210:213], v[64:67]
	s_setprio 0
	s_mov_b32 m0, s63
	v_lshl_add_u64 v[184:185], v[226:227], 0, s[14:15]
	s_barrier
	ds_read_b128 v[96:99], v190 offset:49152
	ds_read_b128 v[100:103], v190 offset:50176
	ds_read_b128 v[108:111], v190 offset:51200
	ds_read_b128 v[112:115], v190 offset:52224
	ds_read_b128 v[160:163], v190 offset:53248
	ds_read_b128 v[164:167], v190 offset:54272
	ds_read_b128 v[198:201], v190 offset:55296
	ds_read_b128 v[202:205], v190 offset:56320
	global_load_lds_dwordx4 v[184:185], off
	v_lshl_add_u64 v[184:185], v[234:235], 0, s[14:15]
	s_mov_b32 m0, s66
	s_nop 0
	global_load_lds_dwordx4 v[184:185], off
	s_waitcnt vmcnt(10)
	s_barrier
	s_setprio 1
	s_waitcnt lgkmcnt(7)
	v_mfma_f32_16x16x32_bf16 v[60:63], v[80:83], v[96:99], v[60:63]
	v_mfma_f32_16x16x32_bf16 v[48:51], v[88:91], v[96:99], v[48:51]
	s_waitcnt lgkmcnt(5)
	v_mfma_f32_16x16x32_bf16 v[40:43], v[80:83], v[108:111], v[40:43]
	v_mfma_f32_16x16x32_bf16 v[32:35], v[88:91], v[108:111], v[32:35]
	s_waitcnt lgkmcnt(3)
	v_mfma_f32_16x16x32_bf16 v[24:27], v[80:83], v[160:163], v[24:27]
	v_mfma_f32_16x16x32_bf16 v[16:19], v[88:91], v[160:163], v[16:19]
	s_waitcnt lgkmcnt(1)
	v_mfma_f32_16x16x32_bf16 v[12:15], v[80:83], v[198:201], v[12:15]
	v_mfma_f32_16x16x32_bf16 v[8:11], v[88:91], v[198:201], v[8:11]
	v_mfma_f32_16x16x32_bf16 v[60:63], v[84:87], v[100:103], v[60:63]
	v_mfma_f32_16x16x32_bf16 v[48:51], v[92:95], v[100:103], v[48:51]
	v_mfma_f32_16x16x32_bf16 v[40:43], v[84:87], v[112:115], v[40:43]
	v_mfma_f32_16x16x32_bf16 v[32:35], v[92:95], v[112:115], v[32:35]
	v_mfma_f32_16x16x32_bf16 v[24:27], v[84:87], v[164:167], v[24:27]
	v_mfma_f32_16x16x32_bf16 v[16:19], v[92:95], v[164:167], v[16:19]
	s_waitcnt lgkmcnt(0)
	v_mfma_f32_16x16x32_bf16 v[12:15], v[84:87], v[202:205], v[12:15]
	v_mfma_f32_16x16x32_bf16 v[8:11], v[92:95], v[202:205], v[8:11]
	s_setprio 0
	s_barrier
	s_add_u32 s28, s28, 0x80080
	s_addc_u32 s29, s29, 0
	s_add_i32 s46, s46, s54
	s_mov_b32 m0, s46
	s_nop 0
	global_load_lds_dwordx4 v172, s[28:29]
	s_add_i32 m0, s46, 0x2000
	s_nop 0
	global_load_lds_dwordx4 v168, s[28:29]
	s_waitcnt vmcnt(6)
	s_barrier
; DI float dpp_ror1(float v)  { return __builtin_bit_cast(float, __builtin_amdgcn_update_dpp(0, __builtin_bit_cast(int, v), 0x121, 0xf, 0xf, false)); }
; DI float dpp_ror15(float v) { return __builtin_bit_cast(float, __builtin_amdgcn_update_dpp(0, __builtin_bit_cast(int, v), 0x12F, 0xf, 0xf, false)); }
; #define PG8_BAR __builtin_amdgcn_s_barrier()
;     DI void operator()(const f32x4 (&acc)[2][2][4][2], const Unit& u, int wr, int wc, int fr, int fq) const {
;         const int row0 = u.pm * BM + wr * 64 + fr, ch0 = u.pn * 128 + wc * 32 + 8 * fq;
;         f32x4 w0[2], w1[2], w2[2], bb[2];
; #pragma unroll
;         for (int n = 0; n < 2; ++n) { w0[n] = *(const f32x4*)(cw + ch0 + 4 * n); w1[n] = *(const f32x4*)(cw + DFF + ch0 + 4 * n); w2[n] = *(const f32x4*)(cw + 2 * DFF + ch0 + 4 * n); bb[n] = *(const f32x4*)(cb + ch0 + 4 * n); }
; #pragma unroll
;         for (int ai = 0; ai < 2; ++ai)
; #pragma unroll
;             for (int m = 0; m < 4; ++m) {
;                 const bool efirst = (m == 0) && (fr == 0), elast = (m == 3) && (fr == 15);
;                 const int row = row0 + ai * HALF + m * 16;
;                 f32x4 gc[2];
; #pragma unroll
;                 for (int n = 0; n < 2; ++n) {
;                     const f32x4 g = acc[ai][0][m][n];
;                     const f32x4 gprev = acc[ai][0][m > 0 ? m - 1 : 0][n], gnext = acc[ai][0][m < 3 ? m + 1 : 3][n];
;                     f32x4 up, dn;
; #pragma unroll
;                     for (int e = 0; e < 4; ++e) {
;                         const float pu = (m > 0 && fr == 15) ? gprev[e] : g[e];
;                         const float pd = (m < 3 && fr == 0) ? gnext[e] : g[e];
;                         up[e] = dpp_ror1(pu); dn[e] = dpp_ror15(pd);
;                     }
;                     if (efirst) up = (f32x4){0.f, 0.f, 0.f, 0.f};
;                     if (elast) dn = (f32x4){0.f, 0.f, 0.f, 0.f};
;                     gc[n] = w0[n] * up + w1[n] * g + w2[n] * dn + bb[n];
;                 }
;                 if (efirst || elast) {
; template <class Map, class Epi>
; DI void gemm_phase(LAS unsigned char* lds, const Map& MP, const Epi& E, const int nM, const int nN, const int K, const int lda, const int ldb) {
;     ...
;             PG8_WAIT_V(6); PG8_BAR; PG8_MMA(1, 1, At, B1); PG8_BAR;
;         }
;         { int frr = fr, fqq = fq; asm volatile("" : "+v"(frr), "+v"(fqq)); E(acc, cur, wr, wc, frr, fqq); }
	s_setprio 1
	v_mfma_f32_16x16x32_bf16 v[56:59], v[214:217], v[96:99], v[56:59]
	v_mfma_f32_16x16x32_bf16 v[52:55], v[222:225], v[96:99], v[52:55]
	ds_read_b128 v[80:83], v189
	v_mfma_f32_16x16x32_bf16 v[44:47], v[214:217], v[108:111], v[44:47]
	v_mfma_f32_16x16x32_bf16 v[36:39], v[222:225], v[108:111], v[36:39]
	ds_read_b128 v[84:87], v189 offset:1024
	v_mfma_f32_16x16x32_bf16 v[28:31], v[214:217], v[160:163], v[28:31]
	v_mfma_f32_16x16x32_bf16 v[20:23], v[222:225], v[160:163], v[20:23]
	ds_read_b128 v[88:91], v189 offset:2048
	v_mfma_f32_16x16x32_bf16 v[4:7], v[214:217], v[198:201], v[4:7]
	v_mfma_f32_16x16x32_bf16 v[0:3], v[222:225], v[198:201], v[0:3]
	ds_read_b128 v[92:95], v189 offset:3072
	v_mfma_f32_16x16x32_bf16 v[56:59], v[218:221], v[100:103], v[56:59]
	v_mfma_f32_16x16x32_bf16 v[52:55], v[230:233], v[100:103], v[52:55]
	v_mfma_f32_16x16x32_bf16 v[44:47], v[218:221], v[112:115], v[44:47]
	v_mfma_f32_16x16x32_bf16 v[36:39], v[230:233], v[112:115], v[36:39]
	v_mfma_f32_16x16x32_bf16 v[28:31], v[218:221], v[164:167], v[28:31]
	v_mfma_f32_16x16x32_bf16 v[20:23], v[230:233], v[164:167], v[20:23]
	v_mfma_f32_16x16x32_bf16 v[4:7], v[218:221], v[202:205], v[4:7]
	v_mfma_f32_16x16x32_bf16 v[0:3], v[230:233], v[202:205], v[0:3]
	s_setprio 0
	s_add_i32 s3, s3, 2
	s_add_u32 vcc_lo, vcc_lo, 0x100
	s_addc_u32 vcc_hi, vcc_hi, 0
	s_add_u32 s42, s42, 0x100
	s_addc_u32 s43, s43, 0
	s_cmp_gt_u32 s3, 29
	s_barrier
	s_cbranch_scc0 .LBB1_1908
	s_waitcnt lgkmcnt(0)
	s_lshl_b32 s21, s45, 7
	v_mov_b32_e32 v194, v186
	v_mov_b32_e32 v80, v187
	s_or_b32 s21, s21, s62
	v_mov_b32_e32 v160, 0
	v_lshl_add_u32 v184, v80, 3, s21
	v_ashrrev_i32_e32 v185, 31, v184
	v_lshlrev_b64 v[80:81], 2, v[184:185]
	v_lshl_add_u64 v[84:85], s[4:5], 0, v[80:81]
	v_lshl_add_u64 v[88:89], s[16:17], 0, v[80:81]
	v_lshl_add_u64 v[92:93], s[18:19], 0, v[80:81]
	v_lshl_add_u64 v[112:113], s[6:7], 0, v[80:81]
	global_load_dwordx4 v[80:83], v[84:85], off offset:16
	global_load_dwordx4 v[96:99], v[84:85], off
	s_nop 0
	global_load_dwordx4 v[84:87], v[88:89], off offset:16
	global_load_dwordx4 v[100:103], v[88:89], off
	s_nop 0
	global_load_dwordx4 v[88:91], v[92:93], off offset:16
	global_load_dwordx4 v[108:111], v[92:93], off
	s_nop 0
	global_load_dwordx4 v[92:95], v[112:113], off offset:16
	s_nop 0
	global_load_dwordx4 v[112:115], v[112:113], off
	v_cmp_eq_u32_e32 vcc, 0, v194
	v_mov_b32_e32 v164, 0
	v_mov_b32_e32 v195, 0
	v_cndmask_b32_e32 v161, v148, v136, vcc
	v_cndmask_b32_e32 v162, v149, v137, vcc
	v_cndmask_b32_e32 v163, v150, v138, vcc
	v_mov_b32_dpp v160, v161 row_ror:15 row_mask:0xf bank_mask:0xf
	v_mov_b32_e32 v161, 0
	v_mov_b32_e32 v166, 0
	v_mov_b32_e32 v167, 0
	v_mov_b32_dpp v161, v162 row_ror:15 row_mask:0xf bank_mask:0xf
	v_mov_b32_e32 v162, 0
	v_mov_b32_dpp v164, v150 row_ror:1 row_mask:0xf bank_mask:0xf
	v_cndmask_b32_e32 v165, v151, v139, vcc
	v_mov_b32_dpp v162, v163 row_ror:15 row_mask:0xf bank_mask:0xf
	v_mov_b32_dpp v195, v151 row_ror:1 row_mask:0xf bank_mask:0xf
	v_mov_b32_e32 v163, 0
	v_mov_b32_dpp v166, v148 row_ror:1 row_mask:0xf bank_mask:0xf
	v_mov_b32_dpp v167, v149 row_ror:1 row_mask:0xf bank_mask:0xf
	v_mov_b32_dpp v163, v165 row_ror:15 row_mask:0xf bank_mask:0xf
	v_cndmask_b32_e64 v165, v195, 0, vcc
	v_cndmask_b32_e64 v164, v164, 0, vcc
	v_cndmask_b32_e64 v167, v167, 0, vcc
	v_cndmask_b32_e64 v166, v166, 0, vcc
	v_mov_b32_e32 v195, 0
	v_mov_b32_e32 v196, 0
	v_mov_b32_e32 v198, 0
	v_mov_b32_e32 v200, 0
	v_mov_b32_dpp v195, v144 row_ror:1 row_mask:0xf bank_mask:0xf
	v_mov_b32_dpp v196, v145 row_ror:1 row_mask:0xf bank_mask:0xf
	v_mov_b32_dpp v198, v146 row_ror:1 row_mask:0xf bank_mask:0xf
	v_cndmask_b32_e32 v199, v147, v131, vcc
	v_mov_b32_dpp v200, v147 row_ror:1 row_mask:0xf bank_mask:0xf
	v_cndmask_b32_e64 v198, v198, 0, vcc
	v_cndmask_b32_e64 v201, v196, 0, vcc
	s_lshl_b32 s3, s44, 8
	s_add_i32 s3, s3, s49
	v_add_u32_e32 v193, s3, v194
	v_cmp_ne_u32_e64 s[46:47], 0, v194
	s_waitcnt vmcnt(0)
	v_pk_mul_f32 v[164:165], v[98:99], v[164:165]
	v_pk_mul_f32 v[166:167], v[96:97], v[166:167]
	v_pk_fma_f32 v[164:165], v[150:151], v[102:103], v[164:165]
	v_pk_fma_f32 v[166:167], v[148:149], v[100:101], v[166:167]
	v_pk_fma_f32 v[162:163], v[110:111], v[162:163], v[164:165]
	v_cndmask_b32_e32 v165, v144, v128, vcc
	v_mov_b32_e32 v164, 0
	v_pk_fma_f32 v[160:161], v[108:109], v[160:161], v[166:167]
	v_cndmask_b32_e32 v166, v145, v129, vcc
	v_mov_b32_dpp v164, v165 row_ror:15 row_mask:0xf bank_mask:0xf
	v_mov_b32_e32 v165, 0
	v_cndmask_b32_e32 v167, v146, v130, vcc
	v_pk_add_f32 v[162:163], v[114:115], v[162:163]
	v_mov_b32_dpp v165, v166 row_ror:15 row_mask:0xf bank_mask:0xf
	v_mov_b32_e32 v166, 0
	v_pk_add_f32 v[160:161], v[112:113], v[160:161]
	s_nop 0
	v_mov_b32_dpp v166, v167 row_ror:15 row_mask:0xf bank_mask:0xf
	v_mov_b32_e32 v167, 0
	s_nop 1
	v_mov_b32_dpp v167, v199 row_ror:15 row_mask:0xf bank_mask:0xf
	v_cndmask_b32_e64 v199, v200, 0, vcc
	v_cndmask_b32_e64 v200, v195, 0, vcc
	v_pk_mul_f32 v[200:201], v[80:81], v[200:201]
	v_pk_mul_f32 v[198:199], v[82:83], v[198:199]
	v_pk_fma_f32 v[200:201], v[144:145], v[84:85], v[200:201]
	v_pk_fma_f32 v[198:199], v[146:147], v[86:87], v[198:199]
	v_pk_fma_f32 v[164:165], v[88:89], v[164:165], v[200:201]
	v_pk_fma_f32 v[166:167], v[90:91], v[166:167], v[198:199]
	v_pk_add_f32 v[164:165], v[92:93], v[164:165]
	v_pk_add_f32 v[166:167], v[94:95], v[166:167]
	s_and_saveexec_b64 s[28:29], s[46:47]
	s_xor_b64 s[28:29], exec, s[28:29]
	s_cbranch_execz .LBB1_1911
; DI unsigned pack2(float a, float b) { f32x2 v = {a, b}; hwbf16x2 r = __builtin_convertvector(v, hwbf16x2); return __builtin_bit_cast(unsigned, r); }
; DI float silu_mul(float g, float v) { return g * v * __builtin_amdgcn_rcpf(1.0f + __builtin_amdgcn_exp2f(-LOG2E * g)); }
;     DI void operator()(const f32x4 (&acc)[2][2][4][2], const Unit& u, int wr, int wc, int fr, int fq) const {
;     ...
;                     const f32x4 v0 = acc[ai][1][m][0], v1 = acc[ai][1][m][1];
;                     u32x4 o;
;                     o[0] = pack2(silu_mul(gc[0][0], v0[0]), silu_mul(gc[0][1], v0[1])); o[1] = pack2(silu_mul(gc[0][2], v0[2]), silu_mul(gc[0][3], v0[3]));
;                     o[2] = pack2(silu_mul(gc[1][0], v1[0]), silu_mul(gc[1][1], v1[1])); o[3] = pack2(silu_mul(gc[1][2], v1[2]), silu_mul(gc[1][3], v1[3]));
;                     *(u32x4*)(ACT + (size_t)row * DFF + ch0) = o;
	v_mul_f32_e32 v195, 0xbfb8aa3b, v160
	v_exp_f32_e32 v195, v195
	v_mul_f32_e32 v196, 0xbfb8aa3b, v161
	v_exp_f32_e32 v196, v196
	v_pk_mul_f32 v[160:161], v[156:157], v[160:161]
	v_add_f32_e32 v195, 1.0, v195
	v_rcp_f32_e32 v198, v195
	v_add_f32_e32 v196, 1.0, v196
	v_mul_f32_e32 v195, 0xbfb8aa3b, v162
	v_rcp_f32_e32 v199, v196
	v_exp_f32_e32 v195, v195
	v_mul_f32_e32 v196, 0xbfb8aa3b, v163
	v_exp_f32_e32 v196, v196
	v_pk_mul_f32 v[160:161], v[160:161], v[198:199]
	v_add_f32_e32 v195, 1.0, v195
	v_rcp_f32_e32 v200, v195
	v_add_f32_e32 v195, 1.0, v196
	v_rcp_f32_e32 v201, v195
	v_cvt_pk_bf16_f32 v160, v160, v161
	v_mul_f32_e32 v161, 0xbfb8aa3b, v164
	v_exp_f32_e32 v195, v161
	v_mul_f32_e32 v161, 0xbfb8aa3b, v165
	v_exp_f32_e32 v196, v161
	v_pk_mul_f32 v[162:163], v[158:159], v[162:163]
	v_pk_mul_f32 v[164:165], v[152:153], v[164:165]
	v_pk_mul_f32 v[162:163], v[162:163], v[200:201]
	s_nop 0
	v_cvt_pk_bf16_f32 v161, v162, v163
	v_add_f32_e32 v162, 1.0, v195
	v_mul_f32_e32 v195, 0xbfb8aa3b, v166
	v_add_f32_e32 v163, 1.0, v196
	v_exp_f32_e32 v195, v195
	v_mul_f32_e32 v196, 0xbfb8aa3b, v167
	v_exp_f32_e32 v196, v196
	v_rcp_f32_e32 v162, v162
	v_add_f32_e32 v195, 1.0, v195
	v_rcp_f32_e32 v198, v195
	v_add_f32_e32 v195, 1.0, v196
	v_rcp_f32_e32 v163, v163
	v_rcp_f32_e32 v199, v195
	v_pk_mul_f32 v[166:167], v[154:155], v[166:167]
	v_pk_mul_f32 v[162:163], v[164:165], v[162:163]
	v_pk_mul_f32 v[164:165], v[166:167], v[198:199]
	v_cvt_pk_bf16_f32 v162, v162, v163
	v_cvt_pk_bf16_f32 v163, v164, v165
	v_mov_b64_e32 v[164:165], s[52:53]
	v_mad_i64_i32 v[164:165], s[42:43], v193, s60, v[164:165]
	v_lshl_add_u64 v[164:165], v[184:185], 1, v[164:165]
	global_store_dwordx4 v[164:165], v[160:163], off

;     DI const char* a(const Unit& u) const { return (const char*)(A + (size_t)u.pm * BM * lda); }
;     DI const char* a(const Unit& u) const { return (const char*)(A + (size_t)u.pm * BM * 2048 + (u.pn >> 1) * 512); }
;     DI const char* a(const Unit& u) const { return (const char*)((u.pn < 12 ? A1 : A2) + (size_t)u.pm * BM * 512); }
; #define PG8_STAGE(bufoff, gbase, voff) do { _Pragma("unroll") for (int _i = 0; _i < 2; ++_i) \
;         __builtin_amdgcn_global_load_lds((const unsigned*)((const char*)(gbase) + (voff)[_i]), (LAS unsigned*)(lds + (bufoff) + ldsw + _i * 8192), 16, 0, 0); } while (0)
; #define PG8_LDA(dst, b, h) do { _Pragma("unroll") for (int m = 0; m < 4; ++m) _Pragma("unroll") for (int k = 0; k < 2; ++k) dst[m][k] = *(const LAS bf16x8*)(lds + PG8_SA(b, h) + aoff + m * 2048 + k * 1024); } while (0)
; #define PG8_LDB(dst, b, h) do { _Pragma("unroll") for (int n = 0; n < 2; ++n) _Pragma("unroll") for (int k = 0; k < 2; ++k) dst[n][k] = *(const LAS bf16x8*)(lds + PG8_SB(b, h) + boff + n * 2048 + k * 1024); } while (0)
; #define PG8_BAR __builtin_amdgcn_s_barrier()
; template <class Map, class Epi>
; DI void gemm_phase(LAS unsigned char* lds, const Map& MP, const Epi& E, const int nM, const int nN, const int K, const int lda, const int ldb) {
;     ...
;         const bool has_next = sched_next(ui + 1, nM, nN, G, cblk, nxt);
;         const char* nA = has_next ? MP.a(nxt) : cA; const char* nB = has_next ? MP.b(nxt) : cB;
;         for (int t = 0; t < nt; t += 2) {
;             const bool last = (t == nt - 2);
;             const char* a1 = cA + (size_t)(t + 1) * kstep;
;             const char* a2 = last ? nA : cA + (size_t)(t + 2) * kstep; const char* b2 = last ? nB : cB + (size_t)(t + 2) * kstep;
;             const char* a3 = a2 + kstep; const char* b3 = b2 + kstep;
;             PG8_LDB(B0, 0, 0); PG8_SCHED; PG8_LDA(At, 0, 0); PG8_STAGE(PG8_SA(1, 1), a1 + hstepA, voffA);
;             PG8_WAIT_L(8); PG8_BAR; PG8_WAIT_L(0); PG8_MMA(0, 0, At, B0); PG8_BAR; PG8_SCHED;
;             PG8_LDB(B1, 0, 1); PG8_STAGE(PG8_SB(0, 0), b2, voffB);
;     ...
;         for (int a = 0; a < 2; ++a)
; #pragma unroll
;             for (int b = 0; b < 2; ++b)
; #pragma unroll
;                 for (int m = 0; m < 4; ++m)
; #pragma unroll
;                     for (int n = 0; n < 2; ++n) acc[a][b][m][n] = (f32x4){0.f, 0.f, 0.f, 0.f};
;         cur = nxt; cA = nA; cB = nB; ++ui;
.LBB1_2077:
	s_add_u32 s39, s10, 0x100
	v_mov_b32_e32 v0, 0
	s_addc_u32 s44, s11, 0
	s_mov_b32 s3, -2
	v_mov_b32_e32 v1, v0
	v_mov_b32_e32 v2, v0
	v_mov_b32_e32 v3, v0
	v_mov_b32_e32 v4, v0
	v_mov_b32_e32 v5, v0
	v_mov_b32_e32 v6, v0
	v_mov_b32_e32 v7, v0
	v_mov_b32_e32 v16, v0
	v_mov_b32_e32 v17, v0
	v_mov_b32_e32 v18, v0
	v_mov_b32_e32 v19, v0
	v_mov_b32_e32 v20, v0
	v_mov_b32_e32 v21, v0
	v_mov_b32_e32 v22, v0
	v_mov_b32_e32 v23, v0
	v_mov_b32_e32 v32, v0
	v_mov_b32_e32 v33, v0
	v_mov_b32_e32 v34, v0
	v_mov_b32_e32 v35, v0
	v_mov_b32_e32 v36, v0
	v_mov_b32_e32 v37, v0
	v_mov_b32_e32 v38, v0
	v_mov_b32_e32 v39, v0
	v_mov_b32_e32 v48, v0
	v_mov_b32_e32 v49, v0
	v_mov_b32_e32 v50, v0
	v_mov_b32_e32 v51, v0
	v_mov_b32_e32 v52, v0
	v_mov_b32_e32 v53, v0
	v_mov_b32_e32 v54, v0
	v_mov_b32_e32 v55, v0
	v_mov_b32_e32 v8, v0
	v_mov_b32_e32 v9, v0
	v_mov_b32_e32 v10, v0
	v_mov_b32_e32 v11, v0
	v_mov_b32_e32 v12, v0
	v_mov_b32_e32 v13, v0
	v_mov_b32_e32 v14, v0
	v_mov_b32_e32 v15, v0
	v_mov_b32_e32 v24, v0
	v_mov_b32_e32 v25, v0
	v_mov_b32_e32 v26, v0
	v_mov_b32_e32 v27, v0
	v_mov_b32_e32 v28, v0
	v_mov_b32_e32 v29, v0
	v_mov_b32_e32 v30, v0
	v_mov_b32_e32 v31, v0
	v_mov_b32_e32 v40, v0
	v_mov_b32_e32 v41, v0
	v_mov_b32_e32 v42, v0
	v_mov_b32_e32 v43, v0
	v_mov_b32_e32 v44, v0
	v_mov_b32_e32 v45, v0
	v_mov_b32_e32 v46, v0
	v_mov_b32_e32 v47, v0
	v_mov_b32_e32 v56, v0
	v_mov_b32_e32 v57, v0
	v_mov_b32_e32 v58, v0
	v_mov_b32_e32 v59, v0
	v_mov_b32_e32 v60, v0
	v_mov_b32_e32 v61, v0
	v_mov_b32_e32 v62, v0
	v_mov_b32_e32 v63, v0
	v_mov_b32_e32 v64, v0
	v_mov_b32_e32 v65, v0
	v_mov_b32_e32 v66, v0
	v_mov_b32_e32 v67, v0
	v_mov_b32_e32 v68, v0
	v_mov_b32_e32 v69, v0
	v_mov_b32_e32 v70, v0
	v_mov_b32_e32 v71, v0
	v_mov_b32_e32 v80, v0
	v_mov_b32_e32 v81, v0
	v_mov_b32_e32 v82, v0
	v_mov_b32_e32 v83, v0
	v_mov_b32_e32 v84, v0
	v_mov_b32_e32 v85, v0
	v_mov_b32_e32 v86, v0
	v_mov_b32_e32 v87, v0
	v_mov_b32_e32 v96, v0
	v_mov_b32_e32 v97, v0
	v_mov_b32_e32 v98, v0
	v_mov_b32_e32 v99, v0
	v_mov_b32_e32 v100, v0
	v_mov_b32_e32 v101, v0
	v_mov_b32_e32 v102, v0
	v_mov_b32_e32 v103, v0
	v_mov_b32_e32 v112, v0
	v_mov_b32_e32 v113, v0
	v_mov_b32_e32 v114, v0
	v_mov_b32_e32 v115, v0
	v_mov_b32_e32 v116, v0
	v_mov_b32_e32 v117, v0
	v_mov_b32_e32 v118, v0
	v_mov_b32_e32 v119, v0
	v_mov_b32_e32 v72, v0
	v_mov_b32_e32 v73, v0
	v_mov_b32_e32 v74, v0
	v_mov_b32_e32 v75, v0
	v_mov_b32_e32 v76, v0
	v_mov_b32_e32 v77, v0
	v_mov_b32_e32 v78, v0
	v_mov_b32_e32 v79, v0
	v_mov_b32_e32 v88, v0
	v_mov_b32_e32 v89, v0
	v_mov_b32_e32 v90, v0
	v_mov_b32_e32 v91, v0
	v_mov_b32_e32 v92, v0
	v_mov_b32_e32 v93, v0
	v_mov_b32_e32 v94, v0
	v_mov_b32_e32 v95, v0
	v_mov_b32_e32 v104, v0
	v_mov_b32_e32 v105, v0
	v_mov_b32_e32 v106, v0
	v_mov_b32_e32 v107, v0
	v_mov_b32_e32 v108, v0
	v_mov_b32_e32 v109, v0
	v_mov_b32_e32 v110, v0
	v_mov_b32_e32 v111, v0
	v_mov_b32_e32 v120, v0
	v_mov_b32_e32 v121, v0
	v_mov_b32_e32 v122, v0
	v_mov_b32_e32 v123, v0
	v_mov_b32_e32 v124, v0
	v_mov_b32_e32 v125, v0
	v_mov_b32_e32 v126, v0
	v_mov_b32_e32 v127, v0
	ds_read_b128 v[152:155], v149
	ds_read_b128 v[156:159], v149 offset:1024
	ds_read_b128 v[160:163], v149 offset:2048
	ds_read_b128 v[164:167], v149 offset:3072
.LBB1_2078:
	s_add_u32 s10, s8, 0x100
	s_addc_u32 s11, s9, 0
	s_cmpk_eq_i32 s3, 0x54
	s_cselect_b32 s15, s43, s11
	s_cselect_b32 s14, s42, s10
	s_cselect_b32 s13, s7, s44
	s_cselect_b32 s12, s6, s39
	s_add_i32 m0, s24, 0xc000
	ds_read_b128 v[168:171], v150
	ds_read_b128 v[172:175], v150 offset:1024
	ds_read_b128 v[176:179], v150 offset:2048
	ds_read_b128 v[180:183], v150 offset:3072
	ds_read_b128 v[184:187], v150 offset:4096
	ds_read_b128 v[188:191], v150 offset:5120
	ds_read_b128 v[192:195], v150 offset:6144
	ds_read_b128 v[198:201], v150 offset:7168
	global_load_lds_dwordx4 v138, s[8:9]
	s_add_i32 m0, s24, 0xe000
	s_nop 0
	global_load_lds_dwordx4 v136, s[8:9]
	s_waitcnt lgkmcnt(8)
	s_barrier
	s_setprio 1
	s_waitcnt lgkmcnt(7)
	v_mfma_f32_16x16x32_bf16 v[124:127], v[152:155], v[168:171], v[124:127]
	v_mfma_f32_16x16x32_bf16 v[120:123], v[160:163], v[168:171], v[120:123]
	s_waitcnt lgkmcnt(5)
	v_mfma_f32_16x16x32_bf16 v[108:111], v[152:155], v[176:179], v[108:111]
	v_mfma_f32_16x16x32_bf16 v[104:107], v[160:163], v[176:179], v[104:107]
	s_waitcnt lgkmcnt(3)
	v_mfma_f32_16x16x32_bf16 v[92:95], v[152:155], v[184:187], v[92:95]
	v_mfma_f32_16x16x32_bf16 v[88:91], v[160:163], v[184:187], v[88:91]
	s_waitcnt lgkmcnt(1)
	v_mfma_f32_16x16x32_bf16 v[76:79], v[152:155], v[192:195], v[76:79]
	v_mfma_f32_16x16x32_bf16 v[72:75], v[160:163], v[192:195], v[72:75]
	v_mfma_f32_16x16x32_bf16 v[124:127], v[156:159], v[172:175], v[124:127]
	v_mfma_f32_16x16x32_bf16 v[120:123], v[164:167], v[172:175], v[120:123]
	v_mfma_f32_16x16x32_bf16 v[108:111], v[156:159], v[180:183], v[108:111]
	v_mfma_f32_16x16x32_bf16 v[104:107], v[164:167], v[180:183], v[104:107]
	v_mfma_f32_16x16x32_bf16 v[92:95], v[156:159], v[188:191], v[92:95]
	v_mfma_f32_16x16x32_bf16 v[88:91], v[164:167], v[188:191], v[88:91]
	s_waitcnt lgkmcnt(0)
	v_mfma_f32_16x16x32_bf16 v[76:79], v[156:159], v[198:201], v[76:79]
	v_mfma_f32_16x16x32_bf16 v[72:75], v[164:167], v[198:201], v[72:75]
	s_setprio 0
	s_barrier
	s_add_i32 s8, s35, s22
	v_lshl_add_u64 v[144:145], s[12:13], 0, v[132:133]
	s_mov_b32 m0, s8
	ds_read_b128 v[202:205], v151
	ds_read_b128 v[206:209], v151 offset:1024
	ds_read_b128 v[210:213], v151 offset:2048
	ds_read_b128 v[214:217], v151 offset:3072
	global_load_lds_dwordx4 v[144:145], off
	v_lshl_add_u64 v[218:219], s[12:13], 0, v[128:129]
	s_add_i32 m0, s8, 0x2000
	s_nop 0
	global_load_lds_dwordx4 v[218:219], off
	s_barrier
; #define PG8_STAGE(bufoff, gbase, voff) do { _Pragma("unroll") for (int _i = 0; _i < 2; ++_i) \
;         __builtin_amdgcn_global_load_lds((const unsigned*)((const char*)(gbase) + (voff)[_i]), (LAS unsigned*)(lds + (bufoff) + ldsw + _i * 8192), 16, 0, 0); } while (0)
; #define PG8_LDA(dst, b, h) do { _Pragma("unroll") for (int m = 0; m < 4; ++m) _Pragma("unroll") for (int k = 0; k < 2; ++k) dst[m][k] = *(const LAS bf16x8*)(lds + PG8_SA(b, h) + aoff + m * 2048 + k * 1024); } while (0)
; #define PG8_LDB(dst, b, h) do { _Pragma("unroll") for (int n = 0; n < 2; ++n) _Pragma("unroll") for (int k = 0; k < 2; ++k) dst[n][k] = *(const LAS bf16x8*)(lds + PG8_SB(b, h) + boff + n * 2048 + k * 1024); } while (0)
; #define PG8_MMA(ai, bj, At, Bt) do { __builtin_amdgcn_s_setprio(1); _Pragma("unroll") for (int m = 0; m < 4; ++m) _Pragma("unroll") for (int n = 0; n < 2; ++n) _Pragma("unroll") for (int k = 0; k < 2; ++k) \
;         acc[ai][bj][m][n] = __builtin_amdgcn_mfma_f32_16x16x32_bf16(Bt[n][k], At[m][k], acc[ai][bj][m][n], 0, 0, 0); __builtin_amdgcn_s_setprio(0); } while (0)
; #define PG8_WAIT_V(n) asm volatile("s_waitcnt vmcnt(" #n ")" ::: "memory")
; #define PG8_WAIT_L(n) asm volatile("s_waitcnt lgkmcnt(" #n ")" ::: "memory")
; #define PG8_BAR __builtin_amdgcn_s_barrier()
; #define PG8_SCHED __builtin_amdgcn_sched_barrier(0)
; template <class Map, class Epi>
; DI void gemm_phase(LAS unsigned char* lds, const Map& MP, const Epi& E, const int nM, const int nN, const int K, const int lda, const int ldb) {
;     ...
;             PG8_BAR; PG8_WAIT_L(0); PG8_MMA(0, 1, At, B1); PG8_BAR;
;             PG8_LDA(At, 0, 1); PG8_STAGE(PG8_SA(0, 0), a2, voffA);
;             PG8_BAR; PG8_WAIT_L(0); PG8_MMA(1, 0, At, B0); PG8_BAR; PG8_SCHED;
;             PG8_STAGE(PG8_SB(0, 1), b2 + hstepB, voffB);
;             PG8_WAIT_V(6); PG8_BAR; PG8_MMA(1, 1, At, B1); PG8_BAR;
;             PG8_LDB(B0, 1, 0); PG8_SCHED; PG8_LDA(At, 1, 0); PG8_STAGE(PG8_SA(0, 1), a2 + hstepA, voffA);
	s_setprio 1
	s_waitcnt lgkmcnt(3)
	v_mfma_f32_16x16x32_bf16 v[116:119], v[202:205], v[168:171], v[116:119]
	s_waitcnt lgkmcnt(1)
	v_mfma_f32_16x16x32_bf16 v[112:115], v[210:213], v[168:171], v[112:115]
	v_mfma_f32_16x16x32_bf16 v[100:103], v[202:205], v[176:179], v[100:103]
	v_mfma_f32_16x16x32_bf16 v[96:99], v[210:213], v[176:179], v[96:99]
	v_mfma_f32_16x16x32_bf16 v[84:87], v[202:205], v[184:187], v[84:87]
	v_mfma_f32_16x16x32_bf16 v[80:83], v[210:213], v[184:187], v[80:83]
	v_mfma_f32_16x16x32_bf16 v[68:71], v[202:205], v[192:195], v[68:71]
	v_mfma_f32_16x16x32_bf16 v[64:67], v[210:213], v[192:195], v[64:67]
	v_mfma_f32_16x16x32_bf16 v[116:119], v[206:209], v[172:175], v[116:119]
	s_waitcnt lgkmcnt(0)
	v_mfma_f32_16x16x32_bf16 v[112:115], v[214:217], v[172:175], v[112:115]
	v_mfma_f32_16x16x32_bf16 v[100:103], v[206:209], v[180:183], v[100:103]
	v_mfma_f32_16x16x32_bf16 v[96:99], v[214:217], v[180:183], v[96:99]
	v_mfma_f32_16x16x32_bf16 v[84:87], v[206:209], v[188:191], v[84:87]
	v_mfma_f32_16x16x32_bf16 v[80:83], v[214:217], v[188:191], v[80:83]
	v_mfma_f32_16x16x32_bf16 v[68:71], v[206:209], v[198:201], v[68:71]
	v_mfma_f32_16x16x32_bf16 v[64:67], v[214:217], v[198:201], v[64:67]
	s_setprio 0
	s_mov_b32 m0, s24
	v_lshl_add_u64 v[220:221], s[14:15], 0, v[134:135]
	s_barrier
	ds_read_b128 v[168:171], v150 offset:16384
	ds_read_b128 v[172:175], v150 offset:17408
	ds_read_b128 v[176:179], v150 offset:18432
	ds_read_b128 v[180:183], v150 offset:19456
	ds_read_b128 v[184:187], v150 offset:20480
	ds_read_b128 v[188:191], v150 offset:21504
	ds_read_b128 v[192:195], v150 offset:22528
	ds_read_b128 v[198:201], v150 offset:23552
	global_load_lds_dwordx4 v[220:221], off
	v_lshl_add_u64 v[222:223], s[14:15], 0, v[130:131]
	s_mov_b32 m0, s25
	s_nop 0
	global_load_lds_dwordx4 v[222:223], off
	s_waitcnt vmcnt(10)
	s_barrier
	s_setprio 1
	s_waitcnt lgkmcnt(7)
	v_mfma_f32_16x16x32_bf16 v[60:63], v[152:155], v[168:171], v[60:63]
	v_mfma_f32_16x16x32_bf16 v[56:59], v[160:163], v[168:171], v[56:59]
	s_waitcnt lgkmcnt(5)
	v_mfma_f32_16x16x32_bf16 v[44:47], v[152:155], v[176:179], v[44:47]
	v_mfma_f32_16x16x32_bf16 v[40:43], v[160:163], v[176:179], v[40:43]
	s_waitcnt lgkmcnt(3)
	v_mfma_f32_16x16x32_bf16 v[28:31], v[152:155], v[184:187], v[28:31]
	v_mfma_f32_16x16x32_bf16 v[24:27], v[160:163], v[184:187], v[24:27]
	s_waitcnt lgkmcnt(1)
	v_mfma_f32_16x16x32_bf16 v[12:15], v[152:155], v[192:195], v[12:15]
	v_mfma_f32_16x16x32_bf16 v[8:11], v[160:163], v[192:195], v[8:11]
	v_mfma_f32_16x16x32_bf16 v[60:63], v[156:159], v[172:175], v[60:63]
	v_mfma_f32_16x16x32_bf16 v[56:59], v[164:167], v[172:175], v[56:59]
	v_mfma_f32_16x16x32_bf16 v[44:47], v[156:159], v[180:183], v[44:47]
	v_mfma_f32_16x16x32_bf16 v[40:43], v[164:167], v[180:183], v[40:43]
	v_mfma_f32_16x16x32_bf16 v[28:31], v[156:159], v[188:191], v[28:31]
	v_mfma_f32_16x16x32_bf16 v[24:27], v[164:167], v[188:191], v[24:27]
	s_waitcnt lgkmcnt(0)
	v_mfma_f32_16x16x32_bf16 v[12:15], v[156:159], v[198:201], v[12:15]
	v_mfma_f32_16x16x32_bf16 v[8:11], v[164:167], v[198:201], v[8:11]
	s_setprio 0
	s_barrier
	s_add_u32 s8, s12, 0x160000
	s_addc_u32 s9, s13, 0
	s_add_i32 s45, s36, s22
	s_mov_b32 m0, s45
	s_nop 0
	global_load_lds_dwordx4 v132, s[8:9]
	s_add_i32 m0, s45, 0x2000
	s_nop 0
	global_load_lds_dwordx4 v128, s[8:9]
	s_waitcnt vmcnt(6)
	s_barrier
	s_setprio 1
	v_mfma_f32_16x16x32_bf16 v[52:55], v[202:205], v[168:171], v[52:55]
	v_mfma_f32_16x16x32_bf16 v[48:51], v[210:213], v[168:171], v[48:51]
	s_add_i32 s45, 0, 0x18000
	v_add_u32_e32 v164, s45, v148
	ds_read_b128 v[152:155], v164
	v_mfma_f32_16x16x32_bf16 v[36:39], v[202:205], v[176:179], v[36:39]
	v_mfma_f32_16x16x32_bf16 v[32:35], v[210:213], v[176:179], v[32:35]
	ds_read_b128 v[156:159], v164 offset:1024
	v_mfma_f32_16x16x32_bf16 v[20:23], v[202:205], v[184:187], v[20:23]
	v_mfma_f32_16x16x32_bf16 v[16:19], v[210:213], v[184:187], v[16:19]
	ds_read_b128 v[160:163], v164 offset:2048
	v_mfma_f32_16x16x32_bf16 v[4:7], v[202:205], v[192:195], v[4:7]
	v_mfma_f32_16x16x32_bf16 v[0:3], v[210:213], v[192:195], v[0:3]
	ds_read_b128 v[164:167], v164 offset:3072
	v_mfma_f32_16x16x32_bf16 v[52:55], v[206:209], v[172:175], v[52:55]
	v_mfma_f32_16x16x32_bf16 v[48:51], v[214:217], v[172:175], v[48:51]
	v_mfma_f32_16x16x32_bf16 v[36:39], v[206:209], v[180:183], v[36:39]
	v_mfma_f32_16x16x32_bf16 v[32:35], v[214:217], v[180:183], v[32:35]
	v_mfma_f32_16x16x32_bf16 v[20:23], v[206:209], v[188:191], v[20:23]
	v_mfma_f32_16x16x32_bf16 v[16:19], v[214:217], v[188:191], v[16:19]
	v_mfma_f32_16x16x32_bf16 v[4:7], v[206:209], v[198:201], v[4:7]
	v_mfma_f32_16x16x32_bf16 v[0:3], v[214:217], v[198:201], v[0:3]
	s_setprio 0
	s_barrier
	s_add_u32 s8, s14, 0x160000
	s_addc_u32 s9, s15, 0
	s_mov_b32 m0, s26
	ds_read_b128 v[168:171], v150 offset:32768
	ds_read_b128 v[172:175], v150 offset:33792
	ds_read_b128 v[176:179], v150 offset:34816
	ds_read_b128 v[180:183], v150 offset:35840
	ds_read_b128 v[184:187], v150 offset:36864
	ds_read_b128 v[188:191], v150 offset:37888
	ds_read_b128 v[192:195], v150 offset:38912
	ds_read_b128 v[198:201], v150 offset:39936
	global_load_lds_dwordx4 v134, s[8:9]
	s_mov_b32 m0, s27
	s_nop 0
	global_load_lds_dwordx4 v130, s[8:9]
	s_waitcnt lgkmcnt(8)
	s_barrier
; #define PG8_STAGE(bufoff, gbase, voff) do { _Pragma("unroll") for (int _i = 0; _i < 2; ++_i) \
;         __builtin_amdgcn_global_load_lds((const unsigned*)((const char*)(gbase) + (voff)[_i]), (LAS unsigned*)(lds + (bufoff) + ldsw + _i * 8192), 16, 0, 0); } while (0)
; #define PG8_LDA(dst, b, h) do { _Pragma("unroll") for (int m = 0; m < 4; ++m) _Pragma("unroll") for (int k = 0; k < 2; ++k) dst[m][k] = *(const LAS bf16x8*)(lds + PG8_SA(b, h) + aoff + m * 2048 + k * 1024); } while (0)
; #define PG8_LDB(dst, b, h) do { _Pragma("unroll") for (int n = 0; n < 2; ++n) _Pragma("unroll") for (int k = 0; k < 2; ++k) dst[n][k] = *(const LAS bf16x8*)(lds + PG8_SB(b, h) + boff + n * 2048 + k * 1024); } while (0)
; #define PG8_MMA(ai, bj, At, Bt) do { __builtin_amdgcn_s_setprio(1); _Pragma("unroll") for (int m = 0; m < 4; ++m) _Pragma("unroll") for (int n = 0; n < 2; ++n) _Pragma("unroll") for (int k = 0; k < 2; ++k) \
;         acc[ai][bj][m][n] = __builtin_amdgcn_mfma_f32_16x16x32_bf16(Bt[n][k], At[m][k], acc[ai][bj][m][n], 0, 0, 0); __builtin_amdgcn_s_setprio(0); } while (0)
; #define PG8_WAIT_V(n) asm volatile("s_waitcnt vmcnt(" #n ")" ::: "memory")
; #define PG8_WAIT_L(n) asm volatile("s_waitcnt lgkmcnt(" #n ")" ::: "memory")
; #define PG8_BAR __builtin_amdgcn_s_barrier()
; #define PG8_SCHED __builtin_amdgcn_sched_barrier(0)
; template <class Map, class Epi>
; DI void gemm_phase(LAS unsigned char* lds, const Map& MP, const Epi& E, const int nM, const int nN, const int K, const int lda, const int ldb) {
;     ...
;             PG8_WAIT_L(8); PG8_BAR; PG8_WAIT_L(0); PG8_MMA(0, 0, At, B0); PG8_BAR; PG8_SCHED;
;             PG8_LDB(B1, 1, 1); PG8_STAGE(PG8_SB(1, 0), b3, voffB);
;             PG8_BAR; PG8_WAIT_L(0); PG8_MMA(0, 1, At, B1); PG8_BAR;
;             PG8_LDA(At, 1, 1); PG8_STAGE(PG8_SA(1, 0), a3, voffA);
;             PG8_BAR; PG8_WAIT_L(0); PG8_MMA(1, 0, At, B0); PG8_BAR; PG8_SCHED;
;             PG8_STAGE(PG8_SB(1, 1), b3 + hstepB, voffB);
;             PG8_WAIT_V(6); PG8_BAR; PG8_MMA(1, 1, At, B1); PG8_BAR;
	s_setprio 1
	s_waitcnt lgkmcnt(7)
	v_mfma_f32_16x16x32_bf16 v[124:127], v[152:155], v[168:171], v[124:127]
	v_mfma_f32_16x16x32_bf16 v[120:123], v[160:163], v[168:171], v[120:123]
	s_waitcnt lgkmcnt(5)
	v_mfma_f32_16x16x32_bf16 v[108:111], v[152:155], v[176:179], v[108:111]
	v_mfma_f32_16x16x32_bf16 v[104:107], v[160:163], v[176:179], v[104:107]
	s_waitcnt lgkmcnt(3)
	v_mfma_f32_16x16x32_bf16 v[92:95], v[152:155], v[184:187], v[92:95]
	v_mfma_f32_16x16x32_bf16 v[88:91], v[160:163], v[184:187], v[88:91]
	s_waitcnt lgkmcnt(1)
	v_mfma_f32_16x16x32_bf16 v[76:79], v[152:155], v[192:195], v[76:79]
	v_mfma_f32_16x16x32_bf16 v[72:75], v[160:163], v[192:195], v[72:75]
	v_mfma_f32_16x16x32_bf16 v[124:127], v[156:159], v[172:175], v[124:127]
	v_mfma_f32_16x16x32_bf16 v[120:123], v[164:167], v[172:175], v[120:123]
	v_mfma_f32_16x16x32_bf16 v[108:111], v[156:159], v[180:183], v[108:111]
	v_mfma_f32_16x16x32_bf16 v[104:107], v[164:167], v[180:183], v[104:107]
	v_mfma_f32_16x16x32_bf16 v[92:95], v[156:159], v[188:191], v[92:95]
	v_mfma_f32_16x16x32_bf16 v[88:91], v[164:167], v[188:191], v[88:91]
	s_waitcnt lgkmcnt(0)
	v_mfma_f32_16x16x32_bf16 v[76:79], v[156:159], v[198:201], v[76:79]
	v_mfma_f32_16x16x32_bf16 v[72:75], v[164:167], v[198:201], v[72:75]
	s_setprio 0
	s_barrier
	s_add_i32 s14, 0, 0x1c000
	s_add_i32 s8, s45, s22
	v_add_u32_e32 v196, s14, v148
	v_lshl_add_u64 v[144:145], v[144:145], 0, s[46:47]
	s_mov_b32 m0, s8
	ds_read_b128 v[202:205], v196
	ds_read_b128 v[206:209], v196 offset:1024
	ds_read_b128 v[210:213], v196 offset:2048
	ds_read_b128 v[214:217], v196 offset:3072
	global_load_lds_dwordx4 v[144:145], off
	v_lshl_add_u64 v[144:145], v[218:219], 0, s[46:47]
	s_add_i32 m0, s8, 0x2000
	s_nop 0
	global_load_lds_dwordx4 v[144:145], off
	s_barrier
	s_setprio 1
	s_waitcnt lgkmcnt(3)
	v_mfma_f32_16x16x32_bf16 v[116:119], v[202:205], v[168:171], v[116:119]
	s_waitcnt lgkmcnt(1)
	v_mfma_f32_16x16x32_bf16 v[112:115], v[210:213], v[168:171], v[112:115]
	v_mfma_f32_16x16x32_bf16 v[100:103], v[202:205], v[176:179], v[100:103]
	v_mfma_f32_16x16x32_bf16 v[96:99], v[210:213], v[176:179], v[96:99]
	v_mfma_f32_16x16x32_bf16 v[84:87], v[202:205], v[184:187], v[84:87]
	v_mfma_f32_16x16x32_bf16 v[80:83], v[210:213], v[184:187], v[80:83]
	v_mfma_f32_16x16x32_bf16 v[68:71], v[202:205], v[192:195], v[68:71]
	v_mfma_f32_16x16x32_bf16 v[64:67], v[210:213], v[192:195], v[64:67]
	v_mfma_f32_16x16x32_bf16 v[116:119], v[206:209], v[172:175], v[116:119]
	s_waitcnt lgkmcnt(0)
	v_mfma_f32_16x16x32_bf16 v[112:115], v[214:217], v[172:175], v[112:115]
	v_mfma_f32_16x16x32_bf16 v[100:103], v[206:209], v[180:183], v[100:103]
	v_mfma_f32_16x16x32_bf16 v[96:99], v[214:217], v[180:183], v[96:99]
	v_mfma_f32_16x16x32_bf16 v[84:87], v[206:209], v[188:191], v[84:87]
	v_mfma_f32_16x16x32_bf16 v[80:83], v[214:217], v[188:191], v[80:83]
	v_mfma_f32_16x16x32_bf16 v[68:71], v[206:209], v[198:201], v[68:71]
	v_mfma_f32_16x16x32_bf16 v[64:67], v[214:217], v[198:201], v[64:67]
	s_setprio 0
	s_mov_b32 m0, s30
	v_lshl_add_u64 v[144:145], v[220:221], 0, s[46:47]
	s_barrier
	ds_read_b128 v[168:171], v150 offset:49152
	ds_read_b128 v[172:175], v150 offset:50176
	ds_read_b128 v[176:179], v150 offset:51200
	ds_read_b128 v[180:183], v150 offset:52224
	ds_read_b128 v[184:187], v150 offset:53248
	ds_read_b128 v[188:191], v150 offset:54272
	ds_read_b128 v[192:195], v150 offset:55296
	ds_read_b128 v[198:201], v150 offset:56320
	global_load_lds_dwordx4 v[144:145], off
	v_lshl_add_u64 v[144:145], v[222:223], 0, s[46:47]
	s_mov_b32 m0, s31
	s_nop 0
	global_load_lds_dwordx4 v[144:145], off
	s_waitcnt vmcnt(10)
	s_barrier
	s_setprio 1
	s_waitcnt lgkmcnt(7)
	v_mfma_f32_16x16x32_bf16 v[60:63], v[152:155], v[168:171], v[60:63]
	v_mfma_f32_16x16x32_bf16 v[56:59], v[160:163], v[168:171], v[56:59]
	s_waitcnt lgkmcnt(5)
	v_mfma_f32_16x16x32_bf16 v[44:47], v[152:155], v[176:179], v[44:47]
	v_mfma_f32_16x16x32_bf16 v[40:43], v[160:163], v[176:179], v[40:43]
	s_waitcnt lgkmcnt(3)
	v_mfma_f32_16x16x32_bf16 v[28:31], v[152:155], v[184:187], v[28:31]
	v_mfma_f32_16x16x32_bf16 v[24:27], v[160:163], v[184:187], v[24:27]
	s_waitcnt lgkmcnt(1)
	v_mfma_f32_16x16x32_bf16 v[12:15], v[152:155], v[192:195], v[12:15]
	v_mfma_f32_16x16x32_bf16 v[8:11], v[160:163], v[192:195], v[8:11]
	v_mfma_f32_16x16x32_bf16 v[60:63], v[156:159], v[172:175], v[60:63]
	v_mfma_f32_16x16x32_bf16 v[56:59], v[164:167], v[172:175], v[56:59]
	v_mfma_f32_16x16x32_bf16 v[44:47], v[156:159], v[180:183], v[44:47]
	v_mfma_f32_16x16x32_bf16 v[40:43], v[164:167], v[180:183], v[40:43]
	v_mfma_f32_16x16x32_bf16 v[28:31], v[156:159], v[188:191], v[28:31]
	v_mfma_f32_16x16x32_bf16 v[24:27], v[164:167], v[188:191], v[24:27]
	s_waitcnt lgkmcnt(0)
	v_mfma_f32_16x16x32_bf16 v[12:15], v[156:159], v[198:201], v[12:15]
	v_mfma_f32_16x16x32_bf16 v[8:11], v[164:167], v[198:201], v[8:11]
	s_setprio 0
	s_barrier
	s_add_u32 s8, s12, 0x160080
	s_addc_u32 s9, s13, 0
	s_add_i32 s12, s14, s22
	s_mov_b32 m0, s12
	s_nop 0
	global_load_lds_dwordx4 v132, s[8:9]
	s_add_i32 m0, s12, 0x2000
	s_nop 0
	global_load_lds_dwordx4 v128, s[8:9]
	s_waitcnt vmcnt(6)
	s_barrier
; DI unsigned pack2(float a, float b) { f32x2 v = {a, b}; hwbf16x2 r = __builtin_convertvector(v, hwbf16x2); return __builtin_bit_cast(unsigned, r); }
; DI float bflo(unsigned w) { return __uint_as_float(w << 16); }
; DI float bfhi(unsigned w) { return __uint_as_float(w & 0xffff0000u); }
; #define PG8_MMA(ai, bj, At, Bt) do { __builtin_amdgcn_s_setprio(1); _Pragma("unroll") for (int m = 0; m < 4; ++m) _Pragma("unroll") for (int n = 0; n < 2; ++n) _Pragma("unroll") for (int k = 0; k < 2; ++k) \
;         acc[ai][bj][m][n] = __builtin_amdgcn_mfma_f32_16x16x32_bf16(Bt[n][k], At[m][k], acc[ai][bj][m][n], 0, 0, 0); __builtin_amdgcn_s_setprio(0); } while (0)
; #define PG8_WAIT_V(n) asm volatile("s_waitcnt vmcnt(" #n ")" ::: "memory")
;     DI void operator()(const f32x4 (&acc)[2][2][4][2], const Unit& u, int wr, int wc, int fr, int fq) const {
;     ...
;         for (int ai = 0; ai < 2; ++ai)
; #pragma unroll
;             for (int m = 0; m < 4; ++m) { const size_t ro = (size_t)(row0 + ai * HALF + m * 16) * D + col0;
; #pragma unroll
;                 for (int bj = 0; bj < 2; ++bj) {
;                     f32x4 x0, x1;
;                     if constexpr (IB) { const u32x4 w = *(const u32x4*)((const bf16_t*)Xin + ro + bj * HALF);
;                         x0 = (f32x4){bflo(w[0]), bfhi(w[0]), bflo(w[1]), bfhi(w[1])}; x1 = (f32x4){bflo(w[2]), bfhi(w[2]), bflo(w[3]), bfhi(w[3])}; }
;                     else { x0 = *(const f32x4*)((const float*)Xin + ro + bj * HALF); x1 = *(const f32x4*)((const float*)Xin + ro + bj * HALF + 4); }
;                     x0 += acc[ai][bj][m][0] * sc[bj][0]; x1 += acc[ai][bj][m][1] * sc[bj][1];
;                     if constexpr (OB) { u32x4 o; o[0] = pack2(x0[0], x0[1]); o[1] = pack2(x0[2], x0[3]); o[2] = pack2(x1[0], x1[1]); o[3] = pack2(x1[2], x1[3]);
;                         *(u32x4*)((bf16_t*)Xout + ro + bj * HALF) = o; }
;                     else { *(f32x4*)((float*)Xout + ro + bj * HALF) = x0; *(f32x4*)((float*)Xout + ro + bj * HALF + 4) = x1; } } }
; template <class Map, class Epi>
; DI void gemm_phase(LAS unsigned char* lds, const Map& MP, const Epi& E, const int nM, const int nN, const int K, const int lda, const int ldb) {
;     ...
;             PG8_WAIT_V(6); PG8_BAR; PG8_MMA(1, 1, At, B1); PG8_BAR;
;         }
;         { int frr = fr, fqq = fq; asm volatile("" : "+v"(frr), "+v"(fqq)); E(acc, cur, wr, wc, frr, fqq); }
	s_setprio 1
	v_mfma_f32_16x16x32_bf16 v[52:55], v[202:205], v[168:171], v[52:55]
	v_mfma_f32_16x16x32_bf16 v[48:51], v[210:213], v[168:171], v[48:51]
	ds_read_b128 v[152:155], v149
	v_mfma_f32_16x16x32_bf16 v[36:39], v[202:205], v[176:179], v[36:39]
	v_mfma_f32_16x16x32_bf16 v[32:35], v[210:213], v[176:179], v[32:35]
	ds_read_b128 v[156:159], v149 offset:1024
	v_mfma_f32_16x16x32_bf16 v[20:23], v[202:205], v[184:187], v[20:23]
	v_mfma_f32_16x16x32_bf16 v[16:19], v[210:213], v[184:187], v[16:19]
	ds_read_b128 v[160:163], v149 offset:2048
	v_mfma_f32_16x16x32_bf16 v[4:7], v[202:205], v[192:195], v[4:7]
	v_mfma_f32_16x16x32_bf16 v[0:3], v[210:213], v[192:195], v[0:3]
	ds_read_b128 v[164:167], v149 offset:3072
	v_mfma_f32_16x16x32_bf16 v[52:55], v[206:209], v[172:175], v[52:55]
	v_mfma_f32_16x16x32_bf16 v[48:51], v[214:217], v[172:175], v[48:51]
	v_mfma_f32_16x16x32_bf16 v[36:39], v[206:209], v[180:183], v[36:39]
	v_mfma_f32_16x16x32_bf16 v[32:35], v[214:217], v[180:183], v[32:35]
	v_mfma_f32_16x16x32_bf16 v[20:23], v[206:209], v[188:191], v[20:23]
	v_mfma_f32_16x16x32_bf16 v[16:19], v[214:217], v[188:191], v[16:19]
	v_mfma_f32_16x16x32_bf16 v[4:7], v[206:209], v[198:201], v[4:7]
	v_mfma_f32_16x16x32_bf16 v[0:3], v[214:217], v[198:201], v[0:3]
	s_setprio 0
	s_add_i32 s3, s3, 2
	s_add_u32 s39, s39, 0x100
	s_addc_u32 s44, s44, 0
	s_cmpk_gt_u32 s3, 0x55
	s_mov_b64 s[8:9], s[10:11]
	s_barrier
	s_cbranch_scc0 .LBB1_2078
	s_waitcnt lgkmcnt(0)
	v_mov_b32_e32 v152, v147
	v_mov_b32_e32 v144, v146
	s_lshl_b32 s2, s2, 8
	s_add_i32 s2, s2, s29
	s_lshl_b32 s3, s38, 8
	v_add_u32_e32 v152, s2, v152
	s_or_b32 s3, s3, s52
	v_ashrrev_i32_e32 v153, 31, v152
	v_lshl_add_u32 v144, v144, 3, s3
	v_lshlrev_b64 v[152:153], 12, v[152:153]
	v_ashrrev_i32_e32 v145, 31, v144
	v_lshl_add_u64 v[152:153], s[4:5], 0, v[152:153]
	v_lshl_add_u64 v[144:145], v[144:145], 1, v[152:153]
	global_load_dwordx4 v[160:163], v[144:145], off
	global_load_dwordx4 v[164:167], v[144:145], off offset:256
	s_mov_b64 s[98:99], 0x10000
	v_lshl_add_u64 v[154:155], v[144:145], 0, s[98:99]
	global_load_dwordx4 v[168:171], v[154:155], off
	global_load_dwordx4 v[172:175], v[154:155], off offset:256
	s_mov_b64 s[98:99], 0x20000
	v_lshl_add_u64 v[154:155], v[144:145], 0, s[98:99]
	global_load_dwordx4 v[176:179], v[154:155], off
	global_load_dwordx4 v[180:183], v[154:155], off offset:256
	s_mov_b64 s[98:99], 0x30000
	v_lshl_add_u64 v[154:155], v[144:145], 0, s[98:99]
	global_load_dwordx4 v[184:187], v[154:155], off
	global_load_dwordx4 v[188:191], v[154:155], off offset:256
	s_mov_b64 s[98:99], 0x80000
	v_lshl_add_u64 v[154:155], v[144:145], 0, s[98:99]
	global_load_dwordx4 v[192:195], v[154:155], off
	global_load_dwordx4 v[198:201], v[154:155], off offset:256
	s_mov_b64 s[98:99], 0x90000
	v_lshl_add_u64 v[154:155], v[144:145], 0, s[98:99]
	global_load_dwordx4 v[202:205], v[154:155], off
	global_load_dwordx4 v[206:209], v[154:155], off offset:256
	s_mov_b64 s[98:99], 0xa0000
	v_lshl_add_u64 v[154:155], v[144:145], 0, s[98:99]
	global_load_dwordx4 v[210:213], v[154:155], off
	global_load_dwordx4 v[214:217], v[154:155], off offset:256
	s_mov_b64 s[98:99], 0xb0000
	v_lshl_add_u64 v[154:155], v[144:145], 0, s[98:99]
	global_load_dwordx4 v[248:251], v[154:155], off
	global_load_dwordx4 v[252:255], v[154:155], off offset:256
	s_waitcnt vmcnt(15)
	s_nop 1
	v_mov_b32_e32 v152, v160
	v_mov_b32_e32 v153, v161
	v_mov_b32_e32 v154, v162
	v_mov_b32_e32 v155, v163
	s_mov_b64 s[2:3], 0x10000
	s_mov_b32 s38, s37
	s_mov_b64 s[10:11], s[6:7]
	s_mov_b64 s[8:9], s[42:43]
	s_waitcnt lgkmcnt(0)
	v_lshlrev_b32_e32 v156, 16, v152
	v_and_b32_e32 v157, 0xffff0000, v152
	v_lshlrev_b32_e32 v152, 16, v153
	v_and_b32_e32 v153, 0xffff0000, v153
	v_lshlrev_b32_e32 v158, 16, v154
	v_and_b32_e32 v159, 0xffff0000, v154
	v_lshlrev_b32_e32 v154, 16, v155
	v_and_b32_e32 v155, 0xffff0000, v155
	v_pk_add_f32 v[126:127], v[126:127], v[152:153]
	v_pk_add_f32 v[124:125], v[124:125], v[156:157]
	v_pk_add_f32 v[152:153], v[122:123], v[154:155]
	v_pk_add_f32 v[122:123], v[120:121], v[158:159]
	v_cvt_pk_bf16_f32 v120, v124, v125
	v_cvt_pk_bf16_f32 v121, v126, v127
	v_cvt_pk_bf16_f32 v122, v122, v123
	v_cvt_pk_bf16_f32 v123, v152, v153
	global_store_dwordx4 v[144:145], v[120:123], off
	s_waitcnt vmcnt(15)
	s_nop 1
	v_mov_b32_e32 v120, v164
	v_mov_b32_e32 v121, v165
	v_mov_b32_e32 v122, v166
	v_mov_b32_e32 v123, v167
	s_waitcnt lgkmcnt(0)
	v_lshlrev_b32_e32 v124, 16, v120
	v_and_b32_e32 v125, 0xffff0000, v120
	v_lshlrev_b32_e32 v120, 16, v121
	v_and_b32_e32 v121, 0xffff0000, v121
	v_lshlrev_b32_e32 v126, 16, v122
	v_and_b32_e32 v127, 0xffff0000, v122
	v_lshlrev_b32_e32 v122, 16, v123
	v_and_b32_e32 v123, 0xffff0000, v123
	v_pk_add_f32 v[116:117], v[116:117], v[124:125]
	v_pk_add_f32 v[118:119], v[118:119], v[120:121]
	v_pk_add_f32 v[120:121], v[114:115], v[122:123]
	v_pk_add_f32 v[114:115], v[112:113], v[126:127]
	v_cvt_pk_bf16_f32 v112, v116, v117
	v_lshl_add_u64 v[116:117], v[144:145], 0, s[2:3]
	s_mov_b32 s2, 0x10000
	v_cvt_pk_bf16_f32 v113, v118, v119
	v_add_co_u32_e32 v118, vcc, s2, v144
	v_cvt_pk_bf16_f32 v114, v114, v115
	v_cvt_pk_bf16_f32 v115, v120, v121
	v_addc_co_u32_e32 v119, vcc, 0, v145, vcc
	global_store_dwordx4 v[144:145], v[112:115], off offset:256
	s_waitcnt vmcnt(15)
	s_nop 1
	v_mov_b32_e32 v112, v168
	v_mov_b32_e32 v113, v169
	v_mov_b32_e32 v114, v170
	v_mov_b32_e32 v115, v171
	s_mov_b64 s[2:3], 0x20000
	s_waitcnt lgkmcnt(0)
; DI unsigned pack2(float a, float b) { f32x2 v = {a, b}; hwbf16x2 r = __builtin_convertvector(v, hwbf16x2); return __builtin_bit_cast(unsigned, r); }
; DI float bflo(unsigned w) { return __uint_as_float(w << 16); }
; DI float bfhi(unsigned w) { return __uint_as_float(w & 0xffff0000u); }
;     DI void operator()(const f32x4 (&acc)[2][2][4][2], const Unit& u, int wr, int wc, int fr, int fq) const {
;     ...
;         for (int ai = 0; ai < 2; ++ai)
; #pragma unroll
;             for (int m = 0; m < 4; ++m) { const size_t ro = (size_t)(row0 + ai * HALF + m * 16) * D + col0;
; #pragma unroll
;                 for (int bj = 0; bj < 2; ++bj) {
;                     f32x4 x0, x1;
;                     if constexpr (IB) { const u32x4 w = *(const u32x4*)((const bf16_t*)Xin + ro + bj * HALF);
;                         x0 = (f32x4){bflo(w[0]), bfhi(w[0]), bflo(w[1]), bfhi(w[1])}; x1 = (f32x4){bflo(w[2]), bfhi(w[2]), bflo(w[3]), bfhi(w[3])}; }
;                     else { x0 = *(const f32x4*)((const float*)Xin + ro + bj * HALF); x1 = *(const f32x4*)((const float*)Xin + ro + bj * HALF + 4); }
;                     x0 += acc[ai][bj][m][0] * sc[bj][0]; x1 += acc[ai][bj][m][1] * sc[bj][1];
;                     if constexpr (OB) { u32x4 o; o[0] = pack2(x0[0], x0[1]); o[1] = pack2(x0[2], x0[3]); o[2] = pack2(x1[0], x1[1]); o[3] = pack2(x1[2], x1[3]);
;                         *(u32x4*)((bf16_t*)Xout + ro + bj * HALF) = o; }
;                     else { *(f32x4*)((float*)Xout + ro + bj * HALF) = x0; *(f32x4*)((float*)Xout + ro + bj * HALF + 4) = x1; } } }
	v_lshlrev_b32_e32 v120, 16, v112
	v_and_b32_e32 v121, 0xffff0000, v112
	v_lshlrev_b32_e32 v112, 16, v113
	v_and_b32_e32 v113, 0xffff0000, v113
	v_lshlrev_b32_e32 v122, 16, v114
	v_and_b32_e32 v123, 0xffff0000, v114
	v_lshlrev_b32_e32 v114, 16, v115
	v_and_b32_e32 v115, 0xffff0000, v115
	v_pk_add_f32 v[110:111], v[110:111], v[112:113]
	v_pk_add_f32 v[108:109], v[108:109], v[120:121]
	v_pk_add_f32 v[112:113], v[106:107], v[114:115]
	v_pk_add_f32 v[106:107], v[104:105], v[122:123]
	v_cvt_pk_bf16_f32 v104, v108, v109
	v_cvt_pk_bf16_f32 v105, v110, v111
	v_cvt_pk_bf16_f32 v106, v106, v107
	v_cvt_pk_bf16_f32 v107, v112, v113
	global_store_dwordx4 v[118:119], v[104:107], off
	s_waitcnt vmcnt(15)
	s_nop 1
	v_mov_b32_e32 v104, v172
	v_mov_b32_e32 v105, v173
	v_mov_b32_e32 v106, v174
	v_mov_b32_e32 v107, v175
	s_waitcnt lgkmcnt(0)
	v_lshlrev_b32_e32 v108, 16, v104
	v_and_b32_e32 v109, 0xffff0000, v104
	v_lshlrev_b32_e32 v104, 16, v105
	v_and_b32_e32 v105, 0xffff0000, v105
	v_lshlrev_b32_e32 v110, 16, v106
	v_and_b32_e32 v111, 0xffff0000, v106
	v_lshlrev_b32_e32 v106, 16, v107
	v_and_b32_e32 v107, 0xffff0000, v107
	v_pk_add_f32 v[100:101], v[100:101], v[108:109]
	v_pk_add_f32 v[102:103], v[102:103], v[104:105]
	v_pk_add_f32 v[104:105], v[98:99], v[106:107]
	v_pk_add_f32 v[98:99], v[96:97], v[110:111]
	v_cvt_pk_bf16_f32 v96, v100, v101
	v_lshl_add_u64 v[100:101], v[144:145], 0, s[2:3]
	s_mov_b32 s2, 0x20000
	v_cvt_pk_bf16_f32 v97, v102, v103
	v_add_co_u32_e32 v102, vcc, s2, v144
	v_cvt_pk_bf16_f32 v98, v98, v99
	v_cvt_pk_bf16_f32 v99, v104, v105
	v_addc_co_u32_e32 v103, vcc, 0, v145, vcc
	global_store_dwordx4 v[116:117], v[96:99], off offset:256
	s_waitcnt vmcnt(15)
	s_nop 1
	v_mov_b32_e32 v96, v176
	v_mov_b32_e32 v97, v177
	v_mov_b32_e32 v98, v178
	v_mov_b32_e32 v99, v179
	s_mov_b64 s[2:3], 0x30000
	s_waitcnt lgkmcnt(0)
	v_lshlrev_b32_e32 v104, 16, v96
	v_and_b32_e32 v105, 0xffff0000, v96
	v_lshlrev_b32_e32 v96, 16, v97
	v_and_b32_e32 v97, 0xffff0000, v97
	v_lshlrev_b32_e32 v106, 16, v98
	v_and_b32_e32 v107, 0xffff0000, v98
	v_lshlrev_b32_e32 v98, 16, v99
	v_and_b32_e32 v99, 0xffff0000, v99
	v_pk_add_f32 v[94:95], v[94:95], v[96:97]
	v_pk_add_f32 v[92:93], v[92:93], v[104:105]
	v_pk_add_f32 v[96:97], v[90:91], v[98:99]
	v_pk_add_f32 v[90:91], v[88:89], v[106:107]
	v_cvt_pk_bf16_f32 v88, v92, v93
	v_cvt_pk_bf16_f32 v89, v94, v95
	v_cvt_pk_bf16_f32 v90, v90, v91
	v_cvt_pk_bf16_f32 v91, v96, v97
	global_store_dwordx4 v[102:103], v[88:91], off
	s_waitcnt vmcnt(15)
	s_nop 1
	v_mov_b32_e32 v88, v180
	v_mov_b32_e32 v89, v181
	v_mov_b32_e32 v90, v182
	v_mov_b32_e32 v91, v183
	s_waitcnt lgkmcnt(0)
	v_lshlrev_b32_e32 v92, 16, v88
	v_and_b32_e32 v93, 0xffff0000, v88
	v_lshlrev_b32_e32 v88, 16, v89
	v_and_b32_e32 v89, 0xffff0000, v89
	v_lshlrev_b32_e32 v94, 16, v90
	v_and_b32_e32 v95, 0xffff0000, v90
	v_lshlrev_b32_e32 v90, 16, v91
	v_and_b32_e32 v91, 0xffff0000, v91
	v_pk_add_f32 v[86:87], v[86:87], v[88:89]
	v_pk_add_f32 v[84:85], v[84:85], v[92:93]
	v_pk_add_f32 v[88:89], v[82:83], v[90:91]
	v_pk_add_f32 v[82:83], v[80:81], v[94:95]
	v_cvt_pk_bf16_f32 v80, v84, v85
	v_cvt_pk_bf16_f32 v81, v86, v87
	v_cvt_pk_bf16_f32 v82, v82, v83
	v_cvt_pk_bf16_f32 v83, v88, v89
	global_store_dwordx4 v[100:101], v[80:83], off offset:256
	s_nop 1
	v_lshl_add_u64 v[80:81], v[144:145], 0, s[2:3]
	s_mov_b32 s2, 0x30000
	v_add_co_u32_e32 v86, vcc, s2, v144
	s_mov_b64 s[2:3], 0x80000
	s_nop 0
	v_addc_co_u32_e32 v87, vcc, 0, v145, vcc
	s_waitcnt vmcnt(15)
	s_nop 1
	v_mov_b32_e32 v82, v184
	v_mov_b32_e32 v83, v185
	v_mov_b32_e32 v84, v186
	v_mov_b32_e32 v85, v187
	s_waitcnt lgkmcnt(0)
	v_lshlrev_b32_e32 v88, 16, v82
	v_and_b32_e32 v89, 0xffff0000, v82
	v_lshlrev_b32_e32 v82, 16, v83
	v_and_b32_e32 v83, 0xffff0000, v83
	v_lshlrev_b32_e32 v90, 16, v84
	v_and_b32_e32 v91, 0xffff0000, v84
	v_lshlrev_b32_e32 v84, 16, v85
	v_and_b32_e32 v85, 0xffff0000, v85
	v_pk_add_f32 v[78:79], v[78:79], v[82:83]
	v_pk_add_f32 v[76:77], v[76:77], v[88:89]
	v_pk_add_f32 v[82:83], v[74:75], v[84:85]
	v_pk_add_f32 v[74:75], v[72:73], v[90:91]
	v_cvt_pk_bf16_f32 v72, v76, v77
	v_cvt_pk_bf16_f32 v73, v78, v79
	v_cvt_pk_bf16_f32 v74, v74, v75
	v_cvt_pk_bf16_f32 v75, v82, v83
	global_store_dwordx4 v[86:87], v[72:75], off
	s_waitcnt vmcnt(15)
	s_nop 1
	v_mov_b32_e32 v72, v188
	v_mov_b32_e32 v73, v189
	v_mov_b32_e32 v74, v190
	v_mov_b32_e32 v75, v191
	s_waitcnt lgkmcnt(0)
	v_lshlrev_b32_e32 v76, 16, v72
	v_and_b32_e32 v77, 0xffff0000, v72
	v_lshlrev_b32_e32 v72, 16, v73
	v_and_b32_e32 v73, 0xffff0000, v73
	v_lshlrev_b32_e32 v78, 16, v74
	v_and_b32_e32 v79, 0xffff0000, v74
	v_lshlrev_b32_e32 v74, 16, v75
	v_and_b32_e32 v75, 0xffff0000, v75
	v_pk_add_f32 v[70:71], v[70:71], v[72:73]
	v_pk_add_f32 v[68:69], v[68:69], v[76:77]
	v_pk_add_f32 v[72:73], v[66:67], v[74:75]
	v_pk_add_f32 v[66:67], v[64:65], v[78:79]
	v_cvt_pk_bf16_f32 v64, v68, v69
	v_cvt_pk_bf16_f32 v65, v70, v71
	v_cvt_pk_bf16_f32 v66, v66, v67
	v_cvt_pk_bf16_f32 v67, v72, v73
	global_store_dwordx4 v[80:81], v[64:67], off offset:256
	s_nop 1
	v_lshl_add_u64 v[64:65], v[144:145], 0, s[2:3]
	s_mov_b32 s2, 0x80000
	v_add_co_u32_e32 v70, vcc, s2, v144
	s_mov_b64 s[2:3], 0x90000
	s_nop 0
	v_addc_co_u32_e32 v71, vcc, 0, v145, vcc
	s_waitcnt vmcnt(15)
	s_nop 1
	v_mov_b32_e32 v66, v192
	v_mov_b32_e32 v67, v193
	v_mov_b32_e32 v68, v194
	v_mov_b32_e32 v69, v195
	s_waitcnt lgkmcnt(0)
; DI unsigned pack2(float a, float b) { f32x2 v = {a, b}; hwbf16x2 r = __builtin_convertvector(v, hwbf16x2); return __builtin_bit_cast(unsigned, r); }
; DI float bflo(unsigned w) { return __uint_as_float(w << 16); }
; DI float bfhi(unsigned w) { return __uint_as_float(w & 0xffff0000u); }
; #define PG8_WAIT_V(n) asm volatile("s_waitcnt vmcnt(" #n ")" ::: "memory")
; #define PG8_BAR __builtin_amdgcn_s_barrier()
;     DI void operator()(const f32x4 (&acc)[2][2][4][2], const Unit& u, int wr, int wc, int fr, int fq) const {
;     ...
;         for (int ai = 0; ai < 2; ++ai)
; #pragma unroll
;             for (int m = 0; m < 4; ++m) { const size_t ro = (size_t)(row0 + ai * HALF + m * 16) * D + col0;
; #pragma unroll
;                 for (int bj = 0; bj < 2; ++bj) {
;                     f32x4 x0, x1;
;                     if constexpr (IB) { const u32x4 w = *(const u32x4*)((const bf16_t*)Xin + ro + bj * HALF);
;                         x0 = (f32x4){bflo(w[0]), bfhi(w[0]), bflo(w[1]), bfhi(w[1])}; x1 = (f32x4){bflo(w[2]), bfhi(w[2]), bflo(w[3]), bfhi(w[3])}; }
;                     else { x0 = *(const f32x4*)((const float*)Xin + ro + bj * HALF); x1 = *(const f32x4*)((const float*)Xin + ro + bj * HALF + 4); }
;                     x0 += acc[ai][bj][m][0] * sc[bj][0]; x1 += acc[ai][bj][m][1] * sc[bj][1];
;                     if constexpr (OB) { u32x4 o; o[0] = pack2(x0[0], x0[1]); o[1] = pack2(x0[2], x0[3]); o[2] = pack2(x1[0], x1[1]); o[3] = pack2(x1[2], x1[3]);
;                         *(u32x4*)((bf16_t*)Xout + ro + bj * HALF) = o; }
;                     else { *(f32x4*)((float*)Xout + ro + bj * HALF) = x0; *(f32x4*)((float*)Xout + ro + bj * HALF + 4) = x1; } } }
; template <class Map, class Epi>
; DI void gemm_phase(LAS unsigned char* lds, const Map& MP, const Epi& E, const int nM, const int nN, const int K, const int lda, const int ldb) {
;     ...
;     PG8_WAIT_V(0);
;     if (wr == 0) PG8_BAR;
;     PG8_BAR;
	v_lshlrev_b32_e32 v72, 16, v66
	v_and_b32_e32 v73, 0xffff0000, v66
	v_lshlrev_b32_e32 v66, 16, v67
	v_and_b32_e32 v67, 0xffff0000, v67
	v_lshlrev_b32_e32 v74, 16, v68
	v_and_b32_e32 v75, 0xffff0000, v68
	v_lshlrev_b32_e32 v68, 16, v69
	v_and_b32_e32 v69, 0xffff0000, v69
	v_pk_add_f32 v[62:63], v[62:63], v[66:67]
	v_pk_add_f32 v[60:61], v[60:61], v[72:73]
	v_pk_add_f32 v[66:67], v[58:59], v[68:69]
	v_pk_add_f32 v[58:59], v[56:57], v[74:75]
	v_cvt_pk_bf16_f32 v56, v60, v61
	v_cvt_pk_bf16_f32 v57, v62, v63
	v_cvt_pk_bf16_f32 v58, v58, v59
	v_cvt_pk_bf16_f32 v59, v66, v67
	global_store_dwordx4 v[70:71], v[56:59], off
	s_waitcnt vmcnt(15)
	s_nop 1
	v_mov_b32_e32 v56, v198
	v_mov_b32_e32 v57, v199
	v_mov_b32_e32 v58, v200
	v_mov_b32_e32 v59, v201
	s_waitcnt lgkmcnt(0)
	v_lshlrev_b32_e32 v60, 16, v56
	v_and_b32_e32 v61, 0xffff0000, v56
	v_lshlrev_b32_e32 v56, 16, v57
	v_and_b32_e32 v57, 0xffff0000, v57
	v_lshlrev_b32_e32 v62, 16, v58
	v_and_b32_e32 v63, 0xffff0000, v58
	v_lshlrev_b32_e32 v58, 16, v59
	v_and_b32_e32 v59, 0xffff0000, v59
	v_pk_add_f32 v[54:55], v[54:55], v[56:57]
	v_pk_add_f32 v[52:53], v[52:53], v[60:61]
	v_pk_add_f32 v[56:57], v[50:51], v[58:59]
	v_pk_add_f32 v[50:51], v[48:49], v[62:63]
	v_cvt_pk_bf16_f32 v48, v52, v53
	v_cvt_pk_bf16_f32 v49, v54, v55
	v_cvt_pk_bf16_f32 v50, v50, v51
	v_cvt_pk_bf16_f32 v51, v56, v57
	global_store_dwordx4 v[64:65], v[48:51], off offset:256
	s_nop 1
	v_lshl_add_u64 v[48:49], v[144:145], 0, s[2:3]
	s_mov_b32 s2, 0x90000
	v_add_co_u32_e32 v54, vcc, s2, v144
	s_mov_b64 s[2:3], 0xa0000
	s_nop 0
	v_addc_co_u32_e32 v55, vcc, 0, v145, vcc
	s_waitcnt vmcnt(15)
	s_nop 1
	v_mov_b32_e32 v50, v202
	v_mov_b32_e32 v51, v203
	v_mov_b32_e32 v52, v204
	v_mov_b32_e32 v53, v205
	s_waitcnt lgkmcnt(0)
	v_lshlrev_b32_e32 v56, 16, v50
	v_and_b32_e32 v57, 0xffff0000, v50
	v_lshlrev_b32_e32 v50, 16, v51
	v_and_b32_e32 v51, 0xffff0000, v51
	v_lshlrev_b32_e32 v58, 16, v52
	v_and_b32_e32 v59, 0xffff0000, v52
	v_lshlrev_b32_e32 v52, 16, v53
	v_and_b32_e32 v53, 0xffff0000, v53
	v_pk_add_f32 v[46:47], v[46:47], v[50:51]
	v_pk_add_f32 v[44:45], v[44:45], v[56:57]
	v_pk_add_f32 v[50:51], v[42:43], v[52:53]
	v_pk_add_f32 v[42:43], v[40:41], v[58:59]
	v_cvt_pk_bf16_f32 v40, v44, v45
	v_cvt_pk_bf16_f32 v41, v46, v47
	v_cvt_pk_bf16_f32 v42, v42, v43
	v_cvt_pk_bf16_f32 v43, v50, v51
	global_store_dwordx4 v[54:55], v[40:43], off
	s_waitcnt vmcnt(15)
	s_nop 1
	v_mov_b32_e32 v40, v206
	v_mov_b32_e32 v41, v207
	v_mov_b32_e32 v42, v208
	v_mov_b32_e32 v43, v209
	s_waitcnt lgkmcnt(0)
	v_lshlrev_b32_e32 v44, 16, v40
	v_and_b32_e32 v45, 0xffff0000, v40
	v_lshlrev_b32_e32 v40, 16, v41
	v_and_b32_e32 v41, 0xffff0000, v41
	v_lshlrev_b32_e32 v46, 16, v42
	v_and_b32_e32 v47, 0xffff0000, v42
	v_lshlrev_b32_e32 v42, 16, v43
	v_and_b32_e32 v43, 0xffff0000, v43
	v_pk_add_f32 v[38:39], v[38:39], v[40:41]
	v_pk_add_f32 v[36:37], v[36:37], v[44:45]
	v_pk_add_f32 v[40:41], v[34:35], v[42:43]
	v_pk_add_f32 v[34:35], v[32:33], v[46:47]
	v_cvt_pk_bf16_f32 v32, v36, v37
	v_cvt_pk_bf16_f32 v33, v38, v39
	v_cvt_pk_bf16_f32 v34, v34, v35
	v_cvt_pk_bf16_f32 v35, v40, v41
	global_store_dwordx4 v[48:49], v[32:35], off offset:256
	s_nop 1
	v_lshl_add_u64 v[32:33], v[144:145], 0, s[2:3]
	s_mov_b32 s2, 0xa0000
	v_add_co_u32_e32 v38, vcc, s2, v144
	s_mov_b64 s[2:3], 0xb0000
	s_nop 0
	v_addc_co_u32_e32 v39, vcc, 0, v145, vcc
	s_waitcnt vmcnt(15)
	s_nop 1
	v_mov_b32_e32 v34, v210
	v_mov_b32_e32 v35, v211
	v_mov_b32_e32 v36, v212
	v_mov_b32_e32 v37, v213
	s_waitcnt lgkmcnt(0)
	v_lshlrev_b32_e32 v40, 16, v34
	v_and_b32_e32 v41, 0xffff0000, v34
	v_lshlrev_b32_e32 v34, 16, v35
	v_and_b32_e32 v35, 0xffff0000, v35
	v_lshlrev_b32_e32 v42, 16, v36
	v_and_b32_e32 v43, 0xffff0000, v36
	v_lshlrev_b32_e32 v36, 16, v37
	v_and_b32_e32 v37, 0xffff0000, v37
	v_pk_add_f32 v[30:31], v[30:31], v[34:35]
	v_pk_add_f32 v[28:29], v[28:29], v[40:41]
	v_pk_add_f32 v[34:35], v[26:27], v[36:37]
	v_pk_add_f32 v[26:27], v[24:25], v[42:43]
	v_cvt_pk_bf16_f32 v24, v28, v29
	v_cvt_pk_bf16_f32 v25, v30, v31
	v_cvt_pk_bf16_f32 v26, v26, v27
	v_cvt_pk_bf16_f32 v27, v34, v35
	global_store_dwordx4 v[38:39], v[24:27], off
	s_waitcnt vmcnt(15)
	s_nop 1
	v_mov_b32_e32 v24, v214
	v_mov_b32_e32 v25, v215
	v_mov_b32_e32 v26, v216
	v_mov_b32_e32 v27, v217
	s_waitcnt lgkmcnt(0)
	v_lshlrev_b32_e32 v28, 16, v24
	v_and_b32_e32 v29, 0xffff0000, v24
	v_lshlrev_b32_e32 v24, 16, v25
	v_and_b32_e32 v25, 0xffff0000, v25
	v_lshlrev_b32_e32 v30, 16, v26
	v_and_b32_e32 v31, 0xffff0000, v26
	v_lshlrev_b32_e32 v26, 16, v27
	v_and_b32_e32 v27, 0xffff0000, v27
	v_pk_add_f32 v[22:23], v[22:23], v[24:25]
	v_pk_add_f32 v[20:21], v[20:21], v[28:29]
	v_pk_add_f32 v[24:25], v[18:19], v[26:27]
	v_pk_add_f32 v[18:19], v[16:17], v[30:31]
	v_cvt_pk_bf16_f32 v16, v20, v21
	v_cvt_pk_bf16_f32 v17, v22, v23
	v_cvt_pk_bf16_f32 v18, v18, v19
	v_cvt_pk_bf16_f32 v19, v24, v25
	global_store_dwordx4 v[32:33], v[16:19], off offset:256
	s_nop 1
	v_lshl_add_u64 v[16:17], v[144:145], 0, s[2:3]
	s_mov_b32 s2, 0xb0000
	v_add_co_u32_e32 v22, vcc, s2, v144
	s_mov_b32 s2, s53
	s_nop 0
	v_addc_co_u32_e32 v23, vcc, 0, v145, vcc
	s_waitcnt vmcnt(15)
	s_nop 1
	v_mov_b32_e32 v18, v248
	v_mov_b32_e32 v19, v249
	v_mov_b32_e32 v20, v250
	v_mov_b32_e32 v21, v251
	s_and_b64 vcc, exec, s[40:41]
	s_waitcnt lgkmcnt(0)
	v_lshlrev_b32_e32 v24, 16, v18
	v_and_b32_e32 v25, 0xffff0000, v18
	v_lshlrev_b32_e32 v18, 16, v19
	v_and_b32_e32 v19, 0xffff0000, v19
	v_lshlrev_b32_e32 v26, 16, v20
	v_and_b32_e32 v27, 0xffff0000, v20
	v_lshlrev_b32_e32 v20, 16, v21
	v_and_b32_e32 v21, 0xffff0000, v21
	v_pk_add_f32 v[14:15], v[14:15], v[18:19]
	v_pk_add_f32 v[12:13], v[12:13], v[24:25]
	v_pk_add_f32 v[18:19], v[10:11], v[20:21]
	v_pk_add_f32 v[10:11], v[8:9], v[26:27]
	v_cvt_pk_bf16_f32 v8, v12, v13
	v_cvt_pk_bf16_f32 v9, v14, v15
	v_cvt_pk_bf16_f32 v10, v10, v11
	v_cvt_pk_bf16_f32 v11, v18, v19
	global_store_dwordx4 v[22:23], v[8:11], off
	s_waitcnt vmcnt(15)
	s_nop 1
	v_mov_b32_e32 v8, v252
	v_mov_b32_e32 v9, v253
	v_mov_b32_e32 v10, v254
	v_mov_b32_e32 v11, v255
	s_waitcnt lgkmcnt(0)
	v_lshlrev_b32_e32 v12, 16, v8
	v_and_b32_e32 v13, 0xffff0000, v8
	v_lshlrev_b32_e32 v8, 16, v9
	v_and_b32_e32 v9, 0xffff0000, v9
	v_lshlrev_b32_e32 v14, 16, v10
	v_and_b32_e32 v15, 0xffff0000, v10
	v_lshlrev_b32_e32 v10, 16, v11
	v_and_b32_e32 v11, 0xffff0000, v11
	v_pk_add_f32 v[6:7], v[6:7], v[8:9]
	v_pk_add_f32 v[4:5], v[4:5], v[12:13]
	v_pk_add_f32 v[8:9], v[2:3], v[10:11]
	v_pk_add_f32 v[2:3], v[0:1], v[14:15]
	v_cvt_pk_bf16_f32 v0, v4, v5
	v_cvt_pk_bf16_f32 v1, v6, v7
	v_cvt_pk_bf16_f32 v2, v2, v3
	v_cvt_pk_bf16_f32 v3, v8, v9
	global_store_dwordx4 v[16:17], v[0:3], off offset:256
	s_cbranch_vccz .LBB1_2071
	s_waitcnt vmcnt(0)
	s_cmpk_gt_u32 s17, 0xff
	s_cbranch_scc1 .LBB1_2082
	s_barrier

;     DI const char* a(const Unit& u) const { return (const char*)(A + (size_t)u.pm * BM * lda); }
;     DI const char* a(const Unit& u) const { return (const char*)(A + (size_t)u.pm * BM * 2048 + (u.pn >> 1) * 512); }
;     DI const char* a(const Unit& u) const { return (const char*)((u.pn < 12 ? A1 : A2) + (size_t)u.pm * BM * 512); }
; #define PG8_STAGE(bufoff, gbase, voff) do { _Pragma("unroll") for (int _i = 0; _i < 2; ++_i) \
;         __builtin_amdgcn_global_load_lds((const unsigned*)((const char*)(gbase) + (voff)[_i]), (LAS unsigned*)(lds + (bufoff) + ldsw + _i * 8192), 16, 0, 0); } while (0)
; #define PG8_LDA(dst, b, h) do { _Pragma("unroll") for (int m = 0; m < 4; ++m) _Pragma("unroll") for (int k = 0; k < 2; ++k) dst[m][k] = *(const LAS bf16x8*)(lds + PG8_SA(b, h) + aoff + m * 2048 + k * 1024); } while (0)
; #define PG8_LDB(dst, b, h) do { _Pragma("unroll") for (int n = 0; n < 2; ++n) _Pragma("unroll") for (int k = 0; k < 2; ++k) dst[n][k] = *(const LAS bf16x8*)(lds + PG8_SB(b, h) + boff + n * 2048 + k * 1024); } while (0)
; #define PG8_WAIT_L(n) asm volatile("s_waitcnt lgkmcnt(" #n ")" ::: "memory")
; template <class Map, class Epi>
; DI void gemm_phase(LAS unsigned char* lds, const Map& MP, const Epi& E, const int nM, const int nN, const int K, const int lda, const int ldb) {
;     ...
;         const bool has_next = sched_next(ui + 1, nM, nN, G, cblk, nxt);
;         const char* nA = has_next ? MP.a(nxt) : cA; const char* nB = has_next ? MP.b(nxt) : cB;
;         for (int t = 0; t < nt; t += 2) {
;             const bool last = (t == nt - 2);
;             const char* a1 = cA + (size_t)(t + 1) * kstep;
;             const char* a2 = last ? nA : cA + (size_t)(t + 2) * kstep; const char* b2 = last ? nB : cB + (size_t)(t + 2) * kstep;
;             const char* a3 = a2 + kstep; const char* b3 = b2 + kstep;
;             PG8_LDB(B0, 0, 0); PG8_SCHED; PG8_LDA(At, 0, 0); PG8_STAGE(PG8_SA(1, 1), a1 + hstepA, voffA);
;             PG8_WAIT_L(8); PG8_BAR; PG8_WAIT_L(0); PG8_MMA(0, 0, At, B0); PG8_BAR; PG8_SCHED;
;     ...
;         for (int a = 0; a < 2; ++a)
; #pragma unroll
;             for (int b = 0; b < 2; ++b)
; #pragma unroll
;                 for (int m = 0; m < 4; ++m)
; #pragma unroll
;                     for (int n = 0; n < 2; ++n) acc[a][b][m][n] = (f32x4){0.f, 0.f, 0.f, 0.f};
;         cur = nxt; cA = nA; cB = nB; ++ui;
.LBB1_2338:
	s_ashr_i32 s53, s52, 31
	v_cmp_lt_i64_e32 vcc, s[6:7], v[156:157]
	s_lshl_b64 s[6:7], s[52:53], 20
	s_add_u32 s3, s18, s6
	s_addc_u32 s14, s19, s7
	s_lshl_b32 s6, s37, 8
	s_and_b32 s6, s6, 0xfffffe00
	s_ashr_i32 s7, s6, 31
	s_lshl_b64 s[6:7], s[6:7], 1
	s_add_u32 s6, s3, s6
	s_addc_u32 s7, s14, s7
	s_and_b64 s[14:15], vcc, exec
	s_cselect_b32 s38, s7, s13
	s_cselect_b32 s39, s6, s12
	s_ashr_i32 s14, s37, 1
	s_ashr_i32 s15, s14, 31
	s_lshl_b64 s[14:15], s[14:15], 19
	s_add_u32 s3, s20, s14
	s_addc_u32 s14, s21, s15
	s_lshl_b32 s15, s37, 18
	s_and_b32 s15, s15, 0x40000
	s_add_u32 s54, s3, s15
	s_addc_u32 s55, s14, 0
	s_and_b64 s[14:15], vcc, exec
	s_cselect_b32 s48, s55, s11
	s_cselect_b32 s49, s54, s10
	s_add_u32 s53, s10, 0x100
	s_addc_u32 s56, s11, 0
	s_add_u32 s10, s12, 0x80080
	v_mov_b32_e32 v0, 0
	s_addc_u32 s11, s13, 0
	s_mov_b32 s3, -2
	v_mov_b32_e32 v1, v0
	v_mov_b32_e32 v2, v0
	v_mov_b32_e32 v3, v0
	v_mov_b32_e32 v4, v0
	v_mov_b32_e32 v5, v0
	v_mov_b32_e32 v6, v0
	v_mov_b32_e32 v7, v0
	v_mov_b32_e32 v16, v0
	v_mov_b32_e32 v17, v0
	v_mov_b32_e32 v18, v0
	v_mov_b32_e32 v19, v0
	v_mov_b32_e32 v20, v0
	v_mov_b32_e32 v21, v0
	v_mov_b32_e32 v22, v0
	v_mov_b32_e32 v23, v0
	v_mov_b32_e32 v32, v0
	v_mov_b32_e32 v33, v0
	v_mov_b32_e32 v34, v0
	v_mov_b32_e32 v35, v0
	v_mov_b32_e32 v36, v0
	v_mov_b32_e32 v37, v0
	v_mov_b32_e32 v38, v0
	v_mov_b32_e32 v39, v0
	v_mov_b32_e32 v64, v0
	v_mov_b32_e32 v65, v0
	v_mov_b32_e32 v66, v0
	v_mov_b32_e32 v67, v0
	v_mov_b32_e32 v68, v0
	v_mov_b32_e32 v69, v0
	v_mov_b32_e32 v70, v0
	v_mov_b32_e32 v71, v0
	v_mov_b32_e32 v8, v0
	v_mov_b32_e32 v9, v0
	v_mov_b32_e32 v10, v0
	v_mov_b32_e32 v11, v0
	v_mov_b32_e32 v12, v0
	v_mov_b32_e32 v13, v0
	v_mov_b32_e32 v14, v0
	v_mov_b32_e32 v15, v0
	v_mov_b32_e32 v24, v0
	v_mov_b32_e32 v25, v0
	v_mov_b32_e32 v26, v0
	v_mov_b32_e32 v27, v0
	v_mov_b32_e32 v28, v0
	v_mov_b32_e32 v29, v0
	v_mov_b32_e32 v30, v0
	v_mov_b32_e32 v31, v0
	v_mov_b32_e32 v48, v0
	v_mov_b32_e32 v49, v0
	v_mov_b32_e32 v50, v0
	v_mov_b32_e32 v51, v0
	v_mov_b32_e32 v52, v0
	v_mov_b32_e32 v53, v0
	v_mov_b32_e32 v54, v0
	v_mov_b32_e32 v55, v0
	v_mov_b32_e32 v72, v0
	v_mov_b32_e32 v73, v0
	v_mov_b32_e32 v74, v0
	v_mov_b32_e32 v75, v0
	v_mov_b32_e32 v76, v0
	v_mov_b32_e32 v77, v0
	v_mov_b32_e32 v78, v0
	v_mov_b32_e32 v79, v0
	v_mov_b32_e32 v80, v0
	v_mov_b32_e32 v81, v0
	v_mov_b32_e32 v82, v0
	v_mov_b32_e32 v83, v0
	v_mov_b32_e32 v84, v0
	v_mov_b32_e32 v85, v0
	v_mov_b32_e32 v86, v0
	v_mov_b32_e32 v87, v0
	v_mov_b32_e32 v96, v0
	v_mov_b32_e32 v97, v0
	v_mov_b32_e32 v98, v0
	v_mov_b32_e32 v99, v0
	v_mov_b32_e32 v100, v0
	v_mov_b32_e32 v101, v0
	v_mov_b32_e32 v102, v0
	v_mov_b32_e32 v103, v0
	v_mov_b32_e32 v112, v0
	v_mov_b32_e32 v113, v0
	v_mov_b32_e32 v114, v0
	v_mov_b32_e32 v115, v0
	v_mov_b32_e32 v116, v0
	v_mov_b32_e32 v117, v0
	v_mov_b32_e32 v118, v0
	v_mov_b32_e32 v119, v0
	v_mov_b32_e32 v128, v0
	v_mov_b32_e32 v129, v0
	v_mov_b32_e32 v130, v0
	v_mov_b32_e32 v131, v0
	v_mov_b32_e32 v132, v0
	v_mov_b32_e32 v133, v0
	v_mov_b32_e32 v134, v0
	v_mov_b32_e32 v135, v0
	v_mov_b32_e32 v88, v0
	v_mov_b32_e32 v89, v0
	v_mov_b32_e32 v90, v0
	v_mov_b32_e32 v91, v0
	v_mov_b32_e32 v92, v0
	v_mov_b32_e32 v93, v0
	v_mov_b32_e32 v94, v0
	v_mov_b32_e32 v95, v0
	v_mov_b32_e32 v104, v0
	v_mov_b32_e32 v105, v0
	v_mov_b32_e32 v106, v0
	v_mov_b32_e32 v107, v0
	v_mov_b32_e32 v108, v0
	v_mov_b32_e32 v109, v0
	v_mov_b32_e32 v110, v0
	v_mov_b32_e32 v111, v0
	v_mov_b32_e32 v120, v0
	v_mov_b32_e32 v121, v0
	v_mov_b32_e32 v122, v0
	v_mov_b32_e32 v123, v0
	v_mov_b32_e32 v124, v0
	v_mov_b32_e32 v125, v0
	v_mov_b32_e32 v126, v0
	v_mov_b32_e32 v127, v0
	v_mov_b32_e32 v136, v0
	v_mov_b32_e32 v137, v0
	v_mov_b32_e32 v138, v0
	v_mov_b32_e32 v139, v0
	v_mov_b32_e32 v140, v0
	v_mov_b32_e32 v141, v0
	v_mov_b32_e32 v142, v0
	v_mov_b32_e32 v143, v0
	ds_read_b128 v[40:43], v165
	ds_read_b128 v[44:47], v165 offset:1024
	ds_read_b128 v[56:59], v165 offset:2048
	ds_read_b128 v[60:63], v165 offset:3072
.LBB1_2339:
	s_add_u32 s12, s10, 0xfff80080
	s_addc_u32 s13, s11, -1
	s_cmp_eq_u32 s3, 4
	s_cselect_b32 s15, s38, s13
	s_cselect_b32 s14, s39, s12
	s_cselect_b32 s13, s48, s56
	s_cselect_b32 s12, s49, s53
	s_add_i32 m0, s9, 0xc000
	ds_read_b128 v[168:171], v166
	ds_read_b128 v[172:175], v166 offset:1024
	ds_read_b128 v[176:179], v166 offset:2048
	ds_read_b128 v[180:183], v166 offset:3072
	ds_read_b128 v[184:187], v166 offset:4096
	ds_read_b128 v[188:191], v166 offset:5120
	ds_read_b128 v[192:195], v166 offset:6144
	ds_read_b128 v[198:201], v166 offset:7168
	global_load_lds_dwordx4 v154, s[10:11]
	s_add_i32 m0, s9, 0xe000
	s_nop 0
	global_load_lds_dwordx4 v152, s[10:11]
	s_waitcnt lgkmcnt(8)
	s_barrier
	s_setprio 1
	s_waitcnt lgkmcnt(7)
	v_mfma_f32_16x16x32_bf16 v[140:143], v[40:43], v[168:171], v[140:143]
	v_mfma_f32_16x16x32_bf16 v[136:139], v[56:59], v[168:171], v[136:139]
	s_waitcnt lgkmcnt(5)
	v_mfma_f32_16x16x32_bf16 v[124:127], v[40:43], v[176:179], v[124:127]
	v_mfma_f32_16x16x32_bf16 v[120:123], v[56:59], v[176:179], v[120:123]
	s_waitcnt lgkmcnt(3)
	v_mfma_f32_16x16x32_bf16 v[108:111], v[40:43], v[184:187], v[108:111]
	v_mfma_f32_16x16x32_bf16 v[104:107], v[56:59], v[184:187], v[104:107]
	s_waitcnt lgkmcnt(1)
	v_mfma_f32_16x16x32_bf16 v[92:95], v[40:43], v[192:195], v[92:95]
	v_mfma_f32_16x16x32_bf16 v[88:91], v[56:59], v[192:195], v[88:91]
	v_mfma_f32_16x16x32_bf16 v[140:143], v[44:47], v[172:175], v[140:143]
	v_mfma_f32_16x16x32_bf16 v[136:139], v[60:63], v[172:175], v[136:139]
	v_mfma_f32_16x16x32_bf16 v[124:127], v[44:47], v[180:183], v[124:127]
	v_mfma_f32_16x16x32_bf16 v[120:123], v[60:63], v[180:183], v[120:123]
	v_mfma_f32_16x16x32_bf16 v[108:111], v[44:47], v[188:191], v[108:111]
	v_mfma_f32_16x16x32_bf16 v[104:107], v[60:63], v[188:191], v[104:107]
	s_waitcnt lgkmcnt(0)
	v_mfma_f32_16x16x32_bf16 v[92:95], v[44:47], v[198:201], v[92:95]
	v_mfma_f32_16x16x32_bf16 v[88:91], v[60:63], v[198:201], v[88:91]
	s_setprio 0
	s_barrier
; #define PG8_STAGE(bufoff, gbase, voff) do { _Pragma("unroll") for (int _i = 0; _i < 2; ++_i) \
;         __builtin_amdgcn_global_load_lds((const unsigned*)((const char*)(gbase) + (voff)[_i]), (LAS unsigned*)(lds + (bufoff) + ldsw + _i * 8192), 16, 0, 0); } while (0)
; #define PG8_LDA(dst, b, h) do { _Pragma("unroll") for (int m = 0; m < 4; ++m) _Pragma("unroll") for (int k = 0; k < 2; ++k) dst[m][k] = *(const LAS bf16x8*)(lds + PG8_SA(b, h) + aoff + m * 2048 + k * 1024); } while (0)
; #define PG8_LDB(dst, b, h) do { _Pragma("unroll") for (int n = 0; n < 2; ++n) _Pragma("unroll") for (int k = 0; k < 2; ++k) dst[n][k] = *(const LAS bf16x8*)(lds + PG8_SB(b, h) + boff + n * 2048 + k * 1024); } while (0)
; #define PG8_MMA(ai, bj, At, Bt) do { __builtin_amdgcn_s_setprio(1); _Pragma("unroll") for (int m = 0; m < 4; ++m) _Pragma("unroll") for (int n = 0; n < 2; ++n) _Pragma("unroll") for (int k = 0; k < 2; ++k) \
;         acc[ai][bj][m][n] = __builtin_amdgcn_mfma_f32_16x16x32_bf16(Bt[n][k], At[m][k], acc[ai][bj][m][n], 0, 0, 0); __builtin_amdgcn_s_setprio(0); } while (0)
; #define PG8_WAIT_V(n) asm volatile("s_waitcnt vmcnt(" #n ")" ::: "memory")
; #define PG8_WAIT_L(n) asm volatile("s_waitcnt lgkmcnt(" #n ")" ::: "memory")
; #define PG8_BAR __builtin_amdgcn_s_barrier()
; #define PG8_SCHED __builtin_amdgcn_sched_barrier(0)
; template <class Map, class Epi>
; DI void gemm_phase(LAS unsigned char* lds, const Map& MP, const Epi& E, const int nM, const int nN, const int K, const int lda, const int ldb) {
;     ...
;             PG8_LDB(B1, 0, 1); PG8_STAGE(PG8_SB(0, 0), b2, voffB);
;             PG8_BAR; PG8_WAIT_L(0); PG8_MMA(0, 1, At, B1); PG8_BAR;
;             PG8_LDA(At, 0, 1); PG8_STAGE(PG8_SA(0, 0), a2, voffA);
;             PG8_BAR; PG8_WAIT_L(0); PG8_MMA(1, 0, At, B0); PG8_BAR; PG8_SCHED;
;             PG8_STAGE(PG8_SB(0, 1), b2 + hstepB, voffB);
;             PG8_WAIT_V(6); PG8_BAR; PG8_MMA(1, 1, At, B1); PG8_BAR;
;             PG8_LDB(B0, 1, 0); PG8_SCHED; PG8_LDA(At, 1, 0); PG8_STAGE(PG8_SA(0, 1), a2 + hstepA, voffA);
	s_add_i32 s57, s35, s22
	v_lshl_add_u64 v[160:161], s[12:13], 0, v[148:149]
	s_mov_b32 m0, s57
	ds_read_b128 v[202:205], v167
	ds_read_b128 v[206:209], v167 offset:1024
	ds_read_b128 v[210:213], v167 offset:2048
	ds_read_b128 v[214:217], v167 offset:3072
	global_load_lds_dwordx4 v[160:161], off
	v_lshl_add_u64 v[218:219], s[12:13], 0, v[144:145]
	s_add_i32 m0, s57, 0x2000
	s_nop 0
	global_load_lds_dwordx4 v[218:219], off
	s_barrier
	s_setprio 1
	s_waitcnt lgkmcnt(3)
	v_mfma_f32_16x16x32_bf16 v[132:135], v[202:205], v[168:171], v[132:135]
	s_waitcnt lgkmcnt(1)
	v_mfma_f32_16x16x32_bf16 v[128:131], v[210:213], v[168:171], v[128:131]
	v_mfma_f32_16x16x32_bf16 v[116:119], v[202:205], v[176:179], v[116:119]
	v_mfma_f32_16x16x32_bf16 v[112:115], v[210:213], v[176:179], v[112:115]
	v_mfma_f32_16x16x32_bf16 v[100:103], v[202:205], v[184:187], v[100:103]
	v_mfma_f32_16x16x32_bf16 v[96:99], v[210:213], v[184:187], v[96:99]
	v_mfma_f32_16x16x32_bf16 v[84:87], v[202:205], v[192:195], v[84:87]
	v_mfma_f32_16x16x32_bf16 v[80:83], v[210:213], v[192:195], v[80:83]
	v_mfma_f32_16x16x32_bf16 v[132:135], v[206:209], v[172:175], v[132:135]
	s_waitcnt lgkmcnt(0)
	v_mfma_f32_16x16x32_bf16 v[128:131], v[214:217], v[172:175], v[128:131]
	v_mfma_f32_16x16x32_bf16 v[116:119], v[206:209], v[180:183], v[116:119]
	v_mfma_f32_16x16x32_bf16 v[112:115], v[214:217], v[180:183], v[112:115]
	v_mfma_f32_16x16x32_bf16 v[100:103], v[206:209], v[188:191], v[100:103]
	v_mfma_f32_16x16x32_bf16 v[96:99], v[214:217], v[188:191], v[96:99]
	v_mfma_f32_16x16x32_bf16 v[84:87], v[206:209], v[198:201], v[84:87]
	v_mfma_f32_16x16x32_bf16 v[80:83], v[214:217], v[198:201], v[80:83]
	s_setprio 0
	s_mov_b32 m0, s9
	v_lshl_add_u64 v[220:221], s[14:15], 0, v[150:151]
	s_barrier
	ds_read_b128 v[168:171], v166 offset:16384
	ds_read_b128 v[172:175], v166 offset:17408
	ds_read_b128 v[176:179], v166 offset:18432
	ds_read_b128 v[180:183], v166 offset:19456
	ds_read_b128 v[184:187], v166 offset:20480
	ds_read_b128 v[188:191], v166 offset:21504
	ds_read_b128 v[192:195], v166 offset:22528
	ds_read_b128 v[198:201], v166 offset:23552
	global_load_lds_dwordx4 v[220:221], off
	v_lshl_add_u64 v[222:223], s[14:15], 0, v[146:147]
	s_mov_b32 m0, s24
	s_nop 0
	global_load_lds_dwordx4 v[222:223], off
	s_waitcnt vmcnt(10)
	s_barrier
	s_setprio 1
	s_waitcnt lgkmcnt(7)
	v_mfma_f32_16x16x32_bf16 v[76:79], v[40:43], v[168:171], v[76:79]
	v_mfma_f32_16x16x32_bf16 v[72:75], v[56:59], v[168:171], v[72:75]
	s_waitcnt lgkmcnt(5)
	v_mfma_f32_16x16x32_bf16 v[52:55], v[40:43], v[176:179], v[52:55]
	v_mfma_f32_16x16x32_bf16 v[48:51], v[56:59], v[176:179], v[48:51]
	s_waitcnt lgkmcnt(3)
	v_mfma_f32_16x16x32_bf16 v[28:31], v[40:43], v[184:187], v[28:31]
	v_mfma_f32_16x16x32_bf16 v[24:27], v[56:59], v[184:187], v[24:27]
	s_waitcnt lgkmcnt(1)
	v_mfma_f32_16x16x32_bf16 v[12:15], v[40:43], v[192:195], v[12:15]
	v_mfma_f32_16x16x32_bf16 v[8:11], v[56:59], v[192:195], v[8:11]
	v_mfma_f32_16x16x32_bf16 v[76:79], v[44:47], v[172:175], v[76:79]
	v_mfma_f32_16x16x32_bf16 v[72:75], v[60:63], v[172:175], v[72:75]
	v_mfma_f32_16x16x32_bf16 v[52:55], v[44:47], v[180:183], v[52:55]
	v_mfma_f32_16x16x32_bf16 v[48:51], v[60:63], v[180:183], v[48:51]
	v_mfma_f32_16x16x32_bf16 v[28:31], v[44:47], v[188:191], v[28:31]
	v_mfma_f32_16x16x32_bf16 v[24:27], v[60:63], v[188:191], v[24:27]
	s_waitcnt lgkmcnt(0)
	v_mfma_f32_16x16x32_bf16 v[12:15], v[44:47], v[198:201], v[12:15]
	v_mfma_f32_16x16x32_bf16 v[8:11], v[60:63], v[198:201], v[8:11]
	s_setprio 0
	s_barrier
	s_add_u32 s58, s12, 0x20000
	s_addc_u32 s59, s13, 0
	s_add_i32 s57, s36, s22
	s_mov_b32 m0, s57
	s_nop 0
	global_load_lds_dwordx4 v148, s[58:59]
	s_add_i32 m0, s57, 0x2000
	s_nop 0
	global_load_lds_dwordx4 v144, s[58:59]
	s_waitcnt vmcnt(6)
	s_barrier
	s_setprio 1
	v_mfma_f32_16x16x32_bf16 v[36:39], v[202:205], v[176:179], v[36:39]
	v_mfma_f32_16x16x32_bf16 v[32:35], v[210:213], v[176:179], v[32:35]
	v_mfma_f32_16x16x32_bf16 v[20:23], v[202:205], v[184:187], v[20:23]
	v_mfma_f32_16x16x32_bf16 v[16:19], v[210:213], v[184:187], v[16:19]
	v_mfma_f32_16x16x32_bf16 v[4:7], v[202:205], v[192:195], v[4:7]
	v_mfma_f32_16x16x32_bf16 v[0:3], v[210:213], v[192:195], v[0:3]
	v_mfma_f32_16x16x32_bf16 v[40:43], v[202:205], v[168:171], v[68:71]
	s_add_i32 s57, 0, 0x18000
	v_add_u32_e32 v68, s57, v164
	ds_read_b128 v[56:59], v68
	ds_read_b128 v[60:63], v68 offset:1024
	v_mfma_f32_16x16x32_bf16 v[44:47], v[210:213], v[168:171], v[64:67]
	ds_read_b128 v[64:67], v68 offset:2048
	ds_read_b128 v[68:71], v68 offset:3072
	v_mfma_f32_16x16x32_bf16 v[36:39], v[206:209], v[180:183], v[36:39]
	v_mfma_f32_16x16x32_bf16 v[32:35], v[214:217], v[180:183], v[32:35]
	v_mfma_f32_16x16x32_bf16 v[20:23], v[206:209], v[188:191], v[20:23]
	v_mfma_f32_16x16x32_bf16 v[16:19], v[214:217], v[188:191], v[16:19]
	v_mfma_f32_16x16x32_bf16 v[4:7], v[206:209], v[198:201], v[4:7]
	v_mfma_f32_16x16x32_bf16 v[0:3], v[214:217], v[198:201], v[0:3]
	v_mfma_f32_16x16x32_bf16 v[40:43], v[206:209], v[172:175], v[40:43]
	v_mfma_f32_16x16x32_bf16 v[44:47], v[214:217], v[172:175], v[44:47]
	s_setprio 0
	s_barrier
	s_add_u32 s14, s14, 0x80000
	s_addc_u32 s15, s15, 0
	s_mov_b32 m0, s25
	ds_read_b128 v[168:171], v166 offset:32768
	ds_read_b128 v[172:175], v166 offset:33792
	ds_read_b128 v[176:179], v166 offset:34816
	ds_read_b128 v[180:183], v166 offset:35840
	ds_read_b128 v[184:187], v166 offset:36864
	ds_read_b128 v[188:191], v166 offset:37888
	ds_read_b128 v[192:195], v166 offset:38912
	ds_read_b128 v[198:201], v166 offset:39936
	global_load_lds_dwordx4 v150, s[14:15]
	s_mov_b32 m0, s26
	s_nop 0
	global_load_lds_dwordx4 v146, s[14:15]
	s_waitcnt lgkmcnt(8)
	s_barrier
; #define PG8_STAGE(bufoff, gbase, voff) do { _Pragma("unroll") for (int _i = 0; _i < 2; ++_i) \
;         __builtin_amdgcn_global_load_lds((const unsigned*)((const char*)(gbase) + (voff)[_i]), (LAS unsigned*)(lds + (bufoff) + ldsw + _i * 8192), 16, 0, 0); } while (0)
; #define PG8_LDA(dst, b, h) do { _Pragma("unroll") for (int m = 0; m < 4; ++m) _Pragma("unroll") for (int k = 0; k < 2; ++k) dst[m][k] = *(const LAS bf16x8*)(lds + PG8_SA(b, h) + aoff + m * 2048 + k * 1024); } while (0)
; #define PG8_LDB(dst, b, h) do { _Pragma("unroll") for (int n = 0; n < 2; ++n) _Pragma("unroll") for (int k = 0; k < 2; ++k) dst[n][k] = *(const LAS bf16x8*)(lds + PG8_SB(b, h) + boff + n * 2048 + k * 1024); } while (0)
; #define PG8_MMA(ai, bj, At, Bt) do { __builtin_amdgcn_s_setprio(1); _Pragma("unroll") for (int m = 0; m < 4; ++m) _Pragma("unroll") for (int n = 0; n < 2; ++n) _Pragma("unroll") for (int k = 0; k < 2; ++k) \
;         acc[ai][bj][m][n] = __builtin_amdgcn_mfma_f32_16x16x32_bf16(Bt[n][k], At[m][k], acc[ai][bj][m][n], 0, 0, 0); __builtin_amdgcn_s_setprio(0); } while (0)
; #define PG8_WAIT_V(n) asm volatile("s_waitcnt vmcnt(" #n ")" ::: "memory")
; #define PG8_WAIT_L(n) asm volatile("s_waitcnt lgkmcnt(" #n ")" ::: "memory")
; #define PG8_BAR __builtin_amdgcn_s_barrier()
; #define PG8_SCHED __builtin_amdgcn_sched_barrier(0)
; template <class Map, class Epi>
; DI void gemm_phase(LAS unsigned char* lds, const Map& MP, const Epi& E, const int nM, const int nN, const int K, const int lda, const int ldb) {
;     ...
;             PG8_WAIT_L(8); PG8_BAR; PG8_WAIT_L(0); PG8_MMA(0, 0, At, B0); PG8_BAR; PG8_SCHED;
;             PG8_LDB(B1, 1, 1); PG8_STAGE(PG8_SB(1, 0), b3, voffB);
;             PG8_BAR; PG8_WAIT_L(0); PG8_MMA(0, 1, At, B1); PG8_BAR;
;             PG8_LDA(At, 1, 1); PG8_STAGE(PG8_SA(1, 0), a3, voffA);
;             PG8_BAR; PG8_WAIT_L(0); PG8_MMA(1, 0, At, B0); PG8_BAR; PG8_SCHED;
;             PG8_STAGE(PG8_SB(1, 1), b3 + hstepB, voffB);
;             PG8_WAIT_V(6); PG8_BAR; PG8_MMA(1, 1, At, B1); PG8_BAR;
	s_setprio 1
	s_waitcnt lgkmcnt(7)
	v_mfma_f32_16x16x32_bf16 v[140:143], v[56:59], v[168:171], v[140:143]
	v_mfma_f32_16x16x32_bf16 v[136:139], v[64:67], v[168:171], v[136:139]
	s_waitcnt lgkmcnt(5)
	v_mfma_f32_16x16x32_bf16 v[124:127], v[56:59], v[176:179], v[124:127]
	v_mfma_f32_16x16x32_bf16 v[120:123], v[64:67], v[176:179], v[120:123]
	s_waitcnt lgkmcnt(3)
	v_mfma_f32_16x16x32_bf16 v[108:111], v[56:59], v[184:187], v[108:111]
	v_mfma_f32_16x16x32_bf16 v[104:107], v[64:67], v[184:187], v[104:107]
	s_waitcnt lgkmcnt(1)
	v_mfma_f32_16x16x32_bf16 v[92:95], v[56:59], v[192:195], v[92:95]
	v_mfma_f32_16x16x32_bf16 v[88:91], v[64:67], v[192:195], v[88:91]
	v_mfma_f32_16x16x32_bf16 v[140:143], v[60:63], v[172:175], v[140:143]
	v_mfma_f32_16x16x32_bf16 v[136:139], v[68:71], v[172:175], v[136:139]
	v_mfma_f32_16x16x32_bf16 v[124:127], v[60:63], v[180:183], v[124:127]
	v_mfma_f32_16x16x32_bf16 v[120:123], v[68:71], v[180:183], v[120:123]
	v_mfma_f32_16x16x32_bf16 v[108:111], v[60:63], v[188:191], v[108:111]
	v_mfma_f32_16x16x32_bf16 v[104:107], v[68:71], v[188:191], v[104:107]
	s_waitcnt lgkmcnt(0)
	v_mfma_f32_16x16x32_bf16 v[92:95], v[60:63], v[198:201], v[92:95]
	v_mfma_f32_16x16x32_bf16 v[88:91], v[68:71], v[198:201], v[88:91]
	s_setprio 0
	s_barrier
	s_add_i32 s14, 0, 0x1c000
	s_add_i32 s15, s57, s22
	v_add_u32_e32 v196, s14, v164
	v_lshl_add_u64 v[160:161], v[160:161], 0, s[46:47]
	s_mov_b32 m0, s15
	ds_read_b128 v[202:205], v196
	ds_read_b128 v[206:209], v196 offset:1024
	ds_read_b128 v[210:213], v196 offset:2048
	ds_read_b128 v[214:217], v196 offset:3072
	global_load_lds_dwordx4 v[160:161], off
	v_lshl_add_u64 v[160:161], v[218:219], 0, s[46:47]
	s_add_i32 m0, s15, 0x2000
	s_nop 0
	global_load_lds_dwordx4 v[160:161], off
	s_barrier
	s_setprio 1
	s_waitcnt lgkmcnt(3)
	v_mfma_f32_16x16x32_bf16 v[132:135], v[202:205], v[168:171], v[132:135]
	s_waitcnt lgkmcnt(1)
	v_mfma_f32_16x16x32_bf16 v[128:131], v[210:213], v[168:171], v[128:131]
	v_mfma_f32_16x16x32_bf16 v[116:119], v[202:205], v[176:179], v[116:119]
	v_mfma_f32_16x16x32_bf16 v[112:115], v[210:213], v[176:179], v[112:115]
	v_mfma_f32_16x16x32_bf16 v[100:103], v[202:205], v[184:187], v[100:103]
	v_mfma_f32_16x16x32_bf16 v[96:99], v[210:213], v[184:187], v[96:99]
	v_mfma_f32_16x16x32_bf16 v[84:87], v[202:205], v[192:195], v[84:87]
	v_mfma_f32_16x16x32_bf16 v[80:83], v[210:213], v[192:195], v[80:83]
	v_mfma_f32_16x16x32_bf16 v[132:135], v[206:209], v[172:175], v[132:135]
	s_waitcnt lgkmcnt(0)
	v_mfma_f32_16x16x32_bf16 v[128:131], v[214:217], v[172:175], v[128:131]
	v_mfma_f32_16x16x32_bf16 v[116:119], v[206:209], v[180:183], v[116:119]
	v_mfma_f32_16x16x32_bf16 v[112:115], v[214:217], v[180:183], v[112:115]
	v_mfma_f32_16x16x32_bf16 v[100:103], v[206:209], v[188:191], v[100:103]
	v_mfma_f32_16x16x32_bf16 v[96:99], v[214:217], v[188:191], v[96:99]
	v_mfma_f32_16x16x32_bf16 v[84:87], v[206:209], v[198:201], v[84:87]
	v_mfma_f32_16x16x32_bf16 v[80:83], v[214:217], v[198:201], v[80:83]
	s_setprio 0
	s_mov_b32 m0, s30
	v_lshl_add_u64 v[160:161], v[220:221], 0, s[46:47]
	s_barrier
	ds_read_b128 v[168:171], v166 offset:49152
	ds_read_b128 v[172:175], v166 offset:50176
	ds_read_b128 v[176:179], v166 offset:51200
	ds_read_b128 v[180:183], v166 offset:52224
	ds_read_b128 v[184:187], v166 offset:53248
	ds_read_b128 v[188:191], v166 offset:54272
	ds_read_b128 v[192:195], v166 offset:55296
	ds_read_b128 v[198:201], v166 offset:56320
	global_load_lds_dwordx4 v[160:161], off
	v_lshl_add_u64 v[160:161], v[222:223], 0, s[46:47]
	s_mov_b32 m0, s31
	s_nop 0
	global_load_lds_dwordx4 v[160:161], off
	s_waitcnt vmcnt(10)
	s_barrier
	s_setprio 1
	s_waitcnt lgkmcnt(7)
	v_mfma_f32_16x16x32_bf16 v[76:79], v[56:59], v[168:171], v[76:79]
	v_mfma_f32_16x16x32_bf16 v[72:75], v[64:67], v[168:171], v[72:75]
	s_waitcnt lgkmcnt(5)
	v_mfma_f32_16x16x32_bf16 v[52:55], v[56:59], v[176:179], v[52:55]
	v_mfma_f32_16x16x32_bf16 v[48:51], v[64:67], v[176:179], v[48:51]
	s_waitcnt lgkmcnt(3)
	v_mfma_f32_16x16x32_bf16 v[28:31], v[56:59], v[184:187], v[28:31]
	v_mfma_f32_16x16x32_bf16 v[24:27], v[64:67], v[184:187], v[24:27]
	s_waitcnt lgkmcnt(1)
	v_mfma_f32_16x16x32_bf16 v[12:15], v[56:59], v[192:195], v[12:15]
	v_mfma_f32_16x16x32_bf16 v[8:11], v[64:67], v[192:195], v[8:11]
	v_mfma_f32_16x16x32_bf16 v[76:79], v[60:63], v[172:175], v[76:79]
	v_mfma_f32_16x16x32_bf16 v[72:75], v[68:71], v[172:175], v[72:75]
	v_mfma_f32_16x16x32_bf16 v[52:55], v[60:63], v[180:183], v[52:55]
	v_mfma_f32_16x16x32_bf16 v[48:51], v[68:71], v[180:183], v[48:51]
	v_mfma_f32_16x16x32_bf16 v[28:31], v[60:63], v[188:191], v[28:31]
	v_mfma_f32_16x16x32_bf16 v[24:27], v[68:71], v[188:191], v[24:27]
	s_waitcnt lgkmcnt(0)
	v_mfma_f32_16x16x32_bf16 v[12:15], v[60:63], v[198:201], v[12:15]
	v_mfma_f32_16x16x32_bf16 v[8:11], v[68:71], v[198:201], v[8:11]
	s_setprio 0
	s_barrier
	s_add_u32 s12, s12, 0x20080
	s_addc_u32 s13, s13, 0
	s_add_i32 s14, s14, s22
	s_mov_b32 m0, s14
	s_nop 0
	global_load_lds_dwordx4 v148, s[12:13]
	s_add_i32 m0, s14, 0x2000
	s_nop 0
	global_load_lds_dwordx4 v144, s[12:13]
	s_waitcnt vmcnt(6)
	s_barrier
; DI float bflo(unsigned w) { return __uint_as_float(w << 16); }
; #define PG8_BAR __builtin_amdgcn_s_barrier()
;     DI void operator()(const f32x4 (&acc)[2][2][4][2], const Unit& u, int wr, int wc, int fr, int fq) const {
;         const int row0 = u.pm * BM + wr * 64 + fr, col0 = u.pn * BM + wc * 32 + 8 * fq;
;         f32x4 sc[2][2];
; #pragma unroll
;         for (int bj = 0; bj < 2; ++bj)
; #pragma unroll
;             for (int n = 0; n < 2; ++n) sc[bj][n] = scale ? *(const f32x4*)(scale + col0 + bj * HALF + 4 * n) : (f32x4){1.f, 1.f, 1.f, 1.f};
; #pragma unroll
;         for (int ai = 0; ai < 2; ++ai)
; #pragma unroll
;             for (int m = 0; m < 4; ++m) { const size_t ro = (size_t)(row0 + ai * HALF + m * 16) * D + col0;
; #pragma unroll
;                 for (int bj = 0; bj < 2; ++bj) {
;                     f32x4 x0, x1;
;                     if constexpr (IB) { const u32x4 w = *(const u32x4*)((const bf16_t*)Xin + ro + bj * HALF);
;                         x0 = (f32x4){bflo(w[0]), bfhi(w[0]), bflo(w[1]), bfhi(w[1])}; x1 = (f32x4){bflo(w[2]), bfhi(w[2]), bflo(w[3]), bfhi(w[3])}; }
;                     else { x0 = *(const f32x4*)((const float*)Xin + ro + bj * HALF); x1 = *(const f32x4*)((const float*)Xin + ro + bj * HALF + 4); }
;                     x0 += acc[ai][bj][m][0] * sc[bj][0]; x1 += acc[ai][bj][m][1] * sc[bj][1];
;                     if constexpr (OB) { u32x4 o; o[0] = pack2(x0[0], x0[1]); o[1] = pack2(x0[2], x0[3]); o[2] = pack2(x1[0], x1[1]); o[3] = pack2(x1[2], x1[3]);
;                         *(u32x4*)((bf16_t*)Xout + ro + bj * HALF) = o; }
; template <class Map, class Epi>
; DI void gemm_phase(LAS unsigned char* lds, const Map& MP, const Epi& E, const int nM, const int nN, const int K, const int lda, const int ldb) {
;     ...
;             PG8_LDB(B0, 1, 0); PG8_SCHED; PG8_LDA(At, 1, 0); PG8_STAGE(PG8_SA(0, 1), a2 + hstepA, voffA);
;             PG8_WAIT_L(8); PG8_BAR; PG8_WAIT_L(0); PG8_MMA(0, 0, At, B0); PG8_BAR; PG8_SCHED;
;             PG8_LDB(B1, 1, 1); PG8_STAGE(PG8_SB(1, 0), b3, voffB);
;             PG8_BAR; PG8_WAIT_L(0); PG8_MMA(0, 1, At, B1); PG8_BAR;
;             PG8_LDA(At, 1, 1); PG8_STAGE(PG8_SA(1, 0), a3, voffA);
;             PG8_BAR; PG8_WAIT_L(0); PG8_MMA(1, 0, At, B0); PG8_BAR; PG8_SCHED;
;             PG8_STAGE(PG8_SB(1, 1), b3 + hstepB, voffB);
;             PG8_WAIT_V(6); PG8_BAR; PG8_MMA(1, 1, At, B1); PG8_BAR;
	s_setprio 1
	v_mfma_f32_16x16x32_bf16 v[40:43], v[202:205], v[168:171], v[40:43]
	v_mfma_f32_16x16x32_bf16 v[68:71], v[206:209], v[172:175], v[40:43]
	v_mfma_f32_16x16x32_bf16 v[40:43], v[210:213], v[168:171], v[44:47]
	v_mfma_f32_16x16x32_bf16 v[36:39], v[202:205], v[176:179], v[36:39]
	v_mfma_f32_16x16x32_bf16 v[32:35], v[210:213], v[176:179], v[32:35]
	v_mfma_f32_16x16x32_bf16 v[20:23], v[202:205], v[184:187], v[20:23]
	v_mfma_f32_16x16x32_bf16 v[16:19], v[210:213], v[184:187], v[16:19]
	v_mfma_f32_16x16x32_bf16 v[4:7], v[202:205], v[192:195], v[4:7]
	v_mfma_f32_16x16x32_bf16 v[0:3], v[210:213], v[192:195], v[0:3]
	v_mfma_f32_16x16x32_bf16 v[64:67], v[214:217], v[172:175], v[40:43]
	ds_read_b128 v[40:43], v165
	ds_read_b128 v[44:47], v165 offset:1024
	ds_read_b128 v[56:59], v165 offset:2048
	ds_read_b128 v[60:63], v165 offset:3072
	v_mfma_f32_16x16x32_bf16 v[36:39], v[206:209], v[180:183], v[36:39]
	v_mfma_f32_16x16x32_bf16 v[32:35], v[214:217], v[180:183], v[32:35]
	v_mfma_f32_16x16x32_bf16 v[20:23], v[206:209], v[188:191], v[20:23]
	v_mfma_f32_16x16x32_bf16 v[16:19], v[214:217], v[188:191], v[16:19]
	v_mfma_f32_16x16x32_bf16 v[4:7], v[206:209], v[198:201], v[4:7]
	v_mfma_f32_16x16x32_bf16 v[0:3], v[214:217], v[198:201], v[0:3]
	s_setprio 0
	s_add_i32 s3, s3, 2
	s_add_u32 s53, s53, 0x100
	s_addc_u32 s56, s56, 0
	s_add_u32 s10, s10, 0x100
	s_addc_u32 s11, s11, 0
	s_cmp_gt_u32 s3, 5
	s_barrier
	s_cbranch_scc0 .LBB1_2339
	s_waitcnt lgkmcnt(0)
	s_lshl_b32 s2, s2, 8
	v_mov_b32_e32 v40, v163
	v_mov_b32_e32 v168, v162
	s_or_b32 s2, s2, s29
	s_and_b64 vcc, exec, s[40:41]
	v_lshl_add_u32 v160, v40, 3, s2
	s_lshl_b32 s2, s8, 8
	s_add_i32 s2, s2, s28
	v_add_u32_e32 v168, s2, v168
	v_ashrrev_i32_e32 v169, 31, v168
	v_ashrrev_i32_e32 v161, 31, v160
	v_lshlrev_b64 v[168:169], 11, v[168:169]
	v_lshl_add_u64 v[44:45], v[160:161], 2, s[44:45]
	v_lshl_add_u64 v[160:161], v[168:169], 0, v[160:161]
	v_lshlrev_b64 v[160:161], 1, v[160:161]
	v_lshl_add_u64 v[172:173], s[4:5], 0, v[160:161]
	global_load_dwordx4 v[56:59], v[44:45], off offset:16
	global_load_dwordx4 v[60:63], v[44:45], off
	global_load_dwordx4 v[40:43], v[44:45], off offset:528
	s_nop 0
	global_load_dwordx4 v[44:47], v[44:45], off offset:512
	s_mov_b64 s[2:3], 0x10000
	global_load_dwordx4 v[178:181], v[172:173], off
	global_load_dwordx4 v[182:185], v[172:173], off offset:256
	s_mov_b64 s[98:99], 0x10000
	v_lshl_add_u64 v[170:171], v[172:173], 0, s[98:99]
	global_load_dwordx4 v[186:189], v[170:171], off
	global_load_dwordx4 v[190:193], v[170:171], off offset:256
	s_mov_b64 s[98:99], 0x20000
	v_lshl_add_u64 v[170:171], v[172:173], 0, s[98:99]
	global_load_dwordx4 v[198:201], v[170:171], off
	global_load_dwordx4 v[202:205], v[170:171], off offset:256
	s_mov_b64 s[98:99], 0x30000
	v_lshl_add_u64 v[170:171], v[172:173], 0, s[98:99]
	global_load_dwordx4 v[206:209], v[170:171], off
	global_load_dwordx4 v[210:213], v[170:171], off offset:256
	s_mov_b64 s[98:99], 0x80000
	v_lshl_add_u64 v[170:171], v[172:173], 0, s[98:99]
	global_load_dwordx4 v[214:217], v[170:171], off
	global_load_dwordx4 v[248:251], v[170:171], off offset:256
	s_mov_b64 s[98:99], 0x90000
	v_lshl_add_u64 v[170:171], v[172:173], 0, s[98:99]
	global_load_dwordx4 v[252:255], v[170:171], off
	s_waitcnt vmcnt(10)
	s_nop 1
	v_mov_b32_e32 v168, v178
	v_mov_b32_e32 v169, v179
	v_mov_b32_e32 v170, v180
	v_mov_b32_e32 v171, v181
	s_mov_b32 s8, s52
	s_mov_b64 s[10:11], s[54:55]
	s_mov_b64 s[12:13], s[6:7]
	s_waitcnt lgkmcnt(0)
	v_lshlrev_b32_e32 v174, 16, v168
	v_and_b32_e32 v175, 0xffff0000, v168
	v_lshlrev_b32_e32 v168, 16, v169
	v_and_b32_e32 v169, 0xffff0000, v169
	v_lshlrev_b32_e32 v176, 16, v170
	v_and_b32_e32 v177, 0xffff0000, v170
	v_lshlrev_b32_e32 v170, 16, v171
	v_and_b32_e32 v171, 0xffff0000, v171
	v_pk_fma_f32 v[142:143], v[142:143], v[62:63], v[168:169]
	v_pk_fma_f32 v[140:141], v[140:141], v[60:61], v[174:175]
	v_pk_fma_f32 v[168:169], v[138:139], v[58:59], v[170:171]
	v_pk_fma_f32 v[138:139], v[136:137], v[56:57], v[176:177]
	v_cvt_pk_bf16_f32 v136, v140, v141
	v_cvt_pk_bf16_f32 v137, v142, v143
	v_cvt_pk_bf16_f32 v138, v138, v139
	v_cvt_pk_bf16_f32 v139, v168, v169
	v_lshl_add_u64 v[140:141], s[42:43], 0, v[160:161]
	global_store_dwordx4 v[140:141], v[136:139], off
	s_waitcnt vmcnt(10)
	s_nop 1
	v_mov_b32_e32 v136, v182
	v_mov_b32_e32 v137, v183
	v_mov_b32_e32 v138, v184
	v_mov_b32_e32 v139, v185
	s_waitcnt lgkmcnt(0)
	v_lshlrev_b32_e32 v142, 16, v136
	v_and_b32_e32 v143, 0xffff0000, v136
	v_lshlrev_b32_e32 v136, 16, v137
	v_and_b32_e32 v137, 0xffff0000, v137
	v_lshlrev_b32_e32 v168, 16, v138
	v_and_b32_e32 v169, 0xffff0000, v138
	v_lshlrev_b32_e32 v138, 16, v139
	v_and_b32_e32 v139, 0xffff0000, v139
	v_pk_fma_f32 v[134:135], v[134:135], v[46:47], v[136:137]
	v_pk_fma_f32 v[132:133], v[132:133], v[44:45], v[142:143]
	v_pk_fma_f32 v[136:137], v[130:131], v[42:43], v[138:139]
	v_pk_fma_f32 v[130:131], v[128:129], v[40:41], v[168:169]
	v_cvt_pk_bf16_f32 v128, v132, v133
	v_cvt_pk_bf16_f32 v129, v134, v135
	v_cvt_pk_bf16_f32 v130, v130, v131
	v_cvt_pk_bf16_f32 v131, v136, v137
	v_lshl_add_u64 v[132:133], v[160:161], 0, s[2:3]
	global_store_dwordx4 v[140:141], v[128:131], off offset:256
	v_lshl_add_u64 v[134:135], s[4:5], 0, v[132:133]
	s_waitcnt vmcnt(10)
	s_nop 1
	v_mov_b32_e32 v128, v186
	v_mov_b32_e32 v129, v187
	v_mov_b32_e32 v130, v188
	v_mov_b32_e32 v131, v189
	s_mov_b64 s[2:3], 0x20000
	s_waitcnt lgkmcnt(0)
; DI unsigned pack2(float a, float b) { f32x2 v = {a, b}; hwbf16x2 r = __builtin_convertvector(v, hwbf16x2); return __builtin_bit_cast(unsigned, r); }
; DI float bflo(unsigned w) { return __uint_as_float(w << 16); }
; DI float bfhi(unsigned w) { return __uint_as_float(w & 0xffff0000u); }
;     DI void operator()(const f32x4 (&acc)[2][2][4][2], const Unit& u, int wr, int wc, int fr, int fq) const {
;     ...
;         for (int ai = 0; ai < 2; ++ai)
; #pragma unroll
;             for (int m = 0; m < 4; ++m) { const size_t ro = (size_t)(row0 + ai * HALF + m * 16) * D + col0;
; #pragma unroll
;                 for (int bj = 0; bj < 2; ++bj) {
;                     f32x4 x0, x1;
;                     if constexpr (IB) { const u32x4 w = *(const u32x4*)((const bf16_t*)Xin + ro + bj * HALF);
;                         x0 = (f32x4){bflo(w[0]), bfhi(w[0]), bflo(w[1]), bfhi(w[1])}; x1 = (f32x4){bflo(w[2]), bfhi(w[2]), bflo(w[3]), bfhi(w[3])}; }
;                     else { x0 = *(const f32x4*)((const float*)Xin + ro + bj * HALF); x1 = *(const f32x4*)((const float*)Xin + ro + bj * HALF + 4); }
;                     x0 += acc[ai][bj][m][0] * sc[bj][0]; x1 += acc[ai][bj][m][1] * sc[bj][1];
;                     if constexpr (OB) { u32x4 o; o[0] = pack2(x0[0], x0[1]); o[1] = pack2(x0[2], x0[3]); o[2] = pack2(x1[0], x1[1]); o[3] = pack2(x1[2], x1[3]);
;                         *(u32x4*)((bf16_t*)Xout + ro + bj * HALF) = o; }
;                     else { *(f32x4*)((float*)Xout + ro + bj * HALF) = x0; *(f32x4*)((float*)Xout + ro + bj * HALF + 4) = x1; } } }
	v_lshlrev_b32_e32 v136, 16, v128
	v_and_b32_e32 v137, 0xffff0000, v128
	v_lshlrev_b32_e32 v128, 16, v129
	v_and_b32_e32 v129, 0xffff0000, v129
	v_lshlrev_b32_e32 v138, 16, v130
	v_and_b32_e32 v139, 0xffff0000, v130
	v_lshlrev_b32_e32 v130, 16, v131
	v_and_b32_e32 v131, 0xffff0000, v131
	v_pk_fma_f32 v[126:127], v[126:127], v[62:63], v[128:129]
	v_pk_fma_f32 v[124:125], v[124:125], v[60:61], v[136:137]
	v_pk_fma_f32 v[128:129], v[122:123], v[58:59], v[130:131]
	v_pk_fma_f32 v[122:123], v[120:121], v[56:57], v[138:139]
	v_cvt_pk_bf16_f32 v120, v124, v125
	v_cvt_pk_bf16_f32 v121, v126, v127
	v_cvt_pk_bf16_f32 v122, v122, v123
	v_cvt_pk_bf16_f32 v123, v128, v129
	v_lshl_add_u64 v[124:125], s[42:43], 0, v[132:133]
	global_store_dwordx4 v[124:125], v[120:123], off
	s_waitcnt vmcnt(10)
	s_nop 1
	v_mov_b32_e32 v120, v190
	v_mov_b32_e32 v121, v191
	v_mov_b32_e32 v122, v192
	v_mov_b32_e32 v123, v193
	s_waitcnt lgkmcnt(0)
	v_lshlrev_b32_e32 v126, 16, v120
	v_and_b32_e32 v127, 0xffff0000, v120
	v_lshlrev_b32_e32 v120, 16, v121
	v_and_b32_e32 v121, 0xffff0000, v121
	v_lshlrev_b32_e32 v128, 16, v122
	v_and_b32_e32 v129, 0xffff0000, v122
	v_lshlrev_b32_e32 v122, 16, v123
	v_and_b32_e32 v123, 0xffff0000, v123
	v_pk_fma_f32 v[118:119], v[118:119], v[46:47], v[120:121]
	v_pk_fma_f32 v[116:117], v[116:117], v[44:45], v[126:127]
	v_pk_fma_f32 v[120:121], v[114:115], v[42:43], v[122:123]
	v_pk_fma_f32 v[114:115], v[112:113], v[40:41], v[128:129]
	v_cvt_pk_bf16_f32 v112, v116, v117
	v_cvt_pk_bf16_f32 v113, v118, v119
	v_cvt_pk_bf16_f32 v114, v114, v115
	v_cvt_pk_bf16_f32 v115, v120, v121
	v_lshl_add_u64 v[116:117], v[160:161], 0, s[2:3]
	global_store_dwordx4 v[124:125], v[112:115], off offset:256
	v_lshl_add_u64 v[118:119], s[4:5], 0, v[116:117]
	s_waitcnt vmcnt(10)
	s_nop 1
	v_mov_b32_e32 v112, v198
	v_mov_b32_e32 v113, v199
	v_mov_b32_e32 v114, v200
	v_mov_b32_e32 v115, v201
	s_mov_b64 s[2:3], 0x30000
	s_waitcnt lgkmcnt(0)
	v_lshlrev_b32_e32 v120, 16, v112
	v_and_b32_e32 v121, 0xffff0000, v112
	v_lshlrev_b32_e32 v112, 16, v113
	v_and_b32_e32 v113, 0xffff0000, v113
	v_lshlrev_b32_e32 v122, 16, v114
	v_and_b32_e32 v123, 0xffff0000, v114
	v_lshlrev_b32_e32 v114, 16, v115
	v_and_b32_e32 v115, 0xffff0000, v115
	v_pk_fma_f32 v[110:111], v[110:111], v[62:63], v[112:113]
	v_pk_fma_f32 v[108:109], v[108:109], v[60:61], v[120:121]
	v_pk_fma_f32 v[112:113], v[106:107], v[58:59], v[114:115]
	v_pk_fma_f32 v[106:107], v[104:105], v[56:57], v[122:123]
	v_cvt_pk_bf16_f32 v104, v108, v109
	v_cvt_pk_bf16_f32 v105, v110, v111
	v_cvt_pk_bf16_f32 v106, v106, v107
	v_cvt_pk_bf16_f32 v107, v112, v113
	v_lshl_add_u64 v[108:109], s[42:43], 0, v[116:117]
	global_store_dwordx4 v[108:109], v[104:107], off
	s_waitcnt vmcnt(10)
	s_nop 1
	v_mov_b32_e32 v104, v202
	v_mov_b32_e32 v105, v203
	v_mov_b32_e32 v106, v204
	v_mov_b32_e32 v107, v205
	s_waitcnt lgkmcnt(0)
	v_lshlrev_b32_e32 v110, 16, v104
	v_and_b32_e32 v111, 0xffff0000, v104
	v_lshlrev_b32_e32 v104, 16, v105
	v_and_b32_e32 v105, 0xffff0000, v105
	v_lshlrev_b32_e32 v112, 16, v106
	v_and_b32_e32 v113, 0xffff0000, v106
	v_lshlrev_b32_e32 v106, 16, v107
	v_and_b32_e32 v107, 0xffff0000, v107
	v_pk_fma_f32 v[102:103], v[102:103], v[46:47], v[104:105]
	v_pk_fma_f32 v[100:101], v[100:101], v[44:45], v[110:111]
	v_pk_fma_f32 v[104:105], v[98:99], v[42:43], v[106:107]
	v_pk_fma_f32 v[98:99], v[96:97], v[40:41], v[112:113]
	v_cvt_pk_bf16_f32 v96, v100, v101
	v_cvt_pk_bf16_f32 v97, v102, v103
	v_cvt_pk_bf16_f32 v98, v98, v99
	v_cvt_pk_bf16_f32 v99, v104, v105
	v_lshl_add_u64 v[100:101], v[160:161], 0, s[2:3]
	global_store_dwordx4 v[108:109], v[96:99], off offset:256
	v_lshl_add_u64 v[102:103], s[4:5], 0, v[100:101]
	s_waitcnt vmcnt(10)
	s_nop 1
	v_mov_b32_e32 v96, v206
	v_mov_b32_e32 v97, v207
	v_mov_b32_e32 v98, v208
	v_mov_b32_e32 v99, v209
	s_mov_b64 s[2:3], 0x80000
	s_waitcnt lgkmcnt(0)
	v_lshlrev_b32_e32 v104, 16, v96
	v_and_b32_e32 v105, 0xffff0000, v96
	v_lshlrev_b32_e32 v96, 16, v97
	v_and_b32_e32 v97, 0xffff0000, v97
	v_lshlrev_b32_e32 v106, 16, v98
	v_and_b32_e32 v107, 0xffff0000, v98
	v_lshlrev_b32_e32 v98, 16, v99
	v_and_b32_e32 v99, 0xffff0000, v99
	v_pk_fma_f32 v[94:95], v[94:95], v[62:63], v[96:97]
	v_pk_fma_f32 v[92:93], v[92:93], v[60:61], v[104:105]
	v_pk_fma_f32 v[96:97], v[90:91], v[58:59], v[98:99]
	v_pk_fma_f32 v[90:91], v[88:89], v[56:57], v[106:107]
	v_cvt_pk_bf16_f32 v88, v92, v93
	v_cvt_pk_bf16_f32 v89, v94, v95
	v_cvt_pk_bf16_f32 v90, v90, v91
	v_cvt_pk_bf16_f32 v91, v96, v97
	v_lshl_add_u64 v[92:93], s[42:43], 0, v[100:101]
	global_store_dwordx4 v[92:93], v[88:91], off
	s_waitcnt vmcnt(10)
	s_nop 1
	v_mov_b32_e32 v88, v210
	v_mov_b32_e32 v89, v211
	v_mov_b32_e32 v90, v212
	v_mov_b32_e32 v91, v213
	s_waitcnt lgkmcnt(0)
	v_lshlrev_b32_e32 v94, 16, v88
	v_and_b32_e32 v95, 0xffff0000, v88
	v_lshlrev_b32_e32 v88, 16, v89
	v_and_b32_e32 v89, 0xffff0000, v89
	v_lshlrev_b32_e32 v96, 16, v90
	v_and_b32_e32 v97, 0xffff0000, v90
	v_lshlrev_b32_e32 v90, 16, v91
	v_and_b32_e32 v91, 0xffff0000, v91
	v_pk_fma_f32 v[86:87], v[86:87], v[46:47], v[88:89]
	v_pk_fma_f32 v[84:85], v[84:85], v[44:45], v[94:95]
	v_pk_fma_f32 v[88:89], v[82:83], v[42:43], v[90:91]
	v_pk_fma_f32 v[82:83], v[80:81], v[40:41], v[96:97]
	v_cvt_pk_bf16_f32 v80, v84, v85
	v_cvt_pk_bf16_f32 v81, v86, v87
	v_cvt_pk_bf16_f32 v82, v82, v83
	v_cvt_pk_bf16_f32 v83, v88, v89
	v_lshl_add_u64 v[84:85], v[160:161], 0, s[2:3]
	global_store_dwordx4 v[92:93], v[80:83], off offset:256
	v_lshl_add_u64 v[86:87], s[4:5], 0, v[84:85]
	s_waitcnt vmcnt(10)
	s_nop 1
	v_mov_b32_e32 v80, v214
	v_mov_b32_e32 v81, v215
	v_mov_b32_e32 v82, v216
	v_mov_b32_e32 v83, v217
	s_mov_b64 s[2:3], 0x90000
	s_waitcnt lgkmcnt(0)
; DI unsigned pack2(float a, float b) { f32x2 v = {a, b}; hwbf16x2 r = __builtin_convertvector(v, hwbf16x2); return __builtin_bit_cast(unsigned, r); }
; DI float bflo(unsigned w) { return __uint_as_float(w << 16); }
; DI float bfhi(unsigned w) { return __uint_as_float(w & 0xffff0000u); }
;     DI const char* a(const Unit& u) const { return (const char*)(A + (size_t)u.pm * BM * lda); }
;     DI const char* a(const Unit& u) const { return (const char*)(A + (size_t)u.pm * BM * 2048 + (u.pn >> 1) * 512); }
;     DI void operator()(const f32x4 (&acc)[2][2][4][2], const Unit& u, int wr, int wc, int fr, int fq) const {
;     ...
;         for (int ai = 0; ai < 2; ++ai)
; #pragma unroll
;             for (int m = 0; m < 4; ++m) { const size_t ro = (size_t)(row0 + ai * HALF + m * 16) * D + col0;
; #pragma unroll
;                 for (int bj = 0; bj < 2; ++bj) {
;                     f32x4 x0, x1;
;                     if constexpr (IB) { const u32x4 w = *(const u32x4*)((const bf16_t*)Xin + ro + bj * HALF);
;                         x0 = (f32x4){bflo(w[0]), bfhi(w[0]), bflo(w[1]), bfhi(w[1])}; x1 = (f32x4){bflo(w[2]), bfhi(w[2]), bflo(w[3]), bfhi(w[3])}; }
;                     else { x0 = *(const f32x4*)((const float*)Xin + ro + bj * HALF); x1 = *(const f32x4*)((const float*)Xin + ro + bj * HALF + 4); }
;                     x0 += acc[ai][bj][m][0] * sc[bj][0]; x1 += acc[ai][bj][m][1] * sc[bj][1];
;                     if constexpr (OB) { u32x4 o; o[0] = pack2(x0[0], x0[1]); o[1] = pack2(x0[2], x0[3]); o[2] = pack2(x1[0], x1[1]); o[3] = pack2(x1[2], x1[3]);
;                         *(u32x4*)((bf16_t*)Xout + ro + bj * HALF) = o; }
;                     else { *(f32x4*)((float*)Xout + ro + bj * HALF) = x0; *(f32x4*)((float*)Xout + ro + bj * HALF + 4) = x1; } } }
; template <class Map, class Epi>
; DI void gemm_phase(LAS unsigned char* lds, const Map& MP, const Epi& E, const int nM, const int nN, const int K, const int lda, const int ldb) {
;     ...
;         if (!has_next) break;
; #pragma unroll
;         for (int a = 0; a < 2; ++a)
; #pragma unroll
;             for (int b = 0; b < 2; ++b)
; #pragma unroll
;                 for (int m = 0; m < 4; ++m)
; #pragma unroll
;                     for (int n = 0; n < 2; ++n) acc[a][b][m][n] = (f32x4){0.f, 0.f, 0.f, 0.f};
;         cur = nxt; cA = nA; cB = nB; ++ui;
;     }
;     PG8_WAIT_V(0);
;     if (wr == 0) PG8_BAR;
;     PG8_BAR;
	v_lshlrev_b32_e32 v88, 16, v80
	v_and_b32_e32 v89, 0xffff0000, v80
	v_lshlrev_b32_e32 v80, 16, v81
	v_and_b32_e32 v81, 0xffff0000, v81
	v_lshlrev_b32_e32 v90, 16, v82
	v_and_b32_e32 v91, 0xffff0000, v82
	v_lshlrev_b32_e32 v82, 16, v83
	v_and_b32_e32 v83, 0xffff0000, v83
	v_pk_fma_f32 v[78:79], v[78:79], v[62:63], v[80:81]
	v_pk_fma_f32 v[76:77], v[76:77], v[60:61], v[88:89]
	v_pk_fma_f32 v[80:81], v[74:75], v[58:59], v[82:83]
	v_pk_fma_f32 v[74:75], v[72:73], v[56:57], v[90:91]
	v_cvt_pk_bf16_f32 v72, v76, v77
	v_cvt_pk_bf16_f32 v73, v78, v79
	v_cvt_pk_bf16_f32 v74, v74, v75
	v_cvt_pk_bf16_f32 v75, v80, v81
	v_lshl_add_u64 v[76:77], s[42:43], 0, v[84:85]
	global_store_dwordx4 v[76:77], v[72:75], off
	s_waitcnt vmcnt(10)
	s_nop 1
	v_mov_b32_e32 v72, v248
	v_mov_b32_e32 v73, v249
	v_mov_b32_e32 v74, v250
	v_mov_b32_e32 v75, v251
	s_waitcnt lgkmcnt(0)
	v_lshlrev_b32_e32 v78, 16, v72
	v_and_b32_e32 v79, 0xffff0000, v72
	v_lshlrev_b32_e32 v72, 16, v73
	v_and_b32_e32 v73, 0xffff0000, v73
	v_lshlrev_b32_e32 v80, 16, v74
	v_and_b32_e32 v81, 0xffff0000, v74
	v_lshlrev_b32_e32 v74, 16, v75
	v_and_b32_e32 v75, 0xffff0000, v75
	v_pk_fma_f32 v[70:71], v[70:71], v[46:47], v[72:73]
	v_pk_fma_f32 v[68:69], v[68:69], v[44:45], v[78:79]
	v_pk_fma_f32 v[72:73], v[66:67], v[42:43], v[74:75]
	v_pk_fma_f32 v[66:67], v[64:65], v[40:41], v[80:81]
	v_cvt_pk_bf16_f32 v64, v68, v69
	v_cvt_pk_bf16_f32 v65, v70, v71
	v_cvt_pk_bf16_f32 v66, v66, v67
	v_cvt_pk_bf16_f32 v67, v72, v73
	v_lshl_add_u64 v[68:69], v[160:161], 0, s[2:3]
	global_store_dwordx4 v[76:77], v[64:67], off offset:256
	v_lshl_add_u64 v[70:71], s[4:5], 0, v[68:69]
	s_waitcnt vmcnt(10)
	s_nop 1
	v_mov_b32_e32 v64, v252
	v_mov_b32_e32 v65, v253
	v_mov_b32_e32 v66, v254
	v_mov_b32_e32 v67, v255
	s_mov_b64 s[2:3], 0xa0000
	s_waitcnt lgkmcnt(0)
	v_lshlrev_b32_e32 v72, 16, v64
	v_and_b32_e32 v73, 0xffff0000, v64
	v_lshlrev_b32_e32 v64, 16, v65
	v_and_b32_e32 v65, 0xffff0000, v65
	v_lshlrev_b32_e32 v74, 16, v66
	v_and_b32_e32 v75, 0xffff0000, v66
	v_lshlrev_b32_e32 v66, 16, v67
	v_and_b32_e32 v67, 0xffff0000, v67
	v_pk_fma_f32 v[54:55], v[54:55], v[62:63], v[64:65]
	v_pk_fma_f32 v[52:53], v[52:53], v[60:61], v[72:73]
	v_pk_fma_f32 v[64:65], v[50:51], v[58:59], v[66:67]
	v_pk_fma_f32 v[50:51], v[48:49], v[56:57], v[74:75]
	v_cvt_pk_bf16_f32 v48, v52, v53
	v_cvt_pk_bf16_f32 v49, v54, v55
	v_cvt_pk_bf16_f32 v50, v50, v51
	v_cvt_pk_bf16_f32 v51, v64, v65
	v_lshl_add_u64 v[52:53], s[42:43], 0, v[68:69]
	global_store_dwordx4 v[52:53], v[48:51], off
	global_load_dwordx4 v[48:51], v[70:71], off offset:256
	s_waitcnt vmcnt(0) lgkmcnt(0)
	v_lshlrev_b32_e32 v54, 16, v48
	v_and_b32_e32 v55, 0xffff0000, v48
	v_lshlrev_b32_e32 v48, 16, v49
	v_and_b32_e32 v49, 0xffff0000, v49
	v_lshlrev_b32_e32 v64, 16, v50
	v_and_b32_e32 v65, 0xffff0000, v50
	v_lshlrev_b32_e32 v50, 16, v51
	v_and_b32_e32 v51, 0xffff0000, v51
	v_pk_fma_f32 v[38:39], v[38:39], v[46:47], v[48:49]
	v_pk_fma_f32 v[36:37], v[36:37], v[44:45], v[54:55]
	v_pk_fma_f32 v[48:49], v[34:35], v[42:43], v[50:51]
	v_pk_fma_f32 v[34:35], v[32:33], v[40:41], v[64:65]
	v_cvt_pk_bf16_f32 v32, v36, v37
	v_cvt_pk_bf16_f32 v33, v38, v39
	v_cvt_pk_bf16_f32 v34, v34, v35
	v_cvt_pk_bf16_f32 v35, v48, v49
	v_lshl_add_u64 v[36:37], v[160:161], 0, s[2:3]
	global_store_dwordx4 v[52:53], v[32:35], off offset:256
	v_lshl_add_u64 v[38:39], s[4:5], 0, v[36:37]
	global_load_dwordx4 v[32:35], v[38:39], off
	s_mov_b64 s[2:3], 0xb0000
	s_waitcnt vmcnt(0) lgkmcnt(0)
	v_lshlrev_b32_e32 v48, 16, v32
	v_and_b32_e32 v49, 0xffff0000, v32
	v_lshlrev_b32_e32 v32, 16, v33
	v_and_b32_e32 v33, 0xffff0000, v33
	v_lshlrev_b32_e32 v50, 16, v34
	v_and_b32_e32 v51, 0xffff0000, v34
	v_lshlrev_b32_e32 v34, 16, v35
	v_and_b32_e32 v35, 0xffff0000, v35
	v_pk_fma_f32 v[30:31], v[30:31], v[62:63], v[32:33]
	v_pk_fma_f32 v[28:29], v[28:29], v[60:61], v[48:49]
	v_pk_fma_f32 v[32:33], v[26:27], v[58:59], v[34:35]
	v_pk_fma_f32 v[26:27], v[24:25], v[56:57], v[50:51]
	v_cvt_pk_bf16_f32 v24, v28, v29
	v_cvt_pk_bf16_f32 v25, v30, v31
	v_cvt_pk_bf16_f32 v26, v26, v27
	v_cvt_pk_bf16_f32 v27, v32, v33
	v_lshl_add_u64 v[28:29], s[42:43], 0, v[36:37]
	global_store_dwordx4 v[28:29], v[24:27], off
	global_load_dwordx4 v[24:27], v[38:39], off offset:256
	s_waitcnt vmcnt(0) lgkmcnt(0)
	v_lshlrev_b32_e32 v30, 16, v24
	v_and_b32_e32 v31, 0xffff0000, v24
	v_lshlrev_b32_e32 v24, 16, v25
	v_and_b32_e32 v25, 0xffff0000, v25
	v_lshlrev_b32_e32 v32, 16, v26
	v_and_b32_e32 v33, 0xffff0000, v26
	v_lshlrev_b32_e32 v26, 16, v27
	v_and_b32_e32 v27, 0xffff0000, v27
	v_pk_fma_f32 v[22:23], v[22:23], v[46:47], v[24:25]
	v_pk_fma_f32 v[20:21], v[20:21], v[44:45], v[30:31]
	v_pk_fma_f32 v[24:25], v[18:19], v[42:43], v[26:27]
	v_pk_fma_f32 v[18:19], v[16:17], v[40:41], v[32:33]
	v_cvt_pk_bf16_f32 v16, v20, v21
	v_cvt_pk_bf16_f32 v17, v22, v23
	v_cvt_pk_bf16_f32 v18, v18, v19
	v_cvt_pk_bf16_f32 v19, v24, v25
	v_lshl_add_u64 v[20:21], v[160:161], 0, s[2:3]
	global_store_dwordx4 v[28:29], v[16:19], off offset:256
	v_lshl_add_u64 v[22:23], s[4:5], 0, v[20:21]
	global_load_dwordx4 v[16:19], v[22:23], off
	s_mov_b32 s2, s37
	s_waitcnt vmcnt(0) lgkmcnt(0)
	v_lshlrev_b32_e32 v24, 16, v16
	v_and_b32_e32 v25, 0xffff0000, v16
	v_lshlrev_b32_e32 v16, 16, v17
	v_and_b32_e32 v17, 0xffff0000, v17
	v_lshlrev_b32_e32 v26, 16, v18
	v_and_b32_e32 v27, 0xffff0000, v18
	v_lshlrev_b32_e32 v18, 16, v19
	v_and_b32_e32 v19, 0xffff0000, v19
	v_pk_fma_f32 v[14:15], v[14:15], v[62:63], v[16:17]
	v_pk_fma_f32 v[12:13], v[12:13], v[60:61], v[24:25]
	v_pk_fma_f32 v[16:17], v[10:11], v[58:59], v[18:19]
	v_pk_fma_f32 v[10:11], v[8:9], v[56:57], v[26:27]
	v_cvt_pk_bf16_f32 v8, v12, v13
	v_cvt_pk_bf16_f32 v9, v14, v15
	v_cvt_pk_bf16_f32 v10, v10, v11
	v_cvt_pk_bf16_f32 v11, v16, v17
	v_lshl_add_u64 v[12:13], s[42:43], 0, v[20:21]
	global_store_dwordx4 v[12:13], v[8:11], off
	global_load_dwordx4 v[8:11], v[22:23], off offset:256
	s_waitcnt vmcnt(0) lgkmcnt(0)
	v_lshlrev_b32_e32 v14, 16, v8
	v_and_b32_e32 v15, 0xffff0000, v8
	v_lshlrev_b32_e32 v8, 16, v9
	v_and_b32_e32 v9, 0xffff0000, v9
	v_lshlrev_b32_e32 v16, 16, v10
	v_and_b32_e32 v17, 0xffff0000, v10
	v_lshlrev_b32_e32 v10, 16, v11
	v_and_b32_e32 v11, 0xffff0000, v11
	v_pk_fma_f32 v[6:7], v[6:7], v[46:47], v[8:9]
	v_pk_fma_f32 v[4:5], v[4:5], v[44:45], v[14:15]
	v_pk_fma_f32 v[8:9], v[2:3], v[42:43], v[10:11]
	v_pk_fma_f32 v[2:3], v[0:1], v[40:41], v[16:17]
	v_cvt_pk_bf16_f32 v0, v4, v5
	v_cvt_pk_bf16_f32 v1, v6, v7
	v_cvt_pk_bf16_f32 v2, v2, v3
	v_cvt_pk_bf16_f32 v3, v8, v9
	global_store_dwordx4 v[12:13], v[0:3], off offset:256
	s_cbranch_vccz .LBB1_2336
	s_waitcnt vmcnt(0)
	s_cmpk_gt_u32 s17, 0xff
	s_cbranch_scc1 .LBB1_2343
	s_barrier

; template <class Map, class Epi>
; DI void gemm_phase(LAS unsigned char* lds, const Map& MP, const Epi& E, const int nM, const int nN, const int K, const int lda, const int ldb) {
;     ...
;         const bool has_next = sched_next(ui + 1, nM, nN, G, cblk, nxt);
;         const char* nA = has_next ? MP.a(nxt) : cA; const char* nB = has_next ? MP.b(nxt) : cB;
;         for (int t = 0; t < nt; t += 2) {
;             const bool last = (t == nt - 2);
;             const char* a1 = cA + (size_t)(t + 1) * kstep;
;             const char* a2 = last ? nA : cA + (size_t)(t + 2) * kstep; const char* b2 = last ? nB : cB + (size_t)(t + 2) * kstep;
;             const char* a3 = a2 + kstep; const char* b3 = b2 + kstep;
;             PG8_LDB(B0, 0, 0); PG8_SCHED; PG8_LDA(At, 0, 0); PG8_STAGE(PG8_SA(1, 1), a1 + hstepA, voffA);
;             PG8_WAIT_L(8); PG8_BAR; PG8_WAIT_L(0); PG8_MMA(0, 0, At, B0); PG8_BAR; PG8_SCHED;
;             PG8_LDB(B1, 0, 1); PG8_STAGE(PG8_SB(0, 0), b2, voffB);
;             PG8_BAR; PG8_WAIT_L(0); PG8_MMA(0, 1, At, B1); PG8_BAR;
;             PG8_LDA(At, 0, 1); PG8_STAGE(PG8_SA(0, 0), a2, voffA);
;             PG8_BAR; PG8_WAIT_L(0); PG8_MMA(1, 0, At, B0); PG8_BAR; PG8_SCHED;
;             PG8_STAGE(PG8_SB(0, 1), b2 + hstepB, voffB);
;             PG8_WAIT_V(6); PG8_BAR; PG8_MMA(1, 1, At, B1); PG8_BAR;
;             PG8_LDB(B0, 1, 0); PG8_SCHED; PG8_LDA(At, 1, 0); PG8_STAGE(PG8_SA(0, 1), a2 + hstepA, voffA);
;             PG8_WAIT_L(8); PG8_BAR; PG8_WAIT_L(0); PG8_MMA(0, 0, At, B0); PG8_BAR; PG8_SCHED;
;             PG8_LDB(B1, 1, 1); PG8_STAGE(PG8_SB(1, 0), b3, voffB);
;             PG8_BAR; PG8_WAIT_L(0); PG8_MMA(0, 1, At, B1); PG8_BAR;
;             PG8_LDA(At, 1, 1); PG8_STAGE(PG8_SA(1, 0), a3, voffA);
;             PG8_BAR; PG8_WAIT_L(0); PG8_MMA(1, 0, At, B0); PG8_BAR; PG8_SCHED;
;             PG8_STAGE(PG8_SB(1, 1), b3 + hstepB, voffB);
;             PG8_WAIT_V(6); PG8_BAR; PG8_MMA(1, 1, At, B1); PG8_BAR;
;         }
;         { int frr = fr, fqq = fq; asm volatile("" : "+v"(frr), "+v"(fqq)); E(acc, cur, wr, wc, frr, fqq); }
;         if (!has_next) break;
; #pragma unroll
;         for (int a = 0; a < 2; ++a)
; #pragma unroll
;             for (int b = 0; b < 2; ++b)
; #pragma unroll
;                 for (int m = 0; m < 4; ++m)
; #pragma unroll
;                     for (int n = 0; n < 2; ++n) acc[a][b][m][n] = (f32x4){0.f, 0.f, 0.f, 0.f};
.LBB1_2482:
	s_ashr_i32 s23, s22, 31
	v_cmp_lt_i64_e32 vcc, s[24:25], v[180:181]
	s_lshl_b64 s[24:25], s[22:23], 20
	s_add_u32 s24, s33, s24
	s_addc_u32 s25, s34, s25
	s_and_b64 s[26:27], vcc, exec
	s_cselect_b32 s23, s25, s29
	s_cselect_b32 s58, s24, s28
	s_ashr_i32 s21, s20, 31
	s_lshl_b64 s[26:27], s[20:21], 20
	s_add_u32 s26, s35, s26
	s_addc_u32 s27, s36, s27
	s_and_b64 s[42:43], vcc, exec
	s_cselect_b32 s21, s27, s47
	s_cselect_b32 s59, s26, s46
	s_add_u32 vcc_lo, s46, 0x100
	s_addc_u32 vcc_hi, s47, 0
	s_add_u32 s42, s28, 0x80080
	v_mov_b32_e32 v0, 0
	s_addc_u32 s43, s29, 0
	s_mov_b32 s3, -2
	v_mov_b32_e32 v1, v0
	v_mov_b32_e32 v2, v0
	v_mov_b32_e32 v3, v0
	v_mov_b32_e32 v4, v0
	v_mov_b32_e32 v5, v0
	v_mov_b32_e32 v6, v0
	v_mov_b32_e32 v7, v0
	v_mov_b32_e32 v20, v0
	v_mov_b32_e32 v21, v0
	v_mov_b32_e32 v22, v0
	v_mov_b32_e32 v23, v0
	v_mov_b32_e32 v28, v0
	v_mov_b32_e32 v29, v0
	v_mov_b32_e32 v30, v0
	v_mov_b32_e32 v31, v0
	v_mov_b32_e32 v36, v0
	v_mov_b32_e32 v37, v0
	v_mov_b32_e32 v38, v0
	v_mov_b32_e32 v39, v0
	v_mov_b32_e32 v44, v0
	v_mov_b32_e32 v45, v0
	v_mov_b32_e32 v46, v0
	v_mov_b32_e32 v47, v0
	v_mov_b32_e32 v52, v0
	v_mov_b32_e32 v53, v0
	v_mov_b32_e32 v54, v0
	v_mov_b32_e32 v55, v0
	v_mov_b32_e32 v56, v0
	v_mov_b32_e32 v57, v0
	v_mov_b32_e32 v58, v0
	v_mov_b32_e32 v59, v0
	v_mov_b32_e32 v8, v0
	v_mov_b32_e32 v9, v0
	v_mov_b32_e32 v10, v0
	v_mov_b32_e32 v11, v0
	v_mov_b32_e32 v12, v0
	v_mov_b32_e32 v13, v0
	v_mov_b32_e32 v14, v0
	v_mov_b32_e32 v15, v0
	v_mov_b32_e32 v16, v0
	v_mov_b32_e32 v17, v0
	v_mov_b32_e32 v18, v0
	v_mov_b32_e32 v19, v0
	v_mov_b32_e32 v24, v0
	v_mov_b32_e32 v25, v0
	v_mov_b32_e32 v26, v0
	v_mov_b32_e32 v27, v0
	v_mov_b32_e32 v32, v0
	v_mov_b32_e32 v33, v0
	v_mov_b32_e32 v34, v0
	v_mov_b32_e32 v35, v0
	v_mov_b32_e32 v40, v0
	v_mov_b32_e32 v41, v0
	v_mov_b32_e32 v42, v0
	v_mov_b32_e32 v43, v0
	v_mov_b32_e32 v48, v0
	v_mov_b32_e32 v49, v0
	v_mov_b32_e32 v50, v0
	v_mov_b32_e32 v51, v0
	v_mov_b32_e32 v60, v0
	v_mov_b32_e32 v61, v0
	v_mov_b32_e32 v62, v0
	v_mov_b32_e32 v63, v0
	v_mov_b32_e32 v64, v0
	v_mov_b32_e32 v65, v0
	v_mov_b32_e32 v66, v0
	v_mov_b32_e32 v67, v0
	v_mov_b32_e32 v68, v0
	v_mov_b32_e32 v69, v0
	v_mov_b32_e32 v70, v0
	v_mov_b32_e32 v71, v0
	v_mov_b32_e32 v116, v0
	v_mov_b32_e32 v117, v0
	v_mov_b32_e32 v118, v0
	v_mov_b32_e32 v119, v0
	v_mov_b32_e32 v124, v0
	v_mov_b32_e32 v125, v0
	v_mov_b32_e32 v126, v0
	v_mov_b32_e32 v127, v0
	v_mov_b32_e32 v132, v0
	v_mov_b32_e32 v133, v0
	v_mov_b32_e32 v134, v0
	v_mov_b32_e32 v135, v0
	v_mov_b32_e32 v140, v0
	v_mov_b32_e32 v141, v0
	v_mov_b32_e32 v142, v0
	v_mov_b32_e32 v143, v0
	v_mov_b32_e32 v152, v0
	v_mov_b32_e32 v153, v0
	v_mov_b32_e32 v154, v0
	v_mov_b32_e32 v155, v0
	v_mov_b32_e32 v156, v0
	v_mov_b32_e32 v157, v0
	v_mov_b32_e32 v158, v0
	v_mov_b32_e32 v159, v0
	v_mov_b32_e32 v72, v0
	v_mov_b32_e32 v73, v0
	v_mov_b32_e32 v74, v0
	v_mov_b32_e32 v75, v0
	v_mov_b32_e32 v76, v0
	v_mov_b32_e32 v77, v0
	v_mov_b32_e32 v78, v0
	v_mov_b32_e32 v79, v0
	v_mov_b32_e32 v104, v0
	v_mov_b32_e32 v105, v0
	v_mov_b32_e32 v106, v0
	v_mov_b32_e32 v107, v0
	v_mov_b32_e32 v120, v0
	v_mov_b32_e32 v121, v0
	v_mov_b32_e32 v122, v0
	v_mov_b32_e32 v123, v0
	v_mov_b32_e32 v128, v0
	v_mov_b32_e32 v129, v0
	v_mov_b32_e32 v130, v0
	v_mov_b32_e32 v131, v0
	v_mov_b32_e32 v136, v0
	v_mov_b32_e32 v137, v0
	v_mov_b32_e32 v138, v0
	v_mov_b32_e32 v139, v0
	v_mov_b32_e32 v144, v0
	v_mov_b32_e32 v145, v0
	v_mov_b32_e32 v146, v0
	v_mov_b32_e32 v147, v0
	v_mov_b32_e32 v148, v0
	v_mov_b32_e32 v149, v0
	v_mov_b32_e32 v150, v0
	v_mov_b32_e32 v151, v0
	ds_read_b128 v[80:83], v189
	ds_read_b128 v[84:87], v189 offset:1024
	ds_read_b128 v[88:91], v189 offset:2048
	ds_read_b128 v[92:95], v189 offset:3072
.LBB1_2483:
	s_add_u32 s28, s42, 0xfff80080
	s_addc_u32 s29, s43, -1
	s_cmp_eq_u32 s3, 28
	s_cselect_b32 s47, s23, s29
	s_cselect_b32 s46, s58, s28
	s_cselect_b32 s29, s21, vcc_hi
	s_cselect_b32 s28, s59, vcc_lo
	s_add_i32 m0, s38, 0xc000
	ds_read_b128 v[96:99], v190
	ds_read_b128 v[100:103], v190 offset:1024
	ds_read_b128 v[108:111], v190 offset:2048
	ds_read_b128 v[112:115], v190 offset:3072
	ds_read_b128 v[160:163], v190 offset:4096
	ds_read_b128 v[164:167], v190 offset:5120
	ds_read_b128 v[198:201], v190 offset:6144
	ds_read_b128 v[202:205], v190 offset:7168
	global_load_lds_dwordx4 v178, s[42:43]
	s_add_i32 m0, s38, 0xe000
	s_nop 0
	global_load_lds_dwordx4 v176, s[42:43]
	s_waitcnt lgkmcnt(8)
	s_barrier
	s_setprio 1
	s_waitcnt lgkmcnt(7)
	v_mfma_f32_16x16x32_bf16 v[148:151], v[80:83], v[96:99], v[148:151]
	v_mfma_f32_16x16x32_bf16 v[144:147], v[88:91], v[96:99], v[144:147]
	s_waitcnt lgkmcnt(5)
	v_mfma_f32_16x16x32_bf16 v[136:139], v[80:83], v[108:111], v[136:139]
	v_mfma_f32_16x16x32_bf16 v[128:131], v[88:91], v[108:111], v[128:131]
	s_waitcnt lgkmcnt(3)
	v_mfma_f32_16x16x32_bf16 v[120:123], v[80:83], v[160:163], v[120:123]
	v_mfma_f32_16x16x32_bf16 v[104:107], v[88:91], v[160:163], v[104:107]
	s_waitcnt lgkmcnt(1)
	v_mfma_f32_16x16x32_bf16 v[76:79], v[80:83], v[198:201], v[76:79]
	v_mfma_f32_16x16x32_bf16 v[72:75], v[88:91], v[198:201], v[72:75]
	v_mfma_f32_16x16x32_bf16 v[148:151], v[84:87], v[100:103], v[148:151]
	v_mfma_f32_16x16x32_bf16 v[144:147], v[92:95], v[100:103], v[144:147]
	v_mfma_f32_16x16x32_bf16 v[136:139], v[84:87], v[112:115], v[136:139]
	v_mfma_f32_16x16x32_bf16 v[128:131], v[92:95], v[112:115], v[128:131]
	v_mfma_f32_16x16x32_bf16 v[120:123], v[84:87], v[164:167], v[120:123]
	v_mfma_f32_16x16x32_bf16 v[104:107], v[92:95], v[164:167], v[104:107]
	s_waitcnt lgkmcnt(0)
	v_mfma_f32_16x16x32_bf16 v[76:79], v[84:87], v[202:205], v[76:79]
	v_mfma_f32_16x16x32_bf16 v[72:75], v[92:95], v[202:205], v[72:75]
	s_setprio 0
	s_barrier
; #define PG8_STAGE(bufoff, gbase, voff) do { _Pragma("unroll") for (int _i = 0; _i < 2; ++_i) \
;         __builtin_amdgcn_global_load_lds((const unsigned*)((const char*)(gbase) + (voff)[_i]), (LAS unsigned*)(lds + (bufoff) + ldsw + _i * 8192), 16, 0, 0); } while (0)
; #define PG8_LDA(dst, b, h) do { _Pragma("unroll") for (int m = 0; m < 4; ++m) _Pragma("unroll") for (int k = 0; k < 2; ++k) dst[m][k] = *(const LAS bf16x8*)(lds + PG8_SA(b, h) + aoff + m * 2048 + k * 1024); } while (0)
; #define PG8_LDB(dst, b, h) do { _Pragma("unroll") for (int n = 0; n < 2; ++n) _Pragma("unroll") for (int k = 0; k < 2; ++k) dst[n][k] = *(const LAS bf16x8*)(lds + PG8_SB(b, h) + boff + n * 2048 + k * 1024); } while (0)
; #define PG8_MMA(ai, bj, At, Bt) do { __builtin_amdgcn_s_setprio(1); _Pragma("unroll") for (int m = 0; m < 4; ++m) _Pragma("unroll") for (int n = 0; n < 2; ++n) _Pragma("unroll") for (int k = 0; k < 2; ++k) \
;         acc[ai][bj][m][n] = __builtin_amdgcn_mfma_f32_16x16x32_bf16(Bt[n][k], At[m][k], acc[ai][bj][m][n], 0, 0, 0); __builtin_amdgcn_s_setprio(0); } while (0)
; #define PG8_WAIT_V(n) asm volatile("s_waitcnt vmcnt(" #n ")" ::: "memory")
; #define PG8_WAIT_L(n) asm volatile("s_waitcnt lgkmcnt(" #n ")" ::: "memory")
; #define PG8_BAR __builtin_amdgcn_s_barrier()
; #define PG8_SCHED __builtin_amdgcn_sched_barrier(0)
; template <class Map, class Epi>
; DI void gemm_phase(LAS unsigned char* lds, const Map& MP, const Epi& E, const int nM, const int nN, const int K, const int lda, const int ldb) {
;     ...
;             PG8_LDB(B0, 0, 0); PG8_SCHED; PG8_LDA(At, 0, 0); PG8_STAGE(PG8_SA(1, 1), a1 + hstepA, voffA);
;             PG8_WAIT_L(8); PG8_BAR; PG8_WAIT_L(0); PG8_MMA(0, 0, At, B0); PG8_BAR; PG8_SCHED;
;             PG8_LDB(B1, 0, 1); PG8_STAGE(PG8_SB(0, 0), b2, voffB);
;             PG8_BAR; PG8_WAIT_L(0); PG8_MMA(0, 1, At, B1); PG8_BAR;
;             PG8_LDA(At, 0, 1); PG8_STAGE(PG8_SA(0, 0), a2, voffA);
;             PG8_BAR; PG8_WAIT_L(0); PG8_MMA(1, 0, At, B0); PG8_BAR; PG8_SCHED;
;             PG8_STAGE(PG8_SB(0, 1), b2 + hstepB, voffB);
;             PG8_WAIT_V(6); PG8_BAR; PG8_MMA(1, 1, At, B1); PG8_BAR;
;             PG8_LDB(B0, 1, 0); PG8_SCHED; PG8_LDA(At, 1, 0); PG8_STAGE(PG8_SA(0, 1), a2 + hstepA, voffA);
;             PG8_WAIT_L(8); PG8_BAR; PG8_WAIT_L(0); PG8_MMA(0, 0, At, B0); PG8_BAR; PG8_SCHED;
	s_add_i32 s68, s2, s37
	v_lshl_add_u64 v[184:185], s[28:29], 0, v[172:173]
	s_mov_b32 m0, s68
	ds_read_b128 v[206:209], v191
	ds_read_b128 v[210:213], v191 offset:1024
	ds_read_b128 v[214:217], v191 offset:2048
	ds_read_b128 v[218:221], v191 offset:3072
	global_load_lds_dwordx4 v[184:185], off
	v_lshl_add_u64 v[194:195], s[28:29], 0, v[168:169]
	s_add_i32 m0, s68, 0x2000
	s_nop 0
	global_load_lds_dwordx4 v[194:195], off
	s_barrier
	s_setprio 1
	s_waitcnt lgkmcnt(3)
	v_mfma_f32_16x16x32_bf16 v[156:159], v[206:209], v[96:99], v[156:159]
	s_waitcnt lgkmcnt(1)
	v_mfma_f32_16x16x32_bf16 v[96:99], v[214:217], v[96:99], v[152:155]
	v_mfma_f32_16x16x32_bf16 v[156:159], v[210:213], v[100:103], v[156:159]
	s_waitcnt lgkmcnt(0)
	v_mfma_f32_16x16x32_bf16 v[96:99], v[218:221], v[100:103], v[96:99]
	v_mfma_f32_16x16x32_bf16 v[100:103], v[206:209], v[108:111], v[140:143]
	v_mfma_f32_16x16x32_bf16 v[108:111], v[214:217], v[108:111], v[132:135]
	v_mfma_f32_16x16x32_bf16 v[116:119], v[214:217], v[160:163], v[116:119]
	v_mfma_f32_16x16x32_bf16 v[68:71], v[206:209], v[198:201], v[68:71]
	v_mfma_f32_16x16x32_bf16 v[64:67], v[214:217], v[198:201], v[64:67]
	v_mfma_f32_16x16x32_bf16 v[100:103], v[210:213], v[112:115], v[100:103]
	v_mfma_f32_16x16x32_bf16 v[108:111], v[218:221], v[112:115], v[108:111]
	v_mfma_f32_16x16x32_bf16 v[112:115], v[206:209], v[160:163], v[124:127]
	v_mfma_f32_16x16x32_bf16 v[116:119], v[218:221], v[164:167], v[116:119]
	v_mfma_f32_16x16x32_bf16 v[68:71], v[210:213], v[202:205], v[68:71]
	v_mfma_f32_16x16x32_bf16 v[64:67], v[218:221], v[202:205], v[64:67]
	v_mfma_f32_16x16x32_bf16 v[112:115], v[210:213], v[164:167], v[112:115]
	s_setprio 0
	s_mov_b32 m0, s38
	v_lshl_add_u64 v[230:231], s[46:47], 0, v[174:175]
	s_barrier
	ds_read_b128 v[124:127], v190 offset:16384
	ds_read_b128 v[132:135], v190 offset:17408
	ds_read_b128 v[140:143], v190 offset:18432
	ds_read_b128 v[152:155], v190 offset:19456
	ds_read_b128 v[160:163], v190 offset:20480
	ds_read_b128 v[164:167], v190 offset:21504
	ds_read_b128 v[198:201], v190 offset:22528
	ds_read_b128 v[202:205], v190 offset:23552
	global_load_lds_dwordx4 v[230:231], off
	v_lshl_add_u64 v[232:233], s[46:47], 0, v[170:171]
	s_mov_b32 m0, s39
	s_nop 0
	global_load_lds_dwordx4 v[232:233], off
	s_waitcnt vmcnt(10)
	s_barrier
	s_setprio 1
	s_waitcnt lgkmcnt(7)
	v_mfma_f32_16x16x32_bf16 v[60:63], v[80:83], v[124:127], v[60:63]
	v_mfma_f32_16x16x32_bf16 v[48:51], v[88:91], v[124:127], v[48:51]
	s_waitcnt lgkmcnt(5)
	v_mfma_f32_16x16x32_bf16 v[40:43], v[80:83], v[140:143], v[40:43]
	v_mfma_f32_16x16x32_bf16 v[32:35], v[88:91], v[140:143], v[32:35]
	s_waitcnt lgkmcnt(3)
	v_mfma_f32_16x16x32_bf16 v[24:27], v[80:83], v[160:163], v[24:27]
	v_mfma_f32_16x16x32_bf16 v[16:19], v[88:91], v[160:163], v[16:19]
	s_waitcnt lgkmcnt(1)
	v_mfma_f32_16x16x32_bf16 v[12:15], v[80:83], v[198:201], v[12:15]
	v_mfma_f32_16x16x32_bf16 v[8:11], v[88:91], v[198:201], v[8:11]
	v_mfma_f32_16x16x32_bf16 v[60:63], v[84:87], v[132:135], v[60:63]
	v_mfma_f32_16x16x32_bf16 v[48:51], v[92:95], v[132:135], v[48:51]
	v_mfma_f32_16x16x32_bf16 v[40:43], v[84:87], v[152:155], v[40:43]
	v_mfma_f32_16x16x32_bf16 v[32:35], v[92:95], v[152:155], v[32:35]
	v_mfma_f32_16x16x32_bf16 v[24:27], v[84:87], v[164:167], v[24:27]
	v_mfma_f32_16x16x32_bf16 v[16:19], v[92:95], v[164:167], v[16:19]
	s_waitcnt lgkmcnt(0)
	v_mfma_f32_16x16x32_bf16 v[12:15], v[84:87], v[202:205], v[12:15]
	v_mfma_f32_16x16x32_bf16 v[8:11], v[92:95], v[202:205], v[8:11]
	s_setprio 0
	s_barrier
	s_add_u32 s68, s28, 0x80000
	s_addc_u32 s69, s29, 0
	s_add_i32 s70, s67, s37
	s_mov_b32 m0, s70
	s_nop 0
	global_load_lds_dwordx4 v172, s[68:69]
	s_add_i32 m0, s70, 0x2000
	s_nop 0
	global_load_lds_dwordx4 v168, s[68:69]
	s_waitcnt vmcnt(6)
	s_barrier
	s_setprio 1
	v_mfma_f32_16x16x32_bf16 v[56:59], v[206:209], v[124:127], v[56:59]
	v_mfma_f32_16x16x32_bf16 v[52:55], v[214:217], v[124:127], v[52:55]
	s_add_i32 s68, 0, 0x18000
	v_add_u32_e32 v92, s68, v188
	ds_read_b128 v[80:83], v92
	v_mfma_f32_16x16x32_bf16 v[44:47], v[206:209], v[140:143], v[44:47]
	v_mfma_f32_16x16x32_bf16 v[36:39], v[214:217], v[140:143], v[36:39]
	ds_read_b128 v[84:87], v92 offset:1024
	v_mfma_f32_16x16x32_bf16 v[28:31], v[206:209], v[160:163], v[28:31]
	v_mfma_f32_16x16x32_bf16 v[20:23], v[214:217], v[160:163], v[20:23]
	ds_read_b128 v[88:91], v92 offset:2048
	v_mfma_f32_16x16x32_bf16 v[4:7], v[206:209], v[198:201], v[4:7]
	v_mfma_f32_16x16x32_bf16 v[0:3], v[214:217], v[198:201], v[0:3]
	ds_read_b128 v[92:95], v92 offset:3072
	v_mfma_f32_16x16x32_bf16 v[56:59], v[210:213], v[132:135], v[56:59]
	v_mfma_f32_16x16x32_bf16 v[52:55], v[218:221], v[132:135], v[52:55]
	v_mfma_f32_16x16x32_bf16 v[44:47], v[210:213], v[152:155], v[44:47]
	v_mfma_f32_16x16x32_bf16 v[36:39], v[218:221], v[152:155], v[36:39]
	v_mfma_f32_16x16x32_bf16 v[28:31], v[210:213], v[164:167], v[28:31]
	v_mfma_f32_16x16x32_bf16 v[20:23], v[218:221], v[164:167], v[20:23]
	v_mfma_f32_16x16x32_bf16 v[4:7], v[210:213], v[202:205], v[4:7]
	v_mfma_f32_16x16x32_bf16 v[0:3], v[218:221], v[202:205], v[0:3]
	s_setprio 0
	s_barrier
	s_add_u32 s46, s46, 0x80000
	s_addc_u32 s47, s47, 0
	s_mov_b32 m0, s55
	ds_read_b128 v[124:127], v190 offset:32768
	ds_read_b128 v[132:135], v190 offset:33792
	ds_read_b128 v[160:163], v190 offset:34816
	ds_read_b128 v[164:167], v190 offset:35840
	ds_read_b128 v[198:201], v190 offset:36864
	ds_read_b128 v[202:205], v190 offset:37888
	ds_read_b128 v[206:209], v190 offset:38912
	ds_read_b128 v[210:213], v190 offset:39936
	global_load_lds_dwordx4 v174, s[46:47]
	s_mov_b32 m0, s56
	s_nop 0
	global_load_lds_dwordx4 v170, s[46:47]
	s_waitcnt lgkmcnt(8)
	s_barrier
; #define PG8_STAGE(bufoff, gbase, voff) do { _Pragma("unroll") for (int _i = 0; _i < 2; ++_i) \
;         __builtin_amdgcn_global_load_lds((const unsigned*)((const char*)(gbase) + (voff)[_i]), (LAS unsigned*)(lds + (bufoff) + ldsw + _i * 8192), 16, 0, 0); } while (0)
; #define PG8_LDA(dst, b, h) do { _Pragma("unroll") for (int m = 0; m < 4; ++m) _Pragma("unroll") for (int k = 0; k < 2; ++k) dst[m][k] = *(const LAS bf16x8*)(lds + PG8_SA(b, h) + aoff + m * 2048 + k * 1024); } while (0)
; #define PG8_LDB(dst, b, h) do { _Pragma("unroll") for (int n = 0; n < 2; ++n) _Pragma("unroll") for (int k = 0; k < 2; ++k) dst[n][k] = *(const LAS bf16x8*)(lds + PG8_SB(b, h) + boff + n * 2048 + k * 1024); } while (0)
; #define PG8_MMA(ai, bj, At, Bt) do { __builtin_amdgcn_s_setprio(1); _Pragma("unroll") for (int m = 0; m < 4; ++m) _Pragma("unroll") for (int n = 0; n < 2; ++n) _Pragma("unroll") for (int k = 0; k < 2; ++k) \
;         acc[ai][bj][m][n] = __builtin_amdgcn_mfma_f32_16x16x32_bf16(Bt[n][k], At[m][k], acc[ai][bj][m][n], 0, 0, 0); __builtin_amdgcn_s_setprio(0); } while (0)
; #define PG8_WAIT_V(n) asm volatile("s_waitcnt vmcnt(" #n ")" ::: "memory")
; #define PG8_WAIT_L(n) asm volatile("s_waitcnt lgkmcnt(" #n ")" ::: "memory")
; #define PG8_BAR __builtin_amdgcn_s_barrier()
; #define PG8_SCHED __builtin_amdgcn_sched_barrier(0)
; template <class Map, class Epi>
; DI void gemm_phase(LAS unsigned char* lds, const Map& MP, const Epi& E, const int nM, const int nN, const int K, const int lda, const int ldb) {
;     ...
;             PG8_WAIT_V(6); PG8_BAR; PG8_MMA(1, 1, At, B1); PG8_BAR;
;             PG8_LDB(B0, 1, 0); PG8_SCHED; PG8_LDA(At, 1, 0); PG8_STAGE(PG8_SA(0, 1), a2 + hstepA, voffA);
;             PG8_WAIT_L(8); PG8_BAR; PG8_WAIT_L(0); PG8_MMA(0, 0, At, B0); PG8_BAR; PG8_SCHED;
;             PG8_LDB(B1, 1, 1); PG8_STAGE(PG8_SB(1, 0), b3, voffB);
;             PG8_BAR; PG8_WAIT_L(0); PG8_MMA(0, 1, At, B1); PG8_BAR;
;             PG8_LDA(At, 1, 1); PG8_STAGE(PG8_SA(1, 0), a3, voffA);
;             PG8_BAR; PG8_WAIT_L(0); PG8_MMA(1, 0, At, B0); PG8_BAR; PG8_SCHED;
;             PG8_STAGE(PG8_SB(1, 1), b3 + hstepB, voffB);
;             PG8_WAIT_V(6); PG8_BAR; PG8_MMA(1, 1, At, B1); PG8_BAR;
	s_setprio 1
	s_waitcnt lgkmcnt(7)
	v_mfma_f32_16x16x32_bf16 v[140:143], v[80:83], v[124:127], v[148:151]
	s_waitcnt lgkmcnt(6)
	v_mfma_f32_16x16x32_bf16 v[148:151], v[84:87], v[132:135], v[140:143]
	v_mfma_f32_16x16x32_bf16 v[140:143], v[88:91], v[124:127], v[144:147]
	s_waitcnt lgkmcnt(5)
	v_mfma_f32_16x16x32_bf16 v[136:139], v[80:83], v[160:163], v[136:139]
	v_mfma_f32_16x16x32_bf16 v[128:131], v[88:91], v[160:163], v[128:131]
	s_waitcnt lgkmcnt(3)
	v_mfma_f32_16x16x32_bf16 v[120:123], v[80:83], v[198:201], v[120:123]
	v_mfma_f32_16x16x32_bf16 v[104:107], v[88:91], v[198:201], v[104:107]
	s_waitcnt lgkmcnt(1)
	v_mfma_f32_16x16x32_bf16 v[76:79], v[80:83], v[206:209], v[76:79]
	v_mfma_f32_16x16x32_bf16 v[72:75], v[88:91], v[206:209], v[72:75]
	v_mfma_f32_16x16x32_bf16 v[144:147], v[92:95], v[132:135], v[140:143]
	v_mfma_f32_16x16x32_bf16 v[136:139], v[84:87], v[164:167], v[136:139]
	v_mfma_f32_16x16x32_bf16 v[128:131], v[92:95], v[164:167], v[128:131]
	v_mfma_f32_16x16x32_bf16 v[120:123], v[84:87], v[202:205], v[120:123]
	v_mfma_f32_16x16x32_bf16 v[104:107], v[92:95], v[202:205], v[104:107]
	s_waitcnt lgkmcnt(0)
	v_mfma_f32_16x16x32_bf16 v[76:79], v[84:87], v[210:213], v[76:79]
	v_mfma_f32_16x16x32_bf16 v[72:75], v[92:95], v[210:213], v[72:75]
	s_setprio 0
	s_barrier
	s_add_i32 s46, 0, 0x1c000
	v_add_u32_e32 v140, s46, v188
	s_add_i32 s47, s68, s37
	ds_read_b128 v[214:217], v140
	ds_read_b128 v[218:221], v140 offset:1024
	ds_read_b128 v[222:225], v140 offset:2048
	ds_read_b128 v[226:229], v140 offset:3072
	v_lshl_add_u64 v[140:141], v[184:185], 0, s[14:15]
	s_mov_b32 m0, s47
	s_nop 0
	global_load_lds_dwordx4 v[140:141], off
	v_lshl_add_u64 v[140:141], v[194:195], 0, s[14:15]
	s_add_i32 m0, s47, 0x2000
	s_nop 0
	global_load_lds_dwordx4 v[140:141], off
	s_barrier
	s_setprio 1
	s_waitcnt lgkmcnt(1)
	v_mfma_f32_16x16x32_bf16 v[96:99], v[222:225], v[124:127], v[96:99]
	v_mfma_f32_16x16x32_bf16 v[140:143], v[214:217], v[124:127], v[156:159]
	s_waitcnt lgkmcnt(0)
	v_mfma_f32_16x16x32_bf16 v[152:155], v[226:229], v[132:135], v[96:99]
	v_mfma_f32_16x16x32_bf16 v[96:99], v[214:217], v[160:163], v[100:103]
	v_mfma_f32_16x16x32_bf16 v[156:159], v[218:221], v[132:135], v[140:143]
	v_mfma_f32_16x16x32_bf16 v[140:143], v[218:221], v[164:167], v[96:99]
	v_mfma_f32_16x16x32_bf16 v[96:99], v[222:225], v[160:163], v[108:111]
	v_mfma_f32_16x16x32_bf16 v[132:135], v[226:229], v[164:167], v[96:99]
	v_mfma_f32_16x16x32_bf16 v[96:99], v[214:217], v[198:201], v[112:115]
	v_mfma_f32_16x16x32_bf16 v[124:127], v[218:221], v[202:205], v[96:99]
	v_mfma_f32_16x16x32_bf16 v[96:99], v[222:225], v[198:201], v[116:119]
	v_mfma_f32_16x16x32_bf16 v[68:71], v[214:217], v[206:209], v[68:71]
	v_mfma_f32_16x16x32_bf16 v[64:67], v[222:225], v[206:209], v[64:67]
	v_mfma_f32_16x16x32_bf16 v[116:119], v[226:229], v[202:205], v[96:99]
	v_mfma_f32_16x16x32_bf16 v[68:71], v[218:221], v[210:213], v[68:71]
	v_mfma_f32_16x16x32_bf16 v[64:67], v[226:229], v[210:213], v[64:67]
	s_setprio 0
	s_mov_b32 m0, s62
	v_lshl_add_u64 v[184:185], v[230:231], 0, s[14:15]
	s_barrier
	ds_read_b128 v[96:99], v190 offset:49152
	ds_read_b128 v[100:103], v190 offset:50176
	ds_read_b128 v[108:111], v190 offset:51200
	ds_read_b128 v[112:115], v190 offset:52224
	ds_read_b128 v[160:163], v190 offset:53248
	ds_read_b128 v[164:167], v190 offset:54272
	ds_read_b128 v[198:201], v190 offset:55296
	ds_read_b128 v[202:205], v190 offset:56320
	global_load_lds_dwordx4 v[184:185], off
	v_lshl_add_u64 v[184:185], v[232:233], 0, s[14:15]
	s_mov_b32 m0, s63
	s_nop 0
	global_load_lds_dwordx4 v[184:185], off
	s_waitcnt vmcnt(10)
	s_barrier
	s_setprio 1
	s_waitcnt lgkmcnt(7)
	v_mfma_f32_16x16x32_bf16 v[60:63], v[80:83], v[96:99], v[60:63]
	v_mfma_f32_16x16x32_bf16 v[48:51], v[88:91], v[96:99], v[48:51]
	s_waitcnt lgkmcnt(5)
	v_mfma_f32_16x16x32_bf16 v[40:43], v[80:83], v[108:111], v[40:43]
	v_mfma_f32_16x16x32_bf16 v[32:35], v[88:91], v[108:111], v[32:35]
	s_waitcnt lgkmcnt(3)
	v_mfma_f32_16x16x32_bf16 v[24:27], v[80:83], v[160:163], v[24:27]
	v_mfma_f32_16x16x32_bf16 v[16:19], v[88:91], v[160:163], v[16:19]
	s_waitcnt lgkmcnt(1)
	v_mfma_f32_16x16x32_bf16 v[12:15], v[80:83], v[198:201], v[12:15]
	v_mfma_f32_16x16x32_bf16 v[8:11], v[88:91], v[198:201], v[8:11]
	v_mfma_f32_16x16x32_bf16 v[60:63], v[84:87], v[100:103], v[60:63]
	v_mfma_f32_16x16x32_bf16 v[48:51], v[92:95], v[100:103], v[48:51]
	v_mfma_f32_16x16x32_bf16 v[40:43], v[84:87], v[112:115], v[40:43]
	v_mfma_f32_16x16x32_bf16 v[32:35], v[92:95], v[112:115], v[32:35]
	v_mfma_f32_16x16x32_bf16 v[24:27], v[84:87], v[164:167], v[24:27]
	v_mfma_f32_16x16x32_bf16 v[16:19], v[92:95], v[164:167], v[16:19]
	s_waitcnt lgkmcnt(0)
	v_mfma_f32_16x16x32_bf16 v[12:15], v[84:87], v[202:205], v[12:15]
	v_mfma_f32_16x16x32_bf16 v[8:11], v[92:95], v[202:205], v[8:11]
	s_setprio 0
	s_barrier
	s_add_u32 s28, s28, 0x80080
	s_addc_u32 s29, s29, 0
	s_add_i32 s46, s46, s37
	s_mov_b32 m0, s46
	s_nop 0
	global_load_lds_dwordx4 v172, s[28:29]
	s_add_i32 m0, s46, 0x2000
	s_nop 0
	global_load_lds_dwordx4 v168, s[28:29]
	s_waitcnt vmcnt(6)
	s_barrier
; DI float dpp_ror1(float v)  { return __builtin_bit_cast(float, __builtin_amdgcn_update_dpp(0, __builtin_bit_cast(int, v), 0x121, 0xf, 0xf, false)); }
; #define PG8_WAIT_V(n) asm volatile("s_waitcnt vmcnt(" #n ")" ::: "memory")
;     DI void operator()(const f32x4 (&acc)[2][2][4][2], const Unit& u, int wr, int wc, int fr, int fq) const {
;         const int row0 = u.pm * BM + wr * 64 + fr, ch0 = u.pn * 128 + wc * 32 + 8 * fq;
;         f32x4 w0[2], w1[2], w2[2], bb[2];
; #pragma unroll
;         for (int n = 0; n < 2; ++n) { w0[n] = *(const f32x4*)(cw + ch0 + 4 * n); w1[n] = *(const f32x4*)(cw + DFF + ch0 + 4 * n); w2[n] = *(const f32x4*)(cw + 2 * DFF + ch0 + 4 * n); bb[n] = *(const f32x4*)(cb + ch0 + 4 * n); }
; #pragma unroll
;         for (int ai = 0; ai < 2; ++ai)
; #pragma unroll
;             for (int m = 0; m < 4; ++m) {
;                 const bool efirst = (m == 0) && (fr == 0), elast = (m == 3) && (fr == 15);
;                 const int row = row0 + ai * HALF + m * 16;
;                 f32x4 gc[2];
; #pragma unroll
;                 for (int n = 0; n < 2; ++n) {
;                     const f32x4 g = acc[ai][0][m][n];
;                     const f32x4 gprev = acc[ai][0][m > 0 ? m - 1 : 0][n], gnext = acc[ai][0][m < 3 ? m + 1 : 3][n];
;                     f32x4 up, dn;
; #pragma unroll
;                     for (int e = 0; e < 4; ++e) {
;                         const float pu = (m > 0 && fr == 15) ? gprev[e] : g[e];
;                         const float pd = (m < 3 && fr == 0) ? gnext[e] : g[e];
;                         up[e] = dpp_ror1(pu); dn[e] = dpp_ror15(pd);
;                     }
;                     if (efirst) up = (f32x4){0.f, 0.f, 0.f, 0.f};
;                     if (elast) dn = (f32x4){0.f, 0.f, 0.f, 0.f};
;                     gc[n] = w0[n] * up + w1[n] * g + w2[n] * dn + bb[n];
;                 }
; template <class Map, class Epi>
; DI void gemm_phase(LAS unsigned char* lds, const Map& MP, const Epi& E, const int nM, const int nN, const int K, const int lda, const int ldb) {
;     ...
;             PG8_BAR; PG8_WAIT_L(0); PG8_MMA(1, 0, At, B0); PG8_BAR; PG8_SCHED;
;             PG8_STAGE(PG8_SB(1, 1), b3 + hstepB, voffB);
;             PG8_WAIT_V(6); PG8_BAR; PG8_MMA(1, 1, At, B1); PG8_BAR;
;         }
;         { int frr = fr, fqq = fq; asm volatile("" : "+v"(frr), "+v"(fqq)); E(acc, cur, wr, wc, frr, fqq); }
	s_setprio 1
	v_mfma_f32_16x16x32_bf16 v[56:59], v[214:217], v[96:99], v[56:59]
	v_mfma_f32_16x16x32_bf16 v[52:55], v[222:225], v[96:99], v[52:55]
	ds_read_b128 v[80:83], v189
	v_mfma_f32_16x16x32_bf16 v[44:47], v[214:217], v[108:111], v[44:47]
	v_mfma_f32_16x16x32_bf16 v[36:39], v[222:225], v[108:111], v[36:39]
	ds_read_b128 v[84:87], v189 offset:1024
	v_mfma_f32_16x16x32_bf16 v[28:31], v[214:217], v[160:163], v[28:31]
	v_mfma_f32_16x16x32_bf16 v[20:23], v[222:225], v[160:163], v[20:23]
	ds_read_b128 v[88:91], v189 offset:2048
	v_mfma_f32_16x16x32_bf16 v[4:7], v[214:217], v[198:201], v[4:7]
	v_mfma_f32_16x16x32_bf16 v[0:3], v[222:225], v[198:201], v[0:3]
	ds_read_b128 v[92:95], v189 offset:3072
	v_mfma_f32_16x16x32_bf16 v[56:59], v[218:221], v[100:103], v[56:59]
	v_mfma_f32_16x16x32_bf16 v[52:55], v[226:229], v[100:103], v[52:55]
	v_mfma_f32_16x16x32_bf16 v[44:47], v[218:221], v[112:115], v[44:47]
	v_mfma_f32_16x16x32_bf16 v[36:39], v[226:229], v[112:115], v[36:39]
	v_mfma_f32_16x16x32_bf16 v[28:31], v[218:221], v[164:167], v[28:31]
	v_mfma_f32_16x16x32_bf16 v[20:23], v[226:229], v[164:167], v[20:23]
	v_mfma_f32_16x16x32_bf16 v[4:7], v[218:221], v[202:205], v[4:7]
	v_mfma_f32_16x16x32_bf16 v[0:3], v[226:229], v[202:205], v[0:3]
	s_setprio 0
	s_add_i32 s3, s3, 2
	s_add_u32 vcc_lo, vcc_lo, 0x100
	s_addc_u32 vcc_hi, vcc_hi, 0
	s_add_u32 s42, s42, 0x100
	s_addc_u32 s43, s43, 0
	s_cmp_gt_u32 s3, 29
	s_barrier
	s_cbranch_scc0 .LBB1_2483
	s_waitcnt lgkmcnt(0)
	s_lshl_b32 s21, s45, 7
	v_mov_b32_e32 v80, v187
	v_mov_b32_e32 v194, v186
	s_or_b32 s21, s21, s57
	v_mov_b32_e32 v160, 0
	v_lshl_add_u32 v184, v80, 3, s21
	v_ashrrev_i32_e32 v185, 31, v184
	v_lshlrev_b64 v[80:81], 2, v[184:185]
	v_lshl_add_u64 v[84:85], s[4:5], 0, v[80:81]
	v_lshl_add_u64 v[88:89], s[16:17], 0, v[80:81]
	v_lshl_add_u64 v[92:93], s[18:19], 0, v[80:81]
	v_lshl_add_u64 v[112:113], s[6:7], 0, v[80:81]
	global_load_dwordx4 v[80:83], v[84:85], off offset:16
	global_load_dwordx4 v[96:99], v[84:85], off
	s_nop 0
	global_load_dwordx4 v[84:87], v[88:89], off offset:16
	global_load_dwordx4 v[100:103], v[88:89], off
	s_nop 0
	global_load_dwordx4 v[88:91], v[92:93], off offset:16
	global_load_dwordx4 v[108:111], v[92:93], off
	s_nop 0
	global_load_dwordx4 v[92:95], v[112:113], off offset:16
	s_nop 0
	global_load_dwordx4 v[112:115], v[112:113], off
	v_cmp_eq_u32_e32 vcc, 0, v194
	v_mov_b32_e32 v164, 0
	v_mov_b32_e32 v195, 0
	v_cndmask_b32_e32 v161, v148, v136, vcc
	v_cndmask_b32_e32 v162, v149, v137, vcc
	v_cndmask_b32_e32 v163, v150, v138, vcc
	v_mov_b32_dpp v160, v161 row_ror:15 row_mask:0xf bank_mask:0xf
	v_mov_b32_e32 v161, 0
	v_mov_b32_e32 v166, 0
	v_mov_b32_e32 v167, 0
	v_mov_b32_dpp v161, v162 row_ror:15 row_mask:0xf bank_mask:0xf
	v_mov_b32_e32 v162, 0
	v_mov_b32_dpp v164, v150 row_ror:1 row_mask:0xf bank_mask:0xf
	v_cndmask_b32_e32 v165, v151, v139, vcc
	v_mov_b32_dpp v162, v163 row_ror:15 row_mask:0xf bank_mask:0xf
	v_mov_b32_dpp v195, v151 row_ror:1 row_mask:0xf bank_mask:0xf
	v_mov_b32_e32 v163, 0
	v_mov_b32_dpp v166, v148 row_ror:1 row_mask:0xf bank_mask:0xf
	v_mov_b32_dpp v167, v149 row_ror:1 row_mask:0xf bank_mask:0xf
	v_mov_b32_dpp v163, v165 row_ror:15 row_mask:0xf bank_mask:0xf
	v_cndmask_b32_e64 v165, v195, 0, vcc
	v_cndmask_b32_e64 v164, v164, 0, vcc
	v_cndmask_b32_e64 v167, v167, 0, vcc
	v_cndmask_b32_e64 v166, v166, 0, vcc
	v_mov_b32_e32 v195, 0
	v_mov_b32_e32 v196, 0
	v_mov_b32_e32 v198, 0
	v_mov_b32_e32 v200, 0
	v_mov_b32_dpp v195, v144 row_ror:1 row_mask:0xf bank_mask:0xf
	v_mov_b32_dpp v196, v145 row_ror:1 row_mask:0xf bank_mask:0xf
	v_mov_b32_dpp v198, v146 row_ror:1 row_mask:0xf bank_mask:0xf
	v_cndmask_b32_e32 v199, v147, v131, vcc
	v_mov_b32_dpp v200, v147 row_ror:1 row_mask:0xf bank_mask:0xf
	v_cndmask_b32_e64 v198, v198, 0, vcc
	v_cndmask_b32_e64 v201, v196, 0, vcc
	s_lshl_b32 s3, s44, 8
	s_add_i32 s3, s3, s49
	v_add_u32_e32 v193, s3, v194
	v_cmp_ne_u32_e64 s[46:47], 0, v194
	s_waitcnt vmcnt(0)
	v_pk_mul_f32 v[164:165], v[98:99], v[164:165]
	v_pk_mul_f32 v[166:167], v[96:97], v[166:167]
	v_pk_fma_f32 v[164:165], v[150:151], v[102:103], v[164:165]
	v_pk_fma_f32 v[166:167], v[148:149], v[100:101], v[166:167]
	v_pk_fma_f32 v[162:163], v[110:111], v[162:163], v[164:165]
	v_cndmask_b32_e32 v165, v144, v128, vcc
	v_mov_b32_e32 v164, 0
	v_pk_fma_f32 v[160:161], v[108:109], v[160:161], v[166:167]
	v_cndmask_b32_e32 v166, v145, v129, vcc
	v_mov_b32_dpp v164, v165 row_ror:15 row_mask:0xf bank_mask:0xf
	v_mov_b32_e32 v165, 0
	v_cndmask_b32_e32 v167, v146, v130, vcc
	v_pk_add_f32 v[162:163], v[114:115], v[162:163]
	v_mov_b32_dpp v165, v166 row_ror:15 row_mask:0xf bank_mask:0xf
	v_mov_b32_e32 v166, 0
	v_pk_add_f32 v[160:161], v[112:113], v[160:161]
	s_nop 0
	v_mov_b32_dpp v166, v167 row_ror:15 row_mask:0xf bank_mask:0xf
	v_mov_b32_e32 v167, 0
	s_nop 1
	v_mov_b32_dpp v167, v199 row_ror:15 row_mask:0xf bank_mask:0xf
	v_cndmask_b32_e64 v199, v200, 0, vcc
	v_cndmask_b32_e64 v200, v195, 0, vcc
	v_pk_mul_f32 v[200:201], v[80:81], v[200:201]
	v_pk_mul_f32 v[198:199], v[82:83], v[198:199]
	v_pk_fma_f32 v[200:201], v[144:145], v[84:85], v[200:201]
	v_pk_fma_f32 v[198:199], v[146:147], v[86:87], v[198:199]
	v_pk_fma_f32 v[164:165], v[88:89], v[164:165], v[200:201]
	v_pk_fma_f32 v[166:167], v[90:91], v[166:167], v[198:199]
	v_pk_add_f32 v[164:165], v[92:93], v[164:165]
	v_pk_add_f32 v[166:167], v[94:95], v[166:167]
	s_and_saveexec_b64 s[28:29], s[46:47]
	s_xor_b64 s[28:29], exec, s[28:29]
	s_cbranch_execz .LBB1_2486
; DI unsigned pack2(float a, float b) { f32x2 v = {a, b}; hwbf16x2 r = __builtin_convertvector(v, hwbf16x2); return __builtin_bit_cast(unsigned, r); }
; DI float silu_mul(float g, float v) { return g * v * __builtin_amdgcn_rcpf(1.0f + __builtin_amdgcn_exp2f(-LOG2E * g)); }
;     DI void operator()(const f32x4 (&acc)[2][2][4][2], const Unit& u, int wr, int wc, int fr, int fq) const {
;     ...
;                 } else {
;                     const f32x4 v0 = acc[ai][1][m][0], v1 = acc[ai][1][m][1];
;                     u32x4 o;
;                     o[0] = pack2(silu_mul(gc[0][0], v0[0]), silu_mul(gc[0][1], v0[1])); o[1] = pack2(silu_mul(gc[0][2], v0[2]), silu_mul(gc[0][3], v0[3]));
;                     o[2] = pack2(silu_mul(gc[1][0], v1[0]), silu_mul(gc[1][1], v1[1])); o[3] = pack2(silu_mul(gc[1][2], v1[2]), silu_mul(gc[1][3], v1[3]));
;                     *(u32x4*)(ACT + (size_t)row * DFF + ch0) = o;
;                 }
	v_mul_f32_e32 v195, 0xbfb8aa3b, v160
	v_exp_f32_e32 v195, v195
	v_mul_f32_e32 v196, 0xbfb8aa3b, v161
	v_exp_f32_e32 v196, v196
	v_pk_mul_f32 v[160:161], v[156:157], v[160:161]
	v_add_f32_e32 v195, 1.0, v195
	v_rcp_f32_e32 v198, v195
	v_add_f32_e32 v196, 1.0, v196
	v_mul_f32_e32 v195, 0xbfb8aa3b, v162
	v_rcp_f32_e32 v199, v196
	v_exp_f32_e32 v195, v195
	v_mul_f32_e32 v196, 0xbfb8aa3b, v163
	v_exp_f32_e32 v196, v196
	v_pk_mul_f32 v[160:161], v[160:161], v[198:199]
	v_add_f32_e32 v195, 1.0, v195
	v_rcp_f32_e32 v200, v195
	v_add_f32_e32 v195, 1.0, v196
	v_rcp_f32_e32 v201, v195
	v_cvt_pk_bf16_f32 v160, v160, v161
	v_mul_f32_e32 v161, 0xbfb8aa3b, v164
	v_exp_f32_e32 v195, v161
	v_mul_f32_e32 v161, 0xbfb8aa3b, v165
	v_exp_f32_e32 v196, v161
	v_pk_mul_f32 v[162:163], v[158:159], v[162:163]
	v_pk_mul_f32 v[164:165], v[152:153], v[164:165]
	v_pk_mul_f32 v[162:163], v[162:163], v[200:201]
	s_nop 0
	v_cvt_pk_bf16_f32 v161, v162, v163
	v_add_f32_e32 v162, 1.0, v195
	v_mul_f32_e32 v195, 0xbfb8aa3b, v166
	v_add_f32_e32 v163, 1.0, v196
	v_exp_f32_e32 v195, v195
	v_mul_f32_e32 v196, 0xbfb8aa3b, v167
	v_exp_f32_e32 v196, v196
	v_rcp_f32_e32 v162, v162
	v_add_f32_e32 v195, 1.0, v195
	v_rcp_f32_e32 v198, v195
	v_add_f32_e32 v195, 1.0, v196
	v_rcp_f32_e32 v163, v163
	v_rcp_f32_e32 v199, v195
	v_pk_mul_f32 v[166:167], v[154:155], v[166:167]
	v_pk_mul_f32 v[162:163], v[164:165], v[162:163]
	v_pk_mul_f32 v[164:165], v[166:167], v[198:199]
	v_cvt_pk_bf16_f32 v162, v162, v163
	v_cvt_pk_bf16_f32 v163, v164, v165
	v_mov_b64_e32 v[164:165], s[52:53]
	v_mad_i64_i32 v[164:165], s[42:43], v193, s60, v[164:165]
	v_lshl_add_u64 v[164:165], v[184:185], 1, v[164:165]
	global_store_dwordx4 v[164:165], v[160:163], off

;     DI const char* a(const Unit& u) const { return (const char*)(A + (size_t)u.pm * BM * lda); }
;     DI const char* a(const Unit& u) const { return (const char*)(A + (size_t)u.pm * BM * 2048 + (u.pn >> 1) * 512); }
;     DI const char* a(const Unit& u) const { return (const char*)((u.pn < 12 ? A1 : A2) + (size_t)u.pm * BM * 512); }
; #define PG8_STAGE(bufoff, gbase, voff) do { _Pragma("unroll") for (int _i = 0; _i < 2; ++_i) \
;         __builtin_amdgcn_global_load_lds((const unsigned*)((const char*)(gbase) + (voff)[_i]), (LAS unsigned*)(lds + (bufoff) + ldsw + _i * 8192), 16, 0, 0); } while (0)
; #define PG8_LDA(dst, b, h) do { _Pragma("unroll") for (int m = 0; m < 4; ++m) _Pragma("unroll") for (int k = 0; k < 2; ++k) dst[m][k] = *(const LAS bf16x8*)(lds + PG8_SA(b, h) + aoff + m * 2048 + k * 1024); } while (0)
; #define PG8_LDB(dst, b, h) do { _Pragma("unroll") for (int n = 0; n < 2; ++n) _Pragma("unroll") for (int k = 0; k < 2; ++k) dst[n][k] = *(const LAS bf16x8*)(lds + PG8_SB(b, h) + boff + n * 2048 + k * 1024); } while (0)
; template <class Map, class Epi>
; DI void gemm_phase(LAS unsigned char* lds, const Map& MP, const Epi& E, const int nM, const int nN, const int K, const int lda, const int ldb) {
;     ...
;         const bool has_next = sched_next(ui + 1, nM, nN, G, cblk, nxt);
;         const char* nA = has_next ? MP.a(nxt) : cA; const char* nB = has_next ? MP.b(nxt) : cB;
;         for (int t = 0; t < nt; t += 2) {
;             const bool last = (t == nt - 2);
;             const char* a1 = cA + (size_t)(t + 1) * kstep;
;             const char* a2 = last ? nA : cA + (size_t)(t + 2) * kstep; const char* b2 = last ? nB : cB + (size_t)(t + 2) * kstep;
;             const char* a3 = a2 + kstep; const char* b3 = b2 + kstep;
;             PG8_LDB(B0, 0, 0); PG8_SCHED; PG8_LDA(At, 0, 0); PG8_STAGE(PG8_SA(1, 1), a1 + hstepA, voffA);
;             PG8_WAIT_L(8); PG8_BAR; PG8_WAIT_L(0); PG8_MMA(0, 0, At, B0); PG8_BAR; PG8_SCHED;
;             PG8_LDB(B1, 0, 1); PG8_STAGE(PG8_SB(0, 0), b2, voffB);
;     ...
; #pragma unroll
;         for (int a = 0; a < 2; ++a)
; #pragma unroll
;             for (int b = 0; b < 2; ++b)
; #pragma unroll
;                 for (int m = 0; m < 4; ++m)
; #pragma unroll
;                     for (int n = 0; n < 2; ++n) acc[a][b][m][n] = (f32x4){0.f, 0.f, 0.f, 0.f};
;         cur = nxt; cA = nA; cB = nB; ++ui;
.LBB1_2652:
	s_add_u32 s38, s10, 0x100
	v_mov_b32_e32 v0, 0
	s_addc_u32 s39, s11, 0
	s_mov_b32 s48, -2
	v_mov_b32_e32 v1, v0
	v_mov_b32_e32 v2, v0
	v_mov_b32_e32 v3, v0
	v_mov_b32_e32 v4, v0
	v_mov_b32_e32 v5, v0
	v_mov_b32_e32 v6, v0
	v_mov_b32_e32 v7, v0
	v_mov_b32_e32 v16, v0
	v_mov_b32_e32 v17, v0
	v_mov_b32_e32 v18, v0
	v_mov_b32_e32 v19, v0
	v_mov_b32_e32 v20, v0
	v_mov_b32_e32 v21, v0
	v_mov_b32_e32 v22, v0
	v_mov_b32_e32 v23, v0
	v_mov_b32_e32 v32, v0
	v_mov_b32_e32 v33, v0
	v_mov_b32_e32 v34, v0
	v_mov_b32_e32 v35, v0
	v_mov_b32_e32 v36, v0
	v_mov_b32_e32 v37, v0
	v_mov_b32_e32 v38, v0
	v_mov_b32_e32 v39, v0
	v_mov_b32_e32 v48, v0
	v_mov_b32_e32 v49, v0
	v_mov_b32_e32 v50, v0
	v_mov_b32_e32 v51, v0
	v_mov_b32_e32 v52, v0
	v_mov_b32_e32 v53, v0
	v_mov_b32_e32 v54, v0
	v_mov_b32_e32 v55, v0
	v_mov_b32_e32 v8, v0
	v_mov_b32_e32 v9, v0
	v_mov_b32_e32 v10, v0
	v_mov_b32_e32 v11, v0
	v_mov_b32_e32 v12, v0
	v_mov_b32_e32 v13, v0
	v_mov_b32_e32 v14, v0
	v_mov_b32_e32 v15, v0
	v_mov_b32_e32 v24, v0
	v_mov_b32_e32 v25, v0
	v_mov_b32_e32 v26, v0
	v_mov_b32_e32 v27, v0
	v_mov_b32_e32 v28, v0
	v_mov_b32_e32 v29, v0
	v_mov_b32_e32 v30, v0
	v_mov_b32_e32 v31, v0
	v_mov_b32_e32 v40, v0
	v_mov_b32_e32 v41, v0
	v_mov_b32_e32 v42, v0
	v_mov_b32_e32 v43, v0
	v_mov_b32_e32 v44, v0
	v_mov_b32_e32 v45, v0
	v_mov_b32_e32 v46, v0
	v_mov_b32_e32 v47, v0
	v_mov_b32_e32 v56, v0
	v_mov_b32_e32 v57, v0
	v_mov_b32_e32 v58, v0
	v_mov_b32_e32 v59, v0
	v_mov_b32_e32 v60, v0
	v_mov_b32_e32 v61, v0
	v_mov_b32_e32 v62, v0
	v_mov_b32_e32 v63, v0
	v_mov_b32_e32 v64, v0
	v_mov_b32_e32 v65, v0
	v_mov_b32_e32 v66, v0
	v_mov_b32_e32 v67, v0
	v_mov_b32_e32 v68, v0
	v_mov_b32_e32 v69, v0
	v_mov_b32_e32 v70, v0
	v_mov_b32_e32 v71, v0
	v_mov_b32_e32 v80, v0
	v_mov_b32_e32 v81, v0
	v_mov_b32_e32 v82, v0
	v_mov_b32_e32 v83, v0
	v_mov_b32_e32 v84, v0
	v_mov_b32_e32 v85, v0
	v_mov_b32_e32 v86, v0
	v_mov_b32_e32 v87, v0
	v_mov_b32_e32 v96, v0
	v_mov_b32_e32 v97, v0
	v_mov_b32_e32 v98, v0
	v_mov_b32_e32 v99, v0
	v_mov_b32_e32 v100, v0
	v_mov_b32_e32 v101, v0
	v_mov_b32_e32 v102, v0
	v_mov_b32_e32 v103, v0
	v_mov_b32_e32 v112, v0
	v_mov_b32_e32 v113, v0
	v_mov_b32_e32 v114, v0
	v_mov_b32_e32 v115, v0
	v_mov_b32_e32 v116, v0
	v_mov_b32_e32 v117, v0
	v_mov_b32_e32 v118, v0
	v_mov_b32_e32 v119, v0
	v_mov_b32_e32 v72, v0
	v_mov_b32_e32 v73, v0
	v_mov_b32_e32 v74, v0
	v_mov_b32_e32 v75, v0
	v_mov_b32_e32 v76, v0
	v_mov_b32_e32 v77, v0
	v_mov_b32_e32 v78, v0
	v_mov_b32_e32 v79, v0
	v_mov_b32_e32 v88, v0
	v_mov_b32_e32 v89, v0
	v_mov_b32_e32 v90, v0
	v_mov_b32_e32 v91, v0
	v_mov_b32_e32 v92, v0
	v_mov_b32_e32 v93, v0
	v_mov_b32_e32 v94, v0
	v_mov_b32_e32 v95, v0
	v_mov_b32_e32 v104, v0
	v_mov_b32_e32 v105, v0
	v_mov_b32_e32 v106, v0
	v_mov_b32_e32 v107, v0
	v_mov_b32_e32 v108, v0
	v_mov_b32_e32 v109, v0
	v_mov_b32_e32 v110, v0
	v_mov_b32_e32 v111, v0
	v_mov_b32_e32 v120, v0
	v_mov_b32_e32 v121, v0
	v_mov_b32_e32 v122, v0
	v_mov_b32_e32 v123, v0
	v_mov_b32_e32 v124, v0
	v_mov_b32_e32 v125, v0
	v_mov_b32_e32 v126, v0
	v_mov_b32_e32 v127, v0
	ds_read_b128 v[152:155], v149
	ds_read_b128 v[156:159], v149 offset:1024
	ds_read_b128 v[160:163], v149 offset:2048
	ds_read_b128 v[164:167], v149 offset:3072
.LBB1_2653:
	s_add_u32 s10, s8, 0x100
	s_addc_u32 s11, s9, 0
	s_cmpk_eq_i32 s48, 0x54
	s_cselect_b32 s15, s43, s11
	s_cselect_b32 s14, s42, s10
	s_cselect_b32 s13, s45, s39
	s_cselect_b32 s12, s44, s38
	s_add_i32 m0, s22, 0xc000
	ds_read_b128 v[168:171], v150
	ds_read_b128 v[172:175], v150 offset:1024
	ds_read_b128 v[176:179], v150 offset:2048
	ds_read_b128 v[180:183], v150 offset:3072
	ds_read_b128 v[184:187], v150 offset:4096
	ds_read_b128 v[188:191], v150 offset:5120
	ds_read_b128 v[192:195], v150 offset:6144
	ds_read_b128 v[196:199], v150 offset:7168
	global_load_lds_dwordx4 v138, s[8:9]
	s_add_i32 m0, s22, 0xe000
	s_nop 0
	global_load_lds_dwordx4 v136, s[8:9]
	s_waitcnt lgkmcnt(8)
	s_barrier
	s_setprio 1
	s_waitcnt lgkmcnt(7)
	v_mfma_f32_16x16x32_bf16 v[124:127], v[152:155], v[168:171], v[124:127]
	v_mfma_f32_16x16x32_bf16 v[120:123], v[160:163], v[168:171], v[120:123]
	s_waitcnt lgkmcnt(5)
	v_mfma_f32_16x16x32_bf16 v[108:111], v[152:155], v[176:179], v[108:111]
	v_mfma_f32_16x16x32_bf16 v[104:107], v[160:163], v[176:179], v[104:107]
	s_waitcnt lgkmcnt(3)
	v_mfma_f32_16x16x32_bf16 v[92:95], v[152:155], v[184:187], v[92:95]
	v_mfma_f32_16x16x32_bf16 v[88:91], v[160:163], v[184:187], v[88:91]
	s_waitcnt lgkmcnt(1)
	v_mfma_f32_16x16x32_bf16 v[76:79], v[152:155], v[192:195], v[76:79]
	v_mfma_f32_16x16x32_bf16 v[72:75], v[160:163], v[192:195], v[72:75]
	v_mfma_f32_16x16x32_bf16 v[124:127], v[156:159], v[172:175], v[124:127]
	v_mfma_f32_16x16x32_bf16 v[120:123], v[164:167], v[172:175], v[120:123]
	v_mfma_f32_16x16x32_bf16 v[108:111], v[156:159], v[180:183], v[108:111]
	v_mfma_f32_16x16x32_bf16 v[104:107], v[164:167], v[180:183], v[104:107]
	v_mfma_f32_16x16x32_bf16 v[92:95], v[156:159], v[188:191], v[92:95]
	v_mfma_f32_16x16x32_bf16 v[88:91], v[164:167], v[188:191], v[88:91]
	s_waitcnt lgkmcnt(0)
	v_mfma_f32_16x16x32_bf16 v[76:79], v[156:159], v[196:199], v[76:79]
	v_mfma_f32_16x16x32_bf16 v[72:75], v[164:167], v[196:199], v[72:75]
	s_setprio 0
	s_barrier
	s_add_i32 s8, s33, s20
	v_lshl_add_u64 v[144:145], s[12:13], 0, v[132:133]
	s_mov_b32 m0, s8
	ds_read_b128 v[200:203], v151
	ds_read_b128 v[204:207], v151 offset:1024
	ds_read_b128 v[208:211], v151 offset:2048
	ds_read_b128 v[212:215], v151 offset:3072
	global_load_lds_dwordx4 v[144:145], off
	v_lshl_add_u64 v[216:217], s[12:13], 0, v[128:129]
	s_add_i32 m0, s8, 0x2000
	s_nop 0
	global_load_lds_dwordx4 v[216:217], off
	s_barrier
; #define PG8_STAGE(bufoff, gbase, voff) do { _Pragma("unroll") for (int _i = 0; _i < 2; ++_i) \
;         __builtin_amdgcn_global_load_lds((const unsigned*)((const char*)(gbase) + (voff)[_i]), (LAS unsigned*)(lds + (bufoff) + ldsw + _i * 8192), 16, 0, 0); } while (0)
; #define PG8_LDA(dst, b, h) do { _Pragma("unroll") for (int m = 0; m < 4; ++m) _Pragma("unroll") for (int k = 0; k < 2; ++k) dst[m][k] = *(const LAS bf16x8*)(lds + PG8_SA(b, h) + aoff + m * 2048 + k * 1024); } while (0)
; #define PG8_LDB(dst, b, h) do { _Pragma("unroll") for (int n = 0; n < 2; ++n) _Pragma("unroll") for (int k = 0; k < 2; ++k) dst[n][k] = *(const LAS bf16x8*)(lds + PG8_SB(b, h) + boff + n * 2048 + k * 1024); } while (0)
; #define PG8_MMA(ai, bj, At, Bt) do { __builtin_amdgcn_s_setprio(1); _Pragma("unroll") for (int m = 0; m < 4; ++m) _Pragma("unroll") for (int n = 0; n < 2; ++n) _Pragma("unroll") for (int k = 0; k < 2; ++k) \
;         acc[ai][bj][m][n] = __builtin_amdgcn_mfma_f32_16x16x32_bf16(Bt[n][k], At[m][k], acc[ai][bj][m][n], 0, 0, 0); __builtin_amdgcn_s_setprio(0); } while (0)
; #define PG8_WAIT_V(n) asm volatile("s_waitcnt vmcnt(" #n ")" ::: "memory")
; #define PG8_WAIT_L(n) asm volatile("s_waitcnt lgkmcnt(" #n ")" ::: "memory")
; #define PG8_BAR __builtin_amdgcn_s_barrier()
; #define PG8_SCHED __builtin_amdgcn_sched_barrier(0)
; template <class Map, class Epi>
; DI void gemm_phase(LAS unsigned char* lds, const Map& MP, const Epi& E, const int nM, const int nN, const int K, const int lda, const int ldb) {
;     ...
;             PG8_LDB(B1, 0, 1); PG8_STAGE(PG8_SB(0, 0), b2, voffB);
;             PG8_BAR; PG8_WAIT_L(0); PG8_MMA(0, 1, At, B1); PG8_BAR;
;             PG8_LDA(At, 0, 1); PG8_STAGE(PG8_SA(0, 0), a2, voffA);
;             PG8_BAR; PG8_WAIT_L(0); PG8_MMA(1, 0, At, B0); PG8_BAR; PG8_SCHED;
;             PG8_STAGE(PG8_SB(0, 1), b2 + hstepB, voffB);
;             PG8_WAIT_V(6); PG8_BAR; PG8_MMA(1, 1, At, B1); PG8_BAR;
;             PG8_LDB(B0, 1, 0); PG8_SCHED; PG8_LDA(At, 1, 0); PG8_STAGE(PG8_SA(0, 1), a2 + hstepA, voffA);
;             PG8_WAIT_L(8); PG8_BAR; PG8_WAIT_L(0); PG8_MMA(0, 0, At, B0); PG8_BAR; PG8_SCHED;
	s_setprio 1
	s_waitcnt lgkmcnt(3)
	v_mfma_f32_16x16x32_bf16 v[116:119], v[200:203], v[168:171], v[116:119]
	s_waitcnt lgkmcnt(1)
	v_mfma_f32_16x16x32_bf16 v[112:115], v[208:211], v[168:171], v[112:115]
	v_mfma_f32_16x16x32_bf16 v[100:103], v[200:203], v[176:179], v[100:103]
	v_mfma_f32_16x16x32_bf16 v[96:99], v[208:211], v[176:179], v[96:99]
	v_mfma_f32_16x16x32_bf16 v[84:87], v[200:203], v[184:187], v[84:87]
	v_mfma_f32_16x16x32_bf16 v[80:83], v[208:211], v[184:187], v[80:83]
	v_mfma_f32_16x16x32_bf16 v[68:71], v[200:203], v[192:195], v[68:71]
	v_mfma_f32_16x16x32_bf16 v[64:67], v[208:211], v[192:195], v[64:67]
	v_mfma_f32_16x16x32_bf16 v[116:119], v[204:207], v[172:175], v[116:119]
	s_waitcnt lgkmcnt(0)
	v_mfma_f32_16x16x32_bf16 v[112:115], v[212:215], v[172:175], v[112:115]
	v_mfma_f32_16x16x32_bf16 v[100:103], v[204:207], v[180:183], v[100:103]
	v_mfma_f32_16x16x32_bf16 v[96:99], v[212:215], v[180:183], v[96:99]
	v_mfma_f32_16x16x32_bf16 v[84:87], v[204:207], v[188:191], v[84:87]
	v_mfma_f32_16x16x32_bf16 v[80:83], v[212:215], v[188:191], v[80:83]
	v_mfma_f32_16x16x32_bf16 v[68:71], v[204:207], v[196:199], v[68:71]
	v_mfma_f32_16x16x32_bf16 v[64:67], v[212:215], v[196:199], v[64:67]
	s_setprio 0
	s_mov_b32 m0, s22
	v_lshl_add_u64 v[218:219], s[14:15], 0, v[134:135]
	s_barrier
	ds_read_b128 v[168:171], v150 offset:16384
	ds_read_b128 v[172:175], v150 offset:17408
	ds_read_b128 v[176:179], v150 offset:18432
	ds_read_b128 v[180:183], v150 offset:19456
	ds_read_b128 v[184:187], v150 offset:20480
	ds_read_b128 v[188:191], v150 offset:21504
	ds_read_b128 v[192:195], v150 offset:22528
	ds_read_b128 v[196:199], v150 offset:23552
	global_load_lds_dwordx4 v[218:219], off
	v_lshl_add_u64 v[220:221], s[14:15], 0, v[130:131]
	s_mov_b32 m0, s23
	s_nop 0
	global_load_lds_dwordx4 v[220:221], off
	s_waitcnt vmcnt(10)
	s_barrier
	s_setprio 1
	s_waitcnt lgkmcnt(7)
	v_mfma_f32_16x16x32_bf16 v[60:63], v[152:155], v[168:171], v[60:63]
	v_mfma_f32_16x16x32_bf16 v[56:59], v[160:163], v[168:171], v[56:59]
	s_waitcnt lgkmcnt(5)
	v_mfma_f32_16x16x32_bf16 v[44:47], v[152:155], v[176:179], v[44:47]
	v_mfma_f32_16x16x32_bf16 v[40:43], v[160:163], v[176:179], v[40:43]
	s_waitcnt lgkmcnt(3)
	v_mfma_f32_16x16x32_bf16 v[28:31], v[152:155], v[184:187], v[28:31]
	v_mfma_f32_16x16x32_bf16 v[24:27], v[160:163], v[184:187], v[24:27]
	s_waitcnt lgkmcnt(1)
	v_mfma_f32_16x16x32_bf16 v[12:15], v[152:155], v[192:195], v[12:15]
	v_mfma_f32_16x16x32_bf16 v[8:11], v[160:163], v[192:195], v[8:11]
	v_mfma_f32_16x16x32_bf16 v[60:63], v[156:159], v[172:175], v[60:63]
	v_mfma_f32_16x16x32_bf16 v[56:59], v[164:167], v[172:175], v[56:59]
	v_mfma_f32_16x16x32_bf16 v[44:47], v[156:159], v[180:183], v[44:47]
	v_mfma_f32_16x16x32_bf16 v[40:43], v[164:167], v[180:183], v[40:43]
	v_mfma_f32_16x16x32_bf16 v[28:31], v[156:159], v[188:191], v[28:31]
	v_mfma_f32_16x16x32_bf16 v[24:27], v[164:167], v[188:191], v[24:27]
	s_waitcnt lgkmcnt(0)
	v_mfma_f32_16x16x32_bf16 v[12:15], v[156:159], v[196:199], v[12:15]
	v_mfma_f32_16x16x32_bf16 v[8:11], v[164:167], v[196:199], v[8:11]
	s_setprio 0
	s_barrier
	s_add_u32 s8, s12, 0x160000
	s_addc_u32 s9, s13, 0
	s_add_i32 s49, s34, s20
	s_mov_b32 m0, s49
	s_nop 0
	global_load_lds_dwordx4 v132, s[8:9]
	s_add_i32 m0, s49, 0x2000
	s_nop 0
	global_load_lds_dwordx4 v128, s[8:9]
	s_waitcnt vmcnt(6)
	s_barrier
	s_setprio 1
	v_mfma_f32_16x16x32_bf16 v[52:55], v[200:203], v[168:171], v[52:55]
	v_mfma_f32_16x16x32_bf16 v[48:51], v[208:211], v[168:171], v[48:51]
	s_add_i32 s49, 0, 0x18000
	v_add_u32_e32 v164, s49, v148
	ds_read_b128 v[152:155], v164
	v_mfma_f32_16x16x32_bf16 v[36:39], v[200:203], v[176:179], v[36:39]
	v_mfma_f32_16x16x32_bf16 v[32:35], v[208:211], v[176:179], v[32:35]
	ds_read_b128 v[156:159], v164 offset:1024
	v_mfma_f32_16x16x32_bf16 v[20:23], v[200:203], v[184:187], v[20:23]
	v_mfma_f32_16x16x32_bf16 v[16:19], v[208:211], v[184:187], v[16:19]
	ds_read_b128 v[160:163], v164 offset:2048
	v_mfma_f32_16x16x32_bf16 v[4:7], v[200:203], v[192:195], v[4:7]
	v_mfma_f32_16x16x32_bf16 v[0:3], v[208:211], v[192:195], v[0:3]
	ds_read_b128 v[164:167], v164 offset:3072
	v_mfma_f32_16x16x32_bf16 v[52:55], v[204:207], v[172:175], v[52:55]
	v_mfma_f32_16x16x32_bf16 v[48:51], v[212:215], v[172:175], v[48:51]
	v_mfma_f32_16x16x32_bf16 v[36:39], v[204:207], v[180:183], v[36:39]
	v_mfma_f32_16x16x32_bf16 v[32:35], v[212:215], v[180:183], v[32:35]
	v_mfma_f32_16x16x32_bf16 v[20:23], v[204:207], v[188:191], v[20:23]
	v_mfma_f32_16x16x32_bf16 v[16:19], v[212:215], v[188:191], v[16:19]
	v_mfma_f32_16x16x32_bf16 v[4:7], v[204:207], v[196:199], v[4:7]
	v_mfma_f32_16x16x32_bf16 v[0:3], v[212:215], v[196:199], v[0:3]
	s_setprio 0
	s_barrier
	s_add_u32 s8, s14, 0x160000
	s_addc_u32 s9, s15, 0
	s_mov_b32 m0, s24
	ds_read_b128 v[168:171], v150 offset:32768
	ds_read_b128 v[172:175], v150 offset:33792
	ds_read_b128 v[176:179], v150 offset:34816
	ds_read_b128 v[180:183], v150 offset:35840
	ds_read_b128 v[184:187], v150 offset:36864
	ds_read_b128 v[188:191], v150 offset:37888
	ds_read_b128 v[192:195], v150 offset:38912
	ds_read_b128 v[196:199], v150 offset:39936
	global_load_lds_dwordx4 v134, s[8:9]
	s_mov_b32 m0, s25
	s_nop 0
	global_load_lds_dwordx4 v130, s[8:9]
	s_waitcnt lgkmcnt(8)
	s_barrier
; #define PG8_STAGE(bufoff, gbase, voff) do { _Pragma("unroll") for (int _i = 0; _i < 2; ++_i) \
;         __builtin_amdgcn_global_load_lds((const unsigned*)((const char*)(gbase) + (voff)[_i]), (LAS unsigned*)(lds + (bufoff) + ldsw + _i * 8192), 16, 0, 0); } while (0)
; #define PG8_LDA(dst, b, h) do { _Pragma("unroll") for (int m = 0; m < 4; ++m) _Pragma("unroll") for (int k = 0; k < 2; ++k) dst[m][k] = *(const LAS bf16x8*)(lds + PG8_SA(b, h) + aoff + m * 2048 + k * 1024); } while (0)
; #define PG8_LDB(dst, b, h) do { _Pragma("unroll") for (int n = 0; n < 2; ++n) _Pragma("unroll") for (int k = 0; k < 2; ++k) dst[n][k] = *(const LAS bf16x8*)(lds + PG8_SB(b, h) + boff + n * 2048 + k * 1024); } while (0)
; #define PG8_MMA(ai, bj, At, Bt) do { __builtin_amdgcn_s_setprio(1); _Pragma("unroll") for (int m = 0; m < 4; ++m) _Pragma("unroll") for (int n = 0; n < 2; ++n) _Pragma("unroll") for (int k = 0; k < 2; ++k) \
;         acc[ai][bj][m][n] = __builtin_amdgcn_mfma_f32_16x16x32_bf16(Bt[n][k], At[m][k], acc[ai][bj][m][n], 0, 0, 0); __builtin_amdgcn_s_setprio(0); } while (0)
; #define PG8_WAIT_V(n) asm volatile("s_waitcnt vmcnt(" #n ")" ::: "memory")
; #define PG8_WAIT_L(n) asm volatile("s_waitcnt lgkmcnt(" #n ")" ::: "memory")
; #define PG8_BAR __builtin_amdgcn_s_barrier()
; #define PG8_SCHED __builtin_amdgcn_sched_barrier(0)
; template <class Map, class Epi>
; DI void gemm_phase(LAS unsigned char* lds, const Map& MP, const Epi& E, const int nM, const int nN, const int K, const int lda, const int ldb) {
;     ...
;             PG8_LDB(B0, 1, 0); PG8_SCHED; PG8_LDA(At, 1, 0); PG8_STAGE(PG8_SA(0, 1), a2 + hstepA, voffA);
;             PG8_WAIT_L(8); PG8_BAR; PG8_WAIT_L(0); PG8_MMA(0, 0, At, B0); PG8_BAR; PG8_SCHED;
;             PG8_LDB(B1, 1, 1); PG8_STAGE(PG8_SB(1, 0), b3, voffB);
;             PG8_BAR; PG8_WAIT_L(0); PG8_MMA(0, 1, At, B1); PG8_BAR;
;             PG8_LDA(At, 1, 1); PG8_STAGE(PG8_SA(1, 0), a3, voffA);
;             PG8_BAR; PG8_WAIT_L(0); PG8_MMA(1, 0, At, B0); PG8_BAR; PG8_SCHED;
;             PG8_STAGE(PG8_SB(1, 1), b3 + hstepB, voffB);
;             PG8_WAIT_V(6); PG8_BAR; PG8_MMA(1, 1, At, B1); PG8_BAR;
	s_setprio 1
	s_waitcnt lgkmcnt(7)
	v_mfma_f32_16x16x32_bf16 v[124:127], v[152:155], v[168:171], v[124:127]
	v_mfma_f32_16x16x32_bf16 v[120:123], v[160:163], v[168:171], v[120:123]
	s_waitcnt lgkmcnt(5)
	v_mfma_f32_16x16x32_bf16 v[108:111], v[152:155], v[176:179], v[108:111]
	v_mfma_f32_16x16x32_bf16 v[104:107], v[160:163], v[176:179], v[104:107]
	s_waitcnt lgkmcnt(3)
	v_mfma_f32_16x16x32_bf16 v[92:95], v[152:155], v[184:187], v[92:95]
	v_mfma_f32_16x16x32_bf16 v[88:91], v[160:163], v[184:187], v[88:91]
	s_waitcnt lgkmcnt(1)
	v_mfma_f32_16x16x32_bf16 v[76:79], v[152:155], v[192:195], v[76:79]
	v_mfma_f32_16x16x32_bf16 v[72:75], v[160:163], v[192:195], v[72:75]
	v_mfma_f32_16x16x32_bf16 v[124:127], v[156:159], v[172:175], v[124:127]
	v_mfma_f32_16x16x32_bf16 v[120:123], v[164:167], v[172:175], v[120:123]
	v_mfma_f32_16x16x32_bf16 v[108:111], v[156:159], v[180:183], v[108:111]
	v_mfma_f32_16x16x32_bf16 v[104:107], v[164:167], v[180:183], v[104:107]
	v_mfma_f32_16x16x32_bf16 v[92:95], v[156:159], v[188:191], v[92:95]
	v_mfma_f32_16x16x32_bf16 v[88:91], v[164:167], v[188:191], v[88:91]
	s_waitcnt lgkmcnt(0)
	v_mfma_f32_16x16x32_bf16 v[76:79], v[156:159], v[196:199], v[76:79]
	v_mfma_f32_16x16x32_bf16 v[72:75], v[164:167], v[196:199], v[72:75]
	s_setprio 0
	s_barrier
	s_add_i32 s14, 0, 0x1c000
	s_add_i32 s8, s49, s20
	v_add_u32_e32 v212, s14, v148
	v_lshl_add_u64 v[144:145], v[144:145], 0, s[46:47]
	s_mov_b32 m0, s8
	ds_read_b128 v[200:203], v212
	ds_read_b128 v[204:207], v212 offset:1024
	ds_read_b128 v[208:211], v212 offset:2048
	ds_read_b128 v[212:215], v212 offset:3072
	global_load_lds_dwordx4 v[144:145], off
	v_lshl_add_u64 v[144:145], v[216:217], 0, s[46:47]
	s_add_i32 m0, s8, 0x2000
	s_nop 0
	global_load_lds_dwordx4 v[144:145], off
	s_barrier
	s_setprio 1
	s_waitcnt lgkmcnt(3)
	v_mfma_f32_16x16x32_bf16 v[116:119], v[200:203], v[168:171], v[116:119]
	s_waitcnt lgkmcnt(1)
	v_mfma_f32_16x16x32_bf16 v[112:115], v[208:211], v[168:171], v[112:115]
	v_mfma_f32_16x16x32_bf16 v[100:103], v[200:203], v[176:179], v[100:103]
	v_mfma_f32_16x16x32_bf16 v[96:99], v[208:211], v[176:179], v[96:99]
	v_mfma_f32_16x16x32_bf16 v[84:87], v[200:203], v[184:187], v[84:87]
	v_mfma_f32_16x16x32_bf16 v[80:83], v[208:211], v[184:187], v[80:83]
	v_mfma_f32_16x16x32_bf16 v[68:71], v[200:203], v[192:195], v[68:71]
	v_mfma_f32_16x16x32_bf16 v[64:67], v[208:211], v[192:195], v[64:67]
	v_mfma_f32_16x16x32_bf16 v[116:119], v[204:207], v[172:175], v[116:119]
	s_waitcnt lgkmcnt(0)
	v_mfma_f32_16x16x32_bf16 v[112:115], v[212:215], v[172:175], v[112:115]
	v_mfma_f32_16x16x32_bf16 v[100:103], v[204:207], v[180:183], v[100:103]
	v_mfma_f32_16x16x32_bf16 v[96:99], v[212:215], v[180:183], v[96:99]
	v_mfma_f32_16x16x32_bf16 v[84:87], v[204:207], v[188:191], v[84:87]
	v_mfma_f32_16x16x32_bf16 v[80:83], v[212:215], v[188:191], v[80:83]
	v_mfma_f32_16x16x32_bf16 v[68:71], v[204:207], v[196:199], v[68:71]
	v_mfma_f32_16x16x32_bf16 v[64:67], v[212:215], v[196:199], v[64:67]
	s_setprio 0
	s_mov_b32 m0, s29
	v_lshl_add_u64 v[144:145], v[218:219], 0, s[46:47]
	s_barrier
	ds_read_b128 v[168:171], v150 offset:49152
	ds_read_b128 v[172:175], v150 offset:50176
	ds_read_b128 v[176:179], v150 offset:51200
	ds_read_b128 v[180:183], v150 offset:52224
	ds_read_b128 v[184:187], v150 offset:53248
	ds_read_b128 v[188:191], v150 offset:54272
	ds_read_b128 v[192:195], v150 offset:55296
	ds_read_b128 v[196:199], v150 offset:56320
	global_load_lds_dwordx4 v[144:145], off
	v_lshl_add_u64 v[144:145], v[220:221], 0, s[46:47]
	s_mov_b32 m0, s30
	s_nop 0
	global_load_lds_dwordx4 v[144:145], off
	s_waitcnt vmcnt(10)
	s_barrier
	s_setprio 1
	s_waitcnt lgkmcnt(7)
	v_mfma_f32_16x16x32_bf16 v[60:63], v[152:155], v[168:171], v[60:63]
	v_mfma_f32_16x16x32_bf16 v[56:59], v[160:163], v[168:171], v[56:59]
	s_waitcnt lgkmcnt(5)
	v_mfma_f32_16x16x32_bf16 v[44:47], v[152:155], v[176:179], v[44:47]
	v_mfma_f32_16x16x32_bf16 v[40:43], v[160:163], v[176:179], v[40:43]
	s_waitcnt lgkmcnt(3)
	v_mfma_f32_16x16x32_bf16 v[28:31], v[152:155], v[184:187], v[28:31]
	v_mfma_f32_16x16x32_bf16 v[24:27], v[160:163], v[184:187], v[24:27]
	s_waitcnt lgkmcnt(1)
	v_mfma_f32_16x16x32_bf16 v[12:15], v[152:155], v[192:195], v[12:15]
	v_mfma_f32_16x16x32_bf16 v[8:11], v[160:163], v[192:195], v[8:11]
	v_mfma_f32_16x16x32_bf16 v[60:63], v[156:159], v[172:175], v[60:63]
	v_mfma_f32_16x16x32_bf16 v[56:59], v[164:167], v[172:175], v[56:59]
	v_mfma_f32_16x16x32_bf16 v[44:47], v[156:159], v[180:183], v[44:47]
	v_mfma_f32_16x16x32_bf16 v[40:43], v[164:167], v[180:183], v[40:43]
	v_mfma_f32_16x16x32_bf16 v[28:31], v[156:159], v[188:191], v[28:31]
	v_mfma_f32_16x16x32_bf16 v[24:27], v[164:167], v[188:191], v[24:27]
	s_waitcnt lgkmcnt(0)
	v_mfma_f32_16x16x32_bf16 v[12:15], v[156:159], v[196:199], v[12:15]
	v_mfma_f32_16x16x32_bf16 v[8:11], v[164:167], v[196:199], v[8:11]
	s_setprio 0
	s_barrier
	s_add_u32 s8, s12, 0x160080
	s_addc_u32 s9, s13, 0
	s_add_i32 s12, s14, s20
	s_mov_b32 m0, s12
	s_nop 0
	global_load_lds_dwordx4 v132, s[8:9]
	s_add_i32 m0, s12, 0x2000
	s_nop 0
	global_load_lds_dwordx4 v128, s[8:9]
	s_waitcnt vmcnt(6)
	s_barrier
; DI unsigned pack2(float a, float b) { f32x2 v = {a, b}; hwbf16x2 r = __builtin_convertvector(v, hwbf16x2); return __builtin_bit_cast(unsigned, r); }
; DI float bflo(unsigned w) { return __uint_as_float(w << 16); }
;     DI void operator()(const f32x4 (&acc)[2][2][4][2], const Unit& u, int wr, int wc, int fr, int fq) const {
;         const int row0 = u.pm * BM + wr * 64 + fr, col0 = u.pn * BM + wc * 32 + 8 * fq;
;         f32x4 sc[2][2];
; #pragma unroll
;         for (int bj = 0; bj < 2; ++bj)
; #pragma unroll
;             for (int n = 0; n < 2; ++n) sc[bj][n] = scale ? *(const f32x4*)(scale + col0 + bj * HALF + 4 * n) : (f32x4){1.f, 1.f, 1.f, 1.f};
; #pragma unroll
;         for (int ai = 0; ai < 2; ++ai)
; #pragma unroll
;             for (int m = 0; m < 4; ++m) { const size_t ro = (size_t)(row0 + ai * HALF + m * 16) * D + col0;
; #pragma unroll
;                 for (int bj = 0; bj < 2; ++bj) {
;                     f32x4 x0, x1;
;                     if constexpr (IB) { const u32x4 w = *(const u32x4*)((const bf16_t*)Xin + ro + bj * HALF);
;                         x0 = (f32x4){bflo(w[0]), bfhi(w[0]), bflo(w[1]), bfhi(w[1])}; x1 = (f32x4){bflo(w[2]), bfhi(w[2]), bflo(w[3]), bfhi(w[3])}; }
;                     else { x0 = *(const f32x4*)((const float*)Xin + ro + bj * HALF); x1 = *(const f32x4*)((const float*)Xin + ro + bj * HALF + 4); }
;                     x0 += acc[ai][bj][m][0] * sc[bj][0]; x1 += acc[ai][bj][m][1] * sc[bj][1];
;                     if constexpr (OB) { u32x4 o; o[0] = pack2(x0[0], x0[1]); o[1] = pack2(x0[2], x0[3]); o[2] = pack2(x1[0], x1[1]); o[3] = pack2(x1[2], x1[3]);
;                         *(u32x4*)((bf16_t*)Xout + ro + bj * HALF) = o; }
;                     else { *(f32x4*)((float*)Xout + ro + bj * HALF) = x0; *(f32x4*)((float*)Xout + ro + bj * HALF + 4) = x1; } } }
;     }
; template <class Map, class Epi>
; DI void gemm_phase(LAS unsigned char* lds, const Map& MP, const Epi& E, const int nM, const int nN, const int K, const int lda, const int ldb) {
;     ...
;             PG8_BAR; PG8_WAIT_L(0); PG8_MMA(1, 0, At, B0); PG8_BAR; PG8_SCHED;
;             PG8_STAGE(PG8_SB(1, 1), b3 + hstepB, voffB);
;             PG8_WAIT_V(6); PG8_BAR; PG8_MMA(1, 1, At, B1); PG8_BAR;
;         }
;         { int frr = fr, fqq = fq; asm volatile("" : "+v"(frr), "+v"(fqq)); E(acc, cur, wr, wc, frr, fqq); }
	s_setprio 1
	v_mfma_f32_16x16x32_bf16 v[52:55], v[200:203], v[168:171], v[52:55]
	v_mfma_f32_16x16x32_bf16 v[48:51], v[208:211], v[168:171], v[48:51]
	ds_read_b128 v[152:155], v149
	v_mfma_f32_16x16x32_bf16 v[36:39], v[200:203], v[176:179], v[36:39]
	v_mfma_f32_16x16x32_bf16 v[32:35], v[208:211], v[176:179], v[32:35]
	ds_read_b128 v[156:159], v149 offset:1024
	v_mfma_f32_16x16x32_bf16 v[20:23], v[200:203], v[184:187], v[20:23]
	v_mfma_f32_16x16x32_bf16 v[16:19], v[208:211], v[184:187], v[16:19]
	ds_read_b128 v[160:163], v149 offset:2048
	v_mfma_f32_16x16x32_bf16 v[4:7], v[200:203], v[192:195], v[4:7]
	v_mfma_f32_16x16x32_bf16 v[0:3], v[208:211], v[192:195], v[0:3]
	ds_read_b128 v[164:167], v149 offset:3072
	v_mfma_f32_16x16x32_bf16 v[52:55], v[204:207], v[172:175], v[52:55]
	v_mfma_f32_16x16x32_bf16 v[48:51], v[212:215], v[172:175], v[48:51]
	v_mfma_f32_16x16x32_bf16 v[36:39], v[204:207], v[180:183], v[36:39]
	v_mfma_f32_16x16x32_bf16 v[32:35], v[212:215], v[180:183], v[32:35]
	v_mfma_f32_16x16x32_bf16 v[20:23], v[204:207], v[188:191], v[20:23]
	v_mfma_f32_16x16x32_bf16 v[16:19], v[212:215], v[188:191], v[16:19]
	v_mfma_f32_16x16x32_bf16 v[4:7], v[204:207], v[196:199], v[4:7]
	v_mfma_f32_16x16x32_bf16 v[0:3], v[212:215], v[196:199], v[0:3]
	s_setprio 0
	s_add_i32 s48, s48, 2
	s_add_u32 s38, s38, 0x100
	s_addc_u32 s39, s39, 0
	s_cmpk_gt_u32 s48, 0x55
	s_mov_b64 s[8:9], s[10:11]
	s_barrier
	s_cbranch_scc0 .LBB1_2653
	s_waitcnt lgkmcnt(0)
	v_mov_b32_e32 v144, v147
	v_mov_b32_e32 v152, v146
	s_lshl_b32 s2, s2, 8
	s_lshl_b32 s8, s37, 8
	s_add_i32 s2, s2, s27
	s_or_b32 s8, s8, s28
	v_add_u32_e32 v152, s2, v152
	v_lshl_add_u32 v144, v144, 3, s8
	v_ashrrev_i32_e32 v153, 31, v152
	v_ashrrev_i32_e32 v145, 31, v144
	v_lshlrev_b64 v[152:153], 11, v[152:153]
	v_lshl_add_u64 v[144:145], v[152:153], 0, v[144:145]
	v_lshl_add_u64 v[156:157], v[144:145], 1, s[6:7]
	global_load_dwordx4 v[162:165], v[156:157], off
	global_load_dwordx4 v[166:169], v[156:157], off offset:256
	s_mov_b64 s[98:99], 0x10000
	v_lshl_add_u64 v[154:155], v[156:157], 0, s[98:99]
	global_load_dwordx4 v[170:173], v[154:155], off
	global_load_dwordx4 v[174:177], v[154:155], off offset:256
	s_mov_b64 s[98:99], 0x20000
	v_lshl_add_u64 v[154:155], v[156:157], 0, s[98:99]
	global_load_dwordx4 v[178:181], v[154:155], off
	global_load_dwordx4 v[182:185], v[154:155], off offset:256
	s_mov_b64 s[98:99], 0x30000
	v_lshl_add_u64 v[154:155], v[156:157], 0, s[98:99]
	global_load_dwordx4 v[186:189], v[154:155], off
	global_load_dwordx4 v[190:193], v[154:155], off offset:256
	s_mov_b64 s[98:99], 0x80000
	v_lshl_add_u64 v[154:155], v[156:157], 0, s[98:99]
	global_load_dwordx4 v[194:197], v[154:155], off
	global_load_dwordx4 v[198:201], v[154:155], off offset:256
	s_mov_b64 s[98:99], 0x90000
	v_lshl_add_u64 v[154:155], v[156:157], 0, s[98:99]
	global_load_dwordx4 v[202:205], v[154:155], off
	global_load_dwordx4 v[206:209], v[154:155], off offset:256
	s_mov_b64 s[98:99], 0xa0000
	v_lshl_add_u64 v[154:155], v[156:157], 0, s[98:99]
	global_load_dwordx4 v[210:213], v[154:155], off
	global_load_dwordx4 v[248:251], v[154:155], off offset:256
	s_mov_b64 s[98:99], 0xb0000
	v_lshl_add_u64 v[154:155], v[156:157], 0, s[98:99]
	global_load_dwordx4 v[252:255], v[154:155], off
	s_waitcnt vmcnt(14)
	s_nop 1
	v_mov_b32_e32 v152, v162
	v_mov_b32_e32 v153, v163
	v_mov_b32_e32 v154, v164
	v_mov_b32_e32 v155, v165
	s_mov_b64 s[8:9], 0x8000
	s_and_b64 vcc, exec, s[40:41]
	s_mov_b32 s37, s35
	s_mov_b32 s2, s36
	s_mov_b64 s[10:11], s[44:45]
	s_waitcnt lgkmcnt(0)
	v_lshlrev_b32_e32 v158, 16, v152
	v_and_b32_e32 v159, 0xffff0000, v152
	v_lshlrev_b32_e32 v152, 16, v153
	v_and_b32_e32 v153, 0xffff0000, v153
	v_lshlrev_b32_e32 v160, 16, v154
	v_and_b32_e32 v161, 0xffff0000, v154
	v_lshlrev_b32_e32 v154, 16, v155
	v_and_b32_e32 v155, 0xffff0000, v155
	v_pk_add_f32 v[126:127], v[126:127], v[152:153]
	v_pk_add_f32 v[124:125], v[124:125], v[158:159]
	v_lshl_add_u64 v[152:153], v[144:145], 2, s[4:5]
	v_pk_add_f32 v[122:123], v[122:123], v[154:155]
	v_pk_add_f32 v[120:121], v[120:121], v[160:161]
	global_store_dwordx4 v[152:153], v[124:127], off
	global_store_dwordx4 v[152:153], v[120:123], off offset:16
	s_waitcnt vmcnt(15)
	s_nop 1
	v_mov_b32_e32 v120, v166
	v_mov_b32_e32 v121, v167
	v_mov_b32_e32 v122, v168
	v_mov_b32_e32 v123, v169
	s_waitcnt lgkmcnt(0)
	v_lshlrev_b32_e32 v124, 16, v120
	v_and_b32_e32 v125, 0xffff0000, v120
	v_lshlrev_b32_e32 v120, 16, v121
	v_and_b32_e32 v121, 0xffff0000, v121
	v_lshlrev_b32_e32 v126, 16, v122
	v_and_b32_e32 v127, 0xffff0000, v122
	v_lshlrev_b32_e32 v122, 16, v123
	v_and_b32_e32 v123, 0xffff0000, v123
	v_pk_add_f32 v[118:119], v[118:119], v[120:121]
	v_pk_add_f32 v[116:117], v[116:117], v[124:125]
	v_pk_add_f32 v[114:115], v[114:115], v[122:123]
	v_pk_add_f32 v[112:113], v[112:113], v[126:127]
	global_store_dwordx4 v[152:153], v[116:119], off offset:512
	global_store_dwordx4 v[152:153], v[112:115], off offset:528
	s_nop 0
	v_lshl_add_u64 v[116:117], v[144:145], 0, s[8:9]
	v_lshl_add_u64 v[118:119], v[116:117], 1, s[6:7]
	s_waitcnt vmcnt(16)
	s_nop 1
	v_mov_b32_e32 v112, v170
	v_mov_b32_e32 v113, v171
	v_mov_b32_e32 v114, v172
	v_mov_b32_e32 v115, v173
	s_mov_b64 s[8:9], 0x10000
	s_waitcnt lgkmcnt(0)
	v_lshlrev_b32_e32 v120, 16, v112
	v_and_b32_e32 v121, 0xffff0000, v112
	v_lshlrev_b32_e32 v112, 16, v113
	v_and_b32_e32 v113, 0xffff0000, v113
	v_lshlrev_b32_e32 v122, 16, v114
	v_and_b32_e32 v123, 0xffff0000, v114
	v_lshlrev_b32_e32 v114, 16, v115
	v_and_b32_e32 v115, 0xffff0000, v115
	v_pk_add_f32 v[110:111], v[110:111], v[112:113]
	v_pk_add_f32 v[108:109], v[108:109], v[120:121]
	v_lshl_add_u64 v[112:113], v[116:117], 2, s[4:5]
	v_pk_add_f32 v[106:107], v[106:107], v[114:115]
	v_pk_add_f32 v[104:105], v[104:105], v[122:123]
	global_store_dwordx4 v[112:113], v[108:111], off
	global_store_dwordx4 v[112:113], v[104:107], off offset:16
	s_waitcnt vmcnt(17)
; DI unsigned pack2(float a, float b) { f32x2 v = {a, b}; hwbf16x2 r = __builtin_convertvector(v, hwbf16x2); return __builtin_bit_cast(unsigned, r); }
; DI float bflo(unsigned w) { return __uint_as_float(w << 16); }
; DI float bfhi(unsigned w) { return __uint_as_float(w & 0xffff0000u); }
;     DI void operator()(const f32x4 (&acc)[2][2][4][2], const Unit& u, int wr, int wc, int fr, int fq) const {
;     ...
;         for (int ai = 0; ai < 2; ++ai)
; #pragma unroll
;             for (int m = 0; m < 4; ++m) { const size_t ro = (size_t)(row0 + ai * HALF + m * 16) * D + col0;
; #pragma unroll
;                 for (int bj = 0; bj < 2; ++bj) {
;                     f32x4 x0, x1;
;                     if constexpr (IB) { const u32x4 w = *(const u32x4*)((const bf16_t*)Xin + ro + bj * HALF);
;                         x0 = (f32x4){bflo(w[0]), bfhi(w[0]), bflo(w[1]), bfhi(w[1])}; x1 = (f32x4){bflo(w[2]), bfhi(w[2]), bflo(w[3]), bfhi(w[3])}; }
;                     else { x0 = *(const f32x4*)((const float*)Xin + ro + bj * HALF); x1 = *(const f32x4*)((const float*)Xin + ro + bj * HALF + 4); }
;                     x0 += acc[ai][bj][m][0] * sc[bj][0]; x1 += acc[ai][bj][m][1] * sc[bj][1];
;                     if constexpr (OB) { u32x4 o; o[0] = pack2(x0[0], x0[1]); o[1] = pack2(x0[2], x0[3]); o[2] = pack2(x1[0], x1[1]); o[3] = pack2(x1[2], x1[3]);
;                         *(u32x4*)((bf16_t*)Xout + ro + bj * HALF) = o; }
;                     else { *(f32x4*)((float*)Xout + ro + bj * HALF) = x0; *(f32x4*)((float*)Xout + ro + bj * HALF + 4) = x1; } } }
	s_nop 1
	v_mov_b32_e32 v104, v174
	v_mov_b32_e32 v105, v175
	v_mov_b32_e32 v106, v176
	v_mov_b32_e32 v107, v177
	s_waitcnt lgkmcnt(0)
	v_lshlrev_b32_e32 v108, 16, v104
	v_and_b32_e32 v109, 0xffff0000, v104
	v_lshlrev_b32_e32 v104, 16, v105
	v_and_b32_e32 v105, 0xffff0000, v105
	v_lshlrev_b32_e32 v110, 16, v106
	v_and_b32_e32 v111, 0xffff0000, v106
	v_lshlrev_b32_e32 v106, 16, v107
	v_and_b32_e32 v107, 0xffff0000, v107
	v_pk_add_f32 v[102:103], v[102:103], v[104:105]
	v_pk_add_f32 v[100:101], v[100:101], v[108:109]
	v_pk_add_f32 v[98:99], v[98:99], v[106:107]
	v_pk_add_f32 v[96:97], v[96:97], v[110:111]
	global_store_dwordx4 v[112:113], v[100:103], off offset:512
	global_store_dwordx4 v[112:113], v[96:99], off offset:528
	s_nop 0
	v_lshl_add_u64 v[100:101], v[144:145], 0, s[8:9]
	v_lshl_add_u64 v[102:103], v[100:101], 1, s[6:7]
	s_waitcnt vmcnt(18)
	s_nop 1
	v_mov_b32_e32 v96, v178
	v_mov_b32_e32 v97, v179
	v_mov_b32_e32 v98, v180
	v_mov_b32_e32 v99, v181
	s_mov_b64 s[8:9], 0x18000
	s_waitcnt lgkmcnt(0)
	v_lshlrev_b32_e32 v104, 16, v96
	v_and_b32_e32 v105, 0xffff0000, v96
	v_lshlrev_b32_e32 v96, 16, v97
	v_and_b32_e32 v97, 0xffff0000, v97
	v_lshlrev_b32_e32 v106, 16, v98
	v_and_b32_e32 v107, 0xffff0000, v98
	v_lshlrev_b32_e32 v98, 16, v99
	v_and_b32_e32 v99, 0xffff0000, v99
	v_pk_add_f32 v[94:95], v[94:95], v[96:97]
	v_pk_add_f32 v[92:93], v[92:93], v[104:105]
	v_lshl_add_u64 v[96:97], v[100:101], 2, s[4:5]
	v_pk_add_f32 v[90:91], v[90:91], v[98:99]
	v_pk_add_f32 v[88:89], v[88:89], v[106:107]
	global_store_dwordx4 v[96:97], v[92:95], off
	global_store_dwordx4 v[96:97], v[88:91], off offset:16
	s_waitcnt vmcnt(19)
	s_nop 1
	v_mov_b32_e32 v88, v182
	v_mov_b32_e32 v89, v183
	v_mov_b32_e32 v90, v184
	v_mov_b32_e32 v91, v185
	s_waitcnt lgkmcnt(0)
	v_lshlrev_b32_e32 v92, 16, v88
	v_and_b32_e32 v93, 0xffff0000, v88
	v_lshlrev_b32_e32 v88, 16, v89
	v_and_b32_e32 v89, 0xffff0000, v89
	v_lshlrev_b32_e32 v94, 16, v90
	v_and_b32_e32 v95, 0xffff0000, v90
	v_lshlrev_b32_e32 v90, 16, v91
	v_and_b32_e32 v91, 0xffff0000, v91
	v_pk_add_f32 v[86:87], v[86:87], v[88:89]
	v_pk_add_f32 v[84:85], v[84:85], v[92:93]
	v_pk_add_f32 v[82:83], v[82:83], v[90:91]
	v_pk_add_f32 v[80:81], v[80:81], v[94:95]
	global_store_dwordx4 v[96:97], v[84:87], off offset:512
	global_store_dwordx4 v[96:97], v[80:83], off offset:528
	s_nop 0
	v_lshl_add_u64 v[84:85], v[144:145], 0, s[8:9]
	v_lshl_add_u64 v[86:87], v[84:85], 1, s[6:7]
	s_waitcnt vmcnt(20)
	s_nop 1
	v_mov_b32_e32 v80, v186
	v_mov_b32_e32 v81, v187
	v_mov_b32_e32 v82, v188
	v_mov_b32_e32 v83, v189
	s_mov_b64 s[8:9], 0x40000
	s_waitcnt lgkmcnt(0)
	v_lshlrev_b32_e32 v88, 16, v80
	v_and_b32_e32 v89, 0xffff0000, v80
	v_lshlrev_b32_e32 v80, 16, v81
	v_and_b32_e32 v81, 0xffff0000, v81
	v_lshlrev_b32_e32 v90, 16, v82
	v_and_b32_e32 v91, 0xffff0000, v82
	v_lshlrev_b32_e32 v82, 16, v83
	v_and_b32_e32 v83, 0xffff0000, v83
	v_pk_add_f32 v[78:79], v[78:79], v[80:81]
	v_pk_add_f32 v[76:77], v[76:77], v[88:89]
	v_lshl_add_u64 v[80:81], v[84:85], 2, s[4:5]
	v_pk_add_f32 v[74:75], v[74:75], v[82:83]
	v_pk_add_f32 v[72:73], v[72:73], v[90:91]
	global_store_dwordx4 v[80:81], v[76:79], off
	global_store_dwordx4 v[80:81], v[72:75], off offset:16
	s_waitcnt vmcnt(21)
	s_nop 1
	v_mov_b32_e32 v72, v190
	v_mov_b32_e32 v73, v191
	v_mov_b32_e32 v74, v192
	v_mov_b32_e32 v75, v193
	s_waitcnt lgkmcnt(0)
	v_lshlrev_b32_e32 v76, 16, v72
	v_and_b32_e32 v77, 0xffff0000, v72
	v_lshlrev_b32_e32 v72, 16, v73
	v_and_b32_e32 v73, 0xffff0000, v73
	v_lshlrev_b32_e32 v78, 16, v74
	v_and_b32_e32 v79, 0xffff0000, v74
	v_lshlrev_b32_e32 v74, 16, v75
	v_and_b32_e32 v75, 0xffff0000, v75
	v_pk_add_f32 v[70:71], v[70:71], v[72:73]
	v_pk_add_f32 v[68:69], v[68:69], v[76:77]
	v_pk_add_f32 v[66:67], v[66:67], v[74:75]
	v_pk_add_f32 v[64:65], v[64:65], v[78:79]
	global_store_dwordx4 v[80:81], v[68:71], off offset:512
	global_store_dwordx4 v[80:81], v[64:67], off offset:528
	s_nop 0
	v_lshl_add_u64 v[68:69], v[144:145], 0, s[8:9]
	v_lshl_add_u64 v[70:71], v[68:69], 1, s[6:7]
	s_waitcnt vmcnt(22)
	s_nop 1
	v_mov_b32_e32 v64, v194
	v_mov_b32_e32 v65, v195
	v_mov_b32_e32 v66, v196
	v_mov_b32_e32 v67, v197
	s_mov_b64 s[8:9], 0x48000
	s_waitcnt lgkmcnt(0)
	v_lshlrev_b32_e32 v72, 16, v64
	v_and_b32_e32 v73, 0xffff0000, v64
	v_lshlrev_b32_e32 v64, 16, v65
	v_and_b32_e32 v65, 0xffff0000, v65
	v_lshlrev_b32_e32 v74, 16, v66
	v_and_b32_e32 v75, 0xffff0000, v66
	v_lshlrev_b32_e32 v66, 16, v67
	v_and_b32_e32 v67, 0xffff0000, v67
	v_pk_add_f32 v[62:63], v[62:63], v[64:65]
	v_pk_add_f32 v[60:61], v[60:61], v[72:73]
	v_lshl_add_u64 v[64:65], v[68:69], 2, s[4:5]
	v_pk_add_f32 v[58:59], v[58:59], v[66:67]
	v_pk_add_f32 v[56:57], v[56:57], v[74:75]
	global_store_dwordx4 v[64:65], v[60:63], off
	global_store_dwordx4 v[64:65], v[56:59], off offset:16
	s_waitcnt vmcnt(23)
	s_nop 1
	v_mov_b32_e32 v56, v198
	v_mov_b32_e32 v57, v199
	v_mov_b32_e32 v58, v200
	v_mov_b32_e32 v59, v201
	s_waitcnt lgkmcnt(0)
; DI unsigned pack2(float a, float b) { f32x2 v = {a, b}; hwbf16x2 r = __builtin_convertvector(v, hwbf16x2); return __builtin_bit_cast(unsigned, r); }
; DI float bflo(unsigned w) { return __uint_as_float(w << 16); }
; DI float bfhi(unsigned w) { return __uint_as_float(w & 0xffff0000u); }
;     DI const char* a(const Unit& u) const { return (const char*)(A + (size_t)u.pm * BM * lda); }
;     DI const char* a(const Unit& u) const { return (const char*)(A + (size_t)u.pm * BM * 2048 + (u.pn >> 1) * 512); }
;     DI void operator()(const f32x4 (&acc)[2][2][4][2], const Unit& u, int wr, int wc, int fr, int fq) const {
;     ...
;         for (int ai = 0; ai < 2; ++ai)
; #pragma unroll
;             for (int m = 0; m < 4; ++m) { const size_t ro = (size_t)(row0 + ai * HALF + m * 16) * D + col0;
; #pragma unroll
;                 for (int bj = 0; bj < 2; ++bj) {
;                     f32x4 x0, x1;
;                     if constexpr (IB) { const u32x4 w = *(const u32x4*)((const bf16_t*)Xin + ro + bj * HALF);
;                         x0 = (f32x4){bflo(w[0]), bfhi(w[0]), bflo(w[1]), bfhi(w[1])}; x1 = (f32x4){bflo(w[2]), bfhi(w[2]), bflo(w[3]), bfhi(w[3])}; }
;                     else { x0 = *(const f32x4*)((const float*)Xin + ro + bj * HALF); x1 = *(const f32x4*)((const float*)Xin + ro + bj * HALF + 4); }
;                     x0 += acc[ai][bj][m][0] * sc[bj][0]; x1 += acc[ai][bj][m][1] * sc[bj][1];
;                     if constexpr (OB) { u32x4 o; o[0] = pack2(x0[0], x0[1]); o[1] = pack2(x0[2], x0[3]); o[2] = pack2(x1[0], x1[1]); o[3] = pack2(x1[2], x1[3]);
;                         *(u32x4*)((bf16_t*)Xout + ro + bj * HALF) = o; }
;                     else { *(f32x4*)((float*)Xout + ro + bj * HALF) = x0; *(f32x4*)((float*)Xout + ro + bj * HALF + 4) = x1; } } }
; template <class Map, class Epi>
; DI void gemm_phase(LAS unsigned char* lds, const Map& MP, const Epi& E, const int nM, const int nN, const int K, const int lda, const int ldb) {
;     ...
;         if (!has_next) break;
; #pragma unroll
;         for (int a = 0; a < 2; ++a)
; #pragma unroll
;             for (int b = 0; b < 2; ++b)
; #pragma unroll
;                 for (int m = 0; m < 4; ++m)
; #pragma unroll
;                     for (int n = 0; n < 2; ++n) acc[a][b][m][n] = (f32x4){0.f, 0.f, 0.f, 0.f};
;         cur = nxt; cA = nA; cB = nB; ++ui;
;     }
;     PG8_WAIT_V(0);
;     if (wr == 0) PG8_BAR;
;     PG8_BAR;
	v_lshlrev_b32_e32 v60, 16, v56
	v_and_b32_e32 v61, 0xffff0000, v56
	v_lshlrev_b32_e32 v56, 16, v57
	v_and_b32_e32 v57, 0xffff0000, v57
	v_lshlrev_b32_e32 v62, 16, v58
	v_and_b32_e32 v63, 0xffff0000, v58
	v_lshlrev_b32_e32 v58, 16, v59
	v_and_b32_e32 v59, 0xffff0000, v59
	v_pk_add_f32 v[54:55], v[54:55], v[56:57]
	v_pk_add_f32 v[52:53], v[52:53], v[60:61]
	v_pk_add_f32 v[50:51], v[50:51], v[58:59]
	v_pk_add_f32 v[48:49], v[48:49], v[62:63]
	global_store_dwordx4 v[64:65], v[52:55], off offset:512
	global_store_dwordx4 v[64:65], v[48:51], off offset:528
	s_nop 0
	v_lshl_add_u64 v[52:53], v[144:145], 0, s[8:9]
	v_lshl_add_u64 v[54:55], v[52:53], 1, s[6:7]
	s_waitcnt vmcnt(24)
	s_nop 1
	v_mov_b32_e32 v48, v202
	v_mov_b32_e32 v49, v203
	v_mov_b32_e32 v50, v204
	v_mov_b32_e32 v51, v205
	s_mov_b64 s[8:9], 0x50000
	s_waitcnt lgkmcnt(0)
	v_lshlrev_b32_e32 v56, 16, v48
	v_and_b32_e32 v57, 0xffff0000, v48
	v_lshlrev_b32_e32 v48, 16, v49
	v_and_b32_e32 v49, 0xffff0000, v49
	v_lshlrev_b32_e32 v58, 16, v50
	v_and_b32_e32 v59, 0xffff0000, v50
	v_lshlrev_b32_e32 v50, 16, v51
	v_and_b32_e32 v51, 0xffff0000, v51
	v_pk_add_f32 v[46:47], v[46:47], v[48:49]
	v_pk_add_f32 v[44:45], v[44:45], v[56:57]
	v_lshl_add_u64 v[48:49], v[52:53], 2, s[4:5]
	v_pk_add_f32 v[42:43], v[42:43], v[50:51]
	v_pk_add_f32 v[40:41], v[40:41], v[58:59]
	global_store_dwordx4 v[48:49], v[44:47], off
	global_store_dwordx4 v[48:49], v[40:43], off offset:16
	s_waitcnt vmcnt(25)
	s_nop 1
	v_mov_b32_e32 v40, v206
	v_mov_b32_e32 v41, v207
	v_mov_b32_e32 v42, v208
	v_mov_b32_e32 v43, v209
	s_waitcnt lgkmcnt(0)
	v_lshlrev_b32_e32 v44, 16, v40
	v_and_b32_e32 v45, 0xffff0000, v40
	v_lshlrev_b32_e32 v40, 16, v41
	v_and_b32_e32 v41, 0xffff0000, v41
	v_lshlrev_b32_e32 v46, 16, v42
	v_and_b32_e32 v47, 0xffff0000, v42
	v_lshlrev_b32_e32 v42, 16, v43
	v_and_b32_e32 v43, 0xffff0000, v43
	v_pk_add_f32 v[38:39], v[38:39], v[40:41]
	v_pk_add_f32 v[36:37], v[36:37], v[44:45]
	v_pk_add_f32 v[34:35], v[34:35], v[42:43]
	v_pk_add_f32 v[32:33], v[32:33], v[46:47]
	global_store_dwordx4 v[48:49], v[36:39], off offset:512
	global_store_dwordx4 v[48:49], v[32:35], off offset:528
	s_nop 0
	v_lshl_add_u64 v[36:37], v[144:145], 0, s[8:9]
	v_lshl_add_u64 v[38:39], v[36:37], 1, s[6:7]
	s_waitcnt vmcnt(26)
	s_nop 1
	v_mov_b32_e32 v32, v210
	v_mov_b32_e32 v33, v211
	v_mov_b32_e32 v34, v212
	v_mov_b32_e32 v35, v213
	s_mov_b64 s[8:9], 0x58000
	s_waitcnt lgkmcnt(0)
	v_lshlrev_b32_e32 v40, 16, v32
	v_and_b32_e32 v41, 0xffff0000, v32
	v_lshlrev_b32_e32 v32, 16, v33
	v_and_b32_e32 v33, 0xffff0000, v33
	v_lshlrev_b32_e32 v42, 16, v34
	v_and_b32_e32 v43, 0xffff0000, v34
	v_lshlrev_b32_e32 v34, 16, v35
	v_and_b32_e32 v35, 0xffff0000, v35
	v_pk_add_f32 v[30:31], v[30:31], v[32:33]
	v_pk_add_f32 v[28:29], v[28:29], v[40:41]
	v_lshl_add_u64 v[32:33], v[36:37], 2, s[4:5]
	v_pk_add_f32 v[26:27], v[26:27], v[34:35]
	v_pk_add_f32 v[24:25], v[24:25], v[42:43]
	global_store_dwordx4 v[32:33], v[28:31], off
	global_store_dwordx4 v[32:33], v[24:27], off offset:16
	s_waitcnt vmcnt(27)
	s_nop 1
	v_mov_b32_e32 v24, v248
	v_mov_b32_e32 v25, v249
	v_mov_b32_e32 v26, v250
	v_mov_b32_e32 v27, v251
	s_waitcnt lgkmcnt(0)
	v_lshlrev_b32_e32 v28, 16, v24
	v_and_b32_e32 v29, 0xffff0000, v24
	v_lshlrev_b32_e32 v24, 16, v25
	v_and_b32_e32 v25, 0xffff0000, v25
	v_lshlrev_b32_e32 v30, 16, v26
	v_and_b32_e32 v31, 0xffff0000, v26
	v_lshlrev_b32_e32 v26, 16, v27
	v_and_b32_e32 v27, 0xffff0000, v27
	v_pk_add_f32 v[22:23], v[22:23], v[24:25]
	v_pk_add_f32 v[20:21], v[20:21], v[28:29]
	v_pk_add_f32 v[18:19], v[18:19], v[26:27]
	v_pk_add_f32 v[16:17], v[16:17], v[30:31]
	global_store_dwordx4 v[32:33], v[20:23], off offset:512
	global_store_dwordx4 v[32:33], v[16:19], off offset:528
	s_nop 0
	v_lshl_add_u64 v[20:21], v[144:145], 0, s[8:9]
	v_lshl_add_u64 v[22:23], v[20:21], 1, s[6:7]
	s_waitcnt vmcnt(28)
	s_nop 1
	v_mov_b32_e32 v16, v252
	v_mov_b32_e32 v17, v253
	v_mov_b32_e32 v18, v254
	v_mov_b32_e32 v19, v255
	s_mov_b64 s[8:9], s[42:43]
	s_waitcnt lgkmcnt(0)
	v_lshlrev_b32_e32 v24, 16, v16
	v_and_b32_e32 v25, 0xffff0000, v16
	v_lshlrev_b32_e32 v16, 16, v17
	v_and_b32_e32 v17, 0xffff0000, v17
	v_lshlrev_b32_e32 v26, 16, v18
	v_and_b32_e32 v27, 0xffff0000, v18
	v_lshlrev_b32_e32 v18, 16, v19
	v_and_b32_e32 v19, 0xffff0000, v19
	v_pk_add_f32 v[14:15], v[14:15], v[16:17]
	v_pk_add_f32 v[12:13], v[12:13], v[24:25]
	v_lshl_add_u64 v[16:17], v[20:21], 2, s[4:5]
	v_pk_add_f32 v[10:11], v[10:11], v[18:19]
	v_pk_add_f32 v[8:9], v[8:9], v[26:27]
	global_store_dwordx4 v[16:17], v[12:15], off
	global_store_dwordx4 v[16:17], v[8:11], off offset:16
	global_load_dwordx4 v[8:11], v[22:23], off offset:256
	s_waitcnt vmcnt(0) lgkmcnt(0)
	v_lshlrev_b32_e32 v12, 16, v8
	v_and_b32_e32 v13, 0xffff0000, v8
	v_lshlrev_b32_e32 v8, 16, v9
	v_and_b32_e32 v9, 0xffff0000, v9
	v_lshlrev_b32_e32 v14, 16, v10
	v_and_b32_e32 v15, 0xffff0000, v10
	v_lshlrev_b32_e32 v10, 16, v11
	v_and_b32_e32 v11, 0xffff0000, v11
	v_pk_add_f32 v[6:7], v[6:7], v[8:9]
	v_pk_add_f32 v[4:5], v[4:5], v[12:13]
	v_pk_add_f32 v[2:3], v[2:3], v[10:11]
	v_pk_add_f32 v[0:1], v[0:1], v[14:15]
	global_store_dwordx4 v[16:17], v[4:7], off offset:512
	global_store_dwordx4 v[16:17], v[0:3], off offset:528
	s_cbranch_vccz .LBB1_2646
	s_waitcnt vmcnt(0)
	s_cmpk_gt_u32 s3, 0xff
	s_cbranch_scc1 .LBB1_2657
	s_barrier
